# bf16 GEMM epilogues: integer round trick replaced by v_cvt_pk_bf16_f32; PV MFMAs interleaved with exp stream; setprio around attention MFMA clusters
# speedup vs baseline: 1.0056x; 1.0056x over previous
; __device__ __forceinline__ unsigned f2bf_(float f) { unsigned u = __builtin_bit_cast(unsigned, f); return (u + 0x7fffu + ((u >> 16) & 1u)) >> 16; }
; __device__ __forceinline__ unsigned pk2_(float lo, float hi) { return f2bf_(lo) | (f2bf_(hi) << 16); }
;     __device__ __forceinline__ void operator()(const f32x4 (&acc)[2][2][4][2], const Unit& u, int wr, int wc, int fr, int fq) const {
;         asm volatile("" : "+v"(fr), "+v"(fq));
;         const int row0 = u.pm * BM + wr * 64 + fr; const int col0 = u.pn * BM + wc * 32 + 8 * fq;
; #pragma unroll
;         for (int ai = 0; ai < 2; ++ai)
; #pragma unroll
;             for (int m = 0; m < 4; ++m) { bf16_t* rowp = O + (size_t)(row0 + ai * HALF + m * 16) * ldc + col0;
; #pragma unroll
;                 for (int bj = 0; bj < 2; ++bj) { f32x4 v0 = acc[ai][bj][m][0], v1 = acc[ai][bj][m][1];
;                     if (bias) { v0 += *(const f32x4*)(bias + col0 + bj * HALF); v1 += *(const f32x4*)(bias + col0 + bj * HALF + 4); }
;                     u32x4 w; w.x = pk2_(act_f<ACT>(v0[0]), act_f<ACT>(v0[1])); w.y = pk2_(act_f<ACT>(v0[2]), act_f<ACT>(v0[3]));
;                     w.z = pk2_(act_f<ACT>(v1[0]), act_f<ACT>(v1[1])); w.w = pk2_(act_f<ACT>(v1[2]), act_f<ACT>(v1[3]));
;                     *(u32x4*)(rowp + bj * HALF) = w; } }
.LBB0_95:
	v_cvt_pk_bf16_f32 v124, v124, v125
	v_cvt_pk_bf16_f32 v125, v126, v127
	v_cvt_pk_bf16_f32 v126, v120, v121
	v_cvt_pk_bf16_f32 v127, v122, v123
	v_cvt_pk_bf16_f32 v116, v116, v117
	v_cvt_pk_bf16_f32 v117, v118, v119
	v_cvt_pk_bf16_f32 v118, v108, v109
	v_cvt_pk_bf16_f32 v119, v110, v111
	v_cvt_pk_bf16_f32 v108, v112, v113
	s_lshl_b32 s35, s42, 8
	v_mov_b32_e32 v144, v147
	v_mov_b32_e32 v145, v148
	s_add_i32 s35, s35, s65
	v_cvt_pk_bf16_f32 v109, v114, v115
	s_lshl_b32 s37, s79, 8
	v_add_u32_e32 v154, s35, v145
	s_or_b32 s37, s37, s66
	v_ashrrev_i32_e32 v155, 31, v154
	v_lshl_add_u32 v144, v144, 3, s37
	v_lshlrev_b64 v[154:155], 12, v[154:155]
	v_cvt_pk_bf16_f32 v110, v104, v105
	v_ashrrev_i32_e32 v145, 31, v144
	v_lshl_add_u64 v[154:155], s[20:21], 0, v[154:155]
	v_lshl_add_u64 v[144:145], v[144:145], 1, v[154:155]
	v_cvt_pk_bf16_f32 v111, v106, v107
	v_add_co_u32_e32 v104, vcc, s64, v144
	global_store_dwordx4 v[144:145], v[116:119], off offset:256
	s_nop 0
	v_addc_co_u32_e32 v105, vcc, 0, v145, vcc
	global_store_dwordx4 v[104:105], v[108:111], off
	v_cvt_pk_bf16_f32 v100, v100, v101
	v_cvt_pk_bf16_f32 v101, v102, v103
	v_cvt_pk_bf16_f32 v102, v92, v93
	v_cvt_pk_bf16_f32 v103, v94, v95
	v_cvt_pk_bf16_f32 v92, v96, v97
	v_cvt_pk_bf16_f32 v93, v98, v99
	v_cvt_pk_bf16_f32 v94, v88, v89
	v_cvt_pk_bf16_f32 v95, v90, v91
	v_add_co_u32_e32 v88, vcc, s73, v144
	v_lshl_add_u64 v[116:117], v[144:145], 0, s[10:11]
	s_nop 0
	v_addc_co_u32_e32 v89, vcc, 0, v145, vcc
	global_store_dwordx4 v[88:89], v[92:95], off
	v_cvt_pk_bf16_f32 v84, v84, v85
	v_cvt_pk_bf16_f32 v85, v86, v87
	v_cvt_pk_bf16_f32 v86, v76, v77
	v_cvt_pk_bf16_f32 v87, v78, v79
	v_cvt_pk_bf16_f32 v76, v80, v81
	v_cvt_pk_bf16_f32 v77, v82, v83
	v_cvt_pk_bf16_f32 v78, v72, v73
	v_cvt_pk_bf16_f32 v79, v74, v75
	v_add_co_u32_e32 v72, vcc, s74, v144
	global_store_dwordx4 v[116:117], v[100:103], off offset:256
	s_nop 0
	v_addc_co_u32_e32 v73, vcc, 0, v145, vcc
	global_store_dwordx4 v[72:73], v[76:79], off
	v_cvt_pk_bf16_f32 v68, v68, v69
	v_cvt_pk_bf16_f32 v69, v70, v71
	v_cvt_pk_bf16_f32 v70, v64, v65
	v_cvt_pk_bf16_f32 v60, v60, v61
	v_cvt_pk_bf16_f32 v61, v62, v63
	v_cvt_pk_bf16_f32 v62, v56, v57
	v_cvt_pk_bf16_f32 v63, v58, v59
	v_add_co_u32_e32 v56, vcc, s75, v144
	s_nop 0
	v_addc_co_u32_e32 v57, vcc, 0, v145, vcc
	global_store_dwordx4 v[56:57], v[60:63], off
	v_cvt_pk_bf16_f32 v52, v52, v53
	v_cvt_pk_bf16_f32 v53, v54, v55
	v_cvt_pk_bf16_f32 v54, v44, v45
	v_cvt_pk_bf16_f32 v55, v46, v47
	v_cvt_pk_bf16_f32 v44, v48, v49
	v_cvt_pk_bf16_f32 v45, v50, v51
	v_cvt_pk_bf16_f32 v46, v40, v41
	v_cvt_pk_bf16_f32 v47, v42, v43
	v_add_co_u32_e32 v40, vcc, s76, v144
	s_nop 0
	v_addc_co_u32_e32 v41, vcc, 0, v145, vcc
	global_store_dwordx4 v[40:41], v[44:47], off
	v_cvt_pk_bf16_f32 v36, v36, v37
	v_cvt_pk_bf16_f32 v37, v38, v39
	v_cvt_pk_bf16_f32 v38, v28, v29
	v_cvt_pk_bf16_f32 v39, v30, v31
	v_cvt_pk_bf16_f32 v28, v32, v33
	v_cvt_pk_bf16_f32 v29, v34, v35
	v_cvt_pk_bf16_f32 v30, v24, v25
	v_cvt_pk_bf16_f32 v31, v26, v27
	v_add_co_u32_e32 v24, vcc, s77, v144
	s_nop 0
	v_addc_co_u32_e32 v25, vcc, 0, v145, vcc
	global_store_dwordx4 v[24:25], v[28:31], off
	v_cvt_pk_bf16_f32 v20, v20, v21
	v_cvt_pk_bf16_f32 v21, v22, v23
	v_cvt_pk_bf16_f32 v22, v12, v13
	v_cvt_pk_bf16_f32 v23, v14, v15
	v_cvt_pk_bf16_f32 v12, v16, v17
	v_cvt_pk_bf16_f32 v13, v18, v19
	v_cvt_pk_bf16_f32 v14, v8, v9
	v_cvt_pk_bf16_f32 v15, v10, v11
	v_add_co_u32_e32 v8, vcc, s78, v144
	v_cvt_pk_bf16_f32 v71, v66, v67
	s_nop 0
	v_addc_co_u32_e32 v9, vcc, 0, v145, vcc
	global_store_dwordx4 v[8:9], v[12:15], off
	v_cvt_pk_bf16_f32 v4, v4, v5
	v_cvt_pk_bf16_f32 v5, v6, v7
	v_lshl_add_u64 v[64:65], v[144:145], 0, s[24:25]
	v_cvt_pk_bf16_f32 v6, v0, v1
	global_store_dwordx4 v[64:65], v[52:55], off offset:256
	s_nop 1
	v_lshl_add_u64 v[52:53], v[144:145], 0, s[26:27]
	v_lshl_add_u64 v[100:101], v[144:145], 0, s[12:13]
	global_store_dwordx4 v[52:53], v[36:39], off offset:256
	s_nop 1
	v_lshl_add_u64 v[36:37], v[144:145], 0, s[28:29]
	global_store_dwordx4 v[100:101], v[84:87], off offset:256
	global_store_dwordx4 v[36:37], v[20:23], off offset:256
	v_cvt_pk_bf16_f32 v7, v2, v3
	v_lshl_add_u64 v[84:85], v[144:145], 0, s[22:23]
	v_lshl_add_u64 v[20:21], v[144:145], 0, s[30:31]
	s_andn2_b64 vcc, exec, s[0:1]
	s_mov_b64 s[0:1], -1
	global_store_dwordx4 v[144:145], v[124:127], off
	global_store_dwordx4 v[84:85], v[68:71], off offset:256
	global_store_dwordx4 v[20:21], v[4:7], off offset:256
	s_cbranch_vccnz .LBB0_84
	s_andn2_b64 vcc, exec, s[4:5]
	s_cbranch_vccnz .LBB0_83
	s_barrier
	s_branch .LBB0_83

; __device__ __forceinline__ unsigned f2bf_(float f) { unsigned u = __builtin_bit_cast(unsigned, f); return (u + 0x7fffu + ((u >> 16) & 1u)) >> 16; }
; __device__ __forceinline__ unsigned pk2_(float lo, float hi) { return f2bf_(lo) | (f2bf_(hi) << 16); }
;     __device__ __forceinline__ void operator()(const f32x4 (&acc)[2][2][4][2], const Unit& u, int wr, int wc, int fr, int fq) const {
;         asm volatile("" : "+v"(fr), "+v"(fq));
;         const int row0 = u.pm * BM + wr * 64 + fr; const int col0 = u.pn * BM + wc * 32 + 8 * fq;
; #pragma unroll
;         for (int ai = 0; ai < 2; ++ai)
; #pragma unroll
;             for (int m = 0; m < 4; ++m) { bf16_t* rowp = O + (size_t)(row0 + ai * HALF + m * 16) * ldc + col0;
; #pragma unroll
;                 for (int bj = 0; bj < 2; ++bj) { f32x4 v0 = acc[ai][bj][m][0], v1 = acc[ai][bj][m][1];
;                     if (bias) { v0 += *(const f32x4*)(bias + col0 + bj * HALF); v1 += *(const f32x4*)(bias + col0 + bj * HALF + 4); }
;                     u32x4 w; w.x = pk2_(act_f<ACT>(v0[0]), act_f<ACT>(v0[1])); w.y = pk2_(act_f<ACT>(v0[2]), act_f<ACT>(v0[3]));
;                     w.z = pk2_(act_f<ACT>(v1[0]), act_f<ACT>(v1[1])); w.w = pk2_(act_f<ACT>(v1[2]), act_f<ACT>(v1[3]));
;                     *(u32x4*)(rowp + bj * HALF) = w; } }
.LBB0_119:
	v_cvt_pk_bf16_f32 v124, v124, v125
	v_cvt_pk_bf16_f32 v125, v126, v127
	v_cvt_pk_bf16_f32 v126, v120, v121
	v_cvt_pk_bf16_f32 v127, v122, v123
	v_cvt_pk_bf16_f32 v116, v116, v117
	v_cvt_pk_bf16_f32 v117, v118, v119
	v_cvt_pk_bf16_f32 v118, v108, v109
	v_cvt_pk_bf16_f32 v119, v110, v111
	v_cvt_pk_bf16_f32 v108, v112, v113
	s_lshl_b32 s37, s44, 8
	v_mov_b32_e32 v145, v148
	v_mov_b32_e32 v144, v147
	s_add_i32 s37, s37, s64
	v_cvt_pk_bf16_f32 v109, v114, v115
	s_lshl_b32 s39, s81, 8
	v_add_u32_e32 v154, s37, v145
	s_or_b32 s39, s39, s65
	v_ashrrev_i32_e32 v155, 31, v154
	v_lshl_add_u32 v144, v144, 3, s39
	v_lshlrev_b64 v[154:155], 16, v[154:155]
	v_cvt_pk_bf16_f32 v110, v104, v105
	v_ashrrev_i32_e32 v145, 31, v144
	v_lshl_add_u64 v[154:155], s[4:5], 0, v[154:155]
	v_lshl_add_u64 v[144:145], v[144:145], 1, v[154:155]
	v_cvt_pk_bf16_f32 v111, v106, v107
	v_add_co_u32_e32 v104, vcc, s74, v144
	s_mov_b64 s[46:47], 0x100000
	s_nop 0
	v_addc_co_u32_e32 v105, vcc, 0, v145, vcc
	global_store_dwordx4 v[104:105], v[108:111], off
	v_cvt_pk_bf16_f32 v100, v100, v101
	v_cvt_pk_bf16_f32 v101, v102, v103
	v_cvt_pk_bf16_f32 v102, v92, v93
	v_cvt_pk_bf16_f32 v103, v94, v95
	v_cvt_pk_bf16_f32 v92, v96, v97
	v_cvt_pk_bf16_f32 v93, v98, v99
	v_cvt_pk_bf16_f32 v94, v88, v89
	v_cvt_pk_bf16_f32 v95, v90, v91
	v_add_co_u32_e32 v88, vcc, s75, v144
	global_store_dwordx4 v[144:145], v[116:119], off offset:256
	s_nop 0
	v_addc_co_u32_e32 v89, vcc, 0, v145, vcc
	global_store_dwordx4 v[88:89], v[92:95], off
	v_cvt_pk_bf16_f32 v84, v84, v85
	v_cvt_pk_bf16_f32 v85, v86, v87
	v_cvt_pk_bf16_f32 v86, v76, v77
	v_cvt_pk_bf16_f32 v87, v78, v79
	v_cvt_pk_bf16_f32 v76, v80, v81
	v_cvt_pk_bf16_f32 v77, v82, v83
	v_cvt_pk_bf16_f32 v78, v72, v73
	v_cvt_pk_bf16_f32 v79, v74, v75
	v_add_co_u32_e32 v72, vcc, s76, v144
	v_lshl_add_u64 v[116:117], v[144:145], 0, s[46:47]
	s_nop 0
	v_addc_co_u32_e32 v73, vcc, 0, v145, vcc
	global_store_dwordx4 v[72:73], v[76:79], off
	v_cvt_pk_bf16_f32 v68, v68, v69
	v_cvt_pk_bf16_f32 v69, v70, v71
	v_cvt_pk_bf16_f32 v70, v64, v65
	v_cvt_pk_bf16_f32 v60, v60, v61
	v_cvt_pk_bf16_f32 v61, v62, v63
	v_cvt_pk_bf16_f32 v62, v56, v57
	v_cvt_pk_bf16_f32 v63, v58, v59
	v_add_co_u32_e32 v56, vcc, s77, v144
	s_nop 0
	v_addc_co_u32_e32 v57, vcc, 0, v145, vcc
	global_store_dwordx4 v[56:57], v[60:63], off
	v_cvt_pk_bf16_f32 v52, v52, v53
	v_cvt_pk_bf16_f32 v53, v54, v55
	v_cvt_pk_bf16_f32 v54, v44, v45
	v_cvt_pk_bf16_f32 v55, v46, v47
	v_cvt_pk_bf16_f32 v44, v48, v49
	v_cvt_pk_bf16_f32 v45, v50, v51
	v_cvt_pk_bf16_f32 v46, v40, v41
	v_cvt_pk_bf16_f32 v47, v42, v43
	v_add_co_u32_e32 v40, vcc, s78, v144
	s_nop 0
	v_addc_co_u32_e32 v41, vcc, 0, v145, vcc
	global_store_dwordx4 v[40:41], v[44:47], off
	v_cvt_pk_bf16_f32 v36, v36, v37
	v_cvt_pk_bf16_f32 v37, v38, v39
	v_cvt_pk_bf16_f32 v38, v28, v29
	v_cvt_pk_bf16_f32 v39, v30, v31
	v_cvt_pk_bf16_f32 v28, v32, v33
	v_cvt_pk_bf16_f32 v29, v34, v35
	v_cvt_pk_bf16_f32 v30, v24, v25
	v_cvt_pk_bf16_f32 v31, v26, v27
	v_add_co_u32_e32 v24, vcc, s79, v144
	s_nop 0
	v_addc_co_u32_e32 v25, vcc, 0, v145, vcc
	global_store_dwordx4 v[24:25], v[28:31], off
	v_cvt_pk_bf16_f32 v20, v20, v21
	v_cvt_pk_bf16_f32 v21, v22, v23
	v_cvt_pk_bf16_f32 v22, v12, v13
	v_cvt_pk_bf16_f32 v23, v14, v15
	v_cvt_pk_bf16_f32 v12, v16, v17
	v_cvt_pk_bf16_f32 v13, v18, v19
	v_cvt_pk_bf16_f32 v14, v8, v9
	v_cvt_pk_bf16_f32 v15, v10, v11
	v_add_co_u32_e32 v8, vcc, s80, v144
	v_cvt_pk_bf16_f32 v71, v66, v67
	s_nop 0
	v_addc_co_u32_e32 v9, vcc, 0, v145, vcc
	global_store_dwordx4 v[8:9], v[12:15], off
	v_cvt_pk_bf16_f32 v4, v4, v5
	v_cvt_pk_bf16_f32 v5, v6, v7
	v_lshl_add_u64 v[64:65], v[144:145], 0, s[26:27]
	v_cvt_pk_bf16_f32 v6, v0, v1
	global_store_dwordx4 v[64:65], v[52:55], off offset:256
	s_nop 1
	v_lshl_add_u64 v[52:53], v[144:145], 0, s[28:29]
	global_store_dwordx4 v[116:117], v[100:103], off offset:256
	s_nop 0
	global_store_dwordx4 v[52:53], v[36:39], off offset:256
	s_nop 0
	v_lshl_add_u64 v[100:101], v[144:145], 0, s[12:13]
	v_lshl_add_u64 v[36:37], v[144:145], 0, s[30:31]
	global_store_dwordx4 v[100:101], v[84:87], off offset:256
	global_store_dwordx4 v[36:37], v[20:23], off offset:256
	v_cvt_pk_bf16_f32 v7, v2, v3
	v_lshl_add_u64 v[84:85], v[144:145], 0, s[24:25]
	v_lshl_add_u64 v[20:21], v[144:145], 0, s[34:35]
	s_andn2_b64 vcc, exec, s[0:1]
	s_mov_b64 s[0:1], -1
	global_store_dwordx4 v[144:145], v[124:127], off
	global_store_dwordx4 v[84:85], v[68:71], off offset:256
	global_store_dwordx4 v[20:21], v[4:7], off offset:256
	s_cbranch_vccnz .LBB0_108
	s_andn2_b64 vcc, exec, s[6:7]
	s_cbranch_vccnz .LBB0_107
	s_barrier
	s_branch .LBB0_107

; #define LAS __attribute__((address_space(3)))
; #define MFMA32(a, b, c) __builtin_amdgcn_mfma_f32_32x32x16_bf16((a), (b), (c), 0, 0, 0)
; DEV float fexp2(float x) { return __builtin_amdgcn_exp2f(x); }
; DEV float flog2(float x) { return __builtin_amdgcn_logf(x); }
; template <int DQK> DEV void qk_tile(f32x16 (&st)[2], const LAS unsigned char* kb, const bf16x8 (&qf)[DQK / 16], int r, int h) {
;     ...
;     for (int b2 = 0; b2 < 2; ++b2)
; #pragma unroll
;         for (int s = 0; s < NS; ++s) kf[b2][s] = *(const LAS bf16x8*)(kb + (32 * b2 + r) * KSTR + 32 * s + 16 * h);
;     __builtin_amdgcn_sched_barrier(0);
; #pragma unroll
;     for (int b2 = 0; b2 < 2; ++b2) {
;         f32x16 a;
; #pragma unroll
;         for (int i = 0; i < 16; ++i) a[i] = 0.f;
; #pragma unroll
;         for (int s = 0; s < NS; ++s) a = MFMA32(kf[b2][s], qf[s], a);
;         st[b2] = a;
;     }
; DEV void sb_pass(LAS unsigned char* lds, int tid, int r, int h, int w, const bf16* Kp, size_t kpitch, const bf16* VTp, size_t vpitch, int t_hi, const bf16x8 (&qf)[4], int hi_lim, f32x16 (&o)[2]) {
;     ...
;             qk_tile<64>(st, kb, qf, r, h);
;             f32x16 spv[2]; float G[8], Gp[8];
; #pragma unroll
;             for (int b2 = 0; b2 < 2; ++b2)
; #pragma unroll
;                 for (int g = 0; g < 4; ++g) {
;                     float gs = 0.f;
; #pragma unroll
;                     for (int i = 0; i < 4; ++i) { const int key = k0 + 32 * b2 + 8 * g + 4 * h + i; const bool vis = key <= hi_lim;
;                         const float z = st[b2][4 * g + i] * 0.125f; const float e = fexp2(-fabsf(z) * LOG2E); const float s = vis ? (fmaxf(z, 0.f) + LN2 * flog2(1.f + e)) : 0.f;
;                         spv[b2][4 * g + i] = s; st[b2][4 * g + i] = vis ? (z - s) : -1e30f; gs += s; }
;                     G[4 * b2 + g] = gs;
.LBB0_182:
	s_and_b32 s35, s43, 1
	s_cmp_eq_u32 s35, 0
	s_cselect_b64 s[38:39], -1, 0
	s_add_i32 s6, s34, 64
	v_cmp_lt_i32_e32 vcc, s6, v102
	s_cbranch_vccz .LBB0_184
	s_and_b64 s[6:7], s[38:39], exec
	s_cselect_b32 s6, 0, 0x3400
	v_add_u32_e32 v36, s6, v135
	ds_read_b128 v[32:35], v36
	ds_read_b128 v[48:51], v36 offset:32
	ds_read_b128 v[52:55], v36 offset:64
	ds_read_b128 v[56:59], v36 offset:96
	ds_read_b128 v[60:63], v36 offset:4608
	ds_read_b128 v[110:113], v36 offset:4640
	ds_read_b128 v[114:117], v36 offset:4672
	ds_read_b128 v[118:121], v36 offset:4704
	s_cselect_b32 s45, 0x13800, s29
	s_setprio 1
	s_waitcnt vmcnt(3) lgkmcnt(7)
	v_mfma_f32_32x32x16_bf16 v[32:47], v[32:35], v[64:67], 0
	s_waitcnt vmcnt(2) lgkmcnt(6)
	v_mfma_f32_32x32x16_bf16 v[32:47], v[48:51], v[68:71], v[32:47]
	s_waitcnt vmcnt(1) lgkmcnt(5)
	v_mfma_f32_32x32x16_bf16 v[32:47], v[52:55], v[72:75], v[32:47]
	s_waitcnt vmcnt(0) lgkmcnt(4)
	v_mfma_f32_32x32x16_bf16 v[32:47], v[56:59], v[76:79], v[32:47]
	s_waitcnt lgkmcnt(3)
	v_mfma_f32_32x32x16_bf16 v[48:63], v[60:63], v[64:67], 0
	s_waitcnt lgkmcnt(2)
	v_mfma_f32_32x32x16_bf16 v[48:63], v[110:113], v[68:71], v[48:63]
	s_waitcnt lgkmcnt(1)
	v_mfma_f32_32x32x16_bf16 v[48:63], v[114:117], v[72:75], v[48:63]
	s_waitcnt lgkmcnt(0)
	v_mfma_f32_32x32x16_bf16 v[48:63], v[118:121], v[76:79], v[48:63]
	s_setprio 0
	s_nop 3
	v_mul_f32_e32 v89, 0x3e000000, v38
	v_mul_f32_e64 v110, |v89|, s31
	v_exp_f32_e32 v110, v110
	v_mul_f32_e32 v112, 0x3e000000, v46
	v_mul_f32_e64 v114, |v112|, s31
	v_exp_f32_e32 v114, v114
	v_add_f32_e32 v110, 1.0, v110
	v_log_f32_e32 v110, v110
	v_mul_f32_e32 v111, 0x3e000000, v39
	v_mul_f32_e64 v113, |v111|, s31
	v_max_f32_e32 v115, 0, v111
	v_mul_f32_e32 v152, 0x3f317218, v110
	v_exp_f32_e32 v110, v113
	v_add_f32_e32 v111, 1.0, v114
	v_log_f32_e32 v111, v111
	v_max_f32_e32 v123, 0, v112
	v_add_f32_e32 v110, 1.0, v110
	v_log_f32_e32 v117, v110
	v_mul_f32_e32 v110, 0x3e000000, v47
	v_mul_f32_e32 v114, 0x3f317218, v111
	v_mul_f32_e64 v111, |v110|, s31
	v_mul_f32_e32 v112, 0x3e000000, v54
	v_exp_f32_e32 v111, v111
	v_mul_f32_e64 v113, |v112|, s31
	v_exp_f32_e32 v113, v113
	v_max_f32_e32 v125, 0, v110
	v_add_f32_e32 v110, 1.0, v111
	v_mul_f32_e32 v111, 0x3e000000, v55
	v_log_f32_e32 v127, v110
	v_add_f32_e32 v110, 1.0, v113
	v_mul_f32_e64 v113, |v111|, s31
	v_log_f32_e32 v110, v110
	v_exp_f32_e32 v113, v113
	v_max_f32_e32 v129, 0, v111
	v_max_f32_e32 v121, 0, v112
	v_mul_f32_e32 v116, 0x3f317218, v110
	v_add_f32_e32 v110, 1.0, v113
	v_log_f32_e32 v131, v110
	v_mul_f32_e32 v110, 0x3e000000, v56
	v_mul_f32_e64 v111, |v110|, s31
	v_exp_f32_e32 v111, v111
	v_mul_f32_e32 v112, 0x3e000000, v57
	v_mul_f32_e64 v113, |v112|, s31
	v_exp_f32_e32 v113, v113
	v_add_f32_e32 v111, 1.0, v111
	v_log_f32_e32 v118, v111
	v_max_f32_e32 v111, 0, v110
	v_add_f32_e32 v110, 1.0, v113
	v_log_f32_e32 v110, v110
	v_fmac_f32_e32 v111, 0x3f317218, v118
	v_fma_f32 v120, v56, s28, -v111
	v_mul_f32_e32 v56, 0x3e000000, v58
	v_mul_f32_e32 v119, 0x3f317218, v110
	v_mul_f32_e64 v110, |v56|, s31
	v_max_f32_e32 v149, 0, v56
	v_mul_f32_e32 v56, 0x3e000000, v59
	v_max_f32_e32 v113, 0, v112
	v_mul_f32_e64 v112, |v56|, s31
	v_exp_f32_e32 v112, v112
	v_exp_f32_e32 v110, v110
	v_max_f32_e32 v159, 0, v56
	v_max_f32_e32 v89, 0, v89
	v_add_f32_e32 v56, 1.0, v112
	v_add_f32_e32 v110, 1.0, v110
	v_log_f32_e32 v161, v56
	v_mul_f32_e32 v56, 0x3e000000, v60
	v_mul_f32_e32 v112, 0x3e000000, v61
	v_log_f32_e32 v151, v110
	v_mul_f32_e64 v110, |v56|, s31
	v_mul_f32_e64 v118, |v112|, s31
	v_exp_f32_e32 v110, v110
	v_exp_f32_e32 v122, v118
	v_max_f32_e32 v118, 0, v56
	v_add_f32_e32 v110, 1.0, v110
	v_add_f32_e32 v56, 1.0, v122
	v_log_f32_e32 v110, v110
	v_log_f32_e32 v122, v56
	v_max_f32_e32 v56, 0, v112
	v_mul_f32_e32 v112, 0x3e000000, v62
	v_fmac_f32_e32 v118, 0x3f317218, v110
	v_mul_f32_e32 v110, 0x3f317218, v122
	v_mul_f32_e64 v122, |v112|, s31
	v_max_f32_e32 v148, 0, v112
	v_mul_f32_e32 v112, 0x3e000000, v63
	v_mul_f32_e64 v124, |v112|, s31
	v_exp_f32_e32 v124, v124
	v_exp_f32_e32 v122, v122
	v_max_f32_e32 v158, 0, v112
	v_fma_f32 v60, v60, s28, -v118
	v_add_f32_e32 v112, 1.0, v124
	v_log_f32_e32 v160, v112
	v_add_u32_e32 v112, s34, v94
	v_add_u32_e32 v157, 64, v112
	v_add_u32_e32 v154, 0x4a, v112
	v_add_u32_e32 v153, 0x43, v112
	v_add_u32_e32 v166, 0x51, v112
	v_add_u32_e32 v167, 0x53, v112
	v_add_u32_e32 v124, 0x61, v112
	v_add_u32_e32 v126, 0x63, v112
	v_mov_b32_e32 v112, v88
	v_add_f32_e32 v122, 1.0, v122
	v_pk_add_f32 v[112:113], v[112:113], v[118:119]
	v_log_f32_e32 v150, v122
	v_fma_f32 v122, v57, s28, -v113
	v_mov_b32_e32 v57, v88
	v_pk_add_f32 v[56:57], v[56:57], v[110:111]
	v_pk_fma_f32 v[118:119], v[150:151], s[30:31], v[148:149] op_sel_hi:[1,0,1]
	v_fma_f32 v128, v61, s28, -v56
	v_or_b32_e32 v61, 48, v157
	v_cmp_lt_i32_e32 vcc, v61, v91
	v_or_b32_e32 v61, 49, v157
	v_cmp_lt_i32_e64 s[6:7], v61, v91
	v_or_b32_e32 v61, 50, v157
	v_fma_f32 v58, v58, s28, -v119
	v_or_b32_e32 v110, 57, v157
	v_or_b32_e32 v111, 56, v157
	v_cmp_lt_i32_e64 s[8:9], v61, v91
	v_pk_fma_f32 v[158:159], v[160:161], s[30:31], v[158:159] op_sel_hi:[1,0,1]
	v_cndmask_b32_e32 v147, v144, v120, vcc
	v_or_b32_e32 v120, 58, v157
	v_cndmask_b32_e64 v149, v144, v58, s[8:9]
	v_or_b32_e32 v58, 51, v157
	v_cmp_lt_i32_e64 s[12:13], v111, v102
	v_cndmask_b32_e32 v57, 0, v57, vcc
	v_cmp_lt_i32_e32 vcc, v110, v102
	v_fma_f32 v59, v59, s28, -v159
	v_cndmask_b32_e64 v148, v144, v122, s[6:7]
	v_or_b32_e32 v122, 59, v157
	v_cmp_lt_i32_e64 s[10:11], v58, v91
	v_cndmask_b32_e64 v145, v144, v60, s[12:13]
	v_cndmask_b32_e64 v61, 0, v113, s[6:7]
	v_cndmask_b32_e64 v60, 0, v112, s[12:13]
	v_cndmask_b32_e32 v56, 0, v56, vcc
	v_cmp_lt_i32_e64 s[6:7], v120, v102
	v_cndmask_b32_e64 v150, v144, v59, s[10:11]
	v_pk_add_f32 v[110:111], v[60:61], v[56:57]
	v_cndmask_b32_e64 v59, 0, v119, s[8:9]
	v_cndmask_b32_e64 v58, 0, v118, s[6:7]
	v_cmp_lt_i32_e64 s[8:9], v122, v102
	v_pk_add_f32 v[112:113], v[58:59], v[110:111]
	v_cndmask_b32_e64 v111, 0, v159, s[10:11]
	v_cndmask_b32_e64 v110, 0, v158, s[8:9]
	v_fma_f32 v62, v62, s28, -v118
	v_pk_add_f32 v[118:119], v[110:111], v[112:113]
	ds_bpermute_b32 v113, v136, v119
	ds_bpermute_b32 v112, v136, v118
	v_fma_f32 v63, v63, s28, -v158
	v_cndmask_b32_e64 v60, v144, v62, s[6:7]
	v_cndmask_b32_e64 v151, v144, v63, s[8:9]
	v_cndmask_b32_e32 v57, v144, v128, vcc
	s_waitcnt lgkmcnt(0)
; DEV float shx(float v, int m, int lane) { return __builtin_bit_cast(float, __builtin_amdgcn_ds_bpermute((lane ^ m) << 2, __builtin_bit_cast(int, v))); }
; DEV float fexp2(float x) { return __builtin_amdgcn_exp2f(x); }
; DEV float flog2(float x) { return __builtin_amdgcn_logf(x); }
; DEV void sb_pass(LAS unsigned char* lds, int tid, int r, int h, int w, const bf16* Kp, size_t kpitch, const bf16* VTp, size_t vpitch, int t_hi, const bf16x8 (&qf)[4], int hi_lim, f32x16 (&o)[2]) {
;     ...
;                     for (int i = 0; i < 4; ++i) { const int key = k0 + 32 * b2 + 8 * g + 4 * h + i; const bool vis = key <= hi_lim;
;                         const float z = st[b2][4 * g + i] * 0.125f; const float e = fexp2(-fabsf(z) * LOG2E); const float s = vis ? (fmaxf(z, 0.f) + LN2 * flog2(1.f + e)) : 0.f;
;                         spv[b2][4 * g + i] = s; st[b2][4 * g + i] = vis ? (z - s) : -1e30f; gs += s; }
;                     G[4 * b2 + g] = gs;
;                 }
; #pragma unroll
;             for (int o8 = 0; o8 < 8; ++o8) Gp[o8] = shx(G[o8], 32, lane);
;             float suf[8]; float run = 0.f;
; #pragma unroll
	v_pk_add_f32 v[62:63], v[118:119], v[112:113]
	v_pk_mul_f32 v[118:119], v[48:49], s[28:29] op_sel_hi:[1,0]
	v_cmp_lt_i32_e32 vcc, v124, v102
	v_mul_f32_e64 v130, |v118|, s31
	v_exp_f32_e32 v130, v130
	v_mul_f32_e64 v155, |v119|, s31
	v_exp_f32_e32 v155, v155
	v_max_f32_e32 v118, 0, v118
	v_add_f32_e32 v130, 1.0, v130
	v_log_f32_e32 v160, v130
	v_add_f32_e32 v130, 1.0, v155
	v_log_f32_e32 v161, v130
	v_max_f32_e32 v119, 0, v119
	v_pk_add_f32 v[158:159], v[62:63], v[62:63] op_sel:[0,1] op_sel_hi:[1,0]
	v_mov_b32_e32 v120, v88
	v_pk_fma_f32 v[160:161], v[160:161], s[30:31], v[118:119] op_sel_hi:[1,0,1]
	v_or_b32_e32 v63, 42, v157
	v_or_b32_e32 v128, 32, v157
	v_pk_fma_f32 v[48:49], v[48:49], s[28:29], v[160:161] op_sel_hi:[1,0,1] neg_lo:[0,0,1] neg_hi:[0,0,1]
	v_cndmask_b32_e32 v118, 0, v161, vcc
	v_mov_b32_e32 v161, v116
	v_pk_add_f32 v[120:121], v[120:121], v[160:161]
	v_cndmask_b32_e32 v155, v144, v49, vcc
	v_cmp_lt_i32_e32 vcc, v128, v102
	v_cmp_lt_i32_e64 s[6:7], v63, v91
	v_fma_f32 v54, v54, s28, -v121
	v_cndmask_b32_e32 v156, v144, v48, vcc
	v_cndmask_b32_e64 v49, 0, v121, s[6:7]
	v_cndmask_b32_e32 v48, 0, v120, vcc
	v_pk_mul_f32 v[120:121], v[50:51], s[28:29] op_sel_hi:[1,0]
	v_cndmask_b32_e64 v63, v144, v54, s[6:7]
	v_mul_f32_e64 v116, |v120|, s31
	v_mul_f32_e64 v54, |v121|, s31
	v_exp_f32_e32 v116, v116
	v_exp_f32_e32 v54, v54
	v_max_f32_e32 v128, 0, v120
	v_max_f32_e32 v161, 0, v121
	v_add_f32_e32 v116, 1.0, v116
	v_add_f32_e32 v54, 1.0, v54
	v_log_f32_e32 v130, v116
	v_log_f32_e32 v54, v54
	v_cmp_lt_i32_e32 vcc, v126, v102
	v_or_b32_e32 v162, 34, v157
	v_pk_fma_f32 v[128:129], v[130:131], s[30:31], v[128:129] op_sel_hi:[1,0,1]
	v_fmac_f32_e32 v161, 0x3f317218, v54
	v_mov_b32_e32 v160, v128
	v_cndmask_b32_e32 v120, 0, v161, vcc
	v_pk_fma_f32 v[130:131], v[50:51], s[28:29], v[160:161] op_sel_hi:[1,0,1] neg_lo:[0,0,1] neg_hi:[0,0,1]
	v_pk_mul_f32 v[160:161], v[52:53], s[28:29] op_sel_hi:[1,0]
	v_cmp_lt_i32_e64 s[6:7], v162, v102
	v_mul_f32_e64 v50, |v160|, s31
	v_exp_f32_e32 v50, v50
	v_mul_f32_e64 v51, |v161|, s31
	v_exp_f32_e32 v54, v51
	v_max_f32_e32 v160, 0, v160
	v_add_f32_e32 v50, 1.0, v50
	v_log_f32_e32 v162, v50
	v_add_f32_e32 v50, 1.0, v54
	v_log_f32_e32 v163, v50
	v_max_f32_e32 v161, 0, v161
	v_or_b32_e32 v116, 41, v157
	v_or_b32_e32 v119, 40, v157
	v_pk_fma_f32 v[160:161], v[162:163], s[30:31], v[160:161] op_sel_hi:[1,0,1]
	v_cndmask_b32_e64 v172, v144, v130, s[6:7]
	v_cndmask_b32_e64 v50, 0, v128, s[6:7]
	v_add_f32_e32 v54, 0, v160
	v_cmp_lt_i32_e64 s[6:7], v116, v91
	v_cmp_lt_i32_e64 s[10:11], v119, v102
	v_or_b32_e32 v159, 43, v157
	v_cndmask_b32_e64 v173, 0, v161, s[6:7]
	v_cndmask_b32_e64 v54, 0, v54, s[10:11]
	v_cmp_lt_i32_e64 s[8:9], v159, v91
	v_add_f32_e32 v119, v173, v54
	v_pk_add_f32 v[162:163], v[48:49], v[118:119]
	v_cndmask_b32_e64 v51, 0, v129, s[8:9]
	v_pk_add_f32 v[162:163], v[50:51], v[162:163]
	ds_bpermute_b32 v121, v136, v163
	v_fma_f32 v48, v55, s28, -v129
	v_pk_fma_f32 v[52:53], v[52:53], s[28:29], v[160:161] op_sel_hi:[1,0,1] neg_lo:[0,0,1] neg_hi:[0,0,1]
	v_mov_b32_e32 v55, v158
	v_cndmask_b32_e64 v175, v144, v52, s[10:11]
	s_waitcnt lgkmcnt(0)
	v_pk_add_f32 v[128:129], v[120:121], v[162:163]
	ds_bpermute_b32 v54, v136, v128
	v_cndmask_b32_e64 v176, v144, v53, s[6:7]
	v_cndmask_b32_e32 v119, v144, v131, vcc
	v_add_f32_e32 v174, v103, v158
	v_or_b32_e32 v124, 24, v157
	s_waitcnt lgkmcnt(0)
	v_pk_add_f32 v[52:53], v[128:129], v[54:55]
	v_pk_mul_f32 v[128:129], v[44:45], s[28:29] op_sel_hi:[1,0]
	v_pk_add_f32 v[130:131], v[52:53], v[52:53] op_sel:[0,1] op_sel_hi:[1,0]
	v_mul_f32_e64 v55, |v128|, s31
	v_exp_f32_e32 v55, v55
	v_mul_f32_e64 v116, |v129|, s31
	v_exp_f32_e32 v116, v116
	v_max_f32_e32 v128, 0, v128
	v_add_f32_e32 v52, 1.0, v55
	v_log_f32_e32 v158, v52
	v_add_f32_e32 v52, 1.0, v116
	v_log_f32_e32 v159, v52
	v_max_f32_e32 v129, 0, v129
	v_or_b32_e32 v116, 25, v157
	v_cmp_lt_i32_e32 vcc, v116, v91
	v_pk_fma_f32 v[128:129], v[158:159], s[30:31], v[128:129] op_sel_hi:[1,0,1]
	v_cmp_lt_i32_e64 s[6:7], v124, v102
	v_add_f32_e32 v55, 0, v128
	v_pk_fma_f32 v[44:45], v[44:45], s[28:29], v[128:129] op_sel_hi:[1,0,1] neg_lo:[0,0,1] neg_hi:[0,0,1]
	v_cndmask_b32_e32 v177, 0, v129, vcc
	v_pk_mul_f32 v[128:129], v[42:43], s[28:29] op_sel_hi:[1,0]
	v_cndmask_b32_e32 v178, v144, v45, vcc
	v_mul_f32_e64 v45, |v128|, s31
	v_exp_f32_e32 v116, v45
	v_mul_f32_e64 v45, |v129|, s31
	v_exp_f32_e32 v124, v45
	v_cndmask_b32_e64 v55, 0, v55, s[6:7]
	v_cndmask_b32_e64 v179, v144, v44, s[6:7]
	v_add_f32_e32 v44, 1.0, v116
	v_add_f32_e32 v45, v177, v55
	v_add_f32_e32 v55, 1.0, v124
	v_log_f32_e32 v126, v44
	v_log_f32_e32 v55, v55
	v_max_f32_e32 v124, 0, v128
	v_max_f32_e32 v129, 0, v129
	v_pk_fma_f32 v[124:125], v[126:127], s[30:31], v[124:125] op_sel_hi:[1,0,1]
	v_fmac_f32_e32 v129, 0x3f317218, v55
	v_mov_b32_e32 v128, v124
	v_pk_mul_f32 v[158:159], v[40:41], s[28:29] op_sel_hi:[1,0]
	v_pk_fma_f32 v[126:127], v[42:43], s[28:29], v[128:129] op_sel_hi:[1,0,1] neg_lo:[0,0,1] neg_hi:[0,0,1]
	v_mul_f32_e64 v42, |v158|, s31
	v_exp_f32_e32 v42, v42
	v_mul_f32_e64 v43, |v159|, s31
	v_exp_f32_e32 v44, v43
	v_or_b32_e32 v171, 18, v157
	v_add_f32_e32 v42, 1.0, v42
	v_log_f32_e32 v160, v42
	v_add_f32_e32 v42, 1.0, v44
	v_log_f32_e32 v161, v42
	v_cmp_lt_i32_e32 vcc, v171, v102
	v_max_f32_e32 v158, 0, v158
	v_max_f32_e32 v159, 0, v159
	v_cndmask_b32_e32 v55, v144, v126, vcc
	v_cndmask_b32_e32 v42, 0, v124, vcc
	v_pk_fma_f32 v[158:159], v[160:161], s[30:31], v[158:159] op_sel_hi:[1,0,1]
	v_cmp_lt_i32_e32 vcc, v166, v102
	v_mov_b32_e32 v122, v88
	v_or_b32_e32 v168, 26, v157
	v_or_b32_e32 v169, 16, v157
	v_pk_fma_f32 v[160:161], v[40:41], s[28:29], v[158:159] op_sel_hi:[1,0,1] neg_lo:[0,0,1] neg_hi:[0,0,1]
	v_cndmask_b32_e32 v44, 0, v159, vcc
	v_mov_b32_e32 v159, v114
	v_or_b32_e32 v170, 27, v157
	v_cndmask_b32_e64 v48, v144, v48, s[8:9]
	v_pk_add_f32 v[122:123], v[122:123], v[158:159]
	v_cmp_lt_i32_e64 s[8:9], v169, v102
	v_cmp_lt_i32_e64 s[10:11], v168, v91
	v_cmp_lt_i32_e64 s[6:7], v170, v91
	v_cndmask_b32_e64 v40, 0, v122, s[8:9]
	v_cndmask_b32_e64 v41, 0, v123, s[10:11]
	v_cndmask_b32_e64 v43, 0, v125, s[6:7]
	v_pk_add_f32 v[158:159], v[40:41], v[44:45]
	v_cndmask_b32_e64 v160, v144, v160, s[8:9]
	v_pk_add_f32 v[158:159], v[42:43], v[158:159]
	ds_bpermute_b32 v163, v136, v159
	v_cmp_lt_i32_e64 s[8:9], v167, v102
	v_fma_f32 v40, v47, s28, -v125
	v_fma_f32 v46, v46, s28, -v123
	v_cndmask_b32_e64 v162, 0, v129, s[8:9]
	s_waitcnt lgkmcnt(0)
; DEV float shx(float v, int m, int lane) { return __builtin_bit_cast(float, __builtin_amdgcn_ds_bpermute((lane ^ m) << 2, __builtin_bit_cast(int, v))); }
; DEV float fexp2(float x) { return __builtin_amdgcn_exp2f(x); }
; DEV void sb_pass(LAS unsigned char* lds, int tid, int r, int h, int w, const bf16* Kp, size_t kpitch, const bf16* VTp, size_t vpitch, int t_hi, const bf16x8 (&qf)[4], int hi_lim, f32x16 (&o)[2]) {
;     ...
;             for (int o8 = 0; o8 < 8; ++o8) Gp[o8] = shx(G[o8], 32, lane);
;             float suf[8]; float run = 0.f;
; #pragma unroll
;     ...
; #pragma unroll
;             for (int b2 = 0; b2 < 2; ++b2)
; #pragma unroll
;                 for (int g = 0; g < 4; ++g) {
;                     const int o8 = 4 * b2 + g; float after = Rr + suf[o8] + (h == 0 ? Gp[o8] : 0.f);
; #pragma unroll
;                     for (int i = 3; i >= 0; --i) { const float ls = st[b2][4 * g + i];
;                         const float wgt = (ls > -1e29f) ? fexp2((ls - after) * LOG2E) : 0.f;
;                         after += spv[b2][4 * g + i]; st[b2][4 * g + i] = wgt; }
	v_pk_add_f32 v[124:125], v[162:163], v[158:159]
	ds_bpermute_b32 v122, v136, v124
	v_mov_b32_e32 v123, v130
	v_cndmask_b32_e64 v166, v144, v46, s[10:11]
	v_cndmask_b32_e64 v45, v144, v127, s[8:9]
	v_cndmask_b32_e32 v161, v144, v161, vcc
	s_waitcnt lgkmcnt(0)
	v_cndmask_b32_e64 v167, 0, v122, s[0:1]
	v_pk_add_f32 v[46:47], v[124:125], v[122:123]
	v_pk_mul_f32 v[122:123], v[36:37], s[28:29] op_sel_hi:[1,0]
	v_pk_add_f32 v[124:125], v[46:47], v[46:47] op_sel:[0,1] op_sel_hi:[1,0]
	v_mul_f32_e64 v114, |v122|, s31
	v_exp_f32_e32 v114, v114
	v_mul_f32_e64 v116, |v123|, s31
	v_exp_f32_e32 v116, v116
	v_max_f32_e32 v122, 0, v122
	v_add_f32_e32 v46, 1.0, v114
	v_log_f32_e32 v126, v46
	v_add_f32_e32 v46, 1.0, v116
	v_log_f32_e32 v127, v46
	v_max_f32_e32 v123, 0, v123
	v_or_b32_e32 v116, 9, v157
	v_cmp_lt_i32_e32 vcc, v116, v91
	v_pk_fma_f32 v[122:123], v[126:127], s[30:31], v[122:123] op_sel_hi:[1,0,1]
	v_cndmask_b32_e64 v40, v144, v40, s[6:7]
	v_add_f32_e32 v114, 0, v122
	v_pk_fma_f32 v[36:37], v[36:37], s[28:29], v[122:123] op_sel_hi:[1,0,1] neg_lo:[0,0,1] neg_hi:[0,0,1]
	v_or_b32_e32 v122, 8, v157
	v_cndmask_b32_e32 v125, 0, v123, vcc
	v_cmp_lt_i32_e64 s[6:7], v122, v102
	v_pk_mul_f32 v[122:123], v[34:35], s[28:29] op_sel_hi:[1,0]
	v_cndmask_b32_e32 v168, v144, v37, vcc
	v_mul_f32_e64 v37, |v122|, s31
	v_exp_f32_e32 v116, v37
	v_mul_f32_e64 v37, |v123|, s31
	v_exp_f32_e32 v126, v37
	v_cndmask_b32_e64 v114, 0, v114, s[6:7]
	v_cndmask_b32_e64 v169, v144, v36, s[6:7]
	v_add_f32_e32 v36, 1.0, v116
	v_add_f32_e32 v37, v125, v114
	v_add_f32_e32 v114, 1.0, v126
	v_log_f32_e32 v116, v36
	v_log_f32_e32 v126, v114
	v_max_f32_e32 v114, 0, v122
	v_max_f32_e32 v123, 0, v123
	v_pk_fma_f32 v[114:115], v[116:117], s[30:31], v[114:115] op_sel_hi:[1,0,1]
	v_or_b32_e32 v165, 2, v157
	v_fmac_f32_e32 v123, 0x3f317218, v126
	v_mov_b32_e32 v122, v114
	v_pk_fma_f32 v[34:35], v[34:35], s[28:29], v[122:123] op_sel_hi:[1,0,1] neg_lo:[0,0,1] neg_hi:[0,0,1]
	v_cmp_lt_i32_e32 vcc, v165, v102
	v_pk_mul_f32 v[116:117], v[32:33], s[28:29] op_sel_hi:[1,0]
	v_or_b32_e32 v164, 11, v157
	v_cndmask_b32_e32 v122, v144, v34, vcc
	v_mul_f32_e64 v34, |v116|, s31
	v_exp_f32_e32 v34, v34
	v_mul_f32_e64 v36, |v117|, s31
	v_exp_f32_e32 v36, v36
	v_max_f32_e32 v116, 0, v116
	v_add_f32_e32 v34, 1.0, v34
	v_log_f32_e32 v128, v34
	v_add_f32_e32 v34, 1.0, v36
	v_log_f32_e32 v129, v34
	v_max_f32_e32 v117, 0, v117
	v_cndmask_b32_e32 v126, 0, v114, vcc
	v_cmp_lt_i32_e32 vcc, v157, v101
	v_pk_fma_f32 v[116:117], v[128:129], s[30:31], v[116:117] op_sel_hi:[1,0,1]
	v_cmp_lt_i32_e64 s[8:9], v157, v102
	v_pk_fma_f32 v[32:33], v[32:33], s[28:29], v[116:117] op_sel_hi:[1,0,1] neg_lo:[0,0,1] neg_hi:[0,0,1]
	v_cndmask_b32_e32 v36, 0, v117, vcc
	v_mov_b32_e32 v117, v152
	v_pk_add_f32 v[116:117], v[88:89], v[116:117]
	v_cmp_lt_i32_e64 s[10:11], v154, v91
	v_cmp_lt_i32_e64 s[6:7], v164, v91
	v_cndmask_b32_e64 v128, 0, v116, s[8:9]
	v_cndmask_b32_e64 v129, 0, v117, s[10:11]
	v_add_f32_e32 v52, v103, v130
	v_cndmask_b32_e64 v127, 0, v115, s[6:7]
	v_pk_add_f32 v[130:131], v[128:129], v[36:37]
	v_cndmask_b32_e64 v114, v144, v32, s[8:9]
	v_pk_add_f32 v[130:131], v[126:127], v[130:131]
	ds_bpermute_b32 v159, v136, v131
	v_cmp_lt_i32_e64 s[8:9], v153, v102
	v_cndmask_b32_e32 v89, v144, v33, vcc
	v_fma_f32 v33, v38, s28, -v117
	v_cndmask_b32_e64 v158, 0, v123, s[8:9]
	v_cndmask_b32_e64 v37, v144, v35, s[8:9]
	s_waitcnt lgkmcnt(0)
	v_pk_add_f32 v[34:35], v[158:159], v[130:131]
	ds_bpermute_b32 v32, v136, v34
	v_cndmask_b32_e64 v38, v144, v33, s[10:11]
	v_mov_b32_e32 v33, v124
	v_fma_f32 v39, v39, s28, -v115
	v_cmp_lt_f32_e32 vcc, s33, v37
	s_waitcnt lgkmcnt(0)
	v_cndmask_b32_e64 v115, 0, v32, s[0:1]
	v_pk_add_f32 v[32:33], v[34:35], v[32:33]
	v_add_f32_e32 v46, v103, v124
	v_add_f32_e32 v34, v103, v33
	v_add_f32_e32 v34, v115, v34
	v_sub_f32_e32 v35, v37, v34
	v_add_f32_e32 v34, v158, v34
	v_mul_f32_e32 v35, 0x3fb8aa3b, v35
	v_sub_f32_e32 v115, v122, v34
	v_exp_f32_e32 v35, v35
	v_mul_f32_e32 v115, 0x3fb8aa3b, v115
	v_exp_f32_e32 v115, v115
	v_add_f32_e32 v34, v126, v34
	v_cndmask_b32_e32 v35, 0, v35, vcc
	v_cmp_lt_f32_e32 vcc, s33, v122
	v_cndmask_b32_e64 v116, 0, v159, s[0:1]
	v_cndmask_b32_e64 v39, v144, v39, s[6:7]
	v_cndmask_b32_e32 v37, 0, v115, vcc
	v_sub_f32_e32 v115, v89, v34
	v_mul_f32_e32 v115, 0x3fb8aa3b, v115
	v_exp_f32_e32 v115, v115
	v_add_f32_e32 v34, v36, v34
	v_sub_f32_e32 v34, v114, v34
	v_add_f32_e32 v46, v116, v46
	v_mul_f32_e32 v34, 0x3fb8aa3b, v34
	v_cmp_lt_f32_e32 vcc, s33, v89
	v_sub_f32_e32 v89, v39, v46
	v_exp_f32_e32 v34, v34
	v_mul_f32_e32 v89, 0x3fb8aa3b, v89
	v_add_f32_e32 v46, v127, v46
	v_cndmask_b32_e32 v36, 0, v115, vcc
	v_cmp_lt_f32_e32 vcc, s33, v114
	v_exp_f32_e32 v89, v89
	v_sub_f32_e32 v114, v38, v46
	v_mul_f32_e32 v114, 0x3fb8aa3b, v114
	v_exp_f32_e32 v114, v114
	v_cndmask_b32_e32 v34, 0, v34, vcc
	v_cmp_lt_f32_e32 vcc, s33, v39
	v_add_f32_e32 v46, v129, v46
	v_add_f32_e32 v47, v103, v47
	v_cndmask_b32_e32 v39, 0, v89, vcc
	v_sub_f32_e32 v89, v168, v46
	v_add_f32_e32 v46, v125, v46
	v_cmp_lt_f32_e32 vcc, s33, v38
	v_mul_f32_e32 v89, 0x3fb8aa3b, v89
	v_sub_f32_e32 v46, v169, v46
	v_add_f32_e32 v47, v167, v47
	v_cndmask_b32_e32 v38, 0, v114, vcc
	v_exp_f32_e32 v89, v89
	v_mul_f32_e32 v46, 0x3fb8aa3b, v46
	v_sub_f32_e32 v114, v45, v47
	v_add_f32_e32 v47, v162, v47
	v_exp_f32_e32 v46, v46
	v_mul_f32_e32 v114, 0x3fb8aa3b, v114
	v_sub_f32_e32 v115, v55, v47
	v_add_f32_e32 v42, v42, v47
	v_exp_f32_e32 v114, v114
	v_mul_f32_e32 v115, 0x3fb8aa3b, v115
	v_sub_f32_e32 v47, v161, v42
	v_cmp_lt_f32_e32 vcc, s33, v168
	v_exp_f32_e32 v115, v115
	v_mul_f32_e32 v47, 0x3fb8aa3b, v47
; #define LAS __attribute__((address_space(3)))
; #define MFMA32(a, b, c) __builtin_amdgcn_mfma_f32_32x32x16_bf16((a), (b), (c), 0, 0, 0)
; DEV float fexp2(float x) { return __builtin_amdgcn_exp2f(x); }
; DEV void pv_load(bf16x8 (&vf)[2][4], const LAS unsigned char* vb, int r, int h) {
; #pragma unroll
;     for (int db = 0; db < 2; ++db)
; #pragma unroll
;         for (int f = 0; f < 4; ++f) { const LAS unsigned char* p = vb + (32 * db + r) * 136 + (16 * f + 4 * h) * 2;
;             const s16x4 lo = *(const LAS s16x4*)p, hi = *(const LAS s16x4*)(p + 16);
;             vf[db][f] = __builtin_shufflevector(lo, hi, 0, 1, 2, 3, 4, 5, 6, 7); }
;     __builtin_amdgcn_sched_barrier(0);
; }
; DEV void pv_mma(f32x16 (&o)[2], const bf16x8 (&vf)[2][4], const bf16x8 (&pf)[4]) {
;     __builtin_amdgcn_sched_barrier(0);
; #pragma unroll
;     for (int f = 0; f < 4; ++f)
; #pragma unroll
;         for (int db = 0; db < 2; ++db) o[db] = MFMA32(vf[db][f], pf[f], o[db]);
; DEV void sb_pass(LAS unsigned char* lds, int tid, int r, int h, int w, const bf16* Kp, size_t kpitch, const bf16* VTp, size_t vpitch, int t_hi, const bf16x8 (&qf)[4], int hi_lim, f32x16 (&o)[2]) {
;     ...
;                     const int o8 = 4 * b2 + g; float after = Rr + suf[o8] + (h == 0 ? Gp[o8] : 0.f);
; #pragma unroll
;                     for (int i = 3; i >= 0; --i) { const float ls = st[b2][4 * g + i];
;                         const float wgt = (ls > -1e29f) ? fexp2((ls - after) * LOG2E) : 0.f;
;                         after += spv[b2][4 * g + i]; st[b2][4 * g + i] = wgt; }
;                 }
;             Rr += run;
;             bf16x8 pf[4]; pack_p(pf, st);
;             pv_tile(o, vb, pf, r, h);
	v_cndmask_b32_e32 v89, 0, v89, vcc
	v_cmp_lt_f32_e32 vcc, s33, v169
	v_exp_f32_e32 v47, v47
	v_cndmask_b32_e64 v163, 0, v163, s[0:1]
	v_cndmask_b32_e32 v46, 0, v46, vcc
	v_cmp_lt_f32_e32 vcc, s33, v45
	v_add_f32_e32 v42, v44, v42
	v_sub_f32_e32 v42, v160, v42
	v_cndmask_b32_e32 v45, 0, v114, vcc
	v_cmp_lt_f32_e32 vcc, s33, v55
	v_mul_f32_e32 v42, 0x3fb8aa3b, v42
	v_exp_f32_e32 v42, v42
	v_cndmask_b32_e32 v55, 0, v115, vcc
	v_cmp_lt_f32_e32 vcc, s33, v161
	v_cndmask_b32_e64 v114, 0, v121, s[0:1]
	v_add_f32_e32 v114, v114, v174
	v_cndmask_b32_e32 v44, 0, v47, vcc
	v_add_f32_e32 v47, v163, v52
	v_sub_f32_e32 v52, v40, v47
	v_mul_f32_e32 v52, 0x3fb8aa3b, v52
	v_exp_f32_e32 v52, v52
	v_cmp_lt_f32_e32 vcc, s33, v160
	v_add_f32_e32 v43, v43, v47
	v_sub_f32_e32 v47, v166, v43
	v_cndmask_b32_e32 v42, 0, v42, vcc
	v_cmp_lt_f32_e32 vcc, s33, v40
	v_add_f32_e32 v41, v41, v43
	v_mul_f32_e32 v47, 0x3fb8aa3b, v47
	v_cndmask_b32_e32 v40, 0, v52, vcc
	v_sub_f32_e32 v43, v178, v41
	v_add_f32_e32 v41, v177, v41
	v_add_f32_e32 v52, v103, v53
	v_cndmask_b32_e64 v53, 0, v54, s[0:1]
	v_exp_f32_e32 v47, v47
	v_mul_f32_e32 v43, 0x3fb8aa3b, v43
	v_sub_f32_e32 v41, v179, v41
	v_add_f32_e32 v52, v53, v52
	v_exp_f32_e32 v43, v43
	v_mul_f32_e32 v41, 0x3fb8aa3b, v41
	v_sub_f32_e32 v53, v119, v52
	v_add_f32_e32 v52, v120, v52
	v_exp_f32_e32 v41, v41
	v_mul_f32_e32 v53, 0x3fb8aa3b, v53
	v_sub_f32_e32 v54, v172, v52
	v_add_f32_e32 v50, v50, v52
	v_cmp_lt_f32_e32 vcc, s33, v166
	v_exp_f32_e32 v53, v53
	v_mul_f32_e32 v54, 0x3fb8aa3b, v54
	v_sub_f32_e32 v52, v155, v50
	v_add_f32_e32 v50, v118, v50
	v_cndmask_b32_e32 v47, 0, v47, vcc
	v_cmp_lt_f32_e32 vcc, s33, v178
	v_exp_f32_e32 v54, v54
	v_mul_f32_e32 v52, 0x3fb8aa3b, v52
	v_sub_f32_e32 v50, v156, v50
	v_cndmask_b32_e32 v43, 0, v43, vcc
	v_cmp_lt_f32_e32 vcc, s33, v179
	v_exp_f32_e32 v52, v52
	v_mul_f32_e32 v50, 0x3fb8aa3b, v50
	v_sub_f32_e32 v115, v48, v114
	v_add_f32_e32 v51, v51, v114
	v_cndmask_b32_e32 v41, 0, v41, vcc
	v_cmp_lt_f32_e32 vcc, s33, v119
	v_exp_f32_e32 v50, v50
	v_mul_f32_e32 v115, 0x3fb8aa3b, v115
	v_sub_f32_e32 v114, v63, v51
	v_add_f32_e32 v49, v49, v51
	v_cndmask_b32_e32 v53, 0, v53, vcc
	v_cmp_lt_f32_e32 vcc, s33, v172
	v_exp_f32_e32 v115, v115
	v_mul_f32_e32 v114, 0x3fb8aa3b, v114
	v_sub_f32_e32 v51, v176, v49
	v_add_f32_e32 v49, v173, v49
	v_add_f32_e32 v62, v103, v62
	v_cndmask_b32_e64 v113, 0, v113, s[0:1]
	v_cndmask_b32_e32 v54, 0, v54, vcc
	v_cmp_lt_f32_e32 vcc, s33, v155
	v_exp_f32_e32 v114, v114
	v_mul_f32_e32 v51, 0x3fb8aa3b, v51
	v_sub_f32_e32 v49, v175, v49
	v_add_f32_e32 v62, v113, v62
	v_cndmask_b32_e32 v52, 0, v52, vcc
	v_cmp_lt_f32_e32 vcc, s33, v156
	v_exp_f32_e32 v51, v51
	v_mul_f32_e32 v49, 0x3fb8aa3b, v49
	v_sub_f32_e32 v113, v150, v62
	v_add_f32_e32 v62, v111, v62
	v_cndmask_b32_e32 v50, 0, v50, vcc
	v_cmp_lt_f32_e32 vcc, s33, v48
	v_exp_f32_e32 v49, v49
	v_mul_f32_e32 v113, 0x3fb8aa3b, v113
	v_sub_f32_e32 v111, v149, v62
	v_add_f32_e32 v59, v59, v62
	v_cndmask_b32_e32 v48, 0, v115, vcc
	v_cmp_lt_f32_e32 vcc, s33, v63
	v_exp_f32_e32 v113, v113
	v_mul_f32_e32 v111, 0x3fb8aa3b, v111
	v_sub_f32_e32 v62, v148, v59
	v_add_f32_e32 v59, v61, v59
	v_cndmask_b32_e32 v63, 0, v114, vcc
	v_cmp_lt_f32_e32 vcc, s33, v176
	v_exp_f32_e32 v111, v111
	v_mul_f32_e32 v62, 0x3fb8aa3b, v62
	v_sub_f32_e32 v59, v147, v59
	v_cndmask_b32_e32 v51, 0, v51, vcc
	v_cmp_lt_f32_e32 vcc, s33, v175
	v_exp_f32_e32 v62, v62
	v_mul_f32_e32 v59, 0x3fb8aa3b, v59
	v_cndmask_b32_e32 v49, 0, v49, vcc
	v_cmp_lt_f32_e32 vcc, s33, v150
	v_exp_f32_e32 v59, v59
	v_cndmask_b32_e64 v61, 0, v112, s[0:1]
	v_cndmask_b32_e32 v123, 0, v113, vcc
	v_cmp_lt_f32_e32 vcc, s33, v149
	v_add_f32_e32 v32, v32, v33
	v_cvt_pk_bf16_f32 v33, v37, v35
	v_cndmask_b32_e32 v124, 0, v111, vcc
	v_cmp_lt_f32_e32 vcc, s33, v148
	v_cvt_pk_bf16_f32 v35, v38, v39
	v_cvt_pk_bf16_f32 v37, v55, v45
	v_cndmask_b32_e32 v122, 0, v62, vcc
	v_cmp_lt_f32_e32 vcc, s33, v147
	v_cvt_pk_bf16_f32 v38, v41, v43
	v_cvt_pk_bf16_f32 v39, v47, v40
	v_cndmask_b32_e32 v125, 0, v59, vcc
	v_add_f32_e32 v59, 0, v103
	v_add_f32_e32 v59, v59, v61
	v_sub_f32_e32 v61, v151, v59
	v_add_f32_e32 v59, v110, v59
	v_mul_f32_e32 v61, 0x3fb8aa3b, v61
	v_sub_f32_e32 v62, v60, v59
	v_add_f32_e32 v58, v58, v59
	v_exp_f32_e32 v61, v61
	v_mul_f32_e32 v62, 0x3fb8aa3b, v62
	v_sub_f32_e32 v59, v57, v58
	v_add_f32_e32 v56, v56, v58
	v_exp_f32_e32 v62, v62
	v_mul_f32_e32 v59, 0x3fb8aa3b, v59
	v_sub_f32_e32 v56, v145, v56
	v_exp_f32_e32 v59, v59
	v_mul_f32_e32 v56, 0x3fb8aa3b, v56
	v_cmp_lt_f32_e32 vcc, s33, v151
	v_exp_f32_e32 v56, v56
	v_add_f32_e32 v103, v103, v32
	v_cndmask_b32_e32 v126, 0, v61, vcc
	v_cmp_lt_f32_e32 vcc, s33, v60
	v_add_u32_e32 v60, s45, v137
	v_cvt_pk_bf16_f32 v32, v34, v36
	v_cndmask_b32_e32 v127, 0, v62, vcc
	v_cmp_lt_f32_e32 vcc, s33, v57
	v_cvt_pk_bf16_f32 v34, v46, v89
	v_add_u32_e32 v89, 0x1000, v60
	v_cndmask_b32_e32 v128, 0, v59, vcc
	v_cmp_lt_f32_e32 vcc, s33, v145
	v_cvt_pk_bf16_f32 v36, v42, v44
	v_cvt_pk_bf16_f32 v40, v50, v52
	v_cndmask_b32_e32 v129, 0, v56, vcc
	v_cvt_pk_bf16_f32 v41, v54, v53
	v_cvt_pk_bf16_f32 v42, v49, v51
	v_cvt_pk_bf16_f32 v43, v63, v48
	ds_read2_b64 v[44:47], v60 offset1:2
	ds_read2_b64 v[48:51], v60 offset0:4 offset1:6
	ds_read2_b64 v[52:55], v60 offset0:8 offset1:10
	ds_read2_b64 v[56:59], v60 offset0:12 offset1:14
	ds_read2_b64 v[60:63], v89 offset0:32 offset1:34
	ds_read2_b64 v[110:113], v89 offset0:36 offset1:38
	ds_read2_b64 v[114:117], v89 offset0:40 offset1:42
	ds_read2_b64 v[118:121], v89 offset0:44 offset1:46
	v_cvt_pk_bf16_f32 v122, v125, v122
	v_cvt_pk_bf16_f32 v123, v124, v123
	v_cvt_pk_bf16_f32 v124, v129, v128
	v_cvt_pk_bf16_f32 v125, v127, v126
	s_setprio 1
	s_waitcnt lgkmcnt(7)
	v_mfma_f32_32x32x16_bf16 v[16:31], v[44:47], v[32:35], v[16:31]
	s_waitcnt lgkmcnt(3)
	v_mfma_f32_32x32x16_bf16 v[0:15], v[60:63], v[32:35], v[0:15]
	v_mfma_f32_32x32x16_bf16 v[16:31], v[48:51], v[36:39], v[16:31]
	s_waitcnt lgkmcnt(2)
	v_mfma_f32_32x32x16_bf16 v[0:15], v[110:113], v[36:39], v[0:15]
	v_mfma_f32_32x32x16_bf16 v[16:31], v[52:55], v[40:43], v[16:31]
	s_waitcnt lgkmcnt(1)
	v_mfma_f32_32x32x16_bf16 v[0:15], v[114:117], v[40:43], v[0:15]
	v_mfma_f32_32x32x16_bf16 v[16:31], v[56:59], v[122:125], v[16:31]
	s_waitcnt lgkmcnt(0)
	v_mfma_f32_32x32x16_bf16 v[0:15], v[118:121], v[122:125], v[0:15]
	s_setprio 0

; __device__ __forceinline__ unsigned pk2_(float lo, float hi) { return f2bf_(lo) | (f2bf_(hi) << 16); }
; template <int ACT> __device__ __forceinline__ float act_f(float v) {
;     if (ACT == 2) { const float t = fmaxf(v, 0.f); return t * t; }
;     __device__ __forceinline__ void operator()(const f32x4 (&acc)[2][2][4][2], const Unit& u, int wr, int wc, int fr, int fq) const {
;     ...
;             for (int m = 0; m < 4; ++m) { bf16_t* rowp = O + (size_t)(row0 + ai * HALF + m * 16) * ldc + col0;
; #pragma unroll
;                 for (int bj = 0; bj < 2; ++bj) { f32x4 v0 = acc[ai][bj][m][0], v1 = acc[ai][bj][m][1];
;                     if (bias) { v0 += *(const f32x4*)(bias + col0 + bj * HALF); v1 += *(const f32x4*)(bias + col0 + bj * HALF + 4); }
;                     u32x4 w; w.x = pk2_(act_f<ACT>(v0[0]), act_f<ACT>(v0[1])); w.y = pk2_(act_f<ACT>(v0[2]), act_f<ACT>(v0[3]));
;                     w.z = pk2_(act_f<ACT>(v1[0]), act_f<ACT>(v1[1])); w.w = pk2_(act_f<ACT>(v1[2]), act_f<ACT>(v1[3]));
;                     *(u32x4*)(rowp + bj * HALF) = w; } }
.LBB0_393:
	v_mov_b32_e32 v144, v146
	v_mov_b32_e32 v145, v147
	s_lshl_b32 s35, s42, 8
	s_add_i32 s35, s35, s57
	v_add_u32_e32 v144, s35, v144
	s_lshl_b32 s35, s72, 8
	s_or_b32 s35, s35, s60
	v_lshl_add_u32 v152, v145, 3, s35
	v_ashrrev_i32_e32 v145, 31, v144
	v_lshlrev_b64 v[144:145], 13, v[144:145]
	v_ashrrev_i32_e32 v153, 31, v152
	v_lshl_add_u64 v[144:145], s[20:21], 0, v[144:145]
	v_lshl_add_u64 v[144:145], v[152:153], 1, v[144:145]
	v_max_f32_e32 v152, 0, v125
	v_max_f32_e32 v125, v126, v126
	v_max_f32_e32 v126, v127, v127
	v_max_f32_e32 v153, 0, v126
	v_pk_mul_f32 v[126:127], v[152:153], v[152:153]
	v_max_f32_e32 v152, 0, v121
	v_max_f32_e32 v121, v122, v122
	v_max_f32_e32 v122, v123, v123
	v_max_f32_e32 v153, 0, v122
	v_max_f32_e32 v124, 0, v124
	v_max_f32_e32 v125, 0, v125
	v_max_f32_e32 v120, 0, v120
	v_max_f32_e32 v121, 0, v121
	v_pk_mul_f32 v[122:123], v[152:153], v[152:153]
	v_pk_mul_f32 v[124:125], v[124:125], v[124:125]
	v_pk_mul_f32 v[120:121], v[120:121], v[120:121]
	v_cvt_pk_bf16_f32 v123, v121, v123
	v_cvt_pk_bf16_f32 v122, v120, v122
	v_cvt_pk_bf16_f32 v121, v125, v127
	v_cvt_pk_bf16_f32 v120, v124, v126
	global_store_dwordx4 v[144:145], v[120:123], off
	s_nop 1
	v_max_f32_e32 v120, 0, v117
	v_max_f32_e32 v117, v118, v118
	v_max_f32_e32 v118, v119, v119
	v_max_f32_e32 v121, 0, v118
	v_pk_mul_f32 v[118:119], v[120:121], v[120:121]
	v_max_f32_e32 v120, 0, v113
	v_max_f32_e32 v113, v114, v114
	v_max_f32_e32 v114, v115, v115
	v_max_f32_e32 v121, 0, v114
	v_max_f32_e32 v116, 0, v116
	v_max_f32_e32 v117, 0, v117
	v_max_f32_e32 v112, 0, v112
	v_max_f32_e32 v113, 0, v113
	v_pk_mul_f32 v[114:115], v[120:121], v[120:121]
	v_pk_mul_f32 v[116:117], v[116:117], v[116:117]
	v_pk_mul_f32 v[112:113], v[112:113], v[112:113]
	v_cvt_pk_bf16_f32 v115, v113, v115
	v_cvt_pk_bf16_f32 v114, v112, v114
	v_cvt_pk_bf16_f32 v113, v117, v119
	v_cvt_pk_bf16_f32 v112, v116, v118
	global_store_dwordx4 v[144:145], v[112:115], off offset:256
	s_nop 1
	v_max_f32_e32 v114, 0, v109
	v_max_f32_e32 v109, v110, v110
	v_max_f32_e32 v110, v111, v111
	v_max_f32_e32 v115, 0, v110
	v_pk_mul_f32 v[110:111], v[114:115], v[114:115]
	v_max_f32_e32 v114, 0, v105
	v_max_f32_e32 v105, v106, v106
	v_max_f32_e32 v106, v107, v107
	v_max_f32_e32 v115, 0, v106
	v_max_f32_e32 v108, 0, v108
	v_max_f32_e32 v109, 0, v109
	v_max_f32_e32 v104, 0, v104
	v_max_f32_e32 v105, 0, v105
	v_pk_mul_f32 v[106:107], v[114:115], v[114:115]
	v_pk_mul_f32 v[108:109], v[108:109], v[108:109]
	v_pk_mul_f32 v[104:105], v[104:105], v[104:105]
	s_mov_b32 s35, 0x20000
	v_cvt_pk_bf16_f32 v106, v104, v106
	v_cvt_pk_bf16_f32 v104, v108, v110
	v_add_co_u32_e32 v108, vcc, s35, v144
	v_cvt_pk_bf16_f32 v107, v105, v107
	v_cvt_pk_bf16_f32 v105, v109, v111
	v_addc_co_u32_e32 v109, vcc, 0, v145, vcc
	global_store_dwordx4 v[108:109], v[104:107], off
	s_nop 1
	v_max_f32_e32 v104, 0, v101
	v_max_f32_e32 v101, v102, v102
	v_max_f32_e32 v102, v103, v103
	v_max_f32_e32 v105, 0, v102
	v_pk_mul_f32 v[102:103], v[104:105], v[104:105]
	v_max_f32_e32 v104, 0, v97
	v_max_f32_e32 v97, v98, v98
	v_max_f32_e32 v98, v99, v99
	v_max_f32_e32 v105, 0, v98
	v_max_f32_e32 v100, 0, v100
	v_max_f32_e32 v101, 0, v101
	v_max_f32_e32 v96, 0, v96
	v_max_f32_e32 v97, 0, v97
	v_pk_mul_f32 v[98:99], v[104:105], v[104:105]
	v_pk_mul_f32 v[100:101], v[100:101], v[100:101]
	v_pk_mul_f32 v[96:97], v[96:97], v[96:97]
	s_mov_b64 s[44:45], 0x20000
	v_lshl_add_u64 v[112:113], v[144:145], 0, s[44:45]
	v_cvt_pk_bf16_f32 v99, v97, v99
	v_cvt_pk_bf16_f32 v98, v96, v98
	v_cvt_pk_bf16_f32 v97, v101, v103
	v_cvt_pk_bf16_f32 v96, v100, v102
	global_store_dwordx4 v[112:113], v[96:99], off offset:256
	s_nop 1
	v_max_f32_e32 v98, 0, v93
	v_max_f32_e32 v93, v94, v94
	v_max_f32_e32 v94, v95, v95
	v_max_f32_e32 v99, 0, v94
	v_pk_mul_f32 v[94:95], v[98:99], v[98:99]
	v_max_f32_e32 v98, 0, v89
	v_max_f32_e32 v89, v90, v90
	v_max_f32_e32 v90, v91, v91
	v_max_f32_e32 v99, 0, v90
	v_max_f32_e32 v92, 0, v92
	v_max_f32_e32 v93, 0, v93
	v_max_f32_e32 v88, 0, v88
	v_max_f32_e32 v89, 0, v89
	v_pk_mul_f32 v[90:91], v[98:99], v[98:99]
	v_pk_mul_f32 v[92:93], v[92:93], v[92:93]
	v_pk_mul_f32 v[88:89], v[88:89], v[88:89]
	s_mov_b32 s35, 0x40000
	v_cvt_pk_bf16_f32 v90, v88, v90
	v_cvt_pk_bf16_f32 v88, v92, v94
	v_add_co_u32_e32 v92, vcc, s35, v144
	v_cvt_pk_bf16_f32 v91, v89, v91
	v_cvt_pk_bf16_f32 v89, v93, v95
	v_addc_co_u32_e32 v93, vcc, 0, v145, vcc
	global_store_dwordx4 v[92:93], v[88:91], off
	s_nop 1
	v_max_f32_e32 v88, 0, v85
	v_max_f32_e32 v85, v86, v86
	v_max_f32_e32 v86, v87, v87
	v_max_f32_e32 v89, 0, v86
	v_pk_mul_f32 v[86:87], v[88:89], v[88:89]
	v_max_f32_e32 v88, 0, v81
	v_max_f32_e32 v81, v82, v82
	v_max_f32_e32 v82, v83, v83
	v_max_f32_e32 v89, 0, v82
	v_max_f32_e32 v84, 0, v84
	v_max_f32_e32 v85, 0, v85
	v_max_f32_e32 v80, 0, v80
	v_max_f32_e32 v81, 0, v81
	v_pk_mul_f32 v[82:83], v[88:89], v[88:89]
	v_pk_mul_f32 v[84:85], v[84:85], v[84:85]
	v_pk_mul_f32 v[80:81], v[80:81], v[80:81]
	s_mov_b64 s[44:45], 0x40000
	v_lshl_add_u64 v[96:97], v[144:145], 0, s[44:45]
	v_cvt_pk_bf16_f32 v83, v81, v83
	v_cvt_pk_bf16_f32 v82, v80, v82
	v_cvt_pk_bf16_f32 v81, v85, v87
	v_cvt_pk_bf16_f32 v80, v84, v86
	global_store_dwordx4 v[96:97], v[80:83], off offset:256
	s_nop 1
	v_max_f32_e32 v82, 0, v77
	v_max_f32_e32 v77, v78, v78
	v_max_f32_e32 v78, v79, v79
	v_max_f32_e32 v83, 0, v78
	v_pk_mul_f32 v[78:79], v[82:83], v[82:83]
	v_max_f32_e32 v82, 0, v73
	v_max_f32_e32 v73, v74, v74
	v_max_f32_e32 v74, v75, v75
	v_max_f32_e32 v83, 0, v74
	v_max_f32_e32 v76, 0, v76
	v_max_f32_e32 v77, 0, v77
	v_max_f32_e32 v72, 0, v72
	v_max_f32_e32 v73, 0, v73
	v_pk_mul_f32 v[74:75], v[82:83], v[82:83]
; __device__ __forceinline__ unsigned pk2_(float lo, float hi) { return f2bf_(lo) | (f2bf_(hi) << 16); }
; template <int ACT> __device__ __forceinline__ float act_f(float v) {
;     if (ACT == 2) { const float t = fmaxf(v, 0.f); return t * t; }
;     __device__ __forceinline__ void operator()(const f32x4 (&acc)[2][2][4][2], const Unit& u, int wr, int wc, int fr, int fq) const {
;     ...
;             for (int m = 0; m < 4; ++m) { bf16_t* rowp = O + (size_t)(row0 + ai * HALF + m * 16) * ldc + col0;
; #pragma unroll
;                 for (int bj = 0; bj < 2; ++bj) { f32x4 v0 = acc[ai][bj][m][0], v1 = acc[ai][bj][m][1];
;                     if (bias) { v0 += *(const f32x4*)(bias + col0 + bj * HALF); v1 += *(const f32x4*)(bias + col0 + bj * HALF + 4); }
;                     u32x4 w; w.x = pk2_(act_f<ACT>(v0[0]), act_f<ACT>(v0[1])); w.y = pk2_(act_f<ACT>(v0[2]), act_f<ACT>(v0[3]));
;                     w.z = pk2_(act_f<ACT>(v1[0]), act_f<ACT>(v1[1])); w.w = pk2_(act_f<ACT>(v1[2]), act_f<ACT>(v1[3]));
;                     *(u32x4*)(rowp + bj * HALF) = w; } }
	v_pk_mul_f32 v[76:77], v[76:77], v[76:77]
	v_pk_mul_f32 v[72:73], v[72:73], v[72:73]
	s_mov_b32 s35, 0x60000
	v_cvt_pk_bf16_f32 v74, v72, v74
	v_cvt_pk_bf16_f32 v72, v76, v78
	v_add_co_u32_e32 v76, vcc, s35, v144
	v_cvt_pk_bf16_f32 v75, v73, v75
	v_cvt_pk_bf16_f32 v73, v77, v79
	v_addc_co_u32_e32 v77, vcc, 0, v145, vcc
	global_store_dwordx4 v[76:77], v[72:75], off
	s_nop 1
	v_max_f32_e32 v72, 0, v69
	v_max_f32_e32 v69, v70, v70
	v_max_f32_e32 v70, v71, v71
	v_max_f32_e32 v73, 0, v70
	v_pk_mul_f32 v[70:71], v[72:73], v[72:73]
	v_max_f32_e32 v72, 0, v65
	v_max_f32_e32 v65, v66, v66
	v_max_f32_e32 v66, v67, v67
	v_max_f32_e32 v73, 0, v66
	v_max_f32_e32 v68, 0, v68
	v_max_f32_e32 v69, 0, v69
	v_max_f32_e32 v64, 0, v64
	v_max_f32_e32 v65, 0, v65
	v_pk_mul_f32 v[66:67], v[72:73], v[72:73]
	v_pk_mul_f32 v[68:69], v[68:69], v[68:69]
	v_pk_mul_f32 v[64:65], v[64:65], v[64:65]
	s_mov_b64 s[44:45], 0x60000
	v_lshl_add_u64 v[80:81], v[144:145], 0, s[44:45]
	v_cvt_pk_bf16_f32 v67, v65, v67
	v_cvt_pk_bf16_f32 v66, v64, v66
	v_cvt_pk_bf16_f32 v65, v69, v71
	v_cvt_pk_bf16_f32 v64, v68, v70
	global_store_dwordx4 v[80:81], v[64:67], off offset:256
	s_nop 1
	v_max_f32_e32 v66, 0, v61
	v_max_f32_e32 v61, v62, v62
	v_max_f32_e32 v62, v63, v63
	v_max_f32_e32 v67, 0, v62
	v_pk_mul_f32 v[62:63], v[66:67], v[66:67]
	v_max_f32_e32 v66, 0, v57
	v_max_f32_e32 v57, v58, v58
	v_max_f32_e32 v58, v59, v59
	v_max_f32_e32 v67, 0, v58
	v_max_f32_e32 v60, 0, v60
	v_max_f32_e32 v61, 0, v61
	v_max_f32_e32 v56, 0, v56
	v_max_f32_e32 v57, 0, v57
	v_pk_mul_f32 v[58:59], v[66:67], v[66:67]
	v_pk_mul_f32 v[60:61], v[60:61], v[60:61]
	v_pk_mul_f32 v[56:57], v[56:57], v[56:57]
	s_mov_b32 s35, 0x100000
	v_cvt_pk_bf16_f32 v58, v56, v58
	v_cvt_pk_bf16_f32 v56, v60, v62
	v_add_co_u32_e32 v60, vcc, s35, v144
	v_cvt_pk_bf16_f32 v59, v57, v59
	v_cvt_pk_bf16_f32 v57, v61, v63
	v_addc_co_u32_e32 v61, vcc, 0, v145, vcc
	global_store_dwordx4 v[60:61], v[56:59], off
	s_nop 1
	v_max_f32_e32 v56, 0, v53
	v_max_f32_e32 v53, v54, v54
	v_max_f32_e32 v54, v55, v55
	v_max_f32_e32 v57, 0, v54
	v_pk_mul_f32 v[54:55], v[56:57], v[56:57]
	v_max_f32_e32 v56, 0, v49
	v_max_f32_e32 v49, v50, v50
	v_max_f32_e32 v50, v51, v51
	v_max_f32_e32 v57, 0, v50
	v_max_f32_e32 v52, 0, v52
	v_max_f32_e32 v53, 0, v53
	v_max_f32_e32 v48, 0, v48
	v_max_f32_e32 v49, 0, v49
	v_pk_mul_f32 v[50:51], v[56:57], v[56:57]
	v_pk_mul_f32 v[52:53], v[52:53], v[52:53]
	v_pk_mul_f32 v[48:49], v[48:49], v[48:49]
	s_mov_b64 s[44:45], 0x100000
	v_lshl_add_u64 v[64:65], v[144:145], 0, s[44:45]
	v_cvt_pk_bf16_f32 v51, v49, v51
	v_cvt_pk_bf16_f32 v50, v48, v50
	v_cvt_pk_bf16_f32 v49, v53, v55
	v_cvt_pk_bf16_f32 v48, v52, v54
	global_store_dwordx4 v[64:65], v[48:51], off offset:256
	s_nop 1
	v_max_f32_e32 v50, 0, v45
	v_max_f32_e32 v45, v46, v46
	v_max_f32_e32 v46, v47, v47
	v_max_f32_e32 v51, 0, v46
	v_pk_mul_f32 v[46:47], v[50:51], v[50:51]
	v_max_f32_e32 v50, 0, v41
	v_max_f32_e32 v41, v42, v42
	v_max_f32_e32 v42, v43, v43
	v_max_f32_e32 v51, 0, v42
	v_max_f32_e32 v44, 0, v44
	v_max_f32_e32 v45, 0, v45
	v_max_f32_e32 v40, 0, v40
	v_max_f32_e32 v41, 0, v41
	v_pk_mul_f32 v[42:43], v[50:51], v[50:51]
	v_pk_mul_f32 v[44:45], v[44:45], v[44:45]
	v_pk_mul_f32 v[40:41], v[40:41], v[40:41]
	v_cvt_pk_bf16_f32 v42, v40, v42
	v_cvt_pk_bf16_f32 v40, v44, v46
	v_add_co_u32_e32 v44, vcc, s67, v144
	v_cvt_pk_bf16_f32 v43, v41, v43
	v_cvt_pk_bf16_f32 v41, v45, v47
	v_addc_co_u32_e32 v45, vcc, 0, v145, vcc
	global_store_dwordx4 v[44:45], v[40:43], off
	s_nop 1
	v_max_f32_e32 v40, 0, v37
	v_max_f32_e32 v37, v38, v38
	v_max_f32_e32 v38, v39, v39
	v_max_f32_e32 v41, 0, v38
	v_pk_mul_f32 v[38:39], v[40:41], v[40:41]
	v_max_f32_e32 v40, 0, v33
; __device__ __forceinline__ unsigned pk2_(float lo, float hi) { return f2bf_(lo) | (f2bf_(hi) << 16); }
; template <int ACT> __device__ __forceinline__ float act_f(float v) {
;     if (ACT == 2) { const float t = fmaxf(v, 0.f); return t * t; }
;     __device__ __forceinline__ void operator()(const f32x4 (&acc)[2][2][4][2], const Unit& u, int wr, int wc, int fr, int fq) const {
;     ...
;             for (int m = 0; m < 4; ++m) { bf16_t* rowp = O + (size_t)(row0 + ai * HALF + m * 16) * ldc + col0;
; #pragma unroll
;                 for (int bj = 0; bj < 2; ++bj) { f32x4 v0 = acc[ai][bj][m][0], v1 = acc[ai][bj][m][1];
;                     if (bias) { v0 += *(const f32x4*)(bias + col0 + bj * HALF); v1 += *(const f32x4*)(bias + col0 + bj * HALF + 4); }
;                     u32x4 w; w.x = pk2_(act_f<ACT>(v0[0]), act_f<ACT>(v0[1])); w.y = pk2_(act_f<ACT>(v0[2]), act_f<ACT>(v0[3]));
;                     w.z = pk2_(act_f<ACT>(v1[0]), act_f<ACT>(v1[1])); w.w = pk2_(act_f<ACT>(v1[2]), act_f<ACT>(v1[3]));
;                     *(u32x4*)(rowp + bj * HALF) = w; } }
	v_max_f32_e32 v33, v34, v34
	v_max_f32_e32 v34, v35, v35
	v_max_f32_e32 v41, 0, v34
	v_max_f32_e32 v36, 0, v36
	v_max_f32_e32 v37, 0, v37
	v_max_f32_e32 v32, 0, v32
	v_max_f32_e32 v33, 0, v33
	v_pk_mul_f32 v[34:35], v[40:41], v[40:41]
	v_pk_mul_f32 v[36:37], v[36:37], v[36:37]
	v_pk_mul_f32 v[32:33], v[32:33], v[32:33]
	v_lshl_add_u64 v[48:49], v[144:145], 0, s[26:27]
	v_cvt_pk_bf16_f32 v35, v33, v35
	v_cvt_pk_bf16_f32 v34, v32, v34
	v_cvt_pk_bf16_f32 v33, v37, v39
	v_cvt_pk_bf16_f32 v32, v36, v38
	global_store_dwordx4 v[48:49], v[32:35], off offset:256
	s_nop 1
	v_max_f32_e32 v34, 0, v29
	v_max_f32_e32 v29, v30, v30
	v_max_f32_e32 v30, v31, v31
	v_max_f32_e32 v35, 0, v30
	v_pk_mul_f32 v[30:31], v[34:35], v[34:35]
	v_max_f32_e32 v34, 0, v25
	v_max_f32_e32 v25, v26, v26
	v_max_f32_e32 v26, v27, v27
	v_max_f32_e32 v35, 0, v26
	v_max_f32_e32 v28, 0, v28
	v_max_f32_e32 v29, 0, v29
	v_max_f32_e32 v24, 0, v24
	v_max_f32_e32 v25, 0, v25
	v_pk_mul_f32 v[26:27], v[34:35], v[34:35]
	v_pk_mul_f32 v[28:29], v[28:29], v[28:29]
	v_pk_mul_f32 v[24:25], v[24:25], v[24:25]
	v_cvt_pk_bf16_f32 v26, v24, v26
	v_cvt_pk_bf16_f32 v24, v28, v30
	v_add_co_u32_e32 v28, vcc, s68, v144
	v_cvt_pk_bf16_f32 v27, v25, v27
	v_cvt_pk_bf16_f32 v25, v29, v31
	v_addc_co_u32_e32 v29, vcc, 0, v145, vcc
	global_store_dwordx4 v[28:29], v[24:27], off
	s_nop 1
	v_max_f32_e32 v24, 0, v21
	v_max_f32_e32 v21, v22, v22
	v_max_f32_e32 v22, v23, v23
	v_max_f32_e32 v25, 0, v22
	v_pk_mul_f32 v[22:23], v[24:25], v[24:25]
	v_max_f32_e32 v24, 0, v17
	v_max_f32_e32 v17, v18, v18
	v_max_f32_e32 v18, v19, v19
	v_max_f32_e32 v25, 0, v18
	v_max_f32_e32 v20, 0, v20
	v_max_f32_e32 v21, 0, v21
	v_max_f32_e32 v16, 0, v16
	v_max_f32_e32 v17, 0, v17
	v_pk_mul_f32 v[18:19], v[24:25], v[24:25]
	v_pk_mul_f32 v[20:21], v[20:21], v[20:21]
	v_pk_mul_f32 v[16:17], v[16:17], v[16:17]
	v_lshl_add_u64 v[32:33], v[144:145], 0, s[28:29]
	v_cvt_pk_bf16_f32 v19, v17, v19
	v_cvt_pk_bf16_f32 v18, v16, v18
	v_cvt_pk_bf16_f32 v17, v21, v23
	v_cvt_pk_bf16_f32 v16, v20, v22
	global_store_dwordx4 v[32:33], v[16:19], off offset:256
	s_nop 1
	v_max_f32_e32 v18, 0, v13
	v_max_f32_e32 v13, v14, v14
	v_max_f32_e32 v14, v15, v15
	v_max_f32_e32 v19, 0, v14
	v_pk_mul_f32 v[14:15], v[18:19], v[18:19]
	v_max_f32_e32 v18, 0, v9
	v_max_f32_e32 v9, v10, v10
	v_max_f32_e32 v10, v11, v11
	v_max_f32_e32 v19, 0, v10
	v_max_f32_e32 v12, 0, v12
	v_max_f32_e32 v13, 0, v13
	v_max_f32_e32 v8, 0, v8
	v_max_f32_e32 v9, 0, v9
	v_pk_mul_f32 v[10:11], v[18:19], v[18:19]
	v_pk_mul_f32 v[12:13], v[12:13], v[12:13]
	v_pk_mul_f32 v[8:9], v[8:9], v[8:9]
	v_cvt_pk_bf16_f32 v10, v8, v10
	v_cvt_pk_bf16_f32 v8, v12, v14
	v_add_co_u32_e32 v12, vcc, s69, v144
	v_cvt_pk_bf16_f32 v11, v9, v11
	v_cvt_pk_bf16_f32 v9, v13, v15
	v_addc_co_u32_e32 v13, vcc, 0, v145, vcc
	global_store_dwordx4 v[12:13], v[8:11], off
	s_nop 1
	v_max_f32_e32 v8, 0, v5
	v_max_f32_e32 v5, v6, v6
	v_max_f32_e32 v6, v7, v7
	v_max_f32_e32 v9, 0, v6
	v_pk_mul_f32 v[6:7], v[8:9], v[8:9]
	v_max_f32_e32 v8, 0, v1
	v_max_f32_e32 v1, v2, v2
	v_max_f32_e32 v2, v3, v3
	v_max_f32_e32 v9, 0, v2
	v_max_f32_e32 v4, 0, v4
	v_max_f32_e32 v5, 0, v5
	v_max_f32_e32 v0, 0, v0
	v_max_f32_e32 v1, 0, v1
	v_pk_mul_f32 v[2:3], v[8:9], v[8:9]
	v_pk_mul_f32 v[4:5], v[4:5], v[4:5]
	v_pk_mul_f32 v[0:1], v[0:1], v[0:1]
	v_lshl_add_u64 v[16:17], v[144:145], 0, s[30:31]
	v_cvt_pk_bf16_f32 v3, v1, v3
	v_cvt_pk_bf16_f32 v2, v0, v2
	v_cvt_pk_bf16_f32 v1, v5, v7
	v_cvt_pk_bf16_f32 v0, v4, v6
	s_andn2_b64 vcc, exec, s[0:1]
	s_mov_b64 s[0:1], -1
	global_store_dwordx4 v[16:17], v[0:3], off offset:256
	s_cbranch_vccnz .LBB0_382
	s_andn2_b64 vcc, exec, s[6:7]
	s_cbranch_vccnz .LBB0_381
	s_barrier
	s_branch .LBB0_381

; __device__ __forceinline__ unsigned f2bf_(float f) { unsigned u = __builtin_bit_cast(unsigned, f); return (u + 0x7fffu + ((u >> 16) & 1u)) >> 16; }
; __device__ __forceinline__ unsigned pk2_(float lo, float hi) { return f2bf_(lo) | (f2bf_(hi) << 16); }
;     __device__ __forceinline__ void operator()(const f32x4 (&acc)[2][2][4][2], const Unit& u, int wr, int wc, int fr, int fq) const {
;         asm volatile("" : "+v"(fr), "+v"(fq));
;         const int row0 = u.pm * BM + wr * 64 + fr; const int col0 = u.pn * BM + wc * 32 + 8 * fq;
; #pragma unroll
;         for (int ai = 0; ai < 2; ++ai)
; #pragma unroll
;             for (int m = 0; m < 4; ++m) { bf16_t* rowp = O + (size_t)(row0 + ai * HALF + m * 16) * ldc + col0;
; #pragma unroll
;                 for (int bj = 0; bj < 2; ++bj) { f32x4 v0 = acc[ai][bj][m][0], v1 = acc[ai][bj][m][1];
;                     if (bias) { v0 += *(const f32x4*)(bias + col0 + bj * HALF); v1 += *(const f32x4*)(bias + col0 + bj * HALF + 4); }
;                     u32x4 w; w.x = pk2_(act_f<ACT>(v0[0]), act_f<ACT>(v0[1])); w.y = pk2_(act_f<ACT>(v0[2]), act_f<ACT>(v0[3]));
;                     w.z = pk2_(act_f<ACT>(v1[0]), act_f<ACT>(v1[1])); w.w = pk2_(act_f<ACT>(v1[2]), act_f<ACT>(v1[3]));
;                     *(u32x4*)(rowp + bj * HALF) = w; } }
.LBB0_625:
	s_lshl_b32 s25, s34, 8
	v_mov_b32_e32 v145, v147
	v_mov_b32_e32 v144, v146
	s_add_i32 s25, s25, s44
	s_lshl_b32 s27, s67, 8
	v_add_u32_e32 v152, s25, v145
	s_or_b32 s27, s27, s45
	v_ashrrev_i32_e32 v153, 31, v152
	v_lshl_add_u32 v144, v144, 3, s27
	v_lshlrev_b64 v[152:153], 12, v[152:153]
	v_ashrrev_i32_e32 v145, 31, v144
	v_lshl_add_u64 v[152:153], s[72:73], 0, v[152:153]
	v_lshl_add_u64 v[144:145], v[144:145], 1, v[152:153]
	v_cvt_pk_bf16_f32 v124, v124, v125
	v_cvt_pk_bf16_f32 v125, v126, v127
	v_cvt_pk_bf16_f32 v126, v120, v121
	v_cvt_pk_bf16_f32 v127, v122, v123
	v_cvt_pk_bf16_f32 v116, v116, v117
	v_cvt_pk_bf16_f32 v117, v118, v119
	v_cvt_pk_bf16_f32 v118, v108, v109
	v_cvt_pk_bf16_f32 v119, v110, v111
	v_cvt_pk_bf16_f32 v108, v112, v113
	v_cvt_pk_bf16_f32 v109, v114, v115
	v_cvt_pk_bf16_f32 v110, v104, v105
	s_mov_b32 s25, 0x10000
	v_cvt_pk_bf16_f32 v111, v106, v107
	v_add_co_u32_e32 v104, vcc, s25, v144
	s_mov_b64 s[36:37], 0x10000
	s_nop 0
	v_addc_co_u32_e32 v105, vcc, 0, v145, vcc
	global_store_dwordx4 v[104:105], v[108:111], off
	v_cvt_pk_bf16_f32 v100, v100, v101
	v_cvt_pk_bf16_f32 v101, v102, v103
	v_cvt_pk_bf16_f32 v102, v92, v93
	v_cvt_pk_bf16_f32 v103, v94, v95
	v_cvt_pk_bf16_f32 v92, v96, v97
	v_cvt_pk_bf16_f32 v93, v98, v99
	v_cvt_pk_bf16_f32 v94, v88, v89
	v_cvt_pk_bf16_f32 v95, v90, v91
	v_add_co_u32_e32 v88, vcc, s61, v144
	global_store_dwordx4 v[144:145], v[116:119], off offset:256
	s_nop 0
	v_addc_co_u32_e32 v89, vcc, 0, v145, vcc
	global_store_dwordx4 v[88:89], v[92:95], off
	v_cvt_pk_bf16_f32 v84, v84, v85
	v_cvt_pk_bf16_f32 v85, v86, v87
	v_cvt_pk_bf16_f32 v86, v76, v77
	v_cvt_pk_bf16_f32 v87, v78, v79
	v_cvt_pk_bf16_f32 v76, v80, v81
	v_cvt_pk_bf16_f32 v77, v82, v83
	v_cvt_pk_bf16_f32 v78, v72, v73
	v_cvt_pk_bf16_f32 v79, v74, v75
	v_add_co_u32_e32 v72, vcc, s62, v144
	v_lshl_add_u64 v[116:117], v[144:145], 0, s[36:37]
	s_nop 0
	v_addc_co_u32_e32 v73, vcc, 0, v145, vcc
	global_store_dwordx4 v[72:73], v[76:79], off
	v_cvt_pk_bf16_f32 v68, v68, v69
	v_cvt_pk_bf16_f32 v69, v70, v71
	v_cvt_pk_bf16_f32 v70, v64, v65
	v_cvt_pk_bf16_f32 v60, v60, v61
	v_cvt_pk_bf16_f32 v61, v62, v63
	v_cvt_pk_bf16_f32 v62, v56, v57
	v_cvt_pk_bf16_f32 v63, v58, v59
	v_add_co_u32_e32 v56, vcc, s63, v144
	s_nop 0
	v_addc_co_u32_e32 v57, vcc, 0, v145, vcc
	global_store_dwordx4 v[56:57], v[60:63], off
	v_cvt_pk_bf16_f32 v52, v52, v53
	v_cvt_pk_bf16_f32 v53, v54, v55
	v_cvt_pk_bf16_f32 v54, v44, v45
	v_cvt_pk_bf16_f32 v55, v46, v47
	v_cvt_pk_bf16_f32 v44, v48, v49
	v_cvt_pk_bf16_f32 v45, v50, v51
	v_cvt_pk_bf16_f32 v46, v40, v41
	v_cvt_pk_bf16_f32 v47, v42, v43
	v_add_co_u32_e32 v40, vcc, s64, v144
	s_nop 0
	v_addc_co_u32_e32 v41, vcc, 0, v145, vcc
	global_store_dwordx4 v[40:41], v[44:47], off
	v_cvt_pk_bf16_f32 v36, v36, v37
	v_cvt_pk_bf16_f32 v37, v38, v39
	v_cvt_pk_bf16_f32 v38, v28, v29
	v_cvt_pk_bf16_f32 v39, v30, v31
	v_cvt_pk_bf16_f32 v28, v32, v33
	v_cvt_pk_bf16_f32 v29, v34, v35
	v_cvt_pk_bf16_f32 v30, v24, v25
	v_cvt_pk_bf16_f32 v31, v26, v27
	v_add_co_u32_e32 v24, vcc, s65, v144
	s_nop 0
	v_addc_co_u32_e32 v25, vcc, 0, v145, vcc
	global_store_dwordx4 v[24:25], v[28:31], off
	v_cvt_pk_bf16_f32 v20, v20, v21
	v_cvt_pk_bf16_f32 v21, v22, v23
	v_cvt_pk_bf16_f32 v22, v12, v13
	v_cvt_pk_bf16_f32 v23, v14, v15
	v_cvt_pk_bf16_f32 v12, v16, v17
	v_cvt_pk_bf16_f32 v13, v18, v19
	v_cvt_pk_bf16_f32 v14, v8, v9
	v_cvt_pk_bf16_f32 v15, v10, v11
	v_add_co_u32_e32 v8, vcc, s66, v144
	v_cvt_pk_bf16_f32 v71, v66, v67
	s_nop 0
	v_addc_co_u32_e32 v9, vcc, 0, v145, vcc
	global_store_dwordx4 v[8:9], v[12:15], off
	v_cvt_pk_bf16_f32 v4, v4, v5
	v_cvt_pk_bf16_f32 v5, v6, v7
	v_lshl_add_u64 v[64:65], v[144:145], 0, s[16:17]
	v_cvt_pk_bf16_f32 v6, v0, v1
	s_mov_b64 s[36:37], 0x20000
	global_store_dwordx4 v[64:65], v[52:55], off offset:256
	s_nop 1
	v_lshl_add_u64 v[52:53], v[144:145], 0, s[18:19]
	global_store_dwordx4 v[116:117], v[100:103], off offset:256
	s_nop 0
	global_store_dwordx4 v[52:53], v[36:39], off offset:256
	s_nop 0
	v_lshl_add_u64 v[100:101], v[144:145], 0, s[36:37]
	v_lshl_add_u64 v[36:37], v[144:145], 0, s[20:21]
	global_store_dwordx4 v[100:101], v[84:87], off offset:256
	global_store_dwordx4 v[36:37], v[20:23], off offset:256
	v_cvt_pk_bf16_f32 v7, v2, v3
	v_lshl_add_u64 v[84:85], v[144:145], 0, s[12:13]
	v_lshl_add_u64 v[20:21], v[144:145], 0, s[22:23]
	s_andn2_b64 vcc, exec, s[0:1]
	s_mov_b64 s[0:1], -1
	global_store_dwordx4 v[144:145], v[124:127], off
	global_store_dwordx4 v[84:85], v[68:71], off offset:256
	global_store_dwordx4 v[20:21], v[4:7], off offset:256
	s_cbranch_vccnz .LBB0_614
	s_andn2_b64 vcc, exec, s[6:7]
	s_cbranch_vccnz .LBB0_613
	s_barrier
	s_branch .LBB0_613

; __device__ __forceinline__ unsigned f2bf_(float f) { unsigned u = __builtin_bit_cast(unsigned, f); return (u + 0x7fffu + ((u >> 16) & 1u)) >> 16; }
; __device__ __forceinline__ unsigned pk2_(float lo, float hi) { return f2bf_(lo) | (f2bf_(hi) << 16); }
;     __device__ __forceinline__ void operator()(const f32x4 (&acc)[2][2][4][2], const Unit& u, int wr, int wc, int fr, int fq) const {
;         asm volatile("" : "+v"(fr), "+v"(fq));
;         const int row0 = u.pm * BM + wr * 64 + fr; const int col0 = u.pn * BM + wc * 32 + 8 * fq;
; #pragma unroll
;         for (int ai = 0; ai < 2; ++ai)
; #pragma unroll
;             for (int m = 0; m < 4; ++m) { bf16_t* rowp = O + (size_t)(row0 + ai * HALF + m * 16) * ldc + col0;
; #pragma unroll
;                 for (int bj = 0; bj < 2; ++bj) { f32x4 v0 = acc[ai][bj][m][0], v1 = acc[ai][bj][m][1];
;                     if (bias) { v0 += *(const f32x4*)(bias + col0 + bj * HALF); v1 += *(const f32x4*)(bias + col0 + bj * HALF + 4); }
;                     u32x4 w; w.x = pk2_(act_f<ACT>(v0[0]), act_f<ACT>(v0[1])); w.y = pk2_(act_f<ACT>(v0[2]), act_f<ACT>(v0[3]));
;                     w.z = pk2_(act_f<ACT>(v1[0]), act_f<ACT>(v1[1])); w.w = pk2_(act_f<ACT>(v1[2]), act_f<ACT>(v1[3]));
;                     *(u32x4*)(rowp + bj * HALF) = w; } }
.LBB0_649:
	s_lshl_b32 s25, s34, 8
	v_mov_b32_e32 v145, v147
	v_mov_b32_e32 v144, v146
	s_add_i32 s25, s25, s44
	s_lshl_b32 s27, s66, 8
	v_add_u32_e32 v152, s25, v145
	s_or_b32 s27, s27, s45
	v_ashrrev_i32_e32 v153, 31, v152
	v_lshl_add_u32 v144, v144, 3, s27
	v_lshlrev_b64 v[152:153], 16, v[152:153]
	v_ashrrev_i32_e32 v145, 31, v144
	v_lshl_add_u64 v[152:153], s[6:7], 0, v[152:153]
	v_lshl_add_u64 v[144:145], v[144:145], 1, v[152:153]
	v_cvt_pk_bf16_f32 v124, v124, v125
	v_cvt_pk_bf16_f32 v125, v126, v127
	v_cvt_pk_bf16_f32 v126, v120, v121
	v_cvt_pk_bf16_f32 v127, v122, v123
	v_cvt_pk_bf16_f32 v116, v116, v117
	v_cvt_pk_bf16_f32 v117, v118, v119
	v_cvt_pk_bf16_f32 v118, v108, v109
	v_cvt_pk_bf16_f32 v119, v110, v111
	v_cvt_pk_bf16_f32 v108, v112, v113
	v_cvt_pk_bf16_f32 v109, v114, v115
	v_cvt_pk_bf16_f32 v110, v104, v105
	s_mov_b32 s25, 0x100000
	v_cvt_pk_bf16_f32 v111, v106, v107
	v_add_co_u32_e32 v104, vcc, s25, v144
	s_mov_b32 s25, 0x200000
	s_nop 0
	v_addc_co_u32_e32 v105, vcc, 0, v145, vcc
	global_store_dwordx4 v[104:105], v[108:111], off
	v_cvt_pk_bf16_f32 v100, v100, v101
	v_cvt_pk_bf16_f32 v101, v102, v103
	v_cvt_pk_bf16_f32 v102, v92, v93
	v_cvt_pk_bf16_f32 v103, v94, v95
	v_cvt_pk_bf16_f32 v92, v96, v97
	v_cvt_pk_bf16_f32 v93, v98, v99
	v_cvt_pk_bf16_f32 v94, v88, v89
	v_cvt_pk_bf16_f32 v95, v90, v91
	v_add_co_u32_e32 v88, vcc, s25, v144
	s_mov_b64 s[36:37], 0x100000
	s_nop 0
	v_addc_co_u32_e32 v89, vcc, 0, v145, vcc
	global_store_dwordx4 v[88:89], v[92:95], off
	v_cvt_pk_bf16_f32 v84, v84, v85
	v_cvt_pk_bf16_f32 v85, v86, v87
	v_cvt_pk_bf16_f32 v86, v76, v77
	v_cvt_pk_bf16_f32 v87, v78, v79
	v_cvt_pk_bf16_f32 v76, v80, v81
	v_cvt_pk_bf16_f32 v77, v82, v83
	v_cvt_pk_bf16_f32 v78, v72, v73
	v_cvt_pk_bf16_f32 v79, v74, v75
	v_add_co_u32_e32 v72, vcc, s61, v144
	global_store_dwordx4 v[144:145], v[116:119], off offset:256
	s_nop 0
	v_addc_co_u32_e32 v73, vcc, 0, v145, vcc
	global_store_dwordx4 v[72:73], v[76:79], off
	v_cvt_pk_bf16_f32 v68, v68, v69
	v_cvt_pk_bf16_f32 v69, v70, v71
	v_cvt_pk_bf16_f32 v70, v64, v65
	v_cvt_pk_bf16_f32 v60, v60, v61
	v_cvt_pk_bf16_f32 v61, v62, v63
	v_cvt_pk_bf16_f32 v62, v56, v57
	v_cvt_pk_bf16_f32 v63, v58, v59
	v_add_co_u32_e32 v56, vcc, s62, v144
	s_nop 0
	v_addc_co_u32_e32 v57, vcc, 0, v145, vcc
	global_store_dwordx4 v[56:57], v[60:63], off
	v_cvt_pk_bf16_f32 v52, v52, v53
	v_cvt_pk_bf16_f32 v53, v54, v55
	v_cvt_pk_bf16_f32 v54, v44, v45
	v_cvt_pk_bf16_f32 v55, v46, v47
	v_cvt_pk_bf16_f32 v44, v48, v49
	v_cvt_pk_bf16_f32 v45, v50, v51
	v_cvt_pk_bf16_f32 v46, v40, v41
	v_cvt_pk_bf16_f32 v47, v42, v43
	v_add_co_u32_e32 v40, vcc, s63, v144
	s_nop 0
	v_addc_co_u32_e32 v41, vcc, 0, v145, vcc
	global_store_dwordx4 v[40:41], v[44:47], off
	v_cvt_pk_bf16_f32 v36, v36, v37
	v_cvt_pk_bf16_f32 v37, v38, v39
	v_cvt_pk_bf16_f32 v38, v28, v29
	v_cvt_pk_bf16_f32 v39, v30, v31
	v_cvt_pk_bf16_f32 v28, v32, v33
	v_cvt_pk_bf16_f32 v29, v34, v35
	v_cvt_pk_bf16_f32 v30, v24, v25
	v_cvt_pk_bf16_f32 v31, v26, v27
	v_add_co_u32_e32 v24, vcc, s64, v144
	s_nop 0
	v_addc_co_u32_e32 v25, vcc, 0, v145, vcc
	global_store_dwordx4 v[24:25], v[28:31], off
	v_cvt_pk_bf16_f32 v20, v20, v21
	v_cvt_pk_bf16_f32 v21, v22, v23
	v_cvt_pk_bf16_f32 v22, v12, v13
	v_cvt_pk_bf16_f32 v23, v14, v15
	v_cvt_pk_bf16_f32 v12, v16, v17
	v_cvt_pk_bf16_f32 v13, v18, v19
	v_cvt_pk_bf16_f32 v14, v8, v9
	v_cvt_pk_bf16_f32 v15, v10, v11
	v_add_co_u32_e32 v8, vcc, s65, v144
	v_cvt_pk_bf16_f32 v71, v66, v67
	s_nop 0
	v_addc_co_u32_e32 v9, vcc, 0, v145, vcc
	global_store_dwordx4 v[8:9], v[12:15], off
	v_cvt_pk_bf16_f32 v4, v4, v5
	v_cvt_pk_bf16_f32 v5, v6, v7
	v_lshl_add_u64 v[64:65], v[144:145], 0, s[16:17]
	v_cvt_pk_bf16_f32 v6, v0, v1
	v_lshl_add_u64 v[116:117], v[144:145], 0, s[36:37]
	s_mov_b64 s[36:37], 0x200000
	global_store_dwordx4 v[64:65], v[52:55], off offset:256
	s_nop 1
	v_lshl_add_u64 v[52:53], v[144:145], 0, s[18:19]
	global_store_dwordx4 v[116:117], v[100:103], off offset:256
	s_nop 0
	global_store_dwordx4 v[52:53], v[36:39], off offset:256
	v_lshl_add_u64 v[100:101], v[144:145], 0, s[36:37]
	s_mov_b64 s[36:37], 0x300000
	v_lshl_add_u64 v[36:37], v[144:145], 0, s[20:21]
	global_store_dwordx4 v[100:101], v[84:87], off offset:256
	global_store_dwordx4 v[36:37], v[20:23], off offset:256
	v_cvt_pk_bf16_f32 v7, v2, v3
	v_lshl_add_u64 v[84:85], v[144:145], 0, s[36:37]
	v_lshl_add_u64 v[20:21], v[144:145], 0, s[22:23]
	s_andn2_b64 vcc, exec, s[0:1]
	s_mov_b64 s[0:1], -1
	global_store_dwordx4 v[144:145], v[124:127], off
	global_store_dwordx4 v[84:85], v[68:71], off offset:256
	global_store_dwordx4 v[20:21], v[4:7], off offset:256
	s_cbranch_vccnz .LBB0_638
	s_andn2_b64 vcc, exec, s[8:9]
	s_cbranch_vccnz .LBB0_637
	s_barrier
	s_branch .LBB0_637

; #define MFMA32(a, b, c) __builtin_amdgcn_mfma_f32_32x32x16_bf16((a), (b), (c), 0, 0, 0)
; DEV float fexp2(float x) { return __builtin_amdgcn_exp2f(x); }
; DEV void pv_mma(f32x16 (&o)[2], const bf16x8 (&vf)[2][4], const bf16x8 (&pf)[4]) {
;     __builtin_amdgcn_sched_barrier(0);
; #pragma unroll
;     for (int f = 0; f < 4; ++f)
; #pragma unroll
;         for (int db = 0; db < 2; ++db) o[db] = MFMA32(vf[db][f], pf[f], o[db]);
;     __builtin_amdgcn_sched_barrier(0);
; }
; DEV void wave_attn_full(LAS unsigned char* wl, int lane, int r, int h, const bf16* Kp, size_t kpitch, const bf16* VTp, size_t vpitch, int k0, int nt,
;                         const bf16x8 (&qf)[4], float sc, float& m_run, float& l_run, f32x16 (&o)[2]) {
;     ...
;         const float cb = -m_new; float ps = 0.f;
; #pragma unroll
;         for (int b2 = 0; b2 < 2; ++b2)
; #pragma unroll
;             for (int i = 0; i < 16; ++i) { const float p = fexp2(__builtin_fmaf(st[b2][i], sc, cb)); st[b2][i] = p; ps += p; }
;         l_run += ps;
;         bf16x8 pf[4]; pack_p(pf, st);
;         pv_tile(o, wl + WP_V, pf, r, h);
.LBB0_1047:
	v_fma_f32 v2, v64, s63, -v0
	v_exp_f32_e32 v2, v2
	v_fma_f32 v3, v65, s63, -v0
	v_exp_f32_e32 v3, v3
	v_fma_f32 v4, v66, s63, -v0
	v_exp_f32_e32 v4, v4
	v_fma_f32 v5, v67, s63, -v0
	v_exp_f32_e32 v5, v5
	v_fma_f32 v7, v68, s63, -v0
	v_add_f32_e32 v6, 0, v2
	v_exp_f32_e32 v7, v7
	v_fma_f32 v8, v69, s63, -v0
	v_add_f32_e32 v6, v3, v6
	v_exp_f32_e32 v8, v8
	v_fma_f32 v9, v70, s63, -v0
	v_add_f32_e32 v6, v4, v6
	v_exp_f32_e32 v9, v9
	v_fma_f32 v10, v71, s63, -v0
	v_add_f32_e32 v6, v5, v6
	v_exp_f32_e32 v10, v10
	v_fma_f32 v11, v72, s63, -v0
	v_add_f32_e32 v6, v7, v6
	v_exp_f32_e32 v11, v11
	v_fma_f32 v12, v73, s63, -v0
	v_add_f32_e32 v6, v8, v6
	v_exp_f32_e32 v12, v12
	v_fma_f32 v13, v74, s63, -v0
	v_add_f32_e32 v6, v9, v6
	v_exp_f32_e32 v13, v13
	v_fma_f32 v14, v75, s63, -v0
	v_add_f32_e32 v6, v10, v6
	v_exp_f32_e32 v14, v14
	v_fma_f32 v15, v76, s63, -v0
	v_add_f32_e32 v6, v11, v6
	v_exp_f32_e32 v15, v15
	v_fma_f32 v64, v77, s63, -v0
	v_add_f32_e32 v6, v12, v6
	v_exp_f32_e32 v64, v64
	v_fma_f32 v65, v78, s63, -v0
	v_add_f32_e32 v6, v13, v6
	v_exp_f32_e32 v65, v65
	v_fma_f32 v66, v79, s63, -v0
	v_add_f32_e32 v6, v14, v6
	v_exp_f32_e32 v66, v66
	v_fma_f32 v48, v48, s63, -v0
	v_add_f32_e32 v6, v15, v6
	v_exp_f32_e32 v48, v48
	v_fma_f32 v49, v49, s63, -v0
	v_add_f32_e32 v6, v64, v6
	v_exp_f32_e32 v49, v49
	v_fma_f32 v50, v50, s63, -v0
	v_add_f32_e32 v6, v65, v6
	v_exp_f32_e32 v50, v50
	v_fma_f32 v51, v51, s63, -v0
	v_add_f32_e32 v6, v66, v6
	v_exp_f32_e32 v51, v51
	v_fma_f32 v52, v52, s63, -v0
	v_add_f32_e32 v6, v48, v6
	v_exp_f32_e32 v52, v52
	v_fma_f32 v53, v53, s63, -v0
	v_add_f32_e32 v6, v49, v6
	v_exp_f32_e32 v53, v53
	v_fma_f32 v54, v54, s63, -v0
	v_add_f32_e32 v6, v50, v6
	v_exp_f32_e32 v54, v54
	v_fma_f32 v55, v55, s63, -v0
	v_add_f32_e32 v6, v51, v6
	v_exp_f32_e32 v55, v55
	v_fma_f32 v56, v56, s63, -v0
	v_add_f32_e32 v6, v52, v6
	v_exp_f32_e32 v227, v56
	v_fma_f32 v56, v57, s63, -v0
	v_add_f32_e32 v6, v53, v6
	v_exp_f32_e32 v228, v56
	v_fma_f32 v56, v58, s63, -v0
	v_add_f32_e32 v6, v54, v6
	v_exp_f32_e32 v229, v56
	v_fma_f32 v56, v59, s63, -v0
	v_add_f32_e32 v6, v55, v6
	v_exp_f32_e32 v230, v56
	v_fma_f32 v56, v60, s63, -v0
	v_add_f32_e32 v6, v227, v6
	v_exp_f32_e32 v231, v56
	v_fma_f32 v56, v61, s63, -v0
	v_add_f32_e32 v6, v228, v6
	v_exp_f32_e32 v232, v56
	v_fma_f32 v56, v62, s63, -v0
	v_add_f32_e32 v6, v229, v6
	v_exp_f32_e32 v233, v56
	v_fma_f32 v0, v63, s63, -v0
	v_add_f32_e32 v6, v230, v6
	v_exp_f32_e32 v0, v0
	v_add_f32_e32 v6, v231, v6
	v_add_f32_e32 v6, v232, v6
	v_add_f32_e32 v6, v233, v6
	v_add_f32_e32 v6, v0, v6
	v_cvt_pk_bf16_f32 v2, v2, v3
	v_cvt_pk_bf16_f32 v3, v4, v5
	v_cvt_pk_bf16_f32 v4, v7, v8
	v_cvt_pk_bf16_f32 v7, v13, v14
	v_add_u32_e32 v14, 0x2000, v224
	v_add_f32_e32 v203, v6, v203
	v_cvt_pk_bf16_f32 v5, v9, v10
	v_cvt_pk_bf16_f32 v6, v11, v12
	v_cvt_pk_bf16_f32 v10, v48, v49
	v_cvt_pk_bf16_f32 v11, v50, v51
	v_cvt_pk_bf16_f32 v12, v52, v53
	v_cvt_pk_bf16_f32 v13, v54, v55
	ds_read2_b64 v[48:51], v14 offset0:128 offset1:130
	ds_read2_b64 v[52:55], v14 offset0:132 offset1:134
	ds_read2_b64 v[56:59], v14 offset0:136 offset1:138
	ds_read2_b64 v[60:63], v14 offset0:140 offset1:142
	v_add_u32_e32 v14, 0x3000, v224
	v_cvt_pk_bf16_f32 v8, v15, v64
	v_cvt_pk_bf16_f32 v9, v65, v66
	ds_read2_b64 v[64:67], v14 offset0:160 offset1:162
	ds_read2_b64 v[68:71], v14 offset0:164 offset1:166
	ds_read2_b64 v[72:75], v14 offset0:168 offset1:170
	ds_read2_b64 v[76:79], v14 offset0:172 offset1:174
	v_cvt_pk_bf16_f32 v228, v227, v228
	v_cvt_pk_bf16_f32 v229, v229, v230
	v_cvt_pk_bf16_f32 v230, v231, v232
	v_cvt_pk_bf16_f32 v231, v233, v0
	s_setprio 1
	s_waitcnt lgkmcnt(7)
	v_mfma_f32_32x32x16_bf16 v[32:47], v[48:51], v[2:5], v[32:47]
	s_waitcnt lgkmcnt(3)
	v_mfma_f32_32x32x16_bf16 v[16:31], v[64:67], v[2:5], v[16:31]
	v_mfma_f32_32x32x16_bf16 v[32:47], v[52:55], v[6:9], v[32:47]
	s_waitcnt lgkmcnt(2)
	v_mfma_f32_32x32x16_bf16 v[16:31], v[68:71], v[6:9], v[16:31]
	v_mfma_f32_32x32x16_bf16 v[32:47], v[56:59], v[10:13], v[32:47]
	s_waitcnt lgkmcnt(1)
	v_mfma_f32_32x32x16_bf16 v[16:31], v[72:75], v[10:13], v[16:31]
	v_mfma_f32_32x32x16_bf16 v[32:47], v[60:63], v[228:231], v[32:47]
	s_waitcnt lgkmcnt(0)
	v_mfma_f32_32x32x16_bf16 v[16:31], v[76:79], v[228:231], v[16:31]
	s_setprio 0
	s_add_i32 s20, s20, 64
	s_cmpk_lg_i32 s20, 0x100
	s_cbranch_scc0 .LBB0_1052

; #define LAS __attribute__((address_space(3)))
; #define MFMA32(a, b, c) __builtin_amdgcn_mfma_f32_32x32x16_bf16((a), (b), (c), 0, 0, 0)
; DEV float shx(float v, int m, int lane) { return __builtin_bit_cast(float, __builtin_amdgcn_ds_bpermute((lane ^ m) << 2, __builtin_bit_cast(int, v))); }
; DEV float fexp2(float x) { return __builtin_amdgcn_exp2f(x); }
; DEV float max3f(float a, float b, float c) { float d; asm("v_max3_f32 %0, %1, %2, %3" : "=v"(d) : "v"(a), "v"(b), "v"(c)); return d; }
; template <int DQK> DEV void qk_tile(f32x16 (&st)[2], const LAS unsigned char* kb, const bf16x8 (&qf)[DQK / 16], int r, int h) {
;     ...
;     for (int b2 = 0; b2 < 2; ++b2)
; #pragma unroll
;         for (int s = 0; s < NS; ++s) kf[b2][s] = *(const LAS bf16x8*)(kb + (32 * b2 + r) * KSTR + 32 * s + 16 * h);
;     __builtin_amdgcn_sched_barrier(0);
; #pragma unroll
;     for (int b2 = 0; b2 < 2; ++b2) {
;         f32x16 a;
; #pragma unroll
;         for (int i = 0; i < 16; ++i) a[i] = 0.f;
; #pragma unroll
;         for (int s = 0; s < NS; ++s) a = MFMA32(kf[b2][s], qf[s], a);
;         st[b2] = a;
;     }
; DEV void wave_attn_full(LAS unsigned char* wl, int lane, int r, int h, const bf16* Kp, size_t kpitch, const bf16* VTp, size_t vpitch, int k0, int nt,
;                         const bf16x8 (&qf)[4], float sc, float& m_run, float& l_run, f32x16 (&o)[2]) {
;     ...
;         qk_tile<64>(st, wl, qf, r, h);
;         float mxr = fmaxf(st[0][0], st[1][0]);
;                 mxr = max3f(mxr, st[0][1], st[0][1]);
;         mxr = max3f(mxr, st[1][1], st[0][2]);
; #pragma unroll
;         for (int i = 2; i < 16; i += 2) { mxr = max3f(mxr, st[1][i], st[0][i + 1]); if (i + 2 < 16) mxr = max3f(mxr, st[1][i + 1], st[0][i + 2]); else mxr = max3f(mxr, st[1][i + 1], st[1][i + 1]); }
;         float mx = mxr * sc; mx = fmaxf(mx, shx(mx, 32, lane));
;         const float m_new = fmaxf(m_run, mx);
;         if (__any(m_new > m_run ? 1 : 0)) { const float alpha = fexp2(m_run - m_new); m_run = m_new; l_run *= alpha;
; #pragma unroll
;             for (int db = 0; db < 2; ++db) o[db] = o[db] * alpha; }
.LBB0_1050:
	ds_read_b128 v[2:5], v223
	ds_read_b128 v[6:9], v223 offset:32
	ds_read_b128 v[10:13], v223 offset:64
	ds_read_b128 v[48:51], v223 offset:96
	ds_read_b128 v[52:55], v223 offset:4608
	ds_read_b128 v[228:231], v223 offset:4640
	ds_read_b128 v[232:235], v223 offset:4672
	ds_read_b128 v[236:239], v223 offset:4704
	s_setprio 1
	s_waitcnt lgkmcnt(7)
	v_mfma_f32_32x32x16_bf16 v[64:79], v[2:5], v[80:83], 0
	s_waitcnt lgkmcnt(6)
	v_mfma_f32_32x32x16_bf16 v[64:79], v[6:9], v[84:87], v[64:79]
	s_waitcnt lgkmcnt(5)
	v_mfma_f32_32x32x16_bf16 v[64:79], v[10:13], v[88:91], v[64:79]
	s_waitcnt lgkmcnt(4)
	v_mfma_f32_32x32x16_bf16 v[64:79], v[48:51], v[92:95], v[64:79]
	s_waitcnt lgkmcnt(3)
	v_mfma_f32_32x32x16_bf16 v[48:63], v[52:55], v[80:83], 0
	s_waitcnt lgkmcnt(2)
	v_mfma_f32_32x32x16_bf16 v[48:63], v[228:231], v[84:87], v[48:63]
	s_waitcnt lgkmcnt(1)
	v_mfma_f32_32x32x16_bf16 v[48:63], v[232:235], v[88:91], v[48:63]
	s_waitcnt lgkmcnt(0)
	v_mfma_f32_32x32x16_bf16 v[48:63], v[236:239], v[92:95], v[48:63]
	s_setprio 0
	s_nop 11
	v_max_f32_e32 v0, v48, v48
	v_max_f32_e32 v2, v64, v64
	v_max_f32_e32 v0, v2, v0
	v_max3_f32 v0, v0, v65, v65
	v_max3_f32 v0, v0, v49, v66
	v_max3_f32 v0, v0, v50, v67
	v_max3_f32 v0, v0, v51, v68
	v_max3_f32 v0, v0, v52, v69
	v_max3_f32 v0, v0, v53, v70
	v_max3_f32 v0, v0, v54, v71
	v_max3_f32 v0, v0, v55, v72
	v_max3_f32 v0, v0, v56, v73
	v_max3_f32 v0, v0, v57, v74
	v_max3_f32 v0, v0, v58, v75
	v_max3_f32 v0, v0, v59, v76
	v_max3_f32 v0, v0, v60, v77
	v_max3_f32 v0, v0, v61, v78
	v_max3_f32 v0, v0, v62, v79
	v_max3_f32 v0, v0, v63, v63
	v_mul_f32_e32 v0, 0x3e38aa3b, v0
	ds_bpermute_b32 v2, v220, v0
	s_waitcnt lgkmcnt(0)
	v_max3_f32 v0, v202, v0, v2
	v_cmp_gt_f32_e32 vcc, v0, v202
	s_cbranch_vccz .LBB0_1047
	v_sub_f32_e32 v2, v202, v0
	v_exp_f32_e32 v2, v2
	v_mov_b32_e32 v202, v0
	v_mul_f32_e32 v203, v203, v2
	v_pk_mul_f32 v[46:47], v[46:47], v[2:3] op_sel_hi:[1,0]
	v_pk_mul_f32 v[44:45], v[44:45], v[2:3] op_sel_hi:[1,0]
	v_pk_mul_f32 v[42:43], v[42:43], v[2:3] op_sel_hi:[1,0]
	v_pk_mul_f32 v[40:41], v[40:41], v[2:3] op_sel_hi:[1,0]
	v_pk_mul_f32 v[38:39], v[38:39], v[2:3] op_sel_hi:[1,0]
	v_pk_mul_f32 v[36:37], v[36:37], v[2:3] op_sel_hi:[1,0]
	v_pk_mul_f32 v[34:35], v[34:35], v[2:3] op_sel_hi:[1,0]
	v_pk_mul_f32 v[32:33], v[32:33], v[2:3] op_sel_hi:[1,0]
	v_pk_mul_f32 v[30:31], v[30:31], v[2:3] op_sel_hi:[1,0]
	v_pk_mul_f32 v[28:29], v[28:29], v[2:3] op_sel_hi:[1,0]
	v_pk_mul_f32 v[26:27], v[26:27], v[2:3] op_sel_hi:[1,0]
	v_pk_mul_f32 v[24:25], v[24:25], v[2:3] op_sel_hi:[1,0]
	v_pk_mul_f32 v[22:23], v[22:23], v[2:3] op_sel_hi:[1,0]
	v_pk_mul_f32 v[20:21], v[20:21], v[2:3] op_sel_hi:[1,0]
	v_pk_mul_f32 v[18:19], v[18:19], v[2:3] op_sel_hi:[1,0]
	v_pk_mul_f32 v[16:17], v[16:17], v[2:3] op_sel_hi:[1,0]
	s_branch .LBB0_1047

; template <int DQK> DEV void qk_tile(f32x16 (&st)[2], const LAS unsigned char* kb, const bf16x8 (&qf)[DQK / 16], int r, int h) {
;     ...
;     for (int b2 = 0; b2 < 2; ++b2)
; #pragma unroll
;         for (int s = 0; s < NS; ++s) kf[b2][s] = *(const LAS bf16x8*)(kb + (32 * b2 + r) * KSTR + 32 * s + 16 * h);
;     __builtin_amdgcn_sched_barrier(0);
; #pragma unroll
;     for (int b2 = 0; b2 < 2; ++b2) {
;         f32x16 a;
; #pragma unroll
;         for (int i = 0; i < 16; ++i) a[i] = 0.f;
; #pragma unroll
;         for (int s = 0; s < NS; ++s) a = MFMA32(kf[b2][s], qf[s], a);
;         st[b2] = a;
;     }
;     __builtin_amdgcn_sched_barrier(0);
; }
; DEV void pack_p(bf16x8 (&pf)[4], const f32x16 (&st)[2]) {
; #pragma unroll
;     for (int b2 = 0; b2 < 2; ++b2)
; #pragma unroll
;         for (int s = 0; s < 2; ++s) { u32x4 p; p.x = pk2(st[b2][8 * s], st[b2][8 * s + 1]); p.y = pk2(st[b2][8 * s + 2], st[b2][8 * s + 3]);
;             p.z = pk2(st[b2][8 * s + 4], st[b2][8 * s + 5]); p.w = pk2(st[b2][8 * s + 6], st[b2][8 * s + 7]); pf[2 * b2 + s] = __builtin_bit_cast(bf16x8, p); }
; }
; DEV void pv_load(bf16x8 (&vf)[2][4], const LAS unsigned char* vb, int r, int h) {
; #pragma unroll
;     for (int db = 0; db < 2; ++db)
; #pragma unroll
;         for (int f = 0; f < 4; ++f) { const LAS unsigned char* p = vb + (32 * db + r) * 136 + (16 * f + 4 * h) * 2;
;             const s16x4 lo = *(const LAS s16x4*)p, hi = *(const LAS s16x4*)(p + 16);
;             vf[db][f] = __builtin_shufflevector(lo, hi, 0, 1, 2, 3, 4, 5, 6, 7); }
;     __builtin_amdgcn_sched_barrier(0);
; template <int DQK, int MODE> ...
;     ...
;         LAS unsigned char* kb = lds + AL_K0 + slot * AL_KSTR; LAS unsigned char* vb = lds + AL_V0 + slot * AL_VSTR;
;         const int k0 = 64 * t;
;         bool rowsel = true;
;         if (MODE == 1) rowsel = (selm.x >> (t >> 2)) & 1u;
;         if (MODE == 2) { const int tw = t >> 5; const unsigned w = tw == 0 ? selm.x : (tw == 1 ? selm.y : (tw == 2 ? selm.z : selm.w)); rowsel = (w >> (t & 31)) & 1u; }
;         const bool rowact = rowsel && (k0 <= hi_lim) && (k0 + 63 >= lo_lim);
;         if (__any(rowact ? 1 : 0)) {
;             f32x16 st[2];
;             qk_tile<DQK>(st, kb, qf, r, h);
;             bf16x8 vf[2][4];
;             if (MODE != 3) pv_load(vf, vb, r, h);
;             const bool interior = __all(((k0 + 63 <= hi_lim) && (k0 >= lo_lim)) ? 1 : 0);
.LBB0_1068:
	s_lshl_b32 s21, s18, 6
	s_or_b32 s0, s21, 63
	s_cmp_gt_i32 s0, 0xbfffffff
	v_cmp_le_i32_e32 vcc, s21, v140
	s_cselect_b64 s[22:23], -1, 0
	s_and_b64 vcc, vcc, s[22:23]
	s_cbranch_vccz .LBB0_1074
	s_mul_i32 s1, s20, 0x9c00
	v_add_u32_e32 v0, s1, v152
	ds_read_b128 v[2:5], v0
	ds_read_b128 v[6:9], v0 offset:32
	ds_read_b128 v[10:13], v0 offset:64
	ds_read_b128 v[48:51], v0 offset:96
	ds_read_b128 v[52:55], v0 offset:4608
	ds_read_b128 v[120:123], v0 offset:4640
	ds_read_b128 v[124:127], v0 offset:4672
	ds_read_b128 v[128:131], v0 offset:4704
	s_mul_i32 s1, s20, 0x6600
	s_setprio 1
	s_waitcnt lgkmcnt(7)
	v_mfma_f32_32x32x16_bf16 v[64:79], v[2:5], v[104:107], 0
	s_waitcnt lgkmcnt(6)
	v_mfma_f32_32x32x16_bf16 v[64:79], v[6:9], v[108:111], v[64:79]
	s_waitcnt lgkmcnt(5)
	v_mfma_f32_32x32x16_bf16 v[64:79], v[10:13], v[112:115], v[64:79]
	s_waitcnt lgkmcnt(4)
	v_mfma_f32_32x32x16_bf16 v[64:79], v[48:51], v[116:119], v[64:79]
	s_waitcnt lgkmcnt(3)
	v_mfma_f32_32x32x16_bf16 v[48:63], v[52:55], v[104:107], 0
	s_waitcnt lgkmcnt(2)
	v_mfma_f32_32x32x16_bf16 v[48:63], v[120:123], v[108:111], v[48:63]
	s_waitcnt lgkmcnt(1)
	v_mfma_f32_32x32x16_bf16 v[48:63], v[124:127], v[112:115], v[48:63]
	s_waitcnt lgkmcnt(0)
	v_mfma_f32_32x32x16_bf16 v[48:63], v[128:131], v[116:119], v[48:63]
	s_setprio 0
	v_add_u32_e32 v0, s1, v153
	ds_read2_b64 v[120:123], v0 offset1:2
	ds_read2_b64 v[10:13], v0 offset0:4 offset1:6
	ds_read2_b64 v[6:9], v0 offset0:8 offset1:10
	ds_read2_b64 v[2:5], v0 offset0:12 offset1:14
	v_add_u32_e32 v0, 0x1000, v0
	ds_read2_b64 v[136:139], v0 offset0:32 offset1:34
	ds_read2_b64 v[132:135], v0 offset0:36 offset1:38
	ds_read2_b64 v[128:131], v0 offset0:40 offset1:42
	ds_read2_b64 v[124:127], v0 offset0:44 offset1:46
	s_cmp_gt_i32 s21, 0xbfffffff
	v_cmp_le_i32_e32 vcc, s0, v140
	s_cselect_b64 s[0:1], -1, 0
	s_and_b64 s[0:1], s[0:1], vcc
	v_cndmask_b32_e64 v0, 0, 1, s[0:1]
	v_cmp_ne_u32_e32 vcc, 0, v0
	s_cmp_eq_u64 vcc, exec
	s_cbranch_scc1 .LBB0_1071
; DEV int crow(int i, int h) { return (i & 3) + 8 * (i >> 2) + 4 * h; }
; template <int DQK, int MODE> ...
;     ...
;             const bool interior = __all(((k0 + 63 <= hi_lim) && (k0 >= lo_lim)) ? 1 : 0);
;             if (!interior) {
; #pragma unroll
;                 for (int b2 = 0; b2 < 2; ++b2)
; #pragma unroll
;                     for (int i = 0; i < 16; ++i) { const int key = k0 + 32 * b2 + crow(i, h); const bool vis = (key <= hi_lim) && (key >= lo_lim); st[b2][i] = vis ? st[b2][i] : -INFINITY; }
;             }
	v_add_u32_e32 v0, s21, v154
	v_cmp_gt_i32_e32 vcc, v0, v140
	v_cmp_gt_i32_e64 s[0:1], -2.0, v0
	s_or_b64 vcc, vcc, s[0:1]
	v_add_u32_e32 v14, 1, v0
	v_cndmask_b32_e32 v64, v64, v210, vcc
	v_cmp_gt_i32_e32 vcc, v14, v140
	v_cmp_gt_i32_e64 s[0:1], -2.0, v14
	s_or_b64 vcc, vcc, s[0:1]
	v_add_u32_e32 v14, 2, v0
	v_cndmask_b32_e32 v65, v65, v210, vcc
	v_cmp_gt_i32_e32 vcc, v14, v140
	v_cmp_gt_i32_e64 s[0:1], -2.0, v14
	s_or_b64 vcc, vcc, s[0:1]
	v_add_u32_e32 v14, 3, v0
	v_cndmask_b32_e32 v66, v66, v210, vcc
	v_cmp_gt_i32_e32 vcc, v14, v140
	v_cmp_gt_i32_e64 s[0:1], -2.0, v14
	s_or_b64 vcc, vcc, s[0:1]
	v_add_u32_e32 v14, 8, v0
	v_cndmask_b32_e32 v67, v67, v210, vcc
	v_cmp_gt_i32_e32 vcc, v14, v140
	v_cmp_gt_i32_e64 s[0:1], -2.0, v14
	s_or_b64 vcc, vcc, s[0:1]
	v_add_u32_e32 v14, 9, v0
	v_cndmask_b32_e32 v68, v68, v210, vcc
	v_cmp_gt_i32_e32 vcc, v14, v140
	v_cmp_gt_i32_e64 s[0:1], -2.0, v14
	s_or_b64 vcc, vcc, s[0:1]
	v_add_u32_e32 v14, 10, v0
	v_cndmask_b32_e32 v69, v69, v210, vcc
	v_cmp_gt_i32_e32 vcc, v14, v140
	v_cmp_gt_i32_e64 s[0:1], -2.0, v14
	s_or_b64 vcc, vcc, s[0:1]
	v_add_u32_e32 v14, 11, v0
	v_cndmask_b32_e32 v70, v70, v210, vcc
	v_cmp_gt_i32_e32 vcc, v14, v140
	v_cmp_gt_i32_e64 s[0:1], -2.0, v14
	s_or_b64 vcc, vcc, s[0:1]
	v_add_u32_e32 v14, 16, v0
	v_cndmask_b32_e32 v71, v71, v210, vcc
	v_cmp_gt_i32_e32 vcc, v14, v140
	v_cmp_gt_i32_e64 s[0:1], -2.0, v14
	s_or_b64 vcc, vcc, s[0:1]
	v_add_u32_e32 v14, 17, v0
	v_cndmask_b32_e32 v72, v72, v210, vcc
	v_cmp_gt_i32_e32 vcc, v14, v140
	v_cmp_gt_i32_e64 s[0:1], -2.0, v14
	s_or_b64 vcc, vcc, s[0:1]
	v_add_u32_e32 v14, 18, v0
	v_cndmask_b32_e32 v73, v73, v210, vcc
	v_cmp_gt_i32_e32 vcc, v14, v140
	v_cmp_gt_i32_e64 s[0:1], -2.0, v14
	s_or_b64 vcc, vcc, s[0:1]
	v_add_u32_e32 v14, 19, v0
	v_cndmask_b32_e32 v74, v74, v210, vcc
	v_cmp_gt_i32_e32 vcc, v14, v140
	v_cmp_gt_i32_e64 s[0:1], -2.0, v14
	s_or_b64 vcc, vcc, s[0:1]
	v_add_u32_e32 v14, 24, v0
	v_cndmask_b32_e32 v75, v75, v210, vcc
	v_cmp_gt_i32_e32 vcc, v14, v140
	v_cmp_gt_i32_e64 s[0:1], -2.0, v14
	s_or_b64 vcc, vcc, s[0:1]
	v_add_u32_e32 v14, 25, v0
	v_cndmask_b32_e32 v76, v76, v210, vcc
	v_cmp_gt_i32_e32 vcc, v14, v140
	v_cmp_gt_i32_e64 s[0:1], -2.0, v14
	s_or_b64 vcc, vcc, s[0:1]
	v_add_u32_e32 v14, 26, v0
	v_cndmask_b32_e32 v77, v77, v210, vcc
	v_cmp_gt_i32_e32 vcc, v14, v140
	v_cmp_gt_i32_e64 s[0:1], -2.0, v14
	s_or_b64 vcc, vcc, s[0:1]
	v_add_u32_e32 v14, 27, v0
	v_cndmask_b32_e32 v78, v78, v210, vcc
	v_cmp_gt_i32_e32 vcc, v14, v140
	v_cmp_gt_i32_e64 s[0:1], -2.0, v14
	s_or_b64 vcc, vcc, s[0:1]
	v_add_u32_e32 v14, 32, v0
	v_cndmask_b32_e32 v79, v79, v210, vcc
	v_cmp_gt_i32_e32 vcc, v14, v140
	v_cmp_gt_i32_e64 s[0:1], -2.0, v14
	s_or_b64 vcc, vcc, s[0:1]
	v_add_u32_e32 v14, 33, v0
	v_cndmask_b32_e32 v48, v48, v210, vcc
	v_cmp_gt_i32_e32 vcc, v14, v140
	v_cmp_gt_i32_e64 s[0:1], -2.0, v14
	s_or_b64 vcc, vcc, s[0:1]
	v_add_u32_e32 v14, 34, v0
	v_cndmask_b32_e32 v49, v49, v210, vcc
	v_cmp_gt_i32_e32 vcc, v14, v140
	v_cmp_gt_i32_e64 s[0:1], -2.0, v14
	s_or_b64 vcc, vcc, s[0:1]
	v_add_u32_e32 v14, 35, v0
	v_cndmask_b32_e32 v50, v50, v210, vcc
	v_cmp_gt_i32_e32 vcc, v14, v140
	v_cmp_gt_i32_e64 s[0:1], -2.0, v14
	s_or_b64 vcc, vcc, s[0:1]
	v_add_u32_e32 v14, 40, v0
	v_cndmask_b32_e32 v51, v51, v210, vcc
	v_cmp_gt_i32_e32 vcc, v14, v140
	v_cmp_gt_i32_e64 s[0:1], -2.0, v14
	s_or_b64 vcc, vcc, s[0:1]
	v_add_u32_e32 v14, 41, v0
	v_cndmask_b32_e32 v52, v52, v210, vcc
	v_cmp_gt_i32_e32 vcc, v14, v140
	v_cmp_gt_i32_e64 s[0:1], -2.0, v14
	s_or_b64 vcc, vcc, s[0:1]
	v_add_u32_e32 v14, 42, v0
	v_cndmask_b32_e32 v53, v53, v210, vcc
	v_cmp_gt_i32_e32 vcc, v14, v140
	v_cmp_gt_i32_e64 s[0:1], -2.0, v14
	s_or_b64 vcc, vcc, s[0:1]
	v_add_u32_e32 v14, 43, v0
	v_cndmask_b32_e32 v54, v54, v210, vcc
	v_cmp_gt_i32_e32 vcc, v14, v140
	v_cmp_gt_i32_e64 s[0:1], -2.0, v14
	s_or_b64 vcc, vcc, s[0:1]
	v_add_u32_e32 v14, 48, v0
	v_cndmask_b32_e32 v55, v55, v210, vcc
	v_cmp_gt_i32_e32 vcc, v14, v140
	v_cmp_gt_i32_e64 s[0:1], -2.0, v14
	s_or_b64 vcc, vcc, s[0:1]
	v_add_u32_e32 v14, 49, v0
	v_cndmask_b32_e32 v56, v56, v210, vcc
	v_cmp_gt_i32_e32 vcc, v14, v140
	v_cmp_gt_i32_e64 s[0:1], -2.0, v14
	s_or_b64 vcc, vcc, s[0:1]
	v_add_u32_e32 v14, 50, v0
	v_cndmask_b32_e32 v57, v57, v210, vcc
	v_cmp_gt_i32_e32 vcc, v14, v140
	v_cmp_gt_i32_e64 s[0:1], -2.0, v14
	s_or_b64 vcc, vcc, s[0:1]
	v_add_u32_e32 v14, 51, v0
	v_cndmask_b32_e32 v58, v58, v210, vcc
	v_cmp_gt_i32_e32 vcc, v14, v140
	v_cmp_gt_i32_e64 s[0:1], -2.0, v14
	s_or_b64 vcc, vcc, s[0:1]
	v_add_u32_e32 v14, 56, v0
	v_cndmask_b32_e32 v59, v59, v210, vcc
	v_cmp_gt_i32_e32 vcc, v14, v140
	v_cmp_gt_i32_e64 s[0:1], -2.0, v14
	s_or_b64 vcc, vcc, s[0:1]
	v_add_u32_e32 v14, 57, v0
	v_cndmask_b32_e32 v60, v60, v210, vcc
	v_cmp_gt_i32_e32 vcc, v14, v140
	v_cmp_gt_i32_e64 s[0:1], -2.0, v14
	s_or_b64 vcc, vcc, s[0:1]
	v_add_u32_e32 v14, 58, v0
	v_cndmask_b32_e32 v61, v61, v210, vcc
	v_cmp_gt_i32_e32 vcc, v14, v140
	v_cmp_gt_i32_e64 s[0:1], -2.0, v14
	s_or_b64 vcc, vcc, s[0:1]
	v_add_u32_e32 v0, 59, v0
	v_cndmask_b32_e32 v62, v62, v210, vcc
	v_cmp_gt_i32_e32 vcc, v0, v140
	v_cmp_gt_i32_e64 s[0:1], -2.0, v0
	s_or_b64 vcc, vcc, s[0:1]
	v_cndmask_b32_e32 v63, v63, v210, vcc

; #define MFMA32(a, b, c) __builtin_amdgcn_mfma_f32_32x32x16_bf16((a), (b), (c), 0, 0, 0)
; DEV float fexp2(float x) { return __builtin_amdgcn_exp2f(x); }
; DEV void pv_mma(f32x16 (&o)[2], const bf16x8 (&vf)[2][4], const bf16x8 (&pf)[4]) {
;     __builtin_amdgcn_sched_barrier(0);
; #pragma unroll
;     for (int f = 0; f < 4; ++f)
; #pragma unroll
;         for (int db = 0; db < 2; ++db) o[db] = MFMA32(vf[db][f], pf[f], o[db]);
;     __builtin_amdgcn_sched_barrier(0);
; }
; template <int DQK, int MODE> ...
;     ...
;                 const float cb = rowsel ? -m_new : -INFINITY;
;                 float ps = 0.f;
; #pragma unroll
;                 for (int b2 = 0; b2 < 2; ++b2)
; #pragma unroll
;                     for (int i = 0; i < 16; ++i) { const float p = fexp2(__builtin_fmaf(st[b2][i], sc, cb)); st[b2][i] = p; ps += p; }
;                 l_run += ps;
;                 bf16x8 pf[4]; pack_p(pf, st);
;                 pv_mma(o, vf, pf);
.LBB0_1073:
	v_fma_f32 v14, v64, s63, -v0
	v_exp_f32_e32 v64, v14
	v_fma_f32 v15, v65, s63, -v0
	v_exp_f32_e32 v65, v15
	v_fma_f32 v14, v66, s63, -v0
	v_add_f32_e32 v157, 0, v64
	v_exp_f32_e32 v66, v14
	v_fma_f32 v15, v67, s63, -v0
	v_add_f32_e32 v157, v65, v157
	v_exp_f32_e32 v67, v15
	v_fma_f32 v14, v68, s63, -v0
	v_add_f32_e32 v157, v66, v157
	v_exp_f32_e32 v68, v14
	v_fma_f32 v15, v69, s63, -v0
	v_add_f32_e32 v157, v67, v157
	v_exp_f32_e32 v69, v15
	v_fma_f32 v14, v70, s63, -v0
	v_add_f32_e32 v157, v68, v157
	v_exp_f32_e32 v70, v14
	v_fma_f32 v15, v71, s63, -v0
	v_add_f32_e32 v157, v69, v157
	v_exp_f32_e32 v71, v15
	v_add_f32_e32 v157, v70, v157
	v_add_f32_e32 v157, v71, v157
	v_cvt_pk_bf16_f32 v64, v64, v65
	v_cvt_pk_bf16_f32 v65, v66, v67
	v_cvt_pk_bf16_f32 v66, v68, v69
	v_cvt_pk_bf16_f32 v67, v70, v71
	v_fma_f32 v14, v72, s63, -v0
	v_exp_f32_e32 v72, v14
	v_fma_f32 v15, v73, s63, -v0
	v_exp_f32_e32 v73, v15
	v_mfma_f32_32x32x16_bf16 v[32:47], v[120:123], v[64:67], v[32:47]
	v_mfma_f32_32x32x16_bf16 v[16:31], v[136:139], v[64:67], v[16:31]
	v_fma_f32 v14, v74, s63, -v0
	v_add_f32_e32 v157, v72, v157
	v_exp_f32_e32 v74, v14
	v_fma_f32 v15, v75, s63, -v0
	v_add_f32_e32 v157, v73, v157
	v_exp_f32_e32 v75, v15
	v_fma_f32 v14, v76, s63, -v0
	v_add_f32_e32 v157, v74, v157
	v_exp_f32_e32 v76, v14
	v_fma_f32 v15, v77, s63, -v0
	v_add_f32_e32 v157, v75, v157
	v_exp_f32_e32 v77, v15
	v_fma_f32 v14, v78, s63, -v0
	v_add_f32_e32 v157, v76, v157
	v_exp_f32_e32 v78, v14
	v_fma_f32 v15, v79, s63, -v0
	v_add_f32_e32 v157, v77, v157
	v_exp_f32_e32 v79, v15
	v_add_f32_e32 v157, v78, v157
	v_add_f32_e32 v157, v79, v157
	v_cvt_pk_bf16_f32 v72, v72, v73
	v_cvt_pk_bf16_f32 v73, v74, v75
	v_cvt_pk_bf16_f32 v74, v76, v77
	v_cvt_pk_bf16_f32 v75, v78, v79
	v_fma_f32 v14, v48, s63, -v0
	v_exp_f32_e32 v48, v14
	v_fma_f32 v15, v49, s63, -v0
	v_exp_f32_e32 v49, v15
	v_mfma_f32_32x32x16_bf16 v[32:47], v[10:13], v[72:75], v[32:47]
	v_mfma_f32_32x32x16_bf16 v[16:31], v[132:135], v[72:75], v[16:31]
	v_fma_f32 v14, v50, s63, -v0
	v_add_f32_e32 v157, v48, v157
	v_exp_f32_e32 v50, v14
	v_fma_f32 v15, v51, s63, -v0
	v_add_f32_e32 v157, v49, v157
	v_exp_f32_e32 v51, v15
	v_fma_f32 v14, v52, s63, -v0
	v_add_f32_e32 v157, v50, v157
	v_exp_f32_e32 v52, v14
	v_fma_f32 v15, v53, s63, -v0
	v_add_f32_e32 v157, v51, v157
	v_exp_f32_e32 v53, v15
	v_fma_f32 v14, v54, s63, -v0
	v_add_f32_e32 v157, v52, v157
	v_exp_f32_e32 v54, v14
	v_fma_f32 v15, v55, s63, -v0
	v_add_f32_e32 v157, v53, v157
	v_exp_f32_e32 v55, v15
	v_add_f32_e32 v157, v54, v157
	v_add_f32_e32 v157, v55, v157
	v_cvt_pk_bf16_f32 v48, v48, v49
	v_cvt_pk_bf16_f32 v49, v50, v51
	v_cvt_pk_bf16_f32 v50, v52, v53
	v_cvt_pk_bf16_f32 v51, v54, v55
	v_fma_f32 v14, v56, s63, -v0
	v_exp_f32_e32 v56, v14
	v_fma_f32 v15, v57, s63, -v0
	v_exp_f32_e32 v57, v15
	v_mfma_f32_32x32x16_bf16 v[32:47], v[6:9], v[48:51], v[32:47]
	v_mfma_f32_32x32x16_bf16 v[16:31], v[128:131], v[48:51], v[16:31]
	v_fma_f32 v14, v58, s63, -v0
	v_add_f32_e32 v157, v56, v157
	v_exp_f32_e32 v58, v14
	v_fma_f32 v15, v59, s63, -v0
	v_add_f32_e32 v157, v57, v157
	v_exp_f32_e32 v59, v15
	v_fma_f32 v14, v60, s63, -v0
	v_add_f32_e32 v157, v58, v157
	v_exp_f32_e32 v60, v14
	v_fma_f32 v15, v61, s63, -v0
	v_add_f32_e32 v157, v59, v157
	v_exp_f32_e32 v61, v15
	v_fma_f32 v14, v62, s63, -v0
	v_add_f32_e32 v157, v60, v157
	v_exp_f32_e32 v62, v14
	v_fma_f32 v15, v63, s63, -v0
	v_add_f32_e32 v157, v61, v157
	v_exp_f32_e32 v63, v15
	v_add_f32_e32 v157, v62, v157
	v_add_f32_e32 v157, v63, v157
	v_cvt_pk_bf16_f32 v56, v56, v57
	v_cvt_pk_bf16_f32 v57, v58, v59
	v_cvt_pk_bf16_f32 v58, v60, v61
	v_cvt_pk_bf16_f32 v59, v62, v63
	v_add_f32_e32 v145, v157, v145
	s_nop 0
	v_mfma_f32_32x32x16_bf16 v[32:47], v[2:5], v[56:59], v[32:47]
	v_mfma_f32_32x32x16_bf16 v[16:31], v[124:127], v[56:59], v[16:31]
.LBB0_1074:
	s_cmp_ge_i32 s18, s16
	s_mul_i32 s20, s20, 3
	s_cbranch_scc1 .LBB0_1081
	s_add_i32 s21, s21, 64
	s_or_b32 s0, s21, 63
	s_cmp_gt_i32 s0, 0xbfffffff
	v_cmp_le_i32_e32 vcc, s21, v140
	s_cselect_b64 s[22:23], -1, 0
	s_and_b64 vcc, vcc, s[22:23]
	s_cbranch_vccz .LBB0_1081
	s_add_i32 s1, s20, 1
	s_mul_i32 s22, s1, 0x3400
	v_add_u32_e32 v0, s22, v152
	ds_read_b128 v[2:5], v0
	ds_read_b128 v[6:9], v0 offset:32
	ds_read_b128 v[10:13], v0 offset:64
	ds_read_b128 v[48:51], v0 offset:96
	ds_read_b128 v[52:55], v0 offset:4608
	ds_read_b128 v[120:123], v0 offset:4640
	ds_read_b128 v[124:127], v0 offset:4672
	ds_read_b128 v[128:131], v0 offset:4704
	s_mulk_i32 s1, 0x2200
	s_setprio 1
	s_waitcnt lgkmcnt(7)
	v_mfma_f32_32x32x16_bf16 v[64:79], v[2:5], v[104:107], 0
	s_waitcnt lgkmcnt(6)
	v_mfma_f32_32x32x16_bf16 v[64:79], v[6:9], v[108:111], v[64:79]
	s_waitcnt lgkmcnt(5)
	v_mfma_f32_32x32x16_bf16 v[64:79], v[10:13], v[112:115], v[64:79]
	s_waitcnt lgkmcnt(4)
	v_mfma_f32_32x32x16_bf16 v[64:79], v[48:51], v[116:119], v[64:79]
	s_waitcnt lgkmcnt(3)
	v_mfma_f32_32x32x16_bf16 v[48:63], v[52:55], v[104:107], 0
	s_waitcnt lgkmcnt(2)
	v_mfma_f32_32x32x16_bf16 v[48:63], v[120:123], v[108:111], v[48:63]
	s_waitcnt lgkmcnt(1)
	v_mfma_f32_32x32x16_bf16 v[48:63], v[124:127], v[112:115], v[48:63]
	s_waitcnt lgkmcnt(0)
	v_mfma_f32_32x32x16_bf16 v[48:63], v[128:131], v[116:119], v[48:63]
	s_setprio 0
	v_add_u32_e32 v0, s1, v153
	ds_read2_b64 v[120:123], v0 offset1:2
	ds_read2_b64 v[10:13], v0 offset0:4 offset1:6
	ds_read2_b64 v[6:9], v0 offset0:8 offset1:10
	ds_read2_b64 v[2:5], v0 offset0:12 offset1:14
	v_add_u32_e32 v0, 0x1000, v0
	ds_read2_b64 v[136:139], v0 offset0:32 offset1:34
	ds_read2_b64 v[132:135], v0 offset0:36 offset1:38
	ds_read2_b64 v[128:131], v0 offset0:40 offset1:42
	ds_read2_b64 v[124:127], v0 offset0:44 offset1:46
	s_cmp_gt_i32 s21, 0xbfffffff
	v_cmp_le_i32_e32 vcc, s0, v140
	s_cselect_b64 s[0:1], -1, 0
	s_and_b64 s[0:1], s[0:1], vcc
	v_cndmask_b32_e64 v0, 0, 1, s[0:1]
	v_cmp_ne_u32_e32 vcc, 0, v0
	s_cmp_eq_u64 vcc, exec
	s_cbranch_scc1 .LBB0_1078
; DEV int crow(int i, int h) { return (i & 3) + 8 * (i >> 2) + 4 * h; }
; template <int DQK, int MODE> ...
;     ...
;             const bool interior = __all(((k0 + 63 <= hi_lim) && (k0 >= lo_lim)) ? 1 : 0);
;             if (!interior) {
; #pragma unroll
;                 for (int b2 = 0; b2 < 2; ++b2)
; #pragma unroll
;                     for (int i = 0; i < 16; ++i) { const int key = k0 + 32 * b2 + crow(i, h); const bool vis = (key <= hi_lim) && (key >= lo_lim); st[b2][i] = vis ? st[b2][i] : -INFINITY; }
;             }
	v_add_u32_e32 v0, s21, v154
	v_cmp_gt_i32_e32 vcc, v0, v140
	v_cmp_gt_i32_e64 s[0:1], -2.0, v0
	s_or_b64 vcc, vcc, s[0:1]
	v_add_u32_e32 v14, 1, v0
	v_cndmask_b32_e32 v64, v64, v210, vcc
	v_cmp_gt_i32_e32 vcc, v14, v140
	v_cmp_gt_i32_e64 s[0:1], -2.0, v14
	s_or_b64 vcc, vcc, s[0:1]
	v_add_u32_e32 v14, 2, v0
	v_cndmask_b32_e32 v65, v65, v210, vcc
	v_cmp_gt_i32_e32 vcc, v14, v140
	v_cmp_gt_i32_e64 s[0:1], -2.0, v14
	s_or_b64 vcc, vcc, s[0:1]
	v_add_u32_e32 v14, 3, v0
	v_cndmask_b32_e32 v66, v66, v210, vcc
	v_cmp_gt_i32_e32 vcc, v14, v140
	v_cmp_gt_i32_e64 s[0:1], -2.0, v14
	s_or_b64 vcc, vcc, s[0:1]
	v_add_u32_e32 v14, 8, v0
	v_cndmask_b32_e32 v67, v67, v210, vcc
	v_cmp_gt_i32_e32 vcc, v14, v140
	v_cmp_gt_i32_e64 s[0:1], -2.0, v14
	s_or_b64 vcc, vcc, s[0:1]
	v_add_u32_e32 v14, 9, v0
	v_cndmask_b32_e32 v68, v68, v210, vcc
	v_cmp_gt_i32_e32 vcc, v14, v140
	v_cmp_gt_i32_e64 s[0:1], -2.0, v14
	s_or_b64 vcc, vcc, s[0:1]
	v_add_u32_e32 v14, 10, v0
	v_cndmask_b32_e32 v69, v69, v210, vcc
	v_cmp_gt_i32_e32 vcc, v14, v140
	v_cmp_gt_i32_e64 s[0:1], -2.0, v14
	s_or_b64 vcc, vcc, s[0:1]
	v_add_u32_e32 v14, 11, v0
	v_cndmask_b32_e32 v70, v70, v210, vcc
	v_cmp_gt_i32_e32 vcc, v14, v140
	v_cmp_gt_i32_e64 s[0:1], -2.0, v14
	s_or_b64 vcc, vcc, s[0:1]
	v_add_u32_e32 v14, 16, v0
	v_cndmask_b32_e32 v71, v71, v210, vcc
	v_cmp_gt_i32_e32 vcc, v14, v140
	v_cmp_gt_i32_e64 s[0:1], -2.0, v14
	s_or_b64 vcc, vcc, s[0:1]
	v_add_u32_e32 v14, 17, v0
	v_cndmask_b32_e32 v72, v72, v210, vcc
	v_cmp_gt_i32_e32 vcc, v14, v140
	v_cmp_gt_i32_e64 s[0:1], -2.0, v14
	s_or_b64 vcc, vcc, s[0:1]
	v_add_u32_e32 v14, 18, v0
	v_cndmask_b32_e32 v73, v73, v210, vcc
	v_cmp_gt_i32_e32 vcc, v14, v140
	v_cmp_gt_i32_e64 s[0:1], -2.0, v14
	s_or_b64 vcc, vcc, s[0:1]
	v_add_u32_e32 v14, 19, v0
	v_cndmask_b32_e32 v74, v74, v210, vcc
	v_cmp_gt_i32_e32 vcc, v14, v140
	v_cmp_gt_i32_e64 s[0:1], -2.0, v14
	s_or_b64 vcc, vcc, s[0:1]
	v_add_u32_e32 v14, 24, v0
	v_cndmask_b32_e32 v75, v75, v210, vcc
	v_cmp_gt_i32_e32 vcc, v14, v140
	v_cmp_gt_i32_e64 s[0:1], -2.0, v14
	s_or_b64 vcc, vcc, s[0:1]
	v_add_u32_e32 v14, 25, v0
	v_cndmask_b32_e32 v76, v76, v210, vcc
	v_cmp_gt_i32_e32 vcc, v14, v140
	v_cmp_gt_i32_e64 s[0:1], -2.0, v14
	s_or_b64 vcc, vcc, s[0:1]
	v_add_u32_e32 v14, 26, v0
	v_cndmask_b32_e32 v77, v77, v210, vcc
	v_cmp_gt_i32_e32 vcc, v14, v140
	v_cmp_gt_i32_e64 s[0:1], -2.0, v14
	s_or_b64 vcc, vcc, s[0:1]
	v_add_u32_e32 v14, 27, v0
	v_cndmask_b32_e32 v78, v78, v210, vcc
	v_cmp_gt_i32_e32 vcc, v14, v140
	v_cmp_gt_i32_e64 s[0:1], -2.0, v14
	s_or_b64 vcc, vcc, s[0:1]
	v_add_u32_e32 v14, 32, v0
	v_cndmask_b32_e32 v79, v79, v210, vcc
	v_cmp_gt_i32_e32 vcc, v14, v140
	v_cmp_gt_i32_e64 s[0:1], -2.0, v14
	s_or_b64 vcc, vcc, s[0:1]
	v_add_u32_e32 v14, 33, v0
	v_cndmask_b32_e32 v48, v48, v210, vcc
	v_cmp_gt_i32_e32 vcc, v14, v140
	v_cmp_gt_i32_e64 s[0:1], -2.0, v14
	s_or_b64 vcc, vcc, s[0:1]
	v_add_u32_e32 v14, 34, v0
	v_cndmask_b32_e32 v49, v49, v210, vcc
	v_cmp_gt_i32_e32 vcc, v14, v140
	v_cmp_gt_i32_e64 s[0:1], -2.0, v14
	s_or_b64 vcc, vcc, s[0:1]
	v_add_u32_e32 v14, 35, v0
	v_cndmask_b32_e32 v50, v50, v210, vcc
	v_cmp_gt_i32_e32 vcc, v14, v140
	v_cmp_gt_i32_e64 s[0:1], -2.0, v14
	s_or_b64 vcc, vcc, s[0:1]
	v_add_u32_e32 v14, 40, v0
	v_cndmask_b32_e32 v51, v51, v210, vcc
	v_cmp_gt_i32_e32 vcc, v14, v140
	v_cmp_gt_i32_e64 s[0:1], -2.0, v14
	s_or_b64 vcc, vcc, s[0:1]
	v_add_u32_e32 v14, 41, v0
	v_cndmask_b32_e32 v52, v52, v210, vcc
	v_cmp_gt_i32_e32 vcc, v14, v140
	v_cmp_gt_i32_e64 s[0:1], -2.0, v14
	s_or_b64 vcc, vcc, s[0:1]
	v_add_u32_e32 v14, 42, v0
	v_cndmask_b32_e32 v53, v53, v210, vcc
	v_cmp_gt_i32_e32 vcc, v14, v140
	v_cmp_gt_i32_e64 s[0:1], -2.0, v14
	s_or_b64 vcc, vcc, s[0:1]
	v_add_u32_e32 v14, 43, v0
	v_cndmask_b32_e32 v54, v54, v210, vcc
	v_cmp_gt_i32_e32 vcc, v14, v140
	v_cmp_gt_i32_e64 s[0:1], -2.0, v14
	s_or_b64 vcc, vcc, s[0:1]
	v_add_u32_e32 v14, 48, v0
	v_cndmask_b32_e32 v55, v55, v210, vcc
	v_cmp_gt_i32_e32 vcc, v14, v140
	v_cmp_gt_i32_e64 s[0:1], -2.0, v14
	s_or_b64 vcc, vcc, s[0:1]
	v_add_u32_e32 v14, 49, v0
	v_cndmask_b32_e32 v56, v56, v210, vcc
	v_cmp_gt_i32_e32 vcc, v14, v140
	v_cmp_gt_i32_e64 s[0:1], -2.0, v14
	s_or_b64 vcc, vcc, s[0:1]
	v_add_u32_e32 v14, 50, v0
	v_cndmask_b32_e32 v57, v57, v210, vcc
	v_cmp_gt_i32_e32 vcc, v14, v140
	v_cmp_gt_i32_e64 s[0:1], -2.0, v14
	s_or_b64 vcc, vcc, s[0:1]
	v_add_u32_e32 v14, 51, v0
	v_cndmask_b32_e32 v58, v58, v210, vcc
	v_cmp_gt_i32_e32 vcc, v14, v140
	v_cmp_gt_i32_e64 s[0:1], -2.0, v14
	s_or_b64 vcc, vcc, s[0:1]
	v_add_u32_e32 v14, 56, v0
	v_cndmask_b32_e32 v59, v59, v210, vcc
	v_cmp_gt_i32_e32 vcc, v14, v140
	v_cmp_gt_i32_e64 s[0:1], -2.0, v14
	s_or_b64 vcc, vcc, s[0:1]
	v_add_u32_e32 v14, 57, v0
	v_cndmask_b32_e32 v60, v60, v210, vcc
	v_cmp_gt_i32_e32 vcc, v14, v140
	v_cmp_gt_i32_e64 s[0:1], -2.0, v14
	s_or_b64 vcc, vcc, s[0:1]
	v_add_u32_e32 v14, 58, v0
	v_cndmask_b32_e32 v61, v61, v210, vcc
	v_cmp_gt_i32_e32 vcc, v14, v140
	v_cmp_gt_i32_e64 s[0:1], -2.0, v14
	s_or_b64 vcc, vcc, s[0:1]
	v_add_u32_e32 v0, 59, v0
	v_cndmask_b32_e32 v62, v62, v210, vcc
	v_cmp_gt_i32_e32 vcc, v0, v140
	v_cmp_gt_i32_e64 s[0:1], -2.0, v0
	s_or_b64 vcc, vcc, s[0:1]
	v_cndmask_b32_e32 v63, v63, v210, vcc

; #define LAS __attribute__((address_space(3)))
; #define MFMA32(a, b, c) __builtin_amdgcn_mfma_f32_32x32x16_bf16((a), (b), (c), 0, 0, 0)
; template <int DQK> DEV void qk_tile(f32x16 (&st)[2], const LAS unsigned char* kb, const bf16x8 (&qf)[DQK / 16], int r, int h) {
;     constexpr int KSTR = DQK * 2 + 16, NS = DQK / 16;
;     bf16x8 kf[2][NS];
; #pragma unroll
;     for (int b2 = 0; b2 < 2; ++b2)
; #pragma unroll
;         for (int s = 0; s < NS; ++s) kf[b2][s] = *(const LAS bf16x8*)(kb + (32 * b2 + r) * KSTR + 32 * s + 16 * h);
;     __builtin_amdgcn_sched_barrier(0);
; #pragma unroll
;     for (int b2 = 0; b2 < 2; ++b2) {
;         f32x16 a;
; #pragma unroll
;         for (int i = 0; i < 16; ++i) a[i] = 0.f;
; #pragma unroll
;         for (int s = 0; s < NS; ++s) a = MFMA32(kf[b2][s], qf[s], a);
;         st[b2] = a;
;     }
;     __builtin_amdgcn_sched_barrier(0);
; }
; template <int DQK, int MODE> ...
;     ...
;         LAS unsigned char* kb = lds + AL_K0 + slot * AL_KSTR; LAS unsigned char* vb = lds + AL_V0 + slot * AL_VSTR;
;         const int k0 = 64 * t;
;         bool rowsel = true;
;         if (MODE == 1) rowsel = (selm.x >> (t >> 2)) & 1u;
;         if (MODE == 2) { const int tw = t >> 5; const unsigned w = tw == 0 ? selm.x : (tw == 1 ? selm.y : (tw == 2 ? selm.z : selm.w)); rowsel = (w >> (t & 31)) & 1u; }
;         const bool rowact = rowsel && (k0 <= hi_lim) && (k0 + 63 >= lo_lim);
;         if (__any(rowact ? 1 : 0)) {
;             f32x16 st[2];
;             qk_tile<DQK>(st, kb, qf, r, h);
;             bf16x8 vf[2][4];
;             if (MODE != 3) pv_load(vf, vb, r, h);
;             const bool interior = __all(((k0 + 63 <= hi_lim) && (k0 >= lo_lim)) ? 1 : 0);
.LBB0_1081:
	s_add_i32 s0, s18, 2
	s_cmp_gt_i32 s0, s16
	s_cbranch_scc1 .LBB0_1088
	s_lshl_b32 s0, s0, 6
	s_or_b32 s1, s0, 63
	s_cmp_gt_i32 s1, 0xbfffffff
	v_cmp_le_i32_e32 vcc, s0, v140
	s_cselect_b64 s[22:23], -1, 0
	s_and_b64 vcc, vcc, s[22:23]
	s_cbranch_vccz .LBB0_1088
	s_add_i32 s20, s20, 2
	s_mul_i32 s21, s20, 0x3400
	v_add_u32_e32 v0, s21, v152
	ds_read_b128 v[2:5], v0
	ds_read_b128 v[6:9], v0 offset:32
	ds_read_b128 v[10:13], v0 offset:64
	ds_read_b128 v[48:51], v0 offset:96
	ds_read_b128 v[52:55], v0 offset:4608
	ds_read_b128 v[120:123], v0 offset:4640
	ds_read_b128 v[124:127], v0 offset:4672
	ds_read_b128 v[128:131], v0 offset:4704
	s_mulk_i32 s20, 0x2200
	s_setprio 1
	s_waitcnt lgkmcnt(7)
	v_mfma_f32_32x32x16_bf16 v[64:79], v[2:5], v[104:107], 0
	s_waitcnt lgkmcnt(6)
	v_mfma_f32_32x32x16_bf16 v[64:79], v[6:9], v[108:111], v[64:79]
	s_waitcnt lgkmcnt(5)
	v_mfma_f32_32x32x16_bf16 v[64:79], v[10:13], v[112:115], v[64:79]
	s_waitcnt lgkmcnt(4)
	v_mfma_f32_32x32x16_bf16 v[64:79], v[48:51], v[116:119], v[64:79]
	s_waitcnt lgkmcnt(3)
	v_mfma_f32_32x32x16_bf16 v[48:63], v[52:55], v[104:107], 0
	s_waitcnt lgkmcnt(2)
	v_mfma_f32_32x32x16_bf16 v[48:63], v[120:123], v[108:111], v[48:63]
	s_waitcnt lgkmcnt(1)
	v_mfma_f32_32x32x16_bf16 v[48:63], v[124:127], v[112:115], v[48:63]
	s_waitcnt lgkmcnt(0)
	v_mfma_f32_32x32x16_bf16 v[48:63], v[128:131], v[116:119], v[48:63]
	s_setprio 0
	v_add_u32_e32 v0, s20, v153
	ds_read2_b64 v[120:123], v0 offset1:2
	ds_read2_b64 v[10:13], v0 offset0:4 offset1:6
	ds_read2_b64 v[6:9], v0 offset0:8 offset1:10
	ds_read2_b64 v[2:5], v0 offset0:12 offset1:14
	v_add_u32_e32 v0, 0x1000, v0
	ds_read2_b64 v[136:139], v0 offset0:32 offset1:34
	ds_read2_b64 v[132:135], v0 offset0:36 offset1:38
	ds_read2_b64 v[128:131], v0 offset0:40 offset1:42
	ds_read2_b64 v[124:127], v0 offset0:44 offset1:46
	s_cmp_gt_i32 s18, 0xfefffffd
	v_cmp_le_i32_e32 vcc, s1, v140
	s_cselect_b64 s[20:21], -1, 0
	s_and_b64 s[20:21], s[20:21], vcc
	v_cndmask_b32_e64 v0, 0, 1, s[20:21]
	v_cmp_ne_u32_e32 vcc, 0, v0
	s_cmp_eq_u64 vcc, exec
	s_cbranch_scc1 .LBB0_1085
; DEV int crow(int i, int h) { return (i & 3) + 8 * (i >> 2) + 4 * h; }
; template <int DQK, int MODE> ...
;     ...
;             const bool interior = __all(((k0 + 63 <= hi_lim) && (k0 >= lo_lim)) ? 1 : 0);
;             if (!interior) {
; #pragma unroll
;                 for (int b2 = 0; b2 < 2; ++b2)
; #pragma unroll
;                     for (int i = 0; i < 16; ++i) { const int key = k0 + 32 * b2 + crow(i, h); const bool vis = (key <= hi_lim) && (key >= lo_lim); st[b2][i] = vis ? st[b2][i] : -INFINITY; }
;             }
	v_add_u32_e32 v0, s0, v154
	v_cmp_gt_i32_e32 vcc, v0, v140
	v_cmp_gt_i32_e64 s[0:1], -2.0, v0
	s_or_b64 vcc, vcc, s[0:1]
	v_add_u32_e32 v14, 1, v0
	v_cndmask_b32_e32 v64, v64, v210, vcc
	v_cmp_gt_i32_e32 vcc, v14, v140
	v_cmp_gt_i32_e64 s[0:1], -2.0, v14
	s_or_b64 vcc, vcc, s[0:1]
	v_add_u32_e32 v14, 2, v0
	v_cndmask_b32_e32 v65, v65, v210, vcc
	v_cmp_gt_i32_e32 vcc, v14, v140
	v_cmp_gt_i32_e64 s[0:1], -2.0, v14
	s_or_b64 vcc, vcc, s[0:1]
	v_add_u32_e32 v14, 3, v0
	v_cndmask_b32_e32 v66, v66, v210, vcc
	v_cmp_gt_i32_e32 vcc, v14, v140
	v_cmp_gt_i32_e64 s[0:1], -2.0, v14
	s_or_b64 vcc, vcc, s[0:1]
	v_add_u32_e32 v14, 8, v0
	v_cndmask_b32_e32 v67, v67, v210, vcc
	v_cmp_gt_i32_e32 vcc, v14, v140
	v_cmp_gt_i32_e64 s[0:1], -2.0, v14
	s_or_b64 vcc, vcc, s[0:1]
	v_add_u32_e32 v14, 9, v0
	v_cndmask_b32_e32 v68, v68, v210, vcc
	v_cmp_gt_i32_e32 vcc, v14, v140
	v_cmp_gt_i32_e64 s[0:1], -2.0, v14
	s_or_b64 vcc, vcc, s[0:1]
	v_add_u32_e32 v14, 10, v0
	v_cndmask_b32_e32 v69, v69, v210, vcc
	v_cmp_gt_i32_e32 vcc, v14, v140
	v_cmp_gt_i32_e64 s[0:1], -2.0, v14
	s_or_b64 vcc, vcc, s[0:1]
	v_add_u32_e32 v14, 11, v0
	v_cndmask_b32_e32 v70, v70, v210, vcc
	v_cmp_gt_i32_e32 vcc, v14, v140
	v_cmp_gt_i32_e64 s[0:1], -2.0, v14
	s_or_b64 vcc, vcc, s[0:1]
	v_add_u32_e32 v14, 16, v0
	v_cndmask_b32_e32 v71, v71, v210, vcc
	v_cmp_gt_i32_e32 vcc, v14, v140
	v_cmp_gt_i32_e64 s[0:1], -2.0, v14
	s_or_b64 vcc, vcc, s[0:1]
	v_add_u32_e32 v14, 17, v0
	v_cndmask_b32_e32 v72, v72, v210, vcc
	v_cmp_gt_i32_e32 vcc, v14, v140
	v_cmp_gt_i32_e64 s[0:1], -2.0, v14
	s_or_b64 vcc, vcc, s[0:1]
	v_add_u32_e32 v14, 18, v0
	v_cndmask_b32_e32 v73, v73, v210, vcc
	v_cmp_gt_i32_e32 vcc, v14, v140
	v_cmp_gt_i32_e64 s[0:1], -2.0, v14
	s_or_b64 vcc, vcc, s[0:1]
	v_add_u32_e32 v14, 19, v0
	v_cndmask_b32_e32 v74, v74, v210, vcc
	v_cmp_gt_i32_e32 vcc, v14, v140
	v_cmp_gt_i32_e64 s[0:1], -2.0, v14
	s_or_b64 vcc, vcc, s[0:1]
	v_add_u32_e32 v14, 24, v0
	v_cndmask_b32_e32 v75, v75, v210, vcc
	v_cmp_gt_i32_e32 vcc, v14, v140
	v_cmp_gt_i32_e64 s[0:1], -2.0, v14
	s_or_b64 vcc, vcc, s[0:1]
	v_add_u32_e32 v14, 25, v0
	v_cndmask_b32_e32 v76, v76, v210, vcc
	v_cmp_gt_i32_e32 vcc, v14, v140
	v_cmp_gt_i32_e64 s[0:1], -2.0, v14
	s_or_b64 vcc, vcc, s[0:1]
	v_add_u32_e32 v14, 26, v0
	v_cndmask_b32_e32 v77, v77, v210, vcc
	v_cmp_gt_i32_e32 vcc, v14, v140
	v_cmp_gt_i32_e64 s[0:1], -2.0, v14
	s_or_b64 vcc, vcc, s[0:1]
	v_add_u32_e32 v14, 27, v0
	v_cndmask_b32_e32 v78, v78, v210, vcc
	v_cmp_gt_i32_e32 vcc, v14, v140
	v_cmp_gt_i32_e64 s[0:1], -2.0, v14
	s_or_b64 vcc, vcc, s[0:1]
	v_add_u32_e32 v14, 32, v0
	v_cndmask_b32_e32 v79, v79, v210, vcc
	v_cmp_gt_i32_e32 vcc, v14, v140
	v_cmp_gt_i32_e64 s[0:1], -2.0, v14
	s_or_b64 vcc, vcc, s[0:1]
	v_add_u32_e32 v14, 33, v0
	v_cndmask_b32_e32 v48, v48, v210, vcc
	v_cmp_gt_i32_e32 vcc, v14, v140
	v_cmp_gt_i32_e64 s[0:1], -2.0, v14
	s_or_b64 vcc, vcc, s[0:1]
	v_add_u32_e32 v14, 34, v0
	v_cndmask_b32_e32 v49, v49, v210, vcc
	v_cmp_gt_i32_e32 vcc, v14, v140
	v_cmp_gt_i32_e64 s[0:1], -2.0, v14
	s_or_b64 vcc, vcc, s[0:1]
	v_add_u32_e32 v14, 35, v0
	v_cndmask_b32_e32 v50, v50, v210, vcc
	v_cmp_gt_i32_e32 vcc, v14, v140
	v_cmp_gt_i32_e64 s[0:1], -2.0, v14
	s_or_b64 vcc, vcc, s[0:1]
	v_add_u32_e32 v14, 40, v0
	v_cndmask_b32_e32 v51, v51, v210, vcc
	v_cmp_gt_i32_e32 vcc, v14, v140
	v_cmp_gt_i32_e64 s[0:1], -2.0, v14
	s_or_b64 vcc, vcc, s[0:1]
	v_add_u32_e32 v14, 41, v0
	v_cndmask_b32_e32 v52, v52, v210, vcc
	v_cmp_gt_i32_e32 vcc, v14, v140
	v_cmp_gt_i32_e64 s[0:1], -2.0, v14
	s_or_b64 vcc, vcc, s[0:1]
	v_add_u32_e32 v14, 42, v0
	v_cndmask_b32_e32 v53, v53, v210, vcc
	v_cmp_gt_i32_e32 vcc, v14, v140
	v_cmp_gt_i32_e64 s[0:1], -2.0, v14
	s_or_b64 vcc, vcc, s[0:1]
	v_add_u32_e32 v14, 43, v0
	v_cndmask_b32_e32 v54, v54, v210, vcc
	v_cmp_gt_i32_e32 vcc, v14, v140
	v_cmp_gt_i32_e64 s[0:1], -2.0, v14
	s_or_b64 vcc, vcc, s[0:1]
	v_add_u32_e32 v14, 48, v0
	v_cndmask_b32_e32 v55, v55, v210, vcc
	v_cmp_gt_i32_e32 vcc, v14, v140
	v_cmp_gt_i32_e64 s[0:1], -2.0, v14
	s_or_b64 vcc, vcc, s[0:1]
	v_add_u32_e32 v14, 49, v0
	v_cndmask_b32_e32 v56, v56, v210, vcc
	v_cmp_gt_i32_e32 vcc, v14, v140
	v_cmp_gt_i32_e64 s[0:1], -2.0, v14
	s_or_b64 vcc, vcc, s[0:1]
	v_add_u32_e32 v14, 50, v0
	v_cndmask_b32_e32 v57, v57, v210, vcc
	v_cmp_gt_i32_e32 vcc, v14, v140
	v_cmp_gt_i32_e64 s[0:1], -2.0, v14
	s_or_b64 vcc, vcc, s[0:1]
	v_add_u32_e32 v14, 51, v0
	v_cndmask_b32_e32 v58, v58, v210, vcc
	v_cmp_gt_i32_e32 vcc, v14, v140
	v_cmp_gt_i32_e64 s[0:1], -2.0, v14
	s_or_b64 vcc, vcc, s[0:1]
	v_add_u32_e32 v14, 56, v0
	v_cndmask_b32_e32 v59, v59, v210, vcc
	v_cmp_gt_i32_e32 vcc, v14, v140
	v_cmp_gt_i32_e64 s[0:1], -2.0, v14
	s_or_b64 vcc, vcc, s[0:1]
	v_add_u32_e32 v14, 57, v0
	v_cndmask_b32_e32 v60, v60, v210, vcc
	v_cmp_gt_i32_e32 vcc, v14, v140
	v_cmp_gt_i32_e64 s[0:1], -2.0, v14
	s_or_b64 vcc, vcc, s[0:1]
	v_add_u32_e32 v14, 58, v0
	v_cndmask_b32_e32 v61, v61, v210, vcc
	v_cmp_gt_i32_e32 vcc, v14, v140
	v_cmp_gt_i32_e64 s[0:1], -2.0, v14
	s_or_b64 vcc, vcc, s[0:1]
	v_add_u32_e32 v0, 59, v0
	v_cndmask_b32_e32 v62, v62, v210, vcc
	v_cmp_gt_i32_e32 vcc, v0, v140
	v_cmp_gt_i32_e64 s[0:1], -2.0, v0
	s_or_b64 vcc, vcc, s[0:1]
	v_cndmask_b32_e32 v63, v63, v210, vcc

; __device__ __forceinline__ unsigned f2bf_(float f) { unsigned u = __builtin_bit_cast(unsigned, f); return (u + 0x7fffu + ((u >> 16) & 1u)) >> 16; }
; __device__ __forceinline__ unsigned pk2_(float lo, float hi) { return f2bf_(lo) | (f2bf_(hi) << 16); }
; template <int ACT> __device__ __forceinline__ float act_f(float v) {
;     if (ACT == 2) { const float t = fmaxf(v, 0.f); return t * t; }
;     if (ACT == 3) { const float u = 0.7978845608028654f * (v + 0.044715f * v * v * v); const float e = __expf(2.f * u); const float th = 1.f - 2.f / (e + 1.f); return 0.5f * v * (1.f + th); }
;     __device__ __forceinline__ void operator()(const f32x4 (&acc)[2][2][4][2], const Unit& u, int wr, int wc, int fr, int fq) const {
;     ...
;             for (int m = 0; m < 4; ++m) { bf16_t* rowp = O + (size_t)(row0 + ai * HALF + m * 16) * ldc + col0;
; #pragma unroll
;                 for (int bj = 0; bj < 2; ++bj) { f32x4 v0 = acc[ai][bj][m][0], v1 = acc[ai][bj][m][1];
;                     if (bias) { v0 += *(const f32x4*)(bias + col0 + bj * HALF); v1 += *(const f32x4*)(bias + col0 + bj * HALF + 4); }
;                     u32x4 w; w.x = pk2_(act_f<ACT>(v0[0]), act_f<ACT>(v0[1])); w.y = pk2_(act_f<ACT>(v0[2]), act_f<ACT>(v0[3]));
;                     w.z = pk2_(act_f<ACT>(v1[0]), act_f<ACT>(v1[1])); w.w = pk2_(act_f<ACT>(v1[2]), act_f<ACT>(v1[3]));
;                     *(u32x4*)(rowp + bj * HALF) = w; } }
.LBB0_1327:
	v_mov_b32_e32 v145, v147
	v_mov_b32_e32 v144, v146
	s_lshl_b32 s27, s36, 8
	s_add_i32 s27, s27, s46
	v_add_u32_e32 v144, s27, v144
	s_lshl_b32 s27, s66, 8
	s_or_b32 s27, s27, s47
	v_lshl_add_u32 v152, v145, 3, s27
	v_ashrrev_i32_e32 v145, 31, v144
	v_lshlrev_b64 v[144:145], 13, v[144:145]
	v_ashrrev_i32_e32 v153, 31, v152
	v_lshl_add_u64 v[144:145], s[72:73], 0, v[144:145]
	v_lshl_add_u64 v[144:145], v[152:153], 1, v[144:145]
	v_max_f32_e32 v152, 0, v125
	v_max_f32_e32 v125, v126, v126
	v_max_f32_e32 v126, v127, v127
	v_max_f32_e32 v153, 0, v126
	v_pk_mul_f32 v[126:127], v[152:153], v[152:153]
	v_max_f32_e32 v152, 0, v121
	v_max_f32_e32 v121, v122, v122
	v_max_f32_e32 v122, v123, v123
	v_max_f32_e32 v153, 0, v122
	v_max_f32_e32 v124, 0, v124
	v_max_f32_e32 v125, 0, v125
	v_max_f32_e32 v120, 0, v120
	v_max_f32_e32 v121, 0, v121
	v_pk_mul_f32 v[122:123], v[152:153], v[152:153]
	v_pk_mul_f32 v[124:125], v[124:125], v[124:125]
	v_pk_mul_f32 v[120:121], v[120:121], v[120:121]
	v_cvt_pk_bf16_f32 v123, v121, v123
	v_cvt_pk_bf16_f32 v122, v120, v122
	v_cvt_pk_bf16_f32 v121, v125, v127
	v_cvt_pk_bf16_f32 v120, v124, v126
	global_store_dwordx4 v[144:145], v[120:123], off
	s_nop 1
	v_max_f32_e32 v120, 0, v117
	v_max_f32_e32 v117, v118, v118
	v_max_f32_e32 v118, v119, v119
	v_max_f32_e32 v121, 0, v118
	v_pk_mul_f32 v[118:119], v[120:121], v[120:121]
	v_max_f32_e32 v120, 0, v113
	v_max_f32_e32 v113, v114, v114
	v_max_f32_e32 v114, v115, v115
	v_max_f32_e32 v121, 0, v114
	v_max_f32_e32 v116, 0, v116
	v_max_f32_e32 v117, 0, v117
	v_max_f32_e32 v112, 0, v112
	v_max_f32_e32 v113, 0, v113
	v_pk_mul_f32 v[114:115], v[120:121], v[120:121]
	v_pk_mul_f32 v[116:117], v[116:117], v[116:117]
	v_pk_mul_f32 v[112:113], v[112:113], v[112:113]
	v_cvt_pk_bf16_f32 v115, v113, v115
	v_cvt_pk_bf16_f32 v114, v112, v114
	v_cvt_pk_bf16_f32 v113, v117, v119
	v_cvt_pk_bf16_f32 v112, v116, v118
	global_store_dwordx4 v[144:145], v[112:115], off offset:256
	s_nop 1
	v_max_f32_e32 v114, 0, v109
	v_max_f32_e32 v109, v110, v110
	v_max_f32_e32 v110, v111, v111
	v_max_f32_e32 v115, 0, v110
	v_pk_mul_f32 v[110:111], v[114:115], v[114:115]
	v_max_f32_e32 v114, 0, v105
	v_max_f32_e32 v105, v106, v106
	v_max_f32_e32 v106, v107, v107
	v_max_f32_e32 v115, 0, v106
	v_max_f32_e32 v108, 0, v108
	v_max_f32_e32 v109, 0, v109
	v_max_f32_e32 v104, 0, v104
	v_max_f32_e32 v105, 0, v105
	v_pk_mul_f32 v[106:107], v[114:115], v[114:115]
	v_pk_mul_f32 v[108:109], v[108:109], v[108:109]
	v_pk_mul_f32 v[104:105], v[104:105], v[104:105]
	s_mov_b32 s27, 0x20000
	v_cvt_pk_bf16_f32 v106, v104, v106
	v_cvt_pk_bf16_f32 v104, v108, v110
	v_add_co_u32_e32 v108, vcc, s27, v144
	v_cvt_pk_bf16_f32 v107, v105, v107
	v_cvt_pk_bf16_f32 v105, v109, v111
	v_addc_co_u32_e32 v109, vcc, 0, v145, vcc
	global_store_dwordx4 v[108:109], v[104:107], off
	s_nop 1
	v_max_f32_e32 v104, 0, v101
	v_max_f32_e32 v101, v102, v102
	v_max_f32_e32 v102, v103, v103
	v_max_f32_e32 v105, 0, v102
	v_pk_mul_f32 v[102:103], v[104:105], v[104:105]
	v_max_f32_e32 v104, 0, v97
	v_max_f32_e32 v97, v98, v98
	v_max_f32_e32 v98, v99, v99
	v_max_f32_e32 v105, 0, v98
	v_max_f32_e32 v100, 0, v100
	v_max_f32_e32 v101, 0, v101
	v_max_f32_e32 v96, 0, v96
	v_max_f32_e32 v97, 0, v97
	v_pk_mul_f32 v[98:99], v[104:105], v[104:105]
	v_pk_mul_f32 v[100:101], v[100:101], v[100:101]
	v_pk_mul_f32 v[96:97], v[96:97], v[96:97]
	s_mov_b64 s[38:39], 0x20000
	v_lshl_add_u64 v[112:113], v[144:145], 0, s[38:39]
	v_cvt_pk_bf16_f32 v99, v97, v99
	v_cvt_pk_bf16_f32 v98, v96, v98
	v_cvt_pk_bf16_f32 v97, v101, v103
	v_cvt_pk_bf16_f32 v96, v100, v102
	global_store_dwordx4 v[112:113], v[96:99], off offset:256
	s_nop 1
	v_max_f32_e32 v98, 0, v93
	v_max_f32_e32 v93, v94, v94
	v_max_f32_e32 v94, v95, v95
	v_max_f32_e32 v99, 0, v94
	v_pk_mul_f32 v[94:95], v[98:99], v[98:99]
	v_max_f32_e32 v98, 0, v89
	v_max_f32_e32 v89, v90, v90
	v_max_f32_e32 v90, v91, v91
	v_max_f32_e32 v99, 0, v90
	v_max_f32_e32 v92, 0, v92
	v_max_f32_e32 v93, 0, v93
	v_max_f32_e32 v88, 0, v88
	v_max_f32_e32 v89, 0, v89
	v_pk_mul_f32 v[90:91], v[98:99], v[98:99]
	v_pk_mul_f32 v[92:93], v[92:93], v[92:93]
	v_pk_mul_f32 v[88:89], v[88:89], v[88:89]
	s_mov_b32 s27, 0x40000
	v_cvt_pk_bf16_f32 v90, v88, v90
	v_cvt_pk_bf16_f32 v88, v92, v94
	v_add_co_u32_e32 v92, vcc, s27, v144
	v_cvt_pk_bf16_f32 v91, v89, v91
	v_cvt_pk_bf16_f32 v89, v93, v95
	v_addc_co_u32_e32 v93, vcc, 0, v145, vcc
	global_store_dwordx4 v[92:93], v[88:91], off
	s_nop 1
	v_max_f32_e32 v88, 0, v85
	v_max_f32_e32 v85, v86, v86
	v_max_f32_e32 v86, v87, v87
	v_max_f32_e32 v89, 0, v86
	v_pk_mul_f32 v[86:87], v[88:89], v[88:89]
	v_max_f32_e32 v88, 0, v81
	v_max_f32_e32 v81, v82, v82
	v_max_f32_e32 v82, v83, v83
	v_max_f32_e32 v89, 0, v82
	v_max_f32_e32 v84, 0, v84
	v_max_f32_e32 v85, 0, v85
	v_max_f32_e32 v80, 0, v80
	v_max_f32_e32 v81, 0, v81
	v_pk_mul_f32 v[82:83], v[88:89], v[88:89]
	v_pk_mul_f32 v[84:85], v[84:85], v[84:85]
	v_pk_mul_f32 v[80:81], v[80:81], v[80:81]
	s_mov_b64 s[38:39], 0x40000
	v_lshl_add_u64 v[96:97], v[144:145], 0, s[38:39]
	v_cvt_pk_bf16_f32 v83, v81, v83
	v_cvt_pk_bf16_f32 v82, v80, v82
	v_cvt_pk_bf16_f32 v81, v85, v87
	v_cvt_pk_bf16_f32 v80, v84, v86
	global_store_dwordx4 v[96:97], v[80:83], off offset:256
	s_nop 1
	v_max_f32_e32 v82, 0, v77
	v_max_f32_e32 v77, v78, v78
	v_max_f32_e32 v78, v79, v79
	v_max_f32_e32 v83, 0, v78
	v_pk_mul_f32 v[78:79], v[82:83], v[82:83]
	v_max_f32_e32 v82, 0, v73
	v_max_f32_e32 v73, v74, v74
	v_max_f32_e32 v74, v75, v75
	v_max_f32_e32 v83, 0, v74
	v_max_f32_e32 v76, 0, v76
	v_max_f32_e32 v77, 0, v77
	v_max_f32_e32 v72, 0, v72
	v_max_f32_e32 v73, 0, v73
	v_pk_mul_f32 v[74:75], v[82:83], v[82:83]
; __device__ __forceinline__ unsigned f2bf_(float f) { unsigned u = __builtin_bit_cast(unsigned, f); return (u + 0x7fffu + ((u >> 16) & 1u)) >> 16; }
; __device__ __forceinline__ unsigned pk2_(float lo, float hi) { return f2bf_(lo) | (f2bf_(hi) << 16); }
; template <int ACT> __device__ __forceinline__ float act_f(float v) {
;     if (ACT == 2) { const float t = fmaxf(v, 0.f); return t * t; }
;     if (ACT == 3) { const float u = 0.7978845608028654f * (v + 0.044715f * v * v * v); const float e = __expf(2.f * u); const float th = 1.f - 2.f / (e + 1.f); return 0.5f * v * (1.f + th); }
;     __device__ __forceinline__ void operator()(const f32x4 (&acc)[2][2][4][2], const Unit& u, int wr, int wc, int fr, int fq) const {
;     ...
;             for (int m = 0; m < 4; ++m) { bf16_t* rowp = O + (size_t)(row0 + ai * HALF + m * 16) * ldc + col0;
; #pragma unroll
;                 for (int bj = 0; bj < 2; ++bj) { f32x4 v0 = acc[ai][bj][m][0], v1 = acc[ai][bj][m][1];
;                     if (bias) { v0 += *(const f32x4*)(bias + col0 + bj * HALF); v1 += *(const f32x4*)(bias + col0 + bj * HALF + 4); }
;                     u32x4 w; w.x = pk2_(act_f<ACT>(v0[0]), act_f<ACT>(v0[1])); w.y = pk2_(act_f<ACT>(v0[2]), act_f<ACT>(v0[3]));
;                     w.z = pk2_(act_f<ACT>(v1[0]), act_f<ACT>(v1[1])); w.w = pk2_(act_f<ACT>(v1[2]), act_f<ACT>(v1[3]));
;                     *(u32x4*)(rowp + bj * HALF) = w; } }
	v_pk_mul_f32 v[76:77], v[76:77], v[76:77]
	v_pk_mul_f32 v[72:73], v[72:73], v[72:73]
	s_mov_b32 s27, 0x60000
	v_cvt_pk_bf16_f32 v74, v72, v74
	v_cvt_pk_bf16_f32 v72, v76, v78
	v_add_co_u32_e32 v76, vcc, s27, v144
	v_cvt_pk_bf16_f32 v75, v73, v75
	v_cvt_pk_bf16_f32 v73, v77, v79
	v_addc_co_u32_e32 v77, vcc, 0, v145, vcc
	global_store_dwordx4 v[76:77], v[72:75], off
	s_nop 1
	v_max_f32_e32 v72, 0, v69
	v_max_f32_e32 v69, v70, v70
	v_max_f32_e32 v70, v71, v71
	v_max_f32_e32 v73, 0, v70
	v_pk_mul_f32 v[70:71], v[72:73], v[72:73]
	v_max_f32_e32 v72, 0, v65
	v_max_f32_e32 v65, v66, v66
	v_max_f32_e32 v66, v67, v67
	v_max_f32_e32 v73, 0, v66
	v_max_f32_e32 v68, 0, v68
	v_max_f32_e32 v69, 0, v69
	v_max_f32_e32 v64, 0, v64
	v_max_f32_e32 v65, 0, v65
	v_pk_mul_f32 v[66:67], v[72:73], v[72:73]
	v_pk_mul_f32 v[68:69], v[68:69], v[68:69]
	v_pk_mul_f32 v[64:65], v[64:65], v[64:65]
	s_mov_b64 s[38:39], 0x60000
	v_lshl_add_u64 v[80:81], v[144:145], 0, s[38:39]
	v_cvt_pk_bf16_f32 v67, v65, v67
	v_cvt_pk_bf16_f32 v66, v64, v66
	v_cvt_pk_bf16_f32 v65, v69, v71
	v_cvt_pk_bf16_f32 v64, v68, v70
	global_store_dwordx4 v[80:81], v[64:67], off offset:256
	s_nop 1
	v_max_f32_e32 v66, 0, v61
	v_max_f32_e32 v61, v62, v62
	v_max_f32_e32 v62, v63, v63
	v_max_f32_e32 v67, 0, v62
	v_pk_mul_f32 v[62:63], v[66:67], v[66:67]
	v_max_f32_e32 v66, 0, v57
	v_max_f32_e32 v57, v58, v58
	v_max_f32_e32 v58, v59, v59
	v_max_f32_e32 v67, 0, v58
	v_max_f32_e32 v60, 0, v60
	v_max_f32_e32 v61, 0, v61
	v_max_f32_e32 v56, 0, v56
	v_max_f32_e32 v57, 0, v57
	v_pk_mul_f32 v[58:59], v[66:67], v[66:67]
	v_pk_mul_f32 v[60:61], v[60:61], v[60:61]
	v_pk_mul_f32 v[56:57], v[56:57], v[56:57]
	s_mov_b32 s27, 0x100000
	v_cvt_pk_bf16_f32 v58, v56, v58
	v_cvt_pk_bf16_f32 v56, v60, v62
	v_add_co_u32_e32 v60, vcc, s27, v144
	v_cvt_pk_bf16_f32 v59, v57, v59
	v_cvt_pk_bf16_f32 v57, v61, v63
	v_addc_co_u32_e32 v61, vcc, 0, v145, vcc
	global_store_dwordx4 v[60:61], v[56:59], off
	s_nop 1
	v_max_f32_e32 v56, 0, v53
	v_max_f32_e32 v53, v54, v54
	v_max_f32_e32 v54, v55, v55
	v_max_f32_e32 v57, 0, v54
	v_pk_mul_f32 v[54:55], v[56:57], v[56:57]
	v_max_f32_e32 v56, 0, v49
	v_max_f32_e32 v49, v50, v50
	v_max_f32_e32 v50, v51, v51
	v_max_f32_e32 v57, 0, v50
	v_max_f32_e32 v52, 0, v52
	v_max_f32_e32 v53, 0, v53
	v_max_f32_e32 v48, 0, v48
	v_max_f32_e32 v49, 0, v49
	v_pk_mul_f32 v[50:51], v[56:57], v[56:57]
	v_pk_mul_f32 v[52:53], v[52:53], v[52:53]
	v_pk_mul_f32 v[48:49], v[48:49], v[48:49]
	s_mov_b64 s[38:39], 0x100000
	v_lshl_add_u64 v[64:65], v[144:145], 0, s[38:39]
	v_cvt_pk_bf16_f32 v51, v49, v51
	v_cvt_pk_bf16_f32 v50, v48, v50
	v_cvt_pk_bf16_f32 v49, v53, v55
	v_cvt_pk_bf16_f32 v48, v52, v54
	global_store_dwordx4 v[64:65], v[48:51], off offset:256
	s_nop 1
	v_max_f32_e32 v50, 0, v45
	v_max_f32_e32 v45, v46, v46
	v_max_f32_e32 v46, v47, v47
	v_max_f32_e32 v51, 0, v46
	v_pk_mul_f32 v[46:47], v[50:51], v[50:51]
	v_max_f32_e32 v50, 0, v41
	v_max_f32_e32 v41, v42, v42
	v_max_f32_e32 v42, v43, v43
	v_max_f32_e32 v51, 0, v42
	v_max_f32_e32 v44, 0, v44
	v_max_f32_e32 v45, 0, v45
	v_max_f32_e32 v40, 0, v40
	v_max_f32_e32 v41, 0, v41
	v_pk_mul_f32 v[42:43], v[50:51], v[50:51]
	v_pk_mul_f32 v[44:45], v[44:45], v[44:45]
	v_pk_mul_f32 v[40:41], v[40:41], v[40:41]
	v_cvt_pk_bf16_f32 v42, v40, v42
	v_cvt_pk_bf16_f32 v40, v44, v46
	v_add_co_u32_e32 v44, vcc, s63, v144
	v_cvt_pk_bf16_f32 v43, v41, v43
	v_cvt_pk_bf16_f32 v41, v45, v47
	v_addc_co_u32_e32 v45, vcc, 0, v145, vcc
	global_store_dwordx4 v[44:45], v[40:43], off
	s_nop 1
	v_max_f32_e32 v40, 0, v37
	v_max_f32_e32 v37, v38, v38
	v_max_f32_e32 v38, v39, v39
	v_max_f32_e32 v41, 0, v38
	v_pk_mul_f32 v[38:39], v[40:41], v[40:41]
	v_max_f32_e32 v40, 0, v33
	v_max_f32_e32 v33, v34, v34
; __device__ __forceinline__ unsigned pk2_(float lo, float hi) { return f2bf_(lo) | (f2bf_(hi) << 16); }
; #define PG8_BAR __builtin_amdgcn_s_barrier()
;     __device__ __forceinline__ void operator()(const f32x4 (&acc)[2][2][4][2], const Unit& u, int wr, int wc, int fr, int fq) const {
;     ...
;             for (int m = 0; m < 4; ++m) { bf16_t* rowp = O + (size_t)(row0 + ai * HALF + m * 16) * ldc + col0;
; #pragma unroll
;                 for (int bj = 0; bj < 2; ++bj) { f32x4 v0 = acc[ai][bj][m][0], v1 = acc[ai][bj][m][1];
;                     if (bias) { v0 += *(const f32x4*)(bias + col0 + bj * HALF); v1 += *(const f32x4*)(bias + col0 + bj * HALF + 4); }
;                     u32x4 w; w.x = pk2_(act_f<ACT>(v0[0]), act_f<ACT>(v0[1])); w.y = pk2_(act_f<ACT>(v0[2]), act_f<ACT>(v0[3]));
;                     w.z = pk2_(act_f<ACT>(v1[0]), act_f<ACT>(v1[1])); w.w = pk2_(act_f<ACT>(v1[2]), act_f<ACT>(v1[3]));
;                     *(u32x4*)(rowp + bj * HALF) = w; } }
; template <class Epi, class Sched, bool ALIGN_EPI = false, bool SP2 = false>
; __device__ __forceinline__ void gemm_phase(PG8_LAS unsigned char* lds, const Gemm g, const Sched S, const Epi E) {
;     ...
;         if constexpr (ALIGN_EPI) { if (wr == 0) PG8_BAR; }
;         if constexpr (!Epi::AFTER_DRAIN) { E(acc, cur, wr, wc, fr, fq); S.done(cur); }
;         if (!has_next) break;
; #pragma unroll
;         for (int a = 0; a < 2; ++a)
; #pragma unroll
;             for (int b = 0; b < 2; ++b)
; #pragma unroll
;                 for (int m = 0; m < 4; ++m)
; #pragma unroll
;                     for (int n = 0; n < 2; ++n) acc[a][b][m][n] = (f32x4){0.f, 0.f, 0.f, 0.f};
;         cur = nxt; cA = nA; cB = nB; ++ui;
;         if constexpr (ALIGN_EPI) { if (wr == 1) PG8_BAR; }
	v_max_f32_e32 v34, v35, v35
	v_max_f32_e32 v41, 0, v34
	v_max_f32_e32 v36, 0, v36
	v_max_f32_e32 v37, 0, v37
	v_max_f32_e32 v32, 0, v32
	v_max_f32_e32 v33, 0, v33
	v_pk_mul_f32 v[34:35], v[40:41], v[40:41]
	v_pk_mul_f32 v[36:37], v[36:37], v[36:37]
	v_pk_mul_f32 v[32:33], v[32:33], v[32:33]
	s_mov_b64 s[38:39], 0x120000
	v_lshl_add_u64 v[48:49], v[144:145], 0, s[38:39]
	v_cvt_pk_bf16_f32 v35, v33, v35
	v_cvt_pk_bf16_f32 v34, v32, v34
	v_cvt_pk_bf16_f32 v33, v37, v39
	v_cvt_pk_bf16_f32 v32, v36, v38
	global_store_dwordx4 v[48:49], v[32:35], off offset:256
	s_nop 1
	v_max_f32_e32 v34, 0, v29
	v_max_f32_e32 v29, v30, v30
	v_max_f32_e32 v30, v31, v31
	v_max_f32_e32 v35, 0, v30
	v_pk_mul_f32 v[30:31], v[34:35], v[34:35]
	v_max_f32_e32 v34, 0, v25
	v_max_f32_e32 v25, v26, v26
	v_max_f32_e32 v26, v27, v27
	v_max_f32_e32 v35, 0, v26
	v_max_f32_e32 v28, 0, v28
	v_max_f32_e32 v29, 0, v29
	v_max_f32_e32 v24, 0, v24
	v_max_f32_e32 v25, 0, v25
	v_pk_mul_f32 v[26:27], v[34:35], v[34:35]
	v_pk_mul_f32 v[28:29], v[28:29], v[28:29]
	v_pk_mul_f32 v[24:25], v[24:25], v[24:25]
	v_cvt_pk_bf16_f32 v26, v24, v26
	v_cvt_pk_bf16_f32 v24, v28, v30
	v_add_co_u32_e32 v28, vcc, s64, v144
	v_cvt_pk_bf16_f32 v27, v25, v27
	v_cvt_pk_bf16_f32 v25, v29, v31
	v_addc_co_u32_e32 v29, vcc, 0, v145, vcc
	global_store_dwordx4 v[28:29], v[24:27], off
	s_nop 1
	v_max_f32_e32 v24, 0, v21
	v_max_f32_e32 v21, v22, v22
	v_max_f32_e32 v22, v23, v23
	v_max_f32_e32 v25, 0, v22
	v_pk_mul_f32 v[22:23], v[24:25], v[24:25]
	v_max_f32_e32 v24, 0, v17
	v_max_f32_e32 v17, v18, v18
	v_max_f32_e32 v18, v19, v19
	v_max_f32_e32 v25, 0, v18
	v_max_f32_e32 v20, 0, v20
	v_max_f32_e32 v21, 0, v21
	v_max_f32_e32 v16, 0, v16
	v_max_f32_e32 v17, 0, v17
	v_pk_mul_f32 v[18:19], v[24:25], v[24:25]
	v_pk_mul_f32 v[20:21], v[20:21], v[20:21]
	v_pk_mul_f32 v[16:17], v[16:17], v[16:17]
	v_lshl_add_u64 v[32:33], v[144:145], 0, s[22:23]
	v_cvt_pk_bf16_f32 v19, v17, v19
	v_cvt_pk_bf16_f32 v18, v16, v18
	v_cvt_pk_bf16_f32 v17, v21, v23
	v_cvt_pk_bf16_f32 v16, v20, v22
	global_store_dwordx4 v[32:33], v[16:19], off offset:256
	s_nop 1
	v_max_f32_e32 v18, 0, v13
	v_max_f32_e32 v13, v14, v14
	v_max_f32_e32 v14, v15, v15
	v_max_f32_e32 v19, 0, v14
	v_pk_mul_f32 v[14:15], v[18:19], v[18:19]
	v_max_f32_e32 v18, 0, v9
	v_max_f32_e32 v9, v10, v10
	v_max_f32_e32 v10, v11, v11
	v_max_f32_e32 v19, 0, v10
	v_max_f32_e32 v12, 0, v12
	v_max_f32_e32 v13, 0, v13
	v_max_f32_e32 v8, 0, v8
	v_max_f32_e32 v9, 0, v9
	v_pk_mul_f32 v[10:11], v[18:19], v[18:19]
	v_pk_mul_f32 v[12:13], v[12:13], v[12:13]
	v_pk_mul_f32 v[8:9], v[8:9], v[8:9]
	v_cvt_pk_bf16_f32 v10, v8, v10
	v_cvt_pk_bf16_f32 v8, v12, v14
	v_add_co_u32_e32 v12, vcc, s65, v144
	v_cvt_pk_bf16_f32 v11, v9, v11
	v_cvt_pk_bf16_f32 v9, v13, v15
	v_addc_co_u32_e32 v13, vcc, 0, v145, vcc
	global_store_dwordx4 v[12:13], v[8:11], off
	s_nop 1
	v_max_f32_e32 v8, 0, v5
	v_max_f32_e32 v5, v6, v6
	v_max_f32_e32 v6, v7, v7
	v_max_f32_e32 v9, 0, v6
	v_pk_mul_f32 v[6:7], v[8:9], v[8:9]
	v_max_f32_e32 v8, 0, v1
	v_max_f32_e32 v1, v2, v2
	v_max_f32_e32 v2, v3, v3
	v_max_f32_e32 v9, 0, v2
	v_max_f32_e32 v4, 0, v4
	v_max_f32_e32 v5, 0, v5
	v_max_f32_e32 v0, 0, v0
	v_max_f32_e32 v1, 0, v1
	v_pk_mul_f32 v[2:3], v[8:9], v[8:9]
	v_pk_mul_f32 v[4:5], v[4:5], v[4:5]
	v_pk_mul_f32 v[0:1], v[0:1], v[0:1]
	v_lshl_add_u64 v[16:17], v[144:145], 0, s[24:25]
	v_cvt_pk_bf16_f32 v3, v1, v3
	v_cvt_pk_bf16_f32 v2, v0, v2
	v_cvt_pk_bf16_f32 v1, v5, v7
	v_cvt_pk_bf16_f32 v0, v4, v6
	s_andn2_b64 vcc, exec, s[0:1]
	s_mov_b64 s[0:1], -1
	global_store_dwordx4 v[16:17], v[0:3], off offset:256
	s_cbranch_vccnz .LBB0_1316
	s_andn2_b64 vcc, exec, s[6:7]
	s_cbranch_vccnz .LBB0_1315
	s_barrier
	s_branch .LBB0_1315

; __device__ __forceinline__ unsigned pk2_(float lo, float hi) { return f2bf_(lo) | (f2bf_(hi) << 16); }
;     __device__ __forceinline__ void operator()(const f32x4 (&acc)[2][2][4][2], const Unit& u, int wr, int wc, int fr, int fq) const {
;     ...
;             for (int m = 0; m < 4; ++m) { bf16_t* rowp = O + (size_t)(row0 + ai * HALF + m * 16) * ldc + col0;
; #pragma unroll
;                 for (int bj = 0; bj < 2; ++bj) { f32x4 v0 = acc[ai][bj][m][0], v1 = acc[ai][bj][m][1];
;                     if (bias) { v0 += *(const f32x4*)(bias + col0 + bj * HALF); v1 += *(const f32x4*)(bias + col0 + bj * HALF + 4); }
;                     u32x4 w; w.x = pk2_(act_f<ACT>(v0[0]), act_f<ACT>(v0[1])); w.y = pk2_(act_f<ACT>(v0[2]), act_f<ACT>(v0[3]));
;                     w.z = pk2_(act_f<ACT>(v1[0]), act_f<ACT>(v1[1])); w.w = pk2_(act_f<ACT>(v1[2]), act_f<ACT>(v1[3]));
;                     *(u32x4*)(rowp + bj * HALF) = w; } }
.LBB0_1559:
	s_lshl_b32 s31, s40, 8
	v_mov_b32_e32 v144, v146
	v_mov_b32_e32 v145, v147
	s_add_i32 s31, s31, s60
	s_lshl_b32 s35, s72, 8
	v_add_u32_e32 v152, s31, v145
	s_or_b32 s35, s35, s61
	v_ashrrev_i32_e32 v153, 31, v152
	v_lshl_add_u32 v144, v144, 3, s35
	v_lshlrev_b64 v[152:153], 10, v[152:153]
	v_ashrrev_i32_e32 v145, 31, v144
	v_lshl_add_u64 v[152:153], s[18:19], 0, v[152:153]
	v_lshl_add_u64 v[144:145], v[144:145], 1, v[152:153]
	v_cvt_pk_bf16_f32 v124, v124, v125
	v_cvt_pk_bf16_f32 v125, v126, v127
	v_cvt_pk_bf16_f32 v126, v120, v121
	v_cvt_pk_bf16_f32 v127, v122, v123
	v_cvt_pk_bf16_f32 v116, v116, v117
	v_cvt_pk_bf16_f32 v117, v118, v119
	v_cvt_pk_bf16_f32 v118, v108, v109
	v_cvt_pk_bf16_f32 v119, v110, v111
	v_cvt_pk_bf16_f32 v108, v112, v113
	v_cvt_pk_bf16_f32 v109, v114, v115
	v_cvt_pk_bf16_f32 v110, v104, v105
	s_movk_i32 s31, 0x4000
	v_cvt_pk_bf16_f32 v111, v106, v107
	v_add_co_u32_e32 v104, vcc, s31, v144
	s_mov_b32 s31, 0x8000
	s_nop 0
	v_addc_co_u32_e32 v105, vcc, 0, v145, vcc
	global_store_dwordx4 v[104:105], v[108:111], off
	v_cvt_pk_bf16_f32 v100, v100, v101
	v_cvt_pk_bf16_f32 v101, v102, v103
	v_cvt_pk_bf16_f32 v102, v92, v93
	v_cvt_pk_bf16_f32 v103, v94, v95
	v_cvt_pk_bf16_f32 v92, v96, v97
	v_cvt_pk_bf16_f32 v93, v98, v99
	v_cvt_pk_bf16_f32 v94, v88, v89
	v_cvt_pk_bf16_f32 v95, v90, v91
	v_add_co_u32_e32 v88, vcc, s31, v144
	s_mov_b32 s31, 0xc000
	s_nop 0
	v_addc_co_u32_e32 v89, vcc, 0, v145, vcc
	global_store_dwordx4 v[88:89], v[92:95], off
	v_cvt_pk_bf16_f32 v84, v84, v85
	v_cvt_pk_bf16_f32 v85, v86, v87
	v_cvt_pk_bf16_f32 v86, v76, v77
	v_cvt_pk_bf16_f32 v87, v78, v79
	v_cvt_pk_bf16_f32 v76, v80, v81
	v_cvt_pk_bf16_f32 v77, v82, v83
	v_cvt_pk_bf16_f32 v78, v72, v73
	v_cvt_pk_bf16_f32 v79, v74, v75
	v_add_co_u32_e32 v72, vcc, s31, v144
	s_mov_b64 s[42:43], 0x4000
	s_nop 0
	v_addc_co_u32_e32 v73, vcc, 0, v145, vcc
	global_store_dwordx4 v[72:73], v[76:79], off
	v_cvt_pk_bf16_f32 v68, v68, v69
	v_cvt_pk_bf16_f32 v69, v70, v71
	v_cvt_pk_bf16_f32 v70, v64, v65
	v_cvt_pk_bf16_f32 v60, v60, v61
	v_cvt_pk_bf16_f32 v61, v62, v63
	v_cvt_pk_bf16_f32 v62, v56, v57
	v_cvt_pk_bf16_f32 v63, v58, v59
	v_add_co_u32_e32 v56, vcc, s68, v144
	s_nop 0
	v_addc_co_u32_e32 v57, vcc, 0, v145, vcc
	global_store_dwordx4 v[56:57], v[60:63], off
	v_cvt_pk_bf16_f32 v52, v52, v53
	v_cvt_pk_bf16_f32 v53, v54, v55
	v_cvt_pk_bf16_f32 v54, v44, v45
	v_cvt_pk_bf16_f32 v55, v46, v47
	v_cvt_pk_bf16_f32 v44, v48, v49
	v_cvt_pk_bf16_f32 v45, v50, v51
	v_cvt_pk_bf16_f32 v46, v40, v41
	v_cvt_pk_bf16_f32 v47, v42, v43
	v_add_co_u32_e32 v40, vcc, s69, v144
	s_nop 0
	v_addc_co_u32_e32 v41, vcc, 0, v145, vcc
	global_store_dwordx4 v[40:41], v[44:47], off
	v_cvt_pk_bf16_f32 v36, v36, v37
	v_cvt_pk_bf16_f32 v37, v38, v39
	v_cvt_pk_bf16_f32 v38, v28, v29
	v_cvt_pk_bf16_f32 v39, v30, v31
	v_cvt_pk_bf16_f32 v28, v32, v33
	v_cvt_pk_bf16_f32 v29, v34, v35
	v_cvt_pk_bf16_f32 v30, v24, v25
	v_cvt_pk_bf16_f32 v31, v26, v27
	v_add_co_u32_e32 v24, vcc, s70, v144
	s_nop 0
	v_addc_co_u32_e32 v25, vcc, 0, v145, vcc
	global_store_dwordx4 v[24:25], v[28:31], off
	v_cvt_pk_bf16_f32 v20, v20, v21
	v_cvt_pk_bf16_f32 v21, v22, v23
	v_cvt_pk_bf16_f32 v22, v12, v13
	v_cvt_pk_bf16_f32 v23, v14, v15
	v_cvt_pk_bf16_f32 v12, v16, v17
	v_cvt_pk_bf16_f32 v13, v18, v19
	v_cvt_pk_bf16_f32 v14, v8, v9
	v_cvt_pk_bf16_f32 v15, v10, v11
	v_add_co_u32_e32 v8, vcc, s71, v144
	v_cvt_pk_bf16_f32 v71, v66, v67
	s_nop 0
	v_addc_co_u32_e32 v9, vcc, 0, v145, vcc
	global_store_dwordx4 v[8:9], v[12:15], off
	v_cvt_pk_bf16_f32 v4, v4, v5
	v_cvt_pk_bf16_f32 v5, v6, v7
	v_lshl_add_u64 v[64:65], v[144:145], 0, s[22:23]
	v_cvt_pk_bf16_f32 v6, v0, v1
	global_store_dwordx4 v[144:145], v[116:119], off offset:256
	s_nop 0
	global_store_dwordx4 v[64:65], v[52:55], off offset:256
	v_lshl_add_u64 v[116:117], v[144:145], 0, s[42:43]
	s_mov_b64 s[42:43], 0x8000
	v_lshl_add_u64 v[52:53], v[144:145], 0, s[24:25]
	global_store_dwordx4 v[116:117], v[100:103], off offset:256
	s_nop 0
	global_store_dwordx4 v[52:53], v[36:39], off offset:256
	s_nop 0
	v_lshl_add_u64 v[100:101], v[144:145], 0, s[42:43]
	v_lshl_add_u64 v[36:37], v[144:145], 0, s[26:27]
	global_store_dwordx4 v[100:101], v[84:87], off offset:256
	global_store_dwordx4 v[36:37], v[20:23], off offset:256
	v_cvt_pk_bf16_f32 v7, v2, v3
	v_lshl_add_u64 v[84:85], v[144:145], 0, s[20:21]
	v_lshl_add_u64 v[20:21], v[144:145], 0, s[28:29]
	s_andn2_b64 vcc, exec, s[0:1]
	s_mov_b64 s[0:1], -1
	global_store_dwordx4 v[144:145], v[124:127], off
	global_store_dwordx4 v[84:85], v[68:71], off offset:256
	global_store_dwordx4 v[20:21], v[4:7], off offset:256
	s_cbranch_vccnz .LBB0_1548
	s_andn2_b64 vcc, exec, s[8:9]
	s_cbranch_vccnz .LBB0_1547
	s_barrier
	s_branch .LBB0_1547

; __device__ __forceinline__ unsigned pk2_(float lo, float hi) { return f2bf_(lo) | (f2bf_(hi) << 16); }
;     __device__ __forceinline__ void operator()(const f32x4 (&acc)[2][2][4][2], const Unit& u, int wr, int wc, int fr, int fq) const {
;     ...
;             for (int m = 0; m < 4; ++m) { bf16_t* rowp = O + (size_t)(row0 + ai * HALF + m * 16) * ldc + col0;
; #pragma unroll
;                 for (int bj = 0; bj < 2; ++bj) { f32x4 v0 = acc[ai][bj][m][0], v1 = acc[ai][bj][m][1];
;                     if (bias) { v0 += *(const f32x4*)(bias + col0 + bj * HALF); v1 += *(const f32x4*)(bias + col0 + bj * HALF + 4); }
;                     u32x4 w; w.x = pk2_(act_f<ACT>(v0[0]), act_f<ACT>(v0[1])); w.y = pk2_(act_f<ACT>(v0[2]), act_f<ACT>(v0[3]));
;                     w.z = pk2_(act_f<ACT>(v1[0]), act_f<ACT>(v1[1])); w.w = pk2_(act_f<ACT>(v1[2]), act_f<ACT>(v1[3]));
;                     *(u32x4*)(rowp + bj * HALF) = w; } }
.LBB0_1684:
	v_cvt_pk_bf16_f32 v124, v124, v125
	v_cvt_pk_bf16_f32 v125, v126, v127
	v_cvt_pk_bf16_f32 v126, v120, v121
	v_cvt_pk_bf16_f32 v127, v122, v123
	v_cvt_pk_bf16_f32 v116, v116, v117
	v_cvt_pk_bf16_f32 v117, v118, v119
	s_lshl_b32 s35, s83, 8
	v_mov_b32_e32 v140, v145
	v_mov_b32_e32 v141, v144
	s_lshl_b32 s31, s40, 8
	s_or_b32 s35, s35, s62
	v_cvt_pk_bf16_f32 v118, v108, v109
	s_add_i32 s31, s31, s61
	v_lshl_add_u32 v142, v141, 3, s35
	v_add_u32_e32 v152, s31, v140
	v_ashrrev_i32_e32 v143, 31, v142
	v_mov_b64_e32 v[140:141], s[10:11]
	v_mad_i64_i32 v[150:151], s[42:43], v152, s68, v[140:141]
	v_lshlrev_b64 v[142:143], 1, v[142:143]
	v_cvt_pk_bf16_f32 v119, v110, v111
	v_add_u32_e32 v108, 16, v152
	v_lshl_add_u64 v[150:151], v[150:151], 0, v[142:143]
	v_mad_i64_i32 v[108:109], s[42:43], v108, s68, v[140:141]
	global_store_dwordx4 v[150:151], v[116:119], off offset:256
	s_nop 1
	v_lshl_add_u64 v[116:117], v[108:109], 0, v[142:143]
	v_cvt_pk_bf16_f32 v108, v112, v113
	v_cvt_pk_bf16_f32 v109, v114, v115
	v_cvt_pk_bf16_f32 v110, v104, v105
	v_cvt_pk_bf16_f32 v111, v106, v107
	v_cvt_pk_bf16_f32 v100, v100, v101
	v_cvt_pk_bf16_f32 v101, v102, v103
	v_cvt_pk_bf16_f32 v102, v92, v93
	v_cvt_pk_bf16_f32 v103, v94, v95
	v_add_u32_e32 v92, 32, v152
	v_mad_i64_i32 v[92:93], s[42:43], v92, s68, v[140:141]
	global_store_dwordx4 v[116:117], v[100:103], off offset:256
	s_nop 1
	v_lshl_add_u64 v[100:101], v[92:93], 0, v[142:143]
	v_cvt_pk_bf16_f32 v92, v96, v97
	v_cvt_pk_bf16_f32 v93, v98, v99
	v_cvt_pk_bf16_f32 v94, v88, v89
	v_cvt_pk_bf16_f32 v95, v90, v91
	v_cvt_pk_bf16_f32 v84, v84, v85
	v_cvt_pk_bf16_f32 v85, v86, v87
	v_cvt_pk_bf16_f32 v86, v76, v77
	v_cvt_pk_bf16_f32 v87, v78, v79
	v_add_u32_e32 v76, 48, v152
	v_mad_i64_i32 v[76:77], s[42:43], v76, s68, v[140:141]
	global_store_dwordx4 v[100:101], v[84:87], off offset:256
	s_nop 1
	v_lshl_add_u64 v[84:85], v[76:77], 0, v[142:143]
	v_cvt_pk_bf16_f32 v76, v80, v81
	v_cvt_pk_bf16_f32 v77, v82, v83
	v_cvt_pk_bf16_f32 v78, v72, v73
	v_cvt_pk_bf16_f32 v79, v74, v75
	v_cvt_pk_bf16_f32 v68, v68, v69
	v_cvt_pk_bf16_f32 v69, v70, v71
	v_cvt_pk_bf16_f32 v70, v64, v65
	v_cvt_pk_bf16_f32 v60, v60, v61
	v_cvt_pk_bf16_f32 v61, v62, v63
	v_cvt_pk_bf16_f32 v62, v56, v57
	v_cvt_pk_bf16_f32 v63, v58, v59
	v_cvt_pk_bf16_f32 v52, v52, v53
	v_cvt_pk_bf16_f32 v53, v54, v55
	v_cvt_pk_bf16_f32 v54, v44, v45
	v_cvt_pk_bf16_f32 v71, v66, v67
	v_add_u32_e32 v64, 0x80, v152
	v_mad_i64_i32 v[64:65], s[42:43], v64, s68, v[140:141]
	v_cvt_pk_bf16_f32 v55, v46, v47
	v_add_u32_e32 v44, 0x90, v152
	v_lshl_add_u64 v[64:65], v[64:65], 0, v[142:143]
	v_mad_i64_i32 v[44:45], s[42:43], v44, s68, v[140:141]
	global_store_dwordx4 v[64:65], v[52:55], off offset:256
	s_nop 1
	v_lshl_add_u64 v[52:53], v[44:45], 0, v[142:143]
	v_cvt_pk_bf16_f32 v44, v48, v49
	v_cvt_pk_bf16_f32 v45, v50, v51
	v_cvt_pk_bf16_f32 v46, v40, v41
	v_cvt_pk_bf16_f32 v47, v42, v43
	v_cvt_pk_bf16_f32 v36, v36, v37
	v_cvt_pk_bf16_f32 v37, v38, v39
	v_cvt_pk_bf16_f32 v38, v28, v29
	v_cvt_pk_bf16_f32 v39, v30, v31
	v_add_u32_e32 v28, 0xa0, v152
	v_mad_i64_i32 v[28:29], s[42:43], v28, s68, v[140:141]
	global_store_dwordx4 v[52:53], v[36:39], off offset:256
	s_nop 1
	v_lshl_add_u64 v[36:37], v[28:29], 0, v[142:143]
	v_cvt_pk_bf16_f32 v28, v32, v33
	v_cvt_pk_bf16_f32 v29, v34, v35
	v_cvt_pk_bf16_f32 v30, v24, v25
	v_cvt_pk_bf16_f32 v31, v26, v27
	v_cvt_pk_bf16_f32 v20, v20, v21
	v_cvt_pk_bf16_f32 v21, v22, v23
	v_cvt_pk_bf16_f32 v22, v12, v13
	v_cvt_pk_bf16_f32 v23, v14, v15
	v_add_u32_e32 v12, 0xb0, v152
	v_mad_i64_i32 v[12:13], s[42:43], v12, s68, v[140:141]
	global_store_dwordx4 v[36:37], v[20:23], off offset:256
	s_nop 1
	v_lshl_add_u64 v[20:21], v[12:13], 0, v[142:143]
	v_cvt_pk_bf16_f32 v12, v16, v17
	v_cvt_pk_bf16_f32 v13, v18, v19
	v_cvt_pk_bf16_f32 v14, v8, v9
	v_cvt_pk_bf16_f32 v15, v10, v11
	v_cvt_pk_bf16_f32 v4, v4, v5
	v_cvt_pk_bf16_f32 v5, v6, v7
	v_cvt_pk_bf16_f32 v6, v0, v1
	v_readlane_b32 s86, v254, 20
	v_cvt_pk_bf16_f32 v7, v2, v3
	s_andn2_b64 vcc, exec, s[0:1]
	s_mov_b64 s[0:1], -1
	v_readlane_b32 s92, v254, 25
	v_readlane_b32 s93, v254, 26
	v_readlane_b32 s91, v254, 24
	v_readlane_b32 s87, v254, 21
	global_store_dwordx4 v[150:151], v[124:127], off
	global_store_dwordx4 v[116:117], v[108:111], off
	global_store_dwordx4 v[100:101], v[92:95], off
	global_store_dwordx4 v[84:85], v[76:79], off
	global_store_dwordx4 v[84:85], v[68:71], off offset:256
	global_store_dwordx4 v[64:65], v[60:63], off
	global_store_dwordx4 v[52:53], v[44:47], off
	global_store_dwordx4 v[36:37], v[28:31], off
	global_store_dwordx4 v[20:21], v[12:15], off
	global_store_dwordx4 v[20:21], v[4:7], off offset:256
	s_cbranch_vccnz .LBB0_1677
	s_andn2_b64 vcc, exec, s[8:9]
	s_cbranch_vccnz .LBB0_1676
	s_barrier
	s_branch .LBB0_1676

; __device__ __forceinline__ unsigned pk2_(float lo, float hi) { return f2bf_(lo) | (f2bf_(hi) << 16); }
;     __device__ __forceinline__ void operator()(const f32x4 (&acc)[2][2][4][2], const Unit& u, int wr, int wc, int fr, int fq) const {
;     ...
;             for (int m = 0; m < 4; ++m) { bf16_t* rowp = O + (size_t)(row0 + ai * HALF + m * 16) * ldc + col0;
; #pragma unroll
;                 for (int bj = 0; bj < 2; ++bj) { f32x4 v0 = acc[ai][bj][m][0], v1 = acc[ai][bj][m][1];
;                     if (bias) { v0 += *(const f32x4*)(bias + col0 + bj * HALF); v1 += *(const f32x4*)(bias + col0 + bj * HALF + 4); }
;                     u32x4 w; w.x = pk2_(act_f<ACT>(v0[0]), act_f<ACT>(v0[1])); w.y = pk2_(act_f<ACT>(v0[2]), act_f<ACT>(v0[3]));
;                     w.z = pk2_(act_f<ACT>(v1[0]), act_f<ACT>(v1[1])); w.w = pk2_(act_f<ACT>(v1[2]), act_f<ACT>(v1[3]));
;                     *(u32x4*)(rowp + bj * HALF) = w; } }
.LBB0_1706:
	s_lshl_b32 s41, s70, 8
	v_mov_b32_e32 v140, v142
	v_mov_b32_e32 v141, v143
	s_add_i32 s41, s41, s60
	s_lshl_b32 s43, s81, 8
	v_add_u32_e32 v148, s41, v141
	s_or_b32 s43, s43, s61
	v_ashrrev_i32_e32 v149, 31, v148
	v_lshl_add_u32 v140, v140, 3, s43
	v_lshlrev_b64 v[148:149], 11, v[148:149]
	v_ashrrev_i32_e32 v141, 31, v140
	v_lshl_add_u64 v[148:149], s[8:9], 0, v[148:149]
	v_lshl_add_u64 v[140:141], v[140:141], 1, v[148:149]
	v_cvt_pk_bf16_f32 v124, v124, v125
	v_cvt_pk_bf16_f32 v125, v126, v127
	v_cvt_pk_bf16_f32 v126, v120, v121
	v_cvt_pk_bf16_f32 v127, v122, v123
	v_cvt_pk_bf16_f32 v116, v116, v117
	v_cvt_pk_bf16_f32 v117, v118, v119
	v_cvt_pk_bf16_f32 v118, v112, v113
	v_cvt_pk_bf16_f32 v108, v108, v109
	v_cvt_pk_bf16_f32 v109, v110, v111
	v_cvt_pk_bf16_f32 v110, v104, v105
	s_mov_b32 s41, 0x8000
	v_cvt_pk_bf16_f32 v111, v106, v107
	v_add_co_u32_e32 v104, vcc, s41, v140
	s_mov_b32 s41, 0x10000
	s_nop 0
	v_addc_co_u32_e32 v105, vcc, 0, v141, vcc
	global_store_dwordx4 v[104:105], v[108:111], off
	v_cvt_pk_bf16_f32 v100, v100, v101
	v_cvt_pk_bf16_f32 v101, v102, v103
	v_cvt_pk_bf16_f32 v102, v96, v97
	v_cvt_pk_bf16_f32 v92, v92, v93
	v_cvt_pk_bf16_f32 v93, v94, v95
	v_cvt_pk_bf16_f32 v94, v88, v89
	v_cvt_pk_bf16_f32 v95, v90, v91
	v_add_co_u32_e32 v88, vcc, s41, v140
	s_mov_b32 s41, 0x18000
	s_nop 0
	v_addc_co_u32_e32 v89, vcc, 0, v141, vcc
	global_store_dwordx4 v[88:89], v[92:95], off
	v_cvt_pk_bf16_f32 v84, v84, v85
	v_cvt_pk_bf16_f32 v85, v86, v87
	v_cvt_pk_bf16_f32 v86, v80, v81
	v_cvt_pk_bf16_f32 v76, v76, v77
	v_cvt_pk_bf16_f32 v77, v78, v79
	v_cvt_pk_bf16_f32 v78, v68, v69
	v_cvt_pk_bf16_f32 v79, v70, v71
	v_add_co_u32_e32 v68, vcc, s41, v140
	s_nop 0
	v_addc_co_u32_e32 v69, vcc, 0, v141, vcc
	global_store_dwordx4 v[68:69], v[76:79], off
	v_cvt_pk_bf16_f32 v60, v60, v61
	v_cvt_pk_bf16_f32 v61, v62, v63
	v_cvt_pk_bf16_f32 v62, v52, v53
	v_cvt_pk_bf16_f32 v63, v54, v55
	v_cvt_pk_bf16_f32 v52, v72, v73
	s_mov_b64 s[72:73], 0x8000
	v_cvt_pk_bf16_f32 v53, v74, v75
	v_cvt_pk_bf16_f32 v119, v114, v115
	v_lshl_add_u64 v[112:113], v[140:141], 0, s[72:73]
	s_mov_b64 s[72:73], 0x10000
	v_cvt_pk_bf16_f32 v103, v98, v99
	v_lshl_add_u64 v[96:97], v[140:141], 0, s[72:73]
	s_mov_b64 s[72:73], 0x18000
	v_cvt_pk_bf16_f32 v87, v82, v83
	v_lshl_add_u64 v[80:81], v[140:141], 0, s[72:73]
	v_cvt_pk_bf16_f32 v54, v64, v65
	global_store_dwordx4 v[80:81], v[60:63], off offset:256
	s_mov_b32 s41, 0x40000
	v_cvt_pk_bf16_f32 v55, v66, v67
	v_add_co_u32_e32 v62, vcc, s41, v140
	s_mov_b64 s[72:73], 0x40000
	s_nop 0
	v_addc_co_u32_e32 v63, vcc, 0, v141, vcc
	global_store_dwordx4 v[62:63], v[52:55], off
	v_lshl_add_u64 v[60:61], v[140:141], 0, s[72:73]
	s_mov_b64 s[72:73], 0x48000
	v_cvt_pk_bf16_f32 v52, v56, v57
	v_cvt_pk_bf16_f32 v53, v58, v59
	v_cvt_pk_bf16_f32 v54, v48, v49
	v_cvt_pk_bf16_f32 v44, v44, v45
	v_cvt_pk_bf16_f32 v45, v46, v47
	v_cvt_pk_bf16_f32 v46, v40, v41
	v_cvt_pk_bf16_f32 v47, v42, v43
	v_add_co_u32_e32 v40, vcc, s78, v140
	s_nop 0
	v_addc_co_u32_e32 v41, vcc, 0, v141, vcc
	global_store_dwordx4 v[40:41], v[44:47], off
	v_cvt_pk_bf16_f32 v36, v36, v37
	v_cvt_pk_bf16_f32 v37, v38, v39
	v_cvt_pk_bf16_f32 v38, v32, v33
	v_cvt_pk_bf16_f32 v28, v28, v29
	v_cvt_pk_bf16_f32 v29, v30, v31
	v_cvt_pk_bf16_f32 v30, v24, v25
	v_cvt_pk_bf16_f32 v31, v26, v27
	v_add_co_u32_e32 v24, vcc, s79, v140
	s_nop 0
	v_addc_co_u32_e32 v25, vcc, 0, v141, vcc
	global_store_dwordx4 v[24:25], v[28:31], off
	v_cvt_pk_bf16_f32 v20, v20, v21
	v_cvt_pk_bf16_f32 v21, v22, v23
	v_cvt_pk_bf16_f32 v22, v16, v17
	v_cvt_pk_bf16_f32 v12, v12, v13
	v_cvt_pk_bf16_f32 v13, v14, v15
	v_cvt_pk_bf16_f32 v14, v8, v9
	v_cvt_pk_bf16_f32 v15, v10, v11
	v_add_co_u32_e32 v8, vcc, s80, v140
	s_nop 0
	v_addc_co_u32_e32 v9, vcc, 0, v141, vcc
	global_store_dwordx4 v[8:9], v[12:15], off
	v_cvt_pk_bf16_f32 v4, v4, v5
	v_cvt_pk_bf16_f32 v5, v6, v7
	v_cvt_pk_bf16_f32 v6, v0, v1
	v_cvt_pk_bf16_f32 v55, v50, v51
	v_lshl_add_u64 v[48:49], v[140:141], 0, s[72:73]
	v_cvt_pk_bf16_f32 v39, v34, v35
	v_lshl_add_u64 v[32:33], v[140:141], 0, s[36:37]
	v_cvt_pk_bf16_f32 v23, v18, v19
	v_lshl_add_u64 v[16:17], v[140:141], 0, s[38:39]
	v_cvt_pk_bf16_f32 v7, v2, v3
	s_andn2_b64 vcc, exec, s[0:1]
	s_mov_b64 s[0:1], -1
	global_store_dwordx4 v[140:141], v[124:127], off
	global_store_dwordx4 v[140:141], v[116:119], off offset:256
	global_store_dwordx4 v[112:113], v[100:103], off offset:256
	global_store_dwordx4 v[96:97], v[84:87], off offset:256
	global_store_dwordx4 v[60:61], v[52:55], off offset:256
	global_store_dwordx4 v[48:49], v[36:39], off offset:256
	global_store_dwordx4 v[32:33], v[20:23], off offset:256
	global_store_dwordx4 v[16:17], v[4:7], off offset:256
	s_cbranch_vccnz .LBB0_1697
	s_andn2_b64 vcc, exec, s[26:27]
	s_cbranch_vccnz .LBB0_1696
	s_barrier
	s_branch .LBB0_1696

; __device__ __forceinline__ unsigned pk2_(float lo, float hi) { return f2bf_(lo) | (f2bf_(hi) << 16); }
;     __device__ __forceinline__ void operator()(const f32x4 (&acc)[2][2][4][2], const Unit& u, int wr, int wc, int fr, int fq) const {
;     ...
;             for (int m = 0; m < 4; ++m) { bf16_t* rowp = O + (size_t)(row0 + ai * HALF + m * 16) * ldc + col0;
; #pragma unroll
;                 for (int bj = 0; bj < 2; ++bj) { f32x4 v0 = acc[ai][bj][m][0], v1 = acc[ai][bj][m][1];
;                     if (bias) { v0 += *(const f32x4*)(bias + col0 + bj * HALF); v1 += *(const f32x4*)(bias + col0 + bj * HALF + 4); }
;                     u32x4 w; w.x = pk2_(act_f<ACT>(v0[0]), act_f<ACT>(v0[1])); w.y = pk2_(act_f<ACT>(v0[2]), act_f<ACT>(v0[3]));
;                     w.z = pk2_(act_f<ACT>(v1[0]), act_f<ACT>(v1[1])); w.w = pk2_(act_f<ACT>(v1[2]), act_f<ACT>(v1[3]));
;                     *(u32x4*)(rowp + bj * HALF) = w; } }
.LBB0_1728:
	s_lshl_b32 s43, s72, 8
	v_mov_b32_e32 v140, v142
	v_mov_b32_e32 v141, v143
	s_add_i32 s43, s43, s60
	s_lshl_b32 s45, s82, 8
	v_add_u32_e32 v148, s43, v141
	s_or_b32 s45, s45, s61
	v_ashrrev_i32_e32 v149, 31, v148
	v_lshl_add_u32 v140, v140, 3, s45
	v_lshlrev_b64 v[148:149], 16, v[148:149]
	v_ashrrev_i32_e32 v141, 31, v140
	v_lshl_add_u64 v[148:149], s[28:29], 0, v[148:149]
	v_lshl_add_u64 v[140:141], v[140:141], 1, v[148:149]
	v_cvt_pk_bf16_f32 v124, v124, v125
	v_cvt_pk_bf16_f32 v125, v126, v127
	v_cvt_pk_bf16_f32 v126, v120, v121
	v_cvt_pk_bf16_f32 v127, v122, v123
	v_cvt_pk_bf16_f32 v116, v116, v117
	v_cvt_pk_bf16_f32 v117, v118, v119
	v_cvt_pk_bf16_f32 v118, v112, v113
	v_cvt_pk_bf16_f32 v108, v108, v109
	v_cvt_pk_bf16_f32 v109, v110, v111
	v_cvt_pk_bf16_f32 v110, v104, v105
	s_mov_b32 s43, 0x100000
	v_cvt_pk_bf16_f32 v111, v106, v107
	v_add_co_u32_e32 v104, vcc, s43, v140
	s_mov_b32 s43, 0x200000
	s_nop 0
	v_addc_co_u32_e32 v105, vcc, 0, v141, vcc
	global_store_dwordx4 v[104:105], v[108:111], off
	v_cvt_pk_bf16_f32 v100, v100, v101
	v_cvt_pk_bf16_f32 v101, v102, v103
	v_cvt_pk_bf16_f32 v102, v96, v97
	v_cvt_pk_bf16_f32 v92, v92, v93
	v_cvt_pk_bf16_f32 v93, v94, v95
	v_cvt_pk_bf16_f32 v94, v88, v89
	v_cvt_pk_bf16_f32 v95, v90, v91
	v_add_co_u32_e32 v88, vcc, s43, v140
	s_mov_b32 s43, 0x300000
	s_nop 0
	v_addc_co_u32_e32 v89, vcc, 0, v141, vcc
	global_store_dwordx4 v[88:89], v[92:95], off
	v_cvt_pk_bf16_f32 v84, v84, v85
	v_cvt_pk_bf16_f32 v85, v86, v87
	v_cvt_pk_bf16_f32 v86, v80, v81
	v_cvt_pk_bf16_f32 v76, v76, v77
	v_cvt_pk_bf16_f32 v77, v78, v79
	v_cvt_pk_bf16_f32 v78, v68, v69
	v_cvt_pk_bf16_f32 v79, v70, v71
	v_add_co_u32_e32 v68, vcc, s43, v140
	s_nop 0
	v_addc_co_u32_e32 v69, vcc, 0, v141, vcc
	global_store_dwordx4 v[68:69], v[76:79], off
	v_cvt_pk_bf16_f32 v60, v60, v61
	v_cvt_pk_bf16_f32 v61, v62, v63
	v_cvt_pk_bf16_f32 v62, v52, v53
	v_cvt_pk_bf16_f32 v63, v54, v55
	v_cvt_pk_bf16_f32 v52, v72, v73
	s_mov_b64 s[74:75], 0x100000
	v_cvt_pk_bf16_f32 v53, v74, v75
	v_cvt_pk_bf16_f32 v119, v114, v115
	v_lshl_add_u64 v[112:113], v[140:141], 0, s[74:75]
	s_mov_b64 s[74:75], 0x200000
	v_cvt_pk_bf16_f32 v103, v98, v99
	v_lshl_add_u64 v[96:97], v[140:141], 0, s[74:75]
	s_mov_b64 s[74:75], 0x300000
	v_cvt_pk_bf16_f32 v87, v82, v83
	v_lshl_add_u64 v[80:81], v[140:141], 0, s[74:75]
	v_cvt_pk_bf16_f32 v54, v64, v65
	global_store_dwordx4 v[80:81], v[60:63], off offset:256
	s_mov_b32 s43, 0x800000
	v_cvt_pk_bf16_f32 v55, v66, v67
	v_add_co_u32_e32 v62, vcc, s43, v140
	s_mov_b32 s43, 0x900000
	s_nop 0
	v_addc_co_u32_e32 v63, vcc, 0, v141, vcc
	global_store_dwordx4 v[62:63], v[52:55], off
	s_mov_b64 s[74:75], 0x800000
	v_lshl_add_u64 v[60:61], v[140:141], 0, s[74:75]
	v_cvt_pk_bf16_f32 v52, v56, v57
	v_cvt_pk_bf16_f32 v53, v58, v59
	v_cvt_pk_bf16_f32 v54, v48, v49
	v_cvt_pk_bf16_f32 v44, v44, v45
	v_cvt_pk_bf16_f32 v45, v46, v47
	v_cvt_pk_bf16_f32 v46, v40, v41
	v_cvt_pk_bf16_f32 v47, v42, v43
	v_add_co_u32_e32 v40, vcc, s43, v140
	s_nop 0
	v_addc_co_u32_e32 v41, vcc, 0, v141, vcc
	global_store_dwordx4 v[40:41], v[44:47], off
	v_cvt_pk_bf16_f32 v36, v36, v37
	v_cvt_pk_bf16_f32 v37, v38, v39
	v_cvt_pk_bf16_f32 v38, v32, v33
	v_cvt_pk_bf16_f32 v28, v28, v29
	v_cvt_pk_bf16_f32 v29, v30, v31
	v_cvt_pk_bf16_f32 v30, v24, v25
	v_cvt_pk_bf16_f32 v31, v26, v27
	v_add_co_u32_e32 v24, vcc, s80, v140
	s_nop 0
	v_addc_co_u32_e32 v25, vcc, 0, v141, vcc
	global_store_dwordx4 v[24:25], v[28:31], off
	v_cvt_pk_bf16_f32 v20, v20, v21
	v_cvt_pk_bf16_f32 v21, v22, v23
	v_cvt_pk_bf16_f32 v22, v16, v17
	v_cvt_pk_bf16_f32 v12, v12, v13
	v_cvt_pk_bf16_f32 v13, v14, v15
	v_cvt_pk_bf16_f32 v14, v8, v9
	v_cvt_pk_bf16_f32 v15, v10, v11
	v_add_co_u32_e32 v8, vcc, s81, v140
	s_nop 0
	v_addc_co_u32_e32 v9, vcc, 0, v141, vcc
	global_store_dwordx4 v[8:9], v[12:15], off
	v_cvt_pk_bf16_f32 v4, v4, v5
	v_cvt_pk_bf16_f32 v5, v6, v7
	v_cvt_pk_bf16_f32 v6, v0, v1
	s_mov_b64 s[74:75], 0x900000
	v_cvt_pk_bf16_f32 v55, v50, v51
	v_lshl_add_u64 v[48:49], v[140:141], 0, s[74:75]
	v_cvt_pk_bf16_f32 v39, v34, v35
	v_lshl_add_u64 v[32:33], v[140:141], 0, s[38:39]
	v_cvt_pk_bf16_f32 v23, v18, v19
	v_lshl_add_u64 v[16:17], v[140:141], 0, s[40:41]
	v_cvt_pk_bf16_f32 v7, v2, v3
	s_andn2_b64 vcc, exec, s[0:1]
	s_mov_b64 s[0:1], -1
	global_store_dwordx4 v[140:141], v[124:127], off
	global_store_dwordx4 v[140:141], v[116:119], off offset:256
	global_store_dwordx4 v[112:113], v[100:103], off offset:256
	global_store_dwordx4 v[96:97], v[84:87], off offset:256
	global_store_dwordx4 v[60:61], v[52:55], off offset:256
	global_store_dwordx4 v[48:49], v[36:39], off offset:256
	global_store_dwordx4 v[32:33], v[20:23], off offset:256
	global_store_dwordx4 v[16:17], v[4:7], off offset:256
	s_cbranch_vccnz .LBB0_1719
	s_andn2_b64 vcc, exec, s[26:27]
	s_cbranch_vccnz .LBB0_1718
	s_barrier
	s_branch .LBB0_1718

; #define LAS __attribute__((address_space(3)))
; #define MFMA32(a, b, c) __builtin_amdgcn_mfma_f32_32x32x16_bf16((a), (b), (c), 0, 0, 0)
; template <int DQK> DEV void qk_tile(f32x16 (&st)[2], const LAS unsigned char* kb, const bf16x8 (&qf)[DQK / 16], int r, int h) {
;     constexpr int KSTR = DQK * 2 + 16, NS = DQK / 16;
;     bf16x8 kf[2][NS];
; #pragma unroll
;     for (int b2 = 0; b2 < 2; ++b2)
; #pragma unroll
;         for (int s = 0; s < NS; ++s) kf[b2][s] = *(const LAS bf16x8*)(kb + (32 * b2 + r) * KSTR + 32 * s + 16 * h);
;     __builtin_amdgcn_sched_barrier(0);
; #pragma unroll
;     for (int b2 = 0; b2 < 2; ++b2) {
;         f32x16 a;
; #pragma unroll
;         for (int i = 0; i < 16; ++i) a[i] = 0.f;
; #pragma unroll
;         for (int s = 0; s < NS; ++s) a = MFMA32(kf[b2][s], qf[s], a);
;         st[b2] = a;
;     }
;     __builtin_amdgcn_sched_barrier(0);
; }
; template <int DQK, int MODE> ...
;     ...
;         LAS unsigned char* kb = lds + AL_K0 + slot * AL_KSTR; LAS unsigned char* vb = lds + AL_V0 + slot * AL_VSTR;
;         const int k0 = 64 * t;
;         bool rowsel = true;
;         if (MODE == 1) rowsel = (selm.x >> (t >> 2)) & 1u;
;         if (MODE == 2) { const int tw = t >> 5; const unsigned w = tw == 0 ? selm.x : (tw == 1 ? selm.y : (tw == 2 ? selm.z : selm.w)); rowsel = (w >> (t & 31)) & 1u; }
;         const bool rowact = rowsel && (k0 <= hi_lim) && (k0 + 63 >= lo_lim);
;         if (__any(rowact ? 1 : 0)) {
;             f32x16 st[2];
;             qk_tile<DQK>(st, kb, qf, r, h);
;             bf16x8 vf[2][4];
;             if (MODE != 3) pv_load(vf, vb, r, h);
;             const bool interior = __all(((k0 + 63 <= hi_lim) && (k0 >= lo_lim)) ? 1 : 0);
.LBB0_1836:
	s_lshl_b32 s0, s42, 6
	v_cmp_le_i32_e32 vcc, s0, v172
	s_cbranch_vccz .LBB0_1842
	s_mul_i32 s1, s44, 0x9c00
	v_add_u32_e32 v0, s1, v175
	ds_read_b128 v[2:5], v0
	ds_read_b128 v[6:9], v0 offset:32
	ds_read_b128 v[10:13], v0 offset:64
	ds_read_b128 v[48:51], v0 offset:96
	ds_read_b128 v[52:55], v0 offset:128
	ds_read_b128 v[56:59], v0 offset:160
	ds_read_b128 v[60:63], v0 offset:6656
	ds_read_b128 v[140:143], v0 offset:6688
	ds_read_b128 v[144:147], v0 offset:6720
	ds_read_b128 v[148:151], v0 offset:6752
	ds_read_b128 v[152:155], v0 offset:6784
	ds_read_b128 v[156:159], v0 offset:6816
	s_mul_i32 s1, s44, 0x6600
	s_setprio 1
	s_waitcnt lgkmcnt(11)
	v_mfma_f32_32x32x16_bf16 v[64:79], v[2:5], v[80:83], 0
	s_waitcnt lgkmcnt(10)
	v_mfma_f32_32x32x16_bf16 v[64:79], v[6:9], v[84:87], v[64:79]
	s_waitcnt lgkmcnt(9)
	v_mfma_f32_32x32x16_bf16 v[64:79], v[10:13], v[88:91], v[64:79]
	s_waitcnt lgkmcnt(8)
	v_mfma_f32_32x32x16_bf16 v[64:79], v[48:51], v[92:95], v[64:79]
	s_waitcnt lgkmcnt(7)
	v_mfma_f32_32x32x16_bf16 v[64:79], v[52:55], v[132:135], v[64:79]
	s_waitcnt lgkmcnt(6)
	v_mfma_f32_32x32x16_bf16 v[64:79], v[56:59], v[136:139], v[64:79]
	s_waitcnt lgkmcnt(5)
	v_mfma_f32_32x32x16_bf16 v[48:63], v[60:63], v[80:83], 0
	s_waitcnt lgkmcnt(4)
	v_mfma_f32_32x32x16_bf16 v[48:63], v[140:143], v[84:87], v[48:63]
	s_waitcnt lgkmcnt(3)
	v_mfma_f32_32x32x16_bf16 v[48:63], v[144:147], v[88:91], v[48:63]
	s_waitcnt lgkmcnt(2)
	v_mfma_f32_32x32x16_bf16 v[48:63], v[148:151], v[92:95], v[48:63]
	s_waitcnt lgkmcnt(1)
	v_mfma_f32_32x32x16_bf16 v[48:63], v[152:155], v[132:135], v[48:63]
	s_waitcnt lgkmcnt(0)
	v_mfma_f32_32x32x16_bf16 v[48:63], v[156:159], v[136:139], v[48:63]
	s_setprio 0
	v_add_u32_e32 v0, s1, v179
	ds_read2_b64 v[140:143], v0 offset1:2
	ds_read2_b64 v[10:13], v0 offset0:4 offset1:6
	ds_read2_b64 v[6:9], v0 offset0:8 offset1:10
	ds_read2_b64 v[2:5], v0 offset0:12 offset1:14
	v_add_u32_e32 v0, 0x1000, v0
	ds_read2_b64 v[156:159], v0 offset0:32 offset1:34
	ds_read2_b64 v[152:155], v0 offset0:36 offset1:38
	ds_read2_b64 v[148:151], v0 offset0:40 offset1:42
	ds_read2_b64 v[144:147], v0 offset0:44 offset1:46
	s_or_b32 s1, s0, 63
	v_cmp_le_i32_e32 vcc, s1, v172
	s_cmp_eq_u64 vcc, exec
	s_cbranch_scc1 .LBB0_1839
; DEV int crow(int i, int h) { return (i & 3) + 8 * (i >> 2) + 4 * h; }
; template <int DQK, int MODE> ...
;     ...
;             const bool interior = __all(((k0 + 63 <= hi_lim) && (k0 >= lo_lim)) ? 1 : 0);
;             if (!interior) {
; #pragma unroll
;                 for (int b2 = 0; b2 < 2; ++b2)
; #pragma unroll
;                     for (int i = 0; i < 16; ++i) { const int key = k0 + 32 * b2 + crow(i, h); const bool vis = (key <= hi_lim) && (key >= lo_lim); st[b2][i] = vis ? st[b2][i] : -INFINITY; }
;             }
	v_add_u32_e32 v0, s0, v193
	v_cmp_gt_i32_e32 vcc, v0, v172
	v_cmp_gt_i32_e64 s[0:1], -2.0, v0
	s_or_b64 vcc, vcc, s[0:1]
	v_add_u32_e32 v14, 1, v0
	v_cndmask_b32_e32 v64, v64, v192, vcc
	v_cmp_gt_i32_e32 vcc, v14, v172
	v_cmp_gt_i32_e64 s[0:1], -2.0, v14
	s_or_b64 vcc, vcc, s[0:1]
	v_add_u32_e32 v14, 2, v0
	v_cndmask_b32_e32 v65, v65, v192, vcc
	v_cmp_gt_i32_e32 vcc, v14, v172
	v_cmp_gt_i32_e64 s[0:1], -2.0, v14
	s_or_b64 vcc, vcc, s[0:1]
	v_add_u32_e32 v14, 3, v0
	v_cndmask_b32_e32 v66, v66, v192, vcc
	v_cmp_gt_i32_e32 vcc, v14, v172
	v_cmp_gt_i32_e64 s[0:1], -2.0, v14
	s_or_b64 vcc, vcc, s[0:1]
	v_add_u32_e32 v14, 8, v0
	v_cndmask_b32_e32 v67, v67, v192, vcc
	v_cmp_gt_i32_e32 vcc, v14, v172
	v_cmp_gt_i32_e64 s[0:1], -2.0, v14
	s_or_b64 vcc, vcc, s[0:1]
	v_add_u32_e32 v14, 9, v0
	v_cndmask_b32_e32 v68, v68, v192, vcc
	v_cmp_gt_i32_e32 vcc, v14, v172
	v_cmp_gt_i32_e64 s[0:1], -2.0, v14
	s_or_b64 vcc, vcc, s[0:1]
	v_add_u32_e32 v14, 10, v0
	v_cndmask_b32_e32 v69, v69, v192, vcc
	v_cmp_gt_i32_e32 vcc, v14, v172
	v_cmp_gt_i32_e64 s[0:1], -2.0, v14
	s_or_b64 vcc, vcc, s[0:1]
	v_add_u32_e32 v14, 11, v0
	v_cndmask_b32_e32 v70, v70, v192, vcc
	v_cmp_gt_i32_e32 vcc, v14, v172
	v_cmp_gt_i32_e64 s[0:1], -2.0, v14
	s_or_b64 vcc, vcc, s[0:1]
	v_add_u32_e32 v14, 16, v0
	v_cndmask_b32_e32 v71, v71, v192, vcc
	v_cmp_gt_i32_e32 vcc, v14, v172
	v_cmp_gt_i32_e64 s[0:1], -2.0, v14
	s_or_b64 vcc, vcc, s[0:1]
	v_add_u32_e32 v14, 17, v0
	v_cndmask_b32_e32 v72, v72, v192, vcc
	v_cmp_gt_i32_e32 vcc, v14, v172
	v_cmp_gt_i32_e64 s[0:1], -2.0, v14
	s_or_b64 vcc, vcc, s[0:1]
	v_add_u32_e32 v14, 18, v0
	v_cndmask_b32_e32 v73, v73, v192, vcc
	v_cmp_gt_i32_e32 vcc, v14, v172
	v_cmp_gt_i32_e64 s[0:1], -2.0, v14
	s_or_b64 vcc, vcc, s[0:1]
	v_add_u32_e32 v14, 19, v0
	v_cndmask_b32_e32 v74, v74, v192, vcc
	v_cmp_gt_i32_e32 vcc, v14, v172
	v_cmp_gt_i32_e64 s[0:1], -2.0, v14
	s_or_b64 vcc, vcc, s[0:1]
	v_add_u32_e32 v14, 24, v0
	v_cndmask_b32_e32 v75, v75, v192, vcc
	v_cmp_gt_i32_e32 vcc, v14, v172
	v_cmp_gt_i32_e64 s[0:1], -2.0, v14
	s_or_b64 vcc, vcc, s[0:1]
	v_add_u32_e32 v14, 25, v0
	v_cndmask_b32_e32 v76, v76, v192, vcc
	v_cmp_gt_i32_e32 vcc, v14, v172
	v_cmp_gt_i32_e64 s[0:1], -2.0, v14
	s_or_b64 vcc, vcc, s[0:1]
	v_add_u32_e32 v14, 26, v0
	v_cndmask_b32_e32 v77, v77, v192, vcc
	v_cmp_gt_i32_e32 vcc, v14, v172
	v_cmp_gt_i32_e64 s[0:1], -2.0, v14
	s_or_b64 vcc, vcc, s[0:1]
	v_add_u32_e32 v14, 27, v0
	v_cndmask_b32_e32 v78, v78, v192, vcc
	v_cmp_gt_i32_e32 vcc, v14, v172
	v_cmp_gt_i32_e64 s[0:1], -2.0, v14
	s_or_b64 vcc, vcc, s[0:1]
	v_add_u32_e32 v14, 32, v0
	v_cndmask_b32_e32 v79, v79, v192, vcc
	v_cmp_gt_i32_e32 vcc, v14, v172
	v_cmp_gt_i32_e64 s[0:1], -2.0, v14
	s_or_b64 vcc, vcc, s[0:1]
	v_add_u32_e32 v14, 33, v0
	v_cndmask_b32_e32 v48, v48, v192, vcc
	v_cmp_gt_i32_e32 vcc, v14, v172
	v_cmp_gt_i32_e64 s[0:1], -2.0, v14
	s_or_b64 vcc, vcc, s[0:1]
	v_add_u32_e32 v14, 34, v0
	v_cndmask_b32_e32 v49, v49, v192, vcc
	v_cmp_gt_i32_e32 vcc, v14, v172
	v_cmp_gt_i32_e64 s[0:1], -2.0, v14
	s_or_b64 vcc, vcc, s[0:1]
	v_add_u32_e32 v14, 35, v0
	v_cndmask_b32_e32 v50, v50, v192, vcc
	v_cmp_gt_i32_e32 vcc, v14, v172
	v_cmp_gt_i32_e64 s[0:1], -2.0, v14
	s_or_b64 vcc, vcc, s[0:1]
	v_add_u32_e32 v14, 40, v0
	v_cndmask_b32_e32 v51, v51, v192, vcc
	v_cmp_gt_i32_e32 vcc, v14, v172
	v_cmp_gt_i32_e64 s[0:1], -2.0, v14
	s_or_b64 vcc, vcc, s[0:1]
	v_add_u32_e32 v14, 41, v0
	v_cndmask_b32_e32 v52, v52, v192, vcc
	v_cmp_gt_i32_e32 vcc, v14, v172
	v_cmp_gt_i32_e64 s[0:1], -2.0, v14
	s_or_b64 vcc, vcc, s[0:1]
	v_add_u32_e32 v14, 42, v0
	v_cndmask_b32_e32 v53, v53, v192, vcc
	v_cmp_gt_i32_e32 vcc, v14, v172
	v_cmp_gt_i32_e64 s[0:1], -2.0, v14
	s_or_b64 vcc, vcc, s[0:1]
	v_add_u32_e32 v14, 43, v0
	v_cndmask_b32_e32 v54, v54, v192, vcc
	v_cmp_gt_i32_e32 vcc, v14, v172
	v_cmp_gt_i32_e64 s[0:1], -2.0, v14
	s_or_b64 vcc, vcc, s[0:1]
	v_add_u32_e32 v14, 48, v0
	v_cndmask_b32_e32 v55, v55, v192, vcc
	v_cmp_gt_i32_e32 vcc, v14, v172
	v_cmp_gt_i32_e64 s[0:1], -2.0, v14
	s_or_b64 vcc, vcc, s[0:1]
	v_add_u32_e32 v14, 49, v0
	v_cndmask_b32_e32 v56, v56, v192, vcc
	v_cmp_gt_i32_e32 vcc, v14, v172
	v_cmp_gt_i32_e64 s[0:1], -2.0, v14
	s_or_b64 vcc, vcc, s[0:1]
	v_add_u32_e32 v14, 50, v0
	v_cndmask_b32_e32 v57, v57, v192, vcc
	v_cmp_gt_i32_e32 vcc, v14, v172
	v_cmp_gt_i32_e64 s[0:1], -2.0, v14
	s_or_b64 vcc, vcc, s[0:1]
	v_add_u32_e32 v14, 51, v0
	v_cndmask_b32_e32 v58, v58, v192, vcc
	v_cmp_gt_i32_e32 vcc, v14, v172
	v_cmp_gt_i32_e64 s[0:1], -2.0, v14
	s_or_b64 vcc, vcc, s[0:1]
	v_add_u32_e32 v14, 56, v0
	v_cndmask_b32_e32 v59, v59, v192, vcc
	v_cmp_gt_i32_e32 vcc, v14, v172
	v_cmp_gt_i32_e64 s[0:1], -2.0, v14
	s_or_b64 vcc, vcc, s[0:1]
	v_add_u32_e32 v14, 57, v0
	v_cndmask_b32_e32 v60, v60, v192, vcc
	v_cmp_gt_i32_e32 vcc, v14, v172
	v_cmp_gt_i32_e64 s[0:1], -2.0, v14
	s_or_b64 vcc, vcc, s[0:1]
	v_add_u32_e32 v14, 58, v0
	v_cndmask_b32_e32 v61, v61, v192, vcc
	v_cmp_gt_i32_e32 vcc, v14, v172
	v_cmp_gt_i32_e64 s[0:1], -2.0, v14
	s_or_b64 vcc, vcc, s[0:1]
	v_add_u32_e32 v0, 59, v0
	v_cndmask_b32_e32 v62, v62, v192, vcc
	v_cmp_gt_i32_e32 vcc, v0, v172
	v_cmp_gt_i32_e64 s[0:1], -2.0, v0
	s_or_b64 vcc, vcc, s[0:1]
	v_cndmask_b32_e32 v63, v63, v192, vcc

; #define MFMA32(a, b, c) __builtin_amdgcn_mfma_f32_32x32x16_bf16((a), (b), (c), 0, 0, 0)
; DEV float fexp2(float x) { return __builtin_amdgcn_exp2f(x); }
; DEV void pv_mma(f32x16 (&o)[2], const bf16x8 (&vf)[2][4], const bf16x8 (&pf)[4]) {
;     __builtin_amdgcn_sched_barrier(0);
; #pragma unroll
;     for (int f = 0; f < 4; ++f)
; #pragma unroll
;         for (int db = 0; db < 2; ++db) o[db] = MFMA32(vf[db][f], pf[f], o[db]);
;     __builtin_amdgcn_sched_barrier(0);
; template <int DQK, int MODE> ...
;     ...
;                 const float cb = rowsel ? -m_new : -INFINITY;
;                 float ps = 0.f;
; #pragma unroll
;                 for (int b2 = 0; b2 < 2; ++b2)
; #pragma unroll
;                     for (int i = 0; i < 16; ++i) { const float p = fexp2(__builtin_fmaf(st[b2][i], sc, cb)); st[b2][i] = p; ps += p; }
;                 l_run += ps;
;                 bf16x8 pf[4]; pack_p(pf, st);
;                 pv_mma(o, vf, pf);
.LBB0_1841:
	v_fma_f32 v14, v64, s38, -v0
	v_exp_f32_e32 v64, v14
	v_fma_f32 v15, v65, s38, -v0
	v_exp_f32_e32 v65, v15
	v_fma_f32 v14, v66, s38, -v0
	v_add_f32_e32 v197, 0, v64
	v_exp_f32_e32 v66, v14
	v_fma_f32 v15, v67, s38, -v0
	v_add_f32_e32 v197, v65, v197
	v_exp_f32_e32 v67, v15
	v_fma_f32 v14, v68, s38, -v0
	v_add_f32_e32 v197, v66, v197
	v_exp_f32_e32 v68, v14
	v_fma_f32 v15, v69, s38, -v0
	v_add_f32_e32 v197, v67, v197
	v_exp_f32_e32 v69, v15
	v_fma_f32 v14, v70, s38, -v0
	v_add_f32_e32 v197, v68, v197
	v_exp_f32_e32 v70, v14
	v_fma_f32 v15, v71, s38, -v0
	v_add_f32_e32 v197, v69, v197
	v_exp_f32_e32 v71, v15
	v_add_f32_e32 v197, v70, v197
	v_add_f32_e32 v197, v71, v197
	v_cvt_pk_bf16_f32 v64, v64, v65
	v_cvt_pk_bf16_f32 v65, v66, v67
	v_cvt_pk_bf16_f32 v66, v68, v69
	v_cvt_pk_bf16_f32 v67, v70, v71
	v_fma_f32 v14, v72, s38, -v0
	v_exp_f32_e32 v72, v14
	v_fma_f32 v15, v73, s38, -v0
	v_exp_f32_e32 v73, v15
	v_mfma_f32_32x32x16_bf16 v[32:47], v[140:143], v[64:67], v[32:47]
	v_mfma_f32_32x32x16_bf16 v[16:31], v[156:159], v[64:67], v[16:31]
	v_fma_f32 v14, v74, s38, -v0
	v_add_f32_e32 v197, v72, v197
	v_exp_f32_e32 v74, v14
	v_fma_f32 v15, v75, s38, -v0
	v_add_f32_e32 v197, v73, v197
	v_exp_f32_e32 v75, v15
	v_fma_f32 v14, v76, s38, -v0
	v_add_f32_e32 v197, v74, v197
	v_exp_f32_e32 v76, v14
	v_fma_f32 v15, v77, s38, -v0
	v_add_f32_e32 v197, v75, v197
	v_exp_f32_e32 v77, v15
	v_fma_f32 v14, v78, s38, -v0
	v_add_f32_e32 v197, v76, v197
	v_exp_f32_e32 v78, v14
	v_fma_f32 v15, v79, s38, -v0
	v_add_f32_e32 v197, v77, v197
	v_exp_f32_e32 v79, v15
	v_add_f32_e32 v197, v78, v197
	v_add_f32_e32 v197, v79, v197
	v_cvt_pk_bf16_f32 v72, v72, v73
	v_cvt_pk_bf16_f32 v73, v74, v75
	v_cvt_pk_bf16_f32 v74, v76, v77
	v_cvt_pk_bf16_f32 v75, v78, v79
	v_fma_f32 v14, v48, s38, -v0
	v_exp_f32_e32 v48, v14
	v_fma_f32 v15, v49, s38, -v0
	v_exp_f32_e32 v49, v15
	v_mfma_f32_32x32x16_bf16 v[32:47], v[10:13], v[72:75], v[32:47]
	v_mfma_f32_32x32x16_bf16 v[16:31], v[152:155], v[72:75], v[16:31]
	v_fma_f32 v14, v50, s38, -v0
	v_add_f32_e32 v197, v48, v197
	v_exp_f32_e32 v50, v14
	v_fma_f32 v15, v51, s38, -v0
	v_add_f32_e32 v197, v49, v197
	v_exp_f32_e32 v51, v15
	v_fma_f32 v14, v52, s38, -v0
	v_add_f32_e32 v197, v50, v197
	v_exp_f32_e32 v52, v14
	v_fma_f32 v15, v53, s38, -v0
	v_add_f32_e32 v197, v51, v197
	v_exp_f32_e32 v53, v15
	v_fma_f32 v14, v54, s38, -v0
	v_add_f32_e32 v197, v52, v197
	v_exp_f32_e32 v54, v14
	v_fma_f32 v15, v55, s38, -v0
	v_add_f32_e32 v197, v53, v197
	v_exp_f32_e32 v55, v15
	v_add_f32_e32 v197, v54, v197
	v_add_f32_e32 v197, v55, v197
	v_cvt_pk_bf16_f32 v48, v48, v49
	v_cvt_pk_bf16_f32 v49, v50, v51
	v_cvt_pk_bf16_f32 v50, v52, v53
	v_cvt_pk_bf16_f32 v51, v54, v55
	v_fma_f32 v14, v56, s38, -v0
	v_exp_f32_e32 v56, v14
	v_fma_f32 v15, v57, s38, -v0
	v_exp_f32_e32 v57, v15
	v_mfma_f32_32x32x16_bf16 v[32:47], v[6:9], v[48:51], v[32:47]
	v_mfma_f32_32x32x16_bf16 v[16:31], v[148:151], v[48:51], v[16:31]
	v_fma_f32 v14, v58, s38, -v0
	v_add_f32_e32 v197, v56, v197
	v_exp_f32_e32 v58, v14
	v_fma_f32 v15, v59, s38, -v0
	v_add_f32_e32 v197, v57, v197
	v_exp_f32_e32 v59, v15
	v_fma_f32 v14, v60, s38, -v0
	v_add_f32_e32 v197, v58, v197
	v_exp_f32_e32 v60, v14
	v_fma_f32 v15, v61, s38, -v0
	v_add_f32_e32 v197, v59, v197
	v_exp_f32_e32 v61, v15
	v_fma_f32 v14, v62, s38, -v0
	v_add_f32_e32 v197, v60, v197
	v_exp_f32_e32 v62, v14
	v_fma_f32 v15, v63, s38, -v0
	v_add_f32_e32 v197, v61, v197
	v_exp_f32_e32 v63, v15
	v_add_f32_e32 v197, v62, v197
	v_add_f32_e32 v197, v63, v197
	v_cvt_pk_bf16_f32 v56, v56, v57
	v_cvt_pk_bf16_f32 v57, v58, v59
	v_cvt_pk_bf16_f32 v58, v60, v61
	v_cvt_pk_bf16_f32 v59, v62, v63
	v_add_f32_e32 v195, v197, v195
	s_nop 0
	v_mfma_f32_32x32x16_bf16 v[32:47], v[2:5], v[56:59], v[32:47]
	v_mfma_f32_32x32x16_bf16 v[16:31], v[144:147], v[56:59], v[16:31]
.LBB0_1842:
	s_cmp_ge_i32 s42, s40
	s_mul_i32 s26, s44, 3
	s_cbranch_scc1 .LBB0_1849
	s_lshl_b32 s0, s42, 6
	s_add_i32 s0, s0, 64
	v_cmp_le_i32_e32 vcc, s0, v172
	s_cbranch_vccz .LBB0_1849
	s_add_i32 s1, s26, 1
	s_mul_i32 s44, s1, 0x3400
	v_add_u32_e32 v0, s44, v175
	ds_read_b128 v[2:5], v0
	ds_read_b128 v[6:9], v0 offset:32
	ds_read_b128 v[10:13], v0 offset:64
	ds_read_b128 v[48:51], v0 offset:96
	ds_read_b128 v[52:55], v0 offset:128
	ds_read_b128 v[56:59], v0 offset:160
	ds_read_b128 v[60:63], v0 offset:6656
	ds_read_b128 v[140:143], v0 offset:6688
	ds_read_b128 v[144:147], v0 offset:6720
	ds_read_b128 v[148:151], v0 offset:6752
	ds_read_b128 v[152:155], v0 offset:6784
	ds_read_b128 v[156:159], v0 offset:6816
	s_mulk_i32 s1, 0x2200
	s_setprio 1
	s_waitcnt lgkmcnt(11)
	v_mfma_f32_32x32x16_bf16 v[64:79], v[2:5], v[80:83], 0
	s_waitcnt lgkmcnt(10)
	v_mfma_f32_32x32x16_bf16 v[64:79], v[6:9], v[84:87], v[64:79]
	s_waitcnt lgkmcnt(9)
	v_mfma_f32_32x32x16_bf16 v[64:79], v[10:13], v[88:91], v[64:79]
	s_waitcnt lgkmcnt(8)
	v_mfma_f32_32x32x16_bf16 v[64:79], v[48:51], v[92:95], v[64:79]
	s_waitcnt lgkmcnt(7)
	v_mfma_f32_32x32x16_bf16 v[64:79], v[52:55], v[132:135], v[64:79]
	s_waitcnt lgkmcnt(6)
	v_mfma_f32_32x32x16_bf16 v[64:79], v[56:59], v[136:139], v[64:79]
	s_waitcnt lgkmcnt(5)
	v_mfma_f32_32x32x16_bf16 v[48:63], v[60:63], v[80:83], 0
	s_waitcnt lgkmcnt(4)
	v_mfma_f32_32x32x16_bf16 v[48:63], v[140:143], v[84:87], v[48:63]
	s_waitcnt lgkmcnt(3)
	v_mfma_f32_32x32x16_bf16 v[48:63], v[144:147], v[88:91], v[48:63]
	s_waitcnt lgkmcnt(2)
	v_mfma_f32_32x32x16_bf16 v[48:63], v[148:151], v[92:95], v[48:63]
	s_waitcnt lgkmcnt(1)
	v_mfma_f32_32x32x16_bf16 v[48:63], v[152:155], v[132:135], v[48:63]
	s_waitcnt lgkmcnt(0)
	v_mfma_f32_32x32x16_bf16 v[48:63], v[156:159], v[136:139], v[48:63]
	s_setprio 0
	v_add_u32_e32 v0, s1, v179
	ds_read2_b64 v[140:143], v0 offset1:2
	ds_read2_b64 v[10:13], v0 offset0:4 offset1:6
	ds_read2_b64 v[6:9], v0 offset0:8 offset1:10
	ds_read2_b64 v[2:5], v0 offset0:12 offset1:14
	v_add_u32_e32 v0, 0x1000, v0
	ds_read2_b64 v[156:159], v0 offset0:32 offset1:34
	ds_read2_b64 v[152:155], v0 offset0:36 offset1:38
	ds_read2_b64 v[148:151], v0 offset0:40 offset1:42
	ds_read2_b64 v[144:147], v0 offset0:44 offset1:46
	s_or_b32 s1, s0, 63
	v_cmp_le_i32_e32 vcc, s1, v172
	s_cmp_eq_u64 vcc, exec
	s_cbranch_scc1 .LBB0_1846
; DEV int crow(int i, int h) { return (i & 3) + 8 * (i >> 2) + 4 * h; }
; template <int DQK, int MODE> ...
;     ...
;             const bool interior = __all(((k0 + 63 <= hi_lim) && (k0 >= lo_lim)) ? 1 : 0);
;             if (!interior) {
; #pragma unroll
;                 for (int b2 = 0; b2 < 2; ++b2)
; #pragma unroll
;                     for (int i = 0; i < 16; ++i) { const int key = k0 + 32 * b2 + crow(i, h); const bool vis = (key <= hi_lim) && (key >= lo_lim); st[b2][i] = vis ? st[b2][i] : -INFINITY; }
;             }
	v_add_u32_e32 v0, s0, v193
	v_cmp_gt_i32_e32 vcc, v0, v172
	v_cmp_gt_i32_e64 s[0:1], -2.0, v0
	s_or_b64 vcc, vcc, s[0:1]
	v_add_u32_e32 v14, 1, v0
	v_cndmask_b32_e32 v64, v64, v192, vcc
	v_cmp_gt_i32_e32 vcc, v14, v172
	v_cmp_gt_i32_e64 s[0:1], -2.0, v14
	s_or_b64 vcc, vcc, s[0:1]
	v_add_u32_e32 v14, 2, v0
	v_cndmask_b32_e32 v65, v65, v192, vcc
	v_cmp_gt_i32_e32 vcc, v14, v172
	v_cmp_gt_i32_e64 s[0:1], -2.0, v14
	s_or_b64 vcc, vcc, s[0:1]
	v_add_u32_e32 v14, 3, v0
	v_cndmask_b32_e32 v66, v66, v192, vcc
	v_cmp_gt_i32_e32 vcc, v14, v172
	v_cmp_gt_i32_e64 s[0:1], -2.0, v14
	s_or_b64 vcc, vcc, s[0:1]
	v_add_u32_e32 v14, 8, v0
	v_cndmask_b32_e32 v67, v67, v192, vcc
	v_cmp_gt_i32_e32 vcc, v14, v172
	v_cmp_gt_i32_e64 s[0:1], -2.0, v14
	s_or_b64 vcc, vcc, s[0:1]
	v_add_u32_e32 v14, 9, v0
	v_cndmask_b32_e32 v68, v68, v192, vcc
	v_cmp_gt_i32_e32 vcc, v14, v172
	v_cmp_gt_i32_e64 s[0:1], -2.0, v14
	s_or_b64 vcc, vcc, s[0:1]
	v_add_u32_e32 v14, 10, v0
	v_cndmask_b32_e32 v69, v69, v192, vcc
	v_cmp_gt_i32_e32 vcc, v14, v172
	v_cmp_gt_i32_e64 s[0:1], -2.0, v14
	s_or_b64 vcc, vcc, s[0:1]
	v_add_u32_e32 v14, 11, v0
	v_cndmask_b32_e32 v70, v70, v192, vcc
	v_cmp_gt_i32_e32 vcc, v14, v172
	v_cmp_gt_i32_e64 s[0:1], -2.0, v14
	s_or_b64 vcc, vcc, s[0:1]
	v_add_u32_e32 v14, 16, v0
	v_cndmask_b32_e32 v71, v71, v192, vcc
	v_cmp_gt_i32_e32 vcc, v14, v172
	v_cmp_gt_i32_e64 s[0:1], -2.0, v14
	s_or_b64 vcc, vcc, s[0:1]
	v_add_u32_e32 v14, 17, v0
	v_cndmask_b32_e32 v72, v72, v192, vcc
	v_cmp_gt_i32_e32 vcc, v14, v172
	v_cmp_gt_i32_e64 s[0:1], -2.0, v14
	s_or_b64 vcc, vcc, s[0:1]
	v_add_u32_e32 v14, 18, v0
	v_cndmask_b32_e32 v73, v73, v192, vcc
	v_cmp_gt_i32_e32 vcc, v14, v172
	v_cmp_gt_i32_e64 s[0:1], -2.0, v14
	s_or_b64 vcc, vcc, s[0:1]
	v_add_u32_e32 v14, 19, v0
	v_cndmask_b32_e32 v74, v74, v192, vcc
	v_cmp_gt_i32_e32 vcc, v14, v172
	v_cmp_gt_i32_e64 s[0:1], -2.0, v14
	s_or_b64 vcc, vcc, s[0:1]
	v_add_u32_e32 v14, 24, v0
	v_cndmask_b32_e32 v75, v75, v192, vcc
	v_cmp_gt_i32_e32 vcc, v14, v172
	v_cmp_gt_i32_e64 s[0:1], -2.0, v14
	s_or_b64 vcc, vcc, s[0:1]
	v_add_u32_e32 v14, 25, v0
	v_cndmask_b32_e32 v76, v76, v192, vcc
	v_cmp_gt_i32_e32 vcc, v14, v172
	v_cmp_gt_i32_e64 s[0:1], -2.0, v14
	s_or_b64 vcc, vcc, s[0:1]
	v_add_u32_e32 v14, 26, v0
	v_cndmask_b32_e32 v77, v77, v192, vcc
	v_cmp_gt_i32_e32 vcc, v14, v172
	v_cmp_gt_i32_e64 s[0:1], -2.0, v14
	s_or_b64 vcc, vcc, s[0:1]
	v_add_u32_e32 v14, 27, v0
	v_cndmask_b32_e32 v78, v78, v192, vcc
	v_cmp_gt_i32_e32 vcc, v14, v172
	v_cmp_gt_i32_e64 s[0:1], -2.0, v14
	s_or_b64 vcc, vcc, s[0:1]
	v_add_u32_e32 v14, 32, v0
	v_cndmask_b32_e32 v79, v79, v192, vcc
	v_cmp_gt_i32_e32 vcc, v14, v172
	v_cmp_gt_i32_e64 s[0:1], -2.0, v14
	s_or_b64 vcc, vcc, s[0:1]
	v_add_u32_e32 v14, 33, v0
	v_cndmask_b32_e32 v48, v48, v192, vcc
	v_cmp_gt_i32_e32 vcc, v14, v172
	v_cmp_gt_i32_e64 s[0:1], -2.0, v14
	s_or_b64 vcc, vcc, s[0:1]
	v_add_u32_e32 v14, 34, v0
	v_cndmask_b32_e32 v49, v49, v192, vcc
	v_cmp_gt_i32_e32 vcc, v14, v172
	v_cmp_gt_i32_e64 s[0:1], -2.0, v14
	s_or_b64 vcc, vcc, s[0:1]
	v_add_u32_e32 v14, 35, v0
	v_cndmask_b32_e32 v50, v50, v192, vcc
	v_cmp_gt_i32_e32 vcc, v14, v172
	v_cmp_gt_i32_e64 s[0:1], -2.0, v14
	s_or_b64 vcc, vcc, s[0:1]
	v_add_u32_e32 v14, 40, v0
	v_cndmask_b32_e32 v51, v51, v192, vcc
	v_cmp_gt_i32_e32 vcc, v14, v172
	v_cmp_gt_i32_e64 s[0:1], -2.0, v14
	s_or_b64 vcc, vcc, s[0:1]
	v_add_u32_e32 v14, 41, v0
	v_cndmask_b32_e32 v52, v52, v192, vcc
	v_cmp_gt_i32_e32 vcc, v14, v172
	v_cmp_gt_i32_e64 s[0:1], -2.0, v14
	s_or_b64 vcc, vcc, s[0:1]
	v_add_u32_e32 v14, 42, v0
	v_cndmask_b32_e32 v53, v53, v192, vcc
	v_cmp_gt_i32_e32 vcc, v14, v172
	v_cmp_gt_i32_e64 s[0:1], -2.0, v14
	s_or_b64 vcc, vcc, s[0:1]
	v_add_u32_e32 v14, 43, v0
	v_cndmask_b32_e32 v54, v54, v192, vcc
	v_cmp_gt_i32_e32 vcc, v14, v172
	v_cmp_gt_i32_e64 s[0:1], -2.0, v14
	s_or_b64 vcc, vcc, s[0:1]
	v_add_u32_e32 v14, 48, v0
	v_cndmask_b32_e32 v55, v55, v192, vcc
	v_cmp_gt_i32_e32 vcc, v14, v172
	v_cmp_gt_i32_e64 s[0:1], -2.0, v14
	s_or_b64 vcc, vcc, s[0:1]
	v_add_u32_e32 v14, 49, v0
	v_cndmask_b32_e32 v56, v56, v192, vcc
	v_cmp_gt_i32_e32 vcc, v14, v172
	v_cmp_gt_i32_e64 s[0:1], -2.0, v14
	s_or_b64 vcc, vcc, s[0:1]
	v_add_u32_e32 v14, 50, v0
	v_cndmask_b32_e32 v57, v57, v192, vcc
	v_cmp_gt_i32_e32 vcc, v14, v172
	v_cmp_gt_i32_e64 s[0:1], -2.0, v14
	s_or_b64 vcc, vcc, s[0:1]
	v_add_u32_e32 v14, 51, v0
	v_cndmask_b32_e32 v58, v58, v192, vcc
	v_cmp_gt_i32_e32 vcc, v14, v172
	v_cmp_gt_i32_e64 s[0:1], -2.0, v14
	s_or_b64 vcc, vcc, s[0:1]
	v_add_u32_e32 v14, 56, v0
	v_cndmask_b32_e32 v59, v59, v192, vcc
	v_cmp_gt_i32_e32 vcc, v14, v172
	v_cmp_gt_i32_e64 s[0:1], -2.0, v14
	s_or_b64 vcc, vcc, s[0:1]
	v_add_u32_e32 v14, 57, v0
	v_cndmask_b32_e32 v60, v60, v192, vcc
	v_cmp_gt_i32_e32 vcc, v14, v172
	v_cmp_gt_i32_e64 s[0:1], -2.0, v14
	s_or_b64 vcc, vcc, s[0:1]
	v_add_u32_e32 v14, 58, v0
	v_cndmask_b32_e32 v61, v61, v192, vcc
	v_cmp_gt_i32_e32 vcc, v14, v172
	v_cmp_gt_i32_e64 s[0:1], -2.0, v14
	s_or_b64 vcc, vcc, s[0:1]
	v_add_u32_e32 v0, 59, v0
	v_cndmask_b32_e32 v62, v62, v192, vcc
	v_cmp_gt_i32_e32 vcc, v0, v172
	v_cmp_gt_i32_e64 s[0:1], -2.0, v0
	s_or_b64 vcc, vcc, s[0:1]
	v_cndmask_b32_e32 v63, v63, v192, vcc

; #define LAS __attribute__((address_space(3)))
; #define MFMA32(a, b, c) __builtin_amdgcn_mfma_f32_32x32x16_bf16((a), (b), (c), 0, 0, 0)
; template <int DQK> DEV void qk_tile(f32x16 (&st)[2], const LAS unsigned char* kb, const bf16x8 (&qf)[DQK / 16], int r, int h) {
;     constexpr int KSTR = DQK * 2 + 16, NS = DQK / 16;
;     bf16x8 kf[2][NS];
; #pragma unroll
;     for (int b2 = 0; b2 < 2; ++b2)
; #pragma unroll
;         for (int s = 0; s < NS; ++s) kf[b2][s] = *(const LAS bf16x8*)(kb + (32 * b2 + r) * KSTR + 32 * s + 16 * h);
;     __builtin_amdgcn_sched_barrier(0);
; #pragma unroll
;     for (int b2 = 0; b2 < 2; ++b2) {
;         f32x16 a;
; #pragma unroll
;         for (int i = 0; i < 16; ++i) a[i] = 0.f;
; #pragma unroll
;         for (int s = 0; s < NS; ++s) a = MFMA32(kf[b2][s], qf[s], a);
;         st[b2] = a;
;     }
;     __builtin_amdgcn_sched_barrier(0);
; }
; template <int DQK, int MODE> ...
;     ...
;         LAS unsigned char* kb = lds + AL_K0 + slot * AL_KSTR; LAS unsigned char* vb = lds + AL_V0 + slot * AL_VSTR;
;         const int k0 = 64 * t;
;         bool rowsel = true;
;         if (MODE == 1) rowsel = (selm.x >> (t >> 2)) & 1u;
;         if (MODE == 2) { const int tw = t >> 5; const unsigned w = tw == 0 ? selm.x : (tw == 1 ? selm.y : (tw == 2 ? selm.z : selm.w)); rowsel = (w >> (t & 31)) & 1u; }
;         const bool rowact = rowsel && (k0 <= hi_lim) && (k0 + 63 >= lo_lim);
;         if (__any(rowact ? 1 : 0)) {
;             f32x16 st[2];
;             qk_tile<DQK>(st, kb, qf, r, h);
;             bf16x8 vf[2][4];
;             if (MODE != 3) pv_load(vf, vb, r, h);
;             const bool interior = __all(((k0 + 63 <= hi_lim) && (k0 >= lo_lim)) ? 1 : 0);
.LBB0_1849:
	s_add_i32 s0, s42, 2
	s_cmp_gt_i32 s0, s40
	s_cbranch_scc1 .LBB0_1856
	s_lshl_b32 s0, s0, 6
	v_cmp_le_i32_e32 vcc, s0, v172
	s_cbranch_vccz .LBB0_1856
	s_add_i32 s1, s26, 2
	s_mul_i32 s26, s1, 0x3400
	v_add_u32_e32 v0, s26, v175
	ds_read_b128 v[2:5], v0
	ds_read_b128 v[6:9], v0 offset:32
	ds_read_b128 v[10:13], v0 offset:64
	ds_read_b128 v[48:51], v0 offset:96
	ds_read_b128 v[52:55], v0 offset:128
	ds_read_b128 v[56:59], v0 offset:160
	ds_read_b128 v[60:63], v0 offset:6656
	ds_read_b128 v[140:143], v0 offset:6688
	ds_read_b128 v[144:147], v0 offset:6720
	ds_read_b128 v[148:151], v0 offset:6752
	ds_read_b128 v[152:155], v0 offset:6784
	ds_read_b128 v[156:159], v0 offset:6816
	s_mulk_i32 s1, 0x2200
	s_setprio 1
	s_waitcnt lgkmcnt(11)
	v_mfma_f32_32x32x16_bf16 v[64:79], v[2:5], v[80:83], 0
	s_waitcnt lgkmcnt(10)
	v_mfma_f32_32x32x16_bf16 v[64:79], v[6:9], v[84:87], v[64:79]
	s_waitcnt lgkmcnt(9)
	v_mfma_f32_32x32x16_bf16 v[64:79], v[10:13], v[88:91], v[64:79]
	s_waitcnt lgkmcnt(8)
	v_mfma_f32_32x32x16_bf16 v[64:79], v[48:51], v[92:95], v[64:79]
	s_waitcnt lgkmcnt(7)
	v_mfma_f32_32x32x16_bf16 v[64:79], v[52:55], v[132:135], v[64:79]
	s_waitcnt lgkmcnt(6)
	v_mfma_f32_32x32x16_bf16 v[64:79], v[56:59], v[136:139], v[64:79]
	s_waitcnt lgkmcnt(5)
	v_mfma_f32_32x32x16_bf16 v[48:63], v[60:63], v[80:83], 0
	s_waitcnt lgkmcnt(4)
	v_mfma_f32_32x32x16_bf16 v[48:63], v[140:143], v[84:87], v[48:63]
	s_waitcnt lgkmcnt(3)
	v_mfma_f32_32x32x16_bf16 v[48:63], v[144:147], v[88:91], v[48:63]
	s_waitcnt lgkmcnt(2)
	v_mfma_f32_32x32x16_bf16 v[48:63], v[148:151], v[92:95], v[48:63]
	s_waitcnt lgkmcnt(1)
	v_mfma_f32_32x32x16_bf16 v[48:63], v[152:155], v[132:135], v[48:63]
	s_waitcnt lgkmcnt(0)
	v_mfma_f32_32x32x16_bf16 v[48:63], v[156:159], v[136:139], v[48:63]
	s_setprio 0
	v_add_u32_e32 v0, s1, v179
	ds_read2_b64 v[140:143], v0 offset1:2
	ds_read2_b64 v[10:13], v0 offset0:4 offset1:6
	ds_read2_b64 v[6:9], v0 offset0:8 offset1:10
	ds_read2_b64 v[2:5], v0 offset0:12 offset1:14
	v_add_u32_e32 v0, 0x1000, v0
	ds_read2_b64 v[156:159], v0 offset0:32 offset1:34
	ds_read2_b64 v[152:155], v0 offset0:36 offset1:38
	ds_read2_b64 v[148:151], v0 offset0:40 offset1:42
	ds_read2_b64 v[144:147], v0 offset0:44 offset1:46
	s_or_b32 s1, s0, 63
	v_cmp_le_i32_e32 vcc, s1, v172
	s_cmp_eq_u64 vcc, exec
	s_cbranch_scc1 .LBB0_1853
; DEV int crow(int i, int h) { return (i & 3) + 8 * (i >> 2) + 4 * h; }
; template <int DQK, int MODE> ...
;     ...
;             const bool interior = __all(((k0 + 63 <= hi_lim) && (k0 >= lo_lim)) ? 1 : 0);
;             if (!interior) {
; #pragma unroll
;                 for (int b2 = 0; b2 < 2; ++b2)
; #pragma unroll
;                     for (int i = 0; i < 16; ++i) { const int key = k0 + 32 * b2 + crow(i, h); const bool vis = (key <= hi_lim) && (key >= lo_lim); st[b2][i] = vis ? st[b2][i] : -INFINITY; }
;             }
	v_add_u32_e32 v0, s0, v193
	v_cmp_gt_i32_e32 vcc, v0, v172
	v_cmp_gt_i32_e64 s[0:1], -2.0, v0
	s_or_b64 vcc, vcc, s[0:1]
	v_add_u32_e32 v14, 1, v0
	v_cndmask_b32_e32 v64, v64, v192, vcc
	v_cmp_gt_i32_e32 vcc, v14, v172
	v_cmp_gt_i32_e64 s[0:1], -2.0, v14
	s_or_b64 vcc, vcc, s[0:1]
	v_add_u32_e32 v14, 2, v0
	v_cndmask_b32_e32 v65, v65, v192, vcc
	v_cmp_gt_i32_e32 vcc, v14, v172
	v_cmp_gt_i32_e64 s[0:1], -2.0, v14
	s_or_b64 vcc, vcc, s[0:1]
	v_add_u32_e32 v14, 3, v0
	v_cndmask_b32_e32 v66, v66, v192, vcc
	v_cmp_gt_i32_e32 vcc, v14, v172
	v_cmp_gt_i32_e64 s[0:1], -2.0, v14
	s_or_b64 vcc, vcc, s[0:1]
	v_add_u32_e32 v14, 8, v0
	v_cndmask_b32_e32 v67, v67, v192, vcc
	v_cmp_gt_i32_e32 vcc, v14, v172
	v_cmp_gt_i32_e64 s[0:1], -2.0, v14
	s_or_b64 vcc, vcc, s[0:1]
	v_add_u32_e32 v14, 9, v0
	v_cndmask_b32_e32 v68, v68, v192, vcc
	v_cmp_gt_i32_e32 vcc, v14, v172
	v_cmp_gt_i32_e64 s[0:1], -2.0, v14
	s_or_b64 vcc, vcc, s[0:1]
	v_add_u32_e32 v14, 10, v0
	v_cndmask_b32_e32 v69, v69, v192, vcc
	v_cmp_gt_i32_e32 vcc, v14, v172
	v_cmp_gt_i32_e64 s[0:1], -2.0, v14
	s_or_b64 vcc, vcc, s[0:1]
	v_add_u32_e32 v14, 11, v0
	v_cndmask_b32_e32 v70, v70, v192, vcc
	v_cmp_gt_i32_e32 vcc, v14, v172
	v_cmp_gt_i32_e64 s[0:1], -2.0, v14
	s_or_b64 vcc, vcc, s[0:1]
	v_add_u32_e32 v14, 16, v0
	v_cndmask_b32_e32 v71, v71, v192, vcc
	v_cmp_gt_i32_e32 vcc, v14, v172
	v_cmp_gt_i32_e64 s[0:1], -2.0, v14
	s_or_b64 vcc, vcc, s[0:1]
	v_add_u32_e32 v14, 17, v0
	v_cndmask_b32_e32 v72, v72, v192, vcc
	v_cmp_gt_i32_e32 vcc, v14, v172
	v_cmp_gt_i32_e64 s[0:1], -2.0, v14
	s_or_b64 vcc, vcc, s[0:1]
	v_add_u32_e32 v14, 18, v0
	v_cndmask_b32_e32 v73, v73, v192, vcc
	v_cmp_gt_i32_e32 vcc, v14, v172
	v_cmp_gt_i32_e64 s[0:1], -2.0, v14
	s_or_b64 vcc, vcc, s[0:1]
	v_add_u32_e32 v14, 19, v0
	v_cndmask_b32_e32 v74, v74, v192, vcc
	v_cmp_gt_i32_e32 vcc, v14, v172
	v_cmp_gt_i32_e64 s[0:1], -2.0, v14
	s_or_b64 vcc, vcc, s[0:1]
	v_add_u32_e32 v14, 24, v0
	v_cndmask_b32_e32 v75, v75, v192, vcc
	v_cmp_gt_i32_e32 vcc, v14, v172
	v_cmp_gt_i32_e64 s[0:1], -2.0, v14
	s_or_b64 vcc, vcc, s[0:1]
	v_add_u32_e32 v14, 25, v0
	v_cndmask_b32_e32 v76, v76, v192, vcc
	v_cmp_gt_i32_e32 vcc, v14, v172
	v_cmp_gt_i32_e64 s[0:1], -2.0, v14
	s_or_b64 vcc, vcc, s[0:1]
	v_add_u32_e32 v14, 26, v0
	v_cndmask_b32_e32 v77, v77, v192, vcc
	v_cmp_gt_i32_e32 vcc, v14, v172
	v_cmp_gt_i32_e64 s[0:1], -2.0, v14
	s_or_b64 vcc, vcc, s[0:1]
	v_add_u32_e32 v14, 27, v0
	v_cndmask_b32_e32 v78, v78, v192, vcc
	v_cmp_gt_i32_e32 vcc, v14, v172
	v_cmp_gt_i32_e64 s[0:1], -2.0, v14
	s_or_b64 vcc, vcc, s[0:1]
	v_add_u32_e32 v14, 32, v0
	v_cndmask_b32_e32 v79, v79, v192, vcc
	v_cmp_gt_i32_e32 vcc, v14, v172
	v_cmp_gt_i32_e64 s[0:1], -2.0, v14
	s_or_b64 vcc, vcc, s[0:1]
	v_add_u32_e32 v14, 33, v0
	v_cndmask_b32_e32 v48, v48, v192, vcc
	v_cmp_gt_i32_e32 vcc, v14, v172
	v_cmp_gt_i32_e64 s[0:1], -2.0, v14
	s_or_b64 vcc, vcc, s[0:1]
	v_add_u32_e32 v14, 34, v0
	v_cndmask_b32_e32 v49, v49, v192, vcc
	v_cmp_gt_i32_e32 vcc, v14, v172
	v_cmp_gt_i32_e64 s[0:1], -2.0, v14
	s_or_b64 vcc, vcc, s[0:1]
	v_add_u32_e32 v14, 35, v0
	v_cndmask_b32_e32 v50, v50, v192, vcc
	v_cmp_gt_i32_e32 vcc, v14, v172
	v_cmp_gt_i32_e64 s[0:1], -2.0, v14
	s_or_b64 vcc, vcc, s[0:1]
	v_add_u32_e32 v14, 40, v0
	v_cndmask_b32_e32 v51, v51, v192, vcc
	v_cmp_gt_i32_e32 vcc, v14, v172
	v_cmp_gt_i32_e64 s[0:1], -2.0, v14
	s_or_b64 vcc, vcc, s[0:1]
	v_add_u32_e32 v14, 41, v0
	v_cndmask_b32_e32 v52, v52, v192, vcc
	v_cmp_gt_i32_e32 vcc, v14, v172
	v_cmp_gt_i32_e64 s[0:1], -2.0, v14
	s_or_b64 vcc, vcc, s[0:1]
	v_add_u32_e32 v14, 42, v0
	v_cndmask_b32_e32 v53, v53, v192, vcc
	v_cmp_gt_i32_e32 vcc, v14, v172
	v_cmp_gt_i32_e64 s[0:1], -2.0, v14
	s_or_b64 vcc, vcc, s[0:1]
	v_add_u32_e32 v14, 43, v0
	v_cndmask_b32_e32 v54, v54, v192, vcc
	v_cmp_gt_i32_e32 vcc, v14, v172
	v_cmp_gt_i32_e64 s[0:1], -2.0, v14
	s_or_b64 vcc, vcc, s[0:1]
	v_add_u32_e32 v14, 48, v0
	v_cndmask_b32_e32 v55, v55, v192, vcc
	v_cmp_gt_i32_e32 vcc, v14, v172
	v_cmp_gt_i32_e64 s[0:1], -2.0, v14
	s_or_b64 vcc, vcc, s[0:1]
	v_add_u32_e32 v14, 49, v0
	v_cndmask_b32_e32 v56, v56, v192, vcc
	v_cmp_gt_i32_e32 vcc, v14, v172
	v_cmp_gt_i32_e64 s[0:1], -2.0, v14
	s_or_b64 vcc, vcc, s[0:1]
	v_add_u32_e32 v14, 50, v0
	v_cndmask_b32_e32 v57, v57, v192, vcc
	v_cmp_gt_i32_e32 vcc, v14, v172
	v_cmp_gt_i32_e64 s[0:1], -2.0, v14
	s_or_b64 vcc, vcc, s[0:1]
	v_add_u32_e32 v14, 51, v0
	v_cndmask_b32_e32 v58, v58, v192, vcc
	v_cmp_gt_i32_e32 vcc, v14, v172
	v_cmp_gt_i32_e64 s[0:1], -2.0, v14
	s_or_b64 vcc, vcc, s[0:1]
	v_add_u32_e32 v14, 56, v0
	v_cndmask_b32_e32 v59, v59, v192, vcc
	v_cmp_gt_i32_e32 vcc, v14, v172
	v_cmp_gt_i32_e64 s[0:1], -2.0, v14
	s_or_b64 vcc, vcc, s[0:1]
	v_add_u32_e32 v14, 57, v0
	v_cndmask_b32_e32 v60, v60, v192, vcc
	v_cmp_gt_i32_e32 vcc, v14, v172
	v_cmp_gt_i32_e64 s[0:1], -2.0, v14
	s_or_b64 vcc, vcc, s[0:1]
	v_add_u32_e32 v14, 58, v0
	v_cndmask_b32_e32 v61, v61, v192, vcc
	v_cmp_gt_i32_e32 vcc, v14, v172
	v_cmp_gt_i32_e64 s[0:1], -2.0, v14
	s_or_b64 vcc, vcc, s[0:1]
	v_add_u32_e32 v0, 59, v0
	v_cndmask_b32_e32 v62, v62, v192, vcc
	v_cmp_gt_i32_e32 vcc, v0, v172
	v_cmp_gt_i32_e64 s[0:1], -2.0, v0
	s_or_b64 vcc, vcc, s[0:1]
	v_cndmask_b32_e32 v63, v63, v192, vcc

; __device__ __forceinline__ unsigned pk2_(float lo, float hi) { return f2bf_(lo) | (f2bf_(hi) << 16); }
; template <int ACT> __device__ __forceinline__ float act_f(float v) {
;     if (ACT == 2) { const float t = fmaxf(v, 0.f); return t * t; }
;     __device__ __forceinline__ void operator()(const f32x4 (&acc)[2][2][4][2], const Unit& u, int wr, int wc, int fr, int fq) const {
;     ...
;         const int row0 = u.pm * BM + wr * 64 + fr; const int col0 = u.pn * BM + wc * 32 + 8 * fq;
; #pragma unroll
;         for (int ai = 0; ai < 2; ++ai)
; #pragma unroll
;             for (int m = 0; m < 4; ++m) { bf16_t* rowp = O + (size_t)(row0 + ai * HALF + m * 16) * ldc + col0;
; #pragma unroll
;                 for (int bj = 0; bj < 2; ++bj) { f32x4 v0 = acc[ai][bj][m][0], v1 = acc[ai][bj][m][1];
;                     if (bias) { v0 += *(const f32x4*)(bias + col0 + bj * HALF); v1 += *(const f32x4*)(bias + col0 + bj * HALF + 4); }
;                     u32x4 w; w.x = pk2_(act_f<ACT>(v0[0]), act_f<ACT>(v0[1])); w.y = pk2_(act_f<ACT>(v0[2]), act_f<ACT>(v0[3]));
;                     w.z = pk2_(act_f<ACT>(v1[0]), act_f<ACT>(v1[1])); w.w = pk2_(act_f<ACT>(v1[2]), act_f<ACT>(v1[3]));
;                     *(u32x4*)(rowp + bj * HALF) = w; } }
.LBB0_2082:
	v_mov_b32_e32 v145, v147
	v_mov_b32_e32 v144, v146
	s_lshl_b32 s37, s44, 8
	s_add_i32 s37, s37, s55
	v_add_u32_e32 v144, s37, v144
	s_lshl_b32 s37, s75, 8
	s_or_b32 s37, s37, s57
	v_lshl_add_u32 v152, v145, 3, s37
	v_ashrrev_i32_e32 v145, 31, v144
	v_lshlrev_b64 v[144:145], 13, v[144:145]
	v_ashrrev_i32_e32 v153, 31, v152
	v_lshl_add_u64 v[144:145], s[18:19], 0, v[144:145]
	v_lshl_add_u64 v[144:145], v[152:153], 1, v[144:145]
	v_max_f32_e32 v152, 0, v125
	v_max_f32_e32 v125, v126, v126
	v_max_f32_e32 v126, v127, v127
	v_max_f32_e32 v153, 0, v126
	v_pk_mul_f32 v[126:127], v[152:153], v[152:153]
	v_max_f32_e32 v152, 0, v121
	v_max_f32_e32 v121, v122, v122
	v_max_f32_e32 v122, v123, v123
	v_max_f32_e32 v153, 0, v122
	v_max_f32_e32 v124, 0, v124
	v_max_f32_e32 v125, 0, v125
	v_max_f32_e32 v120, 0, v120
	v_max_f32_e32 v121, 0, v121
	v_pk_mul_f32 v[122:123], v[152:153], v[152:153]
	v_pk_mul_f32 v[124:125], v[124:125], v[124:125]
	v_pk_mul_f32 v[120:121], v[120:121], v[120:121]
	v_cvt_pk_bf16_f32 v123, v121, v123
	v_cvt_pk_bf16_f32 v122, v120, v122
	v_cvt_pk_bf16_f32 v121, v125, v127
	v_cvt_pk_bf16_f32 v120, v124, v126
	global_store_dwordx4 v[144:145], v[120:123], off
	s_nop 1
	v_max_f32_e32 v120, 0, v117
	v_max_f32_e32 v117, v118, v118
	v_max_f32_e32 v118, v119, v119
	v_max_f32_e32 v121, 0, v118
	v_pk_mul_f32 v[118:119], v[120:121], v[120:121]
	v_max_f32_e32 v120, 0, v113
	v_max_f32_e32 v113, v114, v114
	v_max_f32_e32 v114, v115, v115
	v_max_f32_e32 v121, 0, v114
	v_max_f32_e32 v116, 0, v116
	v_max_f32_e32 v117, 0, v117
	v_max_f32_e32 v112, 0, v112
	v_max_f32_e32 v113, 0, v113
	v_pk_mul_f32 v[114:115], v[120:121], v[120:121]
	v_pk_mul_f32 v[116:117], v[116:117], v[116:117]
	v_pk_mul_f32 v[112:113], v[112:113], v[112:113]
	v_cvt_pk_bf16_f32 v115, v113, v115
	v_cvt_pk_bf16_f32 v114, v112, v114
	v_cvt_pk_bf16_f32 v113, v117, v119
	v_cvt_pk_bf16_f32 v112, v116, v118
	global_store_dwordx4 v[144:145], v[112:115], off offset:256
	s_nop 1
	v_max_f32_e32 v114, 0, v109
	v_max_f32_e32 v109, v110, v110
	v_max_f32_e32 v110, v111, v111
	v_max_f32_e32 v115, 0, v110
	v_pk_mul_f32 v[110:111], v[114:115], v[114:115]
	v_max_f32_e32 v114, 0, v105
	v_max_f32_e32 v105, v106, v106
	v_max_f32_e32 v106, v107, v107
	v_max_f32_e32 v115, 0, v106
	v_max_f32_e32 v108, 0, v108
	v_max_f32_e32 v109, 0, v109
	v_max_f32_e32 v104, 0, v104
	v_max_f32_e32 v105, 0, v105
	v_pk_mul_f32 v[106:107], v[114:115], v[114:115]
	v_pk_mul_f32 v[108:109], v[108:109], v[108:109]
	v_pk_mul_f32 v[104:105], v[104:105], v[104:105]
	s_mov_b32 s37, 0x20000
	v_cvt_pk_bf16_f32 v106, v104, v106
	v_cvt_pk_bf16_f32 v104, v108, v110
	v_add_co_u32_e32 v108, vcc, s37, v144
	v_cvt_pk_bf16_f32 v107, v105, v107
	v_cvt_pk_bf16_f32 v105, v109, v111
	v_addc_co_u32_e32 v109, vcc, 0, v145, vcc
	global_store_dwordx4 v[108:109], v[104:107], off
	s_nop 1
	v_max_f32_e32 v104, 0, v101
	v_max_f32_e32 v101, v102, v102
	v_max_f32_e32 v102, v103, v103
	v_max_f32_e32 v105, 0, v102
	v_pk_mul_f32 v[102:103], v[104:105], v[104:105]
	v_max_f32_e32 v104, 0, v97
	v_max_f32_e32 v97, v98, v98
	v_max_f32_e32 v98, v99, v99
	v_max_f32_e32 v105, 0, v98
	v_max_f32_e32 v100, 0, v100
	v_max_f32_e32 v101, 0, v101
	v_max_f32_e32 v96, 0, v96
	v_max_f32_e32 v97, 0, v97
	v_pk_mul_f32 v[98:99], v[104:105], v[104:105]
	v_pk_mul_f32 v[100:101], v[100:101], v[100:101]
	v_pk_mul_f32 v[96:97], v[96:97], v[96:97]
	s_mov_b64 s[46:47], 0x20000
	v_lshl_add_u64 v[112:113], v[144:145], 0, s[46:47]
	v_cvt_pk_bf16_f32 v99, v97, v99
	v_cvt_pk_bf16_f32 v98, v96, v98
	v_cvt_pk_bf16_f32 v97, v101, v103
	v_cvt_pk_bf16_f32 v96, v100, v102
	global_store_dwordx4 v[112:113], v[96:99], off offset:256
	s_nop 1
	v_max_f32_e32 v98, 0, v93
	v_max_f32_e32 v93, v94, v94
	v_max_f32_e32 v94, v95, v95
	v_max_f32_e32 v99, 0, v94
	v_pk_mul_f32 v[94:95], v[98:99], v[98:99]
	v_max_f32_e32 v98, 0, v89
	v_max_f32_e32 v89, v90, v90
	v_max_f32_e32 v90, v91, v91
	v_max_f32_e32 v99, 0, v90
	v_max_f32_e32 v92, 0, v92
	v_max_f32_e32 v93, 0, v93
	v_max_f32_e32 v88, 0, v88
	v_max_f32_e32 v89, 0, v89
	v_pk_mul_f32 v[90:91], v[98:99], v[98:99]
	v_pk_mul_f32 v[92:93], v[92:93], v[92:93]
	v_pk_mul_f32 v[88:89], v[88:89], v[88:89]
	s_mov_b32 s37, 0x40000
	v_cvt_pk_bf16_f32 v90, v88, v90
	v_cvt_pk_bf16_f32 v88, v92, v94
	v_add_co_u32_e32 v92, vcc, s37, v144
	v_cvt_pk_bf16_f32 v91, v89, v91
	v_cvt_pk_bf16_f32 v89, v93, v95
	v_addc_co_u32_e32 v93, vcc, 0, v145, vcc
	global_store_dwordx4 v[92:93], v[88:91], off
	s_nop 1
	v_max_f32_e32 v88, 0, v85
	v_max_f32_e32 v85, v86, v86
	v_max_f32_e32 v86, v87, v87
	v_max_f32_e32 v89, 0, v86
	v_pk_mul_f32 v[86:87], v[88:89], v[88:89]
	v_max_f32_e32 v88, 0, v81
	v_max_f32_e32 v81, v82, v82
	v_max_f32_e32 v82, v83, v83
	v_max_f32_e32 v89, 0, v82
	v_max_f32_e32 v84, 0, v84
	v_max_f32_e32 v85, 0, v85
	v_max_f32_e32 v80, 0, v80
	v_max_f32_e32 v81, 0, v81
	v_pk_mul_f32 v[82:83], v[88:89], v[88:89]
	v_pk_mul_f32 v[84:85], v[84:85], v[84:85]
	v_pk_mul_f32 v[80:81], v[80:81], v[80:81]
	s_mov_b64 s[46:47], 0x40000
	v_lshl_add_u64 v[96:97], v[144:145], 0, s[46:47]
	v_cvt_pk_bf16_f32 v83, v81, v83
	v_cvt_pk_bf16_f32 v82, v80, v82
	v_cvt_pk_bf16_f32 v81, v85, v87
	v_cvt_pk_bf16_f32 v80, v84, v86
	global_store_dwordx4 v[96:97], v[80:83], off offset:256
	s_nop 1
	v_max_f32_e32 v82, 0, v77
	v_max_f32_e32 v77, v78, v78
	v_max_f32_e32 v78, v79, v79
	v_max_f32_e32 v83, 0, v78
	v_pk_mul_f32 v[78:79], v[82:83], v[82:83]
	v_max_f32_e32 v82, 0, v73
	v_max_f32_e32 v73, v74, v74
	v_max_f32_e32 v74, v75, v75
	v_max_f32_e32 v83, 0, v74
	v_max_f32_e32 v76, 0, v76
	v_max_f32_e32 v77, 0, v77
	v_max_f32_e32 v72, 0, v72
	v_max_f32_e32 v73, 0, v73
	v_pk_mul_f32 v[74:75], v[82:83], v[82:83]
; __device__ __forceinline__ unsigned pk2_(float lo, float hi) { return f2bf_(lo) | (f2bf_(hi) << 16); }
; template <int ACT> __device__ __forceinline__ float act_f(float v) {
;     if (ACT == 2) { const float t = fmaxf(v, 0.f); return t * t; }
;     __device__ __forceinline__ void operator()(const f32x4 (&acc)[2][2][4][2], const Unit& u, int wr, int wc, int fr, int fq) const {
;     ...
;         const int row0 = u.pm * BM + wr * 64 + fr; const int col0 = u.pn * BM + wc * 32 + 8 * fq;
; #pragma unroll
;         for (int ai = 0; ai < 2; ++ai)
; #pragma unroll
;             for (int m = 0; m < 4; ++m) { bf16_t* rowp = O + (size_t)(row0 + ai * HALF + m * 16) * ldc + col0;
; #pragma unroll
;                 for (int bj = 0; bj < 2; ++bj) { f32x4 v0 = acc[ai][bj][m][0], v1 = acc[ai][bj][m][1];
;                     if (bias) { v0 += *(const f32x4*)(bias + col0 + bj * HALF); v1 += *(const f32x4*)(bias + col0 + bj * HALF + 4); }
;                     u32x4 w; w.x = pk2_(act_f<ACT>(v0[0]), act_f<ACT>(v0[1])); w.y = pk2_(act_f<ACT>(v0[2]), act_f<ACT>(v0[3]));
;                     w.z = pk2_(act_f<ACT>(v1[0]), act_f<ACT>(v1[1])); w.w = pk2_(act_f<ACT>(v1[2]), act_f<ACT>(v1[3]));
;                     *(u32x4*)(rowp + bj * HALF) = w; } }
	v_pk_mul_f32 v[76:77], v[76:77], v[76:77]
	v_pk_mul_f32 v[72:73], v[72:73], v[72:73]
	s_mov_b32 s37, 0x60000
	v_cvt_pk_bf16_f32 v74, v72, v74
	v_cvt_pk_bf16_f32 v72, v76, v78
	v_add_co_u32_e32 v76, vcc, s37, v144
	v_cvt_pk_bf16_f32 v75, v73, v75
	v_cvt_pk_bf16_f32 v73, v77, v79
	v_addc_co_u32_e32 v77, vcc, 0, v145, vcc
	global_store_dwordx4 v[76:77], v[72:75], off
	s_nop 1
	v_max_f32_e32 v72, 0, v69
	v_max_f32_e32 v69, v70, v70
	v_max_f32_e32 v70, v71, v71
	v_max_f32_e32 v73, 0, v70
	v_pk_mul_f32 v[70:71], v[72:73], v[72:73]
	v_max_f32_e32 v72, 0, v65
	v_max_f32_e32 v65, v66, v66
	v_max_f32_e32 v66, v67, v67
	v_max_f32_e32 v73, 0, v66
	v_max_f32_e32 v68, 0, v68
	v_max_f32_e32 v69, 0, v69
	v_max_f32_e32 v64, 0, v64
	v_max_f32_e32 v65, 0, v65
	v_pk_mul_f32 v[66:67], v[72:73], v[72:73]
	v_pk_mul_f32 v[68:69], v[68:69], v[68:69]
	v_pk_mul_f32 v[64:65], v[64:65], v[64:65]
	s_mov_b64 s[46:47], 0x60000
	v_lshl_add_u64 v[80:81], v[144:145], 0, s[46:47]
	v_cvt_pk_bf16_f32 v67, v65, v67
	v_cvt_pk_bf16_f32 v66, v64, v66
	v_cvt_pk_bf16_f32 v65, v69, v71
	v_cvt_pk_bf16_f32 v64, v68, v70
	global_store_dwordx4 v[80:81], v[64:67], off offset:256
	s_nop 1
	v_max_f32_e32 v66, 0, v61
	v_max_f32_e32 v61, v62, v62
	v_max_f32_e32 v62, v63, v63
	v_max_f32_e32 v67, 0, v62
	v_pk_mul_f32 v[62:63], v[66:67], v[66:67]
	v_max_f32_e32 v66, 0, v57
	v_max_f32_e32 v57, v58, v58
	v_max_f32_e32 v58, v59, v59
	v_max_f32_e32 v67, 0, v58
	v_max_f32_e32 v60, 0, v60
	v_max_f32_e32 v61, 0, v61
	v_max_f32_e32 v56, 0, v56
	v_max_f32_e32 v57, 0, v57
	v_pk_mul_f32 v[58:59], v[66:67], v[66:67]
	v_pk_mul_f32 v[60:61], v[60:61], v[60:61]
	v_pk_mul_f32 v[56:57], v[56:57], v[56:57]
	v_cvt_pk_bf16_f32 v58, v56, v58
	v_cvt_pk_bf16_f32 v56, v60, v62
	v_add_co_u32_e32 v60, vcc, s67, v144
	v_cvt_pk_bf16_f32 v59, v57, v59
	v_cvt_pk_bf16_f32 v57, v61, v63
	v_addc_co_u32_e32 v61, vcc, 0, v145, vcc
	global_store_dwordx4 v[60:61], v[56:59], off
	s_nop 1
	v_max_f32_e32 v56, 0, v53
	v_max_f32_e32 v53, v54, v54
	v_max_f32_e32 v54, v55, v55
	v_max_f32_e32 v57, 0, v54
	v_pk_mul_f32 v[54:55], v[56:57], v[56:57]
	v_max_f32_e32 v56, 0, v49
	v_max_f32_e32 v49, v50, v50
	v_max_f32_e32 v50, v51, v51
	v_max_f32_e32 v57, 0, v50
	v_max_f32_e32 v52, 0, v52
	v_max_f32_e32 v53, 0, v53
	v_max_f32_e32 v48, 0, v48
	v_max_f32_e32 v49, 0, v49
	v_pk_mul_f32 v[50:51], v[56:57], v[56:57]
	v_pk_mul_f32 v[52:53], v[52:53], v[52:53]
	v_pk_mul_f32 v[48:49], v[48:49], v[48:49]
	s_mov_b64 s[46:47], 0x100000
	v_lshl_add_u64 v[64:65], v[144:145], 0, s[46:47]
	v_cvt_pk_bf16_f32 v51, v49, v51
	v_cvt_pk_bf16_f32 v50, v48, v50
	v_cvt_pk_bf16_f32 v49, v53, v55
	v_cvt_pk_bf16_f32 v48, v52, v54
	global_store_dwordx4 v[64:65], v[48:51], off offset:256
	s_nop 1
	v_max_f32_e32 v50, 0, v45
	v_max_f32_e32 v45, v46, v46
	v_max_f32_e32 v46, v47, v47
	v_max_f32_e32 v51, 0, v46
	v_pk_mul_f32 v[46:47], v[50:51], v[50:51]
	v_max_f32_e32 v50, 0, v41
	v_max_f32_e32 v41, v42, v42
	v_max_f32_e32 v42, v43, v43
	v_max_f32_e32 v51, 0, v42
	v_max_f32_e32 v44, 0, v44
	v_max_f32_e32 v45, 0, v45
	v_max_f32_e32 v40, 0, v40
	v_max_f32_e32 v41, 0, v41
	v_pk_mul_f32 v[42:43], v[50:51], v[50:51]
	v_pk_mul_f32 v[44:45], v[44:45], v[44:45]
	v_pk_mul_f32 v[40:41], v[40:41], v[40:41]
	v_cvt_pk_bf16_f32 v42, v40, v42
	v_cvt_pk_bf16_f32 v40, v44, v46
	v_add_co_u32_e32 v44, vcc, s72, v144
	v_cvt_pk_bf16_f32 v43, v41, v43
	v_cvt_pk_bf16_f32 v41, v45, v47
	v_addc_co_u32_e32 v45, vcc, 0, v145, vcc
	global_store_dwordx4 v[44:45], v[40:43], off
	s_nop 1
	v_max_f32_e32 v40, 0, v37
	v_max_f32_e32 v37, v38, v38
	v_max_f32_e32 v38, v39, v39
	v_max_f32_e32 v41, 0, v38
	v_pk_mul_f32 v[38:39], v[40:41], v[40:41]
	v_max_f32_e32 v40, 0, v33
	v_max_f32_e32 v33, v34, v34
; __device__ __forceinline__ unsigned pk2_(float lo, float hi) { return f2bf_(lo) | (f2bf_(hi) << 16); }
; template <int ACT> __device__ __forceinline__ float act_f(float v) {
;     if (ACT == 2) { const float t = fmaxf(v, 0.f); return t * t; }
;     __device__ __forceinline__ void operator()(const f32x4 (&acc)[2][2][4][2], const Unit& u, int wr, int wc, int fr, int fq) const {
;     ...
;         const int row0 = u.pm * BM + wr * 64 + fr; const int col0 = u.pn * BM + wc * 32 + 8 * fq;
; #pragma unroll
;         for (int ai = 0; ai < 2; ++ai)
; #pragma unroll
;             for (int m = 0; m < 4; ++m) { bf16_t* rowp = O + (size_t)(row0 + ai * HALF + m * 16) * ldc + col0;
; #pragma unroll
;                 for (int bj = 0; bj < 2; ++bj) { f32x4 v0 = acc[ai][bj][m][0], v1 = acc[ai][bj][m][1];
;                     if (bias) { v0 += *(const f32x4*)(bias + col0 + bj * HALF); v1 += *(const f32x4*)(bias + col0 + bj * HALF + 4); }
;                     u32x4 w; w.x = pk2_(act_f<ACT>(v0[0]), act_f<ACT>(v0[1])); w.y = pk2_(act_f<ACT>(v0[2]), act_f<ACT>(v0[3]));
;                     w.z = pk2_(act_f<ACT>(v1[0]), act_f<ACT>(v1[1])); w.w = pk2_(act_f<ACT>(v1[2]), act_f<ACT>(v1[3]));
;                     *(u32x4*)(rowp + bj * HALF) = w; } }
	v_max_f32_e32 v34, v35, v35
	v_max_f32_e32 v41, 0, v34
	v_max_f32_e32 v36, 0, v36
	v_max_f32_e32 v37, 0, v37
	v_max_f32_e32 v32, 0, v32
	v_max_f32_e32 v33, 0, v33
	v_pk_mul_f32 v[34:35], v[40:41], v[40:41]
	v_pk_mul_f32 v[36:37], v[36:37], v[36:37]
	v_pk_mul_f32 v[32:33], v[32:33], v[32:33]
	v_lshl_add_u64 v[48:49], v[144:145], 0, s[28:29]
	v_cvt_pk_bf16_f32 v35, v33, v35
	v_cvt_pk_bf16_f32 v34, v32, v34
	v_cvt_pk_bf16_f32 v33, v37, v39
	v_cvt_pk_bf16_f32 v32, v36, v38
	global_store_dwordx4 v[48:49], v[32:35], off offset:256
	s_nop 1
	v_max_f32_e32 v34, 0, v29
	v_max_f32_e32 v29, v30, v30
	v_max_f32_e32 v30, v31, v31
	v_max_f32_e32 v35, 0, v30
	v_pk_mul_f32 v[30:31], v[34:35], v[34:35]
	v_max_f32_e32 v34, 0, v25
	v_max_f32_e32 v25, v26, v26
	v_max_f32_e32 v26, v27, v27
	v_max_f32_e32 v35, 0, v26
	v_max_f32_e32 v28, 0, v28
	v_max_f32_e32 v29, 0, v29
	v_max_f32_e32 v24, 0, v24
	v_max_f32_e32 v25, 0, v25
	v_pk_mul_f32 v[26:27], v[34:35], v[34:35]
	v_pk_mul_f32 v[28:29], v[28:29], v[28:29]
	v_pk_mul_f32 v[24:25], v[24:25], v[24:25]
	v_cvt_pk_bf16_f32 v26, v24, v26
	v_cvt_pk_bf16_f32 v24, v28, v30
	v_add_co_u32_e32 v28, vcc, s73, v144
	v_cvt_pk_bf16_f32 v27, v25, v27
	v_cvt_pk_bf16_f32 v25, v29, v31
	v_addc_co_u32_e32 v29, vcc, 0, v145, vcc
	global_store_dwordx4 v[28:29], v[24:27], off
	s_nop 1
	v_max_f32_e32 v24, 0, v21
	v_max_f32_e32 v21, v22, v22
	v_max_f32_e32 v22, v23, v23
	v_max_f32_e32 v25, 0, v22
	v_pk_mul_f32 v[22:23], v[24:25], v[24:25]
	v_max_f32_e32 v24, 0, v17
	v_max_f32_e32 v17, v18, v18
	v_max_f32_e32 v18, v19, v19
	v_max_f32_e32 v25, 0, v18
	v_max_f32_e32 v20, 0, v20
	v_max_f32_e32 v21, 0, v21
	v_max_f32_e32 v16, 0, v16
	v_max_f32_e32 v17, 0, v17
	v_pk_mul_f32 v[18:19], v[24:25], v[24:25]
	v_pk_mul_f32 v[20:21], v[20:21], v[20:21]
	v_pk_mul_f32 v[16:17], v[16:17], v[16:17]
	v_lshl_add_u64 v[32:33], v[144:145], 0, s[30:31]
	v_cvt_pk_bf16_f32 v19, v17, v19
	v_cvt_pk_bf16_f32 v18, v16, v18
	v_cvt_pk_bf16_f32 v17, v21, v23
	v_cvt_pk_bf16_f32 v16, v20, v22
	global_store_dwordx4 v[32:33], v[16:19], off offset:256
	s_nop 1
	v_max_f32_e32 v18, 0, v13
	v_max_f32_e32 v13, v14, v14
	v_max_f32_e32 v14, v15, v15
	v_max_f32_e32 v19, 0, v14
	v_pk_mul_f32 v[14:15], v[18:19], v[18:19]
	v_max_f32_e32 v18, 0, v9
	v_max_f32_e32 v9, v10, v10
	v_max_f32_e32 v10, v11, v11
	v_max_f32_e32 v19, 0, v10
	v_max_f32_e32 v12, 0, v12
	v_max_f32_e32 v13, 0, v13
	v_max_f32_e32 v8, 0, v8
	v_max_f32_e32 v9, 0, v9
	v_pk_mul_f32 v[10:11], v[18:19], v[18:19]
	v_pk_mul_f32 v[12:13], v[12:13], v[12:13]
	v_pk_mul_f32 v[8:9], v[8:9], v[8:9]
	v_cvt_pk_bf16_f32 v10, v8, v10
	v_cvt_pk_bf16_f32 v8, v12, v14
	v_add_co_u32_e32 v12, vcc, s74, v144
	v_cvt_pk_bf16_f32 v11, v9, v11
	v_cvt_pk_bf16_f32 v9, v13, v15
	v_addc_co_u32_e32 v13, vcc, 0, v145, vcc
	global_store_dwordx4 v[12:13], v[8:11], off
	s_nop 1
	v_max_f32_e32 v8, 0, v5
	v_max_f32_e32 v5, v6, v6
	v_max_f32_e32 v6, v7, v7
	v_max_f32_e32 v9, 0, v6
	v_pk_mul_f32 v[6:7], v[8:9], v[8:9]
	v_max_f32_e32 v8, 0, v1
	v_max_f32_e32 v1, v2, v2
	v_max_f32_e32 v2, v3, v3
	v_max_f32_e32 v9, 0, v2
	v_max_f32_e32 v4, 0, v4
	v_max_f32_e32 v5, 0, v5
	v_max_f32_e32 v0, 0, v0
	v_max_f32_e32 v1, 0, v1
	v_pk_mul_f32 v[2:3], v[8:9], v[8:9]
	v_pk_mul_f32 v[4:5], v[4:5], v[4:5]
	v_pk_mul_f32 v[0:1], v[0:1], v[0:1]
	v_lshl_add_u64 v[16:17], v[144:145], 0, s[34:35]
	v_cvt_pk_bf16_f32 v3, v1, v3
	v_cvt_pk_bf16_f32 v2, v0, v2
	v_cvt_pk_bf16_f32 v1, v5, v7
	v_cvt_pk_bf16_f32 v0, v4, v6
	s_andn2_b64 vcc, exec, s[0:1]
	s_mov_b64 s[0:1], -1
	global_store_dwordx4 v[16:17], v[0:3], off offset:256
	s_cbranch_vccnz .LBB0_2071
	s_andn2_b64 vcc, exec, s[10:11]
	s_cbranch_vccnz .LBB0_2070
	s_barrier
	s_branch .LBB0_2070

; __device__ __forceinline__ unsigned pk2_(float lo, float hi) { return f2bf_(lo) | (f2bf_(hi) << 16); }
;     __device__ __forceinline__ void operator()(const f32x4 (&acc)[2][2][4][2], const Unit& u, int wr, int wc, int fr, int fq) const {
;     ...
;         const int row0 = u.pm * BM + wr * 64 + fr; const int col0 = u.pn * BM + wc * 32 + 8 * fq;
; #pragma unroll
;         for (int ai = 0; ai < 2; ++ai)
; #pragma unroll
;             for (int m = 0; m < 4; ++m) { bf16_t* rowp = O + (size_t)(row0 + ai * HALF + m * 16) * ldc + col0;
; #pragma unroll
;                 for (int bj = 0; bj < 2; ++bj) { f32x4 v0 = acc[ai][bj][m][0], v1 = acc[ai][bj][m][1];
;                     if (bias) { v0 += *(const f32x4*)(bias + col0 + bj * HALF); v1 += *(const f32x4*)(bias + col0 + bj * HALF + 4); }
;                     u32x4 w; w.x = pk2_(act_f<ACT>(v0[0]), act_f<ACT>(v0[1])); w.y = pk2_(act_f<ACT>(v0[2]), act_f<ACT>(v0[3]));
;                     w.z = pk2_(act_f<ACT>(v1[0]), act_f<ACT>(v1[1])); w.w = pk2_(act_f<ACT>(v1[2]), act_f<ACT>(v1[3]));
;                     *(u32x4*)(rowp + bj * HALF) = w; } }
.LBB0_2306:
	v_cvt_pk_bf16_f32 v124, v124, v125
	v_cvt_pk_bf16_f32 v125, v126, v127
	v_cvt_pk_bf16_f32 v126, v120, v121
	v_cvt_pk_bf16_f32 v127, v122, v123
	v_cvt_pk_bf16_f32 v116, v116, v117
	v_cvt_pk_bf16_f32 v117, v118, v119
	s_lshl_b32 s13, s55, 8
	v_mov_b32_e32 v144, v149
	v_mov_b32_e32 v145, v148
	s_lshl_b32 s12, s28, 8
	s_or_b32 s13, s13, s41
	v_cvt_pk_bf16_f32 v118, v108, v109
	s_add_i32 s12, s12, s40
	v_lshl_add_u32 v146, v145, 3, s13
	v_add_u32_e32 v156, s12, v144
	v_ashrrev_i32_e32 v147, 31, v146
	v_mov_b64_e32 v[144:145], s[16:17]
	v_mad_i64_i32 v[154:155], s[12:13], v156, s46, v[144:145]
	v_lshlrev_b64 v[146:147], 1, v[146:147]
	v_cvt_pk_bf16_f32 v119, v110, v111
	v_add_u32_e32 v108, 16, v156
	v_lshl_add_u64 v[154:155], v[154:155], 0, v[146:147]
	v_mad_i64_i32 v[108:109], s[12:13], v108, s46, v[144:145]
	global_store_dwordx4 v[154:155], v[116:119], off offset:256
	s_nop 1
	v_lshl_add_u64 v[116:117], v[108:109], 0, v[146:147]
	v_cvt_pk_bf16_f32 v108, v112, v113
	v_cvt_pk_bf16_f32 v109, v114, v115
	v_cvt_pk_bf16_f32 v110, v104, v105
	v_cvt_pk_bf16_f32 v111, v106, v107
	v_cvt_pk_bf16_f32 v100, v100, v101
	v_cvt_pk_bf16_f32 v101, v102, v103
	v_cvt_pk_bf16_f32 v102, v92, v93
	v_cvt_pk_bf16_f32 v103, v94, v95
	v_add_u32_e32 v92, 32, v156
	v_mad_i64_i32 v[92:93], s[12:13], v92, s46, v[144:145]
	global_store_dwordx4 v[116:117], v[100:103], off offset:256
	s_nop 1
	v_lshl_add_u64 v[100:101], v[92:93], 0, v[146:147]
	v_cvt_pk_bf16_f32 v92, v96, v97
	v_cvt_pk_bf16_f32 v93, v98, v99
	v_cvt_pk_bf16_f32 v94, v88, v89
	v_cvt_pk_bf16_f32 v95, v90, v91
	v_cvt_pk_bf16_f32 v84, v84, v85
	v_cvt_pk_bf16_f32 v85, v86, v87
	v_cvt_pk_bf16_f32 v86, v76, v77
	v_cvt_pk_bf16_f32 v87, v78, v79
	v_add_u32_e32 v76, 48, v156
	v_mad_i64_i32 v[76:77], s[12:13], v76, s46, v[144:145]
	global_store_dwordx4 v[100:101], v[84:87], off offset:256
	s_nop 1
	v_lshl_add_u64 v[84:85], v[76:77], 0, v[146:147]
	v_cvt_pk_bf16_f32 v76, v80, v81
	v_cvt_pk_bf16_f32 v77, v82, v83
	v_cvt_pk_bf16_f32 v78, v72, v73
	v_cvt_pk_bf16_f32 v79, v74, v75
	v_cvt_pk_bf16_f32 v68, v68, v69
	v_cvt_pk_bf16_f32 v69, v70, v71
	v_cvt_pk_bf16_f32 v70, v64, v65
	v_cvt_pk_bf16_f32 v60, v60, v61
	v_cvt_pk_bf16_f32 v61, v62, v63
	v_cvt_pk_bf16_f32 v62, v56, v57
	v_cvt_pk_bf16_f32 v63, v58, v59
	v_cvt_pk_bf16_f32 v52, v52, v53
	v_cvt_pk_bf16_f32 v53, v54, v55
	v_cvt_pk_bf16_f32 v54, v44, v45
	v_cvt_pk_bf16_f32 v71, v66, v67
	v_add_u32_e32 v64, 0x80, v156
	v_mad_i64_i32 v[64:65], s[12:13], v64, s46, v[144:145]
	v_cvt_pk_bf16_f32 v55, v46, v47
	v_add_u32_e32 v44, 0x90, v156
	v_lshl_add_u64 v[64:65], v[64:65], 0, v[146:147]
	v_mad_i64_i32 v[44:45], s[12:13], v44, s46, v[144:145]
	global_store_dwordx4 v[64:65], v[52:55], off offset:256
	s_nop 1
	v_lshl_add_u64 v[52:53], v[44:45], 0, v[146:147]
	v_cvt_pk_bf16_f32 v44, v48, v49
	v_cvt_pk_bf16_f32 v45, v50, v51
	v_cvt_pk_bf16_f32 v46, v40, v41
	v_cvt_pk_bf16_f32 v47, v42, v43
	v_cvt_pk_bf16_f32 v36, v36, v37
	v_cvt_pk_bf16_f32 v37, v38, v39
	v_cvt_pk_bf16_f32 v38, v28, v29
	v_cvt_pk_bf16_f32 v39, v30, v31
	v_add_u32_e32 v28, 0xa0, v156
	v_mad_i64_i32 v[28:29], s[12:13], v28, s46, v[144:145]
	global_store_dwordx4 v[52:53], v[36:39], off offset:256
	s_nop 1
	v_lshl_add_u64 v[36:37], v[28:29], 0, v[146:147]
	v_cvt_pk_bf16_f32 v28, v32, v33
	v_cvt_pk_bf16_f32 v29, v34, v35
	v_cvt_pk_bf16_f32 v30, v24, v25
	v_cvt_pk_bf16_f32 v31, v26, v27
	v_cvt_pk_bf16_f32 v20, v20, v21
	v_cvt_pk_bf16_f32 v21, v22, v23
	v_cvt_pk_bf16_f32 v22, v12, v13
	v_cvt_pk_bf16_f32 v23, v14, v15
	v_add_u32_e32 v12, 0xb0, v156
	v_mad_i64_i32 v[12:13], s[12:13], v12, s46, v[144:145]
	global_store_dwordx4 v[36:37], v[20:23], off offset:256
	s_nop 1
	v_lshl_add_u64 v[20:21], v[12:13], 0, v[146:147]
	v_cvt_pk_bf16_f32 v12, v16, v17
	v_cvt_pk_bf16_f32 v13, v18, v19
	v_cvt_pk_bf16_f32 v14, v8, v9
	v_cvt_pk_bf16_f32 v15, v10, v11
	v_cvt_pk_bf16_f32 v4, v4, v5
	v_cvt_pk_bf16_f32 v5, v6, v7
	v_cvt_pk_bf16_f32 v6, v0, v1
	v_cvt_pk_bf16_f32 v7, v2, v3
	s_andn2_b64 vcc, exec, s[0:1]
	s_mov_b64 s[0:1], -1
	global_store_dwordx4 v[154:155], v[124:127], off
	global_store_dwordx4 v[116:117], v[108:111], off
	global_store_dwordx4 v[100:101], v[92:95], off
	global_store_dwordx4 v[84:85], v[76:79], off
	global_store_dwordx4 v[84:85], v[68:71], off offset:256
	global_store_dwordx4 v[64:65], v[60:63], off
	global_store_dwordx4 v[52:53], v[44:47], off
	global_store_dwordx4 v[36:37], v[28:31], off
	global_store_dwordx4 v[20:21], v[12:15], off
	global_store_dwordx4 v[20:21], v[4:7], off offset:256
	s_cbranch_vccnz .LBB0_2299
	s_andn2_b64 vcc, exec, s[8:9]
	s_cbranch_vccnz .LBB0_2298
	s_barrier
	s_branch .LBB0_2298

; __device__ __forceinline__ unsigned pk2_(float lo, float hi) { return f2bf_(lo) | (f2bf_(hi) << 16); }
;     __device__ __forceinline__ void operator()(const f32x4 (&acc)[2][2][4][2], const Unit& u, int wr, int wc, int fr, int fq) const {
;     ...
;         const int row0 = u.pm * BM + wr * 64 + fr; const int col0 = u.pn * BM + wc * 32 + 8 * fq;
; #pragma unroll
;         for (int ai = 0; ai < 2; ++ai)
; #pragma unroll
;             for (int m = 0; m < 4; ++m) { bf16_t* rowp = O + (size_t)(row0 + ai * HALF + m * 16) * ldc + col0;
; #pragma unroll
;                 for (int bj = 0; bj < 2; ++bj) { f32x4 v0 = acc[ai][bj][m][0], v1 = acc[ai][bj][m][1];
;                     if (bias) { v0 += *(const f32x4*)(bias + col0 + bj * HALF); v1 += *(const f32x4*)(bias + col0 + bj * HALF + 4); }
;                     u32x4 w; w.x = pk2_(act_f<ACT>(v0[0]), act_f<ACT>(v0[1])); w.y = pk2_(act_f<ACT>(v0[2]), act_f<ACT>(v0[3]));
;                     w.z = pk2_(act_f<ACT>(v1[0]), act_f<ACT>(v1[1])); w.w = pk2_(act_f<ACT>(v1[2]), act_f<ACT>(v1[3]));
;                     *(u32x4*)(rowp + bj * HALF) = w; } }
.LBB0_2330:
	s_lshl_b32 s12, s40, 8
	v_mov_b32_e32 v145, v147
	v_mov_b32_e32 v144, v146
	s_lshl_b32 s13, s75, 8
	s_add_i32 s12, s12, s62
	s_or_b32 s13, s13, s63
	v_add_u32_e32 v152, s12, v145
	v_lshl_add_u32 v144, v144, 3, s13
	v_ashrrev_i32_e32 v153, 31, v152
	v_readlane_b32 s12, v254, 20
	v_lshlrev_b64 v[152:153], 16, v[152:153]
	v_readlane_b32 s13, v254, 21
	v_ashrrev_i32_e32 v145, 31, v144
	s_nop 0
	v_lshl_add_u64 v[152:153], s[12:13], 0, v[152:153]
	v_lshl_add_u64 v[144:145], v[144:145], 1, v[152:153]
	v_cvt_pk_bf16_f32 v124, v124, v125
	v_cvt_pk_bf16_f32 v125, v126, v127
	v_cvt_pk_bf16_f32 v126, v120, v121
	v_cvt_pk_bf16_f32 v127, v122, v123
	v_cvt_pk_bf16_f32 v116, v116, v117
	v_cvt_pk_bf16_f32 v117, v118, v119
	v_cvt_pk_bf16_f32 v118, v108, v109
	v_cvt_pk_bf16_f32 v119, v110, v111
	v_cvt_pk_bf16_f32 v108, v112, v113
	v_cvt_pk_bf16_f32 v109, v114, v115
	v_cvt_pk_bf16_f32 v110, v104, v105
	s_mov_b64 s[12:13], 0x100000
	global_store_dwordx4 v[144:145], v[116:119], off offset:256
	s_nop 1
	v_lshl_add_u64 v[116:117], v[144:145], 0, s[12:13]
	s_mov_b32 s12, 0x100000
	v_cvt_pk_bf16_f32 v111, v106, v107
	v_add_co_u32_e32 v104, vcc, s12, v144
	s_mov_b64 s[12:13], 0x200000
	s_nop 0
	v_addc_co_u32_e32 v105, vcc, 0, v145, vcc
	global_store_dwordx4 v[104:105], v[108:111], off
	v_cvt_pk_bf16_f32 v100, v100, v101
	v_cvt_pk_bf16_f32 v101, v102, v103
	v_cvt_pk_bf16_f32 v102, v92, v93
	v_cvt_pk_bf16_f32 v103, v94, v95
	v_cvt_pk_bf16_f32 v92, v96, v97
	v_cvt_pk_bf16_f32 v93, v98, v99
	v_cvt_pk_bf16_f32 v94, v88, v89
	global_store_dwordx4 v[116:117], v[100:103], off offset:256
	s_nop 1
	v_lshl_add_u64 v[100:101], v[144:145], 0, s[12:13]
	s_mov_b32 s12, 0x200000
	v_cvt_pk_bf16_f32 v95, v90, v91
	v_add_co_u32_e32 v88, vcc, s12, v144
	global_store_dwordx4 v[144:145], v[124:127], off
	s_nop 0
	v_addc_co_u32_e32 v89, vcc, 0, v145, vcc
	global_store_dwordx4 v[88:89], v[92:95], off
	v_cvt_pk_bf16_f32 v84, v84, v85
	v_cvt_pk_bf16_f32 v85, v86, v87
	v_cvt_pk_bf16_f32 v86, v76, v77
	v_cvt_pk_bf16_f32 v87, v78, v79
	v_cvt_pk_bf16_f32 v76, v80, v81
	v_cvt_pk_bf16_f32 v77, v82, v83
	v_cvt_pk_bf16_f32 v78, v72, v73
	v_cvt_pk_bf16_f32 v79, v74, v75
	v_add_co_u32_e32 v72, vcc, s70, v144
	global_store_dwordx4 v[100:101], v[84:87], off offset:256
	s_nop 0
	v_addc_co_u32_e32 v73, vcc, 0, v145, vcc
	global_store_dwordx4 v[72:73], v[76:79], off
	v_cvt_pk_bf16_f32 v68, v68, v69
	v_cvt_pk_bf16_f32 v69, v70, v71
	v_cvt_pk_bf16_f32 v70, v64, v65
	v_cvt_pk_bf16_f32 v60, v60, v61
	v_cvt_pk_bf16_f32 v61, v62, v63
	v_cvt_pk_bf16_f32 v62, v56, v57
	v_cvt_pk_bf16_f32 v63, v58, v59
	v_add_co_u32_e32 v56, vcc, s71, v144
	s_nop 0
	v_addc_co_u32_e32 v57, vcc, 0, v145, vcc
	global_store_dwordx4 v[56:57], v[60:63], off
	v_cvt_pk_bf16_f32 v52, v52, v53
	v_cvt_pk_bf16_f32 v53, v54, v55
	v_cvt_pk_bf16_f32 v54, v44, v45
	v_cvt_pk_bf16_f32 v55, v46, v47
	v_cvt_pk_bf16_f32 v44, v48, v49
	v_cvt_pk_bf16_f32 v45, v50, v51
	v_cvt_pk_bf16_f32 v46, v40, v41
	v_cvt_pk_bf16_f32 v47, v42, v43
	v_add_co_u32_e32 v40, vcc, s72, v144
	s_nop 0
	v_addc_co_u32_e32 v41, vcc, 0, v145, vcc
	global_store_dwordx4 v[40:41], v[44:47], off
	v_cvt_pk_bf16_f32 v36, v36, v37
	v_cvt_pk_bf16_f32 v37, v38, v39
	v_cvt_pk_bf16_f32 v38, v28, v29
	v_cvt_pk_bf16_f32 v39, v30, v31
	v_cvt_pk_bf16_f32 v28, v32, v33
	v_cvt_pk_bf16_f32 v29, v34, v35
	v_cvt_pk_bf16_f32 v30, v24, v25
	v_cvt_pk_bf16_f32 v31, v26, v27
	v_add_co_u32_e32 v24, vcc, s73, v144
	s_nop 0
	v_addc_co_u32_e32 v25, vcc, 0, v145, vcc
	global_store_dwordx4 v[24:25], v[28:31], off
	v_cvt_pk_bf16_f32 v20, v20, v21
	v_cvt_pk_bf16_f32 v21, v22, v23
	v_cvt_pk_bf16_f32 v22, v12, v13
	v_cvt_pk_bf16_f32 v23, v14, v15
	v_cvt_pk_bf16_f32 v12, v16, v17
	v_cvt_pk_bf16_f32 v13, v18, v19
	v_cvt_pk_bf16_f32 v14, v8, v9
	v_cvt_pk_bf16_f32 v15, v10, v11
	v_add_co_u32_e32 v8, vcc, s74, v144
	v_cvt_pk_bf16_f32 v71, v66, v67
	s_nop 0
	v_addc_co_u32_e32 v9, vcc, 0, v145, vcc
	global_store_dwordx4 v[8:9], v[12:15], off
	v_cvt_pk_bf16_f32 v4, v4, v5
	v_cvt_pk_bf16_f32 v5, v6, v7
	v_lshl_add_u64 v[64:65], v[144:145], 0, s[22:23]
	v_cvt_pk_bf16_f32 v6, v0, v1
	global_store_dwordx4 v[64:65], v[52:55], off offset:256
	s_nop 1
	v_lshl_add_u64 v[52:53], v[144:145], 0, s[24:25]
	global_store_dwordx4 v[52:53], v[36:39], off offset:256
	s_nop 1
	v_lshl_add_u64 v[36:37], v[144:145], 0, s[26:27]
	v_lshl_add_u64 v[84:85], v[144:145], 0, s[20:21]
	global_store_dwordx4 v[36:37], v[20:23], off offset:256
	v_cvt_pk_bf16_f32 v7, v2, v3
	s_andn2_b64 vcc, exec, s[0:1]
	v_lshl_add_u64 v[20:21], v[144:145], 0, s[28:29]
	s_mov_b64 s[0:1], -1
	global_store_dwordx4 v[84:85], v[68:71], off offset:256
	global_store_dwordx4 v[20:21], v[4:7], off offset:256
	s_cbranch_vccnz .LBB0_2319
	s_andn2_b64 vcc, exec, s[6:7]
	s_cbranch_vccnz .LBB0_2318
	s_barrier
	s_branch .LBB0_2318

; __device__ __forceinline__ unsigned pk2_(float lo, float hi) { return f2bf_(lo) | (f2bf_(hi) << 16); }
; template <int ACT> __device__ __forceinline__ float act_f(float v) {
;     ...
;     if (ACT == 3) { const float u = 0.7978845608028654f * (v + 0.044715f * v * v * v); const float e = __expf(2.f * u); const float th = 1.f - 2.f / (e + 1.f); return 0.5f * v * (1.f + th); }
;     __device__ __forceinline__ void operator()(const f32x4 (&acc)[2][2][4][2], const Unit& u, int wr, int wc, int fr, int fq) const {
;     ...
;             for (int m = 0; m < 4; ++m) { bf16_t* rowp = O + (size_t)(row0 + ai * HALF + m * 16) * ldc + col0;
; #pragma unroll
;                 for (int bj = 0; bj < 2; ++bj) { f32x4 v0 = acc[ai][bj][m][0], v1 = acc[ai][bj][m][1];
;                     if (bias) { v0 += *(const f32x4*)(bias + col0 + bj * HALF); v1 += *(const f32x4*)(bias + col0 + bj * HALF + 4); }
;                     u32x4 w; w.x = pk2_(act_f<ACT>(v0[0]), act_f<ACT>(v0[1])); w.y = pk2_(act_f<ACT>(v0[2]), act_f<ACT>(v0[3]));
;                     w.z = pk2_(act_f<ACT>(v1[0]), act_f<ACT>(v1[1])); w.w = pk2_(act_f<ACT>(v1[2]), act_f<ACT>(v1[3]));
;                     *(u32x4*)(rowp + bj * HALF) = w; } }
.LBB0_2461:
	s_lshl_b32 s0, s5, 8
	v_mov_b32_e32 v140, v146
	v_mov_b32_e32 v149, v145
	s_or_b32 s0, s0, s86
	s_nop 0
	v_lshl_add_u32 v142, v140, 3, s0
	v_ashrrev_i32_e32 v143, 31, v142
	v_lshl_add_u64 v[140:141], v[142:143], 2, s[34:35]
	global_load_dwordx4 v[150:153], v[140:141], off
	global_load_dwordx4 v[154:157], v[140:141], off offset:16
	s_lshl_b32 s0, s4, 8
	s_add_i32 s0, s0, s85
	v_add_u32_e32 v158, s0, v149
	v_ashrrev_i32_e32 v159, 31, v158
	v_lshlrev_b64 v[158:159], 9, v[158:159]
	v_lshl_add_u64 v[158:159], s[30:31], 0, v[158:159]
	v_lshl_add_u64 v[142:143], v[142:143], 1, v[158:159]
	s_waitcnt vmcnt(0)
	v_pk_add_f32 v[126:127], v[126:127], v[152:153]
	v_pk_add_f32 v[124:125], v[124:125], v[150:151]
	v_mul_f32_e32 v152, 0x3d372713, v126
	v_mul_f32_e32 v149, 0x3d372713, v124
	v_mul_f32_e32 v151, 0x3d372713, v125
	v_mul_f32_e32 v153, 0x3d372713, v127
	v_mul_f32_e32 v149, v124, v149
	v_mul_f32_e32 v151, v125, v151
	v_mul_f32_e32 v152, v126, v152
	v_mov_b32_e32 v150, v124
	v_mul_f32_e32 v153, v127, v153
	v_fma_f32 v124, v124, v149, v124
	v_fma_f32 v149, v125, v151, v125
	v_fma_f32 v151, v126, v152, v126
	v_fma_f32 v152, v127, v153, v127
	v_mul_f32_e32 v124, 0x3f4c422a, v124
	v_mul_f32_e32 v151, 0x3f4c422a, v151
	v_mul_f32_e32 v152, 0x3f4c422a, v152
	v_add_f32_e32 v124, v124, v124
	v_add_f32_e32 v151, v151, v151
	v_mul_f32_e32 v149, 0x3f4c422a, v149
	v_add_f32_e32 v152, v152, v152
	v_mul_f32_e32 v124, 0x3fb8aa3b, v124
	v_mul_f32_e32 v151, 0x3fb8aa3b, v151
	v_pk_add_f32 v[120:121], v[120:121], v[154:155]
	v_add_f32_e32 v149, v149, v149
	v_mul_f32_e32 v155, 0x3fb8aa3b, v152
	v_exp_f32_e32 v152, v124
	v_exp_f32_e32 v153, v151
	v_mul_f32_e32 v149, 0x3fb8aa3b, v149
	v_exp_f32_e32 v154, v149
	v_exp_f32_e32 v155, v155
	v_pk_add_f32 v[152:153], v[152:153], 1.0 op_sel_hi:[1,0]
	v_pk_add_f32 v[122:123], v[122:123], v[156:157]
	v_div_scale_f32 v124, s[0:1], v153, v153, 2.0
	v_pk_add_f32 v[154:155], v[154:155], 1.0 op_sel_hi:[1,0]
	v_div_scale_f32 v149, s[0:1], v152, v152, 2.0
	v_rcp_f32_e32 v161, v124
	v_div_scale_f32 v157, s[4:5], v155, v155, 2.0
	v_rcp_f32_e32 v162, v149
	v_div_scale_f32 v159, s[4:5], v154, v154, 2.0
	v_rcp_f32_e32 v163, v157
	v_rcp_f32_e32 v164, v159
	v_fma_f32 v165, -v124, v161, 1.0
	v_mov_b32_e32 v151, v126
	v_div_scale_f32 v126, vcc, 2.0, v153, 2.0
	v_fma_f32 v166, -v149, v162, 1.0
	v_fmac_f32_e32 v161, v165, v161
	v_div_scale_f32 v156, s[0:1], 2.0, v152, 2.0
	v_fma_f32 v167, -v157, v163, 1.0
	v_fmac_f32_e32 v162, v166, v162
	v_mul_f32_e32 v165, v126, v161
	v_div_scale_f32 v158, s[8:9], 2.0, v155, 2.0
	v_fma_f32 v168, -v159, v164, 1.0
	v_fmac_f32_e32 v163, v167, v163
	v_mul_f32_e32 v166, v156, v162
	v_fma_f32 v169, -v124, v165, v126
	v_div_scale_f32 v160, s[10:11], 2.0, v154, 2.0
	v_fmac_f32_e32 v164, v168, v164
	v_mul_f32_e32 v167, v158, v163
	v_fma_f32 v170, -v149, v166, v156
	v_fmac_f32_e32 v165, v169, v161
	v_mul_f32_e32 v168, v160, v164
	v_fma_f32 v171, -v157, v167, v158
	v_fmac_f32_e32 v166, v170, v162
	v_fma_f32 v124, -v124, v165, v126
	v_fma_f32 v172, -v159, v168, v160
	v_fmac_f32_e32 v167, v171, v163
	v_fma_f32 v126, -v149, v166, v156
	v_div_fmas_f32 v124, v124, v161, v165
	s_mov_b64 vcc, s[0:1]
	v_fmac_f32_e32 v168, v172, v164
	v_fma_f32 v149, -v157, v167, v158
	v_div_fixup_f32 v153, v124, v153, 2.0
	v_div_fmas_f32 v124, v126, v162, v166
	s_mov_b64 vcc, s[8:9]
	v_fma_f32 v156, -v159, v168, v160
	v_div_fixup_f32 v152, v124, v152, 2.0
	v_div_fmas_f32 v124, v149, v163, v167
	s_mov_b64 vcc, s[10:11]
	v_pk_add_f32 v[152:153], v[152:153], 1.0 op_sel_hi:[1,0] neg_lo:[1,0] neg_hi:[1,0]
	v_div_fixup_f32 v155, v124, v155, 2.0
	v_div_fmas_f32 v124, v156, v164, v168
	v_pk_mul_f32 v[150:151], v[150:151], 0.5 op_sel_hi:[1,0]
	v_pk_add_f32 v[152:153], v[152:153], 1.0 op_sel_hi:[1,0]
	v_div_fixup_f32 v154, v124, v154, 2.0
	v_pk_mul_f32 v[150:151], v[150:151], v[152:153]
	v_pk_add_f32 v[152:153], v[154:155], 1.0 op_sel_hi:[1,0] neg_lo:[1,0] neg_hi:[1,0]
	v_mov_b32_e32 v126, v125
	v_pk_mul_f32 v[124:125], v[126:127], 0.5 op_sel_hi:[1,0]
	v_pk_add_f32 v[126:127], v[152:153], 1.0 op_sel_hi:[1,0]
	v_mul_f32_e32 v149, 0x3d372713, v123
	v_pk_mul_f32 v[124:125], v[124:125], v[126:127]
	v_mul_f32_e32 v127, 0x3d372713, v121
	v_mul_f32_e32 v127, v121, v127
	v_fma_f32 v127, v121, v127, v121
	v_mul_f32_e32 v127, 0x3f4c422a, v127
	v_add_f32_e32 v127, v127, v127
	v_mul_f32_e32 v127, 0x3fb8aa3b, v127
	v_mul_f32_e32 v126, 0x3d372713, v120
	v_exp_f32_e32 v152, v127
	v_mul_f32_e32 v127, 0x3d372713, v122
	v_mul_f32_e32 v126, v120, v126
	v_mul_f32_e32 v127, v122, v127
	v_fma_f32 v126, v120, v126, v120
	v_fma_f32 v127, v122, v127, v122
	v_mul_f32_e32 v126, 0x3f4c422a, v126
	v_mul_f32_e32 v127, 0x3f4c422a, v127
	v_add_f32_e32 v126, v126, v126
	v_add_f32_e32 v127, v127, v127
	v_mul_f32_e32 v126, 0x3fb8aa3b, v126
	v_mul_f32_e32 v127, 0x3fb8aa3b, v127
	v_exp_f32_e32 v126, v126
	v_exp_f32_e32 v127, v127
	v_mul_f32_e32 v149, v123, v149
	v_fma_f32 v149, v123, v149, v123
	v_mul_f32_e32 v149, 0x3f4c422a, v149
	v_pk_add_f32 v[126:127], v[126:127], 1.0 op_sel_hi:[1,0]
	v_add_f32_e32 v149, v149, v149
	v_div_scale_f32 v154, s[0:1], v127, v127, 2.0
	v_rcp_f32_e32 v155, v154
	v_mul_f32_e32 v149, 0x3fb8aa3b, v149
	v_exp_f32_e32 v153, v149
	v_fma_f32 v149, -v154, v155, 1.0
	v_fmac_f32_e32 v155, v149, v155
	v_div_scale_f32 v149, vcc, 2.0, v127, 2.0
	v_mul_f32_e32 v156, v149, v155
	v_fma_f32 v157, -v154, v156, v149
	v_fmac_f32_e32 v156, v157, v155
	v_fma_f32 v149, -v154, v156, v149
	v_div_scale_f32 v154, s[0:1], v126, v126, 2.0
	v_rcp_f32_e32 v157, v154
	v_div_fmas_f32 v149, v149, v155, v156
	v_div_fixup_f32 v127, v149, v127, 2.0
	v_pk_add_f32 v[152:153], v[152:153], 1.0 op_sel_hi:[1,0]
; __device__ __forceinline__ unsigned pk2_(float lo, float hi) { return f2bf_(lo) | (f2bf_(hi) << 16); }
; template <int ACT> __device__ __forceinline__ float act_f(float v) {
;     ...
;     if (ACT == 3) { const float u = 0.7978845608028654f * (v + 0.044715f * v * v * v); const float e = __expf(2.f * u); const float th = 1.f - 2.f / (e + 1.f); return 0.5f * v * (1.f + th); }
;     __device__ __forceinline__ void operator()(const f32x4 (&acc)[2][2][4][2], const Unit& u, int wr, int wc, int fr, int fq) const {
;     ...
;             for (int m = 0; m < 4; ++m) { bf16_t* rowp = O + (size_t)(row0 + ai * HALF + m * 16) * ldc + col0;
; #pragma unroll
;                 for (int bj = 0; bj < 2; ++bj) { f32x4 v0 = acc[ai][bj][m][0], v1 = acc[ai][bj][m][1];
;                     if (bias) { v0 += *(const f32x4*)(bias + col0 + bj * HALF); v1 += *(const f32x4*)(bias + col0 + bj * HALF + 4); }
;                     u32x4 w; w.x = pk2_(act_f<ACT>(v0[0]), act_f<ACT>(v0[1])); w.y = pk2_(act_f<ACT>(v0[2]), act_f<ACT>(v0[3]));
;                     w.z = pk2_(act_f<ACT>(v1[0]), act_f<ACT>(v1[1])); w.w = pk2_(act_f<ACT>(v1[2]), act_f<ACT>(v1[3]));
;                     *(u32x4*)(rowp + bj * HALF) = w; } }
	v_fma_f32 v149, -v154, v157, 1.0
	v_fmac_f32_e32 v157, v149, v157
	v_div_scale_f32 v149, vcc, 2.0, v126, 2.0
	v_mul_f32_e32 v155, v149, v157
	v_fma_f32 v156, -v154, v155, v149
	v_fmac_f32_e32 v155, v156, v157
	v_fma_f32 v149, -v154, v155, v149
	v_mov_b32_e32 v154, v120
	v_div_scale_f32 v120, s[0:1], v153, v153, 2.0
	v_div_fmas_f32 v149, v149, v157, v155
	v_mov_b32_e32 v155, v122
	v_rcp_f32_e32 v122, v120
	v_div_fixup_f32 v126, v149, v126, 2.0
	v_pk_add_f32 v[126:127], v[126:127], 1.0 op_sel_hi:[1,0] neg_lo:[1,0] neg_hi:[1,0]
	v_pk_mul_f32 v[154:155], v[154:155], 0.5 op_sel_hi:[1,0]
	v_fma_f32 v149, -v120, v122, 1.0
	v_pk_add_f32 v[126:127], v[126:127], 1.0 op_sel_hi:[1,0]
	v_fmac_f32_e32 v122, v149, v122
	v_div_scale_f32 v149, vcc, 2.0, v153, 2.0
	v_pk_mul_f32 v[126:127], v[154:155], v[126:127]
	v_mul_f32_e32 v154, v149, v122
	v_fma_f32 v155, -v120, v154, v149
	v_fmac_f32_e32 v154, v155, v122
	v_fma_f32 v120, -v120, v154, v149
	v_div_scale_f32 v149, s[0:1], v152, v152, 2.0
	v_rcp_f32_e32 v155, v149
	v_div_fmas_f32 v120, v120, v122, v154
	v_div_fixup_f32 v153, v120, v153, 2.0
	v_fma_f32 v120, -v149, v155, 1.0
	v_fmac_f32_e32 v155, v120, v155
	v_div_scale_f32 v120, vcc, 2.0, v152, 2.0
	v_mul_f32_e32 v122, v120, v155
	v_fma_f32 v154, -v149, v122, v120
	v_fmac_f32_e32 v122, v154, v155
	v_fma_f32 v120, -v149, v122, v120
	v_div_fmas_f32 v120, v120, v155, v122
	v_div_fixup_f32 v152, v120, v152, 2.0
	v_pk_add_f32 v[152:153], v[152:153], 1.0 op_sel_hi:[1,0] neg_lo:[1,0] neg_hi:[1,0]
	v_mov_b32_e32 v122, v121
	v_pk_mul_f32 v[120:121], v[122:123], 0.5 op_sel_hi:[1,0]
	v_pk_add_f32 v[122:123], v[152:153], 1.0 op_sel_hi:[1,0]
	v_pk_mul_f32 v[120:121], v[120:121], v[122:123]
	v_cvt_pk_bf16_f32 v123, v127, v121
	v_cvt_pk_bf16_f32 v122, v126, v120
	v_cvt_pk_bf16_f32 v121, v151, v125
	v_cvt_pk_bf16_f32 v120, v150, v124
	global_store_dwordx4 v[142:143], v[120:123], off
	global_load_dwordx4 v[120:123], v[140:141], off offset:512
	s_nop 0
	global_load_dwordx4 v[124:127], v[140:141], off offset:528
	s_waitcnt vmcnt(1)
	v_pk_add_f32 v[120:121], v[116:117], v[120:121]
	s_nop 0
	v_mul_f32_e32 v117, 0x3d372713, v121
	v_mul_f32_e32 v117, v121, v117
	v_fma_f32 v117, v121, v117, v121
	v_mul_f32_e32 v117, 0x3f4c422a, v117
	v_add_f32_e32 v117, v117, v117
	v_pk_add_f32 v[118:119], v[118:119], v[122:123]
	v_mul_f32_e32 v117, 0x3fb8aa3b, v117
	v_mul_f32_e32 v116, 0x3d372713, v120
	v_exp_f32_e32 v122, v117
	v_mul_f32_e32 v117, 0x3d372713, v118
	v_mul_f32_e32 v116, v120, v116
	v_mul_f32_e32 v117, v118, v117
	v_fma_f32 v116, v120, v116, v120
	v_fma_f32 v117, v118, v117, v118
	v_mul_f32_e32 v116, 0x3f4c422a, v116
	v_mul_f32_e32 v117, 0x3f4c422a, v117
	v_add_f32_e32 v116, v116, v116
	v_add_f32_e32 v117, v117, v117
	v_mul_f32_e32 v116, 0x3fb8aa3b, v116
	v_mul_f32_e32 v117, 0x3fb8aa3b, v117
	v_exp_f32_e32 v116, v116
	v_exp_f32_e32 v117, v117
	s_waitcnt vmcnt(0)
	v_pk_add_f32 v[112:113], v[112:113], v[124:125]
	v_pk_add_f32 v[114:115], v[114:115], v[126:127]
	v_mul_f32_e32 v123, 0x3d372713, v119
	v_pk_add_f32 v[116:117], v[116:117], 1.0 op_sel_hi:[1,0]
	v_mul_f32_e32 v123, v119, v123
	v_div_scale_f32 v124, s[0:1], v117, v117, 2.0
	v_rcp_f32_e32 v125, v124
	v_fma_f32 v123, v119, v123, v119
	v_mul_f32_e32 v123, 0x3f4c422a, v123
	v_add_f32_e32 v123, v123, v123
	v_fma_f32 v126, -v124, v125, 1.0
	v_fmac_f32_e32 v125, v126, v125
	v_div_scale_f32 v126, vcc, 2.0, v117, 2.0
	v_mul_f32_e32 v127, v126, v125
	v_fma_f32 v149, -v124, v127, v126
	v_fmac_f32_e32 v127, v149, v125
	v_fma_f32 v124, -v124, v127, v126
	v_div_scale_f32 v126, s[0:1], v116, v116, 2.0
	v_rcp_f32_e32 v149, v126
	v_div_fmas_f32 v124, v124, v125, v127
	v_mul_f32_e32 v123, 0x3fb8aa3b, v123
	v_div_fixup_f32 v117, v124, v117, 2.0
	v_fma_f32 v124, -v126, v149, 1.0
	v_exp_f32_e32 v123, v123
	v_fmac_f32_e32 v149, v124, v149
	v_div_scale_f32 v124, vcc, 2.0, v116, 2.0
	v_mul_f32_e32 v125, v124, v149
	v_fma_f32 v127, -v126, v125, v124
	v_fmac_f32_e32 v125, v127, v149
	v_fma_f32 v124, -v126, v125, v124
	v_pk_add_f32 v[122:123], v[122:123], 1.0 op_sel_hi:[1,0]
	v_div_fmas_f32 v124, v124, v149, v125
	v_mov_b32_e32 v125, v118
	v_div_scale_f32 v118, s[0:1], v123, v123, 2.0
	v_div_fixup_f32 v116, v124, v116, 2.0
	v_mov_b32_e32 v124, v120
	v_rcp_f32_e32 v120, v118
	v_pk_add_f32 v[116:117], v[116:117], 1.0 op_sel_hi:[1,0] neg_lo:[1,0] neg_hi:[1,0]
	v_pk_mul_f32 v[124:125], v[124:125], 0.5 op_sel_hi:[1,0]
	v_pk_add_f32 v[116:117], v[116:117], 1.0 op_sel_hi:[1,0]
	s_nop 0
	v_pk_mul_f32 v[116:117], v[124:125], v[116:117]
	v_fma_f32 v124, -v118, v120, 1.0
	v_fmac_f32_e32 v120, v124, v120
	v_div_scale_f32 v124, vcc, 2.0, v123, 2.0
	v_mul_f32_e32 v125, v124, v120
	v_fma_f32 v126, -v118, v125, v124
	v_fmac_f32_e32 v125, v126, v120
	v_fma_f32 v118, -v118, v125, v124
	v_div_scale_f32 v124, s[0:1], v122, v122, 2.0
	v_rcp_f32_e32 v126, v124
	v_div_fmas_f32 v118, v118, v120, v125
	v_div_fixup_f32 v123, v118, v123, 2.0
	v_fma_f32 v118, -v124, v126, 1.0
	v_fmac_f32_e32 v126, v118, v126
	v_div_scale_f32 v118, vcc, 2.0, v122, 2.0
	v_mul_f32_e32 v120, v118, v126
	v_fma_f32 v125, -v124, v120, v118
	v_fmac_f32_e32 v120, v125, v126
	v_fma_f32 v118, -v124, v120, v118
	v_div_fmas_f32 v118, v118, v126, v120
	v_div_fixup_f32 v122, v118, v122, 2.0
	v_pk_add_f32 v[122:123], v[122:123], 1.0 op_sel_hi:[1,0] neg_lo:[1,0] neg_hi:[1,0]
	v_mov_b32_e32 v118, v121
	v_pk_mul_f32 v[118:119], v[118:119], 0.5 op_sel_hi:[1,0]
	v_pk_add_f32 v[120:121], v[122:123], 1.0 op_sel_hi:[1,0]
	v_mul_f32_e32 v123, 0x3d372713, v115
	v_pk_mul_f32 v[118:119], v[118:119], v[120:121]
	v_mul_f32_e32 v121, 0x3d372713, v113
	v_mul_f32_e32 v121, v113, v121
	v_fma_f32 v121, v113, v121, v113
; __device__ __forceinline__ unsigned pk2_(float lo, float hi) { return f2bf_(lo) | (f2bf_(hi) << 16); }
; template <int ACT> __device__ __forceinline__ float act_f(float v) {
;     ...
;     if (ACT == 3) { const float u = 0.7978845608028654f * (v + 0.044715f * v * v * v); const float e = __expf(2.f * u); const float th = 1.f - 2.f / (e + 1.f); return 0.5f * v * (1.f + th); }
;     __device__ __forceinline__ void operator()(const f32x4 (&acc)[2][2][4][2], const Unit& u, int wr, int wc, int fr, int fq) const {
;     ...
;             for (int m = 0; m < 4; ++m) { bf16_t* rowp = O + (size_t)(row0 + ai * HALF + m * 16) * ldc + col0;
; #pragma unroll
;                 for (int bj = 0; bj < 2; ++bj) { f32x4 v0 = acc[ai][bj][m][0], v1 = acc[ai][bj][m][1];
;                     if (bias) { v0 += *(const f32x4*)(bias + col0 + bj * HALF); v1 += *(const f32x4*)(bias + col0 + bj * HALF + 4); }
;                     u32x4 w; w.x = pk2_(act_f<ACT>(v0[0]), act_f<ACT>(v0[1])); w.y = pk2_(act_f<ACT>(v0[2]), act_f<ACT>(v0[3]));
;                     w.z = pk2_(act_f<ACT>(v1[0]), act_f<ACT>(v1[1])); w.w = pk2_(act_f<ACT>(v1[2]), act_f<ACT>(v1[3]));
;                     *(u32x4*)(rowp + bj * HALF) = w; } }
	v_mul_f32_e32 v121, 0x3f4c422a, v121
	v_add_f32_e32 v121, v121, v121
	v_mul_f32_e32 v121, 0x3fb8aa3b, v121
	v_mul_f32_e32 v120, 0x3d372713, v112
	v_exp_f32_e32 v122, v121
	v_mul_f32_e32 v121, 0x3d372713, v114
	v_mul_f32_e32 v120, v112, v120
	v_mul_f32_e32 v121, v114, v121
	v_fma_f32 v120, v112, v120, v112
	v_fma_f32 v121, v114, v121, v114
	v_mul_f32_e32 v120, 0x3f4c422a, v120
	v_mul_f32_e32 v121, 0x3f4c422a, v121
	v_add_f32_e32 v120, v120, v120
	v_add_f32_e32 v121, v121, v121
	v_mul_f32_e32 v120, 0x3fb8aa3b, v120
	v_mul_f32_e32 v121, 0x3fb8aa3b, v121
	v_exp_f32_e32 v120, v120
	v_exp_f32_e32 v121, v121
	v_mul_f32_e32 v123, v115, v123
	v_fma_f32 v123, v115, v123, v115
	v_mul_f32_e32 v123, 0x3f4c422a, v123
	v_pk_add_f32 v[120:121], v[120:121], 1.0 op_sel_hi:[1,0]
	v_add_f32_e32 v123, v123, v123
	v_div_scale_f32 v124, s[0:1], v121, v121, 2.0
	v_rcp_f32_e32 v125, v124
	v_mul_f32_e32 v123, 0x3fb8aa3b, v123
	v_exp_f32_e32 v123, v123
	v_fma_f32 v126, -v124, v125, 1.0
	v_fmac_f32_e32 v125, v126, v125
	v_div_scale_f32 v126, vcc, 2.0, v121, 2.0
	v_mul_f32_e32 v127, v126, v125
	v_fma_f32 v149, -v124, v127, v126
	v_fmac_f32_e32 v127, v149, v125
	v_fma_f32 v124, -v124, v127, v126
	v_div_scale_f32 v126, s[0:1], v120, v120, 2.0
	v_rcp_f32_e32 v149, v126
	v_div_fmas_f32 v124, v124, v125, v127
	v_div_fixup_f32 v121, v124, v121, 2.0
	v_pk_add_f32 v[122:123], v[122:123], 1.0 op_sel_hi:[1,0]
	v_fma_f32 v124, -v126, v149, 1.0
	v_fmac_f32_e32 v149, v124, v149
	v_div_scale_f32 v124, vcc, 2.0, v120, 2.0
	v_mul_f32_e32 v125, v124, v149
	v_fma_f32 v127, -v126, v125, v124
	v_fmac_f32_e32 v125, v127, v149
	v_fma_f32 v124, -v126, v125, v124
	v_div_fmas_f32 v124, v124, v149, v125
	v_div_fixup_f32 v120, v124, v120, 2.0
	v_mov_b32_e32 v124, v112
	v_div_scale_f32 v112, s[0:1], v123, v123, 2.0
	v_mov_b32_e32 v125, v114
	v_rcp_f32_e32 v114, v112
	v_pk_add_f32 v[120:121], v[120:121], 1.0 op_sel_hi:[1,0] neg_lo:[1,0] neg_hi:[1,0]
	v_pk_mul_f32 v[124:125], v[124:125], 0.5 op_sel_hi:[1,0]
	v_pk_add_f32 v[120:121], v[120:121], 1.0 op_sel_hi:[1,0]
	s_nop 0
	v_pk_mul_f32 v[120:121], v[124:125], v[120:121]
	v_fma_f32 v124, -v112, v114, 1.0
	v_fmac_f32_e32 v114, v124, v114
	v_div_scale_f32 v124, vcc, 2.0, v123, 2.0
	v_mul_f32_e32 v125, v124, v114
	v_fma_f32 v126, -v112, v125, v124
	v_fmac_f32_e32 v125, v126, v114
	v_fma_f32 v112, -v112, v125, v124
	v_div_scale_f32 v124, s[0:1], v122, v122, 2.0
	v_rcp_f32_e32 v126, v124
	v_div_fmas_f32 v112, v112, v114, v125
	v_div_fixup_f32 v123, v112, v123, 2.0
	v_fma_f32 v112, -v124, v126, 1.0
	v_fmac_f32_e32 v126, v112, v126
	v_div_scale_f32 v112, vcc, 2.0, v122, 2.0
	v_mul_f32_e32 v114, v112, v126
	v_fma_f32 v125, -v124, v114, v112
	v_fmac_f32_e32 v114, v125, v126
	v_fma_f32 v112, -v124, v114, v112
	v_div_fmas_f32 v112, v112, v126, v114
	v_div_fixup_f32 v122, v112, v122, 2.0
	v_pk_add_f32 v[122:123], v[122:123], 1.0 op_sel_hi:[1,0] neg_lo:[1,0] neg_hi:[1,0]
	v_mov_b32_e32 v114, v113
	v_pk_mul_f32 v[112:113], v[114:115], 0.5 op_sel_hi:[1,0]
	v_pk_add_f32 v[114:115], v[122:123], 1.0 op_sel_hi:[1,0]
	v_pk_mul_f32 v[112:113], v[112:113], v[114:115]
	v_cvt_pk_bf16_f32 v115, v121, v113
	v_cvt_pk_bf16_f32 v114, v120, v112
	v_cvt_pk_bf16_f32 v113, v117, v119
	v_cvt_pk_bf16_f32 v112, v116, v118
	global_store_dwordx4 v[142:143], v[112:115], off offset:256
	global_load_dwordx4 v[112:115], v[140:141], off
	s_nop 0
	global_load_dwordx4 v[116:119], v[140:141], off offset:16
	s_waitcnt vmcnt(1)
	v_pk_add_f32 v[112:113], v[108:109], v[112:113]
	s_nop 0
	v_mul_f32_e32 v109, 0x3d372713, v113
	v_mul_f32_e32 v109, v113, v109
	v_fma_f32 v109, v113, v109, v113
	v_mul_f32_e32 v109, 0x3f4c422a, v109
	v_add_f32_e32 v109, v109, v109
	v_pk_add_f32 v[110:111], v[110:111], v[114:115]
	v_mul_f32_e32 v109, 0x3fb8aa3b, v109
	v_mul_f32_e32 v108, 0x3d372713, v112
	v_exp_f32_e32 v114, v109
	v_mul_f32_e32 v109, 0x3d372713, v110
	v_mul_f32_e32 v108, v112, v108
	v_mul_f32_e32 v109, v110, v109
	v_fma_f32 v108, v112, v108, v112
	v_fma_f32 v109, v110, v109, v110
	v_mul_f32_e32 v108, 0x3f4c422a, v108
	v_mul_f32_e32 v109, 0x3f4c422a, v109
	v_add_f32_e32 v108, v108, v108
	v_add_f32_e32 v109, v109, v109
	v_mul_f32_e32 v108, 0x3fb8aa3b, v108
	v_mul_f32_e32 v109, 0x3fb8aa3b, v109
	v_exp_f32_e32 v108, v108
	v_exp_f32_e32 v109, v109
	s_waitcnt vmcnt(0)
; __device__ __forceinline__ unsigned pk2_(float lo, float hi) { return f2bf_(lo) | (f2bf_(hi) << 16); }
; template <int ACT> __device__ __forceinline__ float act_f(float v) {
;     ...
;     if (ACT == 3) { const float u = 0.7978845608028654f * (v + 0.044715f * v * v * v); const float e = __expf(2.f * u); const float th = 1.f - 2.f / (e + 1.f); return 0.5f * v * (1.f + th); }
;     __device__ __forceinline__ void operator()(const f32x4 (&acc)[2][2][4][2], const Unit& u, int wr, int wc, int fr, int fq) const {
;     ...
;             for (int m = 0; m < 4; ++m) { bf16_t* rowp = O + (size_t)(row0 + ai * HALF + m * 16) * ldc + col0;
; #pragma unroll
;                 for (int bj = 0; bj < 2; ++bj) { f32x4 v0 = acc[ai][bj][m][0], v1 = acc[ai][bj][m][1];
;                     if (bias) { v0 += *(const f32x4*)(bias + col0 + bj * HALF); v1 += *(const f32x4*)(bias + col0 + bj * HALF + 4); }
;                     u32x4 w; w.x = pk2_(act_f<ACT>(v0[0]), act_f<ACT>(v0[1])); w.y = pk2_(act_f<ACT>(v0[2]), act_f<ACT>(v0[3]));
;                     w.z = pk2_(act_f<ACT>(v1[0]), act_f<ACT>(v1[1])); w.w = pk2_(act_f<ACT>(v1[2]), act_f<ACT>(v1[3]));
;                     *(u32x4*)(rowp + bj * HALF) = w; } }
	v_pk_add_f32 v[104:105], v[104:105], v[116:117]
	v_pk_add_f32 v[106:107], v[106:107], v[118:119]
	v_mul_f32_e32 v115, 0x3d372713, v111
	v_pk_add_f32 v[108:109], v[108:109], 1.0 op_sel_hi:[1,0]
	v_mul_f32_e32 v115, v111, v115
	v_div_scale_f32 v116, s[0:1], v109, v109, 2.0
	v_rcp_f32_e32 v117, v116
	v_fma_f32 v115, v111, v115, v111
	v_mul_f32_e32 v115, 0x3f4c422a, v115
	v_add_f32_e32 v115, v115, v115
	v_fma_f32 v118, -v116, v117, 1.0
	v_fmac_f32_e32 v117, v118, v117
	v_div_scale_f32 v118, vcc, 2.0, v109, 2.0
	v_mul_f32_e32 v119, v118, v117
	v_fma_f32 v120, -v116, v119, v118
	v_fmac_f32_e32 v119, v120, v117
	v_fma_f32 v116, -v116, v119, v118
	v_div_scale_f32 v118, s[0:1], v108, v108, 2.0
	v_rcp_f32_e32 v120, v118
	v_div_fmas_f32 v116, v116, v117, v119
	v_mul_f32_e32 v115, 0x3fb8aa3b, v115
	v_div_fixup_f32 v109, v116, v109, 2.0
	v_fma_f32 v116, -v118, v120, 1.0
	v_exp_f32_e32 v115, v115
	v_fmac_f32_e32 v120, v116, v120
	v_div_scale_f32 v116, vcc, 2.0, v108, 2.0
	v_mul_f32_e32 v117, v116, v120
	v_fma_f32 v119, -v118, v117, v116
	v_fmac_f32_e32 v117, v119, v120
	v_fma_f32 v116, -v118, v117, v116
	v_pk_add_f32 v[114:115], v[114:115], 1.0 op_sel_hi:[1,0]
	v_div_fmas_f32 v116, v116, v120, v117
	v_mov_b32_e32 v117, v110
	v_div_scale_f32 v110, s[0:1], v115, v115, 2.0
	v_div_fixup_f32 v108, v116, v108, 2.0
	v_mov_b32_e32 v116, v112
	v_rcp_f32_e32 v112, v110
	v_pk_add_f32 v[108:109], v[108:109], 1.0 op_sel_hi:[1,0] neg_lo:[1,0] neg_hi:[1,0]
	v_pk_mul_f32 v[116:117], v[116:117], 0.5 op_sel_hi:[1,0]
	v_pk_add_f32 v[108:109], v[108:109], 1.0 op_sel_hi:[1,0]
	s_nop 0
	v_pk_mul_f32 v[108:109], v[116:117], v[108:109]
	v_fma_f32 v116, -v110, v112, 1.0
	v_fmac_f32_e32 v112, v116, v112
	v_div_scale_f32 v116, vcc, 2.0, v115, 2.0
	v_mul_f32_e32 v117, v116, v112
	v_fma_f32 v118, -v110, v117, v116
	v_fmac_f32_e32 v117, v118, v112
	v_fma_f32 v110, -v110, v117, v116
	v_div_scale_f32 v116, s[0:1], v114, v114, 2.0
	v_rcp_f32_e32 v118, v116
	v_div_fmas_f32 v110, v110, v112, v117
	v_div_fixup_f32 v115, v110, v115, 2.0
	v_fma_f32 v110, -v116, v118, 1.0
	v_fmac_f32_e32 v118, v110, v118
	v_div_scale_f32 v110, vcc, 2.0, v114, 2.0
	v_mul_f32_e32 v112, v110, v118
	v_fma_f32 v117, -v116, v112, v110
	v_fmac_f32_e32 v112, v117, v118
	v_fma_f32 v110, -v116, v112, v110
	v_div_fmas_f32 v110, v110, v118, v112
	v_div_fixup_f32 v114, v110, v114, 2.0
	v_pk_add_f32 v[114:115], v[114:115], 1.0 op_sel_hi:[1,0] neg_lo:[1,0] neg_hi:[1,0]
	v_mov_b32_e32 v110, v113
	v_pk_mul_f32 v[110:111], v[110:111], 0.5 op_sel_hi:[1,0]
	v_pk_add_f32 v[112:113], v[114:115], 1.0 op_sel_hi:[1,0]
	v_mul_f32_e32 v115, 0x3d372713, v107
	v_pk_mul_f32 v[110:111], v[110:111], v[112:113]
	v_mul_f32_e32 v113, 0x3d372713, v105
	v_mul_f32_e32 v113, v105, v113
	v_fma_f32 v113, v105, v113, v105
	v_mul_f32_e32 v113, 0x3f4c422a, v113
	v_add_f32_e32 v113, v113, v113
	v_mul_f32_e32 v113, 0x3fb8aa3b, v113
	v_mul_f32_e32 v112, 0x3d372713, v104
	v_exp_f32_e32 v114, v113
	v_mul_f32_e32 v113, 0x3d372713, v106
	v_mul_f32_e32 v112, v104, v112
	v_mul_f32_e32 v113, v106, v113
	v_fma_f32 v112, v104, v112, v104
	v_fma_f32 v113, v106, v113, v106
	v_mul_f32_e32 v112, 0x3f4c422a, v112
	v_mul_f32_e32 v113, 0x3f4c422a, v113
	v_add_f32_e32 v112, v112, v112
	v_add_f32_e32 v113, v113, v113
	v_mul_f32_e32 v112, 0x3fb8aa3b, v112
	v_mul_f32_e32 v113, 0x3fb8aa3b, v113
	v_exp_f32_e32 v112, v112
	v_exp_f32_e32 v113, v113
	v_mul_f32_e32 v115, v107, v115
	v_fma_f32 v115, v107, v115, v107
	v_mul_f32_e32 v115, 0x3f4c422a, v115
	v_pk_add_f32 v[112:113], v[112:113], 1.0 op_sel_hi:[1,0]
	v_add_f32_e32 v115, v115, v115
	v_div_scale_f32 v116, s[0:1], v113, v113, 2.0
	v_rcp_f32_e32 v117, v116
	v_mul_f32_e32 v115, 0x3fb8aa3b, v115
	v_exp_f32_e32 v115, v115
	v_fma_f32 v118, -v116, v117, 1.0
	v_fmac_f32_e32 v117, v118, v117
	v_div_scale_f32 v118, vcc, 2.0, v113, 2.0
	v_mul_f32_e32 v119, v118, v117
	v_fma_f32 v120, -v116, v119, v118
	v_fmac_f32_e32 v119, v120, v117
	v_fma_f32 v116, -v116, v119, v118
	v_div_scale_f32 v118, s[0:1], v112, v112, 2.0
	v_rcp_f32_e32 v120, v118
	v_div_fmas_f32 v116, v116, v117, v119
	v_div_fixup_f32 v113, v116, v113, 2.0
	v_pk_add_f32 v[114:115], v[114:115], 1.0 op_sel_hi:[1,0]
	v_fma_f32 v116, -v118, v120, 1.0
	v_fmac_f32_e32 v120, v116, v120
	v_div_scale_f32 v116, vcc, 2.0, v112, 2.0
	v_mul_f32_e32 v117, v116, v120
	v_fma_f32 v119, -v118, v117, v116
	v_fmac_f32_e32 v117, v119, v120
	v_fma_f32 v116, -v118, v117, v116
	v_div_fmas_f32 v116, v116, v120, v117
	v_div_fixup_f32 v112, v116, v112, 2.0
	v_mov_b32_e32 v116, v104
	v_div_scale_f32 v104, s[0:1], v115, v115, 2.0
	v_mov_b32_e32 v117, v106
	v_rcp_f32_e32 v106, v104
	v_pk_add_f32 v[112:113], v[112:113], 1.0 op_sel_hi:[1,0] neg_lo:[1,0] neg_hi:[1,0]
	v_pk_mul_f32 v[116:117], v[116:117], 0.5 op_sel_hi:[1,0]
	v_pk_add_f32 v[112:113], v[112:113], 1.0 op_sel_hi:[1,0]
	s_nop 0
	v_pk_mul_f32 v[112:113], v[116:117], v[112:113]
	v_fma_f32 v116, -v104, v106, 1.0
	v_fmac_f32_e32 v106, v116, v106
	v_div_scale_f32 v116, vcc, 2.0, v115, 2.0
	v_mul_f32_e32 v117, v116, v106
	v_fma_f32 v118, -v104, v117, v116
	v_fmac_f32_e32 v117, v118, v106
	v_fma_f32 v104, -v104, v117, v116
	v_div_scale_f32 v116, s[0:1], v114, v114, 2.0
	v_rcp_f32_e32 v118, v116
	v_div_fmas_f32 v104, v104, v106, v117
	v_div_fixup_f32 v115, v104, v115, 2.0
	s_movk_i32 s0, 0x2000
	v_fma_f32 v104, -v116, v118, 1.0
	v_fmac_f32_e32 v118, v104, v118
	v_div_scale_f32 v104, vcc, 2.0, v114, 2.0
	v_mul_f32_e32 v106, v104, v118
	v_fma_f32 v117, -v116, v106, v104
	v_fmac_f32_e32 v106, v117, v118
	v_fma_f32 v104, -v116, v106, v104
	v_div_fmas_f32 v104, v104, v118, v106
	v_div_fixup_f32 v114, v104, v114, 2.0
	v_pk_add_f32 v[114:115], v[114:115], 1.0 op_sel_hi:[1,0] neg_lo:[1,0] neg_hi:[1,0]
	v_mov_b32_e32 v106, v105
	v_pk_mul_f32 v[104:105], v[106:107], 0.5 op_sel_hi:[1,0]
	v_pk_add_f32 v[106:107], v[114:115], 1.0 op_sel_hi:[1,0]
	v_pk_mul_f32 v[104:105], v[104:105], v[106:107]
	v_cvt_pk_bf16_f32 v106, v112, v104
	v_cvt_pk_bf16_f32 v104, v108, v110
	v_add_co_u32_e32 v108, vcc, s0, v142
	v_cvt_pk_bf16_f32 v107, v113, v105
	v_cvt_pk_bf16_f32 v105, v109, v111
	v_addc_co_u32_e32 v109, vcc, 0, v143, vcc
	global_store_dwordx4 v[108:109], v[104:107], off
	global_load_dwordx4 v[106:109], v[140:141], off offset:512
	s_nop 0
	global_load_dwordx4 v[110:113], v[140:141], off offset:528
	s_mov_b64 s[0:1], 0x2000
	v_lshl_add_u64 v[104:105], v[142:143], 0, s[0:1]
	s_waitcnt vmcnt(1)
; __device__ __forceinline__ unsigned pk2_(float lo, float hi) { return f2bf_(lo) | (f2bf_(hi) << 16); }
; template <int ACT> __device__ __forceinline__ float act_f(float v) {
;     ...
;     if (ACT == 3) { const float u = 0.7978845608028654f * (v + 0.044715f * v * v * v); const float e = __expf(2.f * u); const float th = 1.f - 2.f / (e + 1.f); return 0.5f * v * (1.f + th); }
;     __device__ __forceinline__ void operator()(const f32x4 (&acc)[2][2][4][2], const Unit& u, int wr, int wc, int fr, int fq) const {
;     ...
;             for (int m = 0; m < 4; ++m) { bf16_t* rowp = O + (size_t)(row0 + ai * HALF + m * 16) * ldc + col0;
; #pragma unroll
;                 for (int bj = 0; bj < 2; ++bj) { f32x4 v0 = acc[ai][bj][m][0], v1 = acc[ai][bj][m][1];
;                     if (bias) { v0 += *(const f32x4*)(bias + col0 + bj * HALF); v1 += *(const f32x4*)(bias + col0 + bj * HALF + 4); }
;                     u32x4 w; w.x = pk2_(act_f<ACT>(v0[0]), act_f<ACT>(v0[1])); w.y = pk2_(act_f<ACT>(v0[2]), act_f<ACT>(v0[3]));
;                     w.z = pk2_(act_f<ACT>(v1[0]), act_f<ACT>(v1[1])); w.w = pk2_(act_f<ACT>(v1[2]), act_f<ACT>(v1[3]));
;                     *(u32x4*)(rowp + bj * HALF) = w; } }
	v_pk_add_f32 v[106:107], v[100:101], v[106:107]
	s_nop 0
	v_mul_f32_e32 v101, 0x3d372713, v107
	v_mul_f32_e32 v101, v107, v101
	v_fma_f32 v101, v107, v101, v107
	v_mul_f32_e32 v101, 0x3f4c422a, v101
	v_add_f32_e32 v101, v101, v101
	v_pk_add_f32 v[102:103], v[102:103], v[108:109]
	v_mul_f32_e32 v101, 0x3fb8aa3b, v101
	v_mul_f32_e32 v100, 0x3d372713, v106
	v_exp_f32_e32 v108, v101
	v_mul_f32_e32 v101, 0x3d372713, v102
	v_mul_f32_e32 v100, v106, v100
	v_mul_f32_e32 v101, v102, v101
	v_fma_f32 v100, v106, v100, v106
	v_fma_f32 v101, v102, v101, v102
	v_mul_f32_e32 v100, 0x3f4c422a, v100
	v_mul_f32_e32 v101, 0x3f4c422a, v101
	v_add_f32_e32 v100, v100, v100
	v_add_f32_e32 v101, v101, v101
	v_mul_f32_e32 v100, 0x3fb8aa3b, v100
	v_mul_f32_e32 v101, 0x3fb8aa3b, v101
	v_exp_f32_e32 v100, v100
	v_exp_f32_e32 v101, v101
	s_waitcnt vmcnt(0)
	v_pk_add_f32 v[96:97], v[96:97], v[110:111]
	v_pk_add_f32 v[98:99], v[98:99], v[112:113]
	v_mul_f32_e32 v109, 0x3d372713, v103
	v_pk_add_f32 v[100:101], v[100:101], 1.0 op_sel_hi:[1,0]
	v_mul_f32_e32 v109, v103, v109
	v_div_scale_f32 v110, s[0:1], v101, v101, 2.0
	v_rcp_f32_e32 v111, v110
	v_fma_f32 v109, v103, v109, v103
	v_mul_f32_e32 v109, 0x3f4c422a, v109
	v_add_f32_e32 v109, v109, v109
	v_fma_f32 v112, -v110, v111, 1.0
	v_fmac_f32_e32 v111, v112, v111
	v_div_scale_f32 v112, vcc, 2.0, v101, 2.0
	v_mul_f32_e32 v113, v112, v111
	v_fma_f32 v114, -v110, v113, v112
	v_fmac_f32_e32 v113, v114, v111
	v_fma_f32 v110, -v110, v113, v112
	v_div_scale_f32 v112, s[0:1], v100, v100, 2.0
	v_rcp_f32_e32 v114, v112
	v_div_fmas_f32 v110, v110, v111, v113
	v_mul_f32_e32 v109, 0x3fb8aa3b, v109
	v_div_fixup_f32 v101, v110, v101, 2.0
	v_fma_f32 v110, -v112, v114, 1.0
	v_exp_f32_e32 v109, v109
	v_fmac_f32_e32 v114, v110, v114
	v_div_scale_f32 v110, vcc, 2.0, v100, 2.0
	v_mul_f32_e32 v111, v110, v114
	v_fma_f32 v113, -v112, v111, v110
	v_fmac_f32_e32 v111, v113, v114
	v_fma_f32 v110, -v112, v111, v110
	v_pk_add_f32 v[108:109], v[108:109], 1.0 op_sel_hi:[1,0]
	v_div_fmas_f32 v110, v110, v114, v111
	v_mov_b32_e32 v111, v102
	v_div_scale_f32 v102, s[0:1], v109, v109, 2.0
	v_div_fixup_f32 v100, v110, v100, 2.0
	v_mov_b32_e32 v110, v106
	v_rcp_f32_e32 v106, v102
	v_pk_add_f32 v[100:101], v[100:101], 1.0 op_sel_hi:[1,0] neg_lo:[1,0] neg_hi:[1,0]
	v_pk_mul_f32 v[110:111], v[110:111], 0.5 op_sel_hi:[1,0]
	v_pk_add_f32 v[100:101], v[100:101], 1.0 op_sel_hi:[1,0]
	s_nop 0
	v_pk_mul_f32 v[100:101], v[110:111], v[100:101]
	v_fma_f32 v110, -v102, v106, 1.0
	v_fmac_f32_e32 v106, v110, v106
	v_div_scale_f32 v110, vcc, 2.0, v109, 2.0
	v_mul_f32_e32 v111, v110, v106
	v_fma_f32 v112, -v102, v111, v110
	v_fmac_f32_e32 v111, v112, v106
	v_fma_f32 v102, -v102, v111, v110
	v_div_scale_f32 v110, s[0:1], v108, v108, 2.0
	v_rcp_f32_e32 v112, v110
	v_div_fmas_f32 v102, v102, v106, v111
	v_div_fixup_f32 v109, v102, v109, 2.0
	v_fma_f32 v102, -v110, v112, 1.0
	v_fmac_f32_e32 v112, v102, v112
	v_div_scale_f32 v102, vcc, 2.0, v108, 2.0
	v_mul_f32_e32 v106, v102, v112
	v_fma_f32 v111, -v110, v106, v102
	v_fmac_f32_e32 v106, v111, v112
	v_fma_f32 v102, -v110, v106, v102
	v_div_fmas_f32 v102, v102, v112, v106
	v_div_fixup_f32 v108, v102, v108, 2.0
	v_pk_add_f32 v[108:109], v[108:109], 1.0 op_sel_hi:[1,0] neg_lo:[1,0] neg_hi:[1,0]
	v_mov_b32_e32 v102, v107
	v_pk_mul_f32 v[102:103], v[102:103], 0.5 op_sel_hi:[1,0]
	v_pk_add_f32 v[106:107], v[108:109], 1.0 op_sel_hi:[1,0]
	v_mul_f32_e32 v109, 0x3d372713, v99
	v_pk_mul_f32 v[102:103], v[102:103], v[106:107]
	v_mul_f32_e32 v107, 0x3d372713, v97
	v_mul_f32_e32 v107, v97, v107
	v_fma_f32 v107, v97, v107, v97
	v_mul_f32_e32 v107, 0x3f4c422a, v107
	v_add_f32_e32 v107, v107, v107
	v_mul_f32_e32 v107, 0x3fb8aa3b, v107
	v_mul_f32_e32 v106, 0x3d372713, v96
	v_exp_f32_e32 v108, v107
	v_mul_f32_e32 v107, 0x3d372713, v98
	v_mul_f32_e32 v106, v96, v106
	v_mul_f32_e32 v107, v98, v107
	v_fma_f32 v106, v96, v106, v96
	v_fma_f32 v107, v98, v107, v98
	v_mul_f32_e32 v106, 0x3f4c422a, v106
	v_mul_f32_e32 v107, 0x3f4c422a, v107
	v_add_f32_e32 v106, v106, v106
	v_add_f32_e32 v107, v107, v107
	v_mul_f32_e32 v106, 0x3fb8aa3b, v106
	v_mul_f32_e32 v107, 0x3fb8aa3b, v107
	v_exp_f32_e32 v106, v106
	v_exp_f32_e32 v107, v107
	v_mul_f32_e32 v109, v99, v109
	v_fma_f32 v109, v99, v109, v99
	v_mul_f32_e32 v109, 0x3f4c422a, v109
	v_pk_add_f32 v[106:107], v[106:107], 1.0 op_sel_hi:[1,0]
	v_add_f32_e32 v109, v109, v109
	v_div_scale_f32 v110, s[0:1], v107, v107, 2.0
	v_rcp_f32_e32 v111, v110
	v_mul_f32_e32 v109, 0x3fb8aa3b, v109
	v_exp_f32_e32 v109, v109
	v_fma_f32 v112, -v110, v111, 1.0
	v_fmac_f32_e32 v111, v112, v111
	v_div_scale_f32 v112, vcc, 2.0, v107, 2.0
	v_mul_f32_e32 v113, v112, v111
	v_fma_f32 v114, -v110, v113, v112
	v_fmac_f32_e32 v113, v114, v111
	v_fma_f32 v110, -v110, v113, v112
	v_div_scale_f32 v112, s[0:1], v106, v106, 2.0
	v_rcp_f32_e32 v114, v112
	v_div_fmas_f32 v110, v110, v111, v113
	v_div_fixup_f32 v107, v110, v107, 2.0
	v_pk_add_f32 v[108:109], v[108:109], 1.0 op_sel_hi:[1,0]
	v_fma_f32 v110, -v112, v114, 1.0
	v_fmac_f32_e32 v114, v110, v114
	v_div_scale_f32 v110, vcc, 2.0, v106, 2.0
	v_mul_f32_e32 v111, v110, v114
	v_fma_f32 v113, -v112, v111, v110
	v_fmac_f32_e32 v111, v113, v114
	v_fma_f32 v110, -v112, v111, v110
	v_div_fmas_f32 v110, v110, v114, v111
	v_div_fixup_f32 v106, v110, v106, 2.0
	v_mov_b32_e32 v110, v96
	v_div_scale_f32 v96, s[0:1], v109, v109, 2.0
	v_mov_b32_e32 v111, v98
	v_rcp_f32_e32 v98, v96
	v_pk_add_f32 v[106:107], v[106:107], 1.0 op_sel_hi:[1,0] neg_lo:[1,0] neg_hi:[1,0]
	v_pk_mul_f32 v[110:111], v[110:111], 0.5 op_sel_hi:[1,0]
	v_pk_add_f32 v[106:107], v[106:107], 1.0 op_sel_hi:[1,0]
	s_nop 0
	v_pk_mul_f32 v[106:107], v[110:111], v[106:107]
	v_fma_f32 v110, -v96, v98, 1.0
	v_fmac_f32_e32 v98, v110, v98
	v_div_scale_f32 v110, vcc, 2.0, v109, 2.0
	v_mul_f32_e32 v111, v110, v98
	v_fma_f32 v112, -v96, v111, v110
	v_fmac_f32_e32 v111, v112, v98
	v_fma_f32 v96, -v96, v111, v110
	v_div_scale_f32 v110, s[0:1], v108, v108, 2.0
	v_rcp_f32_e32 v112, v110
	v_div_fmas_f32 v96, v96, v98, v111
	v_div_fixup_f32 v109, v96, v109, 2.0
	v_fma_f32 v96, -v110, v112, 1.0
	v_fmac_f32_e32 v112, v96, v112
	v_div_scale_f32 v96, vcc, 2.0, v108, 2.0
	v_mul_f32_e32 v98, v96, v112
	v_fma_f32 v111, -v110, v98, v96
	v_fmac_f32_e32 v98, v111, v112
	v_fma_f32 v96, -v110, v98, v96
	v_div_fmas_f32 v96, v96, v112, v98
	v_div_fixup_f32 v108, v96, v108, 2.0
	v_pk_add_f32 v[108:109], v[108:109], 1.0 op_sel_hi:[1,0] neg_lo:[1,0] neg_hi:[1,0]
	v_mov_b32_e32 v98, v97
	v_pk_mul_f32 v[96:97], v[98:99], 0.5 op_sel_hi:[1,0]
	v_pk_add_f32 v[98:99], v[108:109], 1.0 op_sel_hi:[1,0]
	v_pk_mul_f32 v[96:97], v[96:97], v[98:99]
	v_cvt_pk_bf16_f32 v99, v107, v97
	v_cvt_pk_bf16_f32 v98, v106, v96
	v_cvt_pk_bf16_f32 v97, v101, v103
	v_cvt_pk_bf16_f32 v96, v100, v102
	global_store_dwordx4 v[104:105], v[96:99], off offset:256
	global_load_dwordx4 v[96:99], v[140:141], off
	s_nop 0
	global_load_dwordx4 v[100:103], v[140:141], off offset:16
	s_waitcnt vmcnt(1)
; __device__ __forceinline__ unsigned pk2_(float lo, float hi) { return f2bf_(lo) | (f2bf_(hi) << 16); }
; template <int ACT> __device__ __forceinline__ float act_f(float v) {
;     ...
;     if (ACT == 3) { const float u = 0.7978845608028654f * (v + 0.044715f * v * v * v); const float e = __expf(2.f * u); const float th = 1.f - 2.f / (e + 1.f); return 0.5f * v * (1.f + th); }
;     __device__ __forceinline__ void operator()(const f32x4 (&acc)[2][2][4][2], const Unit& u, int wr, int wc, int fr, int fq) const {
;     ...
;             for (int m = 0; m < 4; ++m) { bf16_t* rowp = O + (size_t)(row0 + ai * HALF + m * 16) * ldc + col0;
; #pragma unroll
;                 for (int bj = 0; bj < 2; ++bj) { f32x4 v0 = acc[ai][bj][m][0], v1 = acc[ai][bj][m][1];
;                     if (bias) { v0 += *(const f32x4*)(bias + col0 + bj * HALF); v1 += *(const f32x4*)(bias + col0 + bj * HALF + 4); }
;                     u32x4 w; w.x = pk2_(act_f<ACT>(v0[0]), act_f<ACT>(v0[1])); w.y = pk2_(act_f<ACT>(v0[2]), act_f<ACT>(v0[3]));
;                     w.z = pk2_(act_f<ACT>(v1[0]), act_f<ACT>(v1[1])); w.w = pk2_(act_f<ACT>(v1[2]), act_f<ACT>(v1[3]));
;                     *(u32x4*)(rowp + bj * HALF) = w; } }
	v_pk_add_f32 v[96:97], v[92:93], v[96:97]
	s_nop 0
	v_mul_f32_e32 v93, 0x3d372713, v97
	v_mul_f32_e32 v93, v97, v93
	v_fma_f32 v93, v97, v93, v97
	v_mul_f32_e32 v93, 0x3f4c422a, v93
	v_add_f32_e32 v93, v93, v93
	v_pk_add_f32 v[94:95], v[94:95], v[98:99]
	v_mul_f32_e32 v93, 0x3fb8aa3b, v93
	v_mul_f32_e32 v92, 0x3d372713, v96
	v_exp_f32_e32 v98, v93
	v_mul_f32_e32 v93, 0x3d372713, v94
	v_mul_f32_e32 v92, v96, v92
	v_mul_f32_e32 v93, v94, v93
	v_fma_f32 v92, v96, v92, v96
	v_fma_f32 v93, v94, v93, v94
	v_mul_f32_e32 v92, 0x3f4c422a, v92
	v_mul_f32_e32 v93, 0x3f4c422a, v93
	v_add_f32_e32 v92, v92, v92
	v_add_f32_e32 v93, v93, v93
	v_mul_f32_e32 v92, 0x3fb8aa3b, v92
	v_mul_f32_e32 v93, 0x3fb8aa3b, v93
	v_exp_f32_e32 v92, v92
	v_exp_f32_e32 v93, v93
	s_waitcnt vmcnt(0)
	v_pk_add_f32 v[88:89], v[88:89], v[100:101]
	v_pk_add_f32 v[90:91], v[90:91], v[102:103]
	v_mul_f32_e32 v99, 0x3d372713, v95
	v_pk_add_f32 v[92:93], v[92:93], 1.0 op_sel_hi:[1,0]
	v_mul_f32_e32 v99, v95, v99
	v_div_scale_f32 v100, s[0:1], v93, v93, 2.0
	v_rcp_f32_e32 v101, v100
	v_fma_f32 v99, v95, v99, v95
	v_mul_f32_e32 v99, 0x3f4c422a, v99
	v_add_f32_e32 v99, v99, v99
	v_fma_f32 v102, -v100, v101, 1.0
	v_fmac_f32_e32 v101, v102, v101
	v_div_scale_f32 v102, vcc, 2.0, v93, 2.0
	v_mul_f32_e32 v103, v102, v101
	v_fma_f32 v104, -v100, v103, v102
	v_fmac_f32_e32 v103, v104, v101
	v_fma_f32 v100, -v100, v103, v102
	v_div_scale_f32 v102, s[0:1], v92, v92, 2.0
	v_rcp_f32_e32 v104, v102
	v_div_fmas_f32 v100, v100, v101, v103
	v_mul_f32_e32 v99, 0x3fb8aa3b, v99
	v_div_fixup_f32 v93, v100, v93, 2.0
	v_fma_f32 v100, -v102, v104, 1.0
	v_exp_f32_e32 v99, v99
	v_fmac_f32_e32 v104, v100, v104
	v_div_scale_f32 v100, vcc, 2.0, v92, 2.0
	v_mul_f32_e32 v101, v100, v104
	v_fma_f32 v103, -v102, v101, v100
	v_fmac_f32_e32 v101, v103, v104
	v_fma_f32 v100, -v102, v101, v100
	v_pk_add_f32 v[98:99], v[98:99], 1.0 op_sel_hi:[1,0]
	v_div_fmas_f32 v100, v100, v104, v101
	v_mov_b32_e32 v101, v94
	v_div_scale_f32 v94, s[0:1], v99, v99, 2.0
	v_div_fixup_f32 v92, v100, v92, 2.0
	v_mov_b32_e32 v100, v96
	v_rcp_f32_e32 v96, v94
	v_pk_add_f32 v[92:93], v[92:93], 1.0 op_sel_hi:[1,0] neg_lo:[1,0] neg_hi:[1,0]
	v_pk_mul_f32 v[100:101], v[100:101], 0.5 op_sel_hi:[1,0]
	v_pk_add_f32 v[92:93], v[92:93], 1.0 op_sel_hi:[1,0]
	s_nop 0
	v_pk_mul_f32 v[92:93], v[100:101], v[92:93]
	v_fma_f32 v100, -v94, v96, 1.0
	v_fmac_f32_e32 v96, v100, v96
	v_div_scale_f32 v100, vcc, 2.0, v99, 2.0
	v_mul_f32_e32 v101, v100, v96
	v_fma_f32 v102, -v94, v101, v100
	v_fmac_f32_e32 v101, v102, v96
	v_fma_f32 v94, -v94, v101, v100
	v_div_scale_f32 v100, s[0:1], v98, v98, 2.0
	v_rcp_f32_e32 v102, v100
	v_div_fmas_f32 v94, v94, v96, v101
	v_div_fixup_f32 v99, v94, v99, 2.0
	v_fma_f32 v94, -v100, v102, 1.0
	v_fmac_f32_e32 v102, v94, v102
	v_div_scale_f32 v94, vcc, 2.0, v98, 2.0
	v_mul_f32_e32 v96, v94, v102
	v_fma_f32 v101, -v100, v96, v94
	v_fmac_f32_e32 v96, v101, v102
	v_fma_f32 v94, -v100, v96, v94
	v_div_fmas_f32 v94, v94, v102, v96
	v_div_fixup_f32 v98, v94, v98, 2.0
	v_pk_add_f32 v[98:99], v[98:99], 1.0 op_sel_hi:[1,0] neg_lo:[1,0] neg_hi:[1,0]
	v_mov_b32_e32 v94, v97
	v_pk_mul_f32 v[94:95], v[94:95], 0.5 op_sel_hi:[1,0]
	v_pk_add_f32 v[96:97], v[98:99], 1.0 op_sel_hi:[1,0]
	v_mul_f32_e32 v99, 0x3d372713, v91
	v_pk_mul_f32 v[94:95], v[94:95], v[96:97]
	v_mul_f32_e32 v97, 0x3d372713, v89
	v_mul_f32_e32 v97, v89, v97
	v_fma_f32 v97, v89, v97, v89
	v_mul_f32_e32 v97, 0x3f4c422a, v97
	v_add_f32_e32 v97, v97, v97
	v_mul_f32_e32 v97, 0x3fb8aa3b, v97
	v_mul_f32_e32 v96, 0x3d372713, v88
	v_exp_f32_e32 v98, v97
	v_mul_f32_e32 v97, 0x3d372713, v90
	v_mul_f32_e32 v96, v88, v96
	v_mul_f32_e32 v97, v90, v97
	v_fma_f32 v96, v88, v96, v88
	v_fma_f32 v97, v90, v97, v90
	v_mul_f32_e32 v96, 0x3f4c422a, v96
	v_mul_f32_e32 v97, 0x3f4c422a, v97
	v_add_f32_e32 v96, v96, v96
	v_add_f32_e32 v97, v97, v97
	v_mul_f32_e32 v96, 0x3fb8aa3b, v96
	v_mul_f32_e32 v97, 0x3fb8aa3b, v97
	v_exp_f32_e32 v96, v96
	v_exp_f32_e32 v97, v97
	v_mul_f32_e32 v99, v91, v99
	v_fma_f32 v99, v91, v99, v91
	v_mul_f32_e32 v99, 0x3f4c422a, v99
	v_pk_add_f32 v[96:97], v[96:97], 1.0 op_sel_hi:[1,0]
	v_add_f32_e32 v99, v99, v99
	v_div_scale_f32 v100, s[0:1], v97, v97, 2.0
	v_rcp_f32_e32 v101, v100
	v_mul_f32_e32 v99, 0x3fb8aa3b, v99
	v_exp_f32_e32 v99, v99
	v_fma_f32 v102, -v100, v101, 1.0
	v_fmac_f32_e32 v101, v102, v101
	v_div_scale_f32 v102, vcc, 2.0, v97, 2.0
	v_mul_f32_e32 v103, v102, v101
	v_fma_f32 v104, -v100, v103, v102
	v_fmac_f32_e32 v103, v104, v101
	v_fma_f32 v100, -v100, v103, v102
	v_div_scale_f32 v102, s[0:1], v96, v96, 2.0
	v_rcp_f32_e32 v104, v102
	v_div_fmas_f32 v100, v100, v101, v103
	v_div_fixup_f32 v97, v100, v97, 2.0
	v_pk_add_f32 v[98:99], v[98:99], 1.0 op_sel_hi:[1,0]
	v_fma_f32 v100, -v102, v104, 1.0
	v_fmac_f32_e32 v104, v100, v104
	v_div_scale_f32 v100, vcc, 2.0, v96, 2.0
	v_mul_f32_e32 v101, v100, v104
	v_fma_f32 v103, -v102, v101, v100
	v_fmac_f32_e32 v101, v103, v104
	v_fma_f32 v100, -v102, v101, v100
	v_div_fmas_f32 v100, v100, v104, v101
	v_div_fixup_f32 v96, v100, v96, 2.0
	v_mov_b32_e32 v100, v88
	v_div_scale_f32 v88, s[0:1], v99, v99, 2.0
	v_mov_b32_e32 v101, v90
	v_rcp_f32_e32 v90, v88
	v_pk_add_f32 v[96:97], v[96:97], 1.0 op_sel_hi:[1,0] neg_lo:[1,0] neg_hi:[1,0]
	v_pk_mul_f32 v[100:101], v[100:101], 0.5 op_sel_hi:[1,0]
	v_pk_add_f32 v[96:97], v[96:97], 1.0 op_sel_hi:[1,0]
	s_nop 0
	v_pk_mul_f32 v[96:97], v[100:101], v[96:97]
	v_fma_f32 v100, -v88, v90, 1.0
	v_fmac_f32_e32 v90, v100, v90
	v_div_scale_f32 v100, vcc, 2.0, v99, 2.0
	v_mul_f32_e32 v101, v100, v90
	v_fma_f32 v102, -v88, v101, v100
	v_fmac_f32_e32 v101, v102, v90
	v_fma_f32 v88, -v88, v101, v100
	v_div_scale_f32 v100, s[0:1], v98, v98, 2.0
	v_rcp_f32_e32 v102, v100
	v_div_fmas_f32 v88, v88, v90, v101
	v_div_fixup_f32 v99, v88, v99, 2.0
	s_movk_i32 s0, 0x4000
	v_fma_f32 v88, -v100, v102, 1.0
	v_fmac_f32_e32 v102, v88, v102
	v_div_scale_f32 v88, vcc, 2.0, v98, 2.0
	v_mul_f32_e32 v90, v88, v102
	v_fma_f32 v101, -v100, v90, v88
	v_fmac_f32_e32 v90, v101, v102
	v_fma_f32 v88, -v100, v90, v88
	v_div_fmas_f32 v88, v88, v102, v90
	v_div_fixup_f32 v98, v88, v98, 2.0
	v_pk_add_f32 v[98:99], v[98:99], 1.0 op_sel_hi:[1,0] neg_lo:[1,0] neg_hi:[1,0]
	v_mov_b32_e32 v90, v89
	v_pk_mul_f32 v[88:89], v[90:91], 0.5 op_sel_hi:[1,0]
	v_pk_add_f32 v[90:91], v[98:99], 1.0 op_sel_hi:[1,0]
	v_pk_mul_f32 v[88:89], v[88:89], v[90:91]
	v_cvt_pk_bf16_f32 v90, v96, v88
	v_cvt_pk_bf16_f32 v88, v92, v94
	v_add_co_u32_e32 v92, vcc, s0, v142
	v_cvt_pk_bf16_f32 v91, v97, v89
	v_cvt_pk_bf16_f32 v89, v93, v95
	v_addc_co_u32_e32 v93, vcc, 0, v143, vcc
	global_store_dwordx4 v[92:93], v[88:91], off
	global_load_dwordx4 v[90:93], v[140:141], off offset:512
	s_nop 0
	global_load_dwordx4 v[94:97], v[140:141], off offset:528
	s_mov_b64 s[0:1], 0x4000
	v_lshl_add_u64 v[88:89], v[142:143], 0, s[0:1]
	s_waitcnt vmcnt(1)
; __device__ __forceinline__ unsigned pk2_(float lo, float hi) { return f2bf_(lo) | (f2bf_(hi) << 16); }
; template <int ACT> __device__ __forceinline__ float act_f(float v) {
;     ...
;     if (ACT == 3) { const float u = 0.7978845608028654f * (v + 0.044715f * v * v * v); const float e = __expf(2.f * u); const float th = 1.f - 2.f / (e + 1.f); return 0.5f * v * (1.f + th); }
;     __device__ __forceinline__ void operator()(const f32x4 (&acc)[2][2][4][2], const Unit& u, int wr, int wc, int fr, int fq) const {
;     ...
;             for (int m = 0; m < 4; ++m) { bf16_t* rowp = O + (size_t)(row0 + ai * HALF + m * 16) * ldc + col0;
; #pragma unroll
;                 for (int bj = 0; bj < 2; ++bj) { f32x4 v0 = acc[ai][bj][m][0], v1 = acc[ai][bj][m][1];
;                     if (bias) { v0 += *(const f32x4*)(bias + col0 + bj * HALF); v1 += *(const f32x4*)(bias + col0 + bj * HALF + 4); }
;                     u32x4 w; w.x = pk2_(act_f<ACT>(v0[0]), act_f<ACT>(v0[1])); w.y = pk2_(act_f<ACT>(v0[2]), act_f<ACT>(v0[3]));
;                     w.z = pk2_(act_f<ACT>(v1[0]), act_f<ACT>(v1[1])); w.w = pk2_(act_f<ACT>(v1[2]), act_f<ACT>(v1[3]));
;                     *(u32x4*)(rowp + bj * HALF) = w; } }
	v_pk_add_f32 v[90:91], v[84:85], v[90:91]
	s_nop 0
	v_mul_f32_e32 v85, 0x3d372713, v91
	v_mul_f32_e32 v85, v91, v85
	v_fma_f32 v85, v91, v85, v91
	v_mul_f32_e32 v85, 0x3f4c422a, v85
	v_add_f32_e32 v85, v85, v85
	v_pk_add_f32 v[86:87], v[86:87], v[92:93]
	v_mul_f32_e32 v85, 0x3fb8aa3b, v85
	v_mul_f32_e32 v84, 0x3d372713, v90
	v_exp_f32_e32 v92, v85
	v_mul_f32_e32 v85, 0x3d372713, v86
	v_mul_f32_e32 v84, v90, v84
	v_mul_f32_e32 v85, v86, v85
	v_fma_f32 v84, v90, v84, v90
	v_fma_f32 v85, v86, v85, v86
	v_mul_f32_e32 v84, 0x3f4c422a, v84
	v_mul_f32_e32 v85, 0x3f4c422a, v85
	v_add_f32_e32 v84, v84, v84
	v_add_f32_e32 v85, v85, v85
	v_mul_f32_e32 v84, 0x3fb8aa3b, v84
	v_mul_f32_e32 v85, 0x3fb8aa3b, v85
	v_exp_f32_e32 v84, v84
	v_exp_f32_e32 v85, v85
	s_waitcnt vmcnt(0)
	v_pk_add_f32 v[80:81], v[80:81], v[94:95]
	v_pk_add_f32 v[82:83], v[82:83], v[96:97]
	v_mul_f32_e32 v93, 0x3d372713, v87
	v_pk_add_f32 v[84:85], v[84:85], 1.0 op_sel_hi:[1,0]
	v_mul_f32_e32 v93, v87, v93
	v_div_scale_f32 v94, s[0:1], v85, v85, 2.0
	v_rcp_f32_e32 v95, v94
	v_fma_f32 v93, v87, v93, v87
	v_mul_f32_e32 v93, 0x3f4c422a, v93
	v_add_f32_e32 v93, v93, v93
	v_fma_f32 v96, -v94, v95, 1.0
	v_fmac_f32_e32 v95, v96, v95
	v_div_scale_f32 v96, vcc, 2.0, v85, 2.0
	v_mul_f32_e32 v97, v96, v95
	v_fma_f32 v98, -v94, v97, v96
	v_fmac_f32_e32 v97, v98, v95
	v_fma_f32 v94, -v94, v97, v96
	v_div_scale_f32 v96, s[0:1], v84, v84, 2.0
	v_rcp_f32_e32 v98, v96
	v_div_fmas_f32 v94, v94, v95, v97
	v_mul_f32_e32 v93, 0x3fb8aa3b, v93
	v_div_fixup_f32 v85, v94, v85, 2.0
	v_fma_f32 v94, -v96, v98, 1.0
	v_exp_f32_e32 v93, v93
	v_fmac_f32_e32 v98, v94, v98
	v_div_scale_f32 v94, vcc, 2.0, v84, 2.0
	v_mul_f32_e32 v95, v94, v98
	v_fma_f32 v97, -v96, v95, v94
	v_fmac_f32_e32 v95, v97, v98
	v_fma_f32 v94, -v96, v95, v94
	v_pk_add_f32 v[92:93], v[92:93], 1.0 op_sel_hi:[1,0]
	v_div_fmas_f32 v94, v94, v98, v95
	v_mov_b32_e32 v95, v86
	v_div_scale_f32 v86, s[0:1], v93, v93, 2.0
	v_div_fixup_f32 v84, v94, v84, 2.0
	v_mov_b32_e32 v94, v90
	v_rcp_f32_e32 v90, v86
	v_pk_add_f32 v[84:85], v[84:85], 1.0 op_sel_hi:[1,0] neg_lo:[1,0] neg_hi:[1,0]
	v_pk_mul_f32 v[94:95], v[94:95], 0.5 op_sel_hi:[1,0]
	v_pk_add_f32 v[84:85], v[84:85], 1.0 op_sel_hi:[1,0]
	s_nop 0
	v_pk_mul_f32 v[84:85], v[94:95], v[84:85]
	v_fma_f32 v94, -v86, v90, 1.0
	v_fmac_f32_e32 v90, v94, v90
	v_div_scale_f32 v94, vcc, 2.0, v93, 2.0
	v_mul_f32_e32 v95, v94, v90
	v_fma_f32 v96, -v86, v95, v94
	v_fmac_f32_e32 v95, v96, v90
	v_fma_f32 v86, -v86, v95, v94
	v_div_scale_f32 v94, s[0:1], v92, v92, 2.0
	v_rcp_f32_e32 v96, v94
	v_div_fmas_f32 v86, v86, v90, v95
	v_div_fixup_f32 v93, v86, v93, 2.0
	v_fma_f32 v86, -v94, v96, 1.0
	v_fmac_f32_e32 v96, v86, v96
	v_div_scale_f32 v86, vcc, 2.0, v92, 2.0
	v_mul_f32_e32 v90, v86, v96
	v_fma_f32 v95, -v94, v90, v86
	v_fmac_f32_e32 v90, v95, v96
	v_fma_f32 v86, -v94, v90, v86
	v_div_fmas_f32 v86, v86, v96, v90
	v_div_fixup_f32 v92, v86, v92, 2.0
	v_pk_add_f32 v[92:93], v[92:93], 1.0 op_sel_hi:[1,0] neg_lo:[1,0] neg_hi:[1,0]
	v_mov_b32_e32 v86, v91
	v_pk_mul_f32 v[86:87], v[86:87], 0.5 op_sel_hi:[1,0]
	v_pk_add_f32 v[90:91], v[92:93], 1.0 op_sel_hi:[1,0]
	v_mul_f32_e32 v93, 0x3d372713, v83
	v_pk_mul_f32 v[86:87], v[86:87], v[90:91]
	v_mul_f32_e32 v91, 0x3d372713, v81
	v_mul_f32_e32 v91, v81, v91
	v_fma_f32 v91, v81, v91, v81
	v_mul_f32_e32 v91, 0x3f4c422a, v91
	v_add_f32_e32 v91, v91, v91
	v_mul_f32_e32 v91, 0x3fb8aa3b, v91
	v_mul_f32_e32 v90, 0x3d372713, v80
	v_exp_f32_e32 v92, v91
	v_mul_f32_e32 v91, 0x3d372713, v82
	v_mul_f32_e32 v90, v80, v90
	v_mul_f32_e32 v91, v82, v91
	v_fma_f32 v90, v80, v90, v80
	v_fma_f32 v91, v82, v91, v82
	v_mul_f32_e32 v90, 0x3f4c422a, v90
	v_mul_f32_e32 v91, 0x3f4c422a, v91
	v_add_f32_e32 v90, v90, v90
	v_add_f32_e32 v91, v91, v91
	v_mul_f32_e32 v90, 0x3fb8aa3b, v90
	v_mul_f32_e32 v91, 0x3fb8aa3b, v91
	v_exp_f32_e32 v90, v90
	v_exp_f32_e32 v91, v91
	v_mul_f32_e32 v93, v83, v93
	v_fma_f32 v93, v83, v93, v83
	v_mul_f32_e32 v93, 0x3f4c422a, v93
	v_pk_add_f32 v[90:91], v[90:91], 1.0 op_sel_hi:[1,0]
	v_add_f32_e32 v93, v93, v93
	v_div_scale_f32 v94, s[0:1], v91, v91, 2.0
	v_rcp_f32_e32 v95, v94
	v_mul_f32_e32 v93, 0x3fb8aa3b, v93
	v_exp_f32_e32 v93, v93
	v_fma_f32 v96, -v94, v95, 1.0
	v_fmac_f32_e32 v95, v96, v95
	v_div_scale_f32 v96, vcc, 2.0, v91, 2.0
	v_mul_f32_e32 v97, v96, v95
	v_fma_f32 v98, -v94, v97, v96
	v_fmac_f32_e32 v97, v98, v95
	v_fma_f32 v94, -v94, v97, v96
	v_div_scale_f32 v96, s[0:1], v90, v90, 2.0
	v_rcp_f32_e32 v98, v96
	v_div_fmas_f32 v94, v94, v95, v97
	v_div_fixup_f32 v91, v94, v91, 2.0
	v_pk_add_f32 v[92:93], v[92:93], 1.0 op_sel_hi:[1,0]
	v_fma_f32 v94, -v96, v98, 1.0
	v_fmac_f32_e32 v98, v94, v98
	v_div_scale_f32 v94, vcc, 2.0, v90, 2.0
	v_mul_f32_e32 v95, v94, v98
	v_fma_f32 v97, -v96, v95, v94
	v_fmac_f32_e32 v95, v97, v98
	v_fma_f32 v94, -v96, v95, v94
	v_div_fmas_f32 v94, v94, v98, v95
	v_div_fixup_f32 v90, v94, v90, 2.0
	v_mov_b32_e32 v94, v80
	v_div_scale_f32 v80, s[0:1], v93, v93, 2.0
	v_mov_b32_e32 v95, v82
	v_rcp_f32_e32 v82, v80
	v_pk_add_f32 v[90:91], v[90:91], 1.0 op_sel_hi:[1,0] neg_lo:[1,0] neg_hi:[1,0]
	v_pk_mul_f32 v[94:95], v[94:95], 0.5 op_sel_hi:[1,0]
	v_pk_add_f32 v[90:91], v[90:91], 1.0 op_sel_hi:[1,0]
	s_nop 0
	v_pk_mul_f32 v[90:91], v[94:95], v[90:91]
	v_fma_f32 v94, -v80, v82, 1.0
	v_fmac_f32_e32 v82, v94, v82
	v_div_scale_f32 v94, vcc, 2.0, v93, 2.0
	v_mul_f32_e32 v95, v94, v82
	v_fma_f32 v96, -v80, v95, v94
	v_fmac_f32_e32 v95, v96, v82
	v_fma_f32 v80, -v80, v95, v94
	v_div_scale_f32 v94, s[0:1], v92, v92, 2.0
	v_rcp_f32_e32 v96, v94
	v_div_fmas_f32 v80, v80, v82, v95
	v_div_fixup_f32 v93, v80, v93, 2.0
	v_fma_f32 v80, -v94, v96, 1.0
	v_fmac_f32_e32 v96, v80, v96
	v_div_scale_f32 v80, vcc, 2.0, v92, 2.0
	v_mul_f32_e32 v82, v80, v96
	v_fma_f32 v95, -v94, v82, v80
	v_fmac_f32_e32 v82, v95, v96
	v_fma_f32 v80, -v94, v82, v80
	v_div_fmas_f32 v80, v80, v96, v82
	v_div_fixup_f32 v92, v80, v92, 2.0
	v_pk_add_f32 v[92:93], v[92:93], 1.0 op_sel_hi:[1,0] neg_lo:[1,0] neg_hi:[1,0]
	v_mov_b32_e32 v82, v81
	v_pk_mul_f32 v[80:81], v[82:83], 0.5 op_sel_hi:[1,0]
	v_pk_add_f32 v[82:83], v[92:93], 1.0 op_sel_hi:[1,0]
	v_pk_mul_f32 v[80:81], v[80:81], v[82:83]
	v_cvt_pk_bf16_f32 v83, v91, v81
	v_cvt_pk_bf16_f32 v82, v90, v80
	v_cvt_pk_bf16_f32 v81, v85, v87
	v_cvt_pk_bf16_f32 v80, v84, v86
	global_store_dwordx4 v[88:89], v[80:83], off offset:256
	global_load_dwordx4 v[80:83], v[140:141], off
	s_nop 0
	global_load_dwordx4 v[84:87], v[140:141], off offset:16
	s_waitcnt vmcnt(1)
; __device__ __forceinline__ unsigned pk2_(float lo, float hi) { return f2bf_(lo) | (f2bf_(hi) << 16); }
; template <int ACT> __device__ __forceinline__ float act_f(float v) {
;     ...
;     if (ACT == 3) { const float u = 0.7978845608028654f * (v + 0.044715f * v * v * v); const float e = __expf(2.f * u); const float th = 1.f - 2.f / (e + 1.f); return 0.5f * v * (1.f + th); }
;     __device__ __forceinline__ void operator()(const f32x4 (&acc)[2][2][4][2], const Unit& u, int wr, int wc, int fr, int fq) const {
;     ...
;             for (int m = 0; m < 4; ++m) { bf16_t* rowp = O + (size_t)(row0 + ai * HALF + m * 16) * ldc + col0;
; #pragma unroll
;                 for (int bj = 0; bj < 2; ++bj) { f32x4 v0 = acc[ai][bj][m][0], v1 = acc[ai][bj][m][1];
;                     if (bias) { v0 += *(const f32x4*)(bias + col0 + bj * HALF); v1 += *(const f32x4*)(bias + col0 + bj * HALF + 4); }
;                     u32x4 w; w.x = pk2_(act_f<ACT>(v0[0]), act_f<ACT>(v0[1])); w.y = pk2_(act_f<ACT>(v0[2]), act_f<ACT>(v0[3]));
;                     w.z = pk2_(act_f<ACT>(v1[0]), act_f<ACT>(v1[1])); w.w = pk2_(act_f<ACT>(v1[2]), act_f<ACT>(v1[3]));
;                     *(u32x4*)(rowp + bj * HALF) = w; } }
	v_pk_add_f32 v[80:81], v[76:77], v[80:81]
	s_nop 0
	v_mul_f32_e32 v77, 0x3d372713, v81
	v_mul_f32_e32 v77, v81, v77
	v_fma_f32 v77, v81, v77, v81
	v_mul_f32_e32 v77, 0x3f4c422a, v77
	v_add_f32_e32 v77, v77, v77
	v_pk_add_f32 v[78:79], v[78:79], v[82:83]
	v_mul_f32_e32 v77, 0x3fb8aa3b, v77
	v_mul_f32_e32 v76, 0x3d372713, v80
	v_exp_f32_e32 v82, v77
	v_mul_f32_e32 v77, 0x3d372713, v78
	v_mul_f32_e32 v76, v80, v76
	v_mul_f32_e32 v77, v78, v77
	v_fma_f32 v76, v80, v76, v80
	v_fma_f32 v77, v78, v77, v78
	v_mul_f32_e32 v76, 0x3f4c422a, v76
	v_mul_f32_e32 v77, 0x3f4c422a, v77
	v_add_f32_e32 v76, v76, v76
	v_add_f32_e32 v77, v77, v77
	v_mul_f32_e32 v76, 0x3fb8aa3b, v76
	v_mul_f32_e32 v77, 0x3fb8aa3b, v77
	v_exp_f32_e32 v76, v76
	v_exp_f32_e32 v77, v77
	s_waitcnt vmcnt(0)
	v_pk_add_f32 v[72:73], v[72:73], v[84:85]
	v_pk_add_f32 v[74:75], v[74:75], v[86:87]
	v_mul_f32_e32 v83, 0x3d372713, v79
	v_pk_add_f32 v[76:77], v[76:77], 1.0 op_sel_hi:[1,0]
	v_mul_f32_e32 v83, v79, v83
	v_div_scale_f32 v84, s[0:1], v77, v77, 2.0
	v_rcp_f32_e32 v85, v84
	v_fma_f32 v83, v79, v83, v79
	v_mul_f32_e32 v83, 0x3f4c422a, v83
	v_add_f32_e32 v83, v83, v83
	v_fma_f32 v86, -v84, v85, 1.0
	v_fmac_f32_e32 v85, v86, v85
	v_div_scale_f32 v86, vcc, 2.0, v77, 2.0
	v_mul_f32_e32 v87, v86, v85
	v_fma_f32 v88, -v84, v87, v86
	v_fmac_f32_e32 v87, v88, v85
	v_fma_f32 v84, -v84, v87, v86
	v_div_scale_f32 v86, s[0:1], v76, v76, 2.0
	v_rcp_f32_e32 v88, v86
	v_div_fmas_f32 v84, v84, v85, v87
	v_mul_f32_e32 v83, 0x3fb8aa3b, v83
	v_div_fixup_f32 v77, v84, v77, 2.0
	v_fma_f32 v84, -v86, v88, 1.0
	v_exp_f32_e32 v83, v83
	v_fmac_f32_e32 v88, v84, v88
	v_div_scale_f32 v84, vcc, 2.0, v76, 2.0
	v_mul_f32_e32 v85, v84, v88
	v_fma_f32 v87, -v86, v85, v84
	v_fmac_f32_e32 v85, v87, v88
	v_fma_f32 v84, -v86, v85, v84
	v_pk_add_f32 v[82:83], v[82:83], 1.0 op_sel_hi:[1,0]
	v_div_fmas_f32 v84, v84, v88, v85
	v_mov_b32_e32 v85, v78
	v_div_scale_f32 v78, s[0:1], v83, v83, 2.0
	v_div_fixup_f32 v76, v84, v76, 2.0
	v_mov_b32_e32 v84, v80
	v_rcp_f32_e32 v80, v78
	v_pk_add_f32 v[76:77], v[76:77], 1.0 op_sel_hi:[1,0] neg_lo:[1,0] neg_hi:[1,0]
	v_pk_mul_f32 v[84:85], v[84:85], 0.5 op_sel_hi:[1,0]
	v_pk_add_f32 v[76:77], v[76:77], 1.0 op_sel_hi:[1,0]
	s_nop 0
	v_pk_mul_f32 v[76:77], v[84:85], v[76:77]
	v_fma_f32 v84, -v78, v80, 1.0
	v_fmac_f32_e32 v80, v84, v80
	v_div_scale_f32 v84, vcc, 2.0, v83, 2.0
	v_mul_f32_e32 v85, v84, v80
	v_fma_f32 v86, -v78, v85, v84
	v_fmac_f32_e32 v85, v86, v80
	v_fma_f32 v78, -v78, v85, v84
	v_div_scale_f32 v84, s[0:1], v82, v82, 2.0
	v_rcp_f32_e32 v86, v84
	v_div_fmas_f32 v78, v78, v80, v85
	v_div_fixup_f32 v83, v78, v83, 2.0
	v_fma_f32 v78, -v84, v86, 1.0
	v_fmac_f32_e32 v86, v78, v86
	v_div_scale_f32 v78, vcc, 2.0, v82, 2.0
	v_mul_f32_e32 v80, v78, v86
	v_fma_f32 v85, -v84, v80, v78
	v_fmac_f32_e32 v80, v85, v86
	v_fma_f32 v78, -v84, v80, v78
	v_div_fmas_f32 v78, v78, v86, v80
	v_div_fixup_f32 v82, v78, v82, 2.0
	v_pk_add_f32 v[82:83], v[82:83], 1.0 op_sel_hi:[1,0] neg_lo:[1,0] neg_hi:[1,0]
	v_mov_b32_e32 v78, v81
	v_pk_mul_f32 v[78:79], v[78:79], 0.5 op_sel_hi:[1,0]
	v_pk_add_f32 v[80:81], v[82:83], 1.0 op_sel_hi:[1,0]
	v_mul_f32_e32 v83, 0x3d372713, v75
	v_pk_mul_f32 v[78:79], v[78:79], v[80:81]
	v_mul_f32_e32 v81, 0x3d372713, v73
	v_mul_f32_e32 v81, v73, v81
	v_fma_f32 v81, v73, v81, v73
	v_mul_f32_e32 v81, 0x3f4c422a, v81
	v_add_f32_e32 v81, v81, v81
	v_mul_f32_e32 v81, 0x3fb8aa3b, v81
	v_mul_f32_e32 v80, 0x3d372713, v72
	v_exp_f32_e32 v82, v81
	v_mul_f32_e32 v81, 0x3d372713, v74
	v_mul_f32_e32 v80, v72, v80
	v_mul_f32_e32 v81, v74, v81
	v_fma_f32 v80, v72, v80, v72
	v_fma_f32 v81, v74, v81, v74
	v_mul_f32_e32 v80, 0x3f4c422a, v80
	v_mul_f32_e32 v81, 0x3f4c422a, v81
	v_add_f32_e32 v80, v80, v80
	v_add_f32_e32 v81, v81, v81
	v_mul_f32_e32 v80, 0x3fb8aa3b, v80
	v_mul_f32_e32 v81, 0x3fb8aa3b, v81
	v_exp_f32_e32 v80, v80
	v_exp_f32_e32 v81, v81
	v_mul_f32_e32 v83, v75, v83
	v_fma_f32 v83, v75, v83, v75
	v_mul_f32_e32 v83, 0x3f4c422a, v83
	v_pk_add_f32 v[80:81], v[80:81], 1.0 op_sel_hi:[1,0]
	v_add_f32_e32 v83, v83, v83
	v_div_scale_f32 v84, s[0:1], v81, v81, 2.0
	v_rcp_f32_e32 v85, v84
	v_mul_f32_e32 v83, 0x3fb8aa3b, v83
	v_exp_f32_e32 v83, v83
	v_fma_f32 v86, -v84, v85, 1.0
	v_fmac_f32_e32 v85, v86, v85
	v_div_scale_f32 v86, vcc, 2.0, v81, 2.0
	v_mul_f32_e32 v87, v86, v85
	v_fma_f32 v88, -v84, v87, v86
	v_fmac_f32_e32 v87, v88, v85
	v_fma_f32 v84, -v84, v87, v86
	v_div_scale_f32 v86, s[0:1], v80, v80, 2.0
	v_rcp_f32_e32 v88, v86
	v_div_fmas_f32 v84, v84, v85, v87
	v_div_fixup_f32 v81, v84, v81, 2.0
	v_pk_add_f32 v[82:83], v[82:83], 1.0 op_sel_hi:[1,0]
	v_fma_f32 v84, -v86, v88, 1.0
	v_fmac_f32_e32 v88, v84, v88
	v_div_scale_f32 v84, vcc, 2.0, v80, 2.0
	v_mul_f32_e32 v85, v84, v88
	v_fma_f32 v87, -v86, v85, v84
	v_fmac_f32_e32 v85, v87, v88
	v_fma_f32 v84, -v86, v85, v84
	v_div_fmas_f32 v84, v84, v88, v85
	v_div_fixup_f32 v80, v84, v80, 2.0
	v_mov_b32_e32 v84, v72
	v_div_scale_f32 v72, s[0:1], v83, v83, 2.0
	v_mov_b32_e32 v85, v74
	v_rcp_f32_e32 v74, v72
	v_pk_add_f32 v[80:81], v[80:81], 1.0 op_sel_hi:[1,0] neg_lo:[1,0] neg_hi:[1,0]
	v_pk_mul_f32 v[84:85], v[84:85], 0.5 op_sel_hi:[1,0]
	v_pk_add_f32 v[80:81], v[80:81], 1.0 op_sel_hi:[1,0]
	s_nop 0
	v_pk_mul_f32 v[80:81], v[84:85], v[80:81]
	v_fma_f32 v84, -v72, v74, 1.0
	v_fmac_f32_e32 v74, v84, v74
	v_div_scale_f32 v84, vcc, 2.0, v83, 2.0
	v_mul_f32_e32 v85, v84, v74
	v_fma_f32 v86, -v72, v85, v84
	v_fmac_f32_e32 v85, v86, v74
	v_fma_f32 v72, -v72, v85, v84
	v_div_scale_f32 v84, s[0:1], v82, v82, 2.0
	v_rcp_f32_e32 v86, v84
	v_div_fmas_f32 v72, v72, v74, v85
	v_div_fixup_f32 v83, v72, v83, 2.0
	s_movk_i32 s0, 0x6000
	v_fma_f32 v72, -v84, v86, 1.0
	v_fmac_f32_e32 v86, v72, v86
	v_div_scale_f32 v72, vcc, 2.0, v82, 2.0
	v_mul_f32_e32 v74, v72, v86
	v_fma_f32 v85, -v84, v74, v72
	v_fmac_f32_e32 v74, v85, v86
	v_fma_f32 v72, -v84, v74, v72
	v_div_fmas_f32 v72, v72, v86, v74
	v_div_fixup_f32 v82, v72, v82, 2.0
	v_pk_add_f32 v[82:83], v[82:83], 1.0 op_sel_hi:[1,0] neg_lo:[1,0] neg_hi:[1,0]
	v_mov_b32_e32 v74, v73
	v_pk_mul_f32 v[72:73], v[74:75], 0.5 op_sel_hi:[1,0]
	v_pk_add_f32 v[74:75], v[82:83], 1.0 op_sel_hi:[1,0]
	v_pk_mul_f32 v[72:73], v[72:73], v[74:75]
	v_cvt_pk_bf16_f32 v74, v80, v72
	v_cvt_pk_bf16_f32 v72, v76, v78
	v_add_co_u32_e32 v76, vcc, s0, v142
	v_cvt_pk_bf16_f32 v75, v81, v73
	v_cvt_pk_bf16_f32 v73, v77, v79
	v_addc_co_u32_e32 v77, vcc, 0, v143, vcc
	global_store_dwordx4 v[76:77], v[72:75], off
	global_load_dwordx4 v[74:77], v[140:141], off offset:512
	s_nop 0
	global_load_dwordx4 v[78:81], v[140:141], off offset:528
	s_mov_b64 s[0:1], 0x6000
	v_lshl_add_u64 v[72:73], v[142:143], 0, s[0:1]
	s_waitcnt vmcnt(1)
; __device__ __forceinline__ unsigned pk2_(float lo, float hi) { return f2bf_(lo) | (f2bf_(hi) << 16); }
; template <int ACT> __device__ __forceinline__ float act_f(float v) {
;     ...
;     if (ACT == 3) { const float u = 0.7978845608028654f * (v + 0.044715f * v * v * v); const float e = __expf(2.f * u); const float th = 1.f - 2.f / (e + 1.f); return 0.5f * v * (1.f + th); }
;     __device__ __forceinline__ void operator()(const f32x4 (&acc)[2][2][4][2], const Unit& u, int wr, int wc, int fr, int fq) const {
;     ...
;             for (int m = 0; m < 4; ++m) { bf16_t* rowp = O + (size_t)(row0 + ai * HALF + m * 16) * ldc + col0;
; #pragma unroll
;                 for (int bj = 0; bj < 2; ++bj) { f32x4 v0 = acc[ai][bj][m][0], v1 = acc[ai][bj][m][1];
;                     if (bias) { v0 += *(const f32x4*)(bias + col0 + bj * HALF); v1 += *(const f32x4*)(bias + col0 + bj * HALF + 4); }
;                     u32x4 w; w.x = pk2_(act_f<ACT>(v0[0]), act_f<ACT>(v0[1])); w.y = pk2_(act_f<ACT>(v0[2]), act_f<ACT>(v0[3]));
;                     w.z = pk2_(act_f<ACT>(v1[0]), act_f<ACT>(v1[1])); w.w = pk2_(act_f<ACT>(v1[2]), act_f<ACT>(v1[3]));
;                     *(u32x4*)(rowp + bj * HALF) = w; } }
	v_pk_add_f32 v[74:75], v[68:69], v[74:75]
	s_nop 0
	v_mul_f32_e32 v69, 0x3d372713, v75
	v_mul_f32_e32 v69, v75, v69
	v_fma_f32 v69, v75, v69, v75
	v_mul_f32_e32 v69, 0x3f4c422a, v69
	v_add_f32_e32 v69, v69, v69
	v_pk_add_f32 v[70:71], v[70:71], v[76:77]
	v_mul_f32_e32 v69, 0x3fb8aa3b, v69
	v_mul_f32_e32 v68, 0x3d372713, v74
	v_exp_f32_e32 v76, v69
	v_mul_f32_e32 v69, 0x3d372713, v70
	v_mul_f32_e32 v68, v74, v68
	v_mul_f32_e32 v69, v70, v69
	v_fma_f32 v68, v74, v68, v74
	v_fma_f32 v69, v70, v69, v70
	v_mul_f32_e32 v68, 0x3f4c422a, v68
	v_mul_f32_e32 v69, 0x3f4c422a, v69
	v_add_f32_e32 v68, v68, v68
	v_add_f32_e32 v69, v69, v69
	v_mul_f32_e32 v68, 0x3fb8aa3b, v68
	v_mul_f32_e32 v69, 0x3fb8aa3b, v69
	v_exp_f32_e32 v68, v68
	v_exp_f32_e32 v69, v69
	s_waitcnt vmcnt(0)
	v_pk_add_f32 v[64:65], v[64:65], v[78:79]
	v_pk_add_f32 v[66:67], v[66:67], v[80:81]
	v_mul_f32_e32 v77, 0x3d372713, v71
	v_pk_add_f32 v[68:69], v[68:69], 1.0 op_sel_hi:[1,0]
	v_mul_f32_e32 v77, v71, v77
	v_div_scale_f32 v78, s[0:1], v69, v69, 2.0
	v_rcp_f32_e32 v79, v78
	v_fma_f32 v77, v71, v77, v71
	v_mul_f32_e32 v77, 0x3f4c422a, v77
	v_add_f32_e32 v77, v77, v77
	v_fma_f32 v80, -v78, v79, 1.0
	v_fmac_f32_e32 v79, v80, v79
	v_div_scale_f32 v80, vcc, 2.0, v69, 2.0
	v_mul_f32_e32 v81, v80, v79
	v_fma_f32 v82, -v78, v81, v80
	v_fmac_f32_e32 v81, v82, v79
	v_fma_f32 v78, -v78, v81, v80
	v_div_scale_f32 v80, s[0:1], v68, v68, 2.0
	v_rcp_f32_e32 v82, v80
	v_div_fmas_f32 v78, v78, v79, v81
	v_mul_f32_e32 v77, 0x3fb8aa3b, v77
	v_div_fixup_f32 v69, v78, v69, 2.0
	v_fma_f32 v78, -v80, v82, 1.0
	v_exp_f32_e32 v77, v77
	v_fmac_f32_e32 v82, v78, v82
	v_div_scale_f32 v78, vcc, 2.0, v68, 2.0
	v_mul_f32_e32 v79, v78, v82
	v_fma_f32 v81, -v80, v79, v78
	v_fmac_f32_e32 v79, v81, v82
	v_fma_f32 v78, -v80, v79, v78
	v_pk_add_f32 v[76:77], v[76:77], 1.0 op_sel_hi:[1,0]
	v_div_fmas_f32 v78, v78, v82, v79
	v_mov_b32_e32 v79, v70
	v_div_scale_f32 v70, s[0:1], v77, v77, 2.0
	v_div_fixup_f32 v68, v78, v68, 2.0
	v_mov_b32_e32 v78, v74
	v_rcp_f32_e32 v74, v70
	v_pk_add_f32 v[68:69], v[68:69], 1.0 op_sel_hi:[1,0] neg_lo:[1,0] neg_hi:[1,0]
	v_pk_mul_f32 v[78:79], v[78:79], 0.5 op_sel_hi:[1,0]
	v_pk_add_f32 v[68:69], v[68:69], 1.0 op_sel_hi:[1,0]
	s_nop 0
	v_pk_mul_f32 v[68:69], v[78:79], v[68:69]
	v_fma_f32 v78, -v70, v74, 1.0
	v_fmac_f32_e32 v74, v78, v74
	v_div_scale_f32 v78, vcc, 2.0, v77, 2.0
	v_mul_f32_e32 v79, v78, v74
	v_fma_f32 v80, -v70, v79, v78
	v_fmac_f32_e32 v79, v80, v74
	v_fma_f32 v70, -v70, v79, v78
	v_div_scale_f32 v78, s[0:1], v76, v76, 2.0
	v_rcp_f32_e32 v80, v78
	v_div_fmas_f32 v70, v70, v74, v79
	v_div_fixup_f32 v77, v70, v77, 2.0
	v_fma_f32 v70, -v78, v80, 1.0
	v_fmac_f32_e32 v80, v70, v80
	v_div_scale_f32 v70, vcc, 2.0, v76, 2.0
	v_mul_f32_e32 v74, v70, v80
	v_fma_f32 v79, -v78, v74, v70
	v_fmac_f32_e32 v74, v79, v80
	v_fma_f32 v70, -v78, v74, v70
	v_div_fmas_f32 v70, v70, v80, v74
	v_div_fixup_f32 v76, v70, v76, 2.0
	v_pk_add_f32 v[76:77], v[76:77], 1.0 op_sel_hi:[1,0] neg_lo:[1,0] neg_hi:[1,0]
	v_mov_b32_e32 v70, v75
	v_pk_mul_f32 v[70:71], v[70:71], 0.5 op_sel_hi:[1,0]
	v_pk_add_f32 v[74:75], v[76:77], 1.0 op_sel_hi:[1,0]
	v_mul_f32_e32 v77, 0x3d372713, v67
	v_pk_mul_f32 v[70:71], v[70:71], v[74:75]
	v_mul_f32_e32 v75, 0x3d372713, v65
	v_mul_f32_e32 v75, v65, v75
	v_fma_f32 v75, v65, v75, v65
	v_mul_f32_e32 v75, 0x3f4c422a, v75
	v_add_f32_e32 v75, v75, v75
	v_mul_f32_e32 v75, 0x3fb8aa3b, v75
	v_mul_f32_e32 v74, 0x3d372713, v64
	v_exp_f32_e32 v76, v75
	v_mul_f32_e32 v75, 0x3d372713, v66
	v_mul_f32_e32 v74, v64, v74
	v_mul_f32_e32 v75, v66, v75
	v_fma_f32 v74, v64, v74, v64
	v_fma_f32 v75, v66, v75, v66
	v_mul_f32_e32 v74, 0x3f4c422a, v74
	v_mul_f32_e32 v75, 0x3f4c422a, v75
	v_add_f32_e32 v74, v74, v74
	v_add_f32_e32 v75, v75, v75
	v_mul_f32_e32 v74, 0x3fb8aa3b, v74
	v_mul_f32_e32 v75, 0x3fb8aa3b, v75
	v_exp_f32_e32 v74, v74
	v_exp_f32_e32 v75, v75
	v_mul_f32_e32 v77, v67, v77
	v_fma_f32 v77, v67, v77, v67
	v_mul_f32_e32 v77, 0x3f4c422a, v77
	v_pk_add_f32 v[74:75], v[74:75], 1.0 op_sel_hi:[1,0]
	v_add_f32_e32 v77, v77, v77
	v_div_scale_f32 v78, s[0:1], v75, v75, 2.0
	v_rcp_f32_e32 v79, v78
	v_mul_f32_e32 v77, 0x3fb8aa3b, v77
	v_exp_f32_e32 v77, v77
	v_fma_f32 v80, -v78, v79, 1.0
	v_fmac_f32_e32 v79, v80, v79
	v_div_scale_f32 v80, vcc, 2.0, v75, 2.0
	v_mul_f32_e32 v81, v80, v79
	v_fma_f32 v82, -v78, v81, v80
	v_fmac_f32_e32 v81, v82, v79
	v_fma_f32 v78, -v78, v81, v80
	v_div_scale_f32 v80, s[0:1], v74, v74, 2.0
	v_rcp_f32_e32 v82, v80
	v_div_fmas_f32 v78, v78, v79, v81
	v_div_fixup_f32 v75, v78, v75, 2.0
	v_pk_add_f32 v[76:77], v[76:77], 1.0 op_sel_hi:[1,0]
	v_fma_f32 v78, -v80, v82, 1.0
	v_fmac_f32_e32 v82, v78, v82
	v_div_scale_f32 v78, vcc, 2.0, v74, 2.0
	v_mul_f32_e32 v79, v78, v82
	v_fma_f32 v81, -v80, v79, v78
	v_fmac_f32_e32 v79, v81, v82
	v_fma_f32 v78, -v80, v79, v78
	v_div_fmas_f32 v78, v78, v82, v79
	v_div_fixup_f32 v74, v78, v74, 2.0
	v_mov_b32_e32 v78, v64
	v_div_scale_f32 v64, s[0:1], v77, v77, 2.0
	v_mov_b32_e32 v79, v66
	v_rcp_f32_e32 v66, v64
	v_pk_add_f32 v[74:75], v[74:75], 1.0 op_sel_hi:[1,0] neg_lo:[1,0] neg_hi:[1,0]
	v_pk_mul_f32 v[78:79], v[78:79], 0.5 op_sel_hi:[1,0]
	v_pk_add_f32 v[74:75], v[74:75], 1.0 op_sel_hi:[1,0]
	s_nop 0
	v_pk_mul_f32 v[74:75], v[78:79], v[74:75]
	v_fma_f32 v78, -v64, v66, 1.0
	v_fmac_f32_e32 v66, v78, v66
	v_div_scale_f32 v78, vcc, 2.0, v77, 2.0
	v_mul_f32_e32 v79, v78, v66
	v_fma_f32 v80, -v64, v79, v78
	v_fmac_f32_e32 v79, v80, v66
	v_fma_f32 v64, -v64, v79, v78
	v_div_scale_f32 v78, s[0:1], v76, v76, 2.0
	v_rcp_f32_e32 v80, v78
	v_div_fmas_f32 v64, v64, v66, v79
	v_div_fixup_f32 v77, v64, v77, 2.0
	v_fma_f32 v64, -v78, v80, 1.0
	v_fmac_f32_e32 v80, v64, v80
	v_div_scale_f32 v64, vcc, 2.0, v76, 2.0
	v_mul_f32_e32 v66, v64, v80
	v_fma_f32 v79, -v78, v66, v64
	v_fmac_f32_e32 v66, v79, v80
	v_fma_f32 v64, -v78, v66, v64
	v_div_fmas_f32 v64, v64, v80, v66
	v_div_fixup_f32 v76, v64, v76, 2.0
	v_pk_add_f32 v[76:77], v[76:77], 1.0 op_sel_hi:[1,0] neg_lo:[1,0] neg_hi:[1,0]
	v_mov_b32_e32 v66, v65
	v_pk_mul_f32 v[64:65], v[66:67], 0.5 op_sel_hi:[1,0]
	v_pk_add_f32 v[66:67], v[76:77], 1.0 op_sel_hi:[1,0]
	v_pk_mul_f32 v[64:65], v[64:65], v[66:67]
	v_cvt_pk_bf16_f32 v67, v75, v65
	v_cvt_pk_bf16_f32 v66, v74, v64
	v_cvt_pk_bf16_f32 v65, v69, v71
	v_cvt_pk_bf16_f32 v64, v68, v70
	global_store_dwordx4 v[72:73], v[64:67], off offset:256
	global_load_dwordx4 v[64:67], v[140:141], off
	s_nop 0
	global_load_dwordx4 v[68:71], v[140:141], off offset:16
	s_waitcnt vmcnt(1)
; __device__ __forceinline__ unsigned pk2_(float lo, float hi) { return f2bf_(lo) | (f2bf_(hi) << 16); }
; template <int ACT> __device__ __forceinline__ float act_f(float v) {
;     ...
;     if (ACT == 3) { const float u = 0.7978845608028654f * (v + 0.044715f * v * v * v); const float e = __expf(2.f * u); const float th = 1.f - 2.f / (e + 1.f); return 0.5f * v * (1.f + th); }
;     __device__ __forceinline__ void operator()(const f32x4 (&acc)[2][2][4][2], const Unit& u, int wr, int wc, int fr, int fq) const {
;     ...
;             for (int m = 0; m < 4; ++m) { bf16_t* rowp = O + (size_t)(row0 + ai * HALF + m * 16) * ldc + col0;
; #pragma unroll
;                 for (int bj = 0; bj < 2; ++bj) { f32x4 v0 = acc[ai][bj][m][0], v1 = acc[ai][bj][m][1];
;                     if (bias) { v0 += *(const f32x4*)(bias + col0 + bj * HALF); v1 += *(const f32x4*)(bias + col0 + bj * HALF + 4); }
;                     u32x4 w; w.x = pk2_(act_f<ACT>(v0[0]), act_f<ACT>(v0[1])); w.y = pk2_(act_f<ACT>(v0[2]), act_f<ACT>(v0[3]));
;                     w.z = pk2_(act_f<ACT>(v1[0]), act_f<ACT>(v1[1])); w.w = pk2_(act_f<ACT>(v1[2]), act_f<ACT>(v1[3]));
;                     *(u32x4*)(rowp + bj * HALF) = w; } }
	v_pk_add_f32 v[64:65], v[60:61], v[64:65]
	s_nop 0
	v_mul_f32_e32 v61, 0x3d372713, v65
	v_mul_f32_e32 v61, v65, v61
	v_fma_f32 v61, v65, v61, v65
	v_mul_f32_e32 v61, 0x3f4c422a, v61
	v_add_f32_e32 v61, v61, v61
	v_pk_add_f32 v[62:63], v[62:63], v[66:67]
	v_mul_f32_e32 v61, 0x3fb8aa3b, v61
	v_mul_f32_e32 v60, 0x3d372713, v64
	v_exp_f32_e32 v66, v61
	v_mul_f32_e32 v61, 0x3d372713, v62
	v_mul_f32_e32 v60, v64, v60
	v_mul_f32_e32 v61, v62, v61
	v_fma_f32 v60, v64, v60, v64
	v_fma_f32 v61, v62, v61, v62
	v_mul_f32_e32 v60, 0x3f4c422a, v60
	v_mul_f32_e32 v61, 0x3f4c422a, v61
	v_add_f32_e32 v60, v60, v60
	v_add_f32_e32 v61, v61, v61
	v_mul_f32_e32 v60, 0x3fb8aa3b, v60
	v_mul_f32_e32 v61, 0x3fb8aa3b, v61
	v_exp_f32_e32 v60, v60
	v_exp_f32_e32 v61, v61
	s_waitcnt vmcnt(0)
	v_pk_add_f32 v[56:57], v[56:57], v[68:69]
	v_pk_add_f32 v[58:59], v[58:59], v[70:71]
	v_mul_f32_e32 v67, 0x3d372713, v63
	v_pk_add_f32 v[60:61], v[60:61], 1.0 op_sel_hi:[1,0]
	v_mul_f32_e32 v67, v63, v67
	v_div_scale_f32 v68, s[0:1], v61, v61, 2.0
	v_rcp_f32_e32 v69, v68
	v_fma_f32 v67, v63, v67, v63
	v_mul_f32_e32 v67, 0x3f4c422a, v67
	v_add_f32_e32 v67, v67, v67
	v_fma_f32 v70, -v68, v69, 1.0
	v_fmac_f32_e32 v69, v70, v69
	v_div_scale_f32 v70, vcc, 2.0, v61, 2.0
	v_mul_f32_e32 v71, v70, v69
	v_fma_f32 v72, -v68, v71, v70
	v_fmac_f32_e32 v71, v72, v69
	v_fma_f32 v68, -v68, v71, v70
	v_div_scale_f32 v70, s[0:1], v60, v60, 2.0
	v_rcp_f32_e32 v72, v70
	v_div_fmas_f32 v68, v68, v69, v71
	v_mul_f32_e32 v67, 0x3fb8aa3b, v67
	v_div_fixup_f32 v61, v68, v61, 2.0
	v_fma_f32 v68, -v70, v72, 1.0
	v_exp_f32_e32 v67, v67
	v_fmac_f32_e32 v72, v68, v72
	v_div_scale_f32 v68, vcc, 2.0, v60, 2.0
	v_mul_f32_e32 v69, v68, v72
	v_fma_f32 v71, -v70, v69, v68
	v_fmac_f32_e32 v69, v71, v72
	v_fma_f32 v68, -v70, v69, v68
	v_pk_add_f32 v[66:67], v[66:67], 1.0 op_sel_hi:[1,0]
	v_div_fmas_f32 v68, v68, v72, v69
	v_mov_b32_e32 v69, v62
	v_div_scale_f32 v62, s[0:1], v67, v67, 2.0
	v_div_fixup_f32 v60, v68, v60, 2.0
	v_mov_b32_e32 v68, v64
	v_rcp_f32_e32 v64, v62
	v_pk_add_f32 v[60:61], v[60:61], 1.0 op_sel_hi:[1,0] neg_lo:[1,0] neg_hi:[1,0]
	v_pk_mul_f32 v[68:69], v[68:69], 0.5 op_sel_hi:[1,0]
	v_pk_add_f32 v[60:61], v[60:61], 1.0 op_sel_hi:[1,0]
	s_nop 0
	v_pk_mul_f32 v[60:61], v[68:69], v[60:61]
	v_fma_f32 v68, -v62, v64, 1.0
	v_fmac_f32_e32 v64, v68, v64
	v_div_scale_f32 v68, vcc, 2.0, v67, 2.0
	v_mul_f32_e32 v69, v68, v64
	v_fma_f32 v70, -v62, v69, v68
	v_fmac_f32_e32 v69, v70, v64
	v_fma_f32 v62, -v62, v69, v68
	v_div_scale_f32 v68, s[0:1], v66, v66, 2.0
	v_rcp_f32_e32 v70, v68
	v_div_fmas_f32 v62, v62, v64, v69
	v_div_fixup_f32 v67, v62, v67, 2.0
	v_fma_f32 v62, -v68, v70, 1.0
	v_fmac_f32_e32 v70, v62, v70
	v_div_scale_f32 v62, vcc, 2.0, v66, 2.0
	v_mul_f32_e32 v64, v62, v70
	v_fma_f32 v69, -v68, v64, v62
	v_fmac_f32_e32 v64, v69, v70
	v_fma_f32 v62, -v68, v64, v62
	v_div_fmas_f32 v62, v62, v70, v64
	v_div_fixup_f32 v66, v62, v66, 2.0
	v_pk_add_f32 v[66:67], v[66:67], 1.0 op_sel_hi:[1,0] neg_lo:[1,0] neg_hi:[1,0]
	v_mov_b32_e32 v62, v65
	v_pk_mul_f32 v[62:63], v[62:63], 0.5 op_sel_hi:[1,0]
	v_pk_add_f32 v[64:65], v[66:67], 1.0 op_sel_hi:[1,0]
	v_mul_f32_e32 v67, 0x3d372713, v59
	v_pk_mul_f32 v[62:63], v[62:63], v[64:65]
	v_mul_f32_e32 v65, 0x3d372713, v57
	v_mul_f32_e32 v65, v57, v65
	v_fma_f32 v65, v57, v65, v57
	v_mul_f32_e32 v65, 0x3f4c422a, v65
	v_add_f32_e32 v65, v65, v65
	v_mul_f32_e32 v65, 0x3fb8aa3b, v65
	v_mul_f32_e32 v64, 0x3d372713, v56
	v_exp_f32_e32 v66, v65
	v_mul_f32_e32 v65, 0x3d372713, v58
	v_mul_f32_e32 v64, v56, v64
	v_mul_f32_e32 v65, v58, v65
	v_fma_f32 v64, v56, v64, v56
	v_fma_f32 v65, v58, v65, v58
	v_mul_f32_e32 v64, 0x3f4c422a, v64
	v_mul_f32_e32 v65, 0x3f4c422a, v65
	v_add_f32_e32 v64, v64, v64
	v_add_f32_e32 v65, v65, v65
	v_mul_f32_e32 v64, 0x3fb8aa3b, v64
	v_mul_f32_e32 v65, 0x3fb8aa3b, v65
	v_exp_f32_e32 v64, v64
	v_exp_f32_e32 v65, v65
	v_mul_f32_e32 v67, v59, v67
	v_fma_f32 v67, v59, v67, v59
	v_mul_f32_e32 v67, 0x3f4c422a, v67
	v_pk_add_f32 v[64:65], v[64:65], 1.0 op_sel_hi:[1,0]
	v_add_f32_e32 v67, v67, v67
	v_div_scale_f32 v68, s[0:1], v65, v65, 2.0
	v_rcp_f32_e32 v69, v68
	v_mul_f32_e32 v67, 0x3fb8aa3b, v67
	v_exp_f32_e32 v67, v67
	v_fma_f32 v70, -v68, v69, 1.0
	v_fmac_f32_e32 v69, v70, v69
	v_div_scale_f32 v70, vcc, 2.0, v65, 2.0
	v_mul_f32_e32 v71, v70, v69
	v_fma_f32 v72, -v68, v71, v70
	v_fmac_f32_e32 v71, v72, v69
	v_fma_f32 v68, -v68, v71, v70
	v_div_scale_f32 v70, s[0:1], v64, v64, 2.0
	v_rcp_f32_e32 v72, v70
	v_div_fmas_f32 v68, v68, v69, v71
	v_div_fixup_f32 v65, v68, v65, 2.0
	v_pk_add_f32 v[66:67], v[66:67], 1.0 op_sel_hi:[1,0]
	v_fma_f32 v68, -v70, v72, 1.0
	v_fmac_f32_e32 v72, v68, v72
	v_div_scale_f32 v68, vcc, 2.0, v64, 2.0
	v_mul_f32_e32 v69, v68, v72
	v_fma_f32 v71, -v70, v69, v68
	v_fmac_f32_e32 v69, v71, v72
	v_fma_f32 v68, -v70, v69, v68
	v_div_fmas_f32 v68, v68, v72, v69
	v_div_fixup_f32 v64, v68, v64, 2.0
	v_mov_b32_e32 v68, v56
	v_div_scale_f32 v56, s[0:1], v67, v67, 2.0
	v_mov_b32_e32 v69, v58
	v_rcp_f32_e32 v58, v56
	v_pk_add_f32 v[64:65], v[64:65], 1.0 op_sel_hi:[1,0] neg_lo:[1,0] neg_hi:[1,0]
	v_pk_mul_f32 v[68:69], v[68:69], 0.5 op_sel_hi:[1,0]
	v_pk_add_f32 v[64:65], v[64:65], 1.0 op_sel_hi:[1,0]
	s_nop 0
	v_pk_mul_f32 v[64:65], v[68:69], v[64:65]
	v_fma_f32 v68, -v56, v58, 1.0
	v_fmac_f32_e32 v58, v68, v58
	v_div_scale_f32 v68, vcc, 2.0, v67, 2.0
	v_mul_f32_e32 v69, v68, v58
	v_fma_f32 v70, -v56, v69, v68
	v_fmac_f32_e32 v69, v70, v58
	v_fma_f32 v56, -v56, v69, v68
	v_div_scale_f32 v68, s[0:1], v66, v66, 2.0
	v_rcp_f32_e32 v70, v68
	v_div_fmas_f32 v56, v56, v58, v69
	v_div_fixup_f32 v67, v56, v67, 2.0
	s_mov_b32 s0, 0x10000
	v_fma_f32 v56, -v68, v70, 1.0
	v_fmac_f32_e32 v70, v56, v70
	v_div_scale_f32 v56, vcc, 2.0, v66, 2.0
	v_mul_f32_e32 v58, v56, v70
	v_fma_f32 v69, -v68, v58, v56
	v_fmac_f32_e32 v58, v69, v70
	v_fma_f32 v56, -v68, v58, v56
	v_div_fmas_f32 v56, v56, v70, v58
	v_div_fixup_f32 v66, v56, v66, 2.0
	v_pk_add_f32 v[66:67], v[66:67], 1.0 op_sel_hi:[1,0] neg_lo:[1,0] neg_hi:[1,0]
	v_mov_b32_e32 v58, v57
	v_pk_mul_f32 v[56:57], v[58:59], 0.5 op_sel_hi:[1,0]
	v_pk_add_f32 v[58:59], v[66:67], 1.0 op_sel_hi:[1,0]
	v_pk_mul_f32 v[56:57], v[56:57], v[58:59]
	v_cvt_pk_bf16_f32 v58, v64, v56
	v_cvt_pk_bf16_f32 v56, v60, v62
	v_add_co_u32_e32 v60, vcc, s0, v142
	v_cvt_pk_bf16_f32 v59, v65, v57
	v_cvt_pk_bf16_f32 v57, v61, v63
	v_addc_co_u32_e32 v61, vcc, 0, v143, vcc
	global_store_dwordx4 v[60:61], v[56:59], off
	global_load_dwordx4 v[58:61], v[140:141], off offset:512
	s_nop 0
	global_load_dwordx4 v[62:65], v[140:141], off offset:528
	s_mov_b64 s[0:1], 0x10000
	v_lshl_add_u64 v[56:57], v[142:143], 0, s[0:1]
	s_waitcnt vmcnt(1)
; __device__ __forceinline__ unsigned pk2_(float lo, float hi) { return f2bf_(lo) | (f2bf_(hi) << 16); }
; template <int ACT> __device__ __forceinline__ float act_f(float v) {
;     ...
;     if (ACT == 3) { const float u = 0.7978845608028654f * (v + 0.044715f * v * v * v); const float e = __expf(2.f * u); const float th = 1.f - 2.f / (e + 1.f); return 0.5f * v * (1.f + th); }
;     __device__ __forceinline__ void operator()(const f32x4 (&acc)[2][2][4][2], const Unit& u, int wr, int wc, int fr, int fq) const {
;     ...
;             for (int m = 0; m < 4; ++m) { bf16_t* rowp = O + (size_t)(row0 + ai * HALF + m * 16) * ldc + col0;
; #pragma unroll
;                 for (int bj = 0; bj < 2; ++bj) { f32x4 v0 = acc[ai][bj][m][0], v1 = acc[ai][bj][m][1];
;                     if (bias) { v0 += *(const f32x4*)(bias + col0 + bj * HALF); v1 += *(const f32x4*)(bias + col0 + bj * HALF + 4); }
;                     u32x4 w; w.x = pk2_(act_f<ACT>(v0[0]), act_f<ACT>(v0[1])); w.y = pk2_(act_f<ACT>(v0[2]), act_f<ACT>(v0[3]));
;                     w.z = pk2_(act_f<ACT>(v1[0]), act_f<ACT>(v1[1])); w.w = pk2_(act_f<ACT>(v1[2]), act_f<ACT>(v1[3]));
;                     *(u32x4*)(rowp + bj * HALF) = w; } }
	v_pk_add_f32 v[58:59], v[52:53], v[58:59]
	s_nop 0
	v_mul_f32_e32 v53, 0x3d372713, v59
	v_mul_f32_e32 v53, v59, v53
	v_fma_f32 v53, v59, v53, v59
	v_mul_f32_e32 v53, 0x3f4c422a, v53
	v_add_f32_e32 v53, v53, v53
	v_pk_add_f32 v[54:55], v[54:55], v[60:61]
	v_mul_f32_e32 v53, 0x3fb8aa3b, v53
	v_mul_f32_e32 v52, 0x3d372713, v58
	v_exp_f32_e32 v60, v53
	v_mul_f32_e32 v53, 0x3d372713, v54
	v_mul_f32_e32 v52, v58, v52
	v_mul_f32_e32 v53, v54, v53
	v_fma_f32 v52, v58, v52, v58
	v_fma_f32 v53, v54, v53, v54
	v_mul_f32_e32 v52, 0x3f4c422a, v52
	v_mul_f32_e32 v53, 0x3f4c422a, v53
	v_add_f32_e32 v52, v52, v52
	v_add_f32_e32 v53, v53, v53
	v_mul_f32_e32 v52, 0x3fb8aa3b, v52
	v_mul_f32_e32 v53, 0x3fb8aa3b, v53
	v_exp_f32_e32 v52, v52
	v_exp_f32_e32 v53, v53
	s_waitcnt vmcnt(0)
	v_pk_add_f32 v[48:49], v[48:49], v[62:63]
	v_pk_add_f32 v[50:51], v[50:51], v[64:65]
	v_mul_f32_e32 v61, 0x3d372713, v55
	v_pk_add_f32 v[52:53], v[52:53], 1.0 op_sel_hi:[1,0]
	v_mul_f32_e32 v61, v55, v61
	v_div_scale_f32 v62, s[0:1], v53, v53, 2.0
	v_rcp_f32_e32 v63, v62
	v_fma_f32 v61, v55, v61, v55
	v_mul_f32_e32 v61, 0x3f4c422a, v61
	v_add_f32_e32 v61, v61, v61
	v_fma_f32 v64, -v62, v63, 1.0
	v_fmac_f32_e32 v63, v64, v63
	v_div_scale_f32 v64, vcc, 2.0, v53, 2.0
	v_mul_f32_e32 v65, v64, v63
	v_fma_f32 v66, -v62, v65, v64
	v_fmac_f32_e32 v65, v66, v63
	v_fma_f32 v62, -v62, v65, v64
	v_div_scale_f32 v64, s[0:1], v52, v52, 2.0
	v_rcp_f32_e32 v66, v64
	v_div_fmas_f32 v62, v62, v63, v65
	v_mul_f32_e32 v61, 0x3fb8aa3b, v61
	v_div_fixup_f32 v53, v62, v53, 2.0
	v_fma_f32 v62, -v64, v66, 1.0
	v_exp_f32_e32 v61, v61
	v_fmac_f32_e32 v66, v62, v66
	v_div_scale_f32 v62, vcc, 2.0, v52, 2.0
	v_mul_f32_e32 v63, v62, v66
	v_fma_f32 v65, -v64, v63, v62
	v_fmac_f32_e32 v63, v65, v66
	v_fma_f32 v62, -v64, v63, v62
	v_pk_add_f32 v[60:61], v[60:61], 1.0 op_sel_hi:[1,0]
	v_div_fmas_f32 v62, v62, v66, v63
	v_mov_b32_e32 v63, v54
	v_div_scale_f32 v54, s[0:1], v61, v61, 2.0
	v_div_fixup_f32 v52, v62, v52, 2.0
	v_mov_b32_e32 v62, v58
	v_rcp_f32_e32 v58, v54
	v_pk_add_f32 v[52:53], v[52:53], 1.0 op_sel_hi:[1,0] neg_lo:[1,0] neg_hi:[1,0]
	v_pk_mul_f32 v[62:63], v[62:63], 0.5 op_sel_hi:[1,0]
	v_pk_add_f32 v[52:53], v[52:53], 1.0 op_sel_hi:[1,0]
	s_nop 0
	v_pk_mul_f32 v[52:53], v[62:63], v[52:53]
	v_fma_f32 v62, -v54, v58, 1.0
	v_fmac_f32_e32 v58, v62, v58
	v_div_scale_f32 v62, vcc, 2.0, v61, 2.0
	v_mul_f32_e32 v63, v62, v58
	v_fma_f32 v64, -v54, v63, v62
	v_fmac_f32_e32 v63, v64, v58
	v_fma_f32 v54, -v54, v63, v62
	v_div_scale_f32 v62, s[0:1], v60, v60, 2.0
	v_rcp_f32_e32 v64, v62
	v_div_fmas_f32 v54, v54, v58, v63
	v_div_fixup_f32 v61, v54, v61, 2.0
	v_fma_f32 v54, -v62, v64, 1.0
	v_fmac_f32_e32 v64, v54, v64
	v_div_scale_f32 v54, vcc, 2.0, v60, 2.0
	v_mul_f32_e32 v58, v54, v64
	v_fma_f32 v63, -v62, v58, v54
	v_fmac_f32_e32 v58, v63, v64
	v_fma_f32 v54, -v62, v58, v54
	v_div_fmas_f32 v54, v54, v64, v58
	v_div_fixup_f32 v60, v54, v60, 2.0
	v_pk_add_f32 v[60:61], v[60:61], 1.0 op_sel_hi:[1,0] neg_lo:[1,0] neg_hi:[1,0]
	v_mov_b32_e32 v54, v59
	v_pk_mul_f32 v[54:55], v[54:55], 0.5 op_sel_hi:[1,0]
	v_pk_add_f32 v[58:59], v[60:61], 1.0 op_sel_hi:[1,0]
	v_mul_f32_e32 v61, 0x3d372713, v51
	v_pk_mul_f32 v[54:55], v[54:55], v[58:59]
	v_mul_f32_e32 v59, 0x3d372713, v49
	v_mul_f32_e32 v59, v49, v59
	v_fma_f32 v59, v49, v59, v49
	v_mul_f32_e32 v59, 0x3f4c422a, v59
	v_add_f32_e32 v59, v59, v59
	v_mul_f32_e32 v59, 0x3fb8aa3b, v59
	v_mul_f32_e32 v58, 0x3d372713, v48
	v_exp_f32_e32 v60, v59
	v_mul_f32_e32 v59, 0x3d372713, v50
	v_mul_f32_e32 v58, v48, v58
	v_mul_f32_e32 v59, v50, v59
	v_fma_f32 v58, v48, v58, v48
	v_fma_f32 v59, v50, v59, v50
	v_mul_f32_e32 v58, 0x3f4c422a, v58
	v_mul_f32_e32 v59, 0x3f4c422a, v59
	v_add_f32_e32 v58, v58, v58
	v_add_f32_e32 v59, v59, v59
	v_mul_f32_e32 v58, 0x3fb8aa3b, v58
	v_mul_f32_e32 v59, 0x3fb8aa3b, v59
	v_exp_f32_e32 v58, v58
	v_exp_f32_e32 v59, v59
	v_mul_f32_e32 v61, v51, v61
	v_fma_f32 v61, v51, v61, v51
	v_mul_f32_e32 v61, 0x3f4c422a, v61
	v_pk_add_f32 v[58:59], v[58:59], 1.0 op_sel_hi:[1,0]
	v_add_f32_e32 v61, v61, v61
	v_div_scale_f32 v62, s[0:1], v59, v59, 2.0
	v_rcp_f32_e32 v63, v62
	v_mul_f32_e32 v61, 0x3fb8aa3b, v61
	v_exp_f32_e32 v61, v61
	v_fma_f32 v64, -v62, v63, 1.0
	v_fmac_f32_e32 v63, v64, v63
	v_div_scale_f32 v64, vcc, 2.0, v59, 2.0
	v_mul_f32_e32 v65, v64, v63
	v_fma_f32 v66, -v62, v65, v64
	v_fmac_f32_e32 v65, v66, v63
	v_fma_f32 v62, -v62, v65, v64
	v_div_scale_f32 v64, s[0:1], v58, v58, 2.0
	v_rcp_f32_e32 v66, v64
	v_div_fmas_f32 v62, v62, v63, v65
	v_div_fixup_f32 v59, v62, v59, 2.0
	v_pk_add_f32 v[60:61], v[60:61], 1.0 op_sel_hi:[1,0]
	v_fma_f32 v62, -v64, v66, 1.0
	v_fmac_f32_e32 v66, v62, v66
	v_div_scale_f32 v62, vcc, 2.0, v58, 2.0
	v_mul_f32_e32 v63, v62, v66
	v_fma_f32 v65, -v64, v63, v62
	v_fmac_f32_e32 v63, v65, v66
	v_fma_f32 v62, -v64, v63, v62
	v_div_fmas_f32 v62, v62, v66, v63
	v_div_fixup_f32 v58, v62, v58, 2.0
	v_mov_b32_e32 v62, v48
	v_div_scale_f32 v48, s[0:1], v61, v61, 2.0
	v_mov_b32_e32 v63, v50
	v_rcp_f32_e32 v50, v48
	v_pk_add_f32 v[58:59], v[58:59], 1.0 op_sel_hi:[1,0] neg_lo:[1,0] neg_hi:[1,0]
	v_pk_mul_f32 v[62:63], v[62:63], 0.5 op_sel_hi:[1,0]
	v_pk_add_f32 v[58:59], v[58:59], 1.0 op_sel_hi:[1,0]
	s_nop 0
	v_pk_mul_f32 v[58:59], v[62:63], v[58:59]
	v_fma_f32 v62, -v48, v50, 1.0
	v_fmac_f32_e32 v50, v62, v50
	v_div_scale_f32 v62, vcc, 2.0, v61, 2.0
	v_mul_f32_e32 v63, v62, v50
	v_fma_f32 v64, -v48, v63, v62
	v_fmac_f32_e32 v63, v64, v50
	v_fma_f32 v48, -v48, v63, v62
	v_div_scale_f32 v62, s[0:1], v60, v60, 2.0
	v_rcp_f32_e32 v64, v62
	v_div_fmas_f32 v48, v48, v50, v63
	v_div_fixup_f32 v61, v48, v61, 2.0
	v_fma_f32 v48, -v62, v64, 1.0
	v_fmac_f32_e32 v64, v48, v64
	v_div_scale_f32 v48, vcc, 2.0, v60, 2.0
	v_mul_f32_e32 v50, v48, v64
	v_fma_f32 v63, -v62, v50, v48
	v_fmac_f32_e32 v50, v63, v64
	v_fma_f32 v48, -v62, v50, v48
	v_div_fmas_f32 v48, v48, v64, v50
	v_div_fixup_f32 v60, v48, v60, 2.0
	v_pk_add_f32 v[60:61], v[60:61], 1.0 op_sel_hi:[1,0] neg_lo:[1,0] neg_hi:[1,0]
	v_mov_b32_e32 v50, v49
	v_pk_mul_f32 v[48:49], v[50:51], 0.5 op_sel_hi:[1,0]
	v_pk_add_f32 v[50:51], v[60:61], 1.0 op_sel_hi:[1,0]
	v_pk_mul_f32 v[48:49], v[48:49], v[50:51]
	v_cvt_pk_bf16_f32 v51, v59, v49
	v_cvt_pk_bf16_f32 v50, v58, v48
	v_cvt_pk_bf16_f32 v49, v53, v55
	v_cvt_pk_bf16_f32 v48, v52, v54
	global_store_dwordx4 v[56:57], v[48:51], off offset:256
	global_load_dwordx4 v[48:51], v[140:141], off
	s_nop 0
	global_load_dwordx4 v[52:55], v[140:141], off offset:16
	s_waitcnt vmcnt(1)
; __device__ __forceinline__ unsigned pk2_(float lo, float hi) { return f2bf_(lo) | (f2bf_(hi) << 16); }
; template <int ACT> __device__ __forceinline__ float act_f(float v) {
;     ...
;     if (ACT == 3) { const float u = 0.7978845608028654f * (v + 0.044715f * v * v * v); const float e = __expf(2.f * u); const float th = 1.f - 2.f / (e + 1.f); return 0.5f * v * (1.f + th); }
;     __device__ __forceinline__ void operator()(const f32x4 (&acc)[2][2][4][2], const Unit& u, int wr, int wc, int fr, int fq) const {
;     ...
;             for (int m = 0; m < 4; ++m) { bf16_t* rowp = O + (size_t)(row0 + ai * HALF + m * 16) * ldc + col0;
; #pragma unroll
;                 for (int bj = 0; bj < 2; ++bj) { f32x4 v0 = acc[ai][bj][m][0], v1 = acc[ai][bj][m][1];
;                     if (bias) { v0 += *(const f32x4*)(bias + col0 + bj * HALF); v1 += *(const f32x4*)(bias + col0 + bj * HALF + 4); }
;                     u32x4 w; w.x = pk2_(act_f<ACT>(v0[0]), act_f<ACT>(v0[1])); w.y = pk2_(act_f<ACT>(v0[2]), act_f<ACT>(v0[3]));
;                     w.z = pk2_(act_f<ACT>(v1[0]), act_f<ACT>(v1[1])); w.w = pk2_(act_f<ACT>(v1[2]), act_f<ACT>(v1[3]));
;                     *(u32x4*)(rowp + bj * HALF) = w; } }
	v_pk_add_f32 v[48:49], v[44:45], v[48:49]
	s_nop 0
	v_mul_f32_e32 v45, 0x3d372713, v49
	v_mul_f32_e32 v45, v49, v45
	v_fma_f32 v45, v49, v45, v49
	v_mul_f32_e32 v45, 0x3f4c422a, v45
	v_add_f32_e32 v45, v45, v45
	v_pk_add_f32 v[46:47], v[46:47], v[50:51]
	v_mul_f32_e32 v45, 0x3fb8aa3b, v45
	v_mul_f32_e32 v44, 0x3d372713, v48
	v_exp_f32_e32 v50, v45
	v_mul_f32_e32 v45, 0x3d372713, v46
	v_mul_f32_e32 v44, v48, v44
	v_mul_f32_e32 v45, v46, v45
	v_fma_f32 v44, v48, v44, v48
	v_fma_f32 v45, v46, v45, v46
	v_mul_f32_e32 v44, 0x3f4c422a, v44
	v_mul_f32_e32 v45, 0x3f4c422a, v45
	v_add_f32_e32 v44, v44, v44
	v_add_f32_e32 v45, v45, v45
	v_mul_f32_e32 v44, 0x3fb8aa3b, v44
	v_mul_f32_e32 v45, 0x3fb8aa3b, v45
	v_exp_f32_e32 v44, v44
	v_exp_f32_e32 v45, v45
	s_waitcnt vmcnt(0)
	v_pk_add_f32 v[40:41], v[40:41], v[52:53]
	v_pk_add_f32 v[42:43], v[42:43], v[54:55]
	v_mul_f32_e32 v51, 0x3d372713, v47
	v_pk_add_f32 v[44:45], v[44:45], 1.0 op_sel_hi:[1,0]
	v_mul_f32_e32 v51, v47, v51
	v_div_scale_f32 v52, s[0:1], v45, v45, 2.0
	v_rcp_f32_e32 v53, v52
	v_fma_f32 v51, v47, v51, v47
	v_mul_f32_e32 v51, 0x3f4c422a, v51
	v_add_f32_e32 v51, v51, v51
	v_fma_f32 v54, -v52, v53, 1.0
	v_fmac_f32_e32 v53, v54, v53
	v_div_scale_f32 v54, vcc, 2.0, v45, 2.0
	v_mul_f32_e32 v55, v54, v53
	v_fma_f32 v56, -v52, v55, v54
	v_fmac_f32_e32 v55, v56, v53
	v_fma_f32 v52, -v52, v55, v54
	v_div_scale_f32 v54, s[0:1], v44, v44, 2.0
	v_rcp_f32_e32 v56, v54
	v_div_fmas_f32 v52, v52, v53, v55
	v_mul_f32_e32 v51, 0x3fb8aa3b, v51
	v_div_fixup_f32 v45, v52, v45, 2.0
	v_fma_f32 v52, -v54, v56, 1.0
	v_exp_f32_e32 v51, v51
	v_fmac_f32_e32 v56, v52, v56
	v_div_scale_f32 v52, vcc, 2.0, v44, 2.0
	v_mul_f32_e32 v53, v52, v56
	v_fma_f32 v55, -v54, v53, v52
	v_fmac_f32_e32 v53, v55, v56
	v_fma_f32 v52, -v54, v53, v52
	v_pk_add_f32 v[50:51], v[50:51], 1.0 op_sel_hi:[1,0]
	v_div_fmas_f32 v52, v52, v56, v53
	v_mov_b32_e32 v53, v46
	v_div_scale_f32 v46, s[0:1], v51, v51, 2.0
	v_div_fixup_f32 v44, v52, v44, 2.0
	v_mov_b32_e32 v52, v48
	v_rcp_f32_e32 v48, v46
	v_pk_add_f32 v[44:45], v[44:45], 1.0 op_sel_hi:[1,0] neg_lo:[1,0] neg_hi:[1,0]
	v_pk_mul_f32 v[52:53], v[52:53], 0.5 op_sel_hi:[1,0]
	v_pk_add_f32 v[44:45], v[44:45], 1.0 op_sel_hi:[1,0]
	s_nop 0
	v_pk_mul_f32 v[44:45], v[52:53], v[44:45]
	v_fma_f32 v52, -v46, v48, 1.0
	v_fmac_f32_e32 v48, v52, v48
	v_div_scale_f32 v52, vcc, 2.0, v51, 2.0
	v_mul_f32_e32 v53, v52, v48
	v_fma_f32 v54, -v46, v53, v52
	v_fmac_f32_e32 v53, v54, v48
	v_fma_f32 v46, -v46, v53, v52
	v_div_scale_f32 v52, s[0:1], v50, v50, 2.0
	v_rcp_f32_e32 v54, v52
	v_div_fmas_f32 v46, v46, v48, v53
	v_div_fixup_f32 v51, v46, v51, 2.0
	v_fma_f32 v46, -v52, v54, 1.0
	v_fmac_f32_e32 v54, v46, v54
	v_div_scale_f32 v46, vcc, 2.0, v50, 2.0
	v_mul_f32_e32 v48, v46, v54
	v_fma_f32 v53, -v52, v48, v46
	v_fmac_f32_e32 v48, v53, v54
	v_fma_f32 v46, -v52, v48, v46
	v_div_fmas_f32 v46, v46, v54, v48
	v_div_fixup_f32 v50, v46, v50, 2.0
	v_pk_add_f32 v[50:51], v[50:51], 1.0 op_sel_hi:[1,0] neg_lo:[1,0] neg_hi:[1,0]
	v_mov_b32_e32 v46, v49
	v_pk_mul_f32 v[46:47], v[46:47], 0.5 op_sel_hi:[1,0]
	v_pk_add_f32 v[48:49], v[50:51], 1.0 op_sel_hi:[1,0]
	v_mul_f32_e32 v51, 0x3d372713, v43
	v_pk_mul_f32 v[46:47], v[46:47], v[48:49]
	v_mul_f32_e32 v49, 0x3d372713, v41
	v_mul_f32_e32 v49, v41, v49
	v_fma_f32 v49, v41, v49, v41
	v_mul_f32_e32 v49, 0x3f4c422a, v49
	v_add_f32_e32 v49, v49, v49
	v_mul_f32_e32 v49, 0x3fb8aa3b, v49
	v_mul_f32_e32 v48, 0x3d372713, v40
	v_exp_f32_e32 v50, v49
	v_mul_f32_e32 v49, 0x3d372713, v42
	v_mul_f32_e32 v48, v40, v48
	v_mul_f32_e32 v49, v42, v49
	v_fma_f32 v48, v40, v48, v40
	v_fma_f32 v49, v42, v49, v42
	v_mul_f32_e32 v48, 0x3f4c422a, v48
	v_mul_f32_e32 v49, 0x3f4c422a, v49
	v_add_f32_e32 v48, v48, v48
	v_add_f32_e32 v49, v49, v49
	v_mul_f32_e32 v48, 0x3fb8aa3b, v48
	v_mul_f32_e32 v49, 0x3fb8aa3b, v49
	v_exp_f32_e32 v48, v48
	v_exp_f32_e32 v49, v49
	v_mul_f32_e32 v51, v43, v51
	v_fma_f32 v51, v43, v51, v43
	v_mul_f32_e32 v51, 0x3f4c422a, v51
	v_pk_add_f32 v[48:49], v[48:49], 1.0 op_sel_hi:[1,0]
	v_add_f32_e32 v51, v51, v51
	v_div_scale_f32 v52, s[0:1], v49, v49, 2.0
	v_rcp_f32_e32 v53, v52
	v_mul_f32_e32 v51, 0x3fb8aa3b, v51
	v_exp_f32_e32 v51, v51
	v_fma_f32 v54, -v52, v53, 1.0
	v_fmac_f32_e32 v53, v54, v53
	v_div_scale_f32 v54, vcc, 2.0, v49, 2.0
	v_mul_f32_e32 v55, v54, v53
	v_fma_f32 v56, -v52, v55, v54
	v_fmac_f32_e32 v55, v56, v53
	v_fma_f32 v52, -v52, v55, v54
	v_div_scale_f32 v54, s[0:1], v48, v48, 2.0
	v_rcp_f32_e32 v56, v54
	v_div_fmas_f32 v52, v52, v53, v55
	v_div_fixup_f32 v49, v52, v49, 2.0
	v_pk_add_f32 v[50:51], v[50:51], 1.0 op_sel_hi:[1,0]
	v_fma_f32 v52, -v54, v56, 1.0
	v_fmac_f32_e32 v56, v52, v56
	v_div_scale_f32 v52, vcc, 2.0, v48, 2.0
	v_mul_f32_e32 v53, v52, v56
	v_fma_f32 v55, -v54, v53, v52
	v_fmac_f32_e32 v53, v55, v56
	v_fma_f32 v52, -v54, v53, v52
	v_div_fmas_f32 v52, v52, v56, v53
	v_div_fixup_f32 v48, v52, v48, 2.0
	v_mov_b32_e32 v52, v40
	v_div_scale_f32 v40, s[0:1], v51, v51, 2.0
	v_mov_b32_e32 v53, v42
	v_rcp_f32_e32 v42, v40
	v_pk_add_f32 v[48:49], v[48:49], 1.0 op_sel_hi:[1,0] neg_lo:[1,0] neg_hi:[1,0]
	v_pk_mul_f32 v[52:53], v[52:53], 0.5 op_sel_hi:[1,0]
	v_pk_add_f32 v[48:49], v[48:49], 1.0 op_sel_hi:[1,0]
	s_nop 0
	v_pk_mul_f32 v[48:49], v[52:53], v[48:49]
	v_fma_f32 v52, -v40, v42, 1.0
	v_fmac_f32_e32 v42, v52, v42
	v_div_scale_f32 v52, vcc, 2.0, v51, 2.0
	v_mul_f32_e32 v53, v52, v42
	v_fma_f32 v54, -v40, v53, v52
	v_fmac_f32_e32 v53, v54, v42
	v_fma_f32 v40, -v40, v53, v52
	v_div_scale_f32 v52, s[0:1], v50, v50, 2.0
	v_rcp_f32_e32 v54, v52
	v_div_fmas_f32 v40, v40, v42, v53
	v_div_fixup_f32 v51, v40, v51, 2.0
	s_mov_b32 s0, 0x12000
	v_fma_f32 v40, -v52, v54, 1.0
	v_fmac_f32_e32 v54, v40, v54
	v_div_scale_f32 v40, vcc, 2.0, v50, 2.0
	v_mul_f32_e32 v42, v40, v54
	v_fma_f32 v53, -v52, v42, v40
	v_fmac_f32_e32 v42, v53, v54
	v_fma_f32 v40, -v52, v42, v40
	v_div_fmas_f32 v40, v40, v54, v42
	v_div_fixup_f32 v50, v40, v50, 2.0
	v_pk_add_f32 v[50:51], v[50:51], 1.0 op_sel_hi:[1,0] neg_lo:[1,0] neg_hi:[1,0]
	v_mov_b32_e32 v42, v41
	v_pk_mul_f32 v[40:41], v[42:43], 0.5 op_sel_hi:[1,0]
	v_pk_add_f32 v[42:43], v[50:51], 1.0 op_sel_hi:[1,0]
	v_pk_mul_f32 v[40:41], v[40:41], v[42:43]
	v_cvt_pk_bf16_f32 v42, v48, v40
	v_cvt_pk_bf16_f32 v40, v44, v46
	v_add_co_u32_e32 v44, vcc, s0, v142
	v_cvt_pk_bf16_f32 v43, v49, v41
	v_cvt_pk_bf16_f32 v41, v45, v47
	v_addc_co_u32_e32 v45, vcc, 0, v143, vcc
	global_store_dwordx4 v[44:45], v[40:43], off
	global_load_dwordx4 v[42:45], v[140:141], off offset:512
	s_nop 0
	global_load_dwordx4 v[46:49], v[140:141], off offset:528
	s_mov_b64 s[0:1], 0x12000
	v_lshl_add_u64 v[40:41], v[142:143], 0, s[0:1]
	s_waitcnt vmcnt(1)
; __device__ __forceinline__ unsigned pk2_(float lo, float hi) { return f2bf_(lo) | (f2bf_(hi) << 16); }
; template <int ACT> __device__ __forceinline__ float act_f(float v) {
;     ...
;     if (ACT == 3) { const float u = 0.7978845608028654f * (v + 0.044715f * v * v * v); const float e = __expf(2.f * u); const float th = 1.f - 2.f / (e + 1.f); return 0.5f * v * (1.f + th); }
;     __device__ __forceinline__ void operator()(const f32x4 (&acc)[2][2][4][2], const Unit& u, int wr, int wc, int fr, int fq) const {
;     ...
;             for (int m = 0; m < 4; ++m) { bf16_t* rowp = O + (size_t)(row0 + ai * HALF + m * 16) * ldc + col0;
; #pragma unroll
;                 for (int bj = 0; bj < 2; ++bj) { f32x4 v0 = acc[ai][bj][m][0], v1 = acc[ai][bj][m][1];
;                     if (bias) { v0 += *(const f32x4*)(bias + col0 + bj * HALF); v1 += *(const f32x4*)(bias + col0 + bj * HALF + 4); }
;                     u32x4 w; w.x = pk2_(act_f<ACT>(v0[0]), act_f<ACT>(v0[1])); w.y = pk2_(act_f<ACT>(v0[2]), act_f<ACT>(v0[3]));
;                     w.z = pk2_(act_f<ACT>(v1[0]), act_f<ACT>(v1[1])); w.w = pk2_(act_f<ACT>(v1[2]), act_f<ACT>(v1[3]));
;                     *(u32x4*)(rowp + bj * HALF) = w; } }
	v_pk_add_f32 v[42:43], v[36:37], v[42:43]
	s_nop 0
	v_mul_f32_e32 v37, 0x3d372713, v43
	v_mul_f32_e32 v37, v43, v37
	v_fma_f32 v37, v43, v37, v43
	v_mul_f32_e32 v37, 0x3f4c422a, v37
	v_add_f32_e32 v37, v37, v37
	v_pk_add_f32 v[38:39], v[38:39], v[44:45]
	v_mul_f32_e32 v37, 0x3fb8aa3b, v37
	v_mul_f32_e32 v36, 0x3d372713, v42
	v_exp_f32_e32 v44, v37
	v_mul_f32_e32 v37, 0x3d372713, v38
	v_mul_f32_e32 v36, v42, v36
	v_mul_f32_e32 v37, v38, v37
	v_fma_f32 v36, v42, v36, v42
	v_fma_f32 v37, v38, v37, v38
	v_mul_f32_e32 v36, 0x3f4c422a, v36
	v_mul_f32_e32 v37, 0x3f4c422a, v37
	v_add_f32_e32 v36, v36, v36
	v_add_f32_e32 v37, v37, v37
	v_mul_f32_e32 v36, 0x3fb8aa3b, v36
	v_mul_f32_e32 v37, 0x3fb8aa3b, v37
	v_exp_f32_e32 v36, v36
	v_exp_f32_e32 v37, v37
	s_waitcnt vmcnt(0)
	v_pk_add_f32 v[32:33], v[32:33], v[46:47]
	v_pk_add_f32 v[34:35], v[34:35], v[48:49]
	v_mul_f32_e32 v45, 0x3d372713, v39
	v_pk_add_f32 v[36:37], v[36:37], 1.0 op_sel_hi:[1,0]
	v_mul_f32_e32 v45, v39, v45
	v_div_scale_f32 v46, s[0:1], v37, v37, 2.0
	v_rcp_f32_e32 v47, v46
	v_fma_f32 v45, v39, v45, v39
	v_mul_f32_e32 v45, 0x3f4c422a, v45
	v_add_f32_e32 v45, v45, v45
	v_fma_f32 v48, -v46, v47, 1.0
	v_fmac_f32_e32 v47, v48, v47
	v_div_scale_f32 v48, vcc, 2.0, v37, 2.0
	v_mul_f32_e32 v49, v48, v47
	v_fma_f32 v50, -v46, v49, v48
	v_fmac_f32_e32 v49, v50, v47
	v_fma_f32 v46, -v46, v49, v48
	v_div_scale_f32 v48, s[0:1], v36, v36, 2.0
	v_rcp_f32_e32 v50, v48
	v_div_fmas_f32 v46, v46, v47, v49
	v_mul_f32_e32 v45, 0x3fb8aa3b, v45
	v_div_fixup_f32 v37, v46, v37, 2.0
	v_fma_f32 v46, -v48, v50, 1.0
	v_exp_f32_e32 v45, v45
	v_fmac_f32_e32 v50, v46, v50
	v_div_scale_f32 v46, vcc, 2.0, v36, 2.0
	v_mul_f32_e32 v47, v46, v50
	v_fma_f32 v49, -v48, v47, v46
	v_fmac_f32_e32 v47, v49, v50
	v_fma_f32 v46, -v48, v47, v46
	v_pk_add_f32 v[44:45], v[44:45], 1.0 op_sel_hi:[1,0]
	v_div_fmas_f32 v46, v46, v50, v47
	v_mov_b32_e32 v47, v38
	v_div_scale_f32 v38, s[0:1], v45, v45, 2.0
	v_div_fixup_f32 v36, v46, v36, 2.0
	v_mov_b32_e32 v46, v42
	v_rcp_f32_e32 v42, v38
	v_pk_add_f32 v[36:37], v[36:37], 1.0 op_sel_hi:[1,0] neg_lo:[1,0] neg_hi:[1,0]
	v_pk_mul_f32 v[46:47], v[46:47], 0.5 op_sel_hi:[1,0]
	v_pk_add_f32 v[36:37], v[36:37], 1.0 op_sel_hi:[1,0]
	s_nop 0
	v_pk_mul_f32 v[36:37], v[46:47], v[36:37]
	v_fma_f32 v46, -v38, v42, 1.0
	v_fmac_f32_e32 v42, v46, v42
	v_div_scale_f32 v46, vcc, 2.0, v45, 2.0
	v_mul_f32_e32 v47, v46, v42
	v_fma_f32 v48, -v38, v47, v46
	v_fmac_f32_e32 v47, v48, v42
	v_fma_f32 v38, -v38, v47, v46
	v_div_scale_f32 v46, s[0:1], v44, v44, 2.0
	v_rcp_f32_e32 v48, v46
	v_div_fmas_f32 v38, v38, v42, v47
	v_div_fixup_f32 v45, v38, v45, 2.0
	v_fma_f32 v38, -v46, v48, 1.0
	v_fmac_f32_e32 v48, v38, v48
	v_div_scale_f32 v38, vcc, 2.0, v44, 2.0
	v_mul_f32_e32 v42, v38, v48
	v_fma_f32 v47, -v46, v42, v38
	v_fmac_f32_e32 v42, v47, v48
	v_fma_f32 v38, -v46, v42, v38
	v_div_fmas_f32 v38, v38, v48, v42
	v_div_fixup_f32 v44, v38, v44, 2.0
	v_pk_add_f32 v[44:45], v[44:45], 1.0 op_sel_hi:[1,0] neg_lo:[1,0] neg_hi:[1,0]
	v_mov_b32_e32 v38, v43
	v_pk_mul_f32 v[38:39], v[38:39], 0.5 op_sel_hi:[1,0]
	v_pk_add_f32 v[42:43], v[44:45], 1.0 op_sel_hi:[1,0]
	v_mul_f32_e32 v45, 0x3d372713, v35
	v_pk_mul_f32 v[38:39], v[38:39], v[42:43]
	v_mul_f32_e32 v43, 0x3d372713, v33
	v_mul_f32_e32 v43, v33, v43
	v_fma_f32 v43, v33, v43, v33
	v_mul_f32_e32 v43, 0x3f4c422a, v43
	v_add_f32_e32 v43, v43, v43
	v_mul_f32_e32 v43, 0x3fb8aa3b, v43
	v_mul_f32_e32 v42, 0x3d372713, v32
	v_exp_f32_e32 v44, v43
	v_mul_f32_e32 v43, 0x3d372713, v34
	v_mul_f32_e32 v42, v32, v42
	v_mul_f32_e32 v43, v34, v43
	v_fma_f32 v42, v32, v42, v32
	v_fma_f32 v43, v34, v43, v34
	v_mul_f32_e32 v42, 0x3f4c422a, v42
	v_mul_f32_e32 v43, 0x3f4c422a, v43
	v_add_f32_e32 v42, v42, v42
	v_add_f32_e32 v43, v43, v43
	v_mul_f32_e32 v42, 0x3fb8aa3b, v42
	v_mul_f32_e32 v43, 0x3fb8aa3b, v43
	v_exp_f32_e32 v42, v42
	v_exp_f32_e32 v43, v43
	v_mul_f32_e32 v45, v35, v45
	v_fma_f32 v45, v35, v45, v35
	v_mul_f32_e32 v45, 0x3f4c422a, v45
	v_pk_add_f32 v[42:43], v[42:43], 1.0 op_sel_hi:[1,0]
	v_add_f32_e32 v45, v45, v45
	v_div_scale_f32 v46, s[0:1], v43, v43, 2.0
	v_rcp_f32_e32 v47, v46
	v_mul_f32_e32 v45, 0x3fb8aa3b, v45
	v_exp_f32_e32 v45, v45
	v_fma_f32 v48, -v46, v47, 1.0
	v_fmac_f32_e32 v47, v48, v47
	v_div_scale_f32 v48, vcc, 2.0, v43, 2.0
	v_mul_f32_e32 v49, v48, v47
	v_fma_f32 v50, -v46, v49, v48
	v_fmac_f32_e32 v49, v50, v47
	v_fma_f32 v46, -v46, v49, v48
	v_div_scale_f32 v48, s[0:1], v42, v42, 2.0
	v_rcp_f32_e32 v50, v48
	v_div_fmas_f32 v46, v46, v47, v49
	v_div_fixup_f32 v43, v46, v43, 2.0
	v_pk_add_f32 v[44:45], v[44:45], 1.0 op_sel_hi:[1,0]
	v_fma_f32 v46, -v48, v50, 1.0
	v_fmac_f32_e32 v50, v46, v50
	v_div_scale_f32 v46, vcc, 2.0, v42, 2.0
	v_mul_f32_e32 v47, v46, v50
	v_fma_f32 v49, -v48, v47, v46
	v_fmac_f32_e32 v47, v49, v50
	v_fma_f32 v46, -v48, v47, v46
	v_div_fmas_f32 v46, v46, v50, v47
	v_div_fixup_f32 v42, v46, v42, 2.0
	v_mov_b32_e32 v46, v32
	v_div_scale_f32 v32, s[0:1], v45, v45, 2.0
	v_mov_b32_e32 v47, v34
	v_rcp_f32_e32 v34, v32
	v_pk_add_f32 v[42:43], v[42:43], 1.0 op_sel_hi:[1,0] neg_lo:[1,0] neg_hi:[1,0]
	v_pk_mul_f32 v[46:47], v[46:47], 0.5 op_sel_hi:[1,0]
	v_pk_add_f32 v[42:43], v[42:43], 1.0 op_sel_hi:[1,0]
	s_nop 0
	v_pk_mul_f32 v[42:43], v[46:47], v[42:43]
	v_fma_f32 v46, -v32, v34, 1.0
	v_fmac_f32_e32 v34, v46, v34
	v_div_scale_f32 v46, vcc, 2.0, v45, 2.0
	v_mul_f32_e32 v47, v46, v34
	v_fma_f32 v48, -v32, v47, v46
	v_fmac_f32_e32 v47, v48, v34
	v_fma_f32 v32, -v32, v47, v46
	v_div_scale_f32 v46, s[0:1], v44, v44, 2.0
	v_rcp_f32_e32 v48, v46
	v_div_fmas_f32 v32, v32, v34, v47
	v_div_fixup_f32 v45, v32, v45, 2.0
	v_fma_f32 v32, -v46, v48, 1.0
	v_fmac_f32_e32 v48, v32, v48
	v_div_scale_f32 v32, vcc, 2.0, v44, 2.0
	v_mul_f32_e32 v34, v32, v48
	v_fma_f32 v47, -v46, v34, v32
	v_fmac_f32_e32 v34, v47, v48
	v_fma_f32 v32, -v46, v34, v32
	v_div_fmas_f32 v32, v32, v48, v34
	v_div_fixup_f32 v44, v32, v44, 2.0
	v_pk_add_f32 v[44:45], v[44:45], 1.0 op_sel_hi:[1,0] neg_lo:[1,0] neg_hi:[1,0]
	v_mov_b32_e32 v34, v33
	v_pk_mul_f32 v[32:33], v[34:35], 0.5 op_sel_hi:[1,0]
	v_pk_add_f32 v[34:35], v[44:45], 1.0 op_sel_hi:[1,0]
	v_pk_mul_f32 v[32:33], v[32:33], v[34:35]
	v_cvt_pk_bf16_f32 v35, v43, v33
	v_cvt_pk_bf16_f32 v34, v42, v32
	v_cvt_pk_bf16_f32 v33, v37, v39
	v_cvt_pk_bf16_f32 v32, v36, v38
	global_store_dwordx4 v[40:41], v[32:35], off offset:256
	global_load_dwordx4 v[32:35], v[140:141], off
	s_nop 0
	global_load_dwordx4 v[36:39], v[140:141], off offset:16
	s_waitcnt vmcnt(1)
; __device__ __forceinline__ unsigned pk2_(float lo, float hi) { return f2bf_(lo) | (f2bf_(hi) << 16); }
; template <int ACT> __device__ __forceinline__ float act_f(float v) {
;     ...
;     if (ACT == 3) { const float u = 0.7978845608028654f * (v + 0.044715f * v * v * v); const float e = __expf(2.f * u); const float th = 1.f - 2.f / (e + 1.f); return 0.5f * v * (1.f + th); }
;     __device__ __forceinline__ void operator()(const f32x4 (&acc)[2][2][4][2], const Unit& u, int wr, int wc, int fr, int fq) const {
;     ...
;             for (int m = 0; m < 4; ++m) { bf16_t* rowp = O + (size_t)(row0 + ai * HALF + m * 16) * ldc + col0;
; #pragma unroll
;                 for (int bj = 0; bj < 2; ++bj) { f32x4 v0 = acc[ai][bj][m][0], v1 = acc[ai][bj][m][1];
;                     if (bias) { v0 += *(const f32x4*)(bias + col0 + bj * HALF); v1 += *(const f32x4*)(bias + col0 + bj * HALF + 4); }
;                     u32x4 w; w.x = pk2_(act_f<ACT>(v0[0]), act_f<ACT>(v0[1])); w.y = pk2_(act_f<ACT>(v0[2]), act_f<ACT>(v0[3]));
;                     w.z = pk2_(act_f<ACT>(v1[0]), act_f<ACT>(v1[1])); w.w = pk2_(act_f<ACT>(v1[2]), act_f<ACT>(v1[3]));
;                     *(u32x4*)(rowp + bj * HALF) = w; } }
	v_pk_add_f32 v[32:33], v[28:29], v[32:33]
	s_nop 0
	v_mul_f32_e32 v29, 0x3d372713, v33
	v_mul_f32_e32 v29, v33, v29
	v_fma_f32 v29, v33, v29, v33
	v_mul_f32_e32 v29, 0x3f4c422a, v29
	v_add_f32_e32 v29, v29, v29
	v_pk_add_f32 v[30:31], v[30:31], v[34:35]
	v_mul_f32_e32 v29, 0x3fb8aa3b, v29
	v_mul_f32_e32 v28, 0x3d372713, v32
	v_exp_f32_e32 v34, v29
	v_mul_f32_e32 v29, 0x3d372713, v30
	v_mul_f32_e32 v28, v32, v28
	v_mul_f32_e32 v29, v30, v29
	v_fma_f32 v28, v32, v28, v32
	v_fma_f32 v29, v30, v29, v30
	v_mul_f32_e32 v28, 0x3f4c422a, v28
	v_mul_f32_e32 v29, 0x3f4c422a, v29
	v_add_f32_e32 v28, v28, v28
	v_add_f32_e32 v29, v29, v29
	v_mul_f32_e32 v28, 0x3fb8aa3b, v28
	v_mul_f32_e32 v29, 0x3fb8aa3b, v29
	v_exp_f32_e32 v28, v28
	v_exp_f32_e32 v29, v29
	s_waitcnt vmcnt(0)
	v_pk_add_f32 v[24:25], v[24:25], v[36:37]
	v_pk_add_f32 v[26:27], v[26:27], v[38:39]
	v_mul_f32_e32 v35, 0x3d372713, v31
	v_pk_add_f32 v[28:29], v[28:29], 1.0 op_sel_hi:[1,0]
	v_mul_f32_e32 v35, v31, v35
	v_div_scale_f32 v36, s[0:1], v29, v29, 2.0
	v_rcp_f32_e32 v37, v36
	v_fma_f32 v35, v31, v35, v31
	v_mul_f32_e32 v35, 0x3f4c422a, v35
	v_add_f32_e32 v35, v35, v35
	v_fma_f32 v38, -v36, v37, 1.0
	v_fmac_f32_e32 v37, v38, v37
	v_div_scale_f32 v38, vcc, 2.0, v29, 2.0
	v_mul_f32_e32 v39, v38, v37
	v_fma_f32 v40, -v36, v39, v38
	v_fmac_f32_e32 v39, v40, v37
	v_fma_f32 v36, -v36, v39, v38
	v_div_scale_f32 v38, s[0:1], v28, v28, 2.0
	v_rcp_f32_e32 v40, v38
	v_div_fmas_f32 v36, v36, v37, v39
	v_mul_f32_e32 v35, 0x3fb8aa3b, v35
	v_div_fixup_f32 v29, v36, v29, 2.0
	v_fma_f32 v36, -v38, v40, 1.0
	v_exp_f32_e32 v35, v35
	v_fmac_f32_e32 v40, v36, v40
	v_div_scale_f32 v36, vcc, 2.0, v28, 2.0
	v_mul_f32_e32 v37, v36, v40
	v_fma_f32 v39, -v38, v37, v36
	v_fmac_f32_e32 v37, v39, v40
	v_fma_f32 v36, -v38, v37, v36
	v_pk_add_f32 v[34:35], v[34:35], 1.0 op_sel_hi:[1,0]
	v_div_fmas_f32 v36, v36, v40, v37
	v_mov_b32_e32 v37, v30
	v_div_scale_f32 v30, s[0:1], v35, v35, 2.0
	v_div_fixup_f32 v28, v36, v28, 2.0
	v_mov_b32_e32 v36, v32
	v_rcp_f32_e32 v32, v30
	v_pk_add_f32 v[28:29], v[28:29], 1.0 op_sel_hi:[1,0] neg_lo:[1,0] neg_hi:[1,0]
	v_pk_mul_f32 v[36:37], v[36:37], 0.5 op_sel_hi:[1,0]
	v_pk_add_f32 v[28:29], v[28:29], 1.0 op_sel_hi:[1,0]
	s_nop 0
	v_pk_mul_f32 v[28:29], v[36:37], v[28:29]
	v_fma_f32 v36, -v30, v32, 1.0
	v_fmac_f32_e32 v32, v36, v32
	v_div_scale_f32 v36, vcc, 2.0, v35, 2.0
	v_mul_f32_e32 v37, v36, v32
	v_fma_f32 v38, -v30, v37, v36
	v_fmac_f32_e32 v37, v38, v32
	v_fma_f32 v30, -v30, v37, v36
	v_div_scale_f32 v36, s[0:1], v34, v34, 2.0
	v_rcp_f32_e32 v38, v36
	v_div_fmas_f32 v30, v30, v32, v37
	v_div_fixup_f32 v35, v30, v35, 2.0
	v_fma_f32 v30, -v36, v38, 1.0
	v_fmac_f32_e32 v38, v30, v38
	v_div_scale_f32 v30, vcc, 2.0, v34, 2.0
	v_mul_f32_e32 v32, v30, v38
	v_fma_f32 v37, -v36, v32, v30
	v_fmac_f32_e32 v32, v37, v38
	v_fma_f32 v30, -v36, v32, v30
	v_div_fmas_f32 v30, v30, v38, v32
	v_div_fixup_f32 v34, v30, v34, 2.0
	v_pk_add_f32 v[34:35], v[34:35], 1.0 op_sel_hi:[1,0] neg_lo:[1,0] neg_hi:[1,0]
	v_mov_b32_e32 v30, v33
	v_pk_mul_f32 v[30:31], v[30:31], 0.5 op_sel_hi:[1,0]
	v_pk_add_f32 v[32:33], v[34:35], 1.0 op_sel_hi:[1,0]
	v_mul_f32_e32 v35, 0x3d372713, v27
	v_pk_mul_f32 v[30:31], v[30:31], v[32:33]
	v_mul_f32_e32 v33, 0x3d372713, v25
	v_mul_f32_e32 v33, v25, v33
	v_fma_f32 v33, v25, v33, v25
	v_mul_f32_e32 v33, 0x3f4c422a, v33
	v_add_f32_e32 v33, v33, v33
	v_mul_f32_e32 v33, 0x3fb8aa3b, v33
	v_mul_f32_e32 v32, 0x3d372713, v24
	v_exp_f32_e32 v34, v33
	v_mul_f32_e32 v33, 0x3d372713, v26
	v_mul_f32_e32 v32, v24, v32
	v_mul_f32_e32 v33, v26, v33
	v_fma_f32 v32, v24, v32, v24
	v_fma_f32 v33, v26, v33, v26
	v_mul_f32_e32 v32, 0x3f4c422a, v32
	v_mul_f32_e32 v33, 0x3f4c422a, v33
	v_add_f32_e32 v32, v32, v32
	v_add_f32_e32 v33, v33, v33
	v_mul_f32_e32 v32, 0x3fb8aa3b, v32
	v_mul_f32_e32 v33, 0x3fb8aa3b, v33
	v_exp_f32_e32 v32, v32
	v_exp_f32_e32 v33, v33
	v_mul_f32_e32 v35, v27, v35
	v_fma_f32 v35, v27, v35, v27
	v_mul_f32_e32 v35, 0x3f4c422a, v35
	v_pk_add_f32 v[32:33], v[32:33], 1.0 op_sel_hi:[1,0]
	v_add_f32_e32 v35, v35, v35
	v_div_scale_f32 v36, s[0:1], v33, v33, 2.0
	v_rcp_f32_e32 v37, v36
	v_mul_f32_e32 v35, 0x3fb8aa3b, v35
	v_exp_f32_e32 v35, v35
	v_fma_f32 v38, -v36, v37, 1.0
	v_fmac_f32_e32 v37, v38, v37
	v_div_scale_f32 v38, vcc, 2.0, v33, 2.0
	v_mul_f32_e32 v39, v38, v37
	v_fma_f32 v40, -v36, v39, v38
	v_fmac_f32_e32 v39, v40, v37
	v_fma_f32 v36, -v36, v39, v38
	v_div_scale_f32 v38, s[0:1], v32, v32, 2.0
	v_rcp_f32_e32 v40, v38
	v_div_fmas_f32 v36, v36, v37, v39
	v_div_fixup_f32 v33, v36, v33, 2.0
	v_pk_add_f32 v[34:35], v[34:35], 1.0 op_sel_hi:[1,0]
	v_fma_f32 v36, -v38, v40, 1.0
	v_fmac_f32_e32 v40, v36, v40
	v_div_scale_f32 v36, vcc, 2.0, v32, 2.0
	v_mul_f32_e32 v37, v36, v40
	v_fma_f32 v39, -v38, v37, v36
	v_fmac_f32_e32 v37, v39, v40
	v_fma_f32 v36, -v38, v37, v36
	v_div_fmas_f32 v36, v36, v40, v37
	v_div_fixup_f32 v32, v36, v32, 2.0
	v_mov_b32_e32 v36, v24
	v_div_scale_f32 v24, s[0:1], v35, v35, 2.0
	v_mov_b32_e32 v37, v26
	v_rcp_f32_e32 v26, v24
	v_pk_add_f32 v[32:33], v[32:33], 1.0 op_sel_hi:[1,0] neg_lo:[1,0] neg_hi:[1,0]
	v_pk_mul_f32 v[36:37], v[36:37], 0.5 op_sel_hi:[1,0]
	v_pk_add_f32 v[32:33], v[32:33], 1.0 op_sel_hi:[1,0]
	s_nop 0
	v_pk_mul_f32 v[32:33], v[36:37], v[32:33]
	v_fma_f32 v36, -v24, v26, 1.0
	v_fmac_f32_e32 v26, v36, v26
	v_div_scale_f32 v36, vcc, 2.0, v35, 2.0
	v_mul_f32_e32 v37, v36, v26
	v_fma_f32 v38, -v24, v37, v36
	v_fmac_f32_e32 v37, v38, v26
	v_fma_f32 v24, -v24, v37, v36
	v_div_scale_f32 v36, s[0:1], v34, v34, 2.0
	v_rcp_f32_e32 v38, v36
	v_div_fmas_f32 v24, v24, v26, v37
	v_div_fixup_f32 v35, v24, v35, 2.0
	s_mov_b32 s0, 0x14000
	v_fma_f32 v24, -v36, v38, 1.0
	v_fmac_f32_e32 v38, v24, v38
	v_div_scale_f32 v24, vcc, 2.0, v34, 2.0
	v_mul_f32_e32 v26, v24, v38
	v_fma_f32 v37, -v36, v26, v24
	v_fmac_f32_e32 v26, v37, v38
	v_fma_f32 v24, -v36, v26, v24
	v_div_fmas_f32 v24, v24, v38, v26
	v_div_fixup_f32 v34, v24, v34, 2.0
	v_pk_add_f32 v[34:35], v[34:35], 1.0 op_sel_hi:[1,0] neg_lo:[1,0] neg_hi:[1,0]
	v_mov_b32_e32 v26, v25
	v_pk_mul_f32 v[24:25], v[26:27], 0.5 op_sel_hi:[1,0]
	v_pk_add_f32 v[26:27], v[34:35], 1.0 op_sel_hi:[1,0]
	v_pk_mul_f32 v[24:25], v[24:25], v[26:27]
	v_cvt_pk_bf16_f32 v26, v32, v24
	v_cvt_pk_bf16_f32 v24, v28, v30
	v_add_co_u32_e32 v28, vcc, s0, v142
	v_cvt_pk_bf16_f32 v27, v33, v25
	v_cvt_pk_bf16_f32 v25, v29, v31
	v_addc_co_u32_e32 v29, vcc, 0, v143, vcc
	global_store_dwordx4 v[28:29], v[24:27], off
	global_load_dwordx4 v[26:29], v[140:141], off offset:512
	s_nop 0
	global_load_dwordx4 v[30:33], v[140:141], off offset:528
	s_mov_b64 s[0:1], 0x14000
	v_lshl_add_u64 v[24:25], v[142:143], 0, s[0:1]
	s_waitcnt vmcnt(1)
; __device__ __forceinline__ unsigned pk2_(float lo, float hi) { return f2bf_(lo) | (f2bf_(hi) << 16); }
; template <int ACT> __device__ __forceinline__ float act_f(float v) {
;     ...
;     if (ACT == 3) { const float u = 0.7978845608028654f * (v + 0.044715f * v * v * v); const float e = __expf(2.f * u); const float th = 1.f - 2.f / (e + 1.f); return 0.5f * v * (1.f + th); }
;     __device__ __forceinline__ void operator()(const f32x4 (&acc)[2][2][4][2], const Unit& u, int wr, int wc, int fr, int fq) const {
;     ...
;             for (int m = 0; m < 4; ++m) { bf16_t* rowp = O + (size_t)(row0 + ai * HALF + m * 16) * ldc + col0;
; #pragma unroll
;                 for (int bj = 0; bj < 2; ++bj) { f32x4 v0 = acc[ai][bj][m][0], v1 = acc[ai][bj][m][1];
;                     if (bias) { v0 += *(const f32x4*)(bias + col0 + bj * HALF); v1 += *(const f32x4*)(bias + col0 + bj * HALF + 4); }
;                     u32x4 w; w.x = pk2_(act_f<ACT>(v0[0]), act_f<ACT>(v0[1])); w.y = pk2_(act_f<ACT>(v0[2]), act_f<ACT>(v0[3]));
;                     w.z = pk2_(act_f<ACT>(v1[0]), act_f<ACT>(v1[1])); w.w = pk2_(act_f<ACT>(v1[2]), act_f<ACT>(v1[3]));
;                     *(u32x4*)(rowp + bj * HALF) = w; } }
	v_pk_add_f32 v[26:27], v[20:21], v[26:27]
	s_nop 0
	v_mul_f32_e32 v21, 0x3d372713, v27
	v_mul_f32_e32 v21, v27, v21
	v_fma_f32 v21, v27, v21, v27
	v_mul_f32_e32 v21, 0x3f4c422a, v21
	v_add_f32_e32 v21, v21, v21
	v_pk_add_f32 v[22:23], v[22:23], v[28:29]
	v_mul_f32_e32 v21, 0x3fb8aa3b, v21
	v_mul_f32_e32 v20, 0x3d372713, v26
	v_exp_f32_e32 v28, v21
	v_mul_f32_e32 v21, 0x3d372713, v22
	v_mul_f32_e32 v20, v26, v20
	v_mul_f32_e32 v21, v22, v21
	v_fma_f32 v20, v26, v20, v26
	v_fma_f32 v21, v22, v21, v22
	v_mul_f32_e32 v20, 0x3f4c422a, v20
	v_mul_f32_e32 v21, 0x3f4c422a, v21
	v_add_f32_e32 v20, v20, v20
	v_add_f32_e32 v21, v21, v21
	v_mul_f32_e32 v20, 0x3fb8aa3b, v20
	v_mul_f32_e32 v21, 0x3fb8aa3b, v21
	v_exp_f32_e32 v20, v20
	v_exp_f32_e32 v21, v21
	s_waitcnt vmcnt(0)
	v_pk_add_f32 v[16:17], v[16:17], v[30:31]
	v_pk_add_f32 v[18:19], v[18:19], v[32:33]
	v_mul_f32_e32 v29, 0x3d372713, v23
	v_pk_add_f32 v[20:21], v[20:21], 1.0 op_sel_hi:[1,0]
	v_mul_f32_e32 v29, v23, v29
	v_div_scale_f32 v30, s[0:1], v21, v21, 2.0
	v_rcp_f32_e32 v31, v30
	v_fma_f32 v29, v23, v29, v23
	v_mul_f32_e32 v29, 0x3f4c422a, v29
	v_add_f32_e32 v29, v29, v29
	v_fma_f32 v32, -v30, v31, 1.0
	v_fmac_f32_e32 v31, v32, v31
	v_div_scale_f32 v32, vcc, 2.0, v21, 2.0
	v_mul_f32_e32 v33, v32, v31
	v_fma_f32 v34, -v30, v33, v32
	v_fmac_f32_e32 v33, v34, v31
	v_fma_f32 v30, -v30, v33, v32
	v_div_scale_f32 v32, s[0:1], v20, v20, 2.0
	v_rcp_f32_e32 v34, v32
	v_div_fmas_f32 v30, v30, v31, v33
	v_mul_f32_e32 v29, 0x3fb8aa3b, v29
	v_div_fixup_f32 v21, v30, v21, 2.0
	v_fma_f32 v30, -v32, v34, 1.0
	v_exp_f32_e32 v29, v29
	v_fmac_f32_e32 v34, v30, v34
	v_div_scale_f32 v30, vcc, 2.0, v20, 2.0
	v_mul_f32_e32 v31, v30, v34
	v_fma_f32 v33, -v32, v31, v30
	v_fmac_f32_e32 v31, v33, v34
	v_fma_f32 v30, -v32, v31, v30
	v_pk_add_f32 v[28:29], v[28:29], 1.0 op_sel_hi:[1,0]
	v_div_fmas_f32 v30, v30, v34, v31
	v_mov_b32_e32 v31, v22
	v_div_scale_f32 v22, s[0:1], v29, v29, 2.0
	v_div_fixup_f32 v20, v30, v20, 2.0
	v_mov_b32_e32 v30, v26
	v_rcp_f32_e32 v26, v22
	v_pk_add_f32 v[20:21], v[20:21], 1.0 op_sel_hi:[1,0] neg_lo:[1,0] neg_hi:[1,0]
	v_pk_mul_f32 v[30:31], v[30:31], 0.5 op_sel_hi:[1,0]
	v_pk_add_f32 v[20:21], v[20:21], 1.0 op_sel_hi:[1,0]
	s_nop 0
	v_pk_mul_f32 v[20:21], v[30:31], v[20:21]
	v_fma_f32 v30, -v22, v26, 1.0
	v_fmac_f32_e32 v26, v30, v26
	v_div_scale_f32 v30, vcc, 2.0, v29, 2.0
	v_mul_f32_e32 v31, v30, v26
	v_fma_f32 v32, -v22, v31, v30
	v_fmac_f32_e32 v31, v32, v26
	v_fma_f32 v22, -v22, v31, v30
	v_div_scale_f32 v30, s[0:1], v28, v28, 2.0
	v_rcp_f32_e32 v32, v30
	v_div_fmas_f32 v22, v22, v26, v31
	v_div_fixup_f32 v29, v22, v29, 2.0
	v_fma_f32 v22, -v30, v32, 1.0
	v_fmac_f32_e32 v32, v22, v32
	v_div_scale_f32 v22, vcc, 2.0, v28, 2.0
	v_mul_f32_e32 v26, v22, v32
	v_fma_f32 v31, -v30, v26, v22
	v_fmac_f32_e32 v26, v31, v32
	v_fma_f32 v22, -v30, v26, v22
	v_div_fmas_f32 v22, v22, v32, v26
	v_div_fixup_f32 v28, v22, v28, 2.0
	v_pk_add_f32 v[28:29], v[28:29], 1.0 op_sel_hi:[1,0] neg_lo:[1,0] neg_hi:[1,0]
	v_mov_b32_e32 v22, v27
	v_pk_mul_f32 v[22:23], v[22:23], 0.5 op_sel_hi:[1,0]
	v_pk_add_f32 v[26:27], v[28:29], 1.0 op_sel_hi:[1,0]
	v_mul_f32_e32 v29, 0x3d372713, v19
	v_pk_mul_f32 v[22:23], v[22:23], v[26:27]
	v_mul_f32_e32 v27, 0x3d372713, v17
	v_mul_f32_e32 v27, v17, v27
	v_fma_f32 v27, v17, v27, v17
	v_mul_f32_e32 v27, 0x3f4c422a, v27
	v_add_f32_e32 v27, v27, v27
	v_mul_f32_e32 v27, 0x3fb8aa3b, v27
	v_mul_f32_e32 v26, 0x3d372713, v16
	v_exp_f32_e32 v28, v27
	v_mul_f32_e32 v27, 0x3d372713, v18
	v_mul_f32_e32 v26, v16, v26
	v_mul_f32_e32 v27, v18, v27
	v_fma_f32 v26, v16, v26, v16
	v_fma_f32 v27, v18, v27, v18
	v_mul_f32_e32 v26, 0x3f4c422a, v26
	v_mul_f32_e32 v27, 0x3f4c422a, v27
	v_add_f32_e32 v26, v26, v26
	v_add_f32_e32 v27, v27, v27
	v_mul_f32_e32 v26, 0x3fb8aa3b, v26
	v_mul_f32_e32 v27, 0x3fb8aa3b, v27
	v_exp_f32_e32 v26, v26
	v_exp_f32_e32 v27, v27
	v_mul_f32_e32 v29, v19, v29
	v_fma_f32 v29, v19, v29, v19
	v_mul_f32_e32 v29, 0x3f4c422a, v29
	v_pk_add_f32 v[26:27], v[26:27], 1.0 op_sel_hi:[1,0]
	v_add_f32_e32 v29, v29, v29
	v_div_scale_f32 v30, s[0:1], v27, v27, 2.0
	v_rcp_f32_e32 v31, v30
	v_mul_f32_e32 v29, 0x3fb8aa3b, v29
	v_exp_f32_e32 v29, v29
	v_fma_f32 v32, -v30, v31, 1.0
	v_fmac_f32_e32 v31, v32, v31
	v_div_scale_f32 v32, vcc, 2.0, v27, 2.0
	v_mul_f32_e32 v33, v32, v31
	v_fma_f32 v34, -v30, v33, v32
	v_fmac_f32_e32 v33, v34, v31
	v_fma_f32 v30, -v30, v33, v32
	v_div_scale_f32 v32, s[0:1], v26, v26, 2.0
	v_rcp_f32_e32 v34, v32
	v_div_fmas_f32 v30, v30, v31, v33
	v_div_fixup_f32 v27, v30, v27, 2.0
	v_pk_add_f32 v[28:29], v[28:29], 1.0 op_sel_hi:[1,0]
	v_fma_f32 v30, -v32, v34, 1.0
	v_fmac_f32_e32 v34, v30, v34
	v_div_scale_f32 v30, vcc, 2.0, v26, 2.0
	v_mul_f32_e32 v31, v30, v34
	v_fma_f32 v33, -v32, v31, v30
	v_fmac_f32_e32 v31, v33, v34
	v_fma_f32 v30, -v32, v31, v30
	v_div_fmas_f32 v30, v30, v34, v31
	v_div_fixup_f32 v26, v30, v26, 2.0
	v_mov_b32_e32 v30, v16
	v_div_scale_f32 v16, s[0:1], v29, v29, 2.0
	v_mov_b32_e32 v31, v18
	v_rcp_f32_e32 v18, v16
	v_pk_add_f32 v[26:27], v[26:27], 1.0 op_sel_hi:[1,0] neg_lo:[1,0] neg_hi:[1,0]
	v_pk_mul_f32 v[30:31], v[30:31], 0.5 op_sel_hi:[1,0]
	v_pk_add_f32 v[26:27], v[26:27], 1.0 op_sel_hi:[1,0]
	s_nop 0
	v_pk_mul_f32 v[26:27], v[30:31], v[26:27]
	v_fma_f32 v30, -v16, v18, 1.0
	v_fmac_f32_e32 v18, v30, v18
	v_div_scale_f32 v30, vcc, 2.0, v29, 2.0
	v_mul_f32_e32 v31, v30, v18
	v_fma_f32 v32, -v16, v31, v30
	v_fmac_f32_e32 v31, v32, v18
	v_fma_f32 v16, -v16, v31, v30
	v_div_scale_f32 v30, s[0:1], v28, v28, 2.0
	v_rcp_f32_e32 v32, v30
	v_div_fmas_f32 v16, v16, v18, v31
	v_div_fixup_f32 v29, v16, v29, 2.0
	v_fma_f32 v16, -v30, v32, 1.0
	v_fmac_f32_e32 v32, v16, v32
	v_div_scale_f32 v16, vcc, 2.0, v28, 2.0
	v_mul_f32_e32 v18, v16, v32
	v_fma_f32 v31, -v30, v18, v16
	v_fmac_f32_e32 v18, v31, v32
	v_fma_f32 v16, -v30, v18, v16
	v_div_fmas_f32 v16, v16, v32, v18
	v_div_fixup_f32 v28, v16, v28, 2.0
	v_pk_add_f32 v[28:29], v[28:29], 1.0 op_sel_hi:[1,0] neg_lo:[1,0] neg_hi:[1,0]
	v_mov_b32_e32 v18, v17
	v_pk_mul_f32 v[16:17], v[18:19], 0.5 op_sel_hi:[1,0]
	v_pk_add_f32 v[18:19], v[28:29], 1.0 op_sel_hi:[1,0]
	v_pk_mul_f32 v[16:17], v[16:17], v[18:19]
	v_cvt_pk_bf16_f32 v19, v27, v17
	v_cvt_pk_bf16_f32 v18, v26, v16
	v_cvt_pk_bf16_f32 v17, v21, v23
	v_cvt_pk_bf16_f32 v16, v20, v22
	global_store_dwordx4 v[24:25], v[16:19], off offset:256
	global_load_dwordx4 v[16:19], v[140:141], off
	s_nop 0
	global_load_dwordx4 v[20:23], v[140:141], off offset:16
	s_waitcnt vmcnt(1)
; __device__ __forceinline__ unsigned pk2_(float lo, float hi) { return f2bf_(lo) | (f2bf_(hi) << 16); }
; template <int ACT> __device__ __forceinline__ float act_f(float v) {
;     ...
;     if (ACT == 3) { const float u = 0.7978845608028654f * (v + 0.044715f * v * v * v); const float e = __expf(2.f * u); const float th = 1.f - 2.f / (e + 1.f); return 0.5f * v * (1.f + th); }
;     __device__ __forceinline__ void operator()(const f32x4 (&acc)[2][2][4][2], const Unit& u, int wr, int wc, int fr, int fq) const {
;     ...
;             for (int m = 0; m < 4; ++m) { bf16_t* rowp = O + (size_t)(row0 + ai * HALF + m * 16) * ldc + col0;
; #pragma unroll
;                 for (int bj = 0; bj < 2; ++bj) { f32x4 v0 = acc[ai][bj][m][0], v1 = acc[ai][bj][m][1];
;                     if (bias) { v0 += *(const f32x4*)(bias + col0 + bj * HALF); v1 += *(const f32x4*)(bias + col0 + bj * HALF + 4); }
;                     u32x4 w; w.x = pk2_(act_f<ACT>(v0[0]), act_f<ACT>(v0[1])); w.y = pk2_(act_f<ACT>(v0[2]), act_f<ACT>(v0[3]));
;                     w.z = pk2_(act_f<ACT>(v1[0]), act_f<ACT>(v1[1])); w.w = pk2_(act_f<ACT>(v1[2]), act_f<ACT>(v1[3]));
;                     *(u32x4*)(rowp + bj * HALF) = w; } }
	v_pk_add_f32 v[16:17], v[12:13], v[16:17]
	s_nop 0
	v_mul_f32_e32 v13, 0x3d372713, v17
	v_mul_f32_e32 v13, v17, v13
	v_fma_f32 v13, v17, v13, v17
	v_mul_f32_e32 v13, 0x3f4c422a, v13
	v_add_f32_e32 v13, v13, v13
	v_pk_add_f32 v[14:15], v[14:15], v[18:19]
	v_mul_f32_e32 v13, 0x3fb8aa3b, v13
	v_mul_f32_e32 v12, 0x3d372713, v16
	v_exp_f32_e32 v18, v13
	v_mul_f32_e32 v13, 0x3d372713, v14
	v_mul_f32_e32 v12, v16, v12
	v_mul_f32_e32 v13, v14, v13
	v_fma_f32 v12, v16, v12, v16
	v_fma_f32 v13, v14, v13, v14
	v_mul_f32_e32 v12, 0x3f4c422a, v12
	v_mul_f32_e32 v13, 0x3f4c422a, v13
	v_add_f32_e32 v12, v12, v12
	v_add_f32_e32 v13, v13, v13
	v_mul_f32_e32 v12, 0x3fb8aa3b, v12
	v_mul_f32_e32 v13, 0x3fb8aa3b, v13
	v_exp_f32_e32 v12, v12
	v_exp_f32_e32 v13, v13
	s_waitcnt vmcnt(0)
	v_pk_add_f32 v[8:9], v[8:9], v[20:21]
	v_pk_add_f32 v[10:11], v[10:11], v[22:23]
	v_mul_f32_e32 v19, 0x3d372713, v15
	v_pk_add_f32 v[12:13], v[12:13], 1.0 op_sel_hi:[1,0]
	v_mul_f32_e32 v19, v15, v19
	v_div_scale_f32 v20, s[0:1], v13, v13, 2.0
	v_rcp_f32_e32 v21, v20
	v_fma_f32 v19, v15, v19, v15
	v_mul_f32_e32 v19, 0x3f4c422a, v19
	v_add_f32_e32 v19, v19, v19
	v_fma_f32 v22, -v20, v21, 1.0
	v_fmac_f32_e32 v21, v22, v21
	v_div_scale_f32 v22, vcc, 2.0, v13, 2.0
	v_mul_f32_e32 v23, v22, v21
	v_fma_f32 v24, -v20, v23, v22
	v_fmac_f32_e32 v23, v24, v21
	v_fma_f32 v20, -v20, v23, v22
	v_div_scale_f32 v22, s[0:1], v12, v12, 2.0
	v_rcp_f32_e32 v24, v22
	v_div_fmas_f32 v20, v20, v21, v23
	v_mul_f32_e32 v19, 0x3fb8aa3b, v19
	v_div_fixup_f32 v13, v20, v13, 2.0
	v_fma_f32 v20, -v22, v24, 1.0
	v_exp_f32_e32 v19, v19
	v_fmac_f32_e32 v24, v20, v24
	v_div_scale_f32 v20, vcc, 2.0, v12, 2.0
	v_mul_f32_e32 v21, v20, v24
	v_fma_f32 v23, -v22, v21, v20
	v_fmac_f32_e32 v21, v23, v24
	v_fma_f32 v20, -v22, v21, v20
	v_pk_add_f32 v[18:19], v[18:19], 1.0 op_sel_hi:[1,0]
	v_div_fmas_f32 v20, v20, v24, v21
	v_mov_b32_e32 v21, v14
	v_div_scale_f32 v14, s[0:1], v19, v19, 2.0
	v_div_fixup_f32 v12, v20, v12, 2.0
	v_mov_b32_e32 v20, v16
	v_rcp_f32_e32 v16, v14
	v_pk_add_f32 v[12:13], v[12:13], 1.0 op_sel_hi:[1,0] neg_lo:[1,0] neg_hi:[1,0]
	v_pk_mul_f32 v[20:21], v[20:21], 0.5 op_sel_hi:[1,0]
	v_pk_add_f32 v[12:13], v[12:13], 1.0 op_sel_hi:[1,0]
	s_nop 0
	v_pk_mul_f32 v[12:13], v[20:21], v[12:13]
	v_fma_f32 v20, -v14, v16, 1.0
	v_fmac_f32_e32 v16, v20, v16
	v_div_scale_f32 v20, vcc, 2.0, v19, 2.0
	v_mul_f32_e32 v21, v20, v16
	v_fma_f32 v22, -v14, v21, v20
	v_fmac_f32_e32 v21, v22, v16
	v_fma_f32 v14, -v14, v21, v20
	v_div_scale_f32 v20, s[0:1], v18, v18, 2.0
	v_rcp_f32_e32 v22, v20
	v_div_fmas_f32 v14, v14, v16, v21
	v_div_fixup_f32 v19, v14, v19, 2.0
	v_fma_f32 v14, -v20, v22, 1.0
	v_fmac_f32_e32 v22, v14, v22
	v_div_scale_f32 v14, vcc, 2.0, v18, 2.0
	v_mul_f32_e32 v16, v14, v22
	v_fma_f32 v21, -v20, v16, v14
	v_fmac_f32_e32 v16, v21, v22
	v_fma_f32 v14, -v20, v16, v14
	v_div_fmas_f32 v14, v14, v22, v16
	v_div_fixup_f32 v18, v14, v18, 2.0
	v_pk_add_f32 v[18:19], v[18:19], 1.0 op_sel_hi:[1,0] neg_lo:[1,0] neg_hi:[1,0]
	v_mov_b32_e32 v14, v17
	v_pk_mul_f32 v[14:15], v[14:15], 0.5 op_sel_hi:[1,0]
	v_pk_add_f32 v[16:17], v[18:19], 1.0 op_sel_hi:[1,0]
	v_mul_f32_e32 v19, 0x3d372713, v11
	v_pk_mul_f32 v[14:15], v[14:15], v[16:17]
	v_mul_f32_e32 v17, 0x3d372713, v9
	v_mul_f32_e32 v17, v9, v17
	v_fma_f32 v17, v9, v17, v9
	v_mul_f32_e32 v17, 0x3f4c422a, v17
	v_add_f32_e32 v17, v17, v17
	v_mul_f32_e32 v17, 0x3fb8aa3b, v17
	v_mul_f32_e32 v16, 0x3d372713, v8
	v_exp_f32_e32 v18, v17
	v_mul_f32_e32 v17, 0x3d372713, v10
	v_mul_f32_e32 v16, v8, v16
	v_mul_f32_e32 v17, v10, v17
	v_fma_f32 v16, v8, v16, v8
	v_fma_f32 v17, v10, v17, v10
	v_mul_f32_e32 v16, 0x3f4c422a, v16
	v_mul_f32_e32 v17, 0x3f4c422a, v17
	v_add_f32_e32 v16, v16, v16
	v_add_f32_e32 v17, v17, v17
	v_mul_f32_e32 v16, 0x3fb8aa3b, v16
	v_mul_f32_e32 v17, 0x3fb8aa3b, v17
	v_exp_f32_e32 v16, v16
	v_exp_f32_e32 v17, v17
	v_mul_f32_e32 v19, v11, v19
	v_fma_f32 v19, v11, v19, v11
	v_mul_f32_e32 v19, 0x3f4c422a, v19
	v_pk_add_f32 v[16:17], v[16:17], 1.0 op_sel_hi:[1,0]
	v_add_f32_e32 v19, v19, v19
	v_div_scale_f32 v20, s[0:1], v17, v17, 2.0
	v_rcp_f32_e32 v21, v20
	v_mul_f32_e32 v19, 0x3fb8aa3b, v19
	v_exp_f32_e32 v19, v19
	v_fma_f32 v22, -v20, v21, 1.0
	v_fmac_f32_e32 v21, v22, v21
	v_div_scale_f32 v22, vcc, 2.0, v17, 2.0
	v_mul_f32_e32 v23, v22, v21
	v_fma_f32 v24, -v20, v23, v22
	v_fmac_f32_e32 v23, v24, v21
	v_fma_f32 v20, -v20, v23, v22
	v_div_scale_f32 v22, s[0:1], v16, v16, 2.0
	v_rcp_f32_e32 v24, v22
	v_div_fmas_f32 v20, v20, v21, v23
	v_div_fixup_f32 v17, v20, v17, 2.0
	v_pk_add_f32 v[18:19], v[18:19], 1.0 op_sel_hi:[1,0]
	v_fma_f32 v20, -v22, v24, 1.0
	v_fmac_f32_e32 v24, v20, v24
	v_div_scale_f32 v20, vcc, 2.0, v16, 2.0
	v_mul_f32_e32 v21, v20, v24
	v_fma_f32 v23, -v22, v21, v20
	v_fmac_f32_e32 v21, v23, v24
	v_fma_f32 v20, -v22, v21, v20
	v_div_fmas_f32 v20, v20, v24, v21
	v_div_fixup_f32 v16, v20, v16, 2.0
	v_mov_b32_e32 v20, v8
	v_div_scale_f32 v8, s[0:1], v19, v19, 2.0
	v_mov_b32_e32 v21, v10
	v_rcp_f32_e32 v10, v8
	v_pk_add_f32 v[16:17], v[16:17], 1.0 op_sel_hi:[1,0] neg_lo:[1,0] neg_hi:[1,0]
	v_pk_mul_f32 v[20:21], v[20:21], 0.5 op_sel_hi:[1,0]
	v_pk_add_f32 v[16:17], v[16:17], 1.0 op_sel_hi:[1,0]
	s_nop 0
	v_pk_mul_f32 v[16:17], v[20:21], v[16:17]
	v_fma_f32 v20, -v8, v10, 1.0
	v_fmac_f32_e32 v10, v20, v10
	v_div_scale_f32 v20, vcc, 2.0, v19, 2.0
	v_mul_f32_e32 v21, v20, v10
	v_fma_f32 v22, -v8, v21, v20
	v_fmac_f32_e32 v21, v22, v10
	v_fma_f32 v8, -v8, v21, v20
	v_div_scale_f32 v20, s[0:1], v18, v18, 2.0
	v_rcp_f32_e32 v22, v20
	v_div_fmas_f32 v8, v8, v10, v21
	v_div_fixup_f32 v19, v8, v19, 2.0
	s_mov_b32 s0, 0x16000
	v_fma_f32 v8, -v20, v22, 1.0
	v_fmac_f32_e32 v22, v8, v22
	v_div_scale_f32 v8, vcc, 2.0, v18, 2.0
	v_mul_f32_e32 v10, v8, v22
	v_fma_f32 v21, -v20, v10, v8
	v_fmac_f32_e32 v10, v21, v22
	v_fma_f32 v8, -v20, v10, v8
	v_div_fmas_f32 v8, v8, v22, v10
	v_div_fixup_f32 v18, v8, v18, 2.0
	v_pk_add_f32 v[18:19], v[18:19], 1.0 op_sel_hi:[1,0] neg_lo:[1,0] neg_hi:[1,0]
	v_mov_b32_e32 v10, v9
	v_pk_mul_f32 v[8:9], v[10:11], 0.5 op_sel_hi:[1,0]
	v_pk_add_f32 v[10:11], v[18:19], 1.0 op_sel_hi:[1,0]
	v_pk_mul_f32 v[8:9], v[8:9], v[10:11]
	v_cvt_pk_bf16_f32 v10, v16, v8
	v_cvt_pk_bf16_f32 v8, v12, v14
	v_add_co_u32_e32 v12, vcc, s0, v142
	v_cvt_pk_bf16_f32 v11, v17, v9
	v_cvt_pk_bf16_f32 v9, v13, v15
	v_addc_co_u32_e32 v13, vcc, 0, v143, vcc
	global_store_dwordx4 v[12:13], v[8:11], off
	global_load_dwordx4 v[10:13], v[140:141], off offset:512
	s_nop 0
	global_load_dwordx4 v[14:17], v[140:141], off offset:528
	s_mov_b64 s[0:1], 0x16000
	v_lshl_add_u64 v[8:9], v[142:143], 0, s[0:1]
	s_waitcnt vmcnt(1)
; __device__ __forceinline__ unsigned pk2_(float lo, float hi) { return f2bf_(lo) | (f2bf_(hi) << 16); }
; template <int ACT> __device__ __forceinline__ float act_f(float v) {
;     ...
;     if (ACT == 3) { const float u = 0.7978845608028654f * (v + 0.044715f * v * v * v); const float e = __expf(2.f * u); const float th = 1.f - 2.f / (e + 1.f); return 0.5f * v * (1.f + th); }
;     __device__ __forceinline__ void operator()(const f32x4 (&acc)[2][2][4][2], const Unit& u, int wr, int wc, int fr, int fq) const {
;     ...
;             for (int m = 0; m < 4; ++m) { bf16_t* rowp = O + (size_t)(row0 + ai * HALF + m * 16) * ldc + col0;
; #pragma unroll
;                 for (int bj = 0; bj < 2; ++bj) { f32x4 v0 = acc[ai][bj][m][0], v1 = acc[ai][bj][m][1];
;                     if (bias) { v0 += *(const f32x4*)(bias + col0 + bj * HALF); v1 += *(const f32x4*)(bias + col0 + bj * HALF + 4); }
;                     u32x4 w; w.x = pk2_(act_f<ACT>(v0[0]), act_f<ACT>(v0[1])); w.y = pk2_(act_f<ACT>(v0[2]), act_f<ACT>(v0[3]));
;                     w.z = pk2_(act_f<ACT>(v1[0]), act_f<ACT>(v1[1])); w.w = pk2_(act_f<ACT>(v1[2]), act_f<ACT>(v1[3]));
;                     *(u32x4*)(rowp + bj * HALF) = w; } }
	v_pk_add_f32 v[10:11], v[4:5], v[10:11]
	s_nop 0
	v_mul_f32_e32 v5, 0x3d372713, v11
	v_mul_f32_e32 v5, v11, v5
	v_fma_f32 v5, v11, v5, v11
	v_mul_f32_e32 v5, 0x3f4c422a, v5
	v_add_f32_e32 v5, v5, v5
	v_pk_add_f32 v[6:7], v[6:7], v[12:13]
	v_mul_f32_e32 v5, 0x3fb8aa3b, v5
	v_mul_f32_e32 v4, 0x3d372713, v10
	v_exp_f32_e32 v12, v5
	v_mul_f32_e32 v5, 0x3d372713, v6
	v_mul_f32_e32 v4, v10, v4
	v_mul_f32_e32 v5, v6, v5
	v_fma_f32 v4, v10, v4, v10
	v_fma_f32 v5, v6, v5, v6
	v_mul_f32_e32 v4, 0x3f4c422a, v4
	v_mul_f32_e32 v5, 0x3f4c422a, v5
	v_add_f32_e32 v4, v4, v4
	v_add_f32_e32 v5, v5, v5
	v_mul_f32_e32 v4, 0x3fb8aa3b, v4
	v_mul_f32_e32 v5, 0x3fb8aa3b, v5
	v_exp_f32_e32 v4, v4
	v_exp_f32_e32 v5, v5
	s_waitcnt vmcnt(0)
	v_pk_add_f32 v[0:1], v[0:1], v[14:15]
	v_pk_add_f32 v[2:3], v[2:3], v[16:17]
	v_mul_f32_e32 v13, 0x3d372713, v7
	v_pk_add_f32 v[4:5], v[4:5], 1.0 op_sel_hi:[1,0]
	v_mul_f32_e32 v13, v7, v13
	v_div_scale_f32 v14, s[0:1], v5, v5, 2.0
	v_rcp_f32_e32 v15, v14
	v_fma_f32 v13, v7, v13, v7
	v_mul_f32_e32 v13, 0x3f4c422a, v13
	v_add_f32_e32 v13, v13, v13
	v_fma_f32 v16, -v14, v15, 1.0
	v_fmac_f32_e32 v15, v16, v15
	v_div_scale_f32 v16, vcc, 2.0, v5, 2.0
	v_mul_f32_e32 v17, v16, v15
	v_fma_f32 v18, -v14, v17, v16
	v_fmac_f32_e32 v17, v18, v15
	v_fma_f32 v14, -v14, v17, v16
	v_div_scale_f32 v16, s[0:1], v4, v4, 2.0
	v_rcp_f32_e32 v18, v16
	v_div_fmas_f32 v14, v14, v15, v17
	v_mul_f32_e32 v13, 0x3fb8aa3b, v13
	v_div_fixup_f32 v5, v14, v5, 2.0
	v_fma_f32 v14, -v16, v18, 1.0
	v_exp_f32_e32 v13, v13
	v_fmac_f32_e32 v18, v14, v18
	v_div_scale_f32 v14, vcc, 2.0, v4, 2.0
	v_mul_f32_e32 v15, v14, v18
	v_fma_f32 v17, -v16, v15, v14
	v_fmac_f32_e32 v15, v17, v18
	v_fma_f32 v14, -v16, v15, v14
	v_pk_add_f32 v[12:13], v[12:13], 1.0 op_sel_hi:[1,0]
	v_div_fmas_f32 v14, v14, v18, v15
	v_mov_b32_e32 v15, v6
	v_div_scale_f32 v6, s[0:1], v13, v13, 2.0
	v_div_fixup_f32 v4, v14, v4, 2.0
	v_mov_b32_e32 v14, v10
	v_rcp_f32_e32 v10, v6
	v_pk_add_f32 v[4:5], v[4:5], 1.0 op_sel_hi:[1,0] neg_lo:[1,0] neg_hi:[1,0]
	v_pk_mul_f32 v[14:15], v[14:15], 0.5 op_sel_hi:[1,0]
	v_pk_add_f32 v[4:5], v[4:5], 1.0 op_sel_hi:[1,0]
	s_nop 0
	v_pk_mul_f32 v[4:5], v[14:15], v[4:5]
	v_fma_f32 v14, -v6, v10, 1.0
	v_fmac_f32_e32 v10, v14, v10
	v_div_scale_f32 v14, vcc, 2.0, v13, 2.0
	v_mul_f32_e32 v15, v14, v10
	v_fma_f32 v16, -v6, v15, v14
	v_fmac_f32_e32 v15, v16, v10
	v_fma_f32 v6, -v6, v15, v14
	v_div_scale_f32 v14, s[0:1], v12, v12, 2.0
	v_rcp_f32_e32 v16, v14
	v_div_fmas_f32 v6, v6, v10, v15
	v_div_fixup_f32 v13, v6, v13, 2.0
	v_fma_f32 v6, -v14, v16, 1.0
	v_fmac_f32_e32 v16, v6, v16
	v_div_scale_f32 v6, vcc, 2.0, v12, 2.0
	v_mul_f32_e32 v10, v6, v16
	v_fma_f32 v15, -v14, v10, v6
	v_fmac_f32_e32 v10, v15, v16
	v_fma_f32 v6, -v14, v10, v6
	v_div_fmas_f32 v6, v6, v16, v10
	v_div_fixup_f32 v12, v6, v12, 2.0
	v_pk_add_f32 v[12:13], v[12:13], 1.0 op_sel_hi:[1,0] neg_lo:[1,0] neg_hi:[1,0]
	v_mov_b32_e32 v6, v11
	v_pk_mul_f32 v[6:7], v[6:7], 0.5 op_sel_hi:[1,0]
	v_pk_add_f32 v[10:11], v[12:13], 1.0 op_sel_hi:[1,0]
	v_mul_f32_e32 v13, 0x3d372713, v3
	v_pk_mul_f32 v[6:7], v[6:7], v[10:11]
	v_mul_f32_e32 v11, 0x3d372713, v1
	v_mul_f32_e32 v11, v1, v11
	v_fma_f32 v11, v1, v11, v1
	v_mul_f32_e32 v11, 0x3f4c422a, v11
	v_add_f32_e32 v11, v11, v11
	v_mul_f32_e32 v11, 0x3fb8aa3b, v11
	v_mul_f32_e32 v10, 0x3d372713, v0
	v_exp_f32_e32 v12, v11
	v_mul_f32_e32 v11, 0x3d372713, v2
	v_mul_f32_e32 v10, v0, v10
	v_mul_f32_e32 v11, v2, v11
	v_fma_f32 v10, v0, v10, v0
	v_fma_f32 v11, v2, v11, v2
	v_mul_f32_e32 v10, 0x3f4c422a, v10
	v_mul_f32_e32 v11, 0x3f4c422a, v11
	v_add_f32_e32 v10, v10, v10
	v_add_f32_e32 v11, v11, v11
	v_mul_f32_e32 v10, 0x3fb8aa3b, v10
	v_mul_f32_e32 v11, 0x3fb8aa3b, v11
	v_exp_f32_e32 v10, v10
	v_exp_f32_e32 v11, v11
	v_mul_f32_e32 v13, v3, v13
	v_fma_f32 v13, v3, v13, v3
	v_mul_f32_e32 v13, 0x3f4c422a, v13
	v_pk_add_f32 v[10:11], v[10:11], 1.0 op_sel_hi:[1,0]
	v_add_f32_e32 v13, v13, v13
	v_div_scale_f32 v14, s[0:1], v11, v11, 2.0
	v_rcp_f32_e32 v15, v14
	v_mul_f32_e32 v13, 0x3fb8aa3b, v13
	v_exp_f32_e32 v13, v13
	v_fma_f32 v16, -v14, v15, 1.0
	v_fmac_f32_e32 v15, v16, v15
	v_div_scale_f32 v16, vcc, 2.0, v11, 2.0
	v_mul_f32_e32 v17, v16, v15
	v_fma_f32 v18, -v14, v17, v16
	v_fmac_f32_e32 v17, v18, v15
	v_fma_f32 v14, -v14, v17, v16
	v_div_scale_f32 v16, s[0:1], v10, v10, 2.0
	v_rcp_f32_e32 v18, v16
	v_div_fmas_f32 v14, v14, v15, v17
	v_div_fixup_f32 v11, v14, v11, 2.0
	v_pk_add_f32 v[12:13], v[12:13], 1.0 op_sel_hi:[1,0]
	v_fma_f32 v14, -v16, v18, 1.0
	v_fmac_f32_e32 v18, v14, v18
	v_div_scale_f32 v14, vcc, 2.0, v10, 2.0
	v_mul_f32_e32 v15, v14, v18
	v_fma_f32 v17, -v16, v15, v14
	v_fmac_f32_e32 v15, v17, v18
	v_fma_f32 v14, -v16, v15, v14
	v_div_fmas_f32 v14, v14, v18, v15
	v_div_fixup_f32 v10, v14, v10, 2.0
	v_mov_b32_e32 v14, v0
	v_div_scale_f32 v0, s[0:1], v13, v13, 2.0
	v_mov_b32_e32 v15, v2
	v_rcp_f32_e32 v2, v0
	v_pk_add_f32 v[10:11], v[10:11], 1.0 op_sel_hi:[1,0] neg_lo:[1,0] neg_hi:[1,0]
	v_pk_mul_f32 v[14:15], v[14:15], 0.5 op_sel_hi:[1,0]
	v_pk_add_f32 v[10:11], v[10:11], 1.0 op_sel_hi:[1,0]
	s_nop 0
	v_pk_mul_f32 v[10:11], v[14:15], v[10:11]
	v_fma_f32 v14, -v0, v2, 1.0
	v_fmac_f32_e32 v2, v14, v2
	v_div_scale_f32 v14, vcc, 2.0, v13, 2.0
	v_mul_f32_e32 v15, v14, v2
	v_fma_f32 v16, -v0, v15, v14
	v_fmac_f32_e32 v15, v16, v2
	v_fma_f32 v0, -v0, v15, v14
	v_div_scale_f32 v14, s[0:1], v12, v12, 2.0
	v_rcp_f32_e32 v16, v14
	v_div_fmas_f32 v0, v0, v2, v15
	v_div_fixup_f32 v13, v0, v13, 2.0
	s_mov_b64 s[0:1], -1
	v_fma_f32 v0, -v14, v16, 1.0
	v_fmac_f32_e32 v16, v0, v16
	v_div_scale_f32 v0, vcc, 2.0, v12, 2.0
	v_mul_f32_e32 v2, v0, v16
	v_fma_f32 v15, -v14, v2, v0
	v_fmac_f32_e32 v2, v15, v16
	v_fma_f32 v0, -v14, v2, v0
	v_div_fmas_f32 v0, v0, v16, v2
	v_div_fixup_f32 v12, v0, v12, 2.0
	v_pk_add_f32 v[12:13], v[12:13], 1.0 op_sel_hi:[1,0] neg_lo:[1,0] neg_hi:[1,0]
	v_mov_b32_e32 v2, v1
	v_pk_mul_f32 v[0:1], v[2:3], 0.5 op_sel_hi:[1,0]
	v_pk_add_f32 v[2:3], v[12:13], 1.0 op_sel_hi:[1,0]
	v_pk_mul_f32 v[0:1], v[0:1], v[2:3]
	v_cvt_pk_bf16_f32 v3, v11, v1
	v_cvt_pk_bf16_f32 v2, v10, v0
	v_cvt_pk_bf16_f32 v1, v5, v7
	v_cvt_pk_bf16_f32 v0, v4, v6
	s_and_b64 vcc, exec, s[6:7]
	global_store_dwordx4 v[8:9], v[0:3], off offset:256
	s_cbranch_vccnz .LBB0_2452
	s_andn2_b64 vcc, exec, s[28:29]
	s_cbranch_vccnz .LBB0_2451
	s_barrier
	s_branch .LBB0_2451

; __device__ __forceinline__ unsigned f2bf_(float f) { unsigned u = __builtin_bit_cast(unsigned, f); return (u + 0x7fffu + ((u >> 16) & 1u)) >> 16; }
; __device__ __forceinline__ unsigned pk2_(float lo, float hi) { return f2bf_(lo) | (f2bf_(hi) << 16); }
;     __device__ __forceinline__ void operator()(const f32x4 (&acc)[2][2][4][2], const Unit& u, int wr, int wc, int fr, int fq) const {
;     ...
;                 for (int bj = 0; bj < 2; ++bj) { f32x4 v0 = acc[ai][bj][m][0], v1 = acc[ai][bj][m][1];
;                     if (bias) { v0 += *(const f32x4*)(bias + col0 + bj * HALF); v1 += *(const f32x4*)(bias + col0 + bj * HALF + 4); }
;                     u32x4 w; w.x = pk2_(act_f<ACT>(v0[0]), act_f<ACT>(v0[1])); w.y = pk2_(act_f<ACT>(v0[2]), act_f<ACT>(v0[3]));
;                     w.z = pk2_(act_f<ACT>(v1[0]), act_f<ACT>(v1[1])); w.w = pk2_(act_f<ACT>(v1[2]), act_f<ACT>(v1[3]));
;                     *(u32x4*)(rowp + bj * HALF) = w; } }
.LBB0_2532:
	v_cvt_pk_bf16_f32 v124, v124, v125
	v_cvt_pk_bf16_f32 v125, v126, v127
	v_cvt_pk_bf16_f32 v126, v120, v121
	v_cvt_pk_bf16_f32 v127, v122, v123
	v_cvt_pk_bf16_f32 v116, v116, v117
	v_cvt_pk_bf16_f32 v117, v118, v119
	v_cvt_pk_bf16_f32 v118, v108, v109
	v_cvt_pk_bf16_f32 v119, v110, v111
	v_cvt_pk_bf16_f32 v108, v112, v113
	s_lshl_b32 s4, s38, 8
	v_mov_b32_e32 v137, v140
	v_mov_b32_e32 v136, v139
	s_add_i32 s4, s4, s90
	v_cvt_pk_bf16_f32 v109, v114, v115
	s_lshl_b32 s5, s95, 8
	v_add_u32_e32 v144, s4, v137
	s_or_b32 s5, s5, s91
	v_ashrrev_i32_e32 v145, 31, v144
	v_lshl_add_u32 v136, v136, 3, s5
	v_lshlrev_b64 v[144:145], 12, v[144:145]
	v_cvt_pk_bf16_f32 v110, v104, v105
	v_ashrrev_i32_e32 v137, 31, v136
	v_lshl_add_u64 v[144:145], s[10:11], 0, v[144:145]
	v_lshl_add_u64 v[136:137], v[136:137], 1, v[144:145]
	v_cvt_pk_bf16_f32 v111, v106, v107
	v_add_co_u32_e32 v104, vcc, s78, v136
	global_store_dwordx4 v[136:137], v[116:119], off offset:256
	s_nop 0
	v_addc_co_u32_e32 v105, vcc, 0, v137, vcc
	global_store_dwordx4 v[104:105], v[108:111], off
	v_cvt_pk_bf16_f32 v100, v100, v101
	v_cvt_pk_bf16_f32 v101, v102, v103
	v_cvt_pk_bf16_f32 v102, v92, v93
	v_cvt_pk_bf16_f32 v103, v94, v95
	v_cvt_pk_bf16_f32 v92, v96, v97
	v_cvt_pk_bf16_f32 v93, v98, v99
	v_cvt_pk_bf16_f32 v94, v88, v89
	v_lshl_add_u64 v[116:117], v[136:137], 0, s[0:1]
	s_mov_b64 s[4:5], 0x20000
	global_store_dwordx4 v[116:117], v[100:103], off offset:256
	s_nop 1
	v_lshl_add_u64 v[100:101], v[136:137], 0, s[4:5]
	s_mov_b32 s4, 0x20000
	v_cvt_pk_bf16_f32 v95, v90, v91
	v_add_co_u32_e32 v88, vcc, s4, v136
	s_mov_b64 s[4:5], 0x30000
	s_nop 0
	v_addc_co_u32_e32 v89, vcc, 0, v137, vcc
	global_store_dwordx4 v[88:89], v[92:95], off
	v_cvt_pk_bf16_f32 v84, v84, v85
	v_cvt_pk_bf16_f32 v85, v86, v87
	v_cvt_pk_bf16_f32 v86, v76, v77
	v_cvt_pk_bf16_f32 v87, v78, v79
	v_cvt_pk_bf16_f32 v76, v80, v81
	v_cvt_pk_bf16_f32 v77, v82, v83
	v_cvt_pk_bf16_f32 v78, v72, v73
	global_store_dwordx4 v[100:101], v[84:87], off offset:256
	s_nop 1
	v_lshl_add_u64 v[84:85], v[136:137], 0, s[4:5]
	s_mov_b32 s4, 0x30000
	v_cvt_pk_bf16_f32 v79, v74, v75
	v_add_co_u32_e32 v72, vcc, s4, v136
	s_mov_b64 s[4:5], 0x80000
	s_nop 0
	v_addc_co_u32_e32 v73, vcc, 0, v137, vcc
	global_store_dwordx4 v[72:73], v[76:79], off
	v_cvt_pk_bf16_f32 v68, v68, v69
	v_cvt_pk_bf16_f32 v69, v70, v71
	v_cvt_pk_bf16_f32 v70, v64, v65
	v_cvt_pk_bf16_f32 v60, v60, v61
	v_cvt_pk_bf16_f32 v61, v62, v63
	v_cvt_pk_bf16_f32 v62, v56, v57
	v_cvt_pk_bf16_f32 v71, v66, v67
	v_lshl_add_u64 v[64:65], v[136:137], 0, s[4:5]
	s_mov_b32 s4, 0x80000
	v_cvt_pk_bf16_f32 v63, v58, v59
	v_add_co_u32_e32 v56, vcc, s4, v136
	s_mov_b64 s[4:5], 0x90000
	s_nop 0
	v_addc_co_u32_e32 v57, vcc, 0, v137, vcc
	global_store_dwordx4 v[56:57], v[60:63], off
	v_cvt_pk_bf16_f32 v52, v52, v53
	v_cvt_pk_bf16_f32 v53, v54, v55
	v_cvt_pk_bf16_f32 v54, v44, v45
	v_cvt_pk_bf16_f32 v55, v46, v47
	v_cvt_pk_bf16_f32 v44, v48, v49
	v_cvt_pk_bf16_f32 v45, v50, v51
	v_cvt_pk_bf16_f32 v46, v40, v41
	global_store_dwordx4 v[64:65], v[52:55], off offset:256
	s_nop 1
	v_lshl_add_u64 v[52:53], v[136:137], 0, s[4:5]
	s_mov_b32 s4, 0x90000
	v_cvt_pk_bf16_f32 v47, v42, v43
	v_add_co_u32_e32 v40, vcc, s4, v136
	s_mov_b64 s[4:5], 0xa0000
	s_nop 0
	v_addc_co_u32_e32 v41, vcc, 0, v137, vcc
	global_store_dwordx4 v[40:41], v[44:47], off
	v_cvt_pk_bf16_f32 v36, v36, v37
	v_cvt_pk_bf16_f32 v37, v38, v39
	v_cvt_pk_bf16_f32 v38, v28, v29
	v_cvt_pk_bf16_f32 v39, v30, v31
	v_cvt_pk_bf16_f32 v28, v32, v33
	v_cvt_pk_bf16_f32 v29, v34, v35
	v_cvt_pk_bf16_f32 v30, v24, v25
	global_store_dwordx4 v[52:53], v[36:39], off offset:256
	s_nop 1
	v_lshl_add_u64 v[36:37], v[136:137], 0, s[4:5]
	s_mov_b32 s4, 0xa0000
	v_cvt_pk_bf16_f32 v31, v26, v27
	v_add_co_u32_e32 v24, vcc, s4, v136
	s_mov_b64 s[4:5], 0xb0000
	s_nop 0
	v_addc_co_u32_e32 v25, vcc, 0, v137, vcc
	global_store_dwordx4 v[24:25], v[28:31], off
	v_cvt_pk_bf16_f32 v20, v20, v21
	v_cvt_pk_bf16_f32 v21, v22, v23
	v_cvt_pk_bf16_f32 v22, v12, v13
	v_cvt_pk_bf16_f32 v23, v14, v15
	v_cvt_pk_bf16_f32 v12, v16, v17
	v_cvt_pk_bf16_f32 v13, v18, v19
	v_cvt_pk_bf16_f32 v14, v8, v9
	global_store_dwordx4 v[36:37], v[20:23], off offset:256
	s_nop 1
	v_lshl_add_u64 v[20:21], v[136:137], 0, s[4:5]
	s_mov_b32 s4, 0xb0000
	v_cvt_pk_bf16_f32 v15, v10, v11
	v_add_co_u32_e32 v8, vcc, s4, v136
	global_store_dwordx4 v[136:137], v[124:127], off
	s_nop 0
	v_addc_co_u32_e32 v9, vcc, 0, v137, vcc
	global_store_dwordx4 v[8:9], v[12:15], off
	v_cvt_pk_bf16_f32 v4, v4, v5
	v_cvt_pk_bf16_f32 v5, v6, v7
	v_cvt_pk_bf16_f32 v6, v0, v1
	v_cvt_pk_bf16_f32 v7, v2, v3
	s_andn2_b64 vcc, exec, s[30:31]
	s_mov_b64 s[30:31], -1
	global_store_dwordx4 v[84:85], v[68:71], off offset:256
	global_store_dwordx4 v[20:21], v[4:7], off offset:256
	s_cbranch_vccnz .LBB0_2525
	s_andn2_b64 vcc, exec, s[8:9]
	s_cbranch_vccnz .LBB0_2524
	s_barrier
	s_branch .LBB0_2524

; __device__ __forceinline__ unsigned f2bf_(float f) { unsigned u = __builtin_bit_cast(unsigned, f); return (u + 0x7fffu + ((u >> 16) & 1u)) >> 16; }
; __device__ __forceinline__ unsigned pk2_(float lo, float hi) { return f2bf_(lo) | (f2bf_(hi) << 16); }
;     __device__ __forceinline__ void operator()(const f32x4 (&acc)[2][2][4][2], const Unit& u, int wr, int wc, int fr, int fq) const {
;     ...
;                 for (int bj = 0; bj < 2; ++bj) { f32x4 v0 = acc[ai][bj][m][0], v1 = acc[ai][bj][m][1];
;                     if (bias) { v0 += *(const f32x4*)(bias + col0 + bj * HALF); v1 += *(const f32x4*)(bias + col0 + bj * HALF + 4); }
;                     u32x4 w; w.x = pk2_(act_f<ACT>(v0[0]), act_f<ACT>(v0[1])); w.y = pk2_(act_f<ACT>(v0[2]), act_f<ACT>(v0[3]));
;                     w.z = pk2_(act_f<ACT>(v1[0]), act_f<ACT>(v1[1])); w.w = pk2_(act_f<ACT>(v1[2]), act_f<ACT>(v1[3]));
;                     *(u32x4*)(rowp + bj * HALF) = w; } }
.LBB0_2550:
	v_cvt_pk_bf16_f32 v124, v124, v125
	v_cvt_pk_bf16_f32 v125, v126, v127
	v_cvt_pk_bf16_f32 v126, v120, v121
	v_cvt_pk_bf16_f32 v127, v122, v123
	v_cvt_pk_bf16_f32 v116, v116, v117
	v_cvt_pk_bf16_f32 v117, v118, v119
	v_cvt_pk_bf16_f32 v118, v108, v109
	v_cvt_pk_bf16_f32 v119, v110, v111
	v_cvt_pk_bf16_f32 v108, v112, v113
	s_lshl_b32 s4, s38, 8
	v_mov_b32_e32 v137, v140
	v_mov_b32_e32 v136, v139
	s_add_i32 s4, s4, s84
	s_lshl_b32 s5, s94, 8
	v_add_u32_e32 v144, s4, v137
	v_cvt_pk_bf16_f32 v109, v114, v115
	s_or_b32 s5, s5, s90
	v_ashrrev_i32_e32 v145, 31, v144
	v_lshl_add_u32 v136, v136, 3, s5
	v_lshlrev_b64 v[144:145], 9, v[144:145]
	v_ashrrev_i32_e32 v137, 31, v136
	v_lshl_add_u64 v[144:145], s[10:11], 0, v[144:145]
	v_cvt_pk_bf16_f32 v110, v104, v105
	v_lshl_add_u64 v[136:137], v[136:137], 1, v[144:145]
	s_mov_b64 s[4:5], 0x2000
	global_store_dwordx4 v[136:137], v[116:119], off offset:256
	s_nop 1
	v_lshl_add_u64 v[116:117], v[136:137], 0, s[4:5]
	s_movk_i32 s4, 0x2000
	v_cvt_pk_bf16_f32 v111, v106, v107
	v_add_co_u32_e32 v104, vcc, s4, v136
	s_mov_b64 s[4:5], 0x4000
	s_nop 0
	v_addc_co_u32_e32 v105, vcc, 0, v137, vcc
	global_store_dwordx4 v[104:105], v[108:111], off
	v_cvt_pk_bf16_f32 v100, v100, v101
	v_cvt_pk_bf16_f32 v101, v102, v103
	v_cvt_pk_bf16_f32 v102, v92, v93
	v_cvt_pk_bf16_f32 v103, v94, v95
	v_cvt_pk_bf16_f32 v92, v96, v97
	v_cvt_pk_bf16_f32 v93, v98, v99
	v_cvt_pk_bf16_f32 v94, v88, v89
	global_store_dwordx4 v[116:117], v[100:103], off offset:256
	s_nop 1
	v_lshl_add_u64 v[100:101], v[136:137], 0, s[4:5]
	s_movk_i32 s4, 0x4000
	v_cvt_pk_bf16_f32 v95, v90, v91
	v_add_co_u32_e32 v88, vcc, s4, v136
	s_mov_b64 s[4:5], 0x6000
	s_nop 0
	v_addc_co_u32_e32 v89, vcc, 0, v137, vcc
	global_store_dwordx4 v[88:89], v[92:95], off
	v_cvt_pk_bf16_f32 v84, v84, v85
	v_cvt_pk_bf16_f32 v85, v86, v87
	v_cvt_pk_bf16_f32 v86, v76, v77
	v_cvt_pk_bf16_f32 v87, v78, v79
	v_cvt_pk_bf16_f32 v76, v80, v81
	v_cvt_pk_bf16_f32 v77, v82, v83
	v_cvt_pk_bf16_f32 v78, v72, v73
	global_store_dwordx4 v[100:101], v[84:87], off offset:256
	s_nop 1
	v_lshl_add_u64 v[84:85], v[136:137], 0, s[4:5]
	s_movk_i32 s4, 0x6000
	v_cvt_pk_bf16_f32 v79, v74, v75
	v_add_co_u32_e32 v72, vcc, s4, v136
	s_mov_b64 s[4:5], 0x12000
	s_nop 0
	v_addc_co_u32_e32 v73, vcc, 0, v137, vcc
	global_store_dwordx4 v[72:73], v[76:79], off
	v_cvt_pk_bf16_f32 v68, v68, v69
	v_cvt_pk_bf16_f32 v69, v70, v71
	v_cvt_pk_bf16_f32 v70, v64, v65
	v_cvt_pk_bf16_f32 v60, v60, v61
	v_cvt_pk_bf16_f32 v61, v62, v63
	v_cvt_pk_bf16_f32 v62, v56, v57
	v_cvt_pk_bf16_f32 v63, v58, v59
	v_add_co_u32_e32 v56, vcc, s78, v136
	s_nop 0
	v_addc_co_u32_e32 v57, vcc, 0, v137, vcc
	global_store_dwordx4 v[56:57], v[60:63], off
	v_cvt_pk_bf16_f32 v52, v52, v53
	v_cvt_pk_bf16_f32 v53, v54, v55
	v_cvt_pk_bf16_f32 v54, v44, v45
	v_cvt_pk_bf16_f32 v55, v46, v47
	v_cvt_pk_bf16_f32 v44, v48, v49
	v_cvt_pk_bf16_f32 v45, v50, v51
	v_cvt_pk_bf16_f32 v46, v40, v41
	v_cvt_pk_bf16_f32 v71, v66, v67
	v_lshl_add_u64 v[64:65], v[136:137], 0, s[0:1]
	global_store_dwordx4 v[64:65], v[52:55], off offset:256
	s_nop 1
	v_lshl_add_u64 v[52:53], v[136:137], 0, s[4:5]
	s_mov_b32 s4, 0x12000
	v_cvt_pk_bf16_f32 v47, v42, v43
	v_add_co_u32_e32 v40, vcc, s4, v136
	s_mov_b64 s[4:5], 0x14000
	s_nop 0
	v_addc_co_u32_e32 v41, vcc, 0, v137, vcc
	global_store_dwordx4 v[40:41], v[44:47], off
	v_cvt_pk_bf16_f32 v36, v36, v37
	v_cvt_pk_bf16_f32 v37, v38, v39
	v_cvt_pk_bf16_f32 v38, v28, v29
	v_cvt_pk_bf16_f32 v39, v30, v31
	v_cvt_pk_bf16_f32 v28, v32, v33
	v_cvt_pk_bf16_f32 v29, v34, v35
	v_cvt_pk_bf16_f32 v30, v24, v25
	global_store_dwordx4 v[52:53], v[36:39], off offset:256
	s_nop 1
	v_lshl_add_u64 v[36:37], v[136:137], 0, s[4:5]
	s_mov_b32 s4, 0x14000
	v_cvt_pk_bf16_f32 v31, v26, v27
	v_add_co_u32_e32 v24, vcc, s4, v136
	s_mov_b64 s[4:5], 0x16000
	s_nop 0
	v_addc_co_u32_e32 v25, vcc, 0, v137, vcc
	global_store_dwordx4 v[24:25], v[28:31], off
	v_cvt_pk_bf16_f32 v20, v20, v21
	v_cvt_pk_bf16_f32 v21, v22, v23
	v_cvt_pk_bf16_f32 v22, v12, v13
	v_cvt_pk_bf16_f32 v23, v14, v15
	v_cvt_pk_bf16_f32 v12, v16, v17
	v_cvt_pk_bf16_f32 v13, v18, v19
	v_cvt_pk_bf16_f32 v14, v8, v9
	global_store_dwordx4 v[36:37], v[20:23], off offset:256
	s_nop 1
	v_lshl_add_u64 v[20:21], v[136:137], 0, s[4:5]
	s_mov_b32 s4, 0x16000
	v_cvt_pk_bf16_f32 v15, v10, v11
	v_add_co_u32_e32 v8, vcc, s4, v136
	global_store_dwordx4 v[136:137], v[124:127], off
	s_nop 0
	v_addc_co_u32_e32 v9, vcc, 0, v137, vcc
	global_store_dwordx4 v[8:9], v[12:15], off
	v_cvt_pk_bf16_f32 v4, v4, v5
	v_cvt_pk_bf16_f32 v5, v6, v7
	v_cvt_pk_bf16_f32 v6, v0, v1
	v_cvt_pk_bf16_f32 v7, v2, v3
	s_andn2_b64 vcc, exec, s[30:31]
	s_mov_b64 s[30:31], -1
	global_store_dwordx4 v[84:85], v[68:71], off offset:256
	global_store_dwordx4 v[20:21], v[4:7], off offset:256
	s_cbranch_vccnz .LBB0_2543
	s_andn2_b64 vcc, exec, s[8:9]
	s_cbranch_vccnz .LBB0_2542
	s_barrier
	s_branch .LBB0_2542

; #define LAS __attribute__((address_space(3)))
; #define MFMA32(a, b, c) __builtin_amdgcn_mfma_f32_32x32x16_bf16((a), (b), (c), 0, 0, 0)
; DEV unsigned pk2(float lo, float hi) { f32x2_ v; v.x = lo; v.y = hi; return __builtin_bit_cast(unsigned, __builtin_convertvector(v, bf16x2_)); }
; template <int DQK> DEV void qk_tile(f32x16 (&st)[2], const LAS unsigned char* kb, const bf16x8 (&qf)[DQK / 16], int r, int h) {
;     constexpr int KSTR = DQK * 2 + 16, NS = DQK / 16;
;     bf16x8 kf[2][NS];
; #pragma unroll
;     for (int b2 = 0; b2 < 2; ++b2)
; #pragma unroll
;         for (int s = 0; s < NS; ++s) kf[b2][s] = *(const LAS bf16x8*)(kb + (32 * b2 + r) * KSTR + 32 * s + 16 * h);
;     __builtin_amdgcn_sched_barrier(0);
; #pragma unroll
;     for (int b2 = 0; b2 < 2; ++b2) {
;         f32x16 a;
; #pragma unroll
;         for (int i = 0; i < 16; ++i) a[i] = 0.f;
; #pragma unroll
;         for (int s = 0; s < NS; ++s) a = MFMA32(kf[b2][s], qf[s], a);
;         st[b2] = a;
;     }
;     __builtin_amdgcn_sched_barrier(0);
; }
; DEV void pack_p(bf16x8 (&pf)[4], const f32x16 (&st)[2]) {
; #pragma unroll
;     for (int b2 = 0; b2 < 2; ++b2)
; #pragma unroll
;         for (int s = 0; s < 2; ++s) { u32x4 p; p.x = pk2(st[b2][8 * s], st[b2][8 * s + 1]); p.y = pk2(st[b2][8 * s + 2], st[b2][8 * s + 3]);
;             p.z = pk2(st[b2][8 * s + 4], st[b2][8 * s + 5]); p.w = pk2(st[b2][8 * s + 6], st[b2][8 * s + 7]); pf[2 * b2 + s] = __builtin_bit_cast(bf16x8, p); }
; }
; DEV void pv_load(bf16x8 (&vf)[2][4], const LAS unsigned char* vb, int r, int h) {
; #pragma unroll
;     for (int db = 0; db < 2; ++db)
; #pragma unroll
;         for (int f = 0; f < 4; ++f) { const LAS unsigned char* p = vb + (32 * db + r) * 136 + (16 * f + 4 * h) * 2;
;             const s16x4 lo = *(const LAS s16x4*)p, hi = *(const LAS s16x4*)(p + 16);
;             vf[db][f] = __builtin_shufflevector(lo, hi, 0, 1, 2, 3, 4, 5, 6, 7); }
;     __builtin_amdgcn_sched_barrier(0);
; template <int DQK, int MODE> ...
;     ...
;         if (__any(rowact ? 1 : 0)) {
;             f32x16 st[2];
;             qk_tile<DQK>(st, kb, qf, r, h);
;             bf16x8 vf[2][4];
;             if (MODE != 3) pv_load(vf, vb, r, h);
;             const bool interior = __all(((k0 + 63 <= hi_lim) && (k0 >= lo_lim)) ? 1 : 0);
.LBB0_2632:
	s_lshl_b32 s85, s55, 6
	s_or_b32 s0, s85, 63
	s_cmp_gt_i32 s0, 0xbfffffff
	v_cmp_le_i32_e32 vcc, s85, v131
	s_cselect_b64 s[12:13], -1, 0
	s_and_b64 vcc, vcc, s[12:13]
	s_cbranch_vccz .LBB0_2638
	s_mul_i32 s1, s84, 0x9c00
	v_add_u32_e32 v0, s1, v136
	ds_read_b128 v[2:5], v0
	ds_read_b128 v[6:9], v0 offset:32
	ds_read_b128 v[10:13], v0 offset:64
	ds_read_b128 v[14:17], v0 offset:96
	ds_read_b128 v[18:21], v0 offset:4608
	ds_read_b128 v[22:25], v0 offset:4640
	ds_read_b128 v[26:29], v0 offset:4672
	ds_read_b128 v[104:107], v0 offset:4704
	s_mul_i32 s1, s84, 0x6600
	s_setprio 1
	s_waitcnt lgkmcnt(7)
	v_mfma_f32_32x32x16_bf16 v[64:79], v[2:5], v[144:147], 0
	s_waitcnt lgkmcnt(6)
	v_mfma_f32_32x32x16_bf16 v[64:79], v[6:9], v[152:155], v[64:79]
	s_waitcnt lgkmcnt(5)
	v_mfma_f32_32x32x16_bf16 v[64:79], v[10:13], v[148:151], v[64:79]
	s_waitcnt lgkmcnt(4)
	v_mfma_f32_32x32x16_bf16 v[64:79], v[14:17], v[156:159], v[64:79]
	s_waitcnt lgkmcnt(3)
	v_mfma_f32_32x32x16_bf16 v[2:17], v[18:21], v[144:147], 0
	s_waitcnt lgkmcnt(2)
	v_mfma_f32_32x32x16_bf16 v[2:17], v[22:25], v[152:155], v[2:17]
	s_waitcnt lgkmcnt(1)
	v_mfma_f32_32x32x16_bf16 v[2:17], v[26:29], v[148:151], v[2:17]
	s_waitcnt lgkmcnt(0)
	v_mfma_f32_32x32x16_bf16 v[2:17], v[104:107], v[156:159], v[2:17]
	s_setprio 0
	v_add_u32_e32 v0, s1, v137
	ds_read2_b64 v[120:123], v0 offset1:2
	ds_read2_b64 v[26:29], v0 offset0:4 offset1:6
	ds_read2_b64 v[22:25], v0 offset0:8 offset1:10
	ds_read2_b64 v[18:21], v0 offset0:12 offset1:14
	v_add_u32_e32 v0, 0x1000, v0
	ds_read2_b64 v[116:119], v0 offset0:32 offset1:34
	ds_read2_b64 v[112:115], v0 offset0:36 offset1:38
	ds_read2_b64 v[108:111], v0 offset0:40 offset1:42
	ds_read2_b64 v[104:107], v0 offset0:44 offset1:46
	s_cmp_gt_i32 s85, 0xbfffffff
	v_cmp_le_i32_e32 vcc, s0, v131
	s_cselect_b64 s[0:1], -1, 0
	s_and_b64 s[0:1], s[0:1], vcc
	v_cndmask_b32_e64 v0, 0, 1, s[0:1]
	v_cmp_ne_u32_e32 vcc, 0, v0
	s_cmp_eq_u64 vcc, exec
	s_cbranch_scc1 .LBB0_2635
; DEV int crow(int i, int h) { return (i & 3) + 8 * (i >> 2) + 4 * h; }
; template <int DQK, int MODE> ...
;     ...
;             if (!interior) {
; #pragma unroll
;                 for (int b2 = 0; b2 < 2; ++b2)
; #pragma unroll
;                     for (int i = 0; i < 16; ++i) { const int key = k0 + 32 * b2 + crow(i, h); const bool vis = (key <= hi_lim) && (key >= lo_lim); st[b2][i] = vis ? st[b2][i] : -INFINITY; }
;             }
	v_add_u32_e32 v0, s85, v138
	v_cmp_gt_i32_e32 vcc, v0, v131
	v_cmp_gt_i32_e64 s[0:1], -2.0, v0
	s_or_b64 vcc, vcc, s[0:1]
	v_add_u32_e32 v30, 1, v0
	v_cndmask_b32_e32 v64, v64, v218, vcc
	v_cmp_gt_i32_e32 vcc, v30, v131
	v_cmp_gt_i32_e64 s[0:1], -2.0, v30
	s_or_b64 vcc, vcc, s[0:1]
	v_add_u32_e32 v30, 2, v0
	v_cndmask_b32_e32 v65, v65, v218, vcc
	v_cmp_gt_i32_e32 vcc, v30, v131
	v_cmp_gt_i32_e64 s[0:1], -2.0, v30
	s_or_b64 vcc, vcc, s[0:1]
	v_add_u32_e32 v30, 3, v0
	v_cndmask_b32_e32 v66, v66, v218, vcc
	v_cmp_gt_i32_e32 vcc, v30, v131
	v_cmp_gt_i32_e64 s[0:1], -2.0, v30
	s_or_b64 vcc, vcc, s[0:1]
	v_add_u32_e32 v30, 8, v0
	v_cndmask_b32_e32 v67, v67, v218, vcc
	v_cmp_gt_i32_e32 vcc, v30, v131
	v_cmp_gt_i32_e64 s[0:1], -2.0, v30
	s_or_b64 vcc, vcc, s[0:1]
	v_add_u32_e32 v30, 9, v0
	v_cndmask_b32_e32 v68, v68, v218, vcc
	v_cmp_gt_i32_e32 vcc, v30, v131
	v_cmp_gt_i32_e64 s[0:1], -2.0, v30
	s_or_b64 vcc, vcc, s[0:1]
	v_add_u32_e32 v30, 10, v0
	v_cndmask_b32_e32 v69, v69, v218, vcc
	v_cmp_gt_i32_e32 vcc, v30, v131
	v_cmp_gt_i32_e64 s[0:1], -2.0, v30
	s_or_b64 vcc, vcc, s[0:1]
	v_add_u32_e32 v30, 11, v0
	v_cndmask_b32_e32 v70, v70, v218, vcc
	v_cmp_gt_i32_e32 vcc, v30, v131
	v_cmp_gt_i32_e64 s[0:1], -2.0, v30
	s_or_b64 vcc, vcc, s[0:1]
	v_add_u32_e32 v30, 16, v0
	v_cndmask_b32_e32 v71, v71, v218, vcc
	v_cmp_gt_i32_e32 vcc, v30, v131
	v_cmp_gt_i32_e64 s[0:1], -2.0, v30
	s_or_b64 vcc, vcc, s[0:1]
	v_add_u32_e32 v30, 17, v0
	v_cndmask_b32_e32 v72, v72, v218, vcc
	v_cmp_gt_i32_e32 vcc, v30, v131
	v_cmp_gt_i32_e64 s[0:1], -2.0, v30
	s_or_b64 vcc, vcc, s[0:1]
	v_add_u32_e32 v30, 18, v0
	v_cndmask_b32_e32 v73, v73, v218, vcc
	v_cmp_gt_i32_e32 vcc, v30, v131
	v_cmp_gt_i32_e64 s[0:1], -2.0, v30
	s_or_b64 vcc, vcc, s[0:1]
	v_add_u32_e32 v30, 19, v0
	v_cndmask_b32_e32 v74, v74, v218, vcc
	v_cmp_gt_i32_e32 vcc, v30, v131
	v_cmp_gt_i32_e64 s[0:1], -2.0, v30
	s_or_b64 vcc, vcc, s[0:1]
	v_add_u32_e32 v30, 24, v0
	v_cndmask_b32_e32 v75, v75, v218, vcc
	v_cmp_gt_i32_e32 vcc, v30, v131
	v_cmp_gt_i32_e64 s[0:1], -2.0, v30
	s_or_b64 vcc, vcc, s[0:1]
	v_add_u32_e32 v30, 25, v0
	v_cndmask_b32_e32 v76, v76, v218, vcc
	v_cmp_gt_i32_e32 vcc, v30, v131
	v_cmp_gt_i32_e64 s[0:1], -2.0, v30
	s_or_b64 vcc, vcc, s[0:1]
	v_add_u32_e32 v30, 26, v0
	v_cndmask_b32_e32 v77, v77, v218, vcc
	v_cmp_gt_i32_e32 vcc, v30, v131
	v_cmp_gt_i32_e64 s[0:1], -2.0, v30
	s_or_b64 vcc, vcc, s[0:1]
	v_add_u32_e32 v30, 27, v0
	v_cndmask_b32_e32 v78, v78, v218, vcc
	v_cmp_gt_i32_e32 vcc, v30, v131
	v_cmp_gt_i32_e64 s[0:1], -2.0, v30
	s_or_b64 vcc, vcc, s[0:1]
	v_add_u32_e32 v30, 32, v0
	v_cndmask_b32_e32 v79, v79, v218, vcc
	v_cmp_gt_i32_e32 vcc, v30, v131
	v_cmp_gt_i32_e64 s[0:1], -2.0, v30
	s_or_b64 vcc, vcc, s[0:1]
	v_add_u32_e32 v30, 33, v0
	v_cndmask_b32_e32 v2, v2, v218, vcc
	v_cmp_gt_i32_e32 vcc, v30, v131
	v_cmp_gt_i32_e64 s[0:1], -2.0, v30
	s_or_b64 vcc, vcc, s[0:1]
	v_add_u32_e32 v30, 34, v0
	v_cndmask_b32_e32 v3, v3, v218, vcc
	v_cmp_gt_i32_e32 vcc, v30, v131
	v_cmp_gt_i32_e64 s[0:1], -2.0, v30
	s_or_b64 vcc, vcc, s[0:1]
	v_add_u32_e32 v30, 35, v0
	v_cndmask_b32_e32 v4, v4, v218, vcc
	v_cmp_gt_i32_e32 vcc, v30, v131
	v_cmp_gt_i32_e64 s[0:1], -2.0, v30
	s_or_b64 vcc, vcc, s[0:1]
	v_add_u32_e32 v30, 40, v0
	v_cndmask_b32_e32 v5, v5, v218, vcc
	v_cmp_gt_i32_e32 vcc, v30, v131
	v_cmp_gt_i32_e64 s[0:1], -2.0, v30
	s_or_b64 vcc, vcc, s[0:1]
	v_add_u32_e32 v30, 41, v0
	v_cndmask_b32_e32 v6, v6, v218, vcc
	v_cmp_gt_i32_e32 vcc, v30, v131
	v_cmp_gt_i32_e64 s[0:1], -2.0, v30
	s_or_b64 vcc, vcc, s[0:1]
	v_add_u32_e32 v30, 42, v0
	v_cndmask_b32_e32 v7, v7, v218, vcc
	v_cmp_gt_i32_e32 vcc, v30, v131
	v_cmp_gt_i32_e64 s[0:1], -2.0, v30
	s_or_b64 vcc, vcc, s[0:1]
	v_add_u32_e32 v30, 43, v0
	v_cndmask_b32_e32 v8, v8, v218, vcc
	v_cmp_gt_i32_e32 vcc, v30, v131
	v_cmp_gt_i32_e64 s[0:1], -2.0, v30
	s_or_b64 vcc, vcc, s[0:1]
	v_add_u32_e32 v30, 48, v0
	v_cndmask_b32_e32 v9, v9, v218, vcc
	v_cmp_gt_i32_e32 vcc, v30, v131
	v_cmp_gt_i32_e64 s[0:1], -2.0, v30
	s_or_b64 vcc, vcc, s[0:1]
	v_add_u32_e32 v30, 49, v0
	v_cndmask_b32_e32 v10, v10, v218, vcc
	v_cmp_gt_i32_e32 vcc, v30, v131
	v_cmp_gt_i32_e64 s[0:1], -2.0, v30
	s_or_b64 vcc, vcc, s[0:1]
	v_add_u32_e32 v30, 50, v0
	v_cndmask_b32_e32 v11, v11, v218, vcc
	v_cmp_gt_i32_e32 vcc, v30, v131
	v_cmp_gt_i32_e64 s[0:1], -2.0, v30
	s_or_b64 vcc, vcc, s[0:1]
	v_add_u32_e32 v30, 51, v0
	v_cndmask_b32_e32 v12, v12, v218, vcc
	v_cmp_gt_i32_e32 vcc, v30, v131
	v_cmp_gt_i32_e64 s[0:1], -2.0, v30
	s_or_b64 vcc, vcc, s[0:1]
	v_add_u32_e32 v30, 56, v0
	v_cndmask_b32_e32 v13, v13, v218, vcc
	v_cmp_gt_i32_e32 vcc, v30, v131
	v_cmp_gt_i32_e64 s[0:1], -2.0, v30
	s_or_b64 vcc, vcc, s[0:1]
	v_add_u32_e32 v30, 57, v0
	v_cndmask_b32_e32 v14, v14, v218, vcc
	v_cmp_gt_i32_e32 vcc, v30, v131
	v_cmp_gt_i32_e64 s[0:1], -2.0, v30
	s_or_b64 vcc, vcc, s[0:1]
	v_add_u32_e32 v30, 58, v0
	v_cndmask_b32_e32 v15, v15, v218, vcc
	v_cmp_gt_i32_e32 vcc, v30, v131
	v_cmp_gt_i32_e64 s[0:1], -2.0, v30
	s_or_b64 vcc, vcc, s[0:1]
	v_add_u32_e32 v0, 59, v0
	v_cndmask_b32_e32 v16, v16, v218, vcc
	v_cmp_gt_i32_e32 vcc, v0, v131
	v_cmp_gt_i32_e64 s[0:1], -2.0, v0
	s_or_b64 vcc, vcc, s[0:1]
	v_cndmask_b32_e32 v17, v17, v218, vcc

; #define LAS __attribute__((address_space(3)))
; #define MFMA32(a, b, c) __builtin_amdgcn_mfma_f32_32x32x16_bf16((a), (b), (c), 0, 0, 0)
; DEV unsigned pk2(float lo, float hi) { f32x2_ v; v.x = lo; v.y = hi; return __builtin_bit_cast(unsigned, __builtin_convertvector(v, bf16x2_)); }
; DEV float fexp2(float x) { return __builtin_amdgcn_exp2f(x); }
; DEV void pack_p(bf16x8 (&pf)[4], const f32x16 (&st)[2]) {
; #pragma unroll
;     for (int b2 = 0; b2 < 2; ++b2)
; #pragma unroll
;         for (int s = 0; s < 2; ++s) { u32x4 p; p.x = pk2(st[b2][8 * s], st[b2][8 * s + 1]); p.y = pk2(st[b2][8 * s + 2], st[b2][8 * s + 3]);
;             p.z = pk2(st[b2][8 * s + 4], st[b2][8 * s + 5]); p.w = pk2(st[b2][8 * s + 6], st[b2][8 * s + 7]); pf[2 * b2 + s] = __builtin_bit_cast(bf16x8, p); }
; }
; DEV void pv_load(bf16x8 (&vf)[2][4], const LAS unsigned char* vb, int r, int h) {
; #pragma unroll
;     for (int db = 0; db < 2; ++db)
; #pragma unroll
;         for (int f = 0; f < 4; ++f) { const LAS unsigned char* p = vb + (32 * db + r) * 136 + (16 * f + 4 * h) * 2;
;             const s16x4 lo = *(const LAS s16x4*)p, hi = *(const LAS s16x4*)(p + 16);
;             vf[db][f] = __builtin_shufflevector(lo, hi, 0, 1, 2, 3, 4, 5, 6, 7); }
;     __builtin_amdgcn_sched_barrier(0);
; }
; DEV void pv_mma(f32x16 (&o)[2], const bf16x8 (&vf)[2][4], const bf16x8 (&pf)[4]) {
;     __builtin_amdgcn_sched_barrier(0);
; #pragma unroll
;     for (int f = 0; f < 4; ++f)
; #pragma unroll
;         for (int db = 0; db < 2; ++db) o[db] = MFMA32(vf[db][f], pf[f], o[db]);
;     __builtin_amdgcn_sched_barrier(0);
; }
; template <int DQK, int MODE> ...
;     ...
;                 const float cb = rowsel ? -m_new : -INFINITY;
;                 float ps = 0.f;
; #pragma unroll
;                 for (int b2 = 0; b2 < 2; ++b2)
; #pragma unroll
;                     for (int i = 0; i < 16; ++i) { const float p = fexp2(__builtin_fmaf(st[b2][i], sc, cb)); st[b2][i] = p; ps += p; }
;                 l_run += ps;
;                 bf16x8 pf[4]; pack_p(pf, st);
;                 pv_mma(o, vf, pf);
.LBB0_2637:
	v_fma_f32 v30, v64, s66, -v0
	v_exp_f32_e32 v64, v30
	v_fma_f32 v31, v65, s66, -v0
	v_exp_f32_e32 v65, v31
	v_fma_f32 v30, v66, s66, -v0
	v_add_f32_e32 v140, 0, v64
	v_exp_f32_e32 v66, v30
	v_fma_f32 v31, v67, s66, -v0
	v_add_f32_e32 v140, v65, v140
	v_exp_f32_e32 v67, v31
	v_fma_f32 v30, v68, s66, -v0
	v_add_f32_e32 v140, v66, v140
	v_exp_f32_e32 v68, v30
	v_fma_f32 v31, v69, s66, -v0
	v_add_f32_e32 v140, v67, v140
	v_exp_f32_e32 v69, v31
	v_fma_f32 v30, v70, s66, -v0
	v_add_f32_e32 v140, v68, v140
	v_exp_f32_e32 v70, v30
	v_fma_f32 v31, v71, s66, -v0
	v_add_f32_e32 v140, v69, v140
	v_exp_f32_e32 v71, v31
	v_add_f32_e32 v140, v70, v140
	v_add_f32_e32 v140, v71, v140
	v_cvt_pk_bf16_f32 v64, v64, v65
	v_cvt_pk_bf16_f32 v65, v66, v67
	v_cvt_pk_bf16_f32 v66, v68, v69
	v_cvt_pk_bf16_f32 v67, v70, v71
	v_fma_f32 v30, v72, s66, -v0
	v_exp_f32_e32 v72, v30
	v_fma_f32 v31, v73, s66, -v0
	v_exp_f32_e32 v73, v31
	v_mfma_f32_32x32x16_bf16 v[32:47], v[120:123], v[64:67], v[32:47]
	v_mfma_f32_32x32x16_bf16 v[48:63], v[116:119], v[64:67], v[48:63]
	v_fma_f32 v30, v74, s66, -v0
	v_add_f32_e32 v140, v72, v140
	v_exp_f32_e32 v74, v30
	v_fma_f32 v31, v75, s66, -v0
	v_add_f32_e32 v140, v73, v140
	v_exp_f32_e32 v75, v31
	v_fma_f32 v30, v76, s66, -v0
	v_add_f32_e32 v140, v74, v140
	v_exp_f32_e32 v76, v30
	v_fma_f32 v31, v77, s66, -v0
	v_add_f32_e32 v140, v75, v140
	v_exp_f32_e32 v77, v31
	v_fma_f32 v30, v78, s66, -v0
	v_add_f32_e32 v140, v76, v140
	v_exp_f32_e32 v78, v30
	v_fma_f32 v31, v79, s66, -v0
	v_add_f32_e32 v140, v77, v140
	v_exp_f32_e32 v79, v31
	v_add_f32_e32 v140, v78, v140
	v_add_f32_e32 v140, v79, v140
	v_cvt_pk_bf16_f32 v72, v72, v73
	v_cvt_pk_bf16_f32 v73, v74, v75
	v_cvt_pk_bf16_f32 v74, v76, v77
	v_cvt_pk_bf16_f32 v75, v78, v79
	v_fma_f32 v30, v2, s66, -v0
	v_exp_f32_e32 v2, v30
	v_fma_f32 v31, v3, s66, -v0
	v_exp_f32_e32 v3, v31
	v_mfma_f32_32x32x16_bf16 v[32:47], v[26:29], v[72:75], v[32:47]
	v_mfma_f32_32x32x16_bf16 v[48:63], v[112:115], v[72:75], v[48:63]
	v_fma_f32 v30, v4, s66, -v0
	v_add_f32_e32 v140, v2, v140
	v_exp_f32_e32 v4, v30
	v_fma_f32 v31, v5, s66, -v0
	v_add_f32_e32 v140, v3, v140
	v_exp_f32_e32 v5, v31
	v_fma_f32 v30, v6, s66, -v0
	v_add_f32_e32 v140, v4, v140
	v_exp_f32_e32 v6, v30
	v_fma_f32 v31, v7, s66, -v0
	v_add_f32_e32 v140, v5, v140
	v_exp_f32_e32 v7, v31
	v_fma_f32 v30, v8, s66, -v0
	v_add_f32_e32 v140, v6, v140
	v_exp_f32_e32 v8, v30
	v_fma_f32 v31, v9, s66, -v0
	v_add_f32_e32 v140, v7, v140
	v_exp_f32_e32 v9, v31
	v_add_f32_e32 v140, v8, v140
	v_add_f32_e32 v140, v9, v140
	v_cvt_pk_bf16_f32 v2, v2, v3
	v_cvt_pk_bf16_f32 v3, v4, v5
	v_cvt_pk_bf16_f32 v4, v6, v7
	v_cvt_pk_bf16_f32 v5, v8, v9
	v_fma_f32 v30, v10, s66, -v0
	v_exp_f32_e32 v10, v30
	v_fma_f32 v31, v11, s66, -v0
	v_exp_f32_e32 v11, v31
	v_mfma_f32_32x32x16_bf16 v[32:47], v[22:25], v[2:5], v[32:47]
	v_mfma_f32_32x32x16_bf16 v[48:63], v[108:111], v[2:5], v[48:63]
	v_fma_f32 v30, v12, s66, -v0
	v_add_f32_e32 v140, v10, v140
	v_exp_f32_e32 v12, v30
	v_fma_f32 v31, v13, s66, -v0
	v_add_f32_e32 v140, v11, v140
	v_exp_f32_e32 v13, v31
	v_fma_f32 v30, v14, s66, -v0
	v_add_f32_e32 v140, v12, v140
	v_exp_f32_e32 v14, v30
	v_fma_f32 v31, v15, s66, -v0
	v_add_f32_e32 v140, v13, v140
	v_exp_f32_e32 v15, v31
	v_fma_f32 v30, v16, s66, -v0
	v_add_f32_e32 v140, v14, v140
	v_exp_f32_e32 v16, v30
	v_fma_f32 v31, v17, s66, -v0
	v_add_f32_e32 v140, v15, v140
	v_exp_f32_e32 v17, v31
	v_add_f32_e32 v140, v16, v140
	v_add_f32_e32 v140, v17, v140
	v_cvt_pk_bf16_f32 v10, v10, v11
	v_cvt_pk_bf16_f32 v11, v12, v13
	v_cvt_pk_bf16_f32 v12, v14, v15
	v_cvt_pk_bf16_f32 v13, v16, v17
	v_add_f32_e32 v135, v140, v135
	s_nop 0
	v_mfma_f32_32x32x16_bf16 v[32:47], v[18:21], v[10:13], v[32:47]
	v_mfma_f32_32x32x16_bf16 v[48:63], v[104:107], v[10:13], v[48:63]
.LBB0_2638:
	s_cmp_ge_i32 s55, s4
	s_mul_i32 s24, s84, 3
	s_cbranch_scc1 .LBB0_2645
	s_add_i32 s85, s85, 64
	s_or_b32 s0, s85, 63
	s_cmp_gt_i32 s0, 0xbfffffff
	v_cmp_le_i32_e32 vcc, s85, v131
	s_cselect_b64 s[12:13], -1, 0
	s_and_b64 vcc, vcc, s[12:13]
	s_cbranch_vccz .LBB0_2645
	s_add_i32 s1, s24, 1
	s_mul_i32 s12, s1, 0x3400
	v_add_u32_e32 v0, s12, v136
	ds_read_b128 v[2:5], v0
	ds_read_b128 v[6:9], v0 offset:32
	ds_read_b128 v[10:13], v0 offset:64
	ds_read_b128 v[14:17], v0 offset:96
	ds_read_b128 v[18:21], v0 offset:4608
	ds_read_b128 v[22:25], v0 offset:4640
	ds_read_b128 v[26:29], v0 offset:4672
	ds_read_b128 v[104:107], v0 offset:4704
	s_mulk_i32 s1, 0x2200
	s_setprio 1
	s_waitcnt lgkmcnt(7)
	v_mfma_f32_32x32x16_bf16 v[64:79], v[2:5], v[144:147], 0
	s_waitcnt lgkmcnt(6)
	v_mfma_f32_32x32x16_bf16 v[64:79], v[6:9], v[152:155], v[64:79]
	s_waitcnt lgkmcnt(5)
	v_mfma_f32_32x32x16_bf16 v[64:79], v[10:13], v[148:151], v[64:79]
	s_waitcnt lgkmcnt(4)
	v_mfma_f32_32x32x16_bf16 v[64:79], v[14:17], v[156:159], v[64:79]
	s_waitcnt lgkmcnt(3)
	v_mfma_f32_32x32x16_bf16 v[2:17], v[18:21], v[144:147], 0
	s_waitcnt lgkmcnt(2)
	v_mfma_f32_32x32x16_bf16 v[2:17], v[22:25], v[152:155], v[2:17]
	s_waitcnt lgkmcnt(1)
	v_mfma_f32_32x32x16_bf16 v[2:17], v[26:29], v[148:151], v[2:17]
	s_waitcnt lgkmcnt(0)
	v_mfma_f32_32x32x16_bf16 v[2:17], v[104:107], v[156:159], v[2:17]
	s_setprio 0
	v_add_u32_e32 v0, s1, v137
	ds_read2_b64 v[120:123], v0 offset1:2
	ds_read2_b64 v[26:29], v0 offset0:4 offset1:6
	ds_read2_b64 v[22:25], v0 offset0:8 offset1:10
	ds_read2_b64 v[18:21], v0 offset0:12 offset1:14
	v_add_u32_e32 v0, 0x1000, v0
	ds_read2_b64 v[116:119], v0 offset0:32 offset1:34
	ds_read2_b64 v[112:115], v0 offset0:36 offset1:38
	ds_read2_b64 v[108:111], v0 offset0:40 offset1:42
	ds_read2_b64 v[104:107], v0 offset0:44 offset1:46
	s_cmp_gt_i32 s85, 0xbfffffff
	v_cmp_le_i32_e32 vcc, s0, v131
	s_cselect_b64 s[0:1], -1, 0
	s_and_b64 s[0:1], s[0:1], vcc
	v_cndmask_b32_e64 v0, 0, 1, s[0:1]
	v_cmp_ne_u32_e32 vcc, 0, v0
	s_cmp_eq_u64 vcc, exec
	s_cbranch_scc1 .LBB0_2642
; DEV int crow(int i, int h) { return (i & 3) + 8 * (i >> 2) + 4 * h; }
; template <int DQK, int MODE> ...
;     ...
;             if (!interior) {
; #pragma unroll
;                 for (int b2 = 0; b2 < 2; ++b2)
; #pragma unroll
;                     for (int i = 0; i < 16; ++i) { const int key = k0 + 32 * b2 + crow(i, h); const bool vis = (key <= hi_lim) && (key >= lo_lim); st[b2][i] = vis ? st[b2][i] : -INFINITY; }
;             }
	v_add_u32_e32 v0, s85, v138
	v_cmp_gt_i32_e32 vcc, v0, v131
	v_cmp_gt_i32_e64 s[0:1], -2.0, v0
	s_or_b64 vcc, vcc, s[0:1]
	v_add_u32_e32 v30, 1, v0
	v_cndmask_b32_e32 v64, v64, v218, vcc
	v_cmp_gt_i32_e32 vcc, v30, v131
	v_cmp_gt_i32_e64 s[0:1], -2.0, v30
	s_or_b64 vcc, vcc, s[0:1]
	v_add_u32_e32 v30, 2, v0
	v_cndmask_b32_e32 v65, v65, v218, vcc
	v_cmp_gt_i32_e32 vcc, v30, v131
	v_cmp_gt_i32_e64 s[0:1], -2.0, v30
	s_or_b64 vcc, vcc, s[0:1]
	v_add_u32_e32 v30, 3, v0
	v_cndmask_b32_e32 v66, v66, v218, vcc
	v_cmp_gt_i32_e32 vcc, v30, v131
	v_cmp_gt_i32_e64 s[0:1], -2.0, v30
	s_or_b64 vcc, vcc, s[0:1]
	v_add_u32_e32 v30, 8, v0
	v_cndmask_b32_e32 v67, v67, v218, vcc
	v_cmp_gt_i32_e32 vcc, v30, v131
	v_cmp_gt_i32_e64 s[0:1], -2.0, v30
	s_or_b64 vcc, vcc, s[0:1]
	v_add_u32_e32 v30, 9, v0
	v_cndmask_b32_e32 v68, v68, v218, vcc
	v_cmp_gt_i32_e32 vcc, v30, v131
	v_cmp_gt_i32_e64 s[0:1], -2.0, v30
	s_or_b64 vcc, vcc, s[0:1]
	v_add_u32_e32 v30, 10, v0
	v_cndmask_b32_e32 v69, v69, v218, vcc
	v_cmp_gt_i32_e32 vcc, v30, v131
	v_cmp_gt_i32_e64 s[0:1], -2.0, v30
	s_or_b64 vcc, vcc, s[0:1]
	v_add_u32_e32 v30, 11, v0
	v_cndmask_b32_e32 v70, v70, v218, vcc
	v_cmp_gt_i32_e32 vcc, v30, v131
	v_cmp_gt_i32_e64 s[0:1], -2.0, v30
	s_or_b64 vcc, vcc, s[0:1]
	v_add_u32_e32 v30, 16, v0
	v_cndmask_b32_e32 v71, v71, v218, vcc
	v_cmp_gt_i32_e32 vcc, v30, v131
	v_cmp_gt_i32_e64 s[0:1], -2.0, v30
	s_or_b64 vcc, vcc, s[0:1]
	v_add_u32_e32 v30, 17, v0
	v_cndmask_b32_e32 v72, v72, v218, vcc
	v_cmp_gt_i32_e32 vcc, v30, v131
	v_cmp_gt_i32_e64 s[0:1], -2.0, v30
	s_or_b64 vcc, vcc, s[0:1]
	v_add_u32_e32 v30, 18, v0
	v_cndmask_b32_e32 v73, v73, v218, vcc
	v_cmp_gt_i32_e32 vcc, v30, v131
	v_cmp_gt_i32_e64 s[0:1], -2.0, v30
	s_or_b64 vcc, vcc, s[0:1]
	v_add_u32_e32 v30, 19, v0
	v_cndmask_b32_e32 v74, v74, v218, vcc
	v_cmp_gt_i32_e32 vcc, v30, v131
	v_cmp_gt_i32_e64 s[0:1], -2.0, v30
	s_or_b64 vcc, vcc, s[0:1]
	v_add_u32_e32 v30, 24, v0
	v_cndmask_b32_e32 v75, v75, v218, vcc
	v_cmp_gt_i32_e32 vcc, v30, v131
	v_cmp_gt_i32_e64 s[0:1], -2.0, v30
	s_or_b64 vcc, vcc, s[0:1]
	v_add_u32_e32 v30, 25, v0
	v_cndmask_b32_e32 v76, v76, v218, vcc
	v_cmp_gt_i32_e32 vcc, v30, v131
	v_cmp_gt_i32_e64 s[0:1], -2.0, v30
	s_or_b64 vcc, vcc, s[0:1]
	v_add_u32_e32 v30, 26, v0
	v_cndmask_b32_e32 v77, v77, v218, vcc
	v_cmp_gt_i32_e32 vcc, v30, v131
	v_cmp_gt_i32_e64 s[0:1], -2.0, v30
	s_or_b64 vcc, vcc, s[0:1]
	v_add_u32_e32 v30, 27, v0
	v_cndmask_b32_e32 v78, v78, v218, vcc
	v_cmp_gt_i32_e32 vcc, v30, v131
	v_cmp_gt_i32_e64 s[0:1], -2.0, v30
	s_or_b64 vcc, vcc, s[0:1]
	v_add_u32_e32 v30, 32, v0
	v_cndmask_b32_e32 v79, v79, v218, vcc
	v_cmp_gt_i32_e32 vcc, v30, v131
	v_cmp_gt_i32_e64 s[0:1], -2.0, v30
	s_or_b64 vcc, vcc, s[0:1]
	v_add_u32_e32 v30, 33, v0
	v_cndmask_b32_e32 v2, v2, v218, vcc
	v_cmp_gt_i32_e32 vcc, v30, v131
	v_cmp_gt_i32_e64 s[0:1], -2.0, v30
	s_or_b64 vcc, vcc, s[0:1]
	v_add_u32_e32 v30, 34, v0
	v_cndmask_b32_e32 v3, v3, v218, vcc
	v_cmp_gt_i32_e32 vcc, v30, v131
	v_cmp_gt_i32_e64 s[0:1], -2.0, v30
	s_or_b64 vcc, vcc, s[0:1]
	v_add_u32_e32 v30, 35, v0
	v_cndmask_b32_e32 v4, v4, v218, vcc
	v_cmp_gt_i32_e32 vcc, v30, v131
	v_cmp_gt_i32_e64 s[0:1], -2.0, v30
	s_or_b64 vcc, vcc, s[0:1]
	v_add_u32_e32 v30, 40, v0
	v_cndmask_b32_e32 v5, v5, v218, vcc
	v_cmp_gt_i32_e32 vcc, v30, v131
	v_cmp_gt_i32_e64 s[0:1], -2.0, v30
	s_or_b64 vcc, vcc, s[0:1]
	v_add_u32_e32 v30, 41, v0
	v_cndmask_b32_e32 v6, v6, v218, vcc
	v_cmp_gt_i32_e32 vcc, v30, v131
	v_cmp_gt_i32_e64 s[0:1], -2.0, v30
	s_or_b64 vcc, vcc, s[0:1]
	v_add_u32_e32 v30, 42, v0
	v_cndmask_b32_e32 v7, v7, v218, vcc
	v_cmp_gt_i32_e32 vcc, v30, v131
	v_cmp_gt_i32_e64 s[0:1], -2.0, v30
	s_or_b64 vcc, vcc, s[0:1]
	v_add_u32_e32 v30, 43, v0
	v_cndmask_b32_e32 v8, v8, v218, vcc
	v_cmp_gt_i32_e32 vcc, v30, v131
	v_cmp_gt_i32_e64 s[0:1], -2.0, v30
	s_or_b64 vcc, vcc, s[0:1]
	v_add_u32_e32 v30, 48, v0
	v_cndmask_b32_e32 v9, v9, v218, vcc
	v_cmp_gt_i32_e32 vcc, v30, v131
	v_cmp_gt_i32_e64 s[0:1], -2.0, v30
	s_or_b64 vcc, vcc, s[0:1]
	v_add_u32_e32 v30, 49, v0
	v_cndmask_b32_e32 v10, v10, v218, vcc
	v_cmp_gt_i32_e32 vcc, v30, v131
	v_cmp_gt_i32_e64 s[0:1], -2.0, v30
	s_or_b64 vcc, vcc, s[0:1]
	v_add_u32_e32 v30, 50, v0
	v_cndmask_b32_e32 v11, v11, v218, vcc
	v_cmp_gt_i32_e32 vcc, v30, v131
	v_cmp_gt_i32_e64 s[0:1], -2.0, v30
	s_or_b64 vcc, vcc, s[0:1]
	v_add_u32_e32 v30, 51, v0
	v_cndmask_b32_e32 v12, v12, v218, vcc
	v_cmp_gt_i32_e32 vcc, v30, v131
	v_cmp_gt_i32_e64 s[0:1], -2.0, v30
	s_or_b64 vcc, vcc, s[0:1]
	v_add_u32_e32 v30, 56, v0
	v_cndmask_b32_e32 v13, v13, v218, vcc
	v_cmp_gt_i32_e32 vcc, v30, v131
	v_cmp_gt_i32_e64 s[0:1], -2.0, v30
	s_or_b64 vcc, vcc, s[0:1]
	v_add_u32_e32 v30, 57, v0
	v_cndmask_b32_e32 v14, v14, v218, vcc
	v_cmp_gt_i32_e32 vcc, v30, v131
	v_cmp_gt_i32_e64 s[0:1], -2.0, v30
	s_or_b64 vcc, vcc, s[0:1]
	v_add_u32_e32 v30, 58, v0
	v_cndmask_b32_e32 v15, v15, v218, vcc
	v_cmp_gt_i32_e32 vcc, v30, v131
	v_cmp_gt_i32_e64 s[0:1], -2.0, v30
	s_or_b64 vcc, vcc, s[0:1]
	v_add_u32_e32 v0, 59, v0
	v_cndmask_b32_e32 v16, v16, v218, vcc
	v_cmp_gt_i32_e32 vcc, v0, v131
	v_cmp_gt_i32_e64 s[0:1], -2.0, v0
	s_or_b64 vcc, vcc, s[0:1]
	v_cndmask_b32_e32 v17, v17, v218, vcc

; template <int DQK> DEV void qk_tile(f32x16 (&st)[2], const LAS unsigned char* kb, const bf16x8 (&qf)[DQK / 16], int r, int h) {
;     constexpr int KSTR = DQK * 2 + 16, NS = DQK / 16;
;     bf16x8 kf[2][NS];
; #pragma unroll
;     for (int b2 = 0; b2 < 2; ++b2)
; #pragma unroll
;         for (int s = 0; s < NS; ++s) kf[b2][s] = *(const LAS bf16x8*)(kb + (32 * b2 + r) * KSTR + 32 * s + 16 * h);
;     __builtin_amdgcn_sched_barrier(0);
; #pragma unroll
;     for (int b2 = 0; b2 < 2; ++b2) {
;         f32x16 a;
; #pragma unroll
;         for (int i = 0; i < 16; ++i) a[i] = 0.f;
; #pragma unroll
;         for (int s = 0; s < NS; ++s) a = MFMA32(kf[b2][s], qf[s], a);
;         st[b2] = a;
;     }
;     __builtin_amdgcn_sched_barrier(0);
; }
; DEV void pack_p(bf16x8 (&pf)[4], const f32x16 (&st)[2]) {
; #pragma unroll
;     for (int b2 = 0; b2 < 2; ++b2)
; #pragma unroll
;         for (int s = 0; s < 2; ++s) { u32x4 p; p.x = pk2(st[b2][8 * s], st[b2][8 * s + 1]); p.y = pk2(st[b2][8 * s + 2], st[b2][8 * s + 3]);
;             p.z = pk2(st[b2][8 * s + 4], st[b2][8 * s + 5]); p.w = pk2(st[b2][8 * s + 6], st[b2][8 * s + 7]); pf[2 * b2 + s] = __builtin_bit_cast(bf16x8, p); }
; }
; DEV void pv_load(bf16x8 (&vf)[2][4], const LAS unsigned char* vb, int r, int h) {
; #pragma unroll
;     for (int db = 0; db < 2; ++db)
; #pragma unroll
;         for (int f = 0; f < 4; ++f) { const LAS unsigned char* p = vb + (32 * db + r) * 136 + (16 * f + 4 * h) * 2;
;             const s16x4 lo = *(const LAS s16x4*)p, hi = *(const LAS s16x4*)(p + 16);
;             vf[db][f] = __builtin_shufflevector(lo, hi, 0, 1, 2, 3, 4, 5, 6, 7); }
;     __builtin_amdgcn_sched_barrier(0);
; template <int DQK, int MODE> ...
;     ...
;         const bool rowact = rowsel && (k0 <= hi_lim) && (k0 + 63 >= lo_lim);
;         if (__any(rowact ? 1 : 0)) {
;             f32x16 st[2];
;             qk_tile<DQK>(st, kb, qf, r, h);
;             bf16x8 vf[2][4];
;             if (MODE != 3) pv_load(vf, vb, r, h);
;             const bool interior = __all(((k0 + 63 <= hi_lim) && (k0 >= lo_lim)) ? 1 : 0);
;             if (!interior) {
; #pragma unroll
;                 for (int b2 = 0; b2 < 2; ++b2)
; #pragma unroll
;                     for (int i = 0; i < 16; ++i) { const int key = k0 + 32 * b2 + crow(i, h); const bool vis = (key <= hi_lim) && (key >= lo_lim); st[b2][i] = vis ? st[b2][i] : -INFINITY; }
;             }
.LBB0_2645:
	s_add_i32 s0, s55, 2
	s_cmp_gt_i32 s0, s4
	s_cbranch_scc1 .LBB0_2652
	s_lshl_b32 s0, s0, 6
	v_cmp_le_i32_e32 vcc, s0, v131
	s_cbranch_vccz .LBB0_2652
	s_add_i32 s1, s24, 2
	s_mul_i32 s12, s1, 0x3400
	v_add_u32_e32 v0, s12, v136
	ds_read_b128 v[2:5], v0
	ds_read_b128 v[6:9], v0 offset:32
	ds_read_b128 v[10:13], v0 offset:64
	ds_read_b128 v[14:17], v0 offset:96
	ds_read_b128 v[18:21], v0 offset:4608
	ds_read_b128 v[22:25], v0 offset:4640
	ds_read_b128 v[26:29], v0 offset:4672
	ds_read_b128 v[104:107], v0 offset:4704
	s_or_b32 s12, s0, 63
	s_mulk_i32 s1, 0x2200
	s_setprio 1
	s_waitcnt lgkmcnt(7)
	v_mfma_f32_32x32x16_bf16 v[64:79], v[2:5], v[144:147], 0
	s_waitcnt lgkmcnt(6)
	v_mfma_f32_32x32x16_bf16 v[64:79], v[6:9], v[152:155], v[64:79]
	s_waitcnt lgkmcnt(5)
	v_mfma_f32_32x32x16_bf16 v[64:79], v[10:13], v[148:151], v[64:79]
	s_waitcnt lgkmcnt(4)
	v_mfma_f32_32x32x16_bf16 v[64:79], v[14:17], v[156:159], v[64:79]
	s_waitcnt lgkmcnt(3)
	v_mfma_f32_32x32x16_bf16 v[2:17], v[18:21], v[144:147], 0
	s_waitcnt lgkmcnt(2)
	v_mfma_f32_32x32x16_bf16 v[2:17], v[22:25], v[152:155], v[2:17]
	s_waitcnt lgkmcnt(1)
	v_mfma_f32_32x32x16_bf16 v[2:17], v[26:29], v[148:151], v[2:17]
	s_waitcnt lgkmcnt(0)
	v_mfma_f32_32x32x16_bf16 v[2:17], v[104:107], v[156:159], v[2:17]
	s_setprio 0
	v_add_u32_e32 v0, s1, v137
	ds_read2_b64 v[120:123], v0 offset1:2
	ds_read2_b64 v[26:29], v0 offset0:4 offset1:6
	ds_read2_b64 v[22:25], v0 offset0:8 offset1:10
	ds_read2_b64 v[18:21], v0 offset0:12 offset1:14
	v_add_u32_e32 v0, 0x1000, v0
	ds_read2_b64 v[116:119], v0 offset0:32 offset1:34
	ds_read2_b64 v[112:115], v0 offset0:36 offset1:38
	ds_read2_b64 v[108:111], v0 offset0:40 offset1:42
	ds_read2_b64 v[104:107], v0 offset0:44 offset1:46
	v_cmp_le_i32_e32 vcc, s12, v131
	s_cmp_eq_u64 vcc, exec
	s_cbranch_scc1 .LBB0_2649
	v_add_u32_e32 v0, s0, v138
	v_cmp_gt_i32_e32 vcc, v0, v131
	v_cmp_gt_i32_e64 s[0:1], -2.0, v0
	s_or_b64 vcc, vcc, s[0:1]
	v_add_u32_e32 v30, 1, v0
	v_cndmask_b32_e32 v64, v64, v218, vcc
	v_cmp_gt_i32_e32 vcc, v30, v131
	v_cmp_gt_i32_e64 s[0:1], -2.0, v30
	s_or_b64 vcc, vcc, s[0:1]
	v_add_u32_e32 v30, 2, v0
	v_cndmask_b32_e32 v65, v65, v218, vcc
	v_cmp_gt_i32_e32 vcc, v30, v131
	v_cmp_gt_i32_e64 s[0:1], -2.0, v30
	s_or_b64 vcc, vcc, s[0:1]
	v_add_u32_e32 v30, 3, v0
	v_cndmask_b32_e32 v66, v66, v218, vcc
	v_cmp_gt_i32_e32 vcc, v30, v131
	v_cmp_gt_i32_e64 s[0:1], -2.0, v30
	s_or_b64 vcc, vcc, s[0:1]
	v_add_u32_e32 v30, 8, v0
	v_cndmask_b32_e32 v67, v67, v218, vcc
	v_cmp_gt_i32_e32 vcc, v30, v131
	v_cmp_gt_i32_e64 s[0:1], -2.0, v30
	s_or_b64 vcc, vcc, s[0:1]
	v_add_u32_e32 v30, 9, v0
	v_cndmask_b32_e32 v68, v68, v218, vcc
	v_cmp_gt_i32_e32 vcc, v30, v131
	v_cmp_gt_i32_e64 s[0:1], -2.0, v30
	s_or_b64 vcc, vcc, s[0:1]
	v_add_u32_e32 v30, 10, v0
	v_cndmask_b32_e32 v69, v69, v218, vcc
	v_cmp_gt_i32_e32 vcc, v30, v131
	v_cmp_gt_i32_e64 s[0:1], -2.0, v30
	s_or_b64 vcc, vcc, s[0:1]
	v_add_u32_e32 v30, 11, v0
	v_cndmask_b32_e32 v70, v70, v218, vcc
	v_cmp_gt_i32_e32 vcc, v30, v131
	v_cmp_gt_i32_e64 s[0:1], -2.0, v30
	s_or_b64 vcc, vcc, s[0:1]
	v_add_u32_e32 v30, 16, v0
	v_cndmask_b32_e32 v71, v71, v218, vcc
	v_cmp_gt_i32_e32 vcc, v30, v131
	v_cmp_gt_i32_e64 s[0:1], -2.0, v30
	s_or_b64 vcc, vcc, s[0:1]
	v_add_u32_e32 v30, 17, v0
	v_cndmask_b32_e32 v72, v72, v218, vcc
	v_cmp_gt_i32_e32 vcc, v30, v131
	v_cmp_gt_i32_e64 s[0:1], -2.0, v30
	s_or_b64 vcc, vcc, s[0:1]
	v_add_u32_e32 v30, 18, v0
	v_cndmask_b32_e32 v73, v73, v218, vcc
	v_cmp_gt_i32_e32 vcc, v30, v131
	v_cmp_gt_i32_e64 s[0:1], -2.0, v30
	s_or_b64 vcc, vcc, s[0:1]
	v_add_u32_e32 v30, 19, v0
	v_cndmask_b32_e32 v74, v74, v218, vcc
	v_cmp_gt_i32_e32 vcc, v30, v131
	v_cmp_gt_i32_e64 s[0:1], -2.0, v30
	s_or_b64 vcc, vcc, s[0:1]
	v_add_u32_e32 v30, 24, v0
	v_cndmask_b32_e32 v75, v75, v218, vcc
	v_cmp_gt_i32_e32 vcc, v30, v131
	v_cmp_gt_i32_e64 s[0:1], -2.0, v30
	s_or_b64 vcc, vcc, s[0:1]
	v_add_u32_e32 v30, 25, v0
	v_cndmask_b32_e32 v76, v76, v218, vcc
	v_cmp_gt_i32_e32 vcc, v30, v131
	v_cmp_gt_i32_e64 s[0:1], -2.0, v30
	s_or_b64 vcc, vcc, s[0:1]
	v_add_u32_e32 v30, 26, v0
	v_cndmask_b32_e32 v77, v77, v218, vcc
	v_cmp_gt_i32_e32 vcc, v30, v131
	v_cmp_gt_i32_e64 s[0:1], -2.0, v30
	s_or_b64 vcc, vcc, s[0:1]
	v_add_u32_e32 v30, 27, v0
	v_cndmask_b32_e32 v78, v78, v218, vcc
	v_cmp_gt_i32_e32 vcc, v30, v131
	v_cmp_gt_i32_e64 s[0:1], -2.0, v30
	s_or_b64 vcc, vcc, s[0:1]
	v_add_u32_e32 v30, 32, v0
	v_cndmask_b32_e32 v79, v79, v218, vcc
	v_cmp_gt_i32_e32 vcc, v30, v131
	v_cmp_gt_i32_e64 s[0:1], -2.0, v30
	s_or_b64 vcc, vcc, s[0:1]
	v_add_u32_e32 v30, 33, v0
	v_cndmask_b32_e32 v2, v2, v218, vcc
	v_cmp_gt_i32_e32 vcc, v30, v131
	v_cmp_gt_i32_e64 s[0:1], -2.0, v30
	s_or_b64 vcc, vcc, s[0:1]
	v_add_u32_e32 v30, 34, v0
	v_cndmask_b32_e32 v3, v3, v218, vcc
	v_cmp_gt_i32_e32 vcc, v30, v131
	v_cmp_gt_i32_e64 s[0:1], -2.0, v30
	s_or_b64 vcc, vcc, s[0:1]
	v_add_u32_e32 v30, 35, v0
	v_cndmask_b32_e32 v4, v4, v218, vcc
	v_cmp_gt_i32_e32 vcc, v30, v131
	v_cmp_gt_i32_e64 s[0:1], -2.0, v30
	s_or_b64 vcc, vcc, s[0:1]
	v_add_u32_e32 v30, 40, v0
	v_cndmask_b32_e32 v5, v5, v218, vcc
	v_cmp_gt_i32_e32 vcc, v30, v131
	v_cmp_gt_i32_e64 s[0:1], -2.0, v30
	s_or_b64 vcc, vcc, s[0:1]
	v_add_u32_e32 v30, 41, v0
	v_cndmask_b32_e32 v6, v6, v218, vcc
	v_cmp_gt_i32_e32 vcc, v30, v131
	v_cmp_gt_i32_e64 s[0:1], -2.0, v30
	s_or_b64 vcc, vcc, s[0:1]
	v_add_u32_e32 v30, 42, v0
	v_cndmask_b32_e32 v7, v7, v218, vcc
	v_cmp_gt_i32_e32 vcc, v30, v131
	v_cmp_gt_i32_e64 s[0:1], -2.0, v30
	s_or_b64 vcc, vcc, s[0:1]
	v_add_u32_e32 v30, 43, v0
	v_cndmask_b32_e32 v8, v8, v218, vcc
	v_cmp_gt_i32_e32 vcc, v30, v131
	v_cmp_gt_i32_e64 s[0:1], -2.0, v30
	s_or_b64 vcc, vcc, s[0:1]
	v_add_u32_e32 v30, 48, v0
	v_cndmask_b32_e32 v9, v9, v218, vcc
	v_cmp_gt_i32_e32 vcc, v30, v131
	v_cmp_gt_i32_e64 s[0:1], -2.0, v30
	s_or_b64 vcc, vcc, s[0:1]
	v_add_u32_e32 v30, 49, v0
	v_cndmask_b32_e32 v10, v10, v218, vcc
	v_cmp_gt_i32_e32 vcc, v30, v131
	v_cmp_gt_i32_e64 s[0:1], -2.0, v30
	s_or_b64 vcc, vcc, s[0:1]
	v_add_u32_e32 v30, 50, v0
	v_cndmask_b32_e32 v11, v11, v218, vcc
	v_cmp_gt_i32_e32 vcc, v30, v131
	v_cmp_gt_i32_e64 s[0:1], -2.0, v30
	s_or_b64 vcc, vcc, s[0:1]
	v_add_u32_e32 v30, 51, v0
	v_cndmask_b32_e32 v12, v12, v218, vcc
	v_cmp_gt_i32_e32 vcc, v30, v131
	v_cmp_gt_i32_e64 s[0:1], -2.0, v30
	s_or_b64 vcc, vcc, s[0:1]
	v_add_u32_e32 v30, 56, v0
	v_cndmask_b32_e32 v13, v13, v218, vcc
	v_cmp_gt_i32_e32 vcc, v30, v131
	v_cmp_gt_i32_e64 s[0:1], -2.0, v30
	s_or_b64 vcc, vcc, s[0:1]
	v_add_u32_e32 v30, 57, v0
	v_cndmask_b32_e32 v14, v14, v218, vcc
	v_cmp_gt_i32_e32 vcc, v30, v131
	v_cmp_gt_i32_e64 s[0:1], -2.0, v30
	s_or_b64 vcc, vcc, s[0:1]
	v_add_u32_e32 v30, 58, v0
	v_cndmask_b32_e32 v15, v15, v218, vcc
	v_cmp_gt_i32_e32 vcc, v30, v131
	v_cmp_gt_i32_e64 s[0:1], -2.0, v30
	s_or_b64 vcc, vcc, s[0:1]
	v_add_u32_e32 v0, 59, v0
	v_cndmask_b32_e32 v16, v16, v218, vcc
	v_cmp_gt_i32_e32 vcc, v0, v131
	v_cmp_gt_i32_e64 s[0:1], -2.0, v0
	s_or_b64 vcc, vcc, s[0:1]
	v_cndmask_b32_e32 v17, v17, v218, vcc

; #define LAS __attribute__((address_space(3)))
; #define MFMA32(a, b, c) __builtin_amdgcn_mfma_f32_32x32x16_bf16((a), (b), (c), 0, 0, 0)
; DEV int crow(int i, int h) { return (i & 3) + 8 * (i >> 2) + 4 * h; }
; template <int DQK> DEV void qk_tile(f32x16 (&st)[2], const LAS unsigned char* kb, const bf16x8 (&qf)[DQK / 16], int r, int h) {
;     constexpr int KSTR = DQK * 2 + 16, NS = DQK / 16;
;     bf16x8 kf[2][NS];
; #pragma unroll
;     for (int b2 = 0; b2 < 2; ++b2)
; #pragma unroll
;         for (int s = 0; s < NS; ++s) kf[b2][s] = *(const LAS bf16x8*)(kb + (32 * b2 + r) * KSTR + 32 * s + 16 * h);
;     __builtin_amdgcn_sched_barrier(0);
; #pragma unroll
;     for (int b2 = 0; b2 < 2; ++b2) {
;         f32x16 a;
; #pragma unroll
;         for (int i = 0; i < 16; ++i) a[i] = 0.f;
; #pragma unroll
;         for (int s = 0; s < NS; ++s) a = MFMA32(kf[b2][s], qf[s], a);
;         st[b2] = a;
;     }
;     __builtin_amdgcn_sched_barrier(0);
; template <int DQK, int MODE> ...
;     ...
;         const bool rowact = rowsel && (k0 <= hi_lim) && (k0 + 63 >= lo_lim);
;         if (__any(rowact ? 1 : 0)) {
;             f32x16 st[2];
;             qk_tile<DQK>(st, kb, qf, r, h);
;             bf16x8 vf[2][4];
;             if (MODE != 3) pv_load(vf, vb, r, h);
;             const bool interior = __all(((k0 + 63 <= hi_lim) && (k0 >= lo_lim)) ? 1 : 0);
;             if (!interior) {
; #pragma unroll
;                 for (int b2 = 0; b2 < 2; ++b2)
; #pragma unroll
;                     for (int i = 0; i < 16; ++i) { const int key = k0 + 32 * b2 + crow(i, h); const bool vis = (key <= hi_lim) && (key >= lo_lim); st[b2][i] = vis ? st[b2][i] : -INFINITY; }
;             }
.LBB0_2686:
	s_lshl_b32 s0, s33, 6
	v_cmp_le_i32_e32 vcc, s0, v131
	s_cbranch_vccz .LBB0_2706
	s_mul_i32 s1, s31, 0x9c00
	v_add_u32_e32 v64, s1, v86
	ds_read_b128 v[2:5], v64
	ds_read_b128 v[6:9], v64 offset:32
	ds_read_b128 v[10:13], v64 offset:64
	ds_read_b128 v[14:17], v64 offset:96
	ds_read_b128 v[88:91], v64 offset:4608
	ds_read_b128 v[92:95], v64 offset:4640
	ds_read_b128 v[96:99], v64 offset:4672
	ds_read_b128 v[100:103], v64 offset:4704
	s_setprio 1
	s_waitcnt lgkmcnt(7)
	v_mfma_f32_32x32x16_bf16 v[64:79], v[2:5], v[144:147], 0
	s_waitcnt lgkmcnt(6)
	v_mfma_f32_32x32x16_bf16 v[64:79], v[6:9], v[152:155], v[64:79]
	s_waitcnt lgkmcnt(5)
	v_mfma_f32_32x32x16_bf16 v[64:79], v[10:13], v[148:151], v[64:79]
	s_waitcnt lgkmcnt(4)
	v_mfma_f32_32x32x16_bf16 v[64:79], v[14:17], v[156:159], v[64:79]
	s_waitcnt lgkmcnt(3)
	v_mfma_f32_32x32x16_bf16 v[2:17], v[88:91], v[144:147], 0
	s_waitcnt lgkmcnt(2)
	v_mfma_f32_32x32x16_bf16 v[2:17], v[92:95], v[152:155], v[2:17]
	s_waitcnt lgkmcnt(1)
	v_mfma_f32_32x32x16_bf16 v[2:17], v[96:99], v[148:151], v[2:17]
	s_waitcnt lgkmcnt(0)
	v_mfma_f32_32x32x16_bf16 v[2:17], v[100:103], v[156:159], v[2:17]
	s_setprio 0
	s_or_b32 s1, s0, 63
	v_cmp_le_i32_e32 vcc, s1, v131
	s_cmp_eq_u64 vcc, exec
	s_cbranch_scc1 .LBB0_2689
	v_add_u32_e32 v88, s0, v87
	v_cmp_gt_i32_e32 vcc, v88, v131
	v_cmp_gt_i32_e64 s[0:1], -2.0, v88
	s_or_b64 vcc, vcc, s[0:1]
	v_add_u32_e32 v89, 1, v88
	v_cndmask_b32_e32 v64, v64, v218, vcc
	v_cmp_gt_i32_e32 vcc, v89, v131
	v_cmp_gt_i32_e64 s[0:1], -2.0, v89
	s_or_b64 vcc, vcc, s[0:1]
	v_add_u32_e32 v89, 2, v88
	v_cndmask_b32_e32 v65, v65, v218, vcc
	v_cmp_gt_i32_e32 vcc, v89, v131
	v_cmp_gt_i32_e64 s[0:1], -2.0, v89
	s_or_b64 vcc, vcc, s[0:1]
	v_add_u32_e32 v89, 3, v88
	v_cndmask_b32_e32 v66, v66, v218, vcc
	v_cmp_gt_i32_e32 vcc, v89, v131
	v_cmp_gt_i32_e64 s[0:1], -2.0, v89
	s_or_b64 vcc, vcc, s[0:1]
	v_add_u32_e32 v89, 8, v88
	v_cndmask_b32_e32 v67, v67, v218, vcc
	v_cmp_gt_i32_e32 vcc, v89, v131
	v_cmp_gt_i32_e64 s[0:1], -2.0, v89
	s_or_b64 vcc, vcc, s[0:1]
	v_add_u32_e32 v89, 9, v88
	v_cndmask_b32_e32 v68, v68, v218, vcc
	v_cmp_gt_i32_e32 vcc, v89, v131
	v_cmp_gt_i32_e64 s[0:1], -2.0, v89
	s_or_b64 vcc, vcc, s[0:1]
	v_add_u32_e32 v89, 10, v88
	v_cndmask_b32_e32 v69, v69, v218, vcc
	v_cmp_gt_i32_e32 vcc, v89, v131
	v_cmp_gt_i32_e64 s[0:1], -2.0, v89
	s_or_b64 vcc, vcc, s[0:1]
	v_add_u32_e32 v89, 11, v88
	v_cndmask_b32_e32 v70, v70, v218, vcc
	v_cmp_gt_i32_e32 vcc, v89, v131
	v_cmp_gt_i32_e64 s[0:1], -2.0, v89
	s_or_b64 vcc, vcc, s[0:1]
	v_add_u32_e32 v89, 16, v88
	v_cndmask_b32_e32 v71, v71, v218, vcc
	v_cmp_gt_i32_e32 vcc, v89, v131
	v_cmp_gt_i32_e64 s[0:1], -2.0, v89
	s_or_b64 vcc, vcc, s[0:1]
	v_add_u32_e32 v89, 17, v88
	v_cndmask_b32_e32 v72, v72, v218, vcc
	v_cmp_gt_i32_e32 vcc, v89, v131
	v_cmp_gt_i32_e64 s[0:1], -2.0, v89
	s_or_b64 vcc, vcc, s[0:1]
	v_add_u32_e32 v89, 18, v88
	v_cndmask_b32_e32 v73, v73, v218, vcc
	v_cmp_gt_i32_e32 vcc, v89, v131
	v_cmp_gt_i32_e64 s[0:1], -2.0, v89
	s_or_b64 vcc, vcc, s[0:1]
	v_add_u32_e32 v89, 19, v88
	v_cndmask_b32_e32 v74, v74, v218, vcc
	v_cmp_gt_i32_e32 vcc, v89, v131
	v_cmp_gt_i32_e64 s[0:1], -2.0, v89
	s_or_b64 vcc, vcc, s[0:1]
	v_add_u32_e32 v89, 24, v88
	v_cndmask_b32_e32 v75, v75, v218, vcc
	v_cmp_gt_i32_e32 vcc, v89, v131
	v_cmp_gt_i32_e64 s[0:1], -2.0, v89
	s_or_b64 vcc, vcc, s[0:1]
	v_add_u32_e32 v89, 25, v88
	v_cndmask_b32_e32 v76, v76, v218, vcc
	v_cmp_gt_i32_e32 vcc, v89, v131
	v_cmp_gt_i32_e64 s[0:1], -2.0, v89
	s_or_b64 vcc, vcc, s[0:1]
	v_add_u32_e32 v89, 26, v88
	v_cndmask_b32_e32 v77, v77, v218, vcc
	v_cmp_gt_i32_e32 vcc, v89, v131
	v_cmp_gt_i32_e64 s[0:1], -2.0, v89
	s_or_b64 vcc, vcc, s[0:1]
	v_add_u32_e32 v89, 27, v88
	v_cndmask_b32_e32 v78, v78, v218, vcc
	v_cmp_gt_i32_e32 vcc, v89, v131
	v_cmp_gt_i32_e64 s[0:1], -2.0, v89
	s_or_b64 vcc, vcc, s[0:1]
	v_add_u32_e32 v89, 32, v88
	v_cndmask_b32_e32 v79, v79, v218, vcc
	v_cmp_gt_i32_e32 vcc, v89, v131
	v_cmp_gt_i32_e64 s[0:1], -2.0, v89
	s_or_b64 vcc, vcc, s[0:1]
	v_add_u32_e32 v89, 33, v88
	v_cndmask_b32_e32 v2, v2, v218, vcc
	v_cmp_gt_i32_e32 vcc, v89, v131
	v_cmp_gt_i32_e64 s[0:1], -2.0, v89
	s_or_b64 vcc, vcc, s[0:1]
	v_add_u32_e32 v89, 34, v88
	v_cndmask_b32_e32 v3, v3, v218, vcc
	v_cmp_gt_i32_e32 vcc, v89, v131
	v_cmp_gt_i32_e64 s[0:1], -2.0, v89
	s_or_b64 vcc, vcc, s[0:1]
	v_add_u32_e32 v89, 35, v88
	v_cndmask_b32_e32 v4, v4, v218, vcc
	v_cmp_gt_i32_e32 vcc, v89, v131
	v_cmp_gt_i32_e64 s[0:1], -2.0, v89
	s_or_b64 vcc, vcc, s[0:1]
	v_add_u32_e32 v89, 40, v88
	v_cndmask_b32_e32 v5, v5, v218, vcc
	v_cmp_gt_i32_e32 vcc, v89, v131
	v_cmp_gt_i32_e64 s[0:1], -2.0, v89
	s_or_b64 vcc, vcc, s[0:1]
	v_add_u32_e32 v89, 41, v88
	v_cndmask_b32_e32 v6, v6, v218, vcc
	v_cmp_gt_i32_e32 vcc, v89, v131
	v_cmp_gt_i32_e64 s[0:1], -2.0, v89
	s_or_b64 vcc, vcc, s[0:1]
	v_add_u32_e32 v89, 42, v88
	v_cndmask_b32_e32 v7, v7, v218, vcc
	v_cmp_gt_i32_e32 vcc, v89, v131
	v_cmp_gt_i32_e64 s[0:1], -2.0, v89
	s_or_b64 vcc, vcc, s[0:1]
	v_add_u32_e32 v89, 43, v88
	v_cndmask_b32_e32 v8, v8, v218, vcc
	v_cmp_gt_i32_e32 vcc, v89, v131
	v_cmp_gt_i32_e64 s[0:1], -2.0, v89
	s_or_b64 vcc, vcc, s[0:1]
	v_add_u32_e32 v89, 48, v88
	v_cndmask_b32_e32 v9, v9, v218, vcc
	v_cmp_gt_i32_e32 vcc, v89, v131
	v_cmp_gt_i32_e64 s[0:1], -2.0, v89
	s_or_b64 vcc, vcc, s[0:1]
	v_add_u32_e32 v89, 49, v88
	v_cndmask_b32_e32 v10, v10, v218, vcc
	v_cmp_gt_i32_e32 vcc, v89, v131
	v_cmp_gt_i32_e64 s[0:1], -2.0, v89
	s_or_b64 vcc, vcc, s[0:1]
	v_add_u32_e32 v89, 50, v88
	v_cndmask_b32_e32 v11, v11, v218, vcc
	v_cmp_gt_i32_e32 vcc, v89, v131
	v_cmp_gt_i32_e64 s[0:1], -2.0, v89
	s_or_b64 vcc, vcc, s[0:1]
	v_add_u32_e32 v89, 51, v88
	v_cndmask_b32_e32 v12, v12, v218, vcc
	v_cmp_gt_i32_e32 vcc, v89, v131
	v_cmp_gt_i32_e64 s[0:1], -2.0, v89
	s_or_b64 vcc, vcc, s[0:1]
	v_add_u32_e32 v89, 56, v88
	v_cndmask_b32_e32 v13, v13, v218, vcc
	v_cmp_gt_i32_e32 vcc, v89, v131
	v_cmp_gt_i32_e64 s[0:1], -2.0, v89
	s_or_b64 vcc, vcc, s[0:1]
	v_add_u32_e32 v89, 57, v88
	v_cndmask_b32_e32 v14, v14, v218, vcc
	v_cmp_gt_i32_e32 vcc, v89, v131
	v_cmp_gt_i32_e64 s[0:1], -2.0, v89
	s_or_b64 vcc, vcc, s[0:1]
	v_add_u32_e32 v89, 58, v88
	v_cndmask_b32_e32 v15, v15, v218, vcc
	v_cmp_gt_i32_e32 vcc, v89, v131
	v_cmp_gt_i32_e64 s[0:1], -2.0, v89
	s_or_b64 vcc, vcc, s[0:1]
	v_add_u32_e32 v88, 59, v88
	v_cndmask_b32_e32 v16, v16, v218, vcc
	v_cmp_gt_i32_e32 vcc, v88, v131
	v_cmp_gt_i32_e64 s[0:1], -2.0, v88
	s_or_b64 vcc, vcc, s[0:1]
	v_cndmask_b32_e32 v17, v17, v218, vcc

; #define LAS __attribute__((address_space(3)))
; #define MFMA32(a, b, c) __builtin_amdgcn_mfma_f32_32x32x16_bf16((a), (b), (c), 0, 0, 0)
; DEV int crow(int i, int h) { return (i & 3) + 8 * (i >> 2) + 4 * h; }
; template <int DQK> DEV void qk_tile(f32x16 (&st)[2], const LAS unsigned char* kb, const bf16x8 (&qf)[DQK / 16], int r, int h) {
;     constexpr int KSTR = DQK * 2 + 16, NS = DQK / 16;
;     bf16x8 kf[2][NS];
; #pragma unroll
;     for (int b2 = 0; b2 < 2; ++b2)
; #pragma unroll
;         for (int s = 0; s < NS; ++s) kf[b2][s] = *(const LAS bf16x8*)(kb + (32 * b2 + r) * KSTR + 32 * s + 16 * h);
;     __builtin_amdgcn_sched_barrier(0);
; #pragma unroll
;     for (int b2 = 0; b2 < 2; ++b2) {
;         f32x16 a;
; #pragma unroll
;         for (int i = 0; i < 16; ++i) a[i] = 0.f;
; #pragma unroll
;         for (int s = 0; s < NS; ++s) a = MFMA32(kf[b2][s], qf[s], a);
;         st[b2] = a;
;     }
;     __builtin_amdgcn_sched_barrier(0);
; template <int DQK, int MODE> ...
;     ...
;         const bool rowact = rowsel && (k0 <= hi_lim) && (k0 + 63 >= lo_lim);
;         if (__any(rowact ? 1 : 0)) {
;             f32x16 st[2];
;             qk_tile<DQK>(st, kb, qf, r, h);
;             bf16x8 vf[2][4];
;             if (MODE != 3) pv_load(vf, vb, r, h);
;             const bool interior = __all(((k0 + 63 <= hi_lim) && (k0 >= lo_lim)) ? 1 : 0);
;             if (!interior) {
; #pragma unroll
;                 for (int b2 = 0; b2 < 2; ++b2)
; #pragma unroll
;                     for (int i = 0; i < 16; ++i) { const int key = k0 + 32 * b2 + crow(i, h); const bool vis = (key <= hi_lim) && (key >= lo_lim); st[b2][i] = vis ? st[b2][i] : -INFINITY; }
;             }
.LBB0_2706:
	s_cmp_ge_i32 s33, s4
	s_cbranch_scc1 .LBB0_2727
	s_add_i32 s15, s33, 1
	s_lshl_b32 s0, s15, 6
	v_cmp_le_i32_e32 vcc, s0, v131
	s_cbranch_vccz .LBB0_2727
	s_mul_i32 s1, s31, 0x9c00
	v_add_u32_e32 v64, s1, v86
	ds_read_b128 v[2:5], v64 offset:13312
	ds_read_b128 v[6:9], v64 offset:13344
	ds_read_b128 v[10:13], v64 offset:13376
	ds_read_b128 v[14:17], v64 offset:13408
	ds_read_b128 v[88:91], v64 offset:17920
	ds_read_b128 v[92:95], v64 offset:17952
	ds_read_b128 v[96:99], v64 offset:17984
	ds_read_b128 v[100:103], v64 offset:18016
	s_setprio 1
	s_waitcnt lgkmcnt(7)
	v_mfma_f32_32x32x16_bf16 v[64:79], v[2:5], v[144:147], 0
	s_waitcnt lgkmcnt(6)
	v_mfma_f32_32x32x16_bf16 v[64:79], v[6:9], v[152:155], v[64:79]
	s_waitcnt lgkmcnt(5)
	v_mfma_f32_32x32x16_bf16 v[64:79], v[10:13], v[148:151], v[64:79]
	s_waitcnt lgkmcnt(4)
	v_mfma_f32_32x32x16_bf16 v[64:79], v[14:17], v[156:159], v[64:79]
	s_waitcnt lgkmcnt(3)
	v_mfma_f32_32x32x16_bf16 v[2:17], v[88:91], v[144:147], 0
	s_waitcnt lgkmcnt(2)
	v_mfma_f32_32x32x16_bf16 v[2:17], v[92:95], v[152:155], v[2:17]
	s_waitcnt lgkmcnt(1)
	v_mfma_f32_32x32x16_bf16 v[2:17], v[96:99], v[148:151], v[2:17]
	s_waitcnt lgkmcnt(0)
	v_mfma_f32_32x32x16_bf16 v[2:17], v[100:103], v[156:159], v[2:17]
	s_setprio 0
	s_or_b32 s1, s0, 63
	v_cmp_le_i32_e32 vcc, s1, v131
	s_cmp_eq_u64 vcc, exec
	s_cbranch_scc1 .LBB0_2710
	v_add_u32_e32 v88, s0, v87
	v_cmp_gt_i32_e32 vcc, v88, v131
	v_cmp_gt_i32_e64 s[0:1], -2.0, v88
	s_or_b64 vcc, vcc, s[0:1]
	v_add_u32_e32 v89, 1, v88
	v_cndmask_b32_e32 v64, v64, v218, vcc
	v_cmp_gt_i32_e32 vcc, v89, v131
	v_cmp_gt_i32_e64 s[0:1], -2.0, v89
	s_or_b64 vcc, vcc, s[0:1]
	v_add_u32_e32 v89, 2, v88
	v_cndmask_b32_e32 v65, v65, v218, vcc
	v_cmp_gt_i32_e32 vcc, v89, v131
	v_cmp_gt_i32_e64 s[0:1], -2.0, v89
	s_or_b64 vcc, vcc, s[0:1]
	v_add_u32_e32 v89, 3, v88
	v_cndmask_b32_e32 v66, v66, v218, vcc
	v_cmp_gt_i32_e32 vcc, v89, v131
	v_cmp_gt_i32_e64 s[0:1], -2.0, v89
	s_or_b64 vcc, vcc, s[0:1]
	v_add_u32_e32 v89, 8, v88
	v_cndmask_b32_e32 v67, v67, v218, vcc
	v_cmp_gt_i32_e32 vcc, v89, v131
	v_cmp_gt_i32_e64 s[0:1], -2.0, v89
	s_or_b64 vcc, vcc, s[0:1]
	v_add_u32_e32 v89, 9, v88
	v_cndmask_b32_e32 v68, v68, v218, vcc
	v_cmp_gt_i32_e32 vcc, v89, v131
	v_cmp_gt_i32_e64 s[0:1], -2.0, v89
	s_or_b64 vcc, vcc, s[0:1]
	v_add_u32_e32 v89, 10, v88
	v_cndmask_b32_e32 v69, v69, v218, vcc
	v_cmp_gt_i32_e32 vcc, v89, v131
	v_cmp_gt_i32_e64 s[0:1], -2.0, v89
	s_or_b64 vcc, vcc, s[0:1]
	v_add_u32_e32 v89, 11, v88
	v_cndmask_b32_e32 v70, v70, v218, vcc
	v_cmp_gt_i32_e32 vcc, v89, v131
	v_cmp_gt_i32_e64 s[0:1], -2.0, v89
	s_or_b64 vcc, vcc, s[0:1]
	v_add_u32_e32 v89, 16, v88
	v_cndmask_b32_e32 v71, v71, v218, vcc
	v_cmp_gt_i32_e32 vcc, v89, v131
	v_cmp_gt_i32_e64 s[0:1], -2.0, v89
	s_or_b64 vcc, vcc, s[0:1]
	v_add_u32_e32 v89, 17, v88
	v_cndmask_b32_e32 v72, v72, v218, vcc
	v_cmp_gt_i32_e32 vcc, v89, v131
	v_cmp_gt_i32_e64 s[0:1], -2.0, v89
	s_or_b64 vcc, vcc, s[0:1]
	v_add_u32_e32 v89, 18, v88
	v_cndmask_b32_e32 v73, v73, v218, vcc
	v_cmp_gt_i32_e32 vcc, v89, v131
	v_cmp_gt_i32_e64 s[0:1], -2.0, v89
	s_or_b64 vcc, vcc, s[0:1]
	v_add_u32_e32 v89, 19, v88
	v_cndmask_b32_e32 v74, v74, v218, vcc
	v_cmp_gt_i32_e32 vcc, v89, v131
	v_cmp_gt_i32_e64 s[0:1], -2.0, v89
	s_or_b64 vcc, vcc, s[0:1]
	v_add_u32_e32 v89, 24, v88
	v_cndmask_b32_e32 v75, v75, v218, vcc
	v_cmp_gt_i32_e32 vcc, v89, v131
	v_cmp_gt_i32_e64 s[0:1], -2.0, v89
	s_or_b64 vcc, vcc, s[0:1]
	v_add_u32_e32 v89, 25, v88
	v_cndmask_b32_e32 v76, v76, v218, vcc
	v_cmp_gt_i32_e32 vcc, v89, v131
	v_cmp_gt_i32_e64 s[0:1], -2.0, v89
	s_or_b64 vcc, vcc, s[0:1]
	v_add_u32_e32 v89, 26, v88
	v_cndmask_b32_e32 v77, v77, v218, vcc
	v_cmp_gt_i32_e32 vcc, v89, v131
	v_cmp_gt_i32_e64 s[0:1], -2.0, v89
	s_or_b64 vcc, vcc, s[0:1]
	v_add_u32_e32 v89, 27, v88
	v_cndmask_b32_e32 v78, v78, v218, vcc
	v_cmp_gt_i32_e32 vcc, v89, v131
	v_cmp_gt_i32_e64 s[0:1], -2.0, v89
	s_or_b64 vcc, vcc, s[0:1]
	v_add_u32_e32 v89, 32, v88
	v_cndmask_b32_e32 v79, v79, v218, vcc
	v_cmp_gt_i32_e32 vcc, v89, v131
	v_cmp_gt_i32_e64 s[0:1], -2.0, v89
	s_or_b64 vcc, vcc, s[0:1]
	v_add_u32_e32 v89, 33, v88
	v_cndmask_b32_e32 v2, v2, v218, vcc
	v_cmp_gt_i32_e32 vcc, v89, v131
	v_cmp_gt_i32_e64 s[0:1], -2.0, v89
	s_or_b64 vcc, vcc, s[0:1]
	v_add_u32_e32 v89, 34, v88
	v_cndmask_b32_e32 v3, v3, v218, vcc
	v_cmp_gt_i32_e32 vcc, v89, v131
	v_cmp_gt_i32_e64 s[0:1], -2.0, v89
	s_or_b64 vcc, vcc, s[0:1]
	v_add_u32_e32 v89, 35, v88
	v_cndmask_b32_e32 v4, v4, v218, vcc
	v_cmp_gt_i32_e32 vcc, v89, v131
	v_cmp_gt_i32_e64 s[0:1], -2.0, v89
	s_or_b64 vcc, vcc, s[0:1]
	v_add_u32_e32 v89, 40, v88
	v_cndmask_b32_e32 v5, v5, v218, vcc
	v_cmp_gt_i32_e32 vcc, v89, v131
	v_cmp_gt_i32_e64 s[0:1], -2.0, v89
	s_or_b64 vcc, vcc, s[0:1]
	v_add_u32_e32 v89, 41, v88
	v_cndmask_b32_e32 v6, v6, v218, vcc
	v_cmp_gt_i32_e32 vcc, v89, v131
	v_cmp_gt_i32_e64 s[0:1], -2.0, v89
	s_or_b64 vcc, vcc, s[0:1]
	v_add_u32_e32 v89, 42, v88
	v_cndmask_b32_e32 v7, v7, v218, vcc
	v_cmp_gt_i32_e32 vcc, v89, v131
	v_cmp_gt_i32_e64 s[0:1], -2.0, v89
	s_or_b64 vcc, vcc, s[0:1]
	v_add_u32_e32 v89, 43, v88
	v_cndmask_b32_e32 v8, v8, v218, vcc
	v_cmp_gt_i32_e32 vcc, v89, v131
	v_cmp_gt_i32_e64 s[0:1], -2.0, v89
	s_or_b64 vcc, vcc, s[0:1]
	v_add_u32_e32 v89, 48, v88
	v_cndmask_b32_e32 v9, v9, v218, vcc
	v_cmp_gt_i32_e32 vcc, v89, v131
	v_cmp_gt_i32_e64 s[0:1], -2.0, v89
	s_or_b64 vcc, vcc, s[0:1]
	v_add_u32_e32 v89, 49, v88
	v_cndmask_b32_e32 v10, v10, v218, vcc
	v_cmp_gt_i32_e32 vcc, v89, v131
	v_cmp_gt_i32_e64 s[0:1], -2.0, v89
	s_or_b64 vcc, vcc, s[0:1]
	v_add_u32_e32 v89, 50, v88
	v_cndmask_b32_e32 v11, v11, v218, vcc
	v_cmp_gt_i32_e32 vcc, v89, v131
	v_cmp_gt_i32_e64 s[0:1], -2.0, v89
	s_or_b64 vcc, vcc, s[0:1]
	v_add_u32_e32 v89, 51, v88
	v_cndmask_b32_e32 v12, v12, v218, vcc
	v_cmp_gt_i32_e32 vcc, v89, v131
	v_cmp_gt_i32_e64 s[0:1], -2.0, v89
	s_or_b64 vcc, vcc, s[0:1]
	v_add_u32_e32 v89, 56, v88
	v_cndmask_b32_e32 v13, v13, v218, vcc
	v_cmp_gt_i32_e32 vcc, v89, v131
	v_cmp_gt_i32_e64 s[0:1], -2.0, v89
	s_or_b64 vcc, vcc, s[0:1]
	v_add_u32_e32 v89, 57, v88
	v_cndmask_b32_e32 v14, v14, v218, vcc
	v_cmp_gt_i32_e32 vcc, v89, v131
	v_cmp_gt_i32_e64 s[0:1], -2.0, v89
	s_or_b64 vcc, vcc, s[0:1]
	v_add_u32_e32 v89, 58, v88
	v_cndmask_b32_e32 v15, v15, v218, vcc
	v_cmp_gt_i32_e32 vcc, v89, v131
	v_cmp_gt_i32_e64 s[0:1], -2.0, v89
	s_or_b64 vcc, vcc, s[0:1]
	v_add_u32_e32 v88, 59, v88
	v_cndmask_b32_e32 v16, v16, v218, vcc
	v_cmp_gt_i32_e32 vcc, v88, v131
	v_cmp_gt_i32_e64 s[0:1], -2.0, v88
	s_or_b64 vcc, vcc, s[0:1]
	v_cndmask_b32_e32 v17, v17, v218, vcc

; #define LAS __attribute__((address_space(3)))
; #define MFMA32(a, b, c) __builtin_amdgcn_mfma_f32_32x32x16_bf16((a), (b), (c), 0, 0, 0)
; DEV int crow(int i, int h) { return (i & 3) + 8 * (i >> 2) + 4 * h; }
; template <int DQK> DEV void qk_tile(f32x16 (&st)[2], const LAS unsigned char* kb, const bf16x8 (&qf)[DQK / 16], int r, int h) {
;     constexpr int KSTR = DQK * 2 + 16, NS = DQK / 16;
;     bf16x8 kf[2][NS];
; #pragma unroll
;     for (int b2 = 0; b2 < 2; ++b2)
; #pragma unroll
;         for (int s = 0; s < NS; ++s) kf[b2][s] = *(const LAS bf16x8*)(kb + (32 * b2 + r) * KSTR + 32 * s + 16 * h);
;     __builtin_amdgcn_sched_barrier(0);
; #pragma unroll
;     for (int b2 = 0; b2 < 2; ++b2) {
;         f32x16 a;
; #pragma unroll
;         for (int i = 0; i < 16; ++i) a[i] = 0.f;
; #pragma unroll
;         for (int s = 0; s < NS; ++s) a = MFMA32(kf[b2][s], qf[s], a);
;         st[b2] = a;
;     }
;     __builtin_amdgcn_sched_barrier(0);
; template <int DQK, int MODE> ...
;     ...
;         const bool rowact = rowsel && (k0 <= hi_lim) && (k0 + 63 >= lo_lim);
;         if (__any(rowact ? 1 : 0)) {
;             f32x16 st[2];
;             qk_tile<DQK>(st, kb, qf, r, h);
;             bf16x8 vf[2][4];
;             if (MODE != 3) pv_load(vf, vb, r, h);
;             const bool interior = __all(((k0 + 63 <= hi_lim) && (k0 >= lo_lim)) ? 1 : 0);
;             if (!interior) {
; #pragma unroll
;                 for (int b2 = 0; b2 < 2; ++b2)
; #pragma unroll
;                     for (int i = 0; i < 16; ++i) { const int key = k0 + 32 * b2 + crow(i, h); const bool vis = (key <= hi_lim) && (key >= lo_lim); st[b2][i] = vis ? st[b2][i] : -INFINITY; }
;             }
.LBB0_2727:
	s_add_i32 s33, s33, 2
	s_cmp_gt_i32 s33, s4
	s_cbranch_scc1 .LBB0_2672
	s_lshl_b32 s0, s33, 6
	v_cmp_le_i32_e32 vcc, s0, v131
	s_cbranch_vccz .LBB0_2672
	s_mul_i32 s31, s31, 0x9c00
	v_add_u32_e32 v64, s31, v86
	ds_read_b128 v[2:5], v64 offset:26624
	ds_read_b128 v[6:9], v64 offset:26656
	ds_read_b128 v[10:13], v64 offset:26688
	ds_read_b128 v[14:17], v64 offset:26720
	ds_read_b128 v[88:91], v64 offset:31232
	ds_read_b128 v[92:95], v64 offset:31264
	ds_read_b128 v[96:99], v64 offset:31296
	ds_read_b128 v[100:103], v64 offset:31328
	s_setprio 1
	s_waitcnt lgkmcnt(7)
	v_mfma_f32_32x32x16_bf16 v[64:79], v[2:5], v[144:147], 0
	s_waitcnt lgkmcnt(6)
	v_mfma_f32_32x32x16_bf16 v[64:79], v[6:9], v[152:155], v[64:79]
	s_waitcnt lgkmcnt(5)
	v_mfma_f32_32x32x16_bf16 v[64:79], v[10:13], v[148:151], v[64:79]
	s_waitcnt lgkmcnt(4)
	v_mfma_f32_32x32x16_bf16 v[64:79], v[14:17], v[156:159], v[64:79]
	s_waitcnt lgkmcnt(3)
	v_mfma_f32_32x32x16_bf16 v[2:17], v[88:91], v[144:147], 0
	s_waitcnt lgkmcnt(2)
	v_mfma_f32_32x32x16_bf16 v[2:17], v[92:95], v[152:155], v[2:17]
	s_waitcnt lgkmcnt(1)
	v_mfma_f32_32x32x16_bf16 v[2:17], v[96:99], v[148:151], v[2:17]
	s_waitcnt lgkmcnt(0)
	v_mfma_f32_32x32x16_bf16 v[2:17], v[100:103], v[156:159], v[2:17]
	s_setprio 0
	s_or_b32 s1, s0, 63
	v_cmp_le_i32_e32 vcc, s1, v131
	s_cmp_eq_u64 vcc, exec
	s_cbranch_scc1 .LBB0_2731
	v_add_u32_e32 v88, s0, v87
	v_cmp_gt_i32_e32 vcc, v88, v131
	v_cmp_gt_i32_e64 s[0:1], -2.0, v88
	s_or_b64 vcc, vcc, s[0:1]
	v_add_u32_e32 v89, 1, v88
	v_cndmask_b32_e32 v64, v64, v218, vcc
	v_cmp_gt_i32_e32 vcc, v89, v131
	v_cmp_gt_i32_e64 s[0:1], -2.0, v89
	s_or_b64 vcc, vcc, s[0:1]
	v_add_u32_e32 v89, 2, v88
	v_cndmask_b32_e32 v65, v65, v218, vcc
	v_cmp_gt_i32_e32 vcc, v89, v131
	v_cmp_gt_i32_e64 s[0:1], -2.0, v89
	s_or_b64 vcc, vcc, s[0:1]
	v_add_u32_e32 v89, 3, v88
	v_cndmask_b32_e32 v66, v66, v218, vcc
	v_cmp_gt_i32_e32 vcc, v89, v131
	v_cmp_gt_i32_e64 s[0:1], -2.0, v89
	s_or_b64 vcc, vcc, s[0:1]
	v_add_u32_e32 v89, 8, v88
	v_cndmask_b32_e32 v67, v67, v218, vcc
	v_cmp_gt_i32_e32 vcc, v89, v131
	v_cmp_gt_i32_e64 s[0:1], -2.0, v89
	s_or_b64 vcc, vcc, s[0:1]
	v_add_u32_e32 v89, 9, v88
	v_cndmask_b32_e32 v68, v68, v218, vcc
	v_cmp_gt_i32_e32 vcc, v89, v131
	v_cmp_gt_i32_e64 s[0:1], -2.0, v89
	s_or_b64 vcc, vcc, s[0:1]
	v_add_u32_e32 v89, 10, v88
	v_cndmask_b32_e32 v69, v69, v218, vcc
	v_cmp_gt_i32_e32 vcc, v89, v131
	v_cmp_gt_i32_e64 s[0:1], -2.0, v89
	s_or_b64 vcc, vcc, s[0:1]
	v_add_u32_e32 v89, 11, v88
	v_cndmask_b32_e32 v70, v70, v218, vcc
	v_cmp_gt_i32_e32 vcc, v89, v131
	v_cmp_gt_i32_e64 s[0:1], -2.0, v89
	s_or_b64 vcc, vcc, s[0:1]
	v_add_u32_e32 v89, 16, v88
	v_cndmask_b32_e32 v71, v71, v218, vcc
	v_cmp_gt_i32_e32 vcc, v89, v131
	v_cmp_gt_i32_e64 s[0:1], -2.0, v89
	s_or_b64 vcc, vcc, s[0:1]
	v_add_u32_e32 v89, 17, v88
	v_cndmask_b32_e32 v72, v72, v218, vcc
	v_cmp_gt_i32_e32 vcc, v89, v131
	v_cmp_gt_i32_e64 s[0:1], -2.0, v89
	s_or_b64 vcc, vcc, s[0:1]
	v_add_u32_e32 v89, 18, v88
	v_cndmask_b32_e32 v73, v73, v218, vcc
	v_cmp_gt_i32_e32 vcc, v89, v131
	v_cmp_gt_i32_e64 s[0:1], -2.0, v89
	s_or_b64 vcc, vcc, s[0:1]
	v_add_u32_e32 v89, 19, v88
	v_cndmask_b32_e32 v74, v74, v218, vcc
	v_cmp_gt_i32_e32 vcc, v89, v131
	v_cmp_gt_i32_e64 s[0:1], -2.0, v89
	s_or_b64 vcc, vcc, s[0:1]
	v_add_u32_e32 v89, 24, v88
	v_cndmask_b32_e32 v75, v75, v218, vcc
	v_cmp_gt_i32_e32 vcc, v89, v131
	v_cmp_gt_i32_e64 s[0:1], -2.0, v89
	s_or_b64 vcc, vcc, s[0:1]
	v_add_u32_e32 v89, 25, v88
	v_cndmask_b32_e32 v76, v76, v218, vcc
	v_cmp_gt_i32_e32 vcc, v89, v131
	v_cmp_gt_i32_e64 s[0:1], -2.0, v89
	s_or_b64 vcc, vcc, s[0:1]
	v_add_u32_e32 v89, 26, v88
	v_cndmask_b32_e32 v77, v77, v218, vcc
	v_cmp_gt_i32_e32 vcc, v89, v131
	v_cmp_gt_i32_e64 s[0:1], -2.0, v89
	s_or_b64 vcc, vcc, s[0:1]
	v_add_u32_e32 v89, 27, v88
	v_cndmask_b32_e32 v78, v78, v218, vcc
	v_cmp_gt_i32_e32 vcc, v89, v131
	v_cmp_gt_i32_e64 s[0:1], -2.0, v89
	s_or_b64 vcc, vcc, s[0:1]
	v_add_u32_e32 v89, 32, v88
	v_cndmask_b32_e32 v79, v79, v218, vcc
	v_cmp_gt_i32_e32 vcc, v89, v131
	v_cmp_gt_i32_e64 s[0:1], -2.0, v89
	s_or_b64 vcc, vcc, s[0:1]
	v_add_u32_e32 v89, 33, v88
	v_cndmask_b32_e32 v2, v2, v218, vcc
	v_cmp_gt_i32_e32 vcc, v89, v131
	v_cmp_gt_i32_e64 s[0:1], -2.0, v89
	s_or_b64 vcc, vcc, s[0:1]
	v_add_u32_e32 v89, 34, v88
	v_cndmask_b32_e32 v3, v3, v218, vcc
	v_cmp_gt_i32_e32 vcc, v89, v131
	v_cmp_gt_i32_e64 s[0:1], -2.0, v89
	s_or_b64 vcc, vcc, s[0:1]
	v_add_u32_e32 v89, 35, v88
	v_cndmask_b32_e32 v4, v4, v218, vcc
	v_cmp_gt_i32_e32 vcc, v89, v131
	v_cmp_gt_i32_e64 s[0:1], -2.0, v89
	s_or_b64 vcc, vcc, s[0:1]
	v_add_u32_e32 v89, 40, v88
	v_cndmask_b32_e32 v5, v5, v218, vcc
	v_cmp_gt_i32_e32 vcc, v89, v131
	v_cmp_gt_i32_e64 s[0:1], -2.0, v89
	s_or_b64 vcc, vcc, s[0:1]
	v_add_u32_e32 v89, 41, v88
	v_cndmask_b32_e32 v6, v6, v218, vcc
	v_cmp_gt_i32_e32 vcc, v89, v131
	v_cmp_gt_i32_e64 s[0:1], -2.0, v89
	s_or_b64 vcc, vcc, s[0:1]
	v_add_u32_e32 v89, 42, v88
	v_cndmask_b32_e32 v7, v7, v218, vcc
	v_cmp_gt_i32_e32 vcc, v89, v131
	v_cmp_gt_i32_e64 s[0:1], -2.0, v89
	s_or_b64 vcc, vcc, s[0:1]
	v_add_u32_e32 v89, 43, v88
	v_cndmask_b32_e32 v8, v8, v218, vcc
	v_cmp_gt_i32_e32 vcc, v89, v131
	v_cmp_gt_i32_e64 s[0:1], -2.0, v89
	s_or_b64 vcc, vcc, s[0:1]
	v_add_u32_e32 v89, 48, v88
	v_cndmask_b32_e32 v9, v9, v218, vcc
	v_cmp_gt_i32_e32 vcc, v89, v131
	v_cmp_gt_i32_e64 s[0:1], -2.0, v89
	s_or_b64 vcc, vcc, s[0:1]
	v_add_u32_e32 v89, 49, v88
	v_cndmask_b32_e32 v10, v10, v218, vcc
	v_cmp_gt_i32_e32 vcc, v89, v131
	v_cmp_gt_i32_e64 s[0:1], -2.0, v89
	s_or_b64 vcc, vcc, s[0:1]
	v_add_u32_e32 v89, 50, v88
	v_cndmask_b32_e32 v11, v11, v218, vcc
	v_cmp_gt_i32_e32 vcc, v89, v131
	v_cmp_gt_i32_e64 s[0:1], -2.0, v89
	s_or_b64 vcc, vcc, s[0:1]
	v_add_u32_e32 v89, 51, v88
	v_cndmask_b32_e32 v12, v12, v218, vcc
	v_cmp_gt_i32_e32 vcc, v89, v131
	v_cmp_gt_i32_e64 s[0:1], -2.0, v89
	s_or_b64 vcc, vcc, s[0:1]
	v_add_u32_e32 v89, 56, v88
	v_cndmask_b32_e32 v13, v13, v218, vcc
	v_cmp_gt_i32_e32 vcc, v89, v131
	v_cmp_gt_i32_e64 s[0:1], -2.0, v89
	s_or_b64 vcc, vcc, s[0:1]
	v_add_u32_e32 v89, 57, v88
	v_cndmask_b32_e32 v14, v14, v218, vcc
	v_cmp_gt_i32_e32 vcc, v89, v131
	v_cmp_gt_i32_e64 s[0:1], -2.0, v89
	s_or_b64 vcc, vcc, s[0:1]
	v_add_u32_e32 v89, 58, v88
	v_cndmask_b32_e32 v15, v15, v218, vcc
	v_cmp_gt_i32_e32 vcc, v89, v131
	v_cmp_gt_i32_e64 s[0:1], -2.0, v89
	s_or_b64 vcc, vcc, s[0:1]
	v_add_u32_e32 v88, 59, v88
	v_cndmask_b32_e32 v16, v16, v218, vcc
	v_cmp_gt_i32_e32 vcc, v88, v131
	v_cmp_gt_i32_e64 s[0:1], -2.0, v88
	s_or_b64 vcc, vcc, s[0:1]
	v_cndmask_b32_e32 v17, v17, v218, vcc

; template <int DQK> DEV void qk_tile(f32x16 (&st)[2], const LAS unsigned char* kb, const bf16x8 (&qf)[DQK / 16], int r, int h) {
;     constexpr int KSTR = DQK * 2 + 16, NS = DQK / 16;
;     bf16x8 kf[2][NS];
; #pragma unroll
;     for (int b2 = 0; b2 < 2; ++b2)
; #pragma unroll
;         for (int s = 0; s < NS; ++s) kf[b2][s] = *(const LAS bf16x8*)(kb + (32 * b2 + r) * KSTR + 32 * s + 16 * h);
;     __builtin_amdgcn_sched_barrier(0);
; #pragma unroll
;     for (int b2 = 0; b2 < 2; ++b2) {
;         f32x16 a;
; #pragma unroll
;         for (int i = 0; i < 16; ++i) a[i] = 0.f;
; #pragma unroll
;         for (int s = 0; s < NS; ++s) a = MFMA32(kf[b2][s], qf[s], a);
;         st[b2] = a;
;     }
;     __builtin_amdgcn_sched_barrier(0);
; }
; DEV void pack_p(bf16x8 (&pf)[4], const f32x16 (&st)[2]) {
; #pragma unroll
;     for (int b2 = 0; b2 < 2; ++b2)
; #pragma unroll
;         for (int s = 0; s < 2; ++s) { u32x4 p; p.x = pk2(st[b2][8 * s], st[b2][8 * s + 1]); p.y = pk2(st[b2][8 * s + 2], st[b2][8 * s + 3]);
;             p.z = pk2(st[b2][8 * s + 4], st[b2][8 * s + 5]); p.w = pk2(st[b2][8 * s + 6], st[b2][8 * s + 7]); pf[2 * b2 + s] = __builtin_bit_cast(bf16x8, p); }
; }
; DEV void pv_load(bf16x8 (&vf)[2][4], const LAS unsigned char* vb, int r, int h) {
; #pragma unroll
;     for (int db = 0; db < 2; ++db)
; #pragma unroll
;         for (int f = 0; f < 4; ++f) { const LAS unsigned char* p = vb + (32 * db + r) * 136 + (16 * f + 4 * h) * 2;
; template <int DQK, int MODE> ...
;     ...
;     auto compute = [&](const int t, const int slot) __attribute__((always_inline)) {
;         LAS unsigned char* kb = lds + AL_K0 + slot * AL_KSTR; LAS unsigned char* vb = lds + AL_V0 + slot * AL_VSTR;
;         const int k0 = 64 * t;
;         bool rowsel = true;
;         if (MODE == 1) rowsel = (selm.x >> (t >> 2)) & 1u;
;         if (MODE == 2) { const int tw = t >> 5; const unsigned w = tw == 0 ? selm.x : (tw == 1 ? selm.y : (tw == 2 ? selm.z : selm.w)); rowsel = (w >> (t & 31)) & 1u; }
;         const bool rowact = rowsel && (k0 <= hi_lim) && (k0 + 63 >= lo_lim);
;         if (__any(rowact ? 1 : 0)) {
;             f32x16 st[2];
;             qk_tile<DQK>(st, kb, qf, r, h);
;             bf16x8 vf[2][4];
;             if (MODE != 3) pv_load(vf, vb, r, h);
;             const bool interior = __all(((k0 + 63 <= hi_lim) && (k0 >= lo_lim)) ? 1 : 0);
.LBB0_2797:
	s_lshl_b32 s30, s28, 6
	s_or_b32 s12, s30, 63
	v_cmp_le_i32_e32 vcc, s30, v210
	v_cmp_ge_i32_e64 s[0:1], s12, v227
	s_and_b64 vcc, vcc, s[0:1]
	s_cbranch_vccz .LBB0_2803
	s_mul_i32 s0, s29, 0x9c00
	v_add_u32_e32 v0, s0, v228
	ds_read_b128 v[2:5], v0
	ds_read_b128 v[6:9], v0 offset:32
	ds_read_b128 v[10:13], v0 offset:64
	ds_read_b128 v[14:17], v0 offset:96
	ds_read_b128 v[18:21], v0 offset:4608
	ds_read_b128 v[22:25], v0 offset:4640
	ds_read_b128 v[26:29], v0 offset:4672
	ds_read_b128 v[184:187], v0 offset:4704
	s_mul_i32 s0, s29, 0x6600
	s_setprio 1
	s_waitcnt lgkmcnt(7)
	v_mfma_f32_32x32x16_bf16 v[128:143], v[2:5], v[144:147], 0
	s_waitcnt lgkmcnt(6)
	v_mfma_f32_32x32x16_bf16 v[128:143], v[6:9], v[152:155], v[128:143]
	s_waitcnt lgkmcnt(5)
	v_mfma_f32_32x32x16_bf16 v[128:143], v[10:13], v[148:151], v[128:143]
	s_waitcnt lgkmcnt(4)
	v_mfma_f32_32x32x16_bf16 v[128:143], v[14:17], v[156:159], v[128:143]
	s_waitcnt lgkmcnt(3)
	v_mfma_f32_32x32x16_bf16 v[2:17], v[18:21], v[144:147], 0
	s_waitcnt lgkmcnt(2)
	v_mfma_f32_32x32x16_bf16 v[2:17], v[22:25], v[152:155], v[2:17]
	s_waitcnt lgkmcnt(1)
	v_mfma_f32_32x32x16_bf16 v[2:17], v[26:29], v[148:151], v[2:17]
	s_waitcnt lgkmcnt(0)
	v_mfma_f32_32x32x16_bf16 v[2:17], v[184:187], v[156:159], v[2:17]
	s_setprio 0
	v_add_u32_e32 v0, s0, v229
	ds_read2_b64 v[200:203], v0 offset1:2
	ds_read2_b64 v[26:29], v0 offset0:4 offset1:6
	ds_read2_b64 v[22:25], v0 offset0:8 offset1:10
	ds_read2_b64 v[18:21], v0 offset0:12 offset1:14
	v_add_u32_e32 v0, 0x1000, v0
	ds_read2_b64 v[196:199], v0 offset0:32 offset1:34
	ds_read2_b64 v[192:195], v0 offset0:36 offset1:38
	ds_read2_b64 v[188:191], v0 offset0:40 offset1:42
	ds_read2_b64 v[184:187], v0 offset0:44 offset1:46
	v_cmp_le_i32_e32 vcc, s12, v210
	v_cmp_ge_i32_e64 s[0:1], s30, v227
	s_and_b64 s[0:1], s[0:1], vcc
	s_nop 0
	v_cndmask_b32_e64 v0, 0, 1, s[0:1]
	v_cmp_ne_u32_e32 vcc, 0, v0
	s_cmp_eq_u64 vcc, exec
	s_cbranch_scc1 .LBB0_2800
; DEV int crow(int i, int h) { return (i & 3) + 8 * (i >> 2) + 4 * h; }
; template <int DQK, int MODE> ...
;     ...
;             if (!interior) {
; #pragma unroll
;                 for (int b2 = 0; b2 < 2; ++b2)
; #pragma unroll
;                     for (int i = 0; i < 16; ++i) { const int key = k0 + 32 * b2 + crow(i, h); const bool vis = (key <= hi_lim) && (key >= lo_lim); st[b2][i] = vis ? st[b2][i] : -INFINITY; }
;             }
	v_add_u32_e32 v0, s30, v230
	v_cmp_gt_i32_e32 vcc, v0, v210
	v_cmp_lt_i32_e64 s[0:1], v0, v227
	s_or_b64 vcc, vcc, s[0:1]
	v_add_u32_e32 v30, 1, v0
	v_cndmask_b32_e32 v128, v128, v218, vcc
	v_cmp_gt_i32_e32 vcc, v30, v210
	v_cmp_lt_i32_e64 s[0:1], v30, v227
	s_or_b64 vcc, vcc, s[0:1]
	v_add_u32_e32 v30, 2, v0
	v_cndmask_b32_e32 v129, v129, v218, vcc
	v_cmp_gt_i32_e32 vcc, v30, v210
	v_cmp_lt_i32_e64 s[0:1], v30, v227
	s_or_b64 vcc, vcc, s[0:1]
	v_add_u32_e32 v30, 3, v0
	v_cndmask_b32_e32 v130, v130, v218, vcc
	v_cmp_gt_i32_e32 vcc, v30, v210
	v_cmp_lt_i32_e64 s[0:1], v30, v227
	s_or_b64 vcc, vcc, s[0:1]
	v_add_u32_e32 v30, 8, v0
	v_cndmask_b32_e32 v131, v131, v218, vcc
	v_cmp_gt_i32_e32 vcc, v30, v210
	v_cmp_lt_i32_e64 s[0:1], v30, v227
	s_or_b64 vcc, vcc, s[0:1]
	v_add_u32_e32 v30, 9, v0
	v_cndmask_b32_e32 v132, v132, v218, vcc
	v_cmp_gt_i32_e32 vcc, v30, v210
	v_cmp_lt_i32_e64 s[0:1], v30, v227
	s_or_b64 vcc, vcc, s[0:1]
	v_add_u32_e32 v30, 10, v0
	v_cndmask_b32_e32 v133, v133, v218, vcc
	v_cmp_gt_i32_e32 vcc, v30, v210
	v_cmp_lt_i32_e64 s[0:1], v30, v227
	s_or_b64 vcc, vcc, s[0:1]
	v_add_u32_e32 v30, 11, v0
	v_cndmask_b32_e32 v134, v134, v218, vcc
	v_cmp_gt_i32_e32 vcc, v30, v210
	v_cmp_lt_i32_e64 s[0:1], v30, v227
	s_or_b64 vcc, vcc, s[0:1]
	v_add_u32_e32 v30, 16, v0
	v_cndmask_b32_e32 v135, v135, v218, vcc
	v_cmp_gt_i32_e32 vcc, v30, v210
	v_cmp_lt_i32_e64 s[0:1], v30, v227
	s_or_b64 vcc, vcc, s[0:1]
	v_add_u32_e32 v30, 17, v0
	v_cndmask_b32_e32 v136, v136, v218, vcc
	v_cmp_gt_i32_e32 vcc, v30, v210
	v_cmp_lt_i32_e64 s[0:1], v30, v227
	s_or_b64 vcc, vcc, s[0:1]
	v_add_u32_e32 v30, 18, v0
	v_cndmask_b32_e32 v137, v137, v218, vcc
	v_cmp_gt_i32_e32 vcc, v30, v210
	v_cmp_lt_i32_e64 s[0:1], v30, v227
	s_or_b64 vcc, vcc, s[0:1]
	v_add_u32_e32 v30, 19, v0
	v_cndmask_b32_e32 v138, v138, v218, vcc
	v_cmp_gt_i32_e32 vcc, v30, v210
	v_cmp_lt_i32_e64 s[0:1], v30, v227
	s_or_b64 vcc, vcc, s[0:1]
	v_add_u32_e32 v30, 24, v0
	v_cndmask_b32_e32 v139, v139, v218, vcc
	v_cmp_gt_i32_e32 vcc, v30, v210
	v_cmp_lt_i32_e64 s[0:1], v30, v227
	s_or_b64 vcc, vcc, s[0:1]
	v_add_u32_e32 v30, 25, v0
	v_cndmask_b32_e32 v140, v140, v218, vcc
	v_cmp_gt_i32_e32 vcc, v30, v210
	v_cmp_lt_i32_e64 s[0:1], v30, v227
	s_or_b64 vcc, vcc, s[0:1]
	v_add_u32_e32 v30, 26, v0
	v_cndmask_b32_e32 v141, v141, v218, vcc
	v_cmp_gt_i32_e32 vcc, v30, v210
	v_cmp_lt_i32_e64 s[0:1], v30, v227
	s_or_b64 vcc, vcc, s[0:1]
	v_add_u32_e32 v30, 27, v0
	v_cndmask_b32_e32 v142, v142, v218, vcc
	v_cmp_gt_i32_e32 vcc, v30, v210
	v_cmp_lt_i32_e64 s[0:1], v30, v227
	s_or_b64 vcc, vcc, s[0:1]
	v_add_u32_e32 v30, 32, v0
	v_cndmask_b32_e32 v143, v143, v218, vcc
	v_cmp_gt_i32_e32 vcc, v30, v210
	v_cmp_lt_i32_e64 s[0:1], v30, v227
	s_or_b64 vcc, vcc, s[0:1]
	v_add_u32_e32 v30, 33, v0
	v_cndmask_b32_e32 v2, v2, v218, vcc
	v_cmp_gt_i32_e32 vcc, v30, v210
	v_cmp_lt_i32_e64 s[0:1], v30, v227
	s_or_b64 vcc, vcc, s[0:1]
	v_add_u32_e32 v30, 34, v0
	v_cndmask_b32_e32 v3, v3, v218, vcc
	v_cmp_gt_i32_e32 vcc, v30, v210
	v_cmp_lt_i32_e64 s[0:1], v30, v227
	s_or_b64 vcc, vcc, s[0:1]
	v_add_u32_e32 v30, 35, v0
	v_cndmask_b32_e32 v4, v4, v218, vcc
	v_cmp_gt_i32_e32 vcc, v30, v210
	v_cmp_lt_i32_e64 s[0:1], v30, v227
	s_or_b64 vcc, vcc, s[0:1]
	v_add_u32_e32 v30, 40, v0
	v_cndmask_b32_e32 v5, v5, v218, vcc
	v_cmp_gt_i32_e32 vcc, v30, v210
	v_cmp_lt_i32_e64 s[0:1], v30, v227
	s_or_b64 vcc, vcc, s[0:1]
	v_add_u32_e32 v30, 41, v0
	v_cndmask_b32_e32 v6, v6, v218, vcc
	v_cmp_gt_i32_e32 vcc, v30, v210
	v_cmp_lt_i32_e64 s[0:1], v30, v227
	s_or_b64 vcc, vcc, s[0:1]
	v_add_u32_e32 v30, 42, v0
	v_cndmask_b32_e32 v7, v7, v218, vcc
	v_cmp_gt_i32_e32 vcc, v30, v210
	v_cmp_lt_i32_e64 s[0:1], v30, v227
	s_or_b64 vcc, vcc, s[0:1]
	v_add_u32_e32 v30, 43, v0
	v_cndmask_b32_e32 v8, v8, v218, vcc
	v_cmp_gt_i32_e32 vcc, v30, v210
	v_cmp_lt_i32_e64 s[0:1], v30, v227
	s_or_b64 vcc, vcc, s[0:1]
	v_add_u32_e32 v30, 48, v0
	v_cndmask_b32_e32 v9, v9, v218, vcc
	v_cmp_gt_i32_e32 vcc, v30, v210
	v_cmp_lt_i32_e64 s[0:1], v30, v227
	s_or_b64 vcc, vcc, s[0:1]
	v_add_u32_e32 v30, 49, v0
	v_cndmask_b32_e32 v10, v10, v218, vcc
	v_cmp_gt_i32_e32 vcc, v30, v210
	v_cmp_lt_i32_e64 s[0:1], v30, v227
	s_or_b64 vcc, vcc, s[0:1]
	v_add_u32_e32 v30, 50, v0
	v_cndmask_b32_e32 v11, v11, v218, vcc
	v_cmp_gt_i32_e32 vcc, v30, v210
	v_cmp_lt_i32_e64 s[0:1], v30, v227
	s_or_b64 vcc, vcc, s[0:1]
	v_add_u32_e32 v30, 51, v0
	v_cndmask_b32_e32 v12, v12, v218, vcc
	v_cmp_gt_i32_e32 vcc, v30, v210
	v_cmp_lt_i32_e64 s[0:1], v30, v227
	s_or_b64 vcc, vcc, s[0:1]
	v_add_u32_e32 v30, 56, v0
	v_cndmask_b32_e32 v13, v13, v218, vcc
	v_cmp_gt_i32_e32 vcc, v30, v210
	v_cmp_lt_i32_e64 s[0:1], v30, v227
	s_or_b64 vcc, vcc, s[0:1]
	v_add_u32_e32 v30, 57, v0
	v_cndmask_b32_e32 v14, v14, v218, vcc
	v_cmp_gt_i32_e32 vcc, v30, v210
	v_cmp_lt_i32_e64 s[0:1], v30, v227
	s_or_b64 vcc, vcc, s[0:1]
	v_add_u32_e32 v30, 58, v0
	v_cndmask_b32_e32 v15, v15, v218, vcc
	v_cmp_gt_i32_e32 vcc, v30, v210
	v_cmp_lt_i32_e64 s[0:1], v30, v227
	s_or_b64 vcc, vcc, s[0:1]
	v_add_u32_e32 v0, 59, v0
	v_cndmask_b32_e32 v16, v16, v218, vcc
	v_cmp_gt_i32_e32 vcc, v0, v210
	v_cmp_lt_i32_e64 s[0:1], v0, v227
	s_or_b64 vcc, vcc, s[0:1]
	v_cndmask_b32_e32 v17, v17, v218, vcc

; #define LAS __attribute__((address_space(3)))
; #define MFMA32(a, b, c) __builtin_amdgcn_mfma_f32_32x32x16_bf16((a), (b), (c), 0, 0, 0)
; DEV unsigned pk2(float lo, float hi) { f32x2_ v; v.x = lo; v.y = hi; return __builtin_bit_cast(unsigned, __builtin_convertvector(v, bf16x2_)); }
; DEV float fexp2(float x) { return __builtin_amdgcn_exp2f(x); }
; DEV void pack_p(bf16x8 (&pf)[4], const f32x16 (&st)[2]) {
; #pragma unroll
;     for (int b2 = 0; b2 < 2; ++b2)
; #pragma unroll
;         for (int s = 0; s < 2; ++s) { u32x4 p; p.x = pk2(st[b2][8 * s], st[b2][8 * s + 1]); p.y = pk2(st[b2][8 * s + 2], st[b2][8 * s + 3]);
;             p.z = pk2(st[b2][8 * s + 4], st[b2][8 * s + 5]); p.w = pk2(st[b2][8 * s + 6], st[b2][8 * s + 7]); pf[2 * b2 + s] = __builtin_bit_cast(bf16x8, p); }
; }
; DEV void pv_load(bf16x8 (&vf)[2][4], const LAS unsigned char* vb, int r, int h) {
; #pragma unroll
;     for (int db = 0; db < 2; ++db)
; #pragma unroll
;         for (int f = 0; f < 4; ++f) { const LAS unsigned char* p = vb + (32 * db + r) * 136 + (16 * f + 4 * h) * 2;
;             const s16x4 lo = *(const LAS s16x4*)p, hi = *(const LAS s16x4*)(p + 16);
;             vf[db][f] = __builtin_shufflevector(lo, hi, 0, 1, 2, 3, 4, 5, 6, 7); }
;     __builtin_amdgcn_sched_barrier(0);
; }
; DEV void pv_mma(f32x16 (&o)[2], const bf16x8 (&vf)[2][4], const bf16x8 (&pf)[4]) {
;     __builtin_amdgcn_sched_barrier(0);
; #pragma unroll
;     for (int f = 0; f < 4; ++f)
; #pragma unroll
;         for (int db = 0; db < 2; ++db) o[db] = MFMA32(vf[db][f], pf[f], o[db]);
;     __builtin_amdgcn_sched_barrier(0);
; }
; template <int DQK, int MODE> ...
;     ...
;                 const float cb = rowsel ? -m_new : -INFINITY;
;                 float ps = 0.f;
; #pragma unroll
;                 for (int b2 = 0; b2 < 2; ++b2)
; #pragma unroll
;                     for (int i = 0; i < 16; ++i) { const float p = fexp2(__builtin_fmaf(st[b2][i], sc, cb)); st[b2][i] = p; ps += p; }
;                 l_run += ps;
;                 bf16x8 pf[4]; pack_p(pf, st);
;                 pv_mma(o, vf, pf);
.LBB0_2802:
	v_fma_f32 v30, v128, s66, -v0
	v_exp_f32_e32 v128, v30
	v_fma_f32 v31, v129, s66, -v0
	v_exp_f32_e32 v129, v31
	v_fma_f32 v30, v130, s66, -v0
	v_add_f32_e32 v233, 0, v128
	v_exp_f32_e32 v130, v30
	v_fma_f32 v31, v131, s66, -v0
	v_add_f32_e32 v233, v129, v233
	v_exp_f32_e32 v131, v31
	v_fma_f32 v30, v132, s66, -v0
	v_add_f32_e32 v233, v130, v233
	v_exp_f32_e32 v132, v30
	v_fma_f32 v31, v133, s66, -v0
	v_add_f32_e32 v233, v131, v233
	v_exp_f32_e32 v133, v31
	v_fma_f32 v30, v134, s66, -v0
	v_add_f32_e32 v233, v132, v233
	v_exp_f32_e32 v134, v30
	v_fma_f32 v31, v135, s66, -v0
	v_add_f32_e32 v233, v133, v233
	v_exp_f32_e32 v135, v31
	v_add_f32_e32 v233, v134, v233
	v_add_f32_e32 v233, v135, v233
	v_cvt_pk_bf16_f32 v128, v128, v129
	v_cvt_pk_bf16_f32 v129, v130, v131
	v_cvt_pk_bf16_f32 v130, v132, v133
	v_cvt_pk_bf16_f32 v131, v134, v135
	v_fma_f32 v30, v136, s66, -v0
	v_exp_f32_e32 v136, v30
	v_fma_f32 v31, v137, s66, -v0
	v_exp_f32_e32 v137, v31
	v_mfma_f32_32x32x16_bf16 v[96:111], v[200:203], v[128:131], v[96:111]
	v_mfma_f32_32x32x16_bf16 v[112:127], v[196:199], v[128:131], v[112:127]
	v_fma_f32 v30, v138, s66, -v0
	v_add_f32_e32 v233, v136, v233
	v_exp_f32_e32 v138, v30
	v_fma_f32 v31, v139, s66, -v0
	v_add_f32_e32 v233, v137, v233
	v_exp_f32_e32 v139, v31
	v_fma_f32 v30, v140, s66, -v0
	v_add_f32_e32 v233, v138, v233
	v_exp_f32_e32 v140, v30
	v_fma_f32 v31, v141, s66, -v0
	v_add_f32_e32 v233, v139, v233
	v_exp_f32_e32 v141, v31
	v_fma_f32 v30, v142, s66, -v0
	v_add_f32_e32 v233, v140, v233
	v_exp_f32_e32 v142, v30
	v_fma_f32 v31, v143, s66, -v0
	v_add_f32_e32 v233, v141, v233
	v_exp_f32_e32 v143, v31
	v_add_f32_e32 v233, v142, v233
	v_add_f32_e32 v233, v143, v233
	v_cvt_pk_bf16_f32 v136, v136, v137
	v_cvt_pk_bf16_f32 v137, v138, v139
	v_cvt_pk_bf16_f32 v138, v140, v141
	v_cvt_pk_bf16_f32 v139, v142, v143
	v_fma_f32 v30, v2, s66, -v0
	v_exp_f32_e32 v2, v30
	v_fma_f32 v31, v3, s66, -v0
	v_exp_f32_e32 v3, v31
	v_mfma_f32_32x32x16_bf16 v[96:111], v[26:29], v[136:139], v[96:111]
	v_mfma_f32_32x32x16_bf16 v[112:127], v[192:195], v[136:139], v[112:127]
	v_fma_f32 v30, v4, s66, -v0
	v_add_f32_e32 v233, v2, v233
	v_exp_f32_e32 v4, v30
	v_fma_f32 v31, v5, s66, -v0
	v_add_f32_e32 v233, v3, v233
	v_exp_f32_e32 v5, v31
	v_fma_f32 v30, v6, s66, -v0
	v_add_f32_e32 v233, v4, v233
	v_exp_f32_e32 v6, v30
	v_fma_f32 v31, v7, s66, -v0
	v_add_f32_e32 v233, v5, v233
	v_exp_f32_e32 v7, v31
	v_fma_f32 v30, v8, s66, -v0
	v_add_f32_e32 v233, v6, v233
	v_exp_f32_e32 v8, v30
	v_fma_f32 v31, v9, s66, -v0
	v_add_f32_e32 v233, v7, v233
	v_exp_f32_e32 v9, v31
	v_add_f32_e32 v233, v8, v233
	v_add_f32_e32 v233, v9, v233
	v_cvt_pk_bf16_f32 v2, v2, v3
	v_cvt_pk_bf16_f32 v3, v4, v5
	v_cvt_pk_bf16_f32 v4, v6, v7
	v_cvt_pk_bf16_f32 v5, v8, v9
	v_fma_f32 v30, v10, s66, -v0
	v_exp_f32_e32 v10, v30
	v_fma_f32 v31, v11, s66, -v0
	v_exp_f32_e32 v11, v31
	v_mfma_f32_32x32x16_bf16 v[96:111], v[22:25], v[2:5], v[96:111]
	v_mfma_f32_32x32x16_bf16 v[112:127], v[188:191], v[2:5], v[112:127]
	v_fma_f32 v30, v12, s66, -v0
	v_add_f32_e32 v233, v10, v233
	v_exp_f32_e32 v12, v30
	v_fma_f32 v31, v13, s66, -v0
	v_add_f32_e32 v233, v11, v233
	v_exp_f32_e32 v13, v31
	v_fma_f32 v30, v14, s66, -v0
	v_add_f32_e32 v233, v12, v233
	v_exp_f32_e32 v14, v30
	v_fma_f32 v31, v15, s66, -v0
	v_add_f32_e32 v233, v13, v233
	v_exp_f32_e32 v15, v31
	v_fma_f32 v30, v16, s66, -v0
	v_add_f32_e32 v233, v14, v233
	v_exp_f32_e32 v16, v30
	v_fma_f32 v31, v17, s66, -v0
	v_add_f32_e32 v233, v15, v233
	v_exp_f32_e32 v17, v31
	v_add_f32_e32 v233, v16, v233
	v_add_f32_e32 v233, v17, v233
	v_cvt_pk_bf16_f32 v10, v10, v11
	v_cvt_pk_bf16_f32 v11, v12, v13
	v_cvt_pk_bf16_f32 v12, v14, v15
	v_cvt_pk_bf16_f32 v13, v16, v17
	v_add_f32_e32 v213, v233, v213
	s_nop 0
	v_mfma_f32_32x32x16_bf16 v[96:111], v[18:21], v[10:13], v[96:111]
	v_mfma_f32_32x32x16_bf16 v[112:127], v[184:187], v[10:13], v[112:127]
.LBB0_2803:
	s_cmp_ge_i32 s28, s82
	s_mul_i32 s29, s29, 3
	s_cbranch_scc1 .LBB0_2810
	s_add_i32 s30, s30, 64
	s_or_b32 s12, s30, 63
	v_cmp_le_i32_e32 vcc, s30, v210
	v_cmp_ge_i32_e64 s[0:1], s12, v227
	s_and_b64 vcc, vcc, s[0:1]
	s_cbranch_vccz .LBB0_2810
	s_add_i32 s0, s29, 1
	s_mul_i32 s1, s0, 0x3400
	v_add_u32_e32 v0, s1, v228
	ds_read_b128 v[2:5], v0
	ds_read_b128 v[6:9], v0 offset:32
	ds_read_b128 v[10:13], v0 offset:64
	ds_read_b128 v[14:17], v0 offset:96
	ds_read_b128 v[18:21], v0 offset:4608
	ds_read_b128 v[22:25], v0 offset:4640
	ds_read_b128 v[26:29], v0 offset:4672
	ds_read_b128 v[184:187], v0 offset:4704
	s_mulk_i32 s0, 0x2200
	s_setprio 1
	s_waitcnt lgkmcnt(7)
	v_mfma_f32_32x32x16_bf16 v[128:143], v[2:5], v[144:147], 0
	s_waitcnt lgkmcnt(6)
	v_mfma_f32_32x32x16_bf16 v[128:143], v[6:9], v[152:155], v[128:143]
	s_waitcnt lgkmcnt(5)
	v_mfma_f32_32x32x16_bf16 v[128:143], v[10:13], v[148:151], v[128:143]
	s_waitcnt lgkmcnt(4)
	v_mfma_f32_32x32x16_bf16 v[128:143], v[14:17], v[156:159], v[128:143]
	s_waitcnt lgkmcnt(3)
	v_mfma_f32_32x32x16_bf16 v[2:17], v[18:21], v[144:147], 0
	s_waitcnt lgkmcnt(2)
	v_mfma_f32_32x32x16_bf16 v[2:17], v[22:25], v[152:155], v[2:17]
	s_waitcnt lgkmcnt(1)
	v_mfma_f32_32x32x16_bf16 v[2:17], v[26:29], v[148:151], v[2:17]
	s_waitcnt lgkmcnt(0)
	v_mfma_f32_32x32x16_bf16 v[2:17], v[184:187], v[156:159], v[2:17]
	s_setprio 0
	v_add_u32_e32 v0, s0, v229
	ds_read2_b64 v[200:203], v0 offset1:2
	ds_read2_b64 v[26:29], v0 offset0:4 offset1:6
	ds_read2_b64 v[22:25], v0 offset0:8 offset1:10
	ds_read2_b64 v[18:21], v0 offset0:12 offset1:14
	v_add_u32_e32 v0, 0x1000, v0
	ds_read2_b64 v[196:199], v0 offset0:32 offset1:34
	ds_read2_b64 v[192:195], v0 offset0:36 offset1:38
	ds_read2_b64 v[188:191], v0 offset0:40 offset1:42
	ds_read2_b64 v[184:187], v0 offset0:44 offset1:46
	v_cmp_le_i32_e32 vcc, s12, v210
	v_cmp_ge_i32_e64 s[0:1], s30, v227
	s_and_b64 s[0:1], s[0:1], vcc
	s_nop 0
	v_cndmask_b32_e64 v0, 0, 1, s[0:1]
	v_cmp_ne_u32_e32 vcc, 0, v0
	s_cmp_eq_u64 vcc, exec
	s_cbranch_scc1 .LBB0_2807
; DEV int crow(int i, int h) { return (i & 3) + 8 * (i >> 2) + 4 * h; }
; template <int DQK, int MODE> ...
;     ...
;             if (!interior) {
; #pragma unroll
;                 for (int b2 = 0; b2 < 2; ++b2)
; #pragma unroll
;                     for (int i = 0; i < 16; ++i) { const int key = k0 + 32 * b2 + crow(i, h); const bool vis = (key <= hi_lim) && (key >= lo_lim); st[b2][i] = vis ? st[b2][i] : -INFINITY; }
;             }
	v_add_u32_e32 v0, s30, v230
	v_cmp_gt_i32_e32 vcc, v0, v210
	v_cmp_lt_i32_e64 s[0:1], v0, v227
	s_or_b64 vcc, vcc, s[0:1]
	v_add_u32_e32 v30, 1, v0
	v_cndmask_b32_e32 v128, v128, v218, vcc
	v_cmp_gt_i32_e32 vcc, v30, v210
	v_cmp_lt_i32_e64 s[0:1], v30, v227
	s_or_b64 vcc, vcc, s[0:1]
	v_add_u32_e32 v30, 2, v0
	v_cndmask_b32_e32 v129, v129, v218, vcc
	v_cmp_gt_i32_e32 vcc, v30, v210
	v_cmp_lt_i32_e64 s[0:1], v30, v227
	s_or_b64 vcc, vcc, s[0:1]
	v_add_u32_e32 v30, 3, v0
	v_cndmask_b32_e32 v130, v130, v218, vcc
	v_cmp_gt_i32_e32 vcc, v30, v210
	v_cmp_lt_i32_e64 s[0:1], v30, v227
	s_or_b64 vcc, vcc, s[0:1]
	v_add_u32_e32 v30, 8, v0
	v_cndmask_b32_e32 v131, v131, v218, vcc
	v_cmp_gt_i32_e32 vcc, v30, v210
	v_cmp_lt_i32_e64 s[0:1], v30, v227
	s_or_b64 vcc, vcc, s[0:1]
	v_add_u32_e32 v30, 9, v0
	v_cndmask_b32_e32 v132, v132, v218, vcc
	v_cmp_gt_i32_e32 vcc, v30, v210
	v_cmp_lt_i32_e64 s[0:1], v30, v227
	s_or_b64 vcc, vcc, s[0:1]
	v_add_u32_e32 v30, 10, v0
	v_cndmask_b32_e32 v133, v133, v218, vcc
	v_cmp_gt_i32_e32 vcc, v30, v210
	v_cmp_lt_i32_e64 s[0:1], v30, v227
	s_or_b64 vcc, vcc, s[0:1]
	v_add_u32_e32 v30, 11, v0
	v_cndmask_b32_e32 v134, v134, v218, vcc
	v_cmp_gt_i32_e32 vcc, v30, v210
	v_cmp_lt_i32_e64 s[0:1], v30, v227
	s_or_b64 vcc, vcc, s[0:1]
	v_add_u32_e32 v30, 16, v0
	v_cndmask_b32_e32 v135, v135, v218, vcc
	v_cmp_gt_i32_e32 vcc, v30, v210
	v_cmp_lt_i32_e64 s[0:1], v30, v227
	s_or_b64 vcc, vcc, s[0:1]
	v_add_u32_e32 v30, 17, v0
	v_cndmask_b32_e32 v136, v136, v218, vcc
	v_cmp_gt_i32_e32 vcc, v30, v210
	v_cmp_lt_i32_e64 s[0:1], v30, v227
	s_or_b64 vcc, vcc, s[0:1]
	v_add_u32_e32 v30, 18, v0
	v_cndmask_b32_e32 v137, v137, v218, vcc
	v_cmp_gt_i32_e32 vcc, v30, v210
	v_cmp_lt_i32_e64 s[0:1], v30, v227
	s_or_b64 vcc, vcc, s[0:1]
	v_add_u32_e32 v30, 19, v0
	v_cndmask_b32_e32 v138, v138, v218, vcc
	v_cmp_gt_i32_e32 vcc, v30, v210
	v_cmp_lt_i32_e64 s[0:1], v30, v227
	s_or_b64 vcc, vcc, s[0:1]
	v_add_u32_e32 v30, 24, v0
	v_cndmask_b32_e32 v139, v139, v218, vcc
	v_cmp_gt_i32_e32 vcc, v30, v210
	v_cmp_lt_i32_e64 s[0:1], v30, v227
	s_or_b64 vcc, vcc, s[0:1]
	v_add_u32_e32 v30, 25, v0
	v_cndmask_b32_e32 v140, v140, v218, vcc
	v_cmp_gt_i32_e32 vcc, v30, v210
	v_cmp_lt_i32_e64 s[0:1], v30, v227
	s_or_b64 vcc, vcc, s[0:1]
	v_add_u32_e32 v30, 26, v0
	v_cndmask_b32_e32 v141, v141, v218, vcc
	v_cmp_gt_i32_e32 vcc, v30, v210
	v_cmp_lt_i32_e64 s[0:1], v30, v227
	s_or_b64 vcc, vcc, s[0:1]
	v_add_u32_e32 v30, 27, v0
	v_cndmask_b32_e32 v142, v142, v218, vcc
	v_cmp_gt_i32_e32 vcc, v30, v210
	v_cmp_lt_i32_e64 s[0:1], v30, v227
	s_or_b64 vcc, vcc, s[0:1]
	v_add_u32_e32 v30, 32, v0
	v_cndmask_b32_e32 v143, v143, v218, vcc
	v_cmp_gt_i32_e32 vcc, v30, v210
	v_cmp_lt_i32_e64 s[0:1], v30, v227
	s_or_b64 vcc, vcc, s[0:1]
	v_add_u32_e32 v30, 33, v0
	v_cndmask_b32_e32 v2, v2, v218, vcc
	v_cmp_gt_i32_e32 vcc, v30, v210
	v_cmp_lt_i32_e64 s[0:1], v30, v227
	s_or_b64 vcc, vcc, s[0:1]
	v_add_u32_e32 v30, 34, v0
	v_cndmask_b32_e32 v3, v3, v218, vcc
	v_cmp_gt_i32_e32 vcc, v30, v210
	v_cmp_lt_i32_e64 s[0:1], v30, v227
	s_or_b64 vcc, vcc, s[0:1]
	v_add_u32_e32 v30, 35, v0
	v_cndmask_b32_e32 v4, v4, v218, vcc
	v_cmp_gt_i32_e32 vcc, v30, v210
	v_cmp_lt_i32_e64 s[0:1], v30, v227
	s_or_b64 vcc, vcc, s[0:1]
	v_add_u32_e32 v30, 40, v0
	v_cndmask_b32_e32 v5, v5, v218, vcc
	v_cmp_gt_i32_e32 vcc, v30, v210
	v_cmp_lt_i32_e64 s[0:1], v30, v227
	s_or_b64 vcc, vcc, s[0:1]
	v_add_u32_e32 v30, 41, v0
	v_cndmask_b32_e32 v6, v6, v218, vcc
	v_cmp_gt_i32_e32 vcc, v30, v210
	v_cmp_lt_i32_e64 s[0:1], v30, v227
	s_or_b64 vcc, vcc, s[0:1]
	v_add_u32_e32 v30, 42, v0
	v_cndmask_b32_e32 v7, v7, v218, vcc
	v_cmp_gt_i32_e32 vcc, v30, v210
	v_cmp_lt_i32_e64 s[0:1], v30, v227
	s_or_b64 vcc, vcc, s[0:1]
	v_add_u32_e32 v30, 43, v0
	v_cndmask_b32_e32 v8, v8, v218, vcc
	v_cmp_gt_i32_e32 vcc, v30, v210
	v_cmp_lt_i32_e64 s[0:1], v30, v227
	s_or_b64 vcc, vcc, s[0:1]
	v_add_u32_e32 v30, 48, v0
	v_cndmask_b32_e32 v9, v9, v218, vcc
	v_cmp_gt_i32_e32 vcc, v30, v210
	v_cmp_lt_i32_e64 s[0:1], v30, v227
	s_or_b64 vcc, vcc, s[0:1]
	v_add_u32_e32 v30, 49, v0
	v_cndmask_b32_e32 v10, v10, v218, vcc
	v_cmp_gt_i32_e32 vcc, v30, v210
	v_cmp_lt_i32_e64 s[0:1], v30, v227
	s_or_b64 vcc, vcc, s[0:1]
	v_add_u32_e32 v30, 50, v0
	v_cndmask_b32_e32 v11, v11, v218, vcc
	v_cmp_gt_i32_e32 vcc, v30, v210
	v_cmp_lt_i32_e64 s[0:1], v30, v227
	s_or_b64 vcc, vcc, s[0:1]
	v_add_u32_e32 v30, 51, v0
	v_cndmask_b32_e32 v12, v12, v218, vcc
	v_cmp_gt_i32_e32 vcc, v30, v210
	v_cmp_lt_i32_e64 s[0:1], v30, v227
	s_or_b64 vcc, vcc, s[0:1]
	v_add_u32_e32 v30, 56, v0
	v_cndmask_b32_e32 v13, v13, v218, vcc
	v_cmp_gt_i32_e32 vcc, v30, v210
	v_cmp_lt_i32_e64 s[0:1], v30, v227
	s_or_b64 vcc, vcc, s[0:1]
	v_add_u32_e32 v30, 57, v0
	v_cndmask_b32_e32 v14, v14, v218, vcc
	v_cmp_gt_i32_e32 vcc, v30, v210
	v_cmp_lt_i32_e64 s[0:1], v30, v227
	s_or_b64 vcc, vcc, s[0:1]
	v_add_u32_e32 v30, 58, v0
	v_cndmask_b32_e32 v15, v15, v218, vcc
	v_cmp_gt_i32_e32 vcc, v30, v210
	v_cmp_lt_i32_e64 s[0:1], v30, v227
	s_or_b64 vcc, vcc, s[0:1]
	v_add_u32_e32 v0, 59, v0
	v_cndmask_b32_e32 v16, v16, v218, vcc
	v_cmp_gt_i32_e32 vcc, v0, v210
	v_cmp_lt_i32_e64 s[0:1], v0, v227
	s_or_b64 vcc, vcc, s[0:1]
	v_cndmask_b32_e32 v17, v17, v218, vcc

; template <int DQK> DEV void qk_tile(f32x16 (&st)[2], const LAS unsigned char* kb, const bf16x8 (&qf)[DQK / 16], int r, int h) {
;     constexpr int KSTR = DQK * 2 + 16, NS = DQK / 16;
;     bf16x8 kf[2][NS];
; #pragma unroll
;     for (int b2 = 0; b2 < 2; ++b2)
; #pragma unroll
;         for (int s = 0; s < NS; ++s) kf[b2][s] = *(const LAS bf16x8*)(kb + (32 * b2 + r) * KSTR + 32 * s + 16 * h);
;     __builtin_amdgcn_sched_barrier(0);
; #pragma unroll
;     for (int b2 = 0; b2 < 2; ++b2) {
;         f32x16 a;
; #pragma unroll
;         for (int i = 0; i < 16; ++i) a[i] = 0.f;
; #pragma unroll
;         for (int s = 0; s < NS; ++s) a = MFMA32(kf[b2][s], qf[s], a);
;         st[b2] = a;
;     }
;     __builtin_amdgcn_sched_barrier(0);
; }
; DEV void pack_p(bf16x8 (&pf)[4], const f32x16 (&st)[2]) {
; #pragma unroll
;     for (int b2 = 0; b2 < 2; ++b2)
; #pragma unroll
;         for (int s = 0; s < 2; ++s) { u32x4 p; p.x = pk2(st[b2][8 * s], st[b2][8 * s + 1]); p.y = pk2(st[b2][8 * s + 2], st[b2][8 * s + 3]);
;             p.z = pk2(st[b2][8 * s + 4], st[b2][8 * s + 5]); p.w = pk2(st[b2][8 * s + 6], st[b2][8 * s + 7]); pf[2 * b2 + s] = __builtin_bit_cast(bf16x8, p); }
; }
; DEV void pv_load(bf16x8 (&vf)[2][4], const LAS unsigned char* vb, int r, int h) {
; #pragma unroll
;     for (int db = 0; db < 2; ++db)
; #pragma unroll
;         for (int f = 0; f < 4; ++f) { const LAS unsigned char* p = vb + (32 * db + r) * 136 + (16 * f + 4 * h) * 2;
; template <int DQK, int MODE> ...
;     ...
;     auto compute = [&](const int t, const int slot) __attribute__((always_inline)) {
;         LAS unsigned char* kb = lds + AL_K0 + slot * AL_KSTR; LAS unsigned char* vb = lds + AL_V0 + slot * AL_VSTR;
;         const int k0 = 64 * t;
;         bool rowsel = true;
;         if (MODE == 1) rowsel = (selm.x >> (t >> 2)) & 1u;
;         if (MODE == 2) { const int tw = t >> 5; const unsigned w = tw == 0 ? selm.x : (tw == 1 ? selm.y : (tw == 2 ? selm.z : selm.w)); rowsel = (w >> (t & 31)) & 1u; }
;         const bool rowact = rowsel && (k0 <= hi_lim) && (k0 + 63 >= lo_lim);
;         if (__any(rowact ? 1 : 0)) {
;             f32x16 st[2];
;             qk_tile<DQK>(st, kb, qf, r, h);
;             bf16x8 vf[2][4];
;             if (MODE != 3) pv_load(vf, vb, r, h);
;             const bool interior = __all(((k0 + 63 <= hi_lim) && (k0 >= lo_lim)) ? 1 : 0);
.LBB0_2810:
	s_add_i32 s0, s28, 2
	s_cmp_gt_i32 s0, s82
	s_cbranch_scc1 .LBB0_2817
	s_lshl_b32 s12, s0, 6
	s_or_b32 s13, s12, 63
	v_cmp_le_i32_e32 vcc, s12, v210
	v_cmp_ge_i32_e64 s[0:1], s13, v227
	s_and_b64 vcc, vcc, s[0:1]
	s_cbranch_vccz .LBB0_2817
	s_add_i32 s0, s29, 2
	s_mul_i32 s1, s0, 0x3400
	v_add_u32_e32 v0, s1, v228
	ds_read_b128 v[2:5], v0
	ds_read_b128 v[6:9], v0 offset:32
	ds_read_b128 v[10:13], v0 offset:64
	ds_read_b128 v[14:17], v0 offset:96
	ds_read_b128 v[18:21], v0 offset:4608
	ds_read_b128 v[22:25], v0 offset:4640
	ds_read_b128 v[26:29], v0 offset:4672
	ds_read_b128 v[184:187], v0 offset:4704
	s_mulk_i32 s0, 0x2200
	s_setprio 1
	s_waitcnt lgkmcnt(7)
	v_mfma_f32_32x32x16_bf16 v[128:143], v[2:5], v[144:147], 0
	s_waitcnt lgkmcnt(6)
	v_mfma_f32_32x32x16_bf16 v[128:143], v[6:9], v[152:155], v[128:143]
	s_waitcnt lgkmcnt(5)
	v_mfma_f32_32x32x16_bf16 v[128:143], v[10:13], v[148:151], v[128:143]
	s_waitcnt lgkmcnt(4)
	v_mfma_f32_32x32x16_bf16 v[128:143], v[14:17], v[156:159], v[128:143]
	s_waitcnt lgkmcnt(3)
	v_mfma_f32_32x32x16_bf16 v[2:17], v[18:21], v[144:147], 0
	s_waitcnt lgkmcnt(2)
	v_mfma_f32_32x32x16_bf16 v[2:17], v[22:25], v[152:155], v[2:17]
	s_waitcnt lgkmcnt(1)
	v_mfma_f32_32x32x16_bf16 v[2:17], v[26:29], v[148:151], v[2:17]
	s_waitcnt lgkmcnt(0)
	v_mfma_f32_32x32x16_bf16 v[2:17], v[184:187], v[156:159], v[2:17]
	s_setprio 0
	v_add_u32_e32 v0, s0, v229
	ds_read2_b64 v[200:203], v0 offset1:2
	ds_read2_b64 v[26:29], v0 offset0:4 offset1:6
	ds_read2_b64 v[22:25], v0 offset0:8 offset1:10
	ds_read2_b64 v[18:21], v0 offset0:12 offset1:14
	v_add_u32_e32 v0, 0x1000, v0
	ds_read2_b64 v[196:199], v0 offset0:32 offset1:34
	ds_read2_b64 v[192:195], v0 offset0:36 offset1:38
	ds_read2_b64 v[188:191], v0 offset0:40 offset1:42
	ds_read2_b64 v[184:187], v0 offset0:44 offset1:46
	v_cmp_le_i32_e32 vcc, s13, v210
	v_cmp_ge_i32_e64 s[0:1], s12, v227
	s_and_b64 s[0:1], s[0:1], vcc
	s_nop 0
	v_cndmask_b32_e64 v0, 0, 1, s[0:1]
	v_cmp_ne_u32_e32 vcc, 0, v0
	s_cmp_eq_u64 vcc, exec
	s_cbranch_scc1 .LBB0_2814
; DEV int crow(int i, int h) { return (i & 3) + 8 * (i >> 2) + 4 * h; }
; template <int DQK, int MODE> ...
;     ...
;             if (!interior) {
; #pragma unroll
;                 for (int b2 = 0; b2 < 2; ++b2)
; #pragma unroll
;                     for (int i = 0; i < 16; ++i) { const int key = k0 + 32 * b2 + crow(i, h); const bool vis = (key <= hi_lim) && (key >= lo_lim); st[b2][i] = vis ? st[b2][i] : -INFINITY; }
;             }
	v_add_u32_e32 v0, s12, v230
	v_cmp_gt_i32_e32 vcc, v0, v210
	v_cmp_lt_i32_e64 s[0:1], v0, v227
	s_or_b64 vcc, vcc, s[0:1]
	v_add_u32_e32 v30, 1, v0
	v_cndmask_b32_e32 v128, v128, v218, vcc
	v_cmp_gt_i32_e32 vcc, v30, v210
	v_cmp_lt_i32_e64 s[0:1], v30, v227
	s_or_b64 vcc, vcc, s[0:1]
	v_add_u32_e32 v30, 2, v0
	v_cndmask_b32_e32 v129, v129, v218, vcc
	v_cmp_gt_i32_e32 vcc, v30, v210
	v_cmp_lt_i32_e64 s[0:1], v30, v227
	s_or_b64 vcc, vcc, s[0:1]
	v_add_u32_e32 v30, 3, v0
	v_cndmask_b32_e32 v130, v130, v218, vcc
	v_cmp_gt_i32_e32 vcc, v30, v210
	v_cmp_lt_i32_e64 s[0:1], v30, v227
	s_or_b64 vcc, vcc, s[0:1]
	v_add_u32_e32 v30, 8, v0
	v_cndmask_b32_e32 v131, v131, v218, vcc
	v_cmp_gt_i32_e32 vcc, v30, v210
	v_cmp_lt_i32_e64 s[0:1], v30, v227
	s_or_b64 vcc, vcc, s[0:1]
	v_add_u32_e32 v30, 9, v0
	v_cndmask_b32_e32 v132, v132, v218, vcc
	v_cmp_gt_i32_e32 vcc, v30, v210
	v_cmp_lt_i32_e64 s[0:1], v30, v227
	s_or_b64 vcc, vcc, s[0:1]
	v_add_u32_e32 v30, 10, v0
	v_cndmask_b32_e32 v133, v133, v218, vcc
	v_cmp_gt_i32_e32 vcc, v30, v210
	v_cmp_lt_i32_e64 s[0:1], v30, v227
	s_or_b64 vcc, vcc, s[0:1]
	v_add_u32_e32 v30, 11, v0
	v_cndmask_b32_e32 v134, v134, v218, vcc
	v_cmp_gt_i32_e32 vcc, v30, v210
	v_cmp_lt_i32_e64 s[0:1], v30, v227
	s_or_b64 vcc, vcc, s[0:1]
	v_add_u32_e32 v30, 16, v0
	v_cndmask_b32_e32 v135, v135, v218, vcc
	v_cmp_gt_i32_e32 vcc, v30, v210
	v_cmp_lt_i32_e64 s[0:1], v30, v227
	s_or_b64 vcc, vcc, s[0:1]
	v_add_u32_e32 v30, 17, v0
	v_cndmask_b32_e32 v136, v136, v218, vcc
	v_cmp_gt_i32_e32 vcc, v30, v210
	v_cmp_lt_i32_e64 s[0:1], v30, v227
	s_or_b64 vcc, vcc, s[0:1]
	v_add_u32_e32 v30, 18, v0
	v_cndmask_b32_e32 v137, v137, v218, vcc
	v_cmp_gt_i32_e32 vcc, v30, v210
	v_cmp_lt_i32_e64 s[0:1], v30, v227
	s_or_b64 vcc, vcc, s[0:1]
	v_add_u32_e32 v30, 19, v0
	v_cndmask_b32_e32 v138, v138, v218, vcc
	v_cmp_gt_i32_e32 vcc, v30, v210
	v_cmp_lt_i32_e64 s[0:1], v30, v227
	s_or_b64 vcc, vcc, s[0:1]
	v_add_u32_e32 v30, 24, v0
	v_cndmask_b32_e32 v139, v139, v218, vcc
	v_cmp_gt_i32_e32 vcc, v30, v210
	v_cmp_lt_i32_e64 s[0:1], v30, v227
	s_or_b64 vcc, vcc, s[0:1]
	v_add_u32_e32 v30, 25, v0
	v_cndmask_b32_e32 v140, v140, v218, vcc
	v_cmp_gt_i32_e32 vcc, v30, v210
	v_cmp_lt_i32_e64 s[0:1], v30, v227
	s_or_b64 vcc, vcc, s[0:1]
	v_add_u32_e32 v30, 26, v0
	v_cndmask_b32_e32 v141, v141, v218, vcc
	v_cmp_gt_i32_e32 vcc, v30, v210
	v_cmp_lt_i32_e64 s[0:1], v30, v227
	s_or_b64 vcc, vcc, s[0:1]
	v_add_u32_e32 v30, 27, v0
	v_cndmask_b32_e32 v142, v142, v218, vcc
	v_cmp_gt_i32_e32 vcc, v30, v210
	v_cmp_lt_i32_e64 s[0:1], v30, v227
	s_or_b64 vcc, vcc, s[0:1]
	v_add_u32_e32 v30, 32, v0
	v_cndmask_b32_e32 v143, v143, v218, vcc
	v_cmp_gt_i32_e32 vcc, v30, v210
	v_cmp_lt_i32_e64 s[0:1], v30, v227
	s_or_b64 vcc, vcc, s[0:1]
	v_add_u32_e32 v30, 33, v0
	v_cndmask_b32_e32 v2, v2, v218, vcc
	v_cmp_gt_i32_e32 vcc, v30, v210
	v_cmp_lt_i32_e64 s[0:1], v30, v227
	s_or_b64 vcc, vcc, s[0:1]
	v_add_u32_e32 v30, 34, v0
	v_cndmask_b32_e32 v3, v3, v218, vcc
	v_cmp_gt_i32_e32 vcc, v30, v210
	v_cmp_lt_i32_e64 s[0:1], v30, v227
	s_or_b64 vcc, vcc, s[0:1]
	v_add_u32_e32 v30, 35, v0
	v_cndmask_b32_e32 v4, v4, v218, vcc
	v_cmp_gt_i32_e32 vcc, v30, v210
	v_cmp_lt_i32_e64 s[0:1], v30, v227
	s_or_b64 vcc, vcc, s[0:1]
	v_add_u32_e32 v30, 40, v0
	v_cndmask_b32_e32 v5, v5, v218, vcc
	v_cmp_gt_i32_e32 vcc, v30, v210
	v_cmp_lt_i32_e64 s[0:1], v30, v227
	s_or_b64 vcc, vcc, s[0:1]
	v_add_u32_e32 v30, 41, v0
	v_cndmask_b32_e32 v6, v6, v218, vcc
	v_cmp_gt_i32_e32 vcc, v30, v210
	v_cmp_lt_i32_e64 s[0:1], v30, v227
	s_or_b64 vcc, vcc, s[0:1]
	v_add_u32_e32 v30, 42, v0
	v_cndmask_b32_e32 v7, v7, v218, vcc
	v_cmp_gt_i32_e32 vcc, v30, v210
	v_cmp_lt_i32_e64 s[0:1], v30, v227
	s_or_b64 vcc, vcc, s[0:1]
	v_add_u32_e32 v30, 43, v0
	v_cndmask_b32_e32 v8, v8, v218, vcc
	v_cmp_gt_i32_e32 vcc, v30, v210
	v_cmp_lt_i32_e64 s[0:1], v30, v227
	s_or_b64 vcc, vcc, s[0:1]
	v_add_u32_e32 v30, 48, v0
	v_cndmask_b32_e32 v9, v9, v218, vcc
	v_cmp_gt_i32_e32 vcc, v30, v210
	v_cmp_lt_i32_e64 s[0:1], v30, v227
	s_or_b64 vcc, vcc, s[0:1]
	v_add_u32_e32 v30, 49, v0
	v_cndmask_b32_e32 v10, v10, v218, vcc
	v_cmp_gt_i32_e32 vcc, v30, v210
	v_cmp_lt_i32_e64 s[0:1], v30, v227
	s_or_b64 vcc, vcc, s[0:1]
	v_add_u32_e32 v30, 50, v0
	v_cndmask_b32_e32 v11, v11, v218, vcc
	v_cmp_gt_i32_e32 vcc, v30, v210
	v_cmp_lt_i32_e64 s[0:1], v30, v227
	s_or_b64 vcc, vcc, s[0:1]
	v_add_u32_e32 v30, 51, v0
	v_cndmask_b32_e32 v12, v12, v218, vcc
	v_cmp_gt_i32_e32 vcc, v30, v210
	v_cmp_lt_i32_e64 s[0:1], v30, v227
	s_or_b64 vcc, vcc, s[0:1]
	v_add_u32_e32 v30, 56, v0
	v_cndmask_b32_e32 v13, v13, v218, vcc
	v_cmp_gt_i32_e32 vcc, v30, v210
	v_cmp_lt_i32_e64 s[0:1], v30, v227
	s_or_b64 vcc, vcc, s[0:1]
	v_add_u32_e32 v30, 57, v0
	v_cndmask_b32_e32 v14, v14, v218, vcc
	v_cmp_gt_i32_e32 vcc, v30, v210
	v_cmp_lt_i32_e64 s[0:1], v30, v227
	s_or_b64 vcc, vcc, s[0:1]
	v_add_u32_e32 v30, 58, v0
	v_cndmask_b32_e32 v15, v15, v218, vcc
	v_cmp_gt_i32_e32 vcc, v30, v210
	v_cmp_lt_i32_e64 s[0:1], v30, v227
	s_or_b64 vcc, vcc, s[0:1]
	v_add_u32_e32 v0, 59, v0
	v_cndmask_b32_e32 v16, v16, v218, vcc
	v_cmp_gt_i32_e32 vcc, v0, v210
	v_cmp_lt_i32_e64 s[0:1], v0, v227
	s_or_b64 vcc, vcc, s[0:1]
	v_cndmask_b32_e32 v17, v17, v218, vcc

; template <int DQK> DEV void qk_tile(f32x16 (&st)[2], const LAS unsigned char* kb, const bf16x8 (&qf)[DQK / 16], int r, int h) {
;     constexpr int KSTR = DQK * 2 + 16, NS = DQK / 16;
;     bf16x8 kf[2][NS];
; #pragma unroll
;     for (int b2 = 0; b2 < 2; ++b2)
; #pragma unroll
;         for (int s = 0; s < NS; ++s) kf[b2][s] = *(const LAS bf16x8*)(kb + (32 * b2 + r) * KSTR + 32 * s + 16 * h);
;     __builtin_amdgcn_sched_barrier(0);
; #pragma unroll
;     for (int b2 = 0; b2 < 2; ++b2) {
;         f32x16 a;
; #pragma unroll
;         for (int i = 0; i < 16; ++i) a[i] = 0.f;
; #pragma unroll
;         for (int s = 0; s < NS; ++s) a = MFMA32(kf[b2][s], qf[s], a);
;         st[b2] = a;
;     }
;     __builtin_amdgcn_sched_barrier(0);
; }
; DEV void pack_p(bf16x8 (&pf)[4], const f32x16 (&st)[2]) {
; #pragma unroll
;     for (int b2 = 0; b2 < 2; ++b2)
; #pragma unroll
;         for (int s = 0; s < 2; ++s) { u32x4 p; p.x = pk2(st[b2][8 * s], st[b2][8 * s + 1]); p.y = pk2(st[b2][8 * s + 2], st[b2][8 * s + 3]);
;             p.z = pk2(st[b2][8 * s + 4], st[b2][8 * s + 5]); p.w = pk2(st[b2][8 * s + 6], st[b2][8 * s + 7]); pf[2 * b2 + s] = __builtin_bit_cast(bf16x8, p); }
; }
; DEV void pv_load(bf16x8 (&vf)[2][4], const LAS unsigned char* vb, int r, int h) {
; #pragma unroll
;     for (int db = 0; db < 2; ++db)
; #pragma unroll
;         for (int f = 0; f < 4; ++f) { const LAS unsigned char* p = vb + (32 * db + r) * 136 + (16 * f + 4 * h) * 2;
; template <int DQK, int MODE> ...
;     ...
;     auto compute = [&](const int t, const int slot) __attribute__((always_inline)) {
;         LAS unsigned char* kb = lds + AL_K0 + slot * AL_KSTR; LAS unsigned char* vb = lds + AL_V0 + slot * AL_VSTR;
;         const int k0 = 64 * t;
;         bool rowsel = true;
;         if (MODE == 1) rowsel = (selm.x >> (t >> 2)) & 1u;
;         if (MODE == 2) { const int tw = t >> 5; const unsigned w = tw == 0 ? selm.x : (tw == 1 ? selm.y : (tw == 2 ? selm.z : selm.w)); rowsel = (w >> (t & 31)) & 1u; }
;         const bool rowact = rowsel && (k0 <= hi_lim) && (k0 + 63 >= lo_lim);
;         if (__any(rowact ? 1 : 0)) {
;             f32x16 st[2];
;             qk_tile<DQK>(st, kb, qf, r, h);
;             bf16x8 vf[2][4];
;             if (MODE != 3) pv_load(vf, vb, r, h);
;             const bool interior = __all(((k0 + 63 <= hi_lim) && (k0 >= lo_lim)) ? 1 : 0);
.LBB0_2843:
	v_lshrrev_b32_e32 v0, s33, v0
	s_lshl_b32 s6, s33, 6
	v_and_b32_e32 v0, 1, v0
	v_cmp_eq_u32_e64 s[0:1], 1, v0
	v_cmp_le_i32_e32 vcc, s6, v210
	s_and_b64 s[12:13], s[0:1], vcc
	v_cndmask_b32_e64 v0, 0, 1, s[12:13]
	v_cmp_ne_u32_e32 vcc, 0, v0
	s_cbranch_vccz .LBB0_2851
	s_mul_i32 s7, s54, 0x9c00
	v_add_u32_e32 v0, s7, v183
	ds_read_b128 v[2:5], v0
	ds_read_b128 v[6:9], v0 offset:32
	ds_read_b128 v[10:13], v0 offset:64
	ds_read_b128 v[14:17], v0 offset:96
	ds_read_b128 v[18:21], v0 offset:4608
	ds_read_b128 v[22:25], v0 offset:4640
	ds_read_b128 v[26:29], v0 offset:4672
	ds_read_b128 v[140:143], v0 offset:4704
	s_mul_i32 s7, s54, 0x6600
	s_setprio 1
	s_waitcnt lgkmcnt(7)
	v_mfma_f32_32x32x16_bf16 v[96:111], v[2:5], v[144:147], 0
	s_waitcnt lgkmcnt(6)
	v_mfma_f32_32x32x16_bf16 v[96:111], v[6:9], v[152:155], v[96:111]
	s_waitcnt lgkmcnt(5)
	v_mfma_f32_32x32x16_bf16 v[96:111], v[10:13], v[148:151], v[96:111]
	s_waitcnt lgkmcnt(4)
	v_mfma_f32_32x32x16_bf16 v[96:111], v[14:17], v[156:159], v[96:111]
	s_waitcnt lgkmcnt(3)
	v_mfma_f32_32x32x16_bf16 v[2:17], v[18:21], v[144:147], 0
	s_waitcnt lgkmcnt(2)
	v_mfma_f32_32x32x16_bf16 v[2:17], v[22:25], v[152:155], v[2:17]
	s_waitcnt lgkmcnt(1)
	v_mfma_f32_32x32x16_bf16 v[2:17], v[26:29], v[148:151], v[2:17]
	s_waitcnt lgkmcnt(0)
	v_mfma_f32_32x32x16_bf16 v[2:17], v[140:143], v[156:159], v[2:17]
	s_setprio 0
	v_add_u32_e32 v0, s7, v187
	ds_read2_b64 v[172:175], v0 offset1:2
	ds_read2_b64 v[26:29], v0 offset0:4 offset1:6
	ds_read2_b64 v[22:25], v0 offset0:8 offset1:10
	ds_read2_b64 v[18:21], v0 offset0:12 offset1:14
	v_add_u32_e32 v0, 0x1000, v0
	ds_read2_b64 v[168:171], v0 offset0:32 offset1:34
	ds_read2_b64 v[164:167], v0 offset0:36 offset1:38
	ds_read2_b64 v[160:163], v0 offset0:40 offset1:42
	ds_read2_b64 v[140:143], v0 offset0:44 offset1:46
	s_or_b32 s7, s6, 63
	v_cmp_le_i32_e32 vcc, s7, v210
	s_cmp_eq_u64 vcc, exec
	s_cbranch_scc1 .LBB0_2846
; DEV int crow(int i, int h) { return (i & 3) + 8 * (i >> 2) + 4 * h; }
; template <int DQK, int MODE> ...
;     ...
;             if (!interior) {
; #pragma unroll
;                 for (int b2 = 0; b2 < 2; ++b2)
; #pragma unroll
;                     for (int i = 0; i < 16; ++i) { const int key = k0 + 32 * b2 + crow(i, h); const bool vis = (key <= hi_lim) && (key >= lo_lim); st[b2][i] = vis ? st[b2][i] : -INFINITY; }
;             }
	v_add_u32_e32 v0, s6, v188
	v_cmp_gt_i32_e32 vcc, v0, v210
	v_cmp_gt_i32_e64 s[6:7], -2.0, v0
	s_or_b64 vcc, vcc, s[6:7]
	v_add_u32_e32 v30, 1, v0
	v_cndmask_b32_e32 v96, v96, v218, vcc
	v_cmp_gt_i32_e32 vcc, v30, v210
	v_cmp_gt_i32_e64 s[6:7], -2.0, v30
	s_or_b64 vcc, vcc, s[6:7]
	v_add_u32_e32 v30, 2, v0
	v_cndmask_b32_e32 v97, v97, v218, vcc
	v_cmp_gt_i32_e32 vcc, v30, v210
	v_cmp_gt_i32_e64 s[6:7], -2.0, v30
	s_or_b64 vcc, vcc, s[6:7]
	v_add_u32_e32 v30, 3, v0
	v_cndmask_b32_e32 v98, v98, v218, vcc
	v_cmp_gt_i32_e32 vcc, v30, v210
	v_cmp_gt_i32_e64 s[6:7], -2.0, v30
	s_or_b64 vcc, vcc, s[6:7]
	v_add_u32_e32 v30, 8, v0
	v_cndmask_b32_e32 v99, v99, v218, vcc
	v_cmp_gt_i32_e32 vcc, v30, v210
	v_cmp_gt_i32_e64 s[6:7], -2.0, v30
	s_or_b64 vcc, vcc, s[6:7]
	v_add_u32_e32 v30, 9, v0
	v_cndmask_b32_e32 v100, v100, v218, vcc
	v_cmp_gt_i32_e32 vcc, v30, v210
	v_cmp_gt_i32_e64 s[6:7], -2.0, v30
	s_or_b64 vcc, vcc, s[6:7]
	v_add_u32_e32 v30, 10, v0
	v_cndmask_b32_e32 v101, v101, v218, vcc
	v_cmp_gt_i32_e32 vcc, v30, v210
	v_cmp_gt_i32_e64 s[6:7], -2.0, v30
	s_or_b64 vcc, vcc, s[6:7]
	v_add_u32_e32 v30, 11, v0
	v_cndmask_b32_e32 v102, v102, v218, vcc
	v_cmp_gt_i32_e32 vcc, v30, v210
	v_cmp_gt_i32_e64 s[6:7], -2.0, v30
	s_or_b64 vcc, vcc, s[6:7]
	v_add_u32_e32 v30, 16, v0
	v_cndmask_b32_e32 v103, v103, v218, vcc
	v_cmp_gt_i32_e32 vcc, v30, v210
	v_cmp_gt_i32_e64 s[6:7], -2.0, v30
	s_or_b64 vcc, vcc, s[6:7]
	v_add_u32_e32 v30, 17, v0
	v_cndmask_b32_e32 v104, v104, v218, vcc
	v_cmp_gt_i32_e32 vcc, v30, v210
	v_cmp_gt_i32_e64 s[6:7], -2.0, v30
	s_or_b64 vcc, vcc, s[6:7]
	v_add_u32_e32 v30, 18, v0
	v_cndmask_b32_e32 v105, v105, v218, vcc
	v_cmp_gt_i32_e32 vcc, v30, v210
	v_cmp_gt_i32_e64 s[6:7], -2.0, v30
	s_or_b64 vcc, vcc, s[6:7]
	v_add_u32_e32 v30, 19, v0
	v_cndmask_b32_e32 v106, v106, v218, vcc
	v_cmp_gt_i32_e32 vcc, v30, v210
	v_cmp_gt_i32_e64 s[6:7], -2.0, v30
	s_or_b64 vcc, vcc, s[6:7]
	v_add_u32_e32 v30, 24, v0
	v_cndmask_b32_e32 v107, v107, v218, vcc
	v_cmp_gt_i32_e32 vcc, v30, v210
	v_cmp_gt_i32_e64 s[6:7], -2.0, v30
	s_or_b64 vcc, vcc, s[6:7]
	v_add_u32_e32 v30, 25, v0
	v_cndmask_b32_e32 v108, v108, v218, vcc
	v_cmp_gt_i32_e32 vcc, v30, v210
	v_cmp_gt_i32_e64 s[6:7], -2.0, v30
	s_or_b64 vcc, vcc, s[6:7]
	v_add_u32_e32 v30, 26, v0
	v_cndmask_b32_e32 v109, v109, v218, vcc
	v_cmp_gt_i32_e32 vcc, v30, v210
	v_cmp_gt_i32_e64 s[6:7], -2.0, v30
	s_or_b64 vcc, vcc, s[6:7]
	v_add_u32_e32 v30, 27, v0
	v_cndmask_b32_e32 v110, v110, v218, vcc
	v_cmp_gt_i32_e32 vcc, v30, v210
	v_cmp_gt_i32_e64 s[6:7], -2.0, v30
	s_or_b64 vcc, vcc, s[6:7]
	v_add_u32_e32 v30, 32, v0
	v_cndmask_b32_e32 v111, v111, v218, vcc
	v_cmp_gt_i32_e32 vcc, v30, v210
	v_cmp_gt_i32_e64 s[6:7], -2.0, v30
	s_or_b64 vcc, vcc, s[6:7]
	v_add_u32_e32 v30, 33, v0
	v_cndmask_b32_e32 v2, v2, v218, vcc
	v_cmp_gt_i32_e32 vcc, v30, v210
	v_cmp_gt_i32_e64 s[6:7], -2.0, v30
	s_or_b64 vcc, vcc, s[6:7]
	v_add_u32_e32 v30, 34, v0
	v_cndmask_b32_e32 v3, v3, v218, vcc
	v_cmp_gt_i32_e32 vcc, v30, v210
	v_cmp_gt_i32_e64 s[6:7], -2.0, v30
	s_or_b64 vcc, vcc, s[6:7]
	v_add_u32_e32 v30, 35, v0
	v_cndmask_b32_e32 v4, v4, v218, vcc
	v_cmp_gt_i32_e32 vcc, v30, v210
	v_cmp_gt_i32_e64 s[6:7], -2.0, v30
	s_or_b64 vcc, vcc, s[6:7]
	v_add_u32_e32 v30, 40, v0
	v_cndmask_b32_e32 v5, v5, v218, vcc
	v_cmp_gt_i32_e32 vcc, v30, v210
	v_cmp_gt_i32_e64 s[6:7], -2.0, v30
	s_or_b64 vcc, vcc, s[6:7]
	v_add_u32_e32 v30, 41, v0
	v_cndmask_b32_e32 v6, v6, v218, vcc
	v_cmp_gt_i32_e32 vcc, v30, v210
	v_cmp_gt_i32_e64 s[6:7], -2.0, v30
	s_or_b64 vcc, vcc, s[6:7]
	v_add_u32_e32 v30, 42, v0
	v_cndmask_b32_e32 v7, v7, v218, vcc
	v_cmp_gt_i32_e32 vcc, v30, v210
	v_cmp_gt_i32_e64 s[6:7], -2.0, v30
	s_or_b64 vcc, vcc, s[6:7]
	v_add_u32_e32 v30, 43, v0
	v_cndmask_b32_e32 v8, v8, v218, vcc
	v_cmp_gt_i32_e32 vcc, v30, v210
	v_cmp_gt_i32_e64 s[6:7], -2.0, v30
	s_or_b64 vcc, vcc, s[6:7]
	v_add_u32_e32 v30, 48, v0
	v_cndmask_b32_e32 v9, v9, v218, vcc
	v_cmp_gt_i32_e32 vcc, v30, v210
	v_cmp_gt_i32_e64 s[6:7], -2.0, v30
	s_or_b64 vcc, vcc, s[6:7]
	v_add_u32_e32 v30, 49, v0
	v_cndmask_b32_e32 v10, v10, v218, vcc
	v_cmp_gt_i32_e32 vcc, v30, v210
	v_cmp_gt_i32_e64 s[6:7], -2.0, v30
	s_or_b64 vcc, vcc, s[6:7]
	v_add_u32_e32 v30, 50, v0
	v_cndmask_b32_e32 v11, v11, v218, vcc
	v_cmp_gt_i32_e32 vcc, v30, v210
	v_cmp_gt_i32_e64 s[6:7], -2.0, v30
	s_or_b64 vcc, vcc, s[6:7]
	v_add_u32_e32 v30, 51, v0
	v_cndmask_b32_e32 v12, v12, v218, vcc
	v_cmp_gt_i32_e32 vcc, v30, v210
	v_cmp_gt_i32_e64 s[6:7], -2.0, v30
	s_or_b64 vcc, vcc, s[6:7]
	v_add_u32_e32 v30, 56, v0
	v_cndmask_b32_e32 v13, v13, v218, vcc
	v_cmp_gt_i32_e32 vcc, v30, v210
	v_cmp_gt_i32_e64 s[6:7], -2.0, v30
	s_or_b64 vcc, vcc, s[6:7]
	v_add_u32_e32 v30, 57, v0
	v_cndmask_b32_e32 v14, v14, v218, vcc
	v_cmp_gt_i32_e32 vcc, v30, v210
	v_cmp_gt_i32_e64 s[6:7], -2.0, v30
	s_or_b64 vcc, vcc, s[6:7]
	v_add_u32_e32 v30, 58, v0
	v_cndmask_b32_e32 v15, v15, v218, vcc
	v_cmp_gt_i32_e32 vcc, v30, v210
	v_cmp_gt_i32_e64 s[6:7], -2.0, v30
	s_or_b64 vcc, vcc, s[6:7]
	v_add_u32_e32 v0, 59, v0
	v_cndmask_b32_e32 v16, v16, v218, vcc
	v_cmp_gt_i32_e32 vcc, v0, v210
	v_cmp_gt_i32_e64 s[6:7], -2.0, v0
	s_or_b64 vcc, vcc, s[6:7]
	v_cndmask_b32_e32 v17, v17, v218, vcc

; #define LAS __attribute__((address_space(3)))
; #define MFMA32(a, b, c) __builtin_amdgcn_mfma_f32_32x32x16_bf16((a), (b), (c), 0, 0, 0)
; DEV unsigned pk2(float lo, float hi) { f32x2_ v; v.x = lo; v.y = hi; return __builtin_bit_cast(unsigned, __builtin_convertvector(v, bf16x2_)); }
; DEV float fexp2(float x) { return __builtin_amdgcn_exp2f(x); }
; DEV void pack_p(bf16x8 (&pf)[4], const f32x16 (&st)[2]) {
; #pragma unroll
;     for (int b2 = 0; b2 < 2; ++b2)
; #pragma unroll
;         for (int s = 0; s < 2; ++s) { u32x4 p; p.x = pk2(st[b2][8 * s], st[b2][8 * s + 1]); p.y = pk2(st[b2][8 * s + 2], st[b2][8 * s + 3]);
;             p.z = pk2(st[b2][8 * s + 4], st[b2][8 * s + 5]); p.w = pk2(st[b2][8 * s + 6], st[b2][8 * s + 7]); pf[2 * b2 + s] = __builtin_bit_cast(bf16x8, p); }
; }
; DEV void pv_load(bf16x8 (&vf)[2][4], const LAS unsigned char* vb, int r, int h) {
; #pragma unroll
;     for (int db = 0; db < 2; ++db)
; #pragma unroll
;         for (int f = 0; f < 4; ++f) { const LAS unsigned char* p = vb + (32 * db + r) * 136 + (16 * f + 4 * h) * 2;
;             const s16x4 lo = *(const LAS s16x4*)p, hi = *(const LAS s16x4*)(p + 16);
;             vf[db][f] = __builtin_shufflevector(lo, hi, 0, 1, 2, 3, 4, 5, 6, 7); }
;     __builtin_amdgcn_sched_barrier(0);
; }
; DEV void pv_mma(f32x16 (&o)[2], const bf16x8 (&vf)[2][4], const bf16x8 (&pf)[4]) {
;     __builtin_amdgcn_sched_barrier(0);
; #pragma unroll
;     for (int f = 0; f < 4; ++f)
; #pragma unroll
;         for (int db = 0; db < 2; ++db) o[db] = MFMA32(vf[db][f], pf[f], o[db]);
;     __builtin_amdgcn_sched_barrier(0);
; }
; template <int DQK, int MODE> ...
;     ...
;                 const float cb = rowsel ? -m_new : -INFINITY;
;                 float ps = 0.f;
; #pragma unroll
;                 for (int b2 = 0; b2 < 2; ++b2)
; #pragma unroll
;                     for (int i = 0; i < 16; ++i) { const float p = fexp2(__builtin_fmaf(st[b2][i], sc, cb)); st[b2][i] = p; ps += p; }
;                 l_run += ps;
;                 bf16x8 pf[4]; pack_p(pf, st);
;                 pv_mma(o, vf, pf);
.LBB0_2850:
	v_cndmask_b32_e64 v0, v218, -v0, s[0:1]
	v_fmamk_f32 v30, v96, 0x3e38aa3b, v0
	v_exp_f32_e32 v96, v30
	v_fmamk_f32 v31, v97, 0x3e38aa3b, v0
	v_exp_f32_e32 v97, v31
	v_fmamk_f32 v30, v98, 0x3e38aa3b, v0
	v_add_f32_e32 v191, 0, v96
	v_exp_f32_e32 v98, v30
	v_fmamk_f32 v31, v99, 0x3e38aa3b, v0
	v_add_f32_e32 v191, v97, v191
	v_exp_f32_e32 v99, v31
	v_fmamk_f32 v30, v100, 0x3e38aa3b, v0
	v_add_f32_e32 v191, v98, v191
	v_exp_f32_e32 v100, v30
	v_fmamk_f32 v31, v101, 0x3e38aa3b, v0
	v_add_f32_e32 v191, v99, v191
	v_exp_f32_e32 v101, v31
	v_fmamk_f32 v30, v102, 0x3e38aa3b, v0
	v_add_f32_e32 v191, v100, v191
	v_exp_f32_e32 v102, v30
	v_fmamk_f32 v31, v103, 0x3e38aa3b, v0
	v_add_f32_e32 v191, v101, v191
	v_exp_f32_e32 v103, v31
	v_add_f32_e32 v191, v102, v191
	v_add_f32_e32 v191, v103, v191
	v_cvt_pk_bf16_f32 v96, v96, v97
	v_cvt_pk_bf16_f32 v97, v98, v99
	v_cvt_pk_bf16_f32 v98, v100, v101
	v_cvt_pk_bf16_f32 v99, v102, v103
	v_fmamk_f32 v30, v104, 0x3e38aa3b, v0
	v_exp_f32_e32 v104, v30
	v_fmamk_f32 v31, v105, 0x3e38aa3b, v0
	v_exp_f32_e32 v105, v31
	v_mfma_f32_32x32x16_bf16 v[64:79], v[172:175], v[96:99], v[64:79]
	v_mfma_f32_32x32x16_bf16 v[80:95], v[168:171], v[96:99], v[80:95]
	v_fmamk_f32 v30, v106, 0x3e38aa3b, v0
	v_add_f32_e32 v191, v104, v191
	v_exp_f32_e32 v106, v30
	v_fmamk_f32 v31, v107, 0x3e38aa3b, v0
	v_add_f32_e32 v191, v105, v191
	v_exp_f32_e32 v107, v31
	v_fmamk_f32 v30, v108, 0x3e38aa3b, v0
	v_add_f32_e32 v191, v106, v191
	v_exp_f32_e32 v108, v30
	v_fmamk_f32 v31, v109, 0x3e38aa3b, v0
	v_add_f32_e32 v191, v107, v191
	v_exp_f32_e32 v109, v31
	v_fmamk_f32 v30, v110, 0x3e38aa3b, v0
	v_add_f32_e32 v191, v108, v191
	v_exp_f32_e32 v110, v30
	v_fmamk_f32 v31, v111, 0x3e38aa3b, v0
	v_add_f32_e32 v191, v109, v191
	v_exp_f32_e32 v111, v31
	v_add_f32_e32 v191, v110, v191
	v_add_f32_e32 v191, v111, v191
	v_cvt_pk_bf16_f32 v104, v104, v105
	v_cvt_pk_bf16_f32 v105, v106, v107
	v_cvt_pk_bf16_f32 v106, v108, v109
	v_cvt_pk_bf16_f32 v107, v110, v111
	v_fmamk_f32 v30, v2, 0x3e38aa3b, v0
	v_exp_f32_e32 v2, v30
	v_fmamk_f32 v31, v3, 0x3e38aa3b, v0
	v_exp_f32_e32 v3, v31
	v_mfma_f32_32x32x16_bf16 v[64:79], v[26:29], v[104:107], v[64:79]
	v_mfma_f32_32x32x16_bf16 v[80:95], v[164:167], v[104:107], v[80:95]
	v_fmamk_f32 v30, v4, 0x3e38aa3b, v0
	v_add_f32_e32 v191, v2, v191
	v_exp_f32_e32 v4, v30
	v_fmamk_f32 v31, v5, 0x3e38aa3b, v0
	v_add_f32_e32 v191, v3, v191
	v_exp_f32_e32 v5, v31
	v_fmamk_f32 v30, v6, 0x3e38aa3b, v0
	v_add_f32_e32 v191, v4, v191
	v_exp_f32_e32 v6, v30
	v_fmamk_f32 v31, v7, 0x3e38aa3b, v0
	v_add_f32_e32 v191, v5, v191
	v_exp_f32_e32 v7, v31
	v_fmamk_f32 v30, v8, 0x3e38aa3b, v0
	v_add_f32_e32 v191, v6, v191
	v_exp_f32_e32 v8, v30
	v_fmamk_f32 v31, v9, 0x3e38aa3b, v0
	v_add_f32_e32 v191, v7, v191
	v_exp_f32_e32 v9, v31
	v_add_f32_e32 v191, v8, v191
	v_add_f32_e32 v191, v9, v191
	v_cvt_pk_bf16_f32 v2, v2, v3
	v_cvt_pk_bf16_f32 v3, v4, v5
	v_cvt_pk_bf16_f32 v4, v6, v7
	v_cvt_pk_bf16_f32 v5, v8, v9
	v_fmamk_f32 v30, v10, 0x3e38aa3b, v0
	v_exp_f32_e32 v10, v30
	v_fmamk_f32 v31, v11, 0x3e38aa3b, v0
	v_exp_f32_e32 v11, v31
	v_mfma_f32_32x32x16_bf16 v[64:79], v[22:25], v[2:5], v[64:79]
	v_mfma_f32_32x32x16_bf16 v[80:95], v[160:163], v[2:5], v[80:95]
	v_fmamk_f32 v30, v12, 0x3e38aa3b, v0
	v_add_f32_e32 v191, v10, v191
	v_exp_f32_e32 v12, v30
	v_fmamk_f32 v31, v13, 0x3e38aa3b, v0
	v_add_f32_e32 v191, v11, v191
	v_exp_f32_e32 v13, v31
	v_fmamk_f32 v30, v14, 0x3e38aa3b, v0
	v_add_f32_e32 v191, v12, v191
	v_exp_f32_e32 v14, v30
	v_fmamk_f32 v31, v15, 0x3e38aa3b, v0
	v_add_f32_e32 v191, v13, v191
	v_exp_f32_e32 v15, v31
	v_fmamk_f32 v30, v16, 0x3e38aa3b, v0
	v_add_f32_e32 v191, v14, v191
	v_exp_f32_e32 v16, v30
	v_fmamk_f32 v31, v17, 0x3e38aa3b, v0
	v_add_f32_e32 v191, v15, v191
	v_exp_f32_e32 v17, v31
	v_add_f32_e32 v191, v16, v191
	v_add_f32_e32 v191, v17, v191
	v_cvt_pk_bf16_f32 v10, v10, v11
	v_cvt_pk_bf16_f32 v11, v12, v13
	v_cvt_pk_bf16_f32 v12, v14, v15
	v_cvt_pk_bf16_f32 v13, v16, v17
	v_add_f32_e32 v223, v191, v223
	s_nop 0
	v_mfma_f32_32x32x16_bf16 v[64:79], v[18:21], v[10:13], v[64:79]
	v_mfma_f32_32x32x16_bf16 v[80:95], v[140:143], v[10:13], v[80:95]

; template <int DQK> DEV void qk_tile(f32x16 (&st)[2], const LAS unsigned char* kb, const bf16x8 (&qf)[DQK / 16], int r, int h) {
;     constexpr int KSTR = DQK * 2 + 16, NS = DQK / 16;
;     bf16x8 kf[2][NS];
; #pragma unroll
;     for (int b2 = 0; b2 < 2; ++b2)
; #pragma unroll
;         for (int s = 0; s < NS; ++s) kf[b2][s] = *(const LAS bf16x8*)(kb + (32 * b2 + r) * KSTR + 32 * s + 16 * h);
;     __builtin_amdgcn_sched_barrier(0);
; #pragma unroll
;     for (int b2 = 0; b2 < 2; ++b2) {
;         f32x16 a;
; #pragma unroll
;         for (int i = 0; i < 16; ++i) a[i] = 0.f;
; #pragma unroll
;         for (int s = 0; s < NS; ++s) a = MFMA32(kf[b2][s], qf[s], a);
;         st[b2] = a;
;     }
;     __builtin_amdgcn_sched_barrier(0);
; }
; DEV void pack_p(bf16x8 (&pf)[4], const f32x16 (&st)[2]) {
; #pragma unroll
;     for (int b2 = 0; b2 < 2; ++b2)
; #pragma unroll
;         for (int s = 0; s < 2; ++s) { u32x4 p; p.x = pk2(st[b2][8 * s], st[b2][8 * s + 1]); p.y = pk2(st[b2][8 * s + 2], st[b2][8 * s + 3]);
;             p.z = pk2(st[b2][8 * s + 4], st[b2][8 * s + 5]); p.w = pk2(st[b2][8 * s + 6], st[b2][8 * s + 7]); pf[2 * b2 + s] = __builtin_bit_cast(bf16x8, p); }
; }
; DEV void pv_load(bf16x8 (&vf)[2][4], const LAS unsigned char* vb, int r, int h) {
; #pragma unroll
;     for (int db = 0; db < 2; ++db)
; #pragma unroll
;         for (int f = 0; f < 4; ++f) { const LAS unsigned char* p = vb + (32 * db + r) * 136 + (16 * f + 4 * h) * 2;
; template <int DQK, int MODE> ...
;     ...
;     auto compute = [&](const int t, const int slot) __attribute__((always_inline)) {
;         LAS unsigned char* kb = lds + AL_K0 + slot * AL_KSTR; LAS unsigned char* vb = lds + AL_V0 + slot * AL_VSTR;
;         const int k0 = 64 * t;
;         bool rowsel = true;
;         if (MODE == 1) rowsel = (selm.x >> (t >> 2)) & 1u;
;         if (MODE == 2) { const int tw = t >> 5; const unsigned w = tw == 0 ? selm.x : (tw == 1 ? selm.y : (tw == 2 ? selm.z : selm.w)); rowsel = (w >> (t & 31)) & 1u; }
;         const bool rowact = rowsel && (k0 <= hi_lim) && (k0 + 63 >= lo_lim);
;         if (__any(rowact ? 1 : 0)) {
;             f32x16 st[2];
;             qk_tile<DQK>(st, kb, qf, r, h);
;             bf16x8 vf[2][4];
;             if (MODE != 3) pv_load(vf, vb, r, h);
;             const bool interior = __all(((k0 + 63 <= hi_lim) && (k0 >= lo_lim)) ? 1 : 0);
.LBB0_2858:
	v_lshrrev_b32_e32 v0, s7, v0
	s_lshl_b32 s6, s7, 6
	v_and_b32_e32 v0, 1, v0
	v_cmp_eq_u32_e64 s[0:1], 1, v0
	v_cmp_le_i32_e32 vcc, s6, v210
	s_and_b64 s[12:13], s[0:1], vcc
	v_cndmask_b32_e64 v0, 0, 1, s[12:13]
	v_cmp_ne_u32_e32 vcc, 0, v0
	s_cbranch_vccz .LBB0_2866
	s_add_i32 s7, s24, 1
	s_mul_i32 s12, s7, 0x3400
	v_add_u32_e32 v0, s12, v183
	ds_read_b128 v[2:5], v0
	ds_read_b128 v[6:9], v0 offset:32
	ds_read_b128 v[10:13], v0 offset:64
	ds_read_b128 v[14:17], v0 offset:96
	ds_read_b128 v[18:21], v0 offset:4608
	ds_read_b128 v[22:25], v0 offset:4640
	ds_read_b128 v[26:29], v0 offset:4672
	ds_read_b128 v[140:143], v0 offset:4704
	s_mulk_i32 s7, 0x2200
	s_setprio 1
	s_waitcnt lgkmcnt(7)
	v_mfma_f32_32x32x16_bf16 v[96:111], v[2:5], v[144:147], 0
	s_waitcnt lgkmcnt(6)
	v_mfma_f32_32x32x16_bf16 v[96:111], v[6:9], v[152:155], v[96:111]
	s_waitcnt lgkmcnt(5)
	v_mfma_f32_32x32x16_bf16 v[96:111], v[10:13], v[148:151], v[96:111]
	s_waitcnt lgkmcnt(4)
	v_mfma_f32_32x32x16_bf16 v[96:111], v[14:17], v[156:159], v[96:111]
	s_waitcnt lgkmcnt(3)
	v_mfma_f32_32x32x16_bf16 v[2:17], v[18:21], v[144:147], 0
	s_waitcnt lgkmcnt(2)
	v_mfma_f32_32x32x16_bf16 v[2:17], v[22:25], v[152:155], v[2:17]
	s_waitcnt lgkmcnt(1)
	v_mfma_f32_32x32x16_bf16 v[2:17], v[26:29], v[148:151], v[2:17]
	s_waitcnt lgkmcnt(0)
	v_mfma_f32_32x32x16_bf16 v[2:17], v[140:143], v[156:159], v[2:17]
	s_setprio 0
	v_add_u32_e32 v0, s7, v187
	ds_read2_b64 v[172:175], v0 offset1:2
	ds_read2_b64 v[26:29], v0 offset0:4 offset1:6
	ds_read2_b64 v[22:25], v0 offset0:8 offset1:10
	ds_read2_b64 v[18:21], v0 offset0:12 offset1:14
	v_add_u32_e32 v0, 0x1000, v0
	ds_read2_b64 v[168:171], v0 offset0:32 offset1:34
	ds_read2_b64 v[164:167], v0 offset0:36 offset1:38
	ds_read2_b64 v[160:163], v0 offset0:40 offset1:42
	ds_read2_b64 v[140:143], v0 offset0:44 offset1:46
	s_or_b32 s7, s6, 63
	v_cmp_le_i32_e32 vcc, s7, v210
	s_cmp_eq_u64 vcc, exec
	s_cbranch_scc1 .LBB0_2861
; DEV int crow(int i, int h) { return (i & 3) + 8 * (i >> 2) + 4 * h; }
; template <int DQK, int MODE> ...
;     ...
;             if (!interior) {
; #pragma unroll
;                 for (int b2 = 0; b2 < 2; ++b2)
; #pragma unroll
;                     for (int i = 0; i < 16; ++i) { const int key = k0 + 32 * b2 + crow(i, h); const bool vis = (key <= hi_lim) && (key >= lo_lim); st[b2][i] = vis ? st[b2][i] : -INFINITY; }
;             }
	v_add_u32_e32 v0, s6, v188
	v_cmp_gt_i32_e32 vcc, v0, v210
	v_cmp_gt_i32_e64 s[6:7], -2.0, v0
	s_or_b64 vcc, vcc, s[6:7]
	v_add_u32_e32 v30, 1, v0
	v_cndmask_b32_e32 v96, v96, v218, vcc
	v_cmp_gt_i32_e32 vcc, v30, v210
	v_cmp_gt_i32_e64 s[6:7], -2.0, v30
	s_or_b64 vcc, vcc, s[6:7]
	v_add_u32_e32 v30, 2, v0
	v_cndmask_b32_e32 v97, v97, v218, vcc
	v_cmp_gt_i32_e32 vcc, v30, v210
	v_cmp_gt_i32_e64 s[6:7], -2.0, v30
	s_or_b64 vcc, vcc, s[6:7]
	v_add_u32_e32 v30, 3, v0
	v_cndmask_b32_e32 v98, v98, v218, vcc
	v_cmp_gt_i32_e32 vcc, v30, v210
	v_cmp_gt_i32_e64 s[6:7], -2.0, v30
	s_or_b64 vcc, vcc, s[6:7]
	v_add_u32_e32 v30, 8, v0
	v_cndmask_b32_e32 v99, v99, v218, vcc
	v_cmp_gt_i32_e32 vcc, v30, v210
	v_cmp_gt_i32_e64 s[6:7], -2.0, v30
	s_or_b64 vcc, vcc, s[6:7]
	v_add_u32_e32 v30, 9, v0
	v_cndmask_b32_e32 v100, v100, v218, vcc
	v_cmp_gt_i32_e32 vcc, v30, v210
	v_cmp_gt_i32_e64 s[6:7], -2.0, v30
	s_or_b64 vcc, vcc, s[6:7]
	v_add_u32_e32 v30, 10, v0
	v_cndmask_b32_e32 v101, v101, v218, vcc
	v_cmp_gt_i32_e32 vcc, v30, v210
	v_cmp_gt_i32_e64 s[6:7], -2.0, v30
	s_or_b64 vcc, vcc, s[6:7]
	v_add_u32_e32 v30, 11, v0
	v_cndmask_b32_e32 v102, v102, v218, vcc
	v_cmp_gt_i32_e32 vcc, v30, v210
	v_cmp_gt_i32_e64 s[6:7], -2.0, v30
	s_or_b64 vcc, vcc, s[6:7]
	v_add_u32_e32 v30, 16, v0
	v_cndmask_b32_e32 v103, v103, v218, vcc
	v_cmp_gt_i32_e32 vcc, v30, v210
	v_cmp_gt_i32_e64 s[6:7], -2.0, v30
	s_or_b64 vcc, vcc, s[6:7]
	v_add_u32_e32 v30, 17, v0
	v_cndmask_b32_e32 v104, v104, v218, vcc
	v_cmp_gt_i32_e32 vcc, v30, v210
	v_cmp_gt_i32_e64 s[6:7], -2.0, v30
	s_or_b64 vcc, vcc, s[6:7]
	v_add_u32_e32 v30, 18, v0
	v_cndmask_b32_e32 v105, v105, v218, vcc
	v_cmp_gt_i32_e32 vcc, v30, v210
	v_cmp_gt_i32_e64 s[6:7], -2.0, v30
	s_or_b64 vcc, vcc, s[6:7]
	v_add_u32_e32 v30, 19, v0
	v_cndmask_b32_e32 v106, v106, v218, vcc
	v_cmp_gt_i32_e32 vcc, v30, v210
	v_cmp_gt_i32_e64 s[6:7], -2.0, v30
	s_or_b64 vcc, vcc, s[6:7]
	v_add_u32_e32 v30, 24, v0
	v_cndmask_b32_e32 v107, v107, v218, vcc
	v_cmp_gt_i32_e32 vcc, v30, v210
	v_cmp_gt_i32_e64 s[6:7], -2.0, v30
	s_or_b64 vcc, vcc, s[6:7]
	v_add_u32_e32 v30, 25, v0
	v_cndmask_b32_e32 v108, v108, v218, vcc
	v_cmp_gt_i32_e32 vcc, v30, v210
	v_cmp_gt_i32_e64 s[6:7], -2.0, v30
	s_or_b64 vcc, vcc, s[6:7]
	v_add_u32_e32 v30, 26, v0
	v_cndmask_b32_e32 v109, v109, v218, vcc
	v_cmp_gt_i32_e32 vcc, v30, v210
	v_cmp_gt_i32_e64 s[6:7], -2.0, v30
	s_or_b64 vcc, vcc, s[6:7]
	v_add_u32_e32 v30, 27, v0
	v_cndmask_b32_e32 v110, v110, v218, vcc
	v_cmp_gt_i32_e32 vcc, v30, v210
	v_cmp_gt_i32_e64 s[6:7], -2.0, v30
	s_or_b64 vcc, vcc, s[6:7]
	v_add_u32_e32 v30, 32, v0
	v_cndmask_b32_e32 v111, v111, v218, vcc
	v_cmp_gt_i32_e32 vcc, v30, v210
	v_cmp_gt_i32_e64 s[6:7], -2.0, v30
	s_or_b64 vcc, vcc, s[6:7]
	v_add_u32_e32 v30, 33, v0
	v_cndmask_b32_e32 v2, v2, v218, vcc
	v_cmp_gt_i32_e32 vcc, v30, v210
	v_cmp_gt_i32_e64 s[6:7], -2.0, v30
	s_or_b64 vcc, vcc, s[6:7]
	v_add_u32_e32 v30, 34, v0
	v_cndmask_b32_e32 v3, v3, v218, vcc
	v_cmp_gt_i32_e32 vcc, v30, v210
	v_cmp_gt_i32_e64 s[6:7], -2.0, v30
	s_or_b64 vcc, vcc, s[6:7]
	v_add_u32_e32 v30, 35, v0
	v_cndmask_b32_e32 v4, v4, v218, vcc
	v_cmp_gt_i32_e32 vcc, v30, v210
	v_cmp_gt_i32_e64 s[6:7], -2.0, v30
	s_or_b64 vcc, vcc, s[6:7]
	v_add_u32_e32 v30, 40, v0
	v_cndmask_b32_e32 v5, v5, v218, vcc
	v_cmp_gt_i32_e32 vcc, v30, v210
	v_cmp_gt_i32_e64 s[6:7], -2.0, v30
	s_or_b64 vcc, vcc, s[6:7]
	v_add_u32_e32 v30, 41, v0
	v_cndmask_b32_e32 v6, v6, v218, vcc
	v_cmp_gt_i32_e32 vcc, v30, v210
	v_cmp_gt_i32_e64 s[6:7], -2.0, v30
	s_or_b64 vcc, vcc, s[6:7]
	v_add_u32_e32 v30, 42, v0
	v_cndmask_b32_e32 v7, v7, v218, vcc
	v_cmp_gt_i32_e32 vcc, v30, v210
	v_cmp_gt_i32_e64 s[6:7], -2.0, v30
	s_or_b64 vcc, vcc, s[6:7]
	v_add_u32_e32 v30, 43, v0
	v_cndmask_b32_e32 v8, v8, v218, vcc
	v_cmp_gt_i32_e32 vcc, v30, v210
	v_cmp_gt_i32_e64 s[6:7], -2.0, v30
	s_or_b64 vcc, vcc, s[6:7]
	v_add_u32_e32 v30, 48, v0
	v_cndmask_b32_e32 v9, v9, v218, vcc
	v_cmp_gt_i32_e32 vcc, v30, v210
	v_cmp_gt_i32_e64 s[6:7], -2.0, v30
	s_or_b64 vcc, vcc, s[6:7]
	v_add_u32_e32 v30, 49, v0
	v_cndmask_b32_e32 v10, v10, v218, vcc
	v_cmp_gt_i32_e32 vcc, v30, v210
	v_cmp_gt_i32_e64 s[6:7], -2.0, v30
	s_or_b64 vcc, vcc, s[6:7]
	v_add_u32_e32 v30, 50, v0
	v_cndmask_b32_e32 v11, v11, v218, vcc
	v_cmp_gt_i32_e32 vcc, v30, v210
	v_cmp_gt_i32_e64 s[6:7], -2.0, v30
	s_or_b64 vcc, vcc, s[6:7]
	v_add_u32_e32 v30, 51, v0
	v_cndmask_b32_e32 v12, v12, v218, vcc
	v_cmp_gt_i32_e32 vcc, v30, v210
	v_cmp_gt_i32_e64 s[6:7], -2.0, v30
	s_or_b64 vcc, vcc, s[6:7]
	v_add_u32_e32 v30, 56, v0
	v_cndmask_b32_e32 v13, v13, v218, vcc
	v_cmp_gt_i32_e32 vcc, v30, v210
	v_cmp_gt_i32_e64 s[6:7], -2.0, v30
	s_or_b64 vcc, vcc, s[6:7]
	v_add_u32_e32 v30, 57, v0
	v_cndmask_b32_e32 v14, v14, v218, vcc
	v_cmp_gt_i32_e32 vcc, v30, v210
	v_cmp_gt_i32_e64 s[6:7], -2.0, v30
	s_or_b64 vcc, vcc, s[6:7]
	v_add_u32_e32 v30, 58, v0
	v_cndmask_b32_e32 v15, v15, v218, vcc
	v_cmp_gt_i32_e32 vcc, v30, v210
	v_cmp_gt_i32_e64 s[6:7], -2.0, v30
	s_or_b64 vcc, vcc, s[6:7]
	v_add_u32_e32 v0, 59, v0
	v_cndmask_b32_e32 v16, v16, v218, vcc
	v_cmp_gt_i32_e32 vcc, v0, v210
	v_cmp_gt_i32_e64 s[6:7], -2.0, v0
	s_or_b64 vcc, vcc, s[6:7]
	v_cndmask_b32_e32 v17, v17, v218, vcc

; template <int DQK> DEV void qk_tile(f32x16 (&st)[2], const LAS unsigned char* kb, const bf16x8 (&qf)[DQK / 16], int r, int h) {
;     constexpr int KSTR = DQK * 2 + 16, NS = DQK / 16;
;     bf16x8 kf[2][NS];
; #pragma unroll
;     for (int b2 = 0; b2 < 2; ++b2)
; #pragma unroll
;         for (int s = 0; s < NS; ++s) kf[b2][s] = *(const LAS bf16x8*)(kb + (32 * b2 + r) * KSTR + 32 * s + 16 * h);
;     __builtin_amdgcn_sched_barrier(0);
; #pragma unroll
;     for (int b2 = 0; b2 < 2; ++b2) {
;         f32x16 a;
; #pragma unroll
;         for (int i = 0; i < 16; ++i) a[i] = 0.f;
; #pragma unroll
;         for (int s = 0; s < NS; ++s) a = MFMA32(kf[b2][s], qf[s], a);
;         st[b2] = a;
;     }
;     __builtin_amdgcn_sched_barrier(0);
; }
; DEV void pack_p(bf16x8 (&pf)[4], const f32x16 (&st)[2]) {
; #pragma unroll
;     for (int b2 = 0; b2 < 2; ++b2)
; #pragma unroll
;         for (int s = 0; s < 2; ++s) { u32x4 p; p.x = pk2(st[b2][8 * s], st[b2][8 * s + 1]); p.y = pk2(st[b2][8 * s + 2], st[b2][8 * s + 3]);
;             p.z = pk2(st[b2][8 * s + 4], st[b2][8 * s + 5]); p.w = pk2(st[b2][8 * s + 6], st[b2][8 * s + 7]); pf[2 * b2 + s] = __builtin_bit_cast(bf16x8, p); }
; }
; DEV void pv_load(bf16x8 (&vf)[2][4], const LAS unsigned char* vb, int r, int h) {
; #pragma unroll
;     for (int db = 0; db < 2; ++db)
; #pragma unroll
;         for (int f = 0; f < 4; ++f) { const LAS unsigned char* p = vb + (32 * db + r) * 136 + (16 * f + 4 * h) * 2;
; template <int DQK, int MODE> ...
;     ...
;     auto compute = [&](const int t, const int slot) __attribute__((always_inline)) {
;         LAS unsigned char* kb = lds + AL_K0 + slot * AL_KSTR; LAS unsigned char* vb = lds + AL_V0 + slot * AL_VSTR;
;         const int k0 = 64 * t;
;         bool rowsel = true;
;         if (MODE == 1) rowsel = (selm.x >> (t >> 2)) & 1u;
;         if (MODE == 2) { const int tw = t >> 5; const unsigned w = tw == 0 ? selm.x : (tw == 1 ? selm.y : (tw == 2 ? selm.z : selm.w)); rowsel = (w >> (t & 31)) & 1u; }
;         const bool rowact = rowsel && (k0 <= hi_lim) && (k0 + 63 >= lo_lim);
;         if (__any(rowact ? 1 : 0)) {
;             f32x16 st[2];
;             qk_tile<DQK>(st, kb, qf, r, h);
;             bf16x8 vf[2][4];
;             if (MODE != 3) pv_load(vf, vb, r, h);
;             const bool interior = __all(((k0 + 63 <= hi_lim) && (k0 >= lo_lim)) ? 1 : 0);
.LBB0_2873:
	v_lshrrev_b32_e32 v0, s7, v0
	s_lshl_b32 s6, s7, 6
	v_and_b32_e32 v0, 1, v0
	v_cmp_eq_u32_e64 s[0:1], 1, v0
	v_cmp_le_i32_e32 vcc, s6, v210
	s_and_b64 s[12:13], s[0:1], vcc
	v_cndmask_b32_e64 v0, 0, 1, s[12:13]
	v_cmp_ne_u32_e32 vcc, 0, v0
	s_cbranch_vccz .LBB0_2881
	s_add_i32 s7, s24, 2
	s_mul_i32 s12, s7, 0x3400
	v_add_u32_e32 v0, s12, v183
	ds_read_b128 v[2:5], v0
	ds_read_b128 v[6:9], v0 offset:32
	ds_read_b128 v[10:13], v0 offset:64
	ds_read_b128 v[14:17], v0 offset:96
	ds_read_b128 v[18:21], v0 offset:4608
	ds_read_b128 v[22:25], v0 offset:4640
	ds_read_b128 v[26:29], v0 offset:4672
	ds_read_b128 v[140:143], v0 offset:4704
	s_mulk_i32 s7, 0x2200
	s_setprio 1
	s_waitcnt lgkmcnt(7)
	v_mfma_f32_32x32x16_bf16 v[96:111], v[2:5], v[144:147], 0
	s_waitcnt lgkmcnt(6)
	v_mfma_f32_32x32x16_bf16 v[96:111], v[6:9], v[152:155], v[96:111]
	s_waitcnt lgkmcnt(5)
	v_mfma_f32_32x32x16_bf16 v[96:111], v[10:13], v[148:151], v[96:111]
	s_waitcnt lgkmcnt(4)
	v_mfma_f32_32x32x16_bf16 v[96:111], v[14:17], v[156:159], v[96:111]
	s_waitcnt lgkmcnt(3)
	v_mfma_f32_32x32x16_bf16 v[2:17], v[18:21], v[144:147], 0
	s_waitcnt lgkmcnt(2)
	v_mfma_f32_32x32x16_bf16 v[2:17], v[22:25], v[152:155], v[2:17]
	s_waitcnt lgkmcnt(1)
	v_mfma_f32_32x32x16_bf16 v[2:17], v[26:29], v[148:151], v[2:17]
	s_waitcnt lgkmcnt(0)
	v_mfma_f32_32x32x16_bf16 v[2:17], v[140:143], v[156:159], v[2:17]
	s_setprio 0
	v_add_u32_e32 v0, s7, v187
	ds_read2_b64 v[172:175], v0 offset1:2
	ds_read2_b64 v[26:29], v0 offset0:4 offset1:6
	ds_read2_b64 v[22:25], v0 offset0:8 offset1:10
	ds_read2_b64 v[18:21], v0 offset0:12 offset1:14
	v_add_u32_e32 v0, 0x1000, v0
	ds_read2_b64 v[168:171], v0 offset0:32 offset1:34
	ds_read2_b64 v[164:167], v0 offset0:36 offset1:38
	ds_read2_b64 v[160:163], v0 offset0:40 offset1:42
	ds_read2_b64 v[140:143], v0 offset0:44 offset1:46
	s_or_b32 s7, s6, 63
	v_cmp_le_i32_e32 vcc, s7, v210
	s_cmp_eq_u64 vcc, exec
	s_cbranch_scc1 .LBB0_2876
; DEV int crow(int i, int h) { return (i & 3) + 8 * (i >> 2) + 4 * h; }
; template <int DQK, int MODE> ...
;     ...
;             if (!interior) {
; #pragma unroll
;                 for (int b2 = 0; b2 < 2; ++b2)
; #pragma unroll
;                     for (int i = 0; i < 16; ++i) { const int key = k0 + 32 * b2 + crow(i, h); const bool vis = (key <= hi_lim) && (key >= lo_lim); st[b2][i] = vis ? st[b2][i] : -INFINITY; }
;             }
	v_add_u32_e32 v0, s6, v188
	v_cmp_gt_i32_e32 vcc, v0, v210
	v_cmp_gt_i32_e64 s[6:7], -2.0, v0
	s_or_b64 vcc, vcc, s[6:7]
	v_add_u32_e32 v30, 1, v0
	v_cndmask_b32_e32 v96, v96, v218, vcc
	v_cmp_gt_i32_e32 vcc, v30, v210
	v_cmp_gt_i32_e64 s[6:7], -2.0, v30
	s_or_b64 vcc, vcc, s[6:7]
	v_add_u32_e32 v30, 2, v0
	v_cndmask_b32_e32 v97, v97, v218, vcc
	v_cmp_gt_i32_e32 vcc, v30, v210
	v_cmp_gt_i32_e64 s[6:7], -2.0, v30
	s_or_b64 vcc, vcc, s[6:7]
	v_add_u32_e32 v30, 3, v0
	v_cndmask_b32_e32 v98, v98, v218, vcc
	v_cmp_gt_i32_e32 vcc, v30, v210
	v_cmp_gt_i32_e64 s[6:7], -2.0, v30
	s_or_b64 vcc, vcc, s[6:7]
	v_add_u32_e32 v30, 8, v0
	v_cndmask_b32_e32 v99, v99, v218, vcc
	v_cmp_gt_i32_e32 vcc, v30, v210
	v_cmp_gt_i32_e64 s[6:7], -2.0, v30
	s_or_b64 vcc, vcc, s[6:7]
	v_add_u32_e32 v30, 9, v0
	v_cndmask_b32_e32 v100, v100, v218, vcc
	v_cmp_gt_i32_e32 vcc, v30, v210
	v_cmp_gt_i32_e64 s[6:7], -2.0, v30
	s_or_b64 vcc, vcc, s[6:7]
	v_add_u32_e32 v30, 10, v0
	v_cndmask_b32_e32 v101, v101, v218, vcc
	v_cmp_gt_i32_e32 vcc, v30, v210
	v_cmp_gt_i32_e64 s[6:7], -2.0, v30
	s_or_b64 vcc, vcc, s[6:7]
	v_add_u32_e32 v30, 11, v0
	v_cndmask_b32_e32 v102, v102, v218, vcc
	v_cmp_gt_i32_e32 vcc, v30, v210
	v_cmp_gt_i32_e64 s[6:7], -2.0, v30
	s_or_b64 vcc, vcc, s[6:7]
	v_add_u32_e32 v30, 16, v0
	v_cndmask_b32_e32 v103, v103, v218, vcc
	v_cmp_gt_i32_e32 vcc, v30, v210
	v_cmp_gt_i32_e64 s[6:7], -2.0, v30
	s_or_b64 vcc, vcc, s[6:7]
	v_add_u32_e32 v30, 17, v0
	v_cndmask_b32_e32 v104, v104, v218, vcc
	v_cmp_gt_i32_e32 vcc, v30, v210
	v_cmp_gt_i32_e64 s[6:7], -2.0, v30
	s_or_b64 vcc, vcc, s[6:7]
	v_add_u32_e32 v30, 18, v0
	v_cndmask_b32_e32 v105, v105, v218, vcc
	v_cmp_gt_i32_e32 vcc, v30, v210
	v_cmp_gt_i32_e64 s[6:7], -2.0, v30
	s_or_b64 vcc, vcc, s[6:7]
	v_add_u32_e32 v30, 19, v0
	v_cndmask_b32_e32 v106, v106, v218, vcc
	v_cmp_gt_i32_e32 vcc, v30, v210
	v_cmp_gt_i32_e64 s[6:7], -2.0, v30
	s_or_b64 vcc, vcc, s[6:7]
	v_add_u32_e32 v30, 24, v0
	v_cndmask_b32_e32 v107, v107, v218, vcc
	v_cmp_gt_i32_e32 vcc, v30, v210
	v_cmp_gt_i32_e64 s[6:7], -2.0, v30
	s_or_b64 vcc, vcc, s[6:7]
	v_add_u32_e32 v30, 25, v0
	v_cndmask_b32_e32 v108, v108, v218, vcc
	v_cmp_gt_i32_e32 vcc, v30, v210
	v_cmp_gt_i32_e64 s[6:7], -2.0, v30
	s_or_b64 vcc, vcc, s[6:7]
	v_add_u32_e32 v30, 26, v0
	v_cndmask_b32_e32 v109, v109, v218, vcc
	v_cmp_gt_i32_e32 vcc, v30, v210
	v_cmp_gt_i32_e64 s[6:7], -2.0, v30
	s_or_b64 vcc, vcc, s[6:7]
	v_add_u32_e32 v30, 27, v0
	v_cndmask_b32_e32 v110, v110, v218, vcc
	v_cmp_gt_i32_e32 vcc, v30, v210
	v_cmp_gt_i32_e64 s[6:7], -2.0, v30
	s_or_b64 vcc, vcc, s[6:7]
	v_add_u32_e32 v30, 32, v0
	v_cndmask_b32_e32 v111, v111, v218, vcc
	v_cmp_gt_i32_e32 vcc, v30, v210
	v_cmp_gt_i32_e64 s[6:7], -2.0, v30
	s_or_b64 vcc, vcc, s[6:7]
	v_add_u32_e32 v30, 33, v0
	v_cndmask_b32_e32 v2, v2, v218, vcc
	v_cmp_gt_i32_e32 vcc, v30, v210
	v_cmp_gt_i32_e64 s[6:7], -2.0, v30
	s_or_b64 vcc, vcc, s[6:7]
	v_add_u32_e32 v30, 34, v0
	v_cndmask_b32_e32 v3, v3, v218, vcc
	v_cmp_gt_i32_e32 vcc, v30, v210
	v_cmp_gt_i32_e64 s[6:7], -2.0, v30
	s_or_b64 vcc, vcc, s[6:7]
	v_add_u32_e32 v30, 35, v0
	v_cndmask_b32_e32 v4, v4, v218, vcc
	v_cmp_gt_i32_e32 vcc, v30, v210
	v_cmp_gt_i32_e64 s[6:7], -2.0, v30
	s_or_b64 vcc, vcc, s[6:7]
	v_add_u32_e32 v30, 40, v0
	v_cndmask_b32_e32 v5, v5, v218, vcc
	v_cmp_gt_i32_e32 vcc, v30, v210
	v_cmp_gt_i32_e64 s[6:7], -2.0, v30
	s_or_b64 vcc, vcc, s[6:7]
	v_add_u32_e32 v30, 41, v0
	v_cndmask_b32_e32 v6, v6, v218, vcc
	v_cmp_gt_i32_e32 vcc, v30, v210
	v_cmp_gt_i32_e64 s[6:7], -2.0, v30
	s_or_b64 vcc, vcc, s[6:7]
	v_add_u32_e32 v30, 42, v0
	v_cndmask_b32_e32 v7, v7, v218, vcc
	v_cmp_gt_i32_e32 vcc, v30, v210
	v_cmp_gt_i32_e64 s[6:7], -2.0, v30
	s_or_b64 vcc, vcc, s[6:7]
	v_add_u32_e32 v30, 43, v0
	v_cndmask_b32_e32 v8, v8, v218, vcc
	v_cmp_gt_i32_e32 vcc, v30, v210
	v_cmp_gt_i32_e64 s[6:7], -2.0, v30
	s_or_b64 vcc, vcc, s[6:7]
	v_add_u32_e32 v30, 48, v0
	v_cndmask_b32_e32 v9, v9, v218, vcc
	v_cmp_gt_i32_e32 vcc, v30, v210
	v_cmp_gt_i32_e64 s[6:7], -2.0, v30
	s_or_b64 vcc, vcc, s[6:7]
	v_add_u32_e32 v30, 49, v0
	v_cndmask_b32_e32 v10, v10, v218, vcc
	v_cmp_gt_i32_e32 vcc, v30, v210
	v_cmp_gt_i32_e64 s[6:7], -2.0, v30
	s_or_b64 vcc, vcc, s[6:7]
	v_add_u32_e32 v30, 50, v0
	v_cndmask_b32_e32 v11, v11, v218, vcc
	v_cmp_gt_i32_e32 vcc, v30, v210
	v_cmp_gt_i32_e64 s[6:7], -2.0, v30
	s_or_b64 vcc, vcc, s[6:7]
	v_add_u32_e32 v30, 51, v0
	v_cndmask_b32_e32 v12, v12, v218, vcc
	v_cmp_gt_i32_e32 vcc, v30, v210
	v_cmp_gt_i32_e64 s[6:7], -2.0, v30
	s_or_b64 vcc, vcc, s[6:7]
	v_add_u32_e32 v30, 56, v0
	v_cndmask_b32_e32 v13, v13, v218, vcc
	v_cmp_gt_i32_e32 vcc, v30, v210
	v_cmp_gt_i32_e64 s[6:7], -2.0, v30
	s_or_b64 vcc, vcc, s[6:7]
	v_add_u32_e32 v30, 57, v0
	v_cndmask_b32_e32 v14, v14, v218, vcc
	v_cmp_gt_i32_e32 vcc, v30, v210
	v_cmp_gt_i32_e64 s[6:7], -2.0, v30
	s_or_b64 vcc, vcc, s[6:7]
	v_add_u32_e32 v30, 58, v0
	v_cndmask_b32_e32 v15, v15, v218, vcc
	v_cmp_gt_i32_e32 vcc, v30, v210
	v_cmp_gt_i32_e64 s[6:7], -2.0, v30
	s_or_b64 vcc, vcc, s[6:7]
	v_add_u32_e32 v0, 59, v0
	v_cndmask_b32_e32 v16, v16, v218, vcc
	v_cmp_gt_i32_e32 vcc, v0, v210
	v_cmp_gt_i32_e64 s[6:7], -2.0, v0
	s_or_b64 vcc, vcc, s[6:7]
	v_cndmask_b32_e32 v17, v17, v218, vcc

; __device__ __forceinline__ unsigned f2bf_(float f) { unsigned u = __builtin_bit_cast(unsigned, f); return (u + 0x7fffu + ((u >> 16) & 1u)) >> 16; }
; __device__ __forceinline__ unsigned pk2_(float lo, float hi) { return f2bf_(lo) | (f2bf_(hi) << 16); }
; template <int ACT> __device__ __forceinline__ float act_f(float v) {
;     if (ACT == 2) { const float t = fmaxf(v, 0.f); return t * t; }
;     if (ACT == 3) { const float u = 0.7978845608028654f * (v + 0.044715f * v * v * v); const float e = __expf(2.f * u); const float th = 1.f - 2.f / (e + 1.f); return 0.5f * v * (1.f + th); }
;     return v;
; }
;     __device__ __forceinline__ void operator()(const f32x4 (&acc)[2][2][4][2], const Unit& u, int wr, int wc, int fr, int fq) const {
;         asm volatile("" : "+v"(fr), "+v"(fq));
;         const int row0 = u.pm * BM + wr * 64 + fr; const int col0 = u.pn * BM + wc * 32 + 8 * fq;
; #pragma unroll
;         for (int ai = 0; ai < 2; ++ai)
; #pragma unroll
;             for (int m = 0; m < 4; ++m) { bf16_t* rowp = O + (size_t)(row0 + ai * HALF + m * 16) * ldc + col0;
; #pragma unroll
;                 for (int bj = 0; bj < 2; ++bj) { f32x4 v0 = acc[ai][bj][m][0], v1 = acc[ai][bj][m][1];
;                     if (bias) { v0 += *(const f32x4*)(bias + col0 + bj * HALF); v1 += *(const f32x4*)(bias + col0 + bj * HALF + 4); }
;                     u32x4 w; w.x = pk2_(act_f<ACT>(v0[0]), act_f<ACT>(v0[1])); w.y = pk2_(act_f<ACT>(v0[2]), act_f<ACT>(v0[3]));
;                     w.z = pk2_(act_f<ACT>(v1[0]), act_f<ACT>(v1[1])); w.w = pk2_(act_f<ACT>(v1[2]), act_f<ACT>(v1[3]));
;                     *(u32x4*)(rowp + bj * HALF) = w; } }
.LBB0_3111:
	v_mov_b32_e32 v144, v146
	v_mov_b32_e32 v145, v147
	s_lshl_b32 s12, s62, 8
	s_add_i32 s12, s12, s63
	v_add_u32_e32 v144, s12, v144
	s_lshl_b32 s12, s84, 8
	s_or_b32 s12, s12, s70
	v_lshl_add_u32 v152, v145, 3, s12
	v_ashrrev_i32_e32 v145, 31, v144
	v_lshlrev_b64 v[144:145], 13, v[144:145]
	v_ashrrev_i32_e32 v153, 31, v152
	v_lshl_add_u64 v[144:145], s[16:17], 0, v[144:145]
	v_lshl_add_u64 v[144:145], v[152:153], 1, v[144:145]
	v_max_f32_e32 v152, 0, v125
	v_max_f32_e32 v125, v126, v126
	v_max_f32_e32 v126, v127, v127
	v_max_f32_e32 v153, 0, v126
	v_pk_mul_f32 v[126:127], v[152:153], v[152:153]
	v_max_f32_e32 v152, 0, v121
	v_max_f32_e32 v121, v122, v122
	v_max_f32_e32 v122, v123, v123
	v_max_f32_e32 v153, 0, v122
	v_max_f32_e32 v124, 0, v124
	v_max_f32_e32 v125, 0, v125
	v_max_f32_e32 v120, 0, v120
	v_max_f32_e32 v121, 0, v121
	v_pk_mul_f32 v[122:123], v[152:153], v[152:153]
	v_pk_mul_f32 v[124:125], v[124:125], v[124:125]
	v_pk_mul_f32 v[120:121], v[120:121], v[120:121]
	v_cvt_pk_bf16_f32 v123, v121, v123
	v_cvt_pk_bf16_f32 v122, v120, v122
	v_cvt_pk_bf16_f32 v121, v125, v127
	v_cvt_pk_bf16_f32 v120, v124, v126
	global_store_dwordx4 v[144:145], v[120:123], off
	s_nop 1
	v_max_f32_e32 v120, 0, v117
	v_max_f32_e32 v117, v118, v118
	v_max_f32_e32 v118, v119, v119
	v_max_f32_e32 v121, 0, v118
	v_pk_mul_f32 v[118:119], v[120:121], v[120:121]
	v_max_f32_e32 v120, 0, v113
	v_max_f32_e32 v113, v114, v114
	v_max_f32_e32 v114, v115, v115
	v_max_f32_e32 v121, 0, v114
	v_max_f32_e32 v116, 0, v116
	v_max_f32_e32 v117, 0, v117
	v_max_f32_e32 v112, 0, v112
	v_max_f32_e32 v113, 0, v113
	v_pk_mul_f32 v[114:115], v[120:121], v[120:121]
	v_pk_mul_f32 v[116:117], v[116:117], v[116:117]
	v_pk_mul_f32 v[112:113], v[112:113], v[112:113]
	v_cvt_pk_bf16_f32 v115, v113, v115
	v_cvt_pk_bf16_f32 v114, v112, v114
	v_cvt_pk_bf16_f32 v113, v117, v119
	v_cvt_pk_bf16_f32 v112, v116, v118
	global_store_dwordx4 v[144:145], v[112:115], off offset:256
	s_nop 1
	v_max_f32_e32 v114, 0, v109
	v_max_f32_e32 v109, v110, v110
	v_max_f32_e32 v110, v111, v111
	v_max_f32_e32 v115, 0, v110
	v_pk_mul_f32 v[110:111], v[114:115], v[114:115]
	v_max_f32_e32 v114, 0, v105
	v_max_f32_e32 v105, v106, v106
	v_max_f32_e32 v106, v107, v107
	v_max_f32_e32 v115, 0, v106
	v_max_f32_e32 v108, 0, v108
	v_max_f32_e32 v109, 0, v109
	v_max_f32_e32 v104, 0, v104
	v_max_f32_e32 v105, 0, v105
	v_pk_mul_f32 v[106:107], v[114:115], v[114:115]
	v_pk_mul_f32 v[108:109], v[108:109], v[108:109]
	v_pk_mul_f32 v[104:105], v[104:105], v[104:105]
	v_cvt_pk_bf16_f32 v106, v104, v106
	v_cvt_pk_bf16_f32 v104, v108, v110
	v_add_co_u32_e32 v108, vcc, s77, v144
	v_cvt_pk_bf16_f32 v107, v105, v107
	v_cvt_pk_bf16_f32 v105, v109, v111
	v_addc_co_u32_e32 v109, vcc, 0, v145, vcc
	global_store_dwordx4 v[108:109], v[104:107], off
	s_nop 1
	v_max_f32_e32 v104, 0, v101
	v_max_f32_e32 v101, v102, v102
	v_max_f32_e32 v102, v103, v103
	v_max_f32_e32 v105, 0, v102
	v_pk_mul_f32 v[102:103], v[104:105], v[104:105]
	v_max_f32_e32 v104, 0, v97
	v_max_f32_e32 v97, v98, v98
	v_max_f32_e32 v98, v99, v99
	v_max_f32_e32 v105, 0, v98
	v_max_f32_e32 v100, 0, v100
	v_max_f32_e32 v101, 0, v101
	v_max_f32_e32 v96, 0, v96
	v_max_f32_e32 v97, 0, v97
	v_pk_mul_f32 v[98:99], v[104:105], v[104:105]
	v_pk_mul_f32 v[100:101], v[100:101], v[100:101]
	v_pk_mul_f32 v[96:97], v[96:97], v[96:97]
	v_lshl_add_u64 v[112:113], v[144:145], 0, s[28:29]
	v_cvt_pk_bf16_f32 v99, v97, v99
	v_cvt_pk_bf16_f32 v98, v96, v98
	v_cvt_pk_bf16_f32 v97, v101, v103
	v_cvt_pk_bf16_f32 v96, v100, v102
	global_store_dwordx4 v[112:113], v[96:99], off offset:256
	s_nop 1
	v_max_f32_e32 v98, 0, v93
	v_max_f32_e32 v93, v94, v94
	v_max_f32_e32 v94, v95, v95
	v_max_f32_e32 v99, 0, v94
	v_pk_mul_f32 v[94:95], v[98:99], v[98:99]
	v_max_f32_e32 v98, 0, v89
	v_max_f32_e32 v89, v90, v90
	v_max_f32_e32 v90, v91, v91
	v_max_f32_e32 v99, 0, v90
	v_max_f32_e32 v92, 0, v92
	v_max_f32_e32 v93, 0, v93
	v_max_f32_e32 v88, 0, v88
	v_max_f32_e32 v89, 0, v89
	v_pk_mul_f32 v[90:91], v[98:99], v[98:99]
	v_pk_mul_f32 v[92:93], v[92:93], v[92:93]
	v_pk_mul_f32 v[88:89], v[88:89], v[88:89]
	v_cvt_pk_bf16_f32 v90, v88, v90
	v_cvt_pk_bf16_f32 v88, v92, v94
	v_add_co_u32_e32 v92, vcc, s78, v144
	v_cvt_pk_bf16_f32 v91, v89, v91
	v_cvt_pk_bf16_f32 v89, v93, v95
	v_addc_co_u32_e32 v93, vcc, 0, v145, vcc
	global_store_dwordx4 v[92:93], v[88:91], off
	s_nop 1
	v_max_f32_e32 v88, 0, v85
	v_max_f32_e32 v85, v86, v86
	v_max_f32_e32 v86, v87, v87
	v_max_f32_e32 v89, 0, v86
	v_pk_mul_f32 v[86:87], v[88:89], v[88:89]
	v_max_f32_e32 v88, 0, v81
	v_max_f32_e32 v81, v82, v82
	v_max_f32_e32 v82, v83, v83
	v_max_f32_e32 v89, 0, v82
	v_max_f32_e32 v84, 0, v84
	v_max_f32_e32 v85, 0, v85
	v_max_f32_e32 v80, 0, v80
	v_max_f32_e32 v81, 0, v81
	v_pk_mul_f32 v[82:83], v[88:89], v[88:89]
	v_pk_mul_f32 v[84:85], v[84:85], v[84:85]
	v_pk_mul_f32 v[80:81], v[80:81], v[80:81]
	v_lshl_add_u64 v[96:97], v[144:145], 0, s[6:7]
	v_cvt_pk_bf16_f32 v83, v81, v83
	v_cvt_pk_bf16_f32 v82, v80, v82
	v_cvt_pk_bf16_f32 v81, v85, v87
	v_cvt_pk_bf16_f32 v80, v84, v86
	global_store_dwordx4 v[96:97], v[80:83], off offset:256
	s_nop 1
	v_max_f32_e32 v82, 0, v77
	v_max_f32_e32 v77, v78, v78
	v_max_f32_e32 v78, v79, v79
	v_max_f32_e32 v83, 0, v78
	v_pk_mul_f32 v[78:79], v[82:83], v[82:83]
	v_max_f32_e32 v82, 0, v73
	v_max_f32_e32 v73, v74, v74
	v_max_f32_e32 v74, v75, v75
	v_max_f32_e32 v83, 0, v74
	v_max_f32_e32 v76, 0, v76
	v_max_f32_e32 v77, 0, v77
	v_max_f32_e32 v72, 0, v72
	v_max_f32_e32 v73, 0, v73
	v_pk_mul_f32 v[74:75], v[82:83], v[82:83]
	v_pk_mul_f32 v[76:77], v[76:77], v[76:77]
	v_pk_mul_f32 v[72:73], v[72:73], v[72:73]
; __device__ __forceinline__ unsigned f2bf_(float f) { unsigned u = __builtin_bit_cast(unsigned, f); return (u + 0x7fffu + ((u >> 16) & 1u)) >> 16; }
; __device__ __forceinline__ unsigned pk2_(float lo, float hi) { return f2bf_(lo) | (f2bf_(hi) << 16); }
; template <int ACT> __device__ __forceinline__ float act_f(float v) {
;     if (ACT == 2) { const float t = fmaxf(v, 0.f); return t * t; }
;     if (ACT == 3) { const float u = 0.7978845608028654f * (v + 0.044715f * v * v * v); const float e = __expf(2.f * u); const float th = 1.f - 2.f / (e + 1.f); return 0.5f * v * (1.f + th); }
;     return v;
; }
;     __device__ __forceinline__ void operator()(const f32x4 (&acc)[2][2][4][2], const Unit& u, int wr, int wc, int fr, int fq) const {
;         asm volatile("" : "+v"(fr), "+v"(fq));
;         const int row0 = u.pm * BM + wr * 64 + fr; const int col0 = u.pn * BM + wc * 32 + 8 * fq;
; #pragma unroll
;         for (int ai = 0; ai < 2; ++ai)
; #pragma unroll
;             for (int m = 0; m < 4; ++m) { bf16_t* rowp = O + (size_t)(row0 + ai * HALF + m * 16) * ldc + col0;
; #pragma unroll
;                 for (int bj = 0; bj < 2; ++bj) { f32x4 v0 = acc[ai][bj][m][0], v1 = acc[ai][bj][m][1];
;                     if (bias) { v0 += *(const f32x4*)(bias + col0 + bj * HALF); v1 += *(const f32x4*)(bias + col0 + bj * HALF + 4); }
;                     u32x4 w; w.x = pk2_(act_f<ACT>(v0[0]), act_f<ACT>(v0[1])); w.y = pk2_(act_f<ACT>(v0[2]), act_f<ACT>(v0[3]));
;                     w.z = pk2_(act_f<ACT>(v1[0]), act_f<ACT>(v1[1])); w.w = pk2_(act_f<ACT>(v1[2]), act_f<ACT>(v1[3]));
;                     *(u32x4*)(rowp + bj * HALF) = w; } }
	v_cvt_pk_bf16_f32 v74, v72, v74
	v_cvt_pk_bf16_f32 v72, v76, v78
	v_add_co_u32_e32 v76, vcc, s79, v144
	v_cvt_pk_bf16_f32 v75, v73, v75
	v_cvt_pk_bf16_f32 v73, v77, v79
	v_addc_co_u32_e32 v77, vcc, 0, v145, vcc
	global_store_dwordx4 v[76:77], v[72:75], off
	s_nop 1
	v_max_f32_e32 v72, 0, v69
	v_max_f32_e32 v69, v70, v70
	v_max_f32_e32 v70, v71, v71
	v_max_f32_e32 v73, 0, v70
	v_pk_mul_f32 v[70:71], v[72:73], v[72:73]
	v_max_f32_e32 v72, 0, v65
	v_max_f32_e32 v65, v66, v66
	v_max_f32_e32 v66, v67, v67
	v_max_f32_e32 v73, 0, v66
	v_max_f32_e32 v68, 0, v68
	v_max_f32_e32 v69, 0, v69
	v_max_f32_e32 v64, 0, v64
	v_max_f32_e32 v65, 0, v65
	v_pk_mul_f32 v[66:67], v[72:73], v[72:73]
	v_pk_mul_f32 v[68:69], v[68:69], v[68:69]
	v_pk_mul_f32 v[64:65], v[64:65], v[64:65]
	v_lshl_add_u64 v[80:81], v[144:145], 0, s[30:31]
	v_cvt_pk_bf16_f32 v67, v65, v67
	v_cvt_pk_bf16_f32 v66, v64, v66
	v_cvt_pk_bf16_f32 v65, v69, v71
	v_cvt_pk_bf16_f32 v64, v68, v70
	global_store_dwordx4 v[80:81], v[64:67], off offset:256
	s_nop 1
	v_max_f32_e32 v66, 0, v61
	v_max_f32_e32 v61, v62, v62
	v_max_f32_e32 v62, v63, v63
	v_max_f32_e32 v67, 0, v62
	v_pk_mul_f32 v[62:63], v[66:67], v[66:67]
	v_max_f32_e32 v66, 0, v57
	v_max_f32_e32 v57, v58, v58
	v_max_f32_e32 v58, v59, v59
	v_max_f32_e32 v67, 0, v58
	v_max_f32_e32 v60, 0, v60
	v_max_f32_e32 v61, 0, v61
	v_max_f32_e32 v56, 0, v56
	v_max_f32_e32 v57, 0, v57
	v_pk_mul_f32 v[58:59], v[66:67], v[66:67]
	v_pk_mul_f32 v[60:61], v[60:61], v[60:61]
	v_pk_mul_f32 v[56:57], v[56:57], v[56:57]
	v_cvt_pk_bf16_f32 v58, v56, v58
	v_cvt_pk_bf16_f32 v56, v60, v62
	v_add_co_u32_e32 v60, vcc, s80, v144
	v_cvt_pk_bf16_f32 v59, v57, v59
	v_cvt_pk_bf16_f32 v57, v61, v63
	v_addc_co_u32_e32 v61, vcc, 0, v145, vcc
	global_store_dwordx4 v[60:61], v[56:59], off
	s_nop 1
	v_max_f32_e32 v56, 0, v53
	v_max_f32_e32 v53, v54, v54
	v_max_f32_e32 v54, v55, v55
	v_max_f32_e32 v57, 0, v54
	v_pk_mul_f32 v[54:55], v[56:57], v[56:57]
	v_max_f32_e32 v56, 0, v49
	v_max_f32_e32 v49, v50, v50
	v_max_f32_e32 v50, v51, v51
	v_max_f32_e32 v57, 0, v50
	v_max_f32_e32 v52, 0, v52
	v_max_f32_e32 v53, 0, v53
	v_max_f32_e32 v48, 0, v48
	v_max_f32_e32 v49, 0, v49
	v_pk_mul_f32 v[50:51], v[56:57], v[56:57]
	v_pk_mul_f32 v[52:53], v[52:53], v[52:53]
	v_pk_mul_f32 v[48:49], v[48:49], v[48:49]
	v_lshl_add_u64 v[64:65], v[144:145], 0, s[34:35]
	v_cvt_pk_bf16_f32 v51, v49, v51
	v_cvt_pk_bf16_f32 v50, v48, v50
	v_cvt_pk_bf16_f32 v49, v53, v55
	v_cvt_pk_bf16_f32 v48, v52, v54
	global_store_dwordx4 v[64:65], v[48:51], off offset:256
	s_nop 1
	v_max_f32_e32 v50, 0, v45
	v_max_f32_e32 v45, v46, v46
	v_max_f32_e32 v46, v47, v47
	v_max_f32_e32 v51, 0, v46
	v_pk_mul_f32 v[46:47], v[50:51], v[50:51]
	v_max_f32_e32 v50, 0, v41
	v_max_f32_e32 v41, v42, v42
	v_max_f32_e32 v42, v43, v43
	v_max_f32_e32 v51, 0, v42
	v_max_f32_e32 v44, 0, v44
	v_max_f32_e32 v45, 0, v45
	v_max_f32_e32 v40, 0, v40
	v_max_f32_e32 v41, 0, v41
	v_pk_mul_f32 v[42:43], v[50:51], v[50:51]
	v_pk_mul_f32 v[44:45], v[44:45], v[44:45]
	v_pk_mul_f32 v[40:41], v[40:41], v[40:41]
	v_cvt_pk_bf16_f32 v42, v40, v42
	v_cvt_pk_bf16_f32 v40, v44, v46
	v_add_co_u32_e32 v44, vcc, s81, v144
	v_cvt_pk_bf16_f32 v43, v41, v43
	v_cvt_pk_bf16_f32 v41, v45, v47
	v_addc_co_u32_e32 v45, vcc, 0, v145, vcc
	global_store_dwordx4 v[44:45], v[40:43], off
	s_nop 1
	v_max_f32_e32 v40, 0, v37
	v_max_f32_e32 v37, v38, v38
	v_max_f32_e32 v38, v39, v39
	v_max_f32_e32 v41, 0, v38
	v_pk_mul_f32 v[38:39], v[40:41], v[40:41]
	v_max_f32_e32 v40, 0, v33
	v_max_f32_e32 v33, v34, v34
	v_max_f32_e32 v34, v35, v35
	v_max_f32_e32 v41, 0, v34
	v_max_f32_e32 v36, 0, v36
; __device__ __forceinline__ unsigned f2bf_(float f) { unsigned u = __builtin_bit_cast(unsigned, f); return (u + 0x7fffu + ((u >> 16) & 1u)) >> 16; }
; __device__ __forceinline__ unsigned pk2_(float lo, float hi) { return f2bf_(lo) | (f2bf_(hi) << 16); }
; template <int ACT> __device__ __forceinline__ float act_f(float v) {
;     if (ACT == 2) { const float t = fmaxf(v, 0.f); return t * t; }
;     if (ACT == 3) { const float u = 0.7978845608028654f * (v + 0.044715f * v * v * v); const float e = __expf(2.f * u); const float th = 1.f - 2.f / (e + 1.f); return 0.5f * v * (1.f + th); }
;     return v;
; }
;     __device__ __forceinline__ void operator()(const f32x4 (&acc)[2][2][4][2], const Unit& u, int wr, int wc, int fr, int fq) const {
;         asm volatile("" : "+v"(fr), "+v"(fq));
;         const int row0 = u.pm * BM + wr * 64 + fr; const int col0 = u.pn * BM + wc * 32 + 8 * fq;
; #pragma unroll
;         for (int ai = 0; ai < 2; ++ai)
; #pragma unroll
;             for (int m = 0; m < 4; ++m) { bf16_t* rowp = O + (size_t)(row0 + ai * HALF + m * 16) * ldc + col0;
; #pragma unroll
;                 for (int bj = 0; bj < 2; ++bj) { f32x4 v0 = acc[ai][bj][m][0], v1 = acc[ai][bj][m][1];
;                     if (bias) { v0 += *(const f32x4*)(bias + col0 + bj * HALF); v1 += *(const f32x4*)(bias + col0 + bj * HALF + 4); }
;                     u32x4 w; w.x = pk2_(act_f<ACT>(v0[0]), act_f<ACT>(v0[1])); w.y = pk2_(act_f<ACT>(v0[2]), act_f<ACT>(v0[3]));
;                     w.z = pk2_(act_f<ACT>(v1[0]), act_f<ACT>(v1[1])); w.w = pk2_(act_f<ACT>(v1[2]), act_f<ACT>(v1[3]));
;                     *(u32x4*)(rowp + bj * HALF) = w; } }
	v_max_f32_e32 v37, 0, v37
	v_max_f32_e32 v32, 0, v32
	v_max_f32_e32 v33, 0, v33
	v_pk_mul_f32 v[34:35], v[40:41], v[40:41]
	v_pk_mul_f32 v[36:37], v[36:37], v[36:37]
	v_pk_mul_f32 v[32:33], v[32:33], v[32:33]
	v_lshl_add_u64 v[48:49], v[144:145], 0, s[36:37]
	v_cvt_pk_bf16_f32 v35, v33, v35
	v_cvt_pk_bf16_f32 v34, v32, v34
	v_cvt_pk_bf16_f32 v33, v37, v39
	v_cvt_pk_bf16_f32 v32, v36, v38
	global_store_dwordx4 v[48:49], v[32:35], off offset:256
	s_nop 1
	v_max_f32_e32 v34, 0, v29
	v_max_f32_e32 v29, v30, v30
	v_max_f32_e32 v30, v31, v31
	v_max_f32_e32 v35, 0, v30
	v_pk_mul_f32 v[30:31], v[34:35], v[34:35]
	v_max_f32_e32 v34, 0, v25
	v_max_f32_e32 v25, v26, v26
	v_max_f32_e32 v26, v27, v27
	v_max_f32_e32 v35, 0, v26
	v_max_f32_e32 v28, 0, v28
	v_max_f32_e32 v29, 0, v29
	v_max_f32_e32 v24, 0, v24
	v_max_f32_e32 v25, 0, v25
	v_pk_mul_f32 v[26:27], v[34:35], v[34:35]
	v_pk_mul_f32 v[28:29], v[28:29], v[28:29]
	v_pk_mul_f32 v[24:25], v[24:25], v[24:25]
	v_cvt_pk_bf16_f32 v26, v24, v26
	v_cvt_pk_bf16_f32 v24, v28, v30
	v_add_co_u32_e32 v28, vcc, s82, v144
	v_cvt_pk_bf16_f32 v27, v25, v27
	v_cvt_pk_bf16_f32 v25, v29, v31
	v_addc_co_u32_e32 v29, vcc, 0, v145, vcc
	global_store_dwordx4 v[28:29], v[24:27], off
	s_nop 1
	v_max_f32_e32 v24, 0, v21
	v_max_f32_e32 v21, v22, v22
	v_max_f32_e32 v22, v23, v23
	v_max_f32_e32 v25, 0, v22
	v_pk_mul_f32 v[22:23], v[24:25], v[24:25]
	v_max_f32_e32 v24, 0, v17
	v_max_f32_e32 v17, v18, v18
	v_max_f32_e32 v18, v19, v19
	v_max_f32_e32 v25, 0, v18
	v_max_f32_e32 v20, 0, v20
	v_max_f32_e32 v21, 0, v21
	v_max_f32_e32 v16, 0, v16
	v_max_f32_e32 v17, 0, v17
	v_pk_mul_f32 v[18:19], v[24:25], v[24:25]
	v_pk_mul_f32 v[20:21], v[20:21], v[20:21]
	v_pk_mul_f32 v[16:17], v[16:17], v[16:17]
	v_lshl_add_u64 v[32:33], v[144:145], 0, s[38:39]
	v_cvt_pk_bf16_f32 v19, v17, v19
	v_cvt_pk_bf16_f32 v18, v16, v18
	v_cvt_pk_bf16_f32 v17, v21, v23
	v_cvt_pk_bf16_f32 v16, v20, v22
	global_store_dwordx4 v[32:33], v[16:19], off offset:256
	s_nop 1
	v_max_f32_e32 v18, 0, v13
	v_max_f32_e32 v13, v14, v14
	v_max_f32_e32 v14, v15, v15
	v_max_f32_e32 v19, 0, v14
	v_pk_mul_f32 v[14:15], v[18:19], v[18:19]
	v_max_f32_e32 v18, 0, v9
	v_max_f32_e32 v9, v10, v10
	v_max_f32_e32 v10, v11, v11
	v_max_f32_e32 v19, 0, v10
	v_max_f32_e32 v12, 0, v12
	v_max_f32_e32 v13, 0, v13
	v_max_f32_e32 v8, 0, v8
	v_max_f32_e32 v9, 0, v9
	v_pk_mul_f32 v[10:11], v[18:19], v[18:19]
	v_pk_mul_f32 v[12:13], v[12:13], v[12:13]
	v_pk_mul_f32 v[8:9], v[8:9], v[8:9]
	v_cvt_pk_bf16_f32 v10, v8, v10
	v_cvt_pk_bf16_f32 v8, v12, v14
	v_add_co_u32_e32 v12, vcc, s83, v144
	v_cvt_pk_bf16_f32 v11, v9, v11
	v_cvt_pk_bf16_f32 v9, v13, v15
	v_addc_co_u32_e32 v13, vcc, 0, v145, vcc
	global_store_dwordx4 v[12:13], v[8:11], off
	s_nop 1
	v_max_f32_e32 v8, 0, v5
	v_max_f32_e32 v5, v6, v6
	v_max_f32_e32 v6, v7, v7
	v_max_f32_e32 v9, 0, v6
	v_pk_mul_f32 v[6:7], v[8:9], v[8:9]
	v_max_f32_e32 v8, 0, v1
	v_max_f32_e32 v1, v2, v2
	v_max_f32_e32 v2, v3, v3
	v_max_f32_e32 v9, 0, v2
	v_max_f32_e32 v4, 0, v4
	v_max_f32_e32 v5, 0, v5
	v_max_f32_e32 v0, 0, v0
	v_max_f32_e32 v1, 0, v1
	v_pk_mul_f32 v[2:3], v[8:9], v[8:9]
	v_pk_mul_f32 v[4:5], v[4:5], v[4:5]
	v_pk_mul_f32 v[0:1], v[0:1], v[0:1]
	v_lshl_add_u64 v[16:17], v[144:145], 0, s[40:41]
	v_cvt_pk_bf16_f32 v3, v1, v3
	v_cvt_pk_bf16_f32 v2, v0, v2
	v_cvt_pk_bf16_f32 v1, v5, v7
	v_cvt_pk_bf16_f32 v0, v4, v6
	s_andn2_b64 vcc, exec, s[0:1]
	s_mov_b64 s[0:1], -1
	global_store_dwordx4 v[16:17], v[0:3], off offset:256
	s_cbranch_vccnz .LBB0_3100
	s_andn2_b64 vcc, exec, s[22:23]
	s_cbranch_vccnz .LBB0_3099
	s_barrier
	s_branch .LBB0_3099
